# all packed f32 VALU ops (v_pk_fma/mul/add_f32) split into scalar pairs
# baseline (speedup 1.0000x reference)
.LBB0_75:
	s_waitcnt vmcnt(0)
	v_mul_f32_e64 v8, v4, v10
	v_mul_f32_e64 v9, v5, v10
	v_mul_f32_e64 v11, v3, v10
	v_mul_f32_e64 v10, v2, v10
	v_mov_b32_e32 v2, 0
	v_mov_b32_e32 v3, 0
	v_mov_b32_e32 v4, 0
	v_mov_b32_e32 v5, 0
	s_and_saveexec_b64 s[6:7], s[4:5]
	s_cbranch_execz .LBB0_77
	v_add3_u32 v1, v58, s12, 16
	v_mad_u64_u32 v[2:3], s[28:29], v1, s22, 0
	v_ashrrev_i32_e32 v5, 31, v1
	v_mov_b32_e32 v4, v3
	v_mad_u64_u32 v[4:5], s[28:29], v5, s22, v[4:5]
	v_mov_b32_e32 v3, v4
	v_lshl_add_u64 v[2:3], v[2:3], 2, s[16:17]
	v_lshl_add_u64 v[2:3], v[6:7], 2, v[2:3]
	global_load_dwordx4 v[2:5], v[2:3], off nt

.LBB0_80:
	s_waitcnt vmcnt(0)
	v_mul_f32_e64 v12, v4, v14
	v_mul_f32_e64 v13, v5, v14
	v_mul_f32_e64 v15, v3, v14
	v_mul_f32_e64 v14, v2, v14
	v_mov_b32_e32 v2, 0
	v_mov_b32_e32 v3, 0
	v_mov_b32_e32 v4, 0
	v_mov_b32_e32 v5, 0
	s_and_saveexec_b64 s[20:21], s[4:5]
	s_cbranch_execz .LBB0_82
	v_add3_u32 v1, v58, s12, 32
	v_mad_u64_u32 v[2:3], s[28:29], v1, s22, 0
	v_ashrrev_i32_e32 v5, 31, v1
	v_mov_b32_e32 v4, v3
	v_mad_u64_u32 v[4:5], s[28:29], v5, s22, v[4:5]
	v_mov_b32_e32 v3, v4
	v_lshl_add_u64 v[2:3], v[2:3], 2, s[16:17]
	v_lshl_add_u64 v[2:3], v[6:7], 2, v[2:3]
	global_load_dwordx4 v[2:5], v[2:3], off nt

.LBB0_85:
	s_waitcnt vmcnt(0)
	v_mul_f32_e64 v16, v4, v18
	v_mul_f32_e64 v17, v5, v18
	v_mul_f32_e64 v19, v3, v18
	v_mul_f32_e64 v18, v2, v18
	v_mov_b32_e32 v2, 0
	v_mov_b32_e32 v3, 0
	v_mov_b32_e32 v4, 0
	v_mov_b32_e32 v5, 0
	s_and_saveexec_b64 s[20:21], s[4:5]
	s_cbranch_execz .LBB0_87
	v_add3_u32 v1, v58, s12, 48
	v_mad_u64_u32 v[2:3], s[4:5], v1, s22, 0
	v_ashrrev_i32_e32 v5, 31, v1
	v_mov_b32_e32 v4, v3
	v_mad_u64_u32 v[4:5], s[4:5], v5, s22, v[4:5]
	v_mov_b32_e32 v3, v4
	v_lshl_add_u64 v[2:3], v[2:3], 2, s[16:17]
	v_lshl_add_u64 v[2:3], v[6:7], 2, v[2:3]
	global_load_dwordx4 v[2:5], v[2:3], off nt
.LBB0_87:
	s_or_b64 exec, exec, s[20:21]
	s_and_b64 vcc, exec, s[6:7]
	s_cbranch_vccnz .LBB0_89
	s_ashr_i32 s13, s12, 31
	v_mov_b32_e32 v59, 0
	v_lshl_add_u64 v[6:7], s[12:13], 0, v[58:59]
	v_lshl_add_u64 v[6:7], v[6:7], 2, s[18:19]
	global_load_dword v6, v[6:7], off offset:192
	s_waitcnt vmcnt(0)
	v_mul_f32_e64 v20, v4, v6
	v_mul_f32_e64 v21, v5, v6
	v_mul_f32_e64 v22, v2, v6
	v_mul_f32_e64 v23, v3, v6
	s_andn2_b64 vcc, exec, s[14:15]
	s_cbranch_vccnz .LBB0_204
	s_branch .LBB0_90
.LBB0_89:
	v_mov_b32_e32 v6, 1.0
	s_waitcnt vmcnt(0)
	v_mul_f32_e64 v20, v4, v6
	v_mul_f32_e64 v21, v5, v6
	v_mul_f32_e64 v22, v2, v6
	v_mul_f32_e64 v23, v3, v6
	s_andn2_b64 vcc, exec, s[14:15]
	s_cbranch_vccnz .LBB0_204

.LBB0_141:
	s_waitcnt vmcnt(0)
	v_mul_f32_e64 v24, v4, v6
	v_mul_f32_e64 v25, v5, v6
	v_mul_f32_e64 v26, v2, v6
	v_mul_f32_e64 v27, v3, v6
	v_mov_b32_e32 v2, 0
	v_mov_b32_e32 v3, 0
	v_mov_b32_e32 v4, 0
	v_mov_b32_e32 v5, 0
	s_and_saveexec_b64 s[6:7], s[4:5]
	s_cbranch_execz .LBB0_143
	v_add_u32_e32 v2, s22, v38
	v_ashrrev_i32_e32 v5, 31, v2
	v_mad_u64_u32 v[2:3], s[94:95], v2, s29, 0
	v_mov_b32_e32 v4, v3
	v_mad_u64_u32 v[4:5], s[94:95], v5, s29, v[4:5]
	v_mov_b32_e32 v3, v4
	v_lshl_add_u64 v[2:3], v[2:3], 2, s[14:15]
	v_lshl_add_u64 v[2:3], v[36:37], 2, v[2:3]
	global_load_dwordx4 v[2:5], v[2:3], off nt

.LBB0_146:
	s_waitcnt vmcnt(0)
	v_mul_f32_e64 v28, v4, v6
	v_mul_f32_e64 v29, v5, v6
	v_mul_f32_e64 v30, v2, v6
	v_mul_f32_e64 v31, v3, v6
	v_mov_b32_e32 v2, 0
	v_mov_b32_e32 v3, 0
	v_mov_b32_e32 v4, 0
	v_mov_b32_e32 v5, 0
	s_and_saveexec_b64 vcc, s[4:5]
	s_cbranch_execz .LBB0_148
	v_add_u32_e32 v2, s22, v39
	v_ashrrev_i32_e32 v5, 31, v2
	v_mad_u64_u32 v[2:3], s[94:95], v2, s29, 0
	v_mov_b32_e32 v4, v3
	v_mad_u64_u32 v[4:5], s[94:95], v5, s29, v[4:5]
	v_mov_b32_e32 v3, v4
	v_lshl_add_u64 v[2:3], v[2:3], 2, s[14:15]
	v_lshl_add_u64 v[2:3], v[36:37], 2, v[2:3]
	global_load_dwordx4 v[2:5], v[2:3], off nt

.LBB0_151:
	v_readlane_b32 s0, v231, 22
	v_readlane_b32 s1, v231, 23
	s_waitcnt vmcnt(0)
	v_mul_f32_e64 v32, v4, v6
	v_mul_f32_e64 v33, v5, v6
	v_mul_f32_e64 v34, v2, v6
	v_mul_f32_e64 v35, v3, v6
	v_mov_b32_e32 v2, 0
	v_mov_b32_e32 v3, 0
	v_mov_b32_e32 v4, 0
	v_mov_b32_e32 v5, 0
	s_and_saveexec_b64 vcc, s[4:5]
	s_cbranch_execz .LBB0_153
	v_add_u32_e32 v2, s22, v40
	v_ashrrev_i32_e32 v5, 31, v2
	v_mad_u64_u32 v[2:3], s[4:5], v2, s29, 0
	v_mov_b32_e32 v4, v3
	v_mad_u64_u32 v[4:5], s[4:5], v5, s29, v[4:5]
	v_mov_b32_e32 v3, v4
	v_lshl_add_u64 v[2:3], v[2:3], 2, s[14:15]
	v_lshl_add_u64 v[2:3], v[36:37], 2, v[2:3]
	global_load_dwordx4 v[2:5], v[2:3], off nt

.LBB0_156:
	s_waitcnt vmcnt(0)
	v_mul_f32_e64 v4, v4, v6
	v_mul_f32_e64 v5, v5, v6
	v_mul_f32_e64 v2, v2, v6
	v_mul_f32_e64 v3, v3, v6

.LBB0_280:
	s_and_b32 s2, s3, 0xffff
	s_mul_hi_u32 s2, s2, 0x147ae15
	s_mulk_i32 s2, 0xff38
	s_bfe_u32 s4, s3, 0xd0003
	s_mul_i32 s5, s4, 0x147b
	s_add_i32 s2, s3, s2
	s_ashr_i32 s4, s2, 3
	s_lshr_b32 s2, s5, 14
	s_and_b32 s5, s3, 7
	s_and_b32 s2, s2, 0xff8
	s_or_b32 s5, s5, s22
	s_add_i32 s2, s2, s5
	s_ashr_i32 s5, s4, 31
	s_lshl_b64 s[6:7], s[4:5], 18
	v_lshl_add_u64 v[120:121], v[100:101], 0, s[6:7]
	s_lshl_b32 s12, s2, 18
	s_movk_i32 s5, 0x2000
	v_lshl_add_u64 v[122:123], v[102:103], 0, s[12:13]
	v_add_co_u32_e32 v22, vcc, s5, v120
	v_lshl_add_u64 v[2:3], v[122:123], 0, v[112:113]
	v_lshl_add_u64 v[10:11], v[122:123], 0, v[114:115]
	v_addc_co_u32_e32 v23, vcc, 0, v121, vcc
	v_lshl_add_u64 v[18:19], v[122:123], 0, v[116:117]
	v_lshl_add_u64 v[26:27], v[122:123], 0, v[118:119]
	s_barrier
	global_load_dwordx4 v[2:5], v[2:3], off
	s_movk_i32 s5, 0x4000
	global_load_dwordx4 v[6:9], v[120:121], off
	global_load_dwordx4 v[14:17], v[22:23], off offset:-4096
	v_add_co_u32_e32 v34, vcc, s5, v120
	global_load_dwordx4 v[10:13], v[10:11], off
	s_nop 0
	v_addc_co_u32_e32 v35, vcc, 0, v121, vcc
	global_load_dwordx4 v[18:21], v[18:19], off
	s_mov_b64 s[6:7], 0x4000
	global_load_dwordx4 v[22:25], v[22:23], off
	s_movk_i32 s5, 0x6000
	global_load_dwordx4 v[26:29], v[26:27], off
	s_lshl_b32 s4, s4, 7
	global_load_dwordx4 v[30:33], v[34:35], off offset:-4096
	s_cmpk_gt_u32 s4, 0xbff
	s_cselect_b64 s[14:15], -1, 0
	s_waitcnt vmcnt(7)
	ds_write_b128 v128, v[2:5]
	s_waitcnt vmcnt(6)
	ds_write_b128 v128, v[6:9] offset:18432
	s_waitcnt vmcnt(5)
	ds_write_b128 v129, v[14:17] offset:18432
	global_load_dwordx4 v[6:9], v[34:35], off
	s_waitcnt vmcnt(5)
	ds_write_b128 v129, v[10:13]
	s_waitcnt vmcnt(4)
	ds_write_b128 v130, v[18:21]
	s_waitcnt vmcnt(3)
	ds_write_b128 v130, v[22:25] offset:18432
	v_add_co_u32_e32 v22, vcc, s5, v120
	s_waitcnt vmcnt(2)
	ds_write_b128 v131, v[26:29]
	v_lshl_add_u64 v[26:27], v[122:123], 0, s[6:7]
	v_lshl_add_u64 v[2:3], v[26:27], 0, v[112:113]
	global_load_dwordx4 v[2:5], v[2:3], off
	v_addc_co_u32_e32 v23, vcc, 0, v121, vcc
	s_mov_b32 s5, 0x8000
	v_add_co_u32_e32 v38, vcc, s5, v120
	v_lshl_add_u64 v[10:11], v[26:27], 0, v[114:115]
	v_lshl_add_u64 v[18:19], v[26:27], 0, v[116:117]
	v_lshl_add_u64 v[26:27], v[26:27], 0, v[118:119]
	v_addc_co_u32_e32 v39, vcc, 0, v121, vcc
	s_waitcnt vmcnt(2)
	ds_write_b128 v131, v[30:33] offset:18432
	global_load_dwordx4 v[10:13], v[10:11], off
	s_mov_b32 s5, 0xc000
	global_load_dwordx4 v[14:17], v[22:23], off offset:-4096
	global_load_dwordx4 v[30:33], v[38:39], off offset:-4096
	s_mov_b64 s[6:7], 0x8000
	global_load_dwordx4 v[18:21], v[18:19], off
	v_add_co_u32_e32 v124, vcc, s5, v120
	global_load_dwordx4 v[22:25], v[22:23], off
	s_nop 0
	v_addc_co_u32_e32 v125, vcc, 0, v121, vcc
	global_load_dwordx4 v[26:29], v[26:27], off
	s_waitcnt lgkmcnt(0)
	s_barrier
	ds_read_b128 v[150:153], v143 offset:18432
	ds_read_b128 v[34:37], v144
	s_waitcnt lgkmcnt(0)
	v_mfma_f32_32x32x16_bf16 v[50:65], v[150:153], v[34:37], 0
	ds_read_b128 v[154:157], v143 offset:23040
	ds_read_b128 v[158:161], v144 offset:4608
	global_load_dwordx4 v[90:93], v[38:39], off
	s_mov_b32 s5, 0xa000
	global_load_dwordx4 v[66:69], v[124:125], off offset:-4096
	s_waitcnt lgkmcnt(1)
	v_mfma_f32_32x32x16_bf16 v[34:49], v[154:157], v[34:37], 0
	s_waitcnt vmcnt(9)
	ds_write_b128 v128, v[6:9] offset:55296
	s_waitcnt vmcnt(8)
	ds_write_b128 v128, v[2:5] offset:36864
	v_lshl_add_u64 v[2:3], v[122:123], 0, s[6:7]
	v_lshl_add_u64 v[4:5], v[2:3], 0, v[118:119]
	global_load_dwordx4 v[70:73], v[4:5], off
	v_add_co_u32_e32 v4, vcc, s5, v120
	s_mov_b32 s5, 0x9000
	s_nop 0
	v_addc_co_u32_e32 v5, vcc, 0, v121, vcc
	global_load_dwordx4 v[74:77], v[4:5], off
	v_lshl_add_u64 v[4:5], v[2:3], 0, v[116:117]
	global_load_dwordx4 v[78:81], v[4:5], off
	v_add_co_u32_e32 v4, vcc, s5, v120
	s_waitcnt vmcnt(10)
	ds_write_b128 v129, v[10:13] offset:36864
	v_addc_co_u32_e32 v5, vcc, 0, v121, vcc
	global_load_dwordx4 v[82:85], v[4:5], off
	v_lshl_add_u64 v[4:5], v[2:3], 0, v[114:115]
	v_lshl_add_u64 v[2:3], v[2:3], 0, v[112:113]
	global_load_dwordx4 v[86:89], v[4:5], off
	global_load_dwordx4 v[94:97], v[2:3], off
	s_waitcnt vmcnt(12)
	ds_write_b128 v129, v[14:17] offset:55296
	s_waitcnt lgkmcnt(4)
	v_mfma_f32_32x32x16_bf16 v[2:17], v[150:153], v[158:161], 0
	s_waitcnt vmcnt(10)
	ds_write_b128 v130, v[18:21] offset:36864
	s_waitcnt vmcnt(9)
	ds_write_b128 v130, v[22:25] offset:55296
	s_waitcnt vmcnt(8)
	ds_write_b128 v131, v[26:29] offset:36864
	ds_write_b128 v131, v[30:33] offset:55296
	s_mov_b32 s5, 0x10000
	s_mov_b64 s[6:7], 0xc000
	v_mfma_f32_32x32x16_bf16 v[18:33], v[154:157], v[158:161], 0
	ds_read_b128 v[162:165], v133 offset:23072
	ds_read_b128 v[168:171], v134 offset:4640
	s_waitcnt lgkmcnt(0)
	v_mfma_f32_32x32x16_bf16 v[18:33], v[162:165], v[168:171], v[18:33]
	ds_read_b128 v[150:153], v133 offset:18464
	ds_read_b128 v[154:157], v133 offset:18496
	s_waitcnt lgkmcnt(1)
	v_mfma_f32_32x32x16_bf16 v[2:17], v[150:153], v[168:171], v[2:17]
	ds_read_b128 v[158:161], v134 offset:32
	ds_read_b128 v[172:175], v134 offset:64
	s_waitcnt lgkmcnt(1)
	v_mfma_f32_32x32x16_bf16 v[50:65], v[150:153], v[158:161], v[50:65]
	ds_read_b128 v[176:179], v133 offset:23104
	ds_read_b128 v[180:183], v134 offset:4672
	v_mfma_f32_32x32x16_bf16 v[34:49], v[162:165], v[158:161], v[34:49]
	ds_read_b128 v[150:153], v133 offset:18528
	ds_read_b128 v[158:161], v134 offset:96
	s_waitcnt lgkmcnt(4)
	v_mfma_f32_32x32x16_bf16 v[50:65], v[154:157], v[172:175], v[50:65]
	ds_read_b128 v[162:165], v133 offset:23136
	ds_read_b128 v[168:171], v134 offset:4704
	s_waitcnt lgkmcnt(0)
	s_barrier
	v_mfma_f32_32x32x16_bf16 v[34:49], v[176:179], v[172:175], v[34:49]
	ds_read_b128 v[172:175], v144 offset:36864
	v_mfma_f32_32x32x16_bf16 v[2:17], v[154:157], v[180:183], v[2:17]
	ds_read_b128 v[154:157], v143 offset:55296
	v_mfma_f32_32x32x16_bf16 v[18:33], v[176:179], v[180:183], v[18:33]
	ds_read_b128 v[176:179], v143 offset:59904
	ds_read_b128 v[180:183], v144 offset:41472
	v_mfma_f32_32x32x16_bf16 v[50:65], v[150:153], v[158:161], v[50:65]
	s_waitcnt vmcnt(7)
	ds_write_b128 v128, v[90:93] offset:18432
	v_add_co_u32_e32 v90, vcc, s5, v120
	s_mov_b32 s5, 0xe000
	s_nop 0
	v_addc_co_u32_e32 v91, vcc, 0, v121, vcc
	s_waitcnt vmcnt(0)
	ds_write_b128 v128, v[94:97]
	v_mfma_f32_32x32x16_bf16 v[34:49], v[162:165], v[158:161], v[34:49]
	ds_write_b128 v129, v[86:89]
	ds_write_b128 v129, v[82:85] offset:18432
	v_lshl_add_u64 v[96:97], v[122:123], 0, s[6:7]
	v_lshl_add_u64 v[86:87], v[96:97], 0, v[114:115]
	global_load_dwordx4 v[92:95], v[124:125], off
	s_mov_b64 s[6:7], 0x10000
	global_load_dwordx4 v[86:89], v[86:87], off
	v_mfma_f32_32x32x16_bf16 v[2:17], v[150:153], v[168:171], v[2:17]
	ds_write_b128 v130, v[74:77] offset:18432
	v_add_co_u32_e32 v74, vcc, s5, v120
	ds_write_b128 v130, v[78:81]
	s_nop 0
	v_addc_co_u32_e32 v75, vcc, 0, v121, vcc
	v_lshl_add_u64 v[78:79], v[96:97], 0, v[116:117]
	v_mfma_f32_32x32x16_bf16 v[18:33], v[162:165], v[168:171], v[18:33]
	ds_write_b128 v131, v[70:73]
	v_lshl_add_u64 v[70:71], v[96:97], 0, v[118:119]
	s_mov_b32 s5, 0xd000
	v_lshl_add_u64 v[96:97], v[96:97], 0, v[112:113]
	v_add_co_u32_e32 v82, vcc, s5, v120
	global_load_dwordx4 v[124:127], v[96:97], off
	s_nop 0
	v_addc_co_u32_e32 v83, vcc, 0, v121, vcc
	global_load_dwordx4 v[74:77], v[74:75], off
	ds_write_b128 v131, v[66:69] offset:18432
	global_load_dwordx4 v[82:85], v[82:83], off
	s_waitcnt lgkmcnt(10)
	v_mfma_f32_32x32x16_bf16 v[50:65], v[154:157], v[172:175], v[50:65]
	global_load_dwordx4 v[70:73], v[70:71], off
	ds_read_b128 v[150:153], v133 offset:59936
	global_load_dwordx4 v[78:81], v[78:79], off
	ds_read_b128 v[158:161], v134 offset:41504
	global_load_dwordx4 v[66:69], v[90:91], off offset:-4096
	s_mov_b32 s5, 0x14000
	s_waitcnt lgkmcnt(11)
	v_mfma_f32_32x32x16_bf16 v[34:49], v[176:179], v[172:175], v[34:49]
	ds_read_b128 v[162:165], v133 offset:55360
	ds_read_b128 v[168:171], v134 offset:36896
	s_waitcnt lgkmcnt(12)
	v_mfma_f32_32x32x16_bf16 v[2:17], v[154:157], v[180:183], v[2:17]
	ds_read_b128 v[154:157], v133 offset:55328
	ds_read_b128 v[172:175], v134 offset:36928
	v_mfma_f32_32x32x16_bf16 v[18:33], v[176:179], v[180:183], v[18:33]
	ds_read_b128 v[176:179], v133 offset:59968
	ds_read_b128 v[180:183], v134 offset:41536
	s_waitcnt lgkmcnt(3)
	v_mfma_f32_32x32x16_bf16 v[50:65], v[154:157], v[168:171], v[50:65]
	v_mfma_f32_32x32x16_bf16 v[34:49], v[150:153], v[168:171], v[34:49]
	ds_read_b128 v[168:171], v134 offset:41568
	v_mfma_f32_32x32x16_bf16 v[2:17], v[154:157], v[158:161], v[2:17]
	ds_read_b128 v[154:157], v134 offset:36960
	v_mfma_f32_32x32x16_bf16 v[18:33], v[150:153], v[158:161], v[18:33]
	ds_read_b128 v[150:153], v133 offset:55392
	ds_read_b128 v[158:161], v133 offset:60000
	s_waitcnt lgkmcnt(0)
	s_barrier
	v_mfma_f32_32x32x16_bf16 v[50:65], v[162:165], v[172:175], v[50:65]
	v_mfma_f32_32x32x16_bf16 v[34:49], v[176:179], v[172:175], v[34:49]
	ds_read_b128 v[172:175], v144
	v_mfma_f32_32x32x16_bf16 v[2:17], v[162:165], v[180:183], v[2:17]
	ds_read_b128 v[162:165], v143 offset:18432
	v_mfma_f32_32x32x16_bf16 v[18:33], v[176:179], v[180:183], v[18:33]
	ds_read_b128 v[176:179], v143 offset:23040
	ds_read_b128 v[180:183], v144 offset:4608
	v_mfma_f32_32x32x16_bf16 v[50:65], v[150:153], v[154:157], v[50:65]
	s_waitcnt vmcnt(5)
	ds_write_b128 v128, v[124:127] offset:36864
	v_add_co_u32_e32 v124, vcc, s5, v120
	s_mov_b32 s5, 0x12000
	s_nop 0
	v_addc_co_u32_e32 v125, vcc, 0, v121, vcc
	ds_write_b128 v128, v[92:95] offset:55296
	v_mfma_f32_32x32x16_bf16 v[34:49], v[158:161], v[154:157], v[34:49]
	ds_write_b128 v129, v[86:89] offset:36864
	s_waitcnt vmcnt(3)
	ds_write_b128 v129, v[82:85] offset:55296
	v_lshl_add_u64 v[94:95], v[122:123], 0, s[6:7]
	v_lshl_add_u64 v[86:87], v[94:95], 0, v[114:115]
	global_load_dwordx4 v[86:89], v[86:87], off
	s_mov_b64 s[6:7], 0x14000
	global_load_dwordx4 v[90:93], v[90:91], off
	v_mfma_f32_32x32x16_bf16 v[2:17], v[150:153], v[168:171], v[2:17]
	ds_write_b128 v130, v[74:77] offset:55296
	v_add_co_u32_e32 v74, vcc, s5, v120
	s_mov_b32 s5, 0x11000
	s_nop 0
	v_addc_co_u32_e32 v75, vcc, 0, v121, vcc
	v_add_co_u32_e32 v82, vcc, s5, v120
	s_waitcnt vmcnt(3)
	ds_write_b128 v130, v[78:81] offset:36864
	v_mfma_f32_32x32x16_bf16 v[18:33], v[158:161], v[168:171], v[18:33]
	ds_write_b128 v131, v[70:73] offset:36864
	v_lshl_add_u64 v[70:71], v[94:95], 0, v[118:119]
	v_lshl_add_u64 v[78:79], v[94:95], 0, v[116:117]
	v_addc_co_u32_e32 v83, vcc, 0, v121, vcc
	v_lshl_add_u64 v[94:95], v[94:95], 0, v[112:113]
	global_load_dwordx4 v[74:77], v[74:75], off
	s_waitcnt vmcnt(3)
	ds_write_b128 v131, v[66:69] offset:55296
	global_load_dwordx4 v[82:85], v[82:83], off
	s_waitcnt lgkmcnt(10)
	v_mfma_f32_32x32x16_bf16 v[50:65], v[162:165], v[172:175], v[50:65]
	global_load_dwordx4 v[94:97], v[94:95], off
	ds_read_b128 v[150:153], v133 offset:23072
	global_load_dwordx4 v[70:73], v[70:71], off
	ds_read_b128 v[154:157], v134 offset:4640
	global_load_dwordx4 v[78:81], v[78:79], off
	s_mov_b32 s5, 0x18000
	global_load_dwordx4 v[66:69], v[124:125], off offset:-4096
	s_waitcnt lgkmcnt(11)
	v_mfma_f32_32x32x16_bf16 v[34:49], v[176:179], v[172:175], v[34:49]
	ds_read_b128 v[158:161], v133 offset:18464
	ds_read_b128 v[168:171], v134 offset:32
	v_add_co_u32_e32 v126, vcc, s5, v120
	s_mov_b32 s5, 0x16000
	s_nop 0
	v_addc_co_u32_e32 v127, vcc, 0, v121, vcc
	s_waitcnt lgkmcnt(12)
	v_mfma_f32_32x32x16_bf16 v[2:17], v[162:165], v[180:183], v[2:17]
	ds_read_b128 v[162:165], v133 offset:18496
	ds_read_b128 v[172:175], v134 offset:64
	v_mfma_f32_32x32x16_bf16 v[18:33], v[176:179], v[180:183], v[18:33]
	ds_read_b128 v[176:179], v133 offset:23104
	ds_read_b128 v[180:183], v134 offset:4672
	s_waitcnt lgkmcnt(4)
	v_mfma_f32_32x32x16_bf16 v[50:65], v[158:161], v[168:171], v[50:65]
	v_mfma_f32_32x32x16_bf16 v[34:49], v[150:153], v[168:171], v[34:49]
	ds_read_b128 v[168:171], v134 offset:4704
	v_mfma_f32_32x32x16_bf16 v[2:17], v[158:161], v[154:157], v[2:17]
	ds_read_b128 v[158:161], v133 offset:23136
	v_mfma_f32_32x32x16_bf16 v[18:33], v[150:153], v[154:157], v[18:33]
	ds_read_b128 v[150:153], v133 offset:18528
	ds_read_b128 v[154:157], v134 offset:96
	s_waitcnt lgkmcnt(0)
	s_barrier
	v_mfma_f32_32x32x16_bf16 v[50:65], v[162:165], v[172:175], v[50:65]
	v_mfma_f32_32x32x16_bf16 v[34:49], v[176:179], v[172:175], v[34:49]
	ds_read_b128 v[172:175], v144 offset:36864
	v_mfma_f32_32x32x16_bf16 v[2:17], v[162:165], v[180:183], v[2:17]
	ds_read_b128 v[162:165], v143 offset:55296
	v_mfma_f32_32x32x16_bf16 v[18:33], v[176:179], v[180:183], v[18:33]
	ds_read_b128 v[176:179], v143 offset:59904
	ds_read_b128 v[180:183], v144 offset:41472
	v_mfma_f32_32x32x16_bf16 v[50:65], v[150:153], v[154:157], v[50:65]
	s_waitcnt vmcnt(3)
	ds_write_b128 v128, v[94:97]
	ds_write_b128 v128, v[90:93] offset:18432
	v_lshl_add_u64 v[94:95], v[122:123], 0, s[6:7]
	global_load_dwordx4 v[90:93], v[124:125], off
	s_mov_b64 s[6:7], 0x18000
	v_mfma_f32_32x32x16_bf16 v[34:49], v[158:161], v[154:157], v[34:49]
	ds_write_b128 v129, v[86:89]
	ds_write_b128 v129, v[82:85] offset:18432
	v_lshl_add_u64 v[86:87], v[94:95], 0, v[114:115]
	global_load_dwordx4 v[86:89], v[86:87], off
	v_mfma_f32_32x32x16_bf16 v[2:17], v[150:153], v[168:171], v[2:17]
	ds_write_b128 v130, v[74:77] offset:18432
	v_add_co_u32_e32 v74, vcc, s5, v120
	s_mov_b32 s5, 0x15000
	s_nop 0
	v_addc_co_u32_e32 v75, vcc, 0, v121, vcc
	v_add_co_u32_e32 v82, vcc, s5, v120
	s_waitcnt vmcnt(3)
	ds_write_b128 v130, v[78:81]
	v_mfma_f32_32x32x16_bf16 v[18:33], v[158:161], v[168:171], v[18:33]
	ds_write_b128 v131, v[70:73]
	v_lshl_add_u64 v[70:71], v[94:95], 0, v[118:119]
	v_lshl_add_u64 v[78:79], v[94:95], 0, v[116:117]
	v_addc_co_u32_e32 v83, vcc, 0, v121, vcc
	v_lshl_add_u64 v[94:95], v[94:95], 0, v[112:113]
	global_load_dwordx4 v[74:77], v[74:75], off
	s_waitcnt vmcnt(3)
	ds_write_b128 v131, v[66:69] offset:18432
	global_load_dwordx4 v[82:85], v[82:83], off
	s_waitcnt lgkmcnt(10)
	v_mfma_f32_32x32x16_bf16 v[50:65], v[162:165], v[172:175], v[50:65]
	global_load_dwordx4 v[94:97], v[94:95], off
	ds_read_b128 v[150:153], v133 offset:59936
	global_load_dwordx4 v[70:73], v[70:71], off
	ds_read_b128 v[154:157], v134 offset:41504
	global_load_dwordx4 v[78:81], v[78:79], off
	s_mov_b32 s5, 0x1c000
	global_load_dwordx4 v[66:69], v[126:127], off offset:-4096
	s_waitcnt lgkmcnt(11)
	v_mfma_f32_32x32x16_bf16 v[34:49], v[176:179], v[172:175], v[34:49]
	ds_read_b128 v[158:161], v133 offset:55328
	ds_read_b128 v[168:171], v134 offset:36896
	v_add_co_u32_e32 v124, vcc, s5, v120
	s_mov_b32 s5, 0x1a000
	s_nop 0
	v_addc_co_u32_e32 v125, vcc, 0, v121, vcc
	s_waitcnt lgkmcnt(12)
	v_mfma_f32_32x32x16_bf16 v[2:17], v[162:165], v[180:183], v[2:17]
	ds_read_b128 v[162:165], v133 offset:55360
	ds_read_b128 v[172:175], v134 offset:36928
	v_mfma_f32_32x32x16_bf16 v[18:33], v[176:179], v[180:183], v[18:33]
	ds_read_b128 v[176:179], v133 offset:59968
	ds_read_b128 v[180:183], v134 offset:41536
	s_waitcnt lgkmcnt(4)
	v_mfma_f32_32x32x16_bf16 v[50:65], v[158:161], v[168:171], v[50:65]
	v_mfma_f32_32x32x16_bf16 v[34:49], v[150:153], v[168:171], v[34:49]
	ds_read_b128 v[168:171], v134 offset:41568
	v_mfma_f32_32x32x16_bf16 v[2:17], v[158:161], v[154:157], v[2:17]
	ds_read_b128 v[158:161], v133 offset:60000
	v_mfma_f32_32x32x16_bf16 v[18:33], v[150:153], v[154:157], v[18:33]
	ds_read_b128 v[150:153], v133 offset:55392
	ds_read_b128 v[154:157], v134 offset:36960
	s_waitcnt lgkmcnt(0)
	s_barrier
	v_mfma_f32_32x32x16_bf16 v[50:65], v[162:165], v[172:175], v[50:65]
	v_mfma_f32_32x32x16_bf16 v[34:49], v[176:179], v[172:175], v[34:49]
	ds_read_b128 v[172:175], v144
	v_mfma_f32_32x32x16_bf16 v[2:17], v[162:165], v[180:183], v[2:17]
	ds_read_b128 v[162:165], v143 offset:18432
	v_mfma_f32_32x32x16_bf16 v[18:33], v[176:179], v[180:183], v[18:33]
	ds_read_b128 v[176:179], v143 offset:23040
	ds_read_b128 v[180:183], v144 offset:4608
	v_mfma_f32_32x32x16_bf16 v[50:65], v[150:153], v[154:157], v[50:65]
	s_waitcnt vmcnt(3)
	ds_write_b128 v128, v[94:97] offset:36864
	ds_write_b128 v128, v[90:93] offset:55296
	v_lshl_add_u64 v[94:95], v[122:123], 0, s[6:7]
	global_load_dwordx4 v[90:93], v[126:127], off
	s_mov_b64 s[6:7], 0x1c000
	v_mfma_f32_32x32x16_bf16 v[34:49], v[158:161], v[154:157], v[34:49]
	ds_write_b128 v129, v[86:89] offset:36864
	ds_write_b128 v129, v[82:85] offset:55296
	v_lshl_add_u64 v[86:87], v[94:95], 0, v[114:115]
	global_load_dwordx4 v[86:89], v[86:87], off
	v_mfma_f32_32x32x16_bf16 v[2:17], v[150:153], v[168:171], v[2:17]
	ds_write_b128 v130, v[74:77] offset:55296
	v_add_co_u32_e32 v74, vcc, s5, v120
	s_mov_b32 s5, 0x19000
	s_nop 0
	v_addc_co_u32_e32 v75, vcc, 0, v121, vcc
	v_add_co_u32_e32 v82, vcc, s5, v120
	s_waitcnt vmcnt(3)
	ds_write_b128 v130, v[78:81] offset:36864
	v_mfma_f32_32x32x16_bf16 v[18:33], v[158:161], v[168:171], v[18:33]
	ds_write_b128 v131, v[70:73] offset:36864
	v_lshl_add_u64 v[70:71], v[94:95], 0, v[118:119]
	v_lshl_add_u64 v[78:79], v[94:95], 0, v[116:117]
	v_addc_co_u32_e32 v83, vcc, 0, v121, vcc
	v_lshl_add_u64 v[94:95], v[94:95], 0, v[112:113]
	global_load_dwordx4 v[74:77], v[74:75], off
	s_waitcnt vmcnt(3)
	ds_write_b128 v131, v[66:69] offset:55296
	global_load_dwordx4 v[82:85], v[82:83], off
	s_waitcnt lgkmcnt(10)
	v_mfma_f32_32x32x16_bf16 v[50:65], v[162:165], v[172:175], v[50:65]
	global_load_dwordx4 v[94:97], v[94:95], off
	ds_read_b128 v[150:153], v133 offset:23072
	global_load_dwordx4 v[70:73], v[70:71], off
	ds_read_b128 v[154:157], v134 offset:4640
	global_load_dwordx4 v[78:81], v[78:79], off
	s_mov_b32 s5, 0x20000
	global_load_dwordx4 v[66:69], v[124:125], off offset:-4096
	s_waitcnt lgkmcnt(11)
	v_mfma_f32_32x32x16_bf16 v[34:49], v[176:179], v[172:175], v[34:49]
	ds_read_b128 v[158:161], v133 offset:18464
	ds_read_b128 v[168:171], v134 offset:32
	v_add_co_u32_e32 v126, vcc, s5, v120
	s_mov_b32 s5, 0x1e000
	s_nop 0
	v_addc_co_u32_e32 v127, vcc, 0, v121, vcc
	s_waitcnt lgkmcnt(12)
	v_mfma_f32_32x32x16_bf16 v[2:17], v[162:165], v[180:183], v[2:17]
	ds_read_b128 v[162:165], v133 offset:18496
	ds_read_b128 v[172:175], v134 offset:64
	v_mfma_f32_32x32x16_bf16 v[18:33], v[176:179], v[180:183], v[18:33]
	ds_read_b128 v[176:179], v133 offset:23104
	ds_read_b128 v[180:183], v134 offset:4672
	s_waitcnt lgkmcnt(4)
	v_mfma_f32_32x32x16_bf16 v[50:65], v[158:161], v[168:171], v[50:65]
	v_mfma_f32_32x32x16_bf16 v[34:49], v[150:153], v[168:171], v[34:49]
	ds_read_b128 v[168:171], v134 offset:4704
	v_mfma_f32_32x32x16_bf16 v[2:17], v[158:161], v[154:157], v[2:17]
	ds_read_b128 v[158:161], v133 offset:23136
	v_mfma_f32_32x32x16_bf16 v[18:33], v[150:153], v[154:157], v[18:33]
	ds_read_b128 v[150:153], v133 offset:18528
	ds_read_b128 v[154:157], v134 offset:96
	s_waitcnt lgkmcnt(0)
	s_barrier
	v_mfma_f32_32x32x16_bf16 v[50:65], v[162:165], v[172:175], v[50:65]
	v_mfma_f32_32x32x16_bf16 v[34:49], v[176:179], v[172:175], v[34:49]
	ds_read_b128 v[172:175], v144 offset:36864
	v_mfma_f32_32x32x16_bf16 v[2:17], v[162:165], v[180:183], v[2:17]
	ds_read_b128 v[162:165], v143 offset:55296
	v_mfma_f32_32x32x16_bf16 v[18:33], v[176:179], v[180:183], v[18:33]
	ds_read_b128 v[176:179], v143 offset:59904
	ds_read_b128 v[180:183], v144 offset:41472
	v_mfma_f32_32x32x16_bf16 v[50:65], v[150:153], v[154:157], v[50:65]
	s_waitcnt vmcnt(3)
	ds_write_b128 v128, v[94:97]
	ds_write_b128 v128, v[90:93] offset:18432
	v_lshl_add_u64 v[94:95], v[122:123], 0, s[6:7]
	global_load_dwordx4 v[90:93], v[124:125], off
	s_mov_b64 s[6:7], 0x20000
	v_mfma_f32_32x32x16_bf16 v[34:49], v[158:161], v[154:157], v[34:49]
	ds_write_b128 v129, v[86:89]
	ds_write_b128 v129, v[82:85] offset:18432
	v_lshl_add_u64 v[86:87], v[94:95], 0, v[114:115]
	global_load_dwordx4 v[86:89], v[86:87], off
	v_mfma_f32_32x32x16_bf16 v[2:17], v[150:153], v[168:171], v[2:17]
	ds_write_b128 v130, v[74:77] offset:18432
	v_add_co_u32_e32 v74, vcc, s5, v120
	s_mov_b32 s5, 0x1d000
	s_nop 0
	v_addc_co_u32_e32 v75, vcc, 0, v121, vcc
	v_add_co_u32_e32 v82, vcc, s5, v120
	s_waitcnt vmcnt(3)
	ds_write_b128 v130, v[78:81]
	v_mfma_f32_32x32x16_bf16 v[18:33], v[158:161], v[168:171], v[18:33]
	ds_write_b128 v131, v[70:73]
	v_lshl_add_u64 v[70:71], v[94:95], 0, v[118:119]
	v_lshl_add_u64 v[78:79], v[94:95], 0, v[116:117]
	v_addc_co_u32_e32 v83, vcc, 0, v121, vcc
	v_lshl_add_u64 v[94:95], v[94:95], 0, v[112:113]
	global_load_dwordx4 v[74:77], v[74:75], off
	s_waitcnt vmcnt(3)
	ds_write_b128 v131, v[66:69] offset:18432
	global_load_dwordx4 v[82:85], v[82:83], off
	s_waitcnt lgkmcnt(10)
	v_mfma_f32_32x32x16_bf16 v[50:65], v[162:165], v[172:175], v[50:65]
	global_load_dwordx4 v[94:97], v[94:95], off
	ds_read_b128 v[150:153], v133 offset:59936
	global_load_dwordx4 v[70:73], v[70:71], off
	ds_read_b128 v[154:157], v134 offset:41504
	global_load_dwordx4 v[78:81], v[78:79], off
	s_mov_b32 s5, 0x24000
	global_load_dwordx4 v[66:69], v[126:127], off offset:-4096
	s_waitcnt lgkmcnt(11)
	v_mfma_f32_32x32x16_bf16 v[34:49], v[176:179], v[172:175], v[34:49]
	ds_read_b128 v[158:161], v133 offset:55328
	ds_read_b128 v[168:171], v134 offset:36896
	v_add_co_u32_e32 v124, vcc, s5, v120
	s_mov_b32 s5, 0x22000
	s_nop 0
	v_addc_co_u32_e32 v125, vcc, 0, v121, vcc
	s_waitcnt lgkmcnt(12)
	v_mfma_f32_32x32x16_bf16 v[2:17], v[162:165], v[180:183], v[2:17]
	ds_read_b128 v[162:165], v133 offset:55360
	ds_read_b128 v[172:175], v134 offset:36928
	v_mfma_f32_32x32x16_bf16 v[18:33], v[176:179], v[180:183], v[18:33]
	ds_read_b128 v[176:179], v133 offset:59968
	ds_read_b128 v[180:183], v134 offset:41536
	s_waitcnt lgkmcnt(4)
	v_mfma_f32_32x32x16_bf16 v[50:65], v[158:161], v[168:171], v[50:65]
	v_mfma_f32_32x32x16_bf16 v[34:49], v[150:153], v[168:171], v[34:49]
	ds_read_b128 v[168:171], v134 offset:41568
	v_mfma_f32_32x32x16_bf16 v[2:17], v[158:161], v[154:157], v[2:17]
	ds_read_b128 v[158:161], v133 offset:60000
	v_mfma_f32_32x32x16_bf16 v[18:33], v[150:153], v[154:157], v[18:33]
	ds_read_b128 v[150:153], v133 offset:55392
	ds_read_b128 v[154:157], v134 offset:36960
	s_waitcnt lgkmcnt(0)
	s_barrier
	v_mfma_f32_32x32x16_bf16 v[50:65], v[162:165], v[172:175], v[50:65]
	v_mfma_f32_32x32x16_bf16 v[34:49], v[176:179], v[172:175], v[34:49]
	ds_read_b128 v[172:175], v144
	v_mfma_f32_32x32x16_bf16 v[2:17], v[162:165], v[180:183], v[2:17]
	ds_read_b128 v[162:165], v143 offset:18432
	v_mfma_f32_32x32x16_bf16 v[18:33], v[176:179], v[180:183], v[18:33]
	ds_read_b128 v[176:179], v143 offset:23040
	ds_read_b128 v[180:183], v144 offset:4608
	v_mfma_f32_32x32x16_bf16 v[50:65], v[150:153], v[154:157], v[50:65]
	s_waitcnt vmcnt(3)
	ds_write_b128 v128, v[94:97] offset:36864
	ds_write_b128 v128, v[90:93] offset:55296
	v_lshl_add_u64 v[94:95], v[122:123], 0, s[6:7]
	global_load_dwordx4 v[90:93], v[126:127], off
	s_mov_b64 s[6:7], 0x24000
	v_mfma_f32_32x32x16_bf16 v[34:49], v[158:161], v[154:157], v[34:49]
	ds_write_b128 v129, v[86:89] offset:36864
	ds_write_b128 v129, v[82:85] offset:55296
	v_lshl_add_u64 v[86:87], v[94:95], 0, v[114:115]
	global_load_dwordx4 v[86:89], v[86:87], off
	v_mfma_f32_32x32x16_bf16 v[2:17], v[150:153], v[168:171], v[2:17]
	ds_write_b128 v130, v[74:77] offset:55296
	v_add_co_u32_e32 v74, vcc, s5, v120
	s_mov_b32 s5, 0x21000
	s_nop 0
	v_addc_co_u32_e32 v75, vcc, 0, v121, vcc
	v_add_co_u32_e32 v82, vcc, s5, v120
	s_waitcnt vmcnt(3)
	ds_write_b128 v130, v[78:81] offset:36864
	v_mfma_f32_32x32x16_bf16 v[18:33], v[158:161], v[168:171], v[18:33]
	ds_write_b128 v131, v[70:73] offset:36864
	v_lshl_add_u64 v[70:71], v[94:95], 0, v[118:119]
	v_lshl_add_u64 v[78:79], v[94:95], 0, v[116:117]
	v_addc_co_u32_e32 v83, vcc, 0, v121, vcc
	v_lshl_add_u64 v[94:95], v[94:95], 0, v[112:113]
	global_load_dwordx4 v[74:77], v[74:75], off
	s_waitcnt vmcnt(3)
	ds_write_b128 v131, v[66:69] offset:55296
	global_load_dwordx4 v[82:85], v[82:83], off
	s_waitcnt lgkmcnt(10)
	v_mfma_f32_32x32x16_bf16 v[50:65], v[162:165], v[172:175], v[50:65]
	global_load_dwordx4 v[94:97], v[94:95], off
	ds_read_b128 v[150:153], v133 offset:23072
	global_load_dwordx4 v[70:73], v[70:71], off
	ds_read_b128 v[154:157], v134 offset:4640
	global_load_dwordx4 v[78:81], v[78:79], off
	s_mov_b32 s5, 0x28000
	global_load_dwordx4 v[66:69], v[124:125], off offset:-4096
	s_waitcnt lgkmcnt(11)
	v_mfma_f32_32x32x16_bf16 v[34:49], v[176:179], v[172:175], v[34:49]
	ds_read_b128 v[158:161], v133 offset:18464
	ds_read_b128 v[168:171], v134 offset:32
	v_add_co_u32_e32 v126, vcc, s5, v120
	s_mov_b32 s5, 0x26000
	s_nop 0
	v_addc_co_u32_e32 v127, vcc, 0, v121, vcc
	s_waitcnt lgkmcnt(12)
	v_mfma_f32_32x32x16_bf16 v[2:17], v[162:165], v[180:183], v[2:17]
	ds_read_b128 v[162:165], v133 offset:18496
	ds_read_b128 v[172:175], v134 offset:64
	v_mfma_f32_32x32x16_bf16 v[18:33], v[176:179], v[180:183], v[18:33]
	ds_read_b128 v[176:179], v133 offset:23104
	ds_read_b128 v[180:183], v134 offset:4672
	s_waitcnt lgkmcnt(4)
	v_mfma_f32_32x32x16_bf16 v[50:65], v[158:161], v[168:171], v[50:65]
	v_mfma_f32_32x32x16_bf16 v[34:49], v[150:153], v[168:171], v[34:49]
	ds_read_b128 v[168:171], v134 offset:4704
	v_mfma_f32_32x32x16_bf16 v[2:17], v[158:161], v[154:157], v[2:17]
	ds_read_b128 v[158:161], v133 offset:23136
	v_mfma_f32_32x32x16_bf16 v[18:33], v[150:153], v[154:157], v[18:33]
	ds_read_b128 v[150:153], v133 offset:18528
	ds_read_b128 v[154:157], v134 offset:96
	s_waitcnt lgkmcnt(0)
	s_barrier
	v_mfma_f32_32x32x16_bf16 v[50:65], v[162:165], v[172:175], v[50:65]
	v_mfma_f32_32x32x16_bf16 v[34:49], v[176:179], v[172:175], v[34:49]
	ds_read_b128 v[172:175], v144 offset:36864
	v_mfma_f32_32x32x16_bf16 v[2:17], v[162:165], v[180:183], v[2:17]
	ds_read_b128 v[162:165], v143 offset:55296
	v_mfma_f32_32x32x16_bf16 v[18:33], v[176:179], v[180:183], v[18:33]
	ds_read_b128 v[176:179], v143 offset:59904
	ds_read_b128 v[180:183], v144 offset:41472
	v_mfma_f32_32x32x16_bf16 v[50:65], v[150:153], v[154:157], v[50:65]
	s_waitcnt vmcnt(3)
	ds_write_b128 v128, v[94:97]
	ds_write_b128 v128, v[90:93] offset:18432
	v_lshl_add_u64 v[94:95], v[122:123], 0, s[6:7]
	global_load_dwordx4 v[90:93], v[124:125], off
	s_mov_b64 s[6:7], 0x28000
	v_mfma_f32_32x32x16_bf16 v[34:49], v[158:161], v[154:157], v[34:49]
	ds_write_b128 v129, v[86:89]
	ds_write_b128 v129, v[82:85] offset:18432
	v_lshl_add_u64 v[86:87], v[94:95], 0, v[114:115]
	global_load_dwordx4 v[86:89], v[86:87], off
	v_mfma_f32_32x32x16_bf16 v[2:17], v[150:153], v[168:171], v[2:17]
	ds_write_b128 v130, v[74:77] offset:18432
	v_add_co_u32_e32 v74, vcc, s5, v120
	s_mov_b32 s5, 0x25000
	s_nop 0
	v_addc_co_u32_e32 v75, vcc, 0, v121, vcc
	v_add_co_u32_e32 v82, vcc, s5, v120
	s_waitcnt vmcnt(3)
	ds_write_b128 v130, v[78:81]
	v_mfma_f32_32x32x16_bf16 v[18:33], v[158:161], v[168:171], v[18:33]
	ds_write_b128 v131, v[70:73]
	v_lshl_add_u64 v[70:71], v[94:95], 0, v[118:119]
	v_lshl_add_u64 v[78:79], v[94:95], 0, v[116:117]
	v_addc_co_u32_e32 v83, vcc, 0, v121, vcc
	v_lshl_add_u64 v[94:95], v[94:95], 0, v[112:113]
	global_load_dwordx4 v[74:77], v[74:75], off
	s_waitcnt vmcnt(3)
	ds_write_b128 v131, v[66:69] offset:18432
	global_load_dwordx4 v[82:85], v[82:83], off
	s_waitcnt lgkmcnt(10)
	v_mfma_f32_32x32x16_bf16 v[50:65], v[162:165], v[172:175], v[50:65]
	global_load_dwordx4 v[94:97], v[94:95], off
	ds_read_b128 v[150:153], v133 offset:59936
	global_load_dwordx4 v[70:73], v[70:71], off
	ds_read_b128 v[154:157], v134 offset:41504
	global_load_dwordx4 v[78:81], v[78:79], off
	s_mov_b32 s5, 0x2c000
	global_load_dwordx4 v[66:69], v[126:127], off offset:-4096
	s_waitcnt lgkmcnt(11)
	v_mfma_f32_32x32x16_bf16 v[34:49], v[176:179], v[172:175], v[34:49]
	ds_read_b128 v[158:161], v133 offset:55328
	ds_read_b128 v[168:171], v134 offset:36896
	v_add_co_u32_e32 v124, vcc, s5, v120
	s_mov_b32 s5, 0x2a000
	s_nop 0
	v_addc_co_u32_e32 v125, vcc, 0, v121, vcc
	s_waitcnt lgkmcnt(12)
	v_mfma_f32_32x32x16_bf16 v[2:17], v[162:165], v[180:183], v[2:17]
	ds_read_b128 v[162:165], v133 offset:55360
	ds_read_b128 v[172:175], v134 offset:36928
	v_mfma_f32_32x32x16_bf16 v[18:33], v[176:179], v[180:183], v[18:33]
	ds_read_b128 v[176:179], v133 offset:59968
	ds_read_b128 v[180:183], v134 offset:41536
	s_waitcnt lgkmcnt(4)
	v_mfma_f32_32x32x16_bf16 v[50:65], v[158:161], v[168:171], v[50:65]
	v_mfma_f32_32x32x16_bf16 v[34:49], v[150:153], v[168:171], v[34:49]
	ds_read_b128 v[168:171], v134 offset:41568
	v_mfma_f32_32x32x16_bf16 v[2:17], v[158:161], v[154:157], v[2:17]
	ds_read_b128 v[158:161], v133 offset:60000
	v_mfma_f32_32x32x16_bf16 v[18:33], v[150:153], v[154:157], v[18:33]
	ds_read_b128 v[150:153], v133 offset:55392
	ds_read_b128 v[154:157], v134 offset:36960
	s_waitcnt lgkmcnt(0)
	s_barrier
	v_mfma_f32_32x32x16_bf16 v[50:65], v[162:165], v[172:175], v[50:65]
	v_mfma_f32_32x32x16_bf16 v[34:49], v[176:179], v[172:175], v[34:49]
	ds_read_b128 v[172:175], v144
	v_mfma_f32_32x32x16_bf16 v[2:17], v[162:165], v[180:183], v[2:17]
	ds_read_b128 v[162:165], v143 offset:18432
	v_mfma_f32_32x32x16_bf16 v[18:33], v[176:179], v[180:183], v[18:33]
	ds_read_b128 v[176:179], v143 offset:23040
	ds_read_b128 v[180:183], v144 offset:4608
	v_mfma_f32_32x32x16_bf16 v[50:65], v[150:153], v[154:157], v[50:65]
	s_waitcnt vmcnt(3)
	ds_write_b128 v128, v[94:97] offset:36864
	ds_write_b128 v128, v[90:93] offset:55296
	v_lshl_add_u64 v[94:95], v[122:123], 0, s[6:7]
	global_load_dwordx4 v[90:93], v[126:127], off
	s_mov_b64 s[6:7], 0x2c000
	v_mfma_f32_32x32x16_bf16 v[34:49], v[158:161], v[154:157], v[34:49]
	ds_write_b128 v129, v[86:89] offset:36864
	ds_write_b128 v129, v[82:85] offset:55296
	v_lshl_add_u64 v[86:87], v[94:95], 0, v[114:115]
	global_load_dwordx4 v[86:89], v[86:87], off
	v_mfma_f32_32x32x16_bf16 v[2:17], v[150:153], v[168:171], v[2:17]
	ds_write_b128 v130, v[74:77] offset:55296
	v_add_co_u32_e32 v74, vcc, s5, v120
	s_mov_b32 s5, 0x29000
	s_nop 0
	v_addc_co_u32_e32 v75, vcc, 0, v121, vcc
	v_add_co_u32_e32 v82, vcc, s5, v120
	s_waitcnt vmcnt(3)
	ds_write_b128 v130, v[78:81] offset:36864
	v_mfma_f32_32x32x16_bf16 v[18:33], v[158:161], v[168:171], v[18:33]
	ds_write_b128 v131, v[70:73] offset:36864
	v_lshl_add_u64 v[70:71], v[94:95], 0, v[118:119]
	v_lshl_add_u64 v[78:79], v[94:95], 0, v[116:117]
	v_addc_co_u32_e32 v83, vcc, 0, v121, vcc
	v_lshl_add_u64 v[94:95], v[94:95], 0, v[112:113]
	global_load_dwordx4 v[74:77], v[74:75], off
	s_waitcnt vmcnt(3)
	ds_write_b128 v131, v[66:69] offset:55296
	global_load_dwordx4 v[82:85], v[82:83], off
	s_waitcnt lgkmcnt(10)
	v_mfma_f32_32x32x16_bf16 v[50:65], v[162:165], v[172:175], v[50:65]
	global_load_dwordx4 v[94:97], v[94:95], off
	ds_read_b128 v[150:153], v133 offset:23072
	global_load_dwordx4 v[70:73], v[70:71], off
	ds_read_b128 v[154:157], v134 offset:4640
	global_load_dwordx4 v[78:81], v[78:79], off
	s_mov_b32 s5, 0x30000
	global_load_dwordx4 v[66:69], v[124:125], off offset:-4096
	s_waitcnt lgkmcnt(11)
	v_mfma_f32_32x32x16_bf16 v[34:49], v[176:179], v[172:175], v[34:49]
	ds_read_b128 v[158:161], v133 offset:18464
	ds_read_b128 v[168:171], v134 offset:32
	v_add_co_u32_e32 v126, vcc, s5, v120
	s_mov_b32 s5, 0x2e000
	s_nop 0
	v_addc_co_u32_e32 v127, vcc, 0, v121, vcc
	s_waitcnt lgkmcnt(12)
	v_mfma_f32_32x32x16_bf16 v[2:17], v[162:165], v[180:183], v[2:17]
	ds_read_b128 v[162:165], v133 offset:18496
	ds_read_b128 v[172:175], v134 offset:64
	v_mfma_f32_32x32x16_bf16 v[18:33], v[176:179], v[180:183], v[18:33]
	ds_read_b128 v[176:179], v133 offset:23104
	ds_read_b128 v[180:183], v134 offset:4672
	s_waitcnt lgkmcnt(4)
	v_mfma_f32_32x32x16_bf16 v[50:65], v[158:161], v[168:171], v[50:65]
	v_mfma_f32_32x32x16_bf16 v[34:49], v[150:153], v[168:171], v[34:49]
	ds_read_b128 v[168:171], v134 offset:4704
	v_mfma_f32_32x32x16_bf16 v[2:17], v[158:161], v[154:157], v[2:17]
	ds_read_b128 v[158:161], v133 offset:23136
	v_mfma_f32_32x32x16_bf16 v[18:33], v[150:153], v[154:157], v[18:33]
	ds_read_b128 v[150:153], v133 offset:18528
	ds_read_b128 v[154:157], v134 offset:96
	s_waitcnt lgkmcnt(0)
	s_barrier
	v_mfma_f32_32x32x16_bf16 v[50:65], v[162:165], v[172:175], v[50:65]
	v_mfma_f32_32x32x16_bf16 v[34:49], v[176:179], v[172:175], v[34:49]
	ds_read_b128 v[172:175], v144 offset:36864
	v_mfma_f32_32x32x16_bf16 v[2:17], v[162:165], v[180:183], v[2:17]
	ds_read_b128 v[162:165], v143 offset:55296
	v_mfma_f32_32x32x16_bf16 v[18:33], v[176:179], v[180:183], v[18:33]
	ds_read_b128 v[176:179], v143 offset:59904
	ds_read_b128 v[180:183], v144 offset:41472
	v_mfma_f32_32x32x16_bf16 v[50:65], v[150:153], v[154:157], v[50:65]
	s_waitcnt vmcnt(3)
	ds_write_b128 v128, v[94:97]
	ds_write_b128 v128, v[90:93] offset:18432
	v_lshl_add_u64 v[94:95], v[122:123], 0, s[6:7]
	global_load_dwordx4 v[90:93], v[124:125], off
	s_mov_b64 s[6:7], 0x30000
	v_mfma_f32_32x32x16_bf16 v[34:49], v[158:161], v[154:157], v[34:49]
	ds_write_b128 v129, v[86:89]
	ds_write_b128 v129, v[82:85] offset:18432
	v_lshl_add_u64 v[86:87], v[94:95], 0, v[114:115]
	global_load_dwordx4 v[86:89], v[86:87], off
	v_mfma_f32_32x32x16_bf16 v[2:17], v[150:153], v[168:171], v[2:17]
	ds_write_b128 v130, v[74:77] offset:18432
	v_add_co_u32_e32 v74, vcc, s5, v120
	s_mov_b32 s5, 0x2d000
	s_nop 0
	v_addc_co_u32_e32 v75, vcc, 0, v121, vcc
	v_add_co_u32_e32 v82, vcc, s5, v120
	s_waitcnt vmcnt(3)
	ds_write_b128 v130, v[78:81]
	v_mfma_f32_32x32x16_bf16 v[18:33], v[158:161], v[168:171], v[18:33]
	ds_write_b128 v131, v[70:73]
	v_lshl_add_u64 v[70:71], v[94:95], 0, v[118:119]
	v_lshl_add_u64 v[78:79], v[94:95], 0, v[116:117]
	v_addc_co_u32_e32 v83, vcc, 0, v121, vcc
	v_lshl_add_u64 v[94:95], v[94:95], 0, v[112:113]
	global_load_dwordx4 v[74:77], v[74:75], off
	s_waitcnt vmcnt(3)
	ds_write_b128 v131, v[66:69] offset:18432
	global_load_dwordx4 v[82:85], v[82:83], off
	s_waitcnt lgkmcnt(10)
	v_mfma_f32_32x32x16_bf16 v[50:65], v[162:165], v[172:175], v[50:65]
	global_load_dwordx4 v[94:97], v[94:95], off
	ds_read_b128 v[150:153], v133 offset:59936
	global_load_dwordx4 v[70:73], v[70:71], off
	ds_read_b128 v[154:157], v134 offset:41504
	global_load_dwordx4 v[78:81], v[78:79], off
	s_mov_b32 s5, 0x34000
	global_load_dwordx4 v[66:69], v[126:127], off offset:-4096
	s_waitcnt lgkmcnt(11)
	v_mfma_f32_32x32x16_bf16 v[34:49], v[176:179], v[172:175], v[34:49]
	ds_read_b128 v[158:161], v133 offset:55328
	ds_read_b128 v[168:171], v134 offset:36896
	v_add_co_u32_e32 v124, vcc, s5, v120
	s_mov_b32 s5, 0x32000
	s_nop 0
	v_addc_co_u32_e32 v125, vcc, 0, v121, vcc
	s_waitcnt lgkmcnt(12)
	v_mfma_f32_32x32x16_bf16 v[2:17], v[162:165], v[180:183], v[2:17]
	ds_read_b128 v[162:165], v133 offset:55360
	ds_read_b128 v[172:175], v134 offset:36928
	v_mfma_f32_32x32x16_bf16 v[18:33], v[176:179], v[180:183], v[18:33]
	ds_read_b128 v[176:179], v133 offset:59968
	ds_read_b128 v[180:183], v134 offset:41536
	s_waitcnt lgkmcnt(4)
	v_mfma_f32_32x32x16_bf16 v[50:65], v[158:161], v[168:171], v[50:65]
	v_mfma_f32_32x32x16_bf16 v[34:49], v[150:153], v[168:171], v[34:49]
	ds_read_b128 v[168:171], v134 offset:41568
	v_mfma_f32_32x32x16_bf16 v[2:17], v[158:161], v[154:157], v[2:17]
	ds_read_b128 v[158:161], v133 offset:60000
	v_mfma_f32_32x32x16_bf16 v[18:33], v[150:153], v[154:157], v[18:33]
	ds_read_b128 v[150:153], v133 offset:55392
	ds_read_b128 v[154:157], v134 offset:36960
	s_waitcnt lgkmcnt(0)
	s_barrier
	v_mfma_f32_32x32x16_bf16 v[50:65], v[162:165], v[172:175], v[50:65]
	v_mfma_f32_32x32x16_bf16 v[34:49], v[176:179], v[172:175], v[34:49]
	ds_read_b128 v[172:175], v144
	v_mfma_f32_32x32x16_bf16 v[2:17], v[162:165], v[180:183], v[2:17]
	ds_read_b128 v[162:165], v143 offset:18432
	v_mfma_f32_32x32x16_bf16 v[18:33], v[176:179], v[180:183], v[18:33]
	ds_read_b128 v[176:179], v143 offset:23040
	ds_read_b128 v[180:183], v144 offset:4608
	v_mfma_f32_32x32x16_bf16 v[50:65], v[150:153], v[154:157], v[50:65]
	s_waitcnt vmcnt(3)
	ds_write_b128 v128, v[94:97] offset:36864
	ds_write_b128 v128, v[90:93] offset:55296
	v_lshl_add_u64 v[94:95], v[122:123], 0, s[6:7]
	global_load_dwordx4 v[90:93], v[126:127], off
	s_mov_b64 s[6:7], 0x34000
	v_mfma_f32_32x32x16_bf16 v[34:49], v[158:161], v[154:157], v[34:49]
	ds_write_b128 v129, v[86:89] offset:36864
	ds_write_b128 v129, v[82:85] offset:55296
	v_lshl_add_u64 v[86:87], v[94:95], 0, v[114:115]
	global_load_dwordx4 v[86:89], v[86:87], off
	v_mfma_f32_32x32x16_bf16 v[2:17], v[150:153], v[168:171], v[2:17]
	ds_write_b128 v130, v[74:77] offset:55296
	v_add_co_u32_e32 v74, vcc, s5, v120
	s_mov_b32 s5, 0x31000
	s_nop 0
	v_addc_co_u32_e32 v75, vcc, 0, v121, vcc
	v_add_co_u32_e32 v82, vcc, s5, v120
	s_waitcnt vmcnt(3)
	ds_write_b128 v130, v[78:81] offset:36864
	v_mfma_f32_32x32x16_bf16 v[18:33], v[158:161], v[168:171], v[18:33]
	ds_write_b128 v131, v[70:73] offset:36864
	v_lshl_add_u64 v[70:71], v[94:95], 0, v[118:119]
	v_lshl_add_u64 v[78:79], v[94:95], 0, v[116:117]
	v_addc_co_u32_e32 v83, vcc, 0, v121, vcc
	v_lshl_add_u64 v[94:95], v[94:95], 0, v[112:113]
	global_load_dwordx4 v[74:77], v[74:75], off
	s_waitcnt vmcnt(3)
	ds_write_b128 v131, v[66:69] offset:55296
	global_load_dwordx4 v[82:85], v[82:83], off
	s_waitcnt lgkmcnt(10)
	v_mfma_f32_32x32x16_bf16 v[50:65], v[162:165], v[172:175], v[50:65]
	global_load_dwordx4 v[94:97], v[94:95], off
	ds_read_b128 v[150:153], v133 offset:23072
	global_load_dwordx4 v[70:73], v[70:71], off
	ds_read_b128 v[154:157], v134 offset:4640
	global_load_dwordx4 v[78:81], v[78:79], off
	s_mov_b32 s5, 0x38000
	global_load_dwordx4 v[66:69], v[124:125], off offset:-4096
	s_waitcnt lgkmcnt(11)
	v_mfma_f32_32x32x16_bf16 v[34:49], v[176:179], v[172:175], v[34:49]
	ds_read_b128 v[158:161], v133 offset:18464
	ds_read_b128 v[168:171], v134 offset:32
	v_add_co_u32_e32 v126, vcc, s5, v120
	s_mov_b32 s5, 0x36000
	s_nop 0
	v_addc_co_u32_e32 v127, vcc, 0, v121, vcc
	s_waitcnt lgkmcnt(12)
	v_mfma_f32_32x32x16_bf16 v[2:17], v[162:165], v[180:183], v[2:17]
	ds_read_b128 v[162:165], v133 offset:18496
	ds_read_b128 v[172:175], v134 offset:64
	v_mfma_f32_32x32x16_bf16 v[18:33], v[176:179], v[180:183], v[18:33]
	ds_read_b128 v[176:179], v133 offset:23104
	ds_read_b128 v[180:183], v134 offset:4672
	s_waitcnt lgkmcnt(4)
	v_mfma_f32_32x32x16_bf16 v[50:65], v[158:161], v[168:171], v[50:65]
	v_mfma_f32_32x32x16_bf16 v[34:49], v[150:153], v[168:171], v[34:49]
	ds_read_b128 v[168:171], v134 offset:4704
	v_mfma_f32_32x32x16_bf16 v[2:17], v[158:161], v[154:157], v[2:17]
	ds_read_b128 v[158:161], v133 offset:23136
	v_mfma_f32_32x32x16_bf16 v[18:33], v[150:153], v[154:157], v[18:33]
	ds_read_b128 v[150:153], v133 offset:18528
	ds_read_b128 v[154:157], v134 offset:96
	s_waitcnt lgkmcnt(0)
	s_barrier
	v_mfma_f32_32x32x16_bf16 v[50:65], v[162:165], v[172:175], v[50:65]
	v_mfma_f32_32x32x16_bf16 v[34:49], v[176:179], v[172:175], v[34:49]
	ds_read_b128 v[172:175], v144 offset:36864
	v_mfma_f32_32x32x16_bf16 v[2:17], v[162:165], v[180:183], v[2:17]
	ds_read_b128 v[162:165], v143 offset:55296
	v_mfma_f32_32x32x16_bf16 v[18:33], v[176:179], v[180:183], v[18:33]
	ds_read_b128 v[176:179], v143 offset:59904
	ds_read_b128 v[180:183], v144 offset:41472
	v_mfma_f32_32x32x16_bf16 v[50:65], v[150:153], v[154:157], v[50:65]
	s_waitcnt vmcnt(3)
	ds_write_b128 v128, v[94:97]
	ds_write_b128 v128, v[90:93] offset:18432
	v_lshl_add_u64 v[94:95], v[122:123], 0, s[6:7]
	global_load_dwordx4 v[90:93], v[124:125], off
	s_mov_b64 s[6:7], 0x38000
	v_mfma_f32_32x32x16_bf16 v[34:49], v[158:161], v[154:157], v[34:49]
	ds_write_b128 v129, v[86:89]
	ds_write_b128 v129, v[82:85] offset:18432
	v_lshl_add_u64 v[86:87], v[94:95], 0, v[114:115]
	global_load_dwordx4 v[86:89], v[86:87], off
	v_mfma_f32_32x32x16_bf16 v[2:17], v[150:153], v[168:171], v[2:17]
	ds_write_b128 v130, v[74:77] offset:18432
	v_add_co_u32_e32 v74, vcc, s5, v120
	s_mov_b32 s5, 0x35000
	s_nop 0
	v_addc_co_u32_e32 v75, vcc, 0, v121, vcc
	v_add_co_u32_e32 v82, vcc, s5, v120
	s_waitcnt vmcnt(3)
	ds_write_b128 v130, v[78:81]
	v_mfma_f32_32x32x16_bf16 v[18:33], v[158:161], v[168:171], v[18:33]
	ds_write_b128 v131, v[70:73]
	v_lshl_add_u64 v[70:71], v[94:95], 0, v[118:119]
	v_lshl_add_u64 v[78:79], v[94:95], 0, v[116:117]
	v_addc_co_u32_e32 v83, vcc, 0, v121, vcc
	v_lshl_add_u64 v[94:95], v[94:95], 0, v[112:113]
	global_load_dwordx4 v[74:77], v[74:75], off
	s_waitcnt vmcnt(3)
	ds_write_b128 v131, v[66:69] offset:18432
	global_load_dwordx4 v[82:85], v[82:83], off
	s_waitcnt lgkmcnt(10)
	v_mfma_f32_32x32x16_bf16 v[50:65], v[162:165], v[172:175], v[50:65]
	global_load_dwordx4 v[94:97], v[94:95], off
	ds_read_b128 v[150:153], v133 offset:59936
	global_load_dwordx4 v[70:73], v[70:71], off
	ds_read_b128 v[154:157], v134 offset:41504
	global_load_dwordx4 v[78:81], v[78:79], off
	s_mov_b32 s5, 0x3c000
	global_load_dwordx4 v[66:69], v[126:127], off offset:-4096
	s_waitcnt lgkmcnt(11)
	v_mfma_f32_32x32x16_bf16 v[34:49], v[176:179], v[172:175], v[34:49]
	ds_read_b128 v[158:161], v133 offset:55328
	ds_read_b128 v[168:171], v134 offset:36896
	v_add_co_u32_e32 v124, vcc, s5, v120
	s_mov_b32 s5, 0x3a000
	s_nop 0
	v_addc_co_u32_e32 v125, vcc, 0, v121, vcc
	s_waitcnt lgkmcnt(12)
	v_mfma_f32_32x32x16_bf16 v[2:17], v[162:165], v[180:183], v[2:17]
	ds_read_b128 v[162:165], v133 offset:55360
	ds_read_b128 v[172:175], v134 offset:36928
	v_mfma_f32_32x32x16_bf16 v[18:33], v[176:179], v[180:183], v[18:33]
	ds_read_b128 v[176:179], v133 offset:59968
	ds_read_b128 v[180:183], v134 offset:41536
	s_waitcnt lgkmcnt(4)
	v_mfma_f32_32x32x16_bf16 v[50:65], v[158:161], v[168:171], v[50:65]
	v_mfma_f32_32x32x16_bf16 v[34:49], v[150:153], v[168:171], v[34:49]
	ds_read_b128 v[168:171], v134 offset:41568
	v_mfma_f32_32x32x16_bf16 v[2:17], v[158:161], v[154:157], v[2:17]
	ds_read_b128 v[158:161], v133 offset:60000
	v_mfma_f32_32x32x16_bf16 v[18:33], v[150:153], v[154:157], v[18:33]
	ds_read_b128 v[150:153], v133 offset:55392
	ds_read_b128 v[154:157], v134 offset:36960
	s_waitcnt lgkmcnt(0)
	s_barrier
	v_mfma_f32_32x32x16_bf16 v[50:65], v[162:165], v[172:175], v[50:65]
	v_mfma_f32_32x32x16_bf16 v[34:49], v[176:179], v[172:175], v[34:49]
	ds_read_b128 v[172:175], v144
	v_mfma_f32_32x32x16_bf16 v[2:17], v[162:165], v[180:183], v[2:17]
	ds_read_b128 v[162:165], v143 offset:18432
	v_mfma_f32_32x32x16_bf16 v[18:33], v[176:179], v[180:183], v[18:33]
	ds_read_b128 v[176:179], v143 offset:23040
	ds_read_b128 v[180:183], v144 offset:4608
	v_mfma_f32_32x32x16_bf16 v[50:65], v[150:153], v[154:157], v[50:65]
	s_waitcnt vmcnt(3)
	ds_write_b128 v128, v[94:97] offset:36864
	ds_write_b128 v128, v[90:93] offset:55296
	v_lshl_add_u64 v[94:95], v[122:123], 0, s[6:7]
	global_load_dwordx4 v[90:93], v[126:127], off
	s_mov_b64 s[6:7], 0x3c000
	v_mfma_f32_32x32x16_bf16 v[34:49], v[158:161], v[154:157], v[34:49]
	ds_write_b128 v129, v[86:89] offset:36864
	ds_write_b128 v129, v[82:85] offset:55296
	v_lshl_add_u64 v[86:87], v[94:95], 0, v[114:115]
	global_load_dwordx4 v[86:89], v[86:87], off
	v_mfma_f32_32x32x16_bf16 v[2:17], v[150:153], v[168:171], v[2:17]
	ds_write_b128 v130, v[74:77] offset:55296
	v_add_co_u32_e32 v74, vcc, s5, v120
	s_mov_b32 s5, 0x39000
	s_nop 0
	v_addc_co_u32_e32 v75, vcc, 0, v121, vcc
	v_add_co_u32_e32 v82, vcc, s5, v120
	s_waitcnt vmcnt(3)
	ds_write_b128 v130, v[78:81] offset:36864
	v_mfma_f32_32x32x16_bf16 v[18:33], v[158:161], v[168:171], v[18:33]
	ds_write_b128 v131, v[70:73] offset:36864
	v_lshl_add_u64 v[70:71], v[94:95], 0, v[118:119]
	v_lshl_add_u64 v[78:79], v[94:95], 0, v[116:117]
	v_addc_co_u32_e32 v83, vcc, 0, v121, vcc
	v_lshl_add_u64 v[94:95], v[94:95], 0, v[112:113]
	s_waitcnt vmcnt(2)
	ds_write_b128 v131, v[66:69] offset:55296
	global_load_dwordx4 v[66:69], v[124:125], off offset:-4096
	s_waitcnt lgkmcnt(10)
	v_mfma_f32_32x32x16_bf16 v[50:65], v[162:165], v[172:175], v[50:65]
	global_load_dwordx4 v[74:77], v[74:75], off
	ds_read_b128 v[150:153], v133 offset:23072
	global_load_dwordx4 v[78:81], v[78:79], off
	ds_read_b128 v[154:157], v134 offset:4640
	global_load_dwordx4 v[82:85], v[82:83], off
	s_mov_b32 s5, 0x3f000
	global_load_dwordx4 v[94:97], v[94:95], off
	s_waitcnt lgkmcnt(11)
	v_mfma_f32_32x32x16_bf16 v[34:49], v[176:179], v[172:175], v[34:49]
	global_load_dwordx4 v[70:73], v[70:71], off
	ds_read_b128 v[158:161], v133 offset:18464
	ds_read_b128 v[168:171], v134 offset:32
	s_waitcnt lgkmcnt(12)
	v_mfma_f32_32x32x16_bf16 v[2:17], v[162:165], v[180:183], v[2:17]
	ds_read_b128 v[162:165], v133 offset:18496
	ds_read_b128 v[172:175], v134 offset:64
	v_mfma_f32_32x32x16_bf16 v[18:33], v[176:179], v[180:183], v[18:33]
	ds_read_b128 v[176:179], v133 offset:23104
	ds_read_b128 v[180:183], v134 offset:4672
	s_waitcnt lgkmcnt(4)
	v_mfma_f32_32x32x16_bf16 v[50:65], v[158:161], v[168:171], v[50:65]
	v_mfma_f32_32x32x16_bf16 v[34:49], v[150:153], v[168:171], v[34:49]
	ds_read_b128 v[168:171], v134 offset:4704
	v_mfma_f32_32x32x16_bf16 v[2:17], v[158:161], v[154:157], v[2:17]
	ds_read_b128 v[158:161], v133 offset:23136
	v_mfma_f32_32x32x16_bf16 v[18:33], v[150:153], v[154:157], v[18:33]
	ds_read_b128 v[150:153], v133 offset:18528
	ds_read_b128 v[154:157], v134 offset:96
	s_waitcnt lgkmcnt(0)
	s_barrier
	v_mfma_f32_32x32x16_bf16 v[50:65], v[162:165], v[172:175], v[50:65]
	v_mfma_f32_32x32x16_bf16 v[34:49], v[176:179], v[172:175], v[34:49]
	ds_read_b128 v[172:175], v144 offset:36864
	v_mfma_f32_32x32x16_bf16 v[2:17], v[162:165], v[180:183], v[2:17]
	ds_read_b128 v[162:165], v143 offset:55296
	v_mfma_f32_32x32x16_bf16 v[18:33], v[176:179], v[180:183], v[18:33]
	ds_read_b128 v[176:179], v143 offset:59904
	ds_read_b128 v[180:183], v144 offset:41472
	v_mfma_f32_32x32x16_bf16 v[50:65], v[150:153], v[154:157], v[50:65]
	s_waitcnt vmcnt(1)
	ds_write_b128 v128, v[94:97]
	ds_write_b128 v128, v[90:93] offset:18432
	v_lshl_add_u64 v[94:95], v[122:123], 0, s[6:7]
	global_load_dwordx4 v[90:93], v[124:125], off
	v_mfma_f32_32x32x16_bf16 v[34:49], v[158:161], v[154:157], v[34:49]
	ds_write_b128 v129, v[86:89]
	ds_write_b128 v129, v[82:85] offset:18432
	v_lshl_add_u64 v[86:87], v[94:95], 0, v[114:115]
	global_load_dwordx4 v[86:89], v[86:87], off
	v_mfma_f32_32x32x16_bf16 v[2:17], v[150:153], v[168:171], v[2:17]
	ds_write_b128 v130, v[78:81]
	ds_write_b128 v130, v[74:77] offset:18432
	v_lshl_add_u64 v[78:79], v[94:95], 0, v[116:117]
	global_load_dwordx4 v[78:81], v[78:79], off
	v_mfma_f32_32x32x16_bf16 v[18:33], v[158:161], v[168:171], v[18:33]
	ds_write_b128 v131, v[66:69] offset:18432
	v_add_co_u32_e32 v66, vcc, s5, v120
	s_mov_b32 s5, 0x3e000
	s_nop 0
	v_addc_co_u32_e32 v67, vcc, 0, v121, vcc
	v_add_co_u32_e32 v74, vcc, s5, v120
	s_mov_b32 s5, 0x3d000
	s_nop 0
	v_addc_co_u32_e32 v75, vcc, 0, v121, vcc
	s_waitcnt vmcnt(3)
	ds_write_b128 v131, v[70:73]
	v_lshl_add_u64 v[70:71], v[94:95], 0, v[118:119]
	v_add_co_u32_e32 v82, vcc, s5, v120
	v_lshl_add_u64 v[94:95], v[94:95], 0, v[112:113]
	s_nop 0
	v_addc_co_u32_e32 v83, vcc, 0, v121, vcc
	global_load_dwordx4 v[94:97], v[94:95], off
	s_waitcnt lgkmcnt(10)
	v_mfma_f32_32x32x16_bf16 v[50:65], v[162:165], v[172:175], v[50:65]
	global_load_dwordx4 v[74:77], v[74:75], off
	ds_read_b128 v[120:123], v133 offset:59936
	global_load_dwordx4 v[82:85], v[82:83], off
	ds_read_b128 v[124:127], v134 offset:41504
	global_load_dwordx4 v[66:69], v[66:67], off
	s_nop 0
	global_load_dwordx4 v[70:73], v[70:71], off
	s_waitcnt lgkmcnt(11)
	v_mfma_f32_32x32x16_bf16 v[34:49], v[176:179], v[172:175], v[34:49]
	ds_read_b128 v[150:153], v133 offset:55328
	ds_read_b128 v[154:157], v133 offset:55360
	s_waitcnt lgkmcnt(12)
	v_mfma_f32_32x32x16_bf16 v[2:17], v[162:165], v[180:183], v[2:17]
	ds_read_b128 v[158:161], v134 offset:36896
	ds_read_b128 v[162:165], v134 offset:36928
	v_mfma_f32_32x32x16_bf16 v[18:33], v[176:179], v[180:183], v[18:33]
	ds_read_b128 v[168:171], v133 offset:59968
	ds_read_b128 v[172:175], v134 offset:41536
	s_waitcnt lgkmcnt(3)
	v_mfma_f32_32x32x16_bf16 v[50:65], v[150:153], v[158:161], v[50:65]
	v_mfma_f32_32x32x16_bf16 v[34:49], v[120:123], v[158:161], v[34:49]
	ds_read_b128 v[158:161], v134 offset:41568
	v_mfma_f32_32x32x16_bf16 v[2:17], v[150:153], v[124:127], v[2:17]
	ds_read_b128 v[150:153], v133 offset:60000
	v_mfma_f32_32x32x16_bf16 v[18:33], v[120:123], v[124:127], v[18:33]
	ds_read_b128 v[120:123], v133 offset:55392
	ds_read_b128 v[124:127], v134 offset:36960
	s_waitcnt lgkmcnt(0)
	s_barrier
	v_mfma_f32_32x32x16_bf16 v[50:65], v[154:157], v[162:165], v[50:65]
	v_mfma_f32_32x32x16_bf16 v[34:49], v[168:171], v[162:165], v[34:49]
	ds_read_b128 v[162:165], v144
	v_mfma_f32_32x32x16_bf16 v[2:17], v[154:157], v[172:175], v[2:17]
	ds_read_b128 v[154:157], v143 offset:18432
	v_mfma_f32_32x32x16_bf16 v[18:33], v[168:171], v[172:175], v[18:33]
	ds_read_b128 v[168:171], v143 offset:23040
	ds_read_b128 v[172:175], v144 offset:4608
	v_mfma_f32_32x32x16_bf16 v[50:65], v[120:123], v[124:127], v[50:65]
	s_waitcnt vmcnt(4)
	ds_write_b128 v128, v[94:97] offset:36864
	ds_write_b128 v128, v[90:93] offset:55296
	v_mfma_f32_32x32x16_bf16 v[34:49], v[150:153], v[124:127], v[34:49]
	ds_write_b128 v129, v[86:89] offset:36864
	s_waitcnt vmcnt(2)
	ds_write_b128 v129, v[82:85] offset:55296
	v_mfma_f32_32x32x16_bf16 v[2:17], v[120:123], v[158:161], v[2:17]
	ds_write_b128 v130, v[78:81] offset:36864
	ds_write_b128 v130, v[74:77] offset:55296
	v_mfma_f32_32x32x16_bf16 v[18:33], v[150:153], v[158:161], v[18:33]
	s_waitcnt vmcnt(0)
	ds_write_b128 v131, v[70:73] offset:36864
	ds_write_b128 v131, v[66:69] offset:55296
	s_waitcnt lgkmcnt(10)
	v_mfma_f32_32x32x16_bf16 v[50:65], v[154:157], v[162:165], v[50:65]
	ds_read_b128 v[66:69], v133 offset:23072
	ds_read_b128 v[70:73], v134 offset:4640
	s_waitcnt lgkmcnt(11)
	v_mfma_f32_32x32x16_bf16 v[34:49], v[168:171], v[162:165], v[34:49]
	ds_read_b128 v[74:77], v133 offset:18464
	ds_read_b128 v[78:81], v133 offset:18496
	s_waitcnt lgkmcnt(12)
	v_mfma_f32_32x32x16_bf16 v[2:17], v[154:157], v[172:175], v[2:17]
	ds_read_b128 v[82:85], v134 offset:32
	ds_read_b128 v[86:89], v134 offset:64
	v_mfma_f32_32x32x16_bf16 v[18:33], v[168:171], v[172:175], v[18:33]
	ds_read_b128 v[90:93], v133 offset:23104
	ds_read_b128 v[94:97], v134 offset:4672
	s_waitcnt lgkmcnt(3)
	v_mfma_f32_32x32x16_bf16 v[50:65], v[74:77], v[82:85], v[50:65]
	v_mfma_f32_32x32x16_bf16 v[34:49], v[66:69], v[82:85], v[34:49]
	ds_read_b128 v[82:85], v134 offset:4704
	v_mfma_f32_32x32x16_bf16 v[2:17], v[74:77], v[70:73], v[2:17]
	ds_read_b128 v[74:77], v133 offset:23136
	v_mfma_f32_32x32x16_bf16 v[18:33], v[66:69], v[70:73], v[18:33]
	ds_read_b128 v[66:69], v133 offset:18528
	ds_read_b128 v[70:73], v134 offset:96
	s_waitcnt lgkmcnt(0)
	s_barrier
	v_mfma_f32_32x32x16_bf16 v[50:65], v[78:81], v[86:89], v[50:65]
	v_mfma_f32_32x32x16_bf16 v[34:49], v[90:93], v[86:89], v[34:49]
	ds_read_b128 v[86:89], v144 offset:36864
	v_mfma_f32_32x32x16_bf16 v[2:17], v[78:81], v[94:97], v[2:17]
	ds_read_b128 v[78:81], v143 offset:55296
	v_mfma_f32_32x32x16_bf16 v[18:33], v[90:93], v[94:97], v[18:33]
	ds_read_b128 v[90:93], v143 offset:59904
	ds_read_b128 v[94:97], v144 offset:41472
	v_mfma_f32_32x32x16_bf16 v[50:65], v[66:69], v[70:73], v[50:65]
	v_mfma_f32_32x32x16_bf16 v[34:49], v[74:77], v[70:73], v[34:49]
	ds_read_b128 v[70:73], v134 offset:41504
	v_mfma_f32_32x32x16_bf16 v[2:17], v[66:69], v[82:85], v[2:17]
	ds_read_b128 v[66:69], v133 offset:59936
	v_mfma_f32_32x32x16_bf16 v[18:33], v[74:77], v[82:85], v[18:33]
	ds_read_b128 v[74:77], v133 offset:55328
	ds_read_b128 v[82:85], v134 offset:36896
	s_waitcnt lgkmcnt(6)
	v_mfma_f32_32x32x16_bf16 v[50:65], v[78:81], v[86:89], v[50:65]
	s_waitcnt lgkmcnt(5)
	v_mfma_f32_32x32x16_bf16 v[34:49], v[90:93], v[86:89], v[34:49]
	ds_read_b128 v[86:89], v134 offset:36928
	s_waitcnt lgkmcnt(5)
	v_mfma_f32_32x32x16_bf16 v[2:17], v[78:81], v[94:97], v[2:17]
	ds_read_b128 v[78:81], v133 offset:55360
	v_mfma_f32_32x32x16_bf16 v[18:33], v[90:93], v[94:97], v[18:33]
	ds_read_b128 v[90:93], v133 offset:59968
	ds_read_b128 v[94:97], v134 offset:41536
	s_waitcnt lgkmcnt(4)
	v_mfma_f32_32x32x16_bf16 v[50:65], v[74:77], v[82:85], v[50:65]
	v_mfma_f32_32x32x16_bf16 v[34:49], v[66:69], v[82:85], v[34:49]
	ds_read_b128 v[82:85], v134 offset:41568
	v_mfma_f32_32x32x16_bf16 v[2:17], v[74:77], v[70:73], v[2:17]
	ds_read_b128 v[74:77], v133 offset:60000
	v_mfma_f32_32x32x16_bf16 v[18:33], v[66:69], v[70:73], v[18:33]
	ds_read_b128 v[66:69], v133 offset:55392
	ds_read_b128 v[70:73], v134 offset:36960
	s_waitcnt lgkmcnt(0)
	s_barrier
	v_mfma_f32_32x32x16_bf16 v[50:65], v[78:81], v[86:89], v[50:65]
	v_mfma_f32_32x32x16_bf16 v[34:49], v[90:93], v[86:89], v[34:49]
	v_mfma_f32_32x32x16_bf16 v[2:17], v[78:81], v[94:97], v[2:17]
	v_mfma_f32_32x32x16_bf16 v[18:33], v[90:93], v[94:97], v[18:33]
	v_mfma_f32_32x32x16_bf16 v[50:65], v[66:69], v[70:73], v[50:65]
	v_mfma_f32_32x32x16_bf16 v[34:49], v[74:77], v[70:73], v[34:49]
	v_or_b32_e32 v72, s4, v105
	v_mfma_f32_32x32x16_bf16 v[2:17], v[66:69], v[82:85], v[2:17]
	v_lshlrev_b32_e32 v67, 1, v72
	v_mfma_f32_32x32x16_bf16 v[18:33], v[74:77], v[82:85], v[18:33]
	v_lshl_add_u32 v75, s2, 7, v132
	s_movk_i32 s2, 0x7ff
	v_lshrrev_b32_e32 v66, 13, v75
	v_cmp_lt_i32_e64 s[8:9], s2, v72
	s_movk_i32 s2, 0xc00
	v_cmp_eq_u32_e64 s[6:7], s2, v72
	v_lshlrev_b32_e32 v74, 4, v66
	v_lshlrev_b32_e32 v66, 11, v66
	s_movk_i32 s2, 0xf000
	v_add3_u32 v67, v67, v66, s2
	v_or_b32_e32 v66, v75, v1
	v_lshlrev_b32_e32 v66, 6, v66
	global_load_dwordx4 v[80:83], v66, s[44:45] offset:16
	global_load_dwordx4 v[84:87], v66, s[44:45]
	global_load_dwordx4 v[68:71], v66, s[44:45] offset:48
	global_load_dwordx4 v[76:79], v66, s[44:45] offset:32
	s_movk_i32 s2, 0x400
	v_cmp_gt_i32_e64 s[4:5], s2, v72
	s_movk_i32 s2, 0x1fdf
	s_waitcnt vmcnt(2)
	v_mov_b32_e32 v88, v85
	v_mov_b32_e32 v89, v86
	v_mov_b32_e32 v85, v87
	v_mov_b32_e32 v86, v81
	v_mov_b32_e32 v87, v82
	v_mov_b32_e32 v81, v83
	v_add_f32_e64 v84, v88, v84
	v_add_f32_e64 v85, v89, v85
	v_add_f32_e64 v80, v86, v80
	v_add_f32_e64 v81, v87, v81
	v_pk_add_f32 v[84:85], v[84:85], v[84:85] op_sel:[0,1] op_sel_hi:[1,0]
	v_pk_add_f32 v[80:81], v[80:81], v[80:81] op_sel:[0,1] op_sel_hi:[1,0]
	s_waitcnt vmcnt(0)
	v_add_f32_e32 v76, v76, v77
	v_add_f32_e32 v78, v78, v79
	v_mov_b32_e32 v85, v68
	v_mov_b32_e32 v81, v69
	v_mov_b32_e32 v77, v70
	v_mov_b32_e32 v79, v71
	v_add_f32_e64 v68, v84, v80
	v_add_f32_e64 v69, v85, v81
	v_add_f32_e64 v70, v76, v78
	v_add_f32_e64 v71, v77, v79
	v_bitop3_b32 v76, v75, s2, v1 bitop3:0xc8
	v_add_f32_e64 v68, v68, v70
	v_add_f32_e64 v69, v69, v71
	s_nop 0
	v_add_f32_e32 v66, v68, v69
	v_fmamk_f32 v66, v66, 0x3a800000, v145
	v_cmp_gt_f32_e32 vcc, s51, v66
	v_mul_f32_e32 v68, 0x4b800000, v66
	s_nop 0
	v_cndmask_b32_e32 v66, v66, v68, vcc
	v_rsq_f32_e32 v66, v66
	s_nop 0
	v_mul_f32_e32 v68, 0x45800000, v66
	v_cndmask_b32_e32 v66, v66, v68, vcc
	s_and_saveexec_b64 s[16:17], s[8:9]
	s_xor_b64 s[16:17], exec, s[16:17]
	s_cbranch_execz .LBB0_287
	s_mov_b64 s[20:21], -1
	s_and_b64 vcc, exec, s[14:15]
	s_cbranch_vccz .LBB0_285
	s_and_saveexec_b64 s[20:21], s[6:7]
	s_cbranch_execz .LBB0_284
	global_load_dword v70, v[110:111], off
	v_lshlrev_b32_e32 v98, 2, v76
	v_lshl_add_u64 v[68:69], s[18:19], 0, v[98:99]
	v_or_b32_e32 v98, v74, v104
	s_waitcnt vmcnt(0)
	v_fmac_f32_e32 v70, v50, v66
	v_mul_f32_e64 v71, |v70|, s60
	v_fma_f32 v77, |v70|, s60, -v71
	v_rndne_f32_e32 v78, v71
	v_fma_f32 v77, |v70|, s61, v77
	v_sub_f32_e32 v71, v71, v78
	v_add_f32_e32 v71, v71, v77
	v_exp_f32_e32 v71, v71
	v_cvt_i32_f32_e32 v77, v78
	v_cmp_ngt_f32_e64 vcc, |v70|, s66
	v_min_f32_e32 v73, 0, v70
	v_ldexp_f32 v71, v71, v77
	v_cndmask_b32_e32 v71, 0, v71, vcc
	v_cmp_nlt_f32_e64 vcc, |v70|, s67
	s_nop 1
	v_cndmask_b32_e32 v77, v147, v71, vcc
	v_add_f32_e32 v78, 1.0, v77
	v_add_f32_e32 v70, -1.0, v78
	v_sub_f32_e32 v71, v70, v78
	v_add_f32_e32 v71, 1.0, v71
	v_sub_f32_e32 v70, v77, v70
	v_add_f32_e32 v79, v70, v71
	v_frexp_mant_f32_e32 v70, v78
	v_cmp_gt_f32_e32 vcc, s69, v70
	v_cvt_f64_f32_e32 v[70:71], v78
	v_frexp_exp_i32_f64_e32 v70, v[70:71]
	v_subbrev_co_u32_e32 v70, vcc, 0, v70, vcc
	v_sub_u32_e32 v71, 0, v70
	v_ldexp_f32 v78, v78, v71
	v_ldexp_f32 v71, v79, v71
	v_add_f32_e32 v79, -1.0, v78
	v_add_f32_e32 v80, 1.0, v79
	v_sub_f32_e32 v80, v78, v80
	v_add_f32_e32 v80, v71, v80
	v_add_f32_e32 v81, v79, v80
	v_sub_f32_e32 v79, v79, v81
	v_add_f32_e32 v79, v80, v79
	v_add_f32_e32 v80, 1.0, v78
	v_add_f32_e32 v82, -1.0, v80
	v_sub_f32_e32 v78, v78, v82
	v_add_f32_e32 v71, v71, v78
	v_add_f32_e32 v78, v80, v71
	v_sub_f32_e32 v80, v80, v78
	v_add_f32_e32 v71, v71, v80
	v_rcp_f32_e32 v80, v78
	v_cvt_f32_i32_e32 v70, v70
	v_cmp_neq_f32_e32 vcc, s68, v77
	v_mul_f32_e32 v82, v81, v80
	v_mul_f32_e32 v83, v78, v82
	v_fma_f32 v84, v82, v78, -v83
	v_fmac_f32_e32 v84, v82, v71
	v_add_f32_e32 v85, v83, v84
	v_sub_f32_e32 v86, v81, v85
	v_sub_f32_e32 v81, v81, v86
	v_sub_f32_e32 v83, v85, v83
	v_sub_f32_e32 v81, v81, v85
	v_add_f32_e32 v79, v79, v81
	v_sub_f32_e32 v81, v83, v84
	v_add_f32_e32 v79, v81, v79
	v_add_f32_e32 v81, v86, v79
	v_mul_f32_e32 v83, v80, v81
	v_mul_f32_e32 v84, v78, v83
	v_fma_f32 v78, v83, v78, -v84
	v_fmac_f32_e32 v78, v83, v71
	v_sub_f32_e32 v71, v86, v81
	v_add_f32_e32 v71, v79, v71
	v_add_f32_e32 v79, v84, v78
	v_sub_f32_e32 v85, v81, v79
	v_sub_f32_e32 v81, v81, v85
	v_sub_f32_e32 v84, v79, v84
	v_sub_f32_e32 v79, v81, v79
	v_add_f32_e32 v71, v71, v79
	v_sub_f32_e32 v78, v84, v78
	v_add_f32_e32 v71, v78, v71
	v_add_f32_e32 v78, v82, v83
	v_add_f32_e32 v71, v85, v71
	v_sub_f32_e32 v79, v78, v82
	v_mul_f32_e32 v71, v80, v71
	v_sub_f32_e32 v79, v83, v79
	v_add_f32_e32 v71, v79, v71
	v_mul_f32_e32 v82, 0x3f317218, v70
	v_add_f32_e32 v79, v78, v71
	v_fma_f32 v83, v70, s70, -v82
	v_mul_f32_e32 v80, v79, v79
	v_fmac_f32_e32 v83, 0xb102e308, v70
	v_sub_f32_e32 v70, v79, v78
	v_fmamk_f32 v81, v80, 0x3e9b6dac, v146
	v_sub_f32_e32 v70, v71, v70
	v_add_f32_e32 v71, v82, v83
	v_fmaak_f32 v81, v80, v81, 0x3f2aaada
	v_sub_f32_e32 v78, v71, v82
	v_ldexp_f32 v82, v79, 1
	v_mul_f32_e32 v79, v79, v80
	v_mul_f32_e32 v79, v79, v81
	v_add_f32_e32 v80, v82, v79
	v_sub_f32_e32 v81, v80, v82
	v_ldexp_f32 v70, v70, 1
	v_sub_f32_e32 v79, v79, v81
	v_add_f32_e32 v70, v70, v79
	v_add_f32_e32 v79, v80, v70
	v_sub_f32_e32 v80, v79, v80
	v_sub_f32_e32 v70, v70, v80
	v_add_f32_e32 v80, v71, v79
	v_sub_f32_e32 v81, v80, v71
	v_sub_f32_e32 v82, v80, v81
	v_sub_f32_e32 v78, v83, v78
	v_sub_f32_e32 v71, v71, v82
	v_sub_f32_e32 v79, v79, v81
	v_add_f32_e32 v71, v79, v71
	v_add_f32_e32 v79, v78, v70
	v_sub_f32_e32 v81, v79, v78
	v_sub_f32_e32 v82, v79, v81
	v_sub_f32_e32 v78, v78, v82
	v_sub_f32_e32 v70, v70, v81
	v_add_f32_e32 v71, v79, v71
	v_add_f32_e32 v70, v70, v78
	v_add_f32_e32 v78, v80, v71
	v_sub_f32_e32 v79, v78, v80
	v_sub_f32_e32 v71, v71, v79
	v_add_f32_e32 v70, v70, v71
	v_add_f32_e32 v70, v78, v70
	v_cndmask_b32_e32 v70, v147, v70, vcc
	v_cmp_lt_f32_e64 vcc, |v77|, s71
	s_nop 1
	v_cndmask_b32_e32 v70, v70, v77, vcc
	v_sub_f32_e32 v73, v73, v70
	v_lshlrev_b64 v[70:71], 15, v[98:99]
	v_lshl_add_u64 v[70:71], v[68:69], 0, v[70:71]
	global_store_dword v[70:71], v73, off
	global_load_dword v70, v[110:111], off offset:4
	v_or_b32_e32 v98, v74, v135
	s_waitcnt vmcnt(0)
	v_fmac_f32_e32 v70, v51, v66
	v_mul_f32_e64 v71, |v70|, s60
	v_fma_f32 v77, |v70|, s60, -v71
	v_rndne_f32_e32 v78, v71
	v_fma_f32 v77, |v70|, s61, v77
	v_sub_f32_e32 v71, v71, v78
	v_add_f32_e32 v71, v71, v77
	v_exp_f32_e32 v71, v71
	v_cvt_i32_f32_e32 v77, v78
	v_cmp_ngt_f32_e64 vcc, |v70|, s66
	v_min_f32_e32 v73, 0, v70
	v_ldexp_f32 v71, v71, v77
	v_cndmask_b32_e32 v71, 0, v71, vcc
	v_cmp_nlt_f32_e64 vcc, |v70|, s67
	s_nop 1
	v_cndmask_b32_e32 v77, v147, v71, vcc
	v_add_f32_e32 v78, 1.0, v77
	v_add_f32_e32 v70, -1.0, v78
	v_sub_f32_e32 v71, v70, v78
	v_add_f32_e32 v71, 1.0, v71
	v_sub_f32_e32 v70, v77, v70
	v_add_f32_e32 v79, v70, v71
	v_frexp_mant_f32_e32 v70, v78
	v_cmp_gt_f32_e32 vcc, s69, v70
	v_cvt_f64_f32_e32 v[70:71], v78
	v_frexp_exp_i32_f64_e32 v70, v[70:71]
	v_subbrev_co_u32_e32 v70, vcc, 0, v70, vcc
	v_sub_u32_e32 v71, 0, v70
	v_ldexp_f32 v78, v78, v71
	v_ldexp_f32 v71, v79, v71
	v_add_f32_e32 v79, -1.0, v78
	v_add_f32_e32 v80, 1.0, v79
	v_sub_f32_e32 v80, v78, v80
	v_add_f32_e32 v80, v71, v80
	v_add_f32_e32 v81, v79, v80
	v_sub_f32_e32 v79, v79, v81
	v_add_f32_e32 v79, v80, v79
	v_add_f32_e32 v80, 1.0, v78
	v_add_f32_e32 v82, -1.0, v80
	v_sub_f32_e32 v78, v78, v82
	v_add_f32_e32 v71, v71, v78
	v_add_f32_e32 v78, v80, v71
	v_sub_f32_e32 v80, v80, v78
	v_add_f32_e32 v71, v71, v80
	v_rcp_f32_e32 v80, v78
	v_cvt_f32_i32_e32 v70, v70
	v_cmp_neq_f32_e32 vcc, s68, v77
	v_mul_f32_e32 v82, v81, v80
	v_mul_f32_e32 v83, v78, v82
	v_fma_f32 v84, v82, v78, -v83
	v_fmac_f32_e32 v84, v82, v71
	v_add_f32_e32 v85, v83, v84
	v_sub_f32_e32 v86, v81, v85
	v_sub_f32_e32 v81, v81, v86
	v_sub_f32_e32 v83, v85, v83
	v_sub_f32_e32 v81, v81, v85
	v_add_f32_e32 v79, v79, v81
	v_sub_f32_e32 v81, v83, v84
	v_add_f32_e32 v79, v81, v79
	v_add_f32_e32 v81, v86, v79
	v_mul_f32_e32 v83, v80, v81
	v_mul_f32_e32 v84, v78, v83
	v_fma_f32 v78, v83, v78, -v84
	v_fmac_f32_e32 v78, v83, v71
	v_sub_f32_e32 v71, v86, v81
	v_add_f32_e32 v71, v79, v71
	v_add_f32_e32 v79, v84, v78
	v_sub_f32_e32 v85, v81, v79
	v_sub_f32_e32 v81, v81, v85
	v_sub_f32_e32 v84, v79, v84
	v_sub_f32_e32 v79, v81, v79
	v_add_f32_e32 v71, v71, v79
	v_sub_f32_e32 v78, v84, v78
	v_add_f32_e32 v71, v78, v71
	v_add_f32_e32 v78, v82, v83
	v_add_f32_e32 v71, v85, v71
	v_sub_f32_e32 v79, v78, v82
	v_mul_f32_e32 v71, v80, v71
	v_sub_f32_e32 v79, v83, v79
	v_add_f32_e32 v71, v79, v71
	v_mul_f32_e32 v82, 0x3f317218, v70
	v_add_f32_e32 v79, v78, v71
	v_fma_f32 v83, v70, s70, -v82
	v_mul_f32_e32 v80, v79, v79
	v_fmac_f32_e32 v83, 0xb102e308, v70
	v_sub_f32_e32 v70, v79, v78
	v_fmamk_f32 v81, v80, 0x3e9b6dac, v146
	v_sub_f32_e32 v70, v71, v70
	v_add_f32_e32 v71, v82, v83
	v_fmaak_f32 v81, v80, v81, 0x3f2aaada
	v_sub_f32_e32 v78, v71, v82
	v_ldexp_f32 v82, v79, 1
	v_mul_f32_e32 v79, v79, v80
	v_mul_f32_e32 v79, v79, v81
	v_add_f32_e32 v80, v82, v79
	v_sub_f32_e32 v81, v80, v82
	v_ldexp_f32 v70, v70, 1
	v_sub_f32_e32 v79, v79, v81
	v_add_f32_e32 v70, v70, v79
	v_add_f32_e32 v79, v80, v70
	v_sub_f32_e32 v80, v79, v80
	v_sub_f32_e32 v70, v70, v80
	v_add_f32_e32 v80, v71, v79
	v_sub_f32_e32 v81, v80, v71
	v_sub_f32_e32 v82, v80, v81
	v_sub_f32_e32 v78, v83, v78
	v_sub_f32_e32 v71, v71, v82
	v_sub_f32_e32 v79, v79, v81
	v_add_f32_e32 v71, v79, v71
	v_add_f32_e32 v79, v78, v70
	v_sub_f32_e32 v81, v79, v78
	v_sub_f32_e32 v82, v79, v81
	v_sub_f32_e32 v78, v78, v82
	v_sub_f32_e32 v70, v70, v81
	v_add_f32_e32 v71, v79, v71
	v_add_f32_e32 v70, v70, v78
	v_add_f32_e32 v78, v80, v71
	v_sub_f32_e32 v79, v78, v80
	v_sub_f32_e32 v71, v71, v79
	v_add_f32_e32 v70, v70, v71
	v_add_f32_e32 v70, v78, v70
	v_cndmask_b32_e32 v70, v147, v70, vcc
	v_cmp_lt_f32_e64 vcc, |v77|, s71
	s_nop 1
	v_cndmask_b32_e32 v70, v70, v77, vcc
	v_sub_f32_e32 v73, v73, v70
	v_lshlrev_b64 v[70:71], 15, v[98:99]
	v_lshl_add_u64 v[70:71], v[68:69], 0, v[70:71]
	global_store_dword v[70:71], v73, off
	global_load_dword v70, v[110:111], off offset:8
	v_or_b32_e32 v98, v74, v136
	s_waitcnt vmcnt(0)
	v_fmac_f32_e32 v70, v52, v66
	v_mul_f32_e64 v71, |v70|, s60
	v_fma_f32 v77, |v70|, s60, -v71
	v_rndne_f32_e32 v78, v71
	v_fma_f32 v77, |v70|, s61, v77
	v_sub_f32_e32 v71, v71, v78
	v_add_f32_e32 v71, v71, v77
	v_exp_f32_e32 v71, v71
	v_cvt_i32_f32_e32 v77, v78
	v_cmp_ngt_f32_e64 vcc, |v70|, s66
	v_min_f32_e32 v73, 0, v70
	v_ldexp_f32 v71, v71, v77
	v_cndmask_b32_e32 v71, 0, v71, vcc
	v_cmp_nlt_f32_e64 vcc, |v70|, s67
	s_nop 1
	v_cndmask_b32_e32 v77, v147, v71, vcc
	v_add_f32_e32 v78, 1.0, v77
	v_add_f32_e32 v70, -1.0, v78
	v_sub_f32_e32 v71, v70, v78
	v_add_f32_e32 v71, 1.0, v71
	v_sub_f32_e32 v70, v77, v70
	v_add_f32_e32 v79, v70, v71
	v_frexp_mant_f32_e32 v70, v78
	v_cmp_gt_f32_e32 vcc, s69, v70
	v_cvt_f64_f32_e32 v[70:71], v78
	v_frexp_exp_i32_f64_e32 v70, v[70:71]
	v_subbrev_co_u32_e32 v70, vcc, 0, v70, vcc
	v_sub_u32_e32 v71, 0, v70
	v_ldexp_f32 v78, v78, v71
	v_ldexp_f32 v71, v79, v71
	v_add_f32_e32 v79, -1.0, v78
	v_add_f32_e32 v80, 1.0, v79
	v_sub_f32_e32 v80, v78, v80
	v_add_f32_e32 v80, v71, v80
	v_add_f32_e32 v81, v79, v80
	v_sub_f32_e32 v79, v79, v81
	v_add_f32_e32 v79, v80, v79
	v_add_f32_e32 v80, 1.0, v78
	v_add_f32_e32 v82, -1.0, v80
	v_sub_f32_e32 v78, v78, v82
	v_add_f32_e32 v71, v71, v78
	v_add_f32_e32 v78, v80, v71
	v_sub_f32_e32 v80, v80, v78
	v_add_f32_e32 v71, v71, v80
	v_rcp_f32_e32 v80, v78
	v_cvt_f32_i32_e32 v70, v70
	v_cmp_neq_f32_e32 vcc, s68, v77
	v_mul_f32_e32 v82, v81, v80
	v_mul_f32_e32 v83, v78, v82
	v_fma_f32 v84, v82, v78, -v83
	v_fmac_f32_e32 v84, v82, v71
	v_add_f32_e32 v85, v83, v84
	v_sub_f32_e32 v86, v81, v85
	v_sub_f32_e32 v81, v81, v86
	v_sub_f32_e32 v83, v85, v83
	v_sub_f32_e32 v81, v81, v85
	v_add_f32_e32 v79, v79, v81
	v_sub_f32_e32 v81, v83, v84
	v_add_f32_e32 v79, v81, v79
	v_add_f32_e32 v81, v86, v79
	v_mul_f32_e32 v83, v80, v81
	v_mul_f32_e32 v84, v78, v83
	v_fma_f32 v78, v83, v78, -v84
	v_fmac_f32_e32 v78, v83, v71
	v_sub_f32_e32 v71, v86, v81
	v_add_f32_e32 v71, v79, v71
	v_add_f32_e32 v79, v84, v78
	v_sub_f32_e32 v85, v81, v79
	v_sub_f32_e32 v81, v81, v85
	v_sub_f32_e32 v84, v79, v84
	v_sub_f32_e32 v79, v81, v79
	v_add_f32_e32 v71, v71, v79
	v_sub_f32_e32 v78, v84, v78
	v_add_f32_e32 v71, v78, v71
	v_add_f32_e32 v78, v82, v83
	v_add_f32_e32 v71, v85, v71
	v_sub_f32_e32 v79, v78, v82
	v_mul_f32_e32 v71, v80, v71
	v_sub_f32_e32 v79, v83, v79
	v_add_f32_e32 v71, v79, v71
	v_mul_f32_e32 v82, 0x3f317218, v70
	v_add_f32_e32 v79, v78, v71
	v_fma_f32 v83, v70, s70, -v82
	v_mul_f32_e32 v80, v79, v79
	v_fmac_f32_e32 v83, 0xb102e308, v70
	v_sub_f32_e32 v70, v79, v78
	v_fmamk_f32 v81, v80, 0x3e9b6dac, v146
	v_sub_f32_e32 v70, v71, v70
	v_add_f32_e32 v71, v82, v83
	v_fmaak_f32 v81, v80, v81, 0x3f2aaada
	v_sub_f32_e32 v78, v71, v82
	v_ldexp_f32 v82, v79, 1
	v_mul_f32_e32 v79, v79, v80
	v_mul_f32_e32 v79, v79, v81
	v_add_f32_e32 v80, v82, v79
	v_sub_f32_e32 v81, v80, v82
	v_ldexp_f32 v70, v70, 1
	v_sub_f32_e32 v79, v79, v81
	v_add_f32_e32 v70, v70, v79
	v_add_f32_e32 v79, v80, v70
	v_sub_f32_e32 v80, v79, v80
	v_sub_f32_e32 v70, v70, v80
	v_add_f32_e32 v80, v71, v79
	v_sub_f32_e32 v81, v80, v71
	v_sub_f32_e32 v82, v80, v81
	v_sub_f32_e32 v78, v83, v78
	v_sub_f32_e32 v71, v71, v82
	v_sub_f32_e32 v79, v79, v81
	v_add_f32_e32 v71, v79, v71
	v_add_f32_e32 v79, v78, v70
	v_sub_f32_e32 v81, v79, v78
	v_sub_f32_e32 v82, v79, v81
	v_sub_f32_e32 v78, v78, v82
	v_sub_f32_e32 v70, v70, v81
	v_add_f32_e32 v71, v79, v71
	v_add_f32_e32 v70, v70, v78
	v_add_f32_e32 v78, v80, v71
	v_sub_f32_e32 v79, v78, v80
	v_sub_f32_e32 v71, v71, v79
	v_add_f32_e32 v70, v70, v71
	v_add_f32_e32 v70, v78, v70
	v_cndmask_b32_e32 v70, v147, v70, vcc
	v_cmp_lt_f32_e64 vcc, |v77|, s71
	s_nop 1
	v_cndmask_b32_e32 v70, v70, v77, vcc
	v_sub_f32_e32 v73, v73, v70
	v_lshlrev_b64 v[70:71], 15, v[98:99]
	v_lshl_add_u64 v[70:71], v[68:69], 0, v[70:71]
	global_store_dword v[70:71], v73, off
	global_load_dword v70, v[110:111], off offset:12
	v_or_b32_e32 v98, v74, v137
	s_waitcnt vmcnt(0)
	v_fmac_f32_e32 v70, v53, v66
	v_mul_f32_e64 v71, |v70|, s60
	v_fma_f32 v77, |v70|, s60, -v71
	v_rndne_f32_e32 v78, v71
	v_fma_f32 v77, |v70|, s61, v77
	v_sub_f32_e32 v71, v71, v78
	v_add_f32_e32 v71, v71, v77
	v_exp_f32_e32 v71, v71
	v_cvt_i32_f32_e32 v77, v78
	v_cmp_ngt_f32_e64 vcc, |v70|, s66
	v_min_f32_e32 v73, 0, v70
	v_ldexp_f32 v71, v71, v77
	v_cndmask_b32_e32 v71, 0, v71, vcc
	v_cmp_nlt_f32_e64 vcc, |v70|, s67
	s_nop 1
	v_cndmask_b32_e32 v77, v147, v71, vcc
	v_add_f32_e32 v78, 1.0, v77
	v_add_f32_e32 v70, -1.0, v78
	v_sub_f32_e32 v71, v70, v78
	v_add_f32_e32 v71, 1.0, v71
	v_sub_f32_e32 v70, v77, v70
	v_add_f32_e32 v79, v70, v71
	v_frexp_mant_f32_e32 v70, v78
	v_cmp_gt_f32_e32 vcc, s69, v70
	v_cvt_f64_f32_e32 v[70:71], v78
	v_frexp_exp_i32_f64_e32 v70, v[70:71]
	v_subbrev_co_u32_e32 v70, vcc, 0, v70, vcc
	v_sub_u32_e32 v71, 0, v70
	v_ldexp_f32 v78, v78, v71
	v_ldexp_f32 v71, v79, v71
	v_add_f32_e32 v79, -1.0, v78
	v_add_f32_e32 v80, 1.0, v79
	v_sub_f32_e32 v80, v78, v80
	v_add_f32_e32 v80, v71, v80
	v_add_f32_e32 v81, v79, v80
	v_sub_f32_e32 v79, v79, v81
	v_add_f32_e32 v79, v80, v79
	v_add_f32_e32 v80, 1.0, v78
	v_add_f32_e32 v82, -1.0, v80
	v_sub_f32_e32 v78, v78, v82
	v_add_f32_e32 v71, v71, v78
	v_add_f32_e32 v78, v80, v71
	v_sub_f32_e32 v80, v80, v78
	v_add_f32_e32 v71, v71, v80
	v_rcp_f32_e32 v80, v78
	v_cvt_f32_i32_e32 v70, v70
	v_cmp_neq_f32_e32 vcc, s68, v77
	v_mul_f32_e32 v82, v81, v80
	v_mul_f32_e32 v83, v78, v82
	v_fma_f32 v84, v82, v78, -v83
	v_fmac_f32_e32 v84, v82, v71
	v_add_f32_e32 v85, v83, v84
	v_sub_f32_e32 v86, v81, v85
	v_sub_f32_e32 v81, v81, v86
	v_sub_f32_e32 v83, v85, v83
	v_sub_f32_e32 v81, v81, v85
	v_add_f32_e32 v79, v79, v81
	v_sub_f32_e32 v81, v83, v84
	v_add_f32_e32 v79, v81, v79
	v_add_f32_e32 v81, v86, v79
	v_mul_f32_e32 v83, v80, v81
	v_mul_f32_e32 v84, v78, v83
	v_fma_f32 v78, v83, v78, -v84
	v_fmac_f32_e32 v78, v83, v71
	v_sub_f32_e32 v71, v86, v81
	v_add_f32_e32 v71, v79, v71
	v_add_f32_e32 v79, v84, v78
	v_sub_f32_e32 v85, v81, v79
	v_sub_f32_e32 v81, v81, v85
	v_sub_f32_e32 v84, v79, v84
	v_sub_f32_e32 v79, v81, v79
	v_add_f32_e32 v71, v71, v79
	v_sub_f32_e32 v78, v84, v78
	v_add_f32_e32 v71, v78, v71
	v_add_f32_e32 v78, v82, v83
	v_add_f32_e32 v71, v85, v71
	v_sub_f32_e32 v79, v78, v82
	v_mul_f32_e32 v71, v80, v71
	v_sub_f32_e32 v79, v83, v79
	v_add_f32_e32 v71, v79, v71
	v_mul_f32_e32 v82, 0x3f317218, v70
	v_add_f32_e32 v79, v78, v71
	v_fma_f32 v83, v70, s70, -v82
	v_mul_f32_e32 v80, v79, v79
	v_fmac_f32_e32 v83, 0xb102e308, v70
	v_sub_f32_e32 v70, v79, v78
	v_fmamk_f32 v81, v80, 0x3e9b6dac, v146
	v_sub_f32_e32 v70, v71, v70
	v_add_f32_e32 v71, v82, v83
	v_fmaak_f32 v81, v80, v81, 0x3f2aaada
	v_sub_f32_e32 v78, v71, v82
	v_ldexp_f32 v82, v79, 1
	v_mul_f32_e32 v79, v79, v80
	v_mul_f32_e32 v79, v79, v81
	v_add_f32_e32 v80, v82, v79
	v_sub_f32_e32 v81, v80, v82
	v_ldexp_f32 v70, v70, 1
	v_sub_f32_e32 v79, v79, v81
	v_add_f32_e32 v70, v70, v79
	v_add_f32_e32 v79, v80, v70
	v_sub_f32_e32 v80, v79, v80
	v_sub_f32_e32 v70, v70, v80
	v_add_f32_e32 v80, v71, v79
	v_sub_f32_e32 v81, v80, v71
	v_sub_f32_e32 v82, v80, v81
	v_sub_f32_e32 v78, v83, v78
	v_sub_f32_e32 v71, v71, v82
	v_sub_f32_e32 v79, v79, v81
	v_add_f32_e32 v71, v79, v71
	v_add_f32_e32 v79, v78, v70
	v_sub_f32_e32 v81, v79, v78
	v_sub_f32_e32 v82, v79, v81
	v_sub_f32_e32 v78, v78, v82
	v_sub_f32_e32 v70, v70, v81
	v_add_f32_e32 v71, v79, v71
	v_add_f32_e32 v70, v70, v78
	v_add_f32_e32 v78, v80, v71
	v_sub_f32_e32 v79, v78, v80
	v_sub_f32_e32 v71, v71, v79
	v_add_f32_e32 v70, v70, v71
	v_add_f32_e32 v70, v78, v70
	v_cndmask_b32_e32 v70, v147, v70, vcc
	v_cmp_lt_f32_e64 vcc, |v77|, s71
	s_nop 1
	v_cndmask_b32_e32 v70, v70, v77, vcc
	v_sub_f32_e32 v73, v73, v70
	v_lshlrev_b64 v[70:71], 15, v[98:99]
	v_lshl_add_u64 v[70:71], v[68:69], 0, v[70:71]
	global_store_dword v[70:71], v73, off
	global_load_dword v70, v[110:111], off offset:32
	v_or_b32_e32 v98, v74, v138
	s_waitcnt vmcnt(0)
	v_fmac_f32_e32 v70, v54, v66
	v_mul_f32_e64 v71, |v70|, s60
	v_fma_f32 v77, |v70|, s60, -v71
	v_rndne_f32_e32 v78, v71
	v_fma_f32 v77, |v70|, s61, v77
	v_sub_f32_e32 v71, v71, v78
	v_add_f32_e32 v71, v71, v77
	v_exp_f32_e32 v71, v71
	v_cvt_i32_f32_e32 v77, v78
	v_cmp_ngt_f32_e64 vcc, |v70|, s66
	v_min_f32_e32 v73, 0, v70
	v_ldexp_f32 v71, v71, v77
	v_cndmask_b32_e32 v71, 0, v71, vcc
	v_cmp_nlt_f32_e64 vcc, |v70|, s67
	s_nop 1
	v_cndmask_b32_e32 v77, v147, v71, vcc
	v_add_f32_e32 v78, 1.0, v77
	v_add_f32_e32 v70, -1.0, v78
	v_sub_f32_e32 v71, v70, v78
	v_add_f32_e32 v71, 1.0, v71
	v_sub_f32_e32 v70, v77, v70
	v_add_f32_e32 v79, v70, v71
	v_frexp_mant_f32_e32 v70, v78
	v_cmp_gt_f32_e32 vcc, s69, v70
	v_cvt_f64_f32_e32 v[70:71], v78
	v_frexp_exp_i32_f64_e32 v70, v[70:71]
	v_subbrev_co_u32_e32 v70, vcc, 0, v70, vcc
	v_sub_u32_e32 v71, 0, v70
	v_ldexp_f32 v78, v78, v71
	v_ldexp_f32 v71, v79, v71
	v_add_f32_e32 v79, -1.0, v78
	v_add_f32_e32 v80, 1.0, v79
	v_sub_f32_e32 v80, v78, v80
	v_add_f32_e32 v80, v71, v80
	v_add_f32_e32 v81, v79, v80
	v_sub_f32_e32 v79, v79, v81
	v_add_f32_e32 v79, v80, v79
	v_add_f32_e32 v80, 1.0, v78
	v_add_f32_e32 v82, -1.0, v80
	v_sub_f32_e32 v78, v78, v82
	v_add_f32_e32 v71, v71, v78
	v_add_f32_e32 v78, v80, v71
	v_sub_f32_e32 v80, v80, v78
	v_add_f32_e32 v71, v71, v80
	v_rcp_f32_e32 v80, v78
	v_cvt_f32_i32_e32 v70, v70
	v_cmp_neq_f32_e32 vcc, s68, v77
	v_mul_f32_e32 v82, v81, v80
	v_mul_f32_e32 v83, v78, v82
	v_fma_f32 v84, v82, v78, -v83
	v_fmac_f32_e32 v84, v82, v71
	v_add_f32_e32 v85, v83, v84
	v_sub_f32_e32 v86, v81, v85
	v_sub_f32_e32 v81, v81, v86
	v_sub_f32_e32 v83, v85, v83
	v_sub_f32_e32 v81, v81, v85
	v_add_f32_e32 v79, v79, v81
	v_sub_f32_e32 v81, v83, v84
	v_add_f32_e32 v79, v81, v79
	v_add_f32_e32 v81, v86, v79
	v_mul_f32_e32 v83, v80, v81
	v_mul_f32_e32 v84, v78, v83
	v_fma_f32 v78, v83, v78, -v84
	v_fmac_f32_e32 v78, v83, v71
	v_sub_f32_e32 v71, v86, v81
	v_add_f32_e32 v71, v79, v71
	v_add_f32_e32 v79, v84, v78
	v_sub_f32_e32 v85, v81, v79
	v_sub_f32_e32 v81, v81, v85
	v_sub_f32_e32 v84, v79, v84
	v_sub_f32_e32 v79, v81, v79
	v_add_f32_e32 v71, v71, v79
	v_sub_f32_e32 v78, v84, v78
	v_add_f32_e32 v71, v78, v71
	v_add_f32_e32 v78, v82, v83
	v_add_f32_e32 v71, v85, v71
	v_sub_f32_e32 v79, v78, v82
	v_mul_f32_e32 v71, v80, v71
	v_sub_f32_e32 v79, v83, v79
	v_add_f32_e32 v71, v79, v71
	v_mul_f32_e32 v82, 0x3f317218, v70
	v_add_f32_e32 v79, v78, v71
	v_fma_f32 v83, v70, s70, -v82
	v_mul_f32_e32 v80, v79, v79
	v_fmac_f32_e32 v83, 0xb102e308, v70
	v_sub_f32_e32 v70, v79, v78
	v_fmamk_f32 v81, v80, 0x3e9b6dac, v146
	v_sub_f32_e32 v70, v71, v70
	v_add_f32_e32 v71, v82, v83
	v_fmaak_f32 v81, v80, v81, 0x3f2aaada
	v_sub_f32_e32 v78, v71, v82
	v_ldexp_f32 v82, v79, 1
	v_mul_f32_e32 v79, v79, v80
	v_mul_f32_e32 v79, v79, v81
	v_add_f32_e32 v80, v82, v79
	v_sub_f32_e32 v81, v80, v82
	v_ldexp_f32 v70, v70, 1
	v_sub_f32_e32 v79, v79, v81
	v_add_f32_e32 v70, v70, v79
	v_add_f32_e32 v79, v80, v70
	v_sub_f32_e32 v80, v79, v80
	v_sub_f32_e32 v70, v70, v80
	v_add_f32_e32 v80, v71, v79
	v_sub_f32_e32 v81, v80, v71
	v_sub_f32_e32 v82, v80, v81
	v_sub_f32_e32 v78, v83, v78
	v_sub_f32_e32 v71, v71, v82
	v_sub_f32_e32 v79, v79, v81
	v_add_f32_e32 v71, v79, v71
	v_add_f32_e32 v79, v78, v70
	v_sub_f32_e32 v81, v79, v78
	v_sub_f32_e32 v82, v79, v81
	v_sub_f32_e32 v78, v78, v82
	v_sub_f32_e32 v70, v70, v81
	v_add_f32_e32 v71, v79, v71
	v_add_f32_e32 v70, v70, v78
	v_add_f32_e32 v78, v80, v71
	v_sub_f32_e32 v79, v78, v80
	v_sub_f32_e32 v71, v71, v79
	v_add_f32_e32 v70, v70, v71
	v_add_f32_e32 v70, v78, v70
	v_cndmask_b32_e32 v70, v147, v70, vcc
	v_cmp_lt_f32_e64 vcc, |v77|, s71
	s_nop 1
	v_cndmask_b32_e32 v70, v70, v77, vcc
	v_sub_f32_e32 v73, v73, v70
	v_lshlrev_b64 v[70:71], 15, v[98:99]
	v_lshl_add_u64 v[70:71], v[68:69], 0, v[70:71]
	global_store_dword v[70:71], v73, off
	global_load_dword v70, v[110:111], off offset:36
	v_or_b32_e32 v98, v74, v139
	s_waitcnt vmcnt(0)
	v_fmac_f32_e32 v70, v55, v66
	v_mul_f32_e64 v71, |v70|, s60
	v_fma_f32 v77, |v70|, s60, -v71
	v_rndne_f32_e32 v78, v71
	v_fma_f32 v77, |v70|, s61, v77
	v_sub_f32_e32 v71, v71, v78
	v_add_f32_e32 v71, v71, v77
	v_exp_f32_e32 v71, v71
	v_cvt_i32_f32_e32 v77, v78
	v_cmp_ngt_f32_e64 vcc, |v70|, s66
	v_min_f32_e32 v73, 0, v70
	v_ldexp_f32 v71, v71, v77
	v_cndmask_b32_e32 v71, 0, v71, vcc
	v_cmp_nlt_f32_e64 vcc, |v70|, s67
	s_nop 1
	v_cndmask_b32_e32 v77, v147, v71, vcc
	v_add_f32_e32 v78, 1.0, v77
	v_add_f32_e32 v70, -1.0, v78
	v_sub_f32_e32 v71, v70, v78
	v_add_f32_e32 v71, 1.0, v71
	v_sub_f32_e32 v70, v77, v70
	v_add_f32_e32 v79, v70, v71
	v_frexp_mant_f32_e32 v70, v78
	v_cmp_gt_f32_e32 vcc, s69, v70
	v_cvt_f64_f32_e32 v[70:71], v78
	v_frexp_exp_i32_f64_e32 v70, v[70:71]
	v_subbrev_co_u32_e32 v70, vcc, 0, v70, vcc
	v_sub_u32_e32 v71, 0, v70
	v_ldexp_f32 v78, v78, v71
	v_ldexp_f32 v71, v79, v71
	v_add_f32_e32 v79, -1.0, v78
	v_add_f32_e32 v80, 1.0, v79
	v_sub_f32_e32 v80, v78, v80
	v_add_f32_e32 v80, v71, v80
	v_add_f32_e32 v81, v79, v80
	v_sub_f32_e32 v79, v79, v81
	v_add_f32_e32 v79, v80, v79
	v_add_f32_e32 v80, 1.0, v78
	v_add_f32_e32 v82, -1.0, v80
	v_sub_f32_e32 v78, v78, v82
	v_add_f32_e32 v71, v71, v78
	v_add_f32_e32 v78, v80, v71
	v_sub_f32_e32 v80, v80, v78
	v_add_f32_e32 v71, v71, v80
	v_rcp_f32_e32 v80, v78
	v_cvt_f32_i32_e32 v70, v70
	v_cmp_neq_f32_e32 vcc, s68, v77
	v_mul_f32_e32 v82, v81, v80
	v_mul_f32_e32 v83, v78, v82
	v_fma_f32 v84, v82, v78, -v83
	v_fmac_f32_e32 v84, v82, v71
	v_add_f32_e32 v85, v83, v84
	v_sub_f32_e32 v86, v81, v85
	v_sub_f32_e32 v81, v81, v86
	v_sub_f32_e32 v83, v85, v83
	v_sub_f32_e32 v81, v81, v85
	v_add_f32_e32 v79, v79, v81
	v_sub_f32_e32 v81, v83, v84
	v_add_f32_e32 v79, v81, v79
	v_add_f32_e32 v81, v86, v79
	v_mul_f32_e32 v83, v80, v81
	v_mul_f32_e32 v84, v78, v83
	v_fma_f32 v78, v83, v78, -v84
	v_fmac_f32_e32 v78, v83, v71
	v_sub_f32_e32 v71, v86, v81
	v_add_f32_e32 v71, v79, v71
	v_add_f32_e32 v79, v84, v78
	v_sub_f32_e32 v85, v81, v79
	v_sub_f32_e32 v81, v81, v85
	v_sub_f32_e32 v84, v79, v84
	v_sub_f32_e32 v79, v81, v79
	v_add_f32_e32 v71, v71, v79
	v_sub_f32_e32 v78, v84, v78
	v_add_f32_e32 v71, v78, v71
	v_add_f32_e32 v78, v82, v83
	v_add_f32_e32 v71, v85, v71
	v_sub_f32_e32 v79, v78, v82
	v_mul_f32_e32 v71, v80, v71
	v_sub_f32_e32 v79, v83, v79
	v_add_f32_e32 v71, v79, v71
	v_mul_f32_e32 v82, 0x3f317218, v70
	v_add_f32_e32 v79, v78, v71
	v_fma_f32 v83, v70, s70, -v82
	v_mul_f32_e32 v80, v79, v79
	v_fmac_f32_e32 v83, 0xb102e308, v70
	v_sub_f32_e32 v70, v79, v78
	v_fmamk_f32 v81, v80, 0x3e9b6dac, v146
	v_sub_f32_e32 v70, v71, v70
	v_add_f32_e32 v71, v82, v83
	v_fmaak_f32 v81, v80, v81, 0x3f2aaada
	v_sub_f32_e32 v78, v71, v82
	v_ldexp_f32 v82, v79, 1
	v_mul_f32_e32 v79, v79, v80
	v_mul_f32_e32 v79, v79, v81
	v_add_f32_e32 v80, v82, v79
	v_sub_f32_e32 v81, v80, v82
	v_ldexp_f32 v70, v70, 1
	v_sub_f32_e32 v79, v79, v81
	v_add_f32_e32 v70, v70, v79
	v_add_f32_e32 v79, v80, v70
	v_sub_f32_e32 v80, v79, v80
	v_sub_f32_e32 v70, v70, v80
	v_add_f32_e32 v80, v71, v79
	v_sub_f32_e32 v81, v80, v71
	v_sub_f32_e32 v82, v80, v81
	v_sub_f32_e32 v78, v83, v78
	v_sub_f32_e32 v71, v71, v82
	v_sub_f32_e32 v79, v79, v81
	v_add_f32_e32 v71, v79, v71
	v_add_f32_e32 v79, v78, v70
	v_sub_f32_e32 v81, v79, v78
	v_sub_f32_e32 v82, v79, v81
	v_sub_f32_e32 v78, v78, v82
	v_sub_f32_e32 v70, v70, v81
	v_add_f32_e32 v71, v79, v71
	v_add_f32_e32 v70, v70, v78
	v_add_f32_e32 v78, v80, v71
	v_sub_f32_e32 v79, v78, v80
	v_sub_f32_e32 v71, v71, v79
	v_add_f32_e32 v70, v70, v71
	v_add_f32_e32 v70, v78, v70
	v_cndmask_b32_e32 v70, v147, v70, vcc
	v_cmp_lt_f32_e64 vcc, |v77|, s71
	s_nop 1
	v_cndmask_b32_e32 v70, v70, v77, vcc
	v_sub_f32_e32 v73, v73, v70
	v_lshlrev_b64 v[70:71], 15, v[98:99]
	v_lshl_add_u64 v[70:71], v[68:69], 0, v[70:71]
	global_store_dword v[70:71], v73, off
	global_load_dword v70, v[110:111], off offset:40
	v_or_b32_e32 v98, v74, v140
	s_waitcnt vmcnt(0)
	v_fmac_f32_e32 v70, v56, v66
	v_mul_f32_e64 v71, |v70|, s60
	v_fma_f32 v77, |v70|, s60, -v71
	v_rndne_f32_e32 v78, v71
	v_fma_f32 v77, |v70|, s61, v77
	v_sub_f32_e32 v71, v71, v78
	v_add_f32_e32 v71, v71, v77
	v_exp_f32_e32 v71, v71
	v_cvt_i32_f32_e32 v77, v78
	v_cmp_ngt_f32_e64 vcc, |v70|, s66
	v_min_f32_e32 v73, 0, v70
	v_ldexp_f32 v71, v71, v77
	v_cndmask_b32_e32 v71, 0, v71, vcc
	v_cmp_nlt_f32_e64 vcc, |v70|, s67
	s_nop 1
	v_cndmask_b32_e32 v77, v147, v71, vcc
	v_add_f32_e32 v78, 1.0, v77
	v_add_f32_e32 v70, -1.0, v78
	v_sub_f32_e32 v71, v70, v78
	v_add_f32_e32 v71, 1.0, v71
	v_sub_f32_e32 v70, v77, v70
	v_add_f32_e32 v79, v70, v71
	v_frexp_mant_f32_e32 v70, v78
	v_cmp_gt_f32_e32 vcc, s69, v70
	v_cvt_f64_f32_e32 v[70:71], v78
	v_frexp_exp_i32_f64_e32 v70, v[70:71]
	v_subbrev_co_u32_e32 v70, vcc, 0, v70, vcc
	v_sub_u32_e32 v71, 0, v70
	v_ldexp_f32 v78, v78, v71
	v_ldexp_f32 v71, v79, v71
	v_add_f32_e32 v79, -1.0, v78
	v_add_f32_e32 v80, 1.0, v79
	v_sub_f32_e32 v80, v78, v80
	v_add_f32_e32 v80, v71, v80
	v_add_f32_e32 v81, v79, v80
	v_sub_f32_e32 v79, v79, v81
	v_add_f32_e32 v79, v80, v79
	v_add_f32_e32 v80, 1.0, v78
	v_add_f32_e32 v82, -1.0, v80
	v_sub_f32_e32 v78, v78, v82
	v_add_f32_e32 v71, v71, v78
	v_add_f32_e32 v78, v80, v71
	v_sub_f32_e32 v80, v80, v78
	v_add_f32_e32 v71, v71, v80
	v_rcp_f32_e32 v80, v78
	v_cvt_f32_i32_e32 v70, v70
	v_cmp_neq_f32_e32 vcc, s68, v77
	v_mul_f32_e32 v82, v81, v80
	v_mul_f32_e32 v83, v78, v82
	v_fma_f32 v84, v82, v78, -v83
	v_fmac_f32_e32 v84, v82, v71
	v_add_f32_e32 v85, v83, v84
	v_sub_f32_e32 v86, v81, v85
	v_sub_f32_e32 v81, v81, v86
	v_sub_f32_e32 v83, v85, v83
	v_sub_f32_e32 v81, v81, v85
	v_add_f32_e32 v79, v79, v81
	v_sub_f32_e32 v81, v83, v84
	v_add_f32_e32 v79, v81, v79
	v_add_f32_e32 v81, v86, v79
	v_mul_f32_e32 v83, v80, v81
	v_mul_f32_e32 v84, v78, v83
	v_fma_f32 v78, v83, v78, -v84
	v_fmac_f32_e32 v78, v83, v71
	v_sub_f32_e32 v71, v86, v81
	v_add_f32_e32 v71, v79, v71
	v_add_f32_e32 v79, v84, v78
	v_sub_f32_e32 v85, v81, v79
	v_sub_f32_e32 v81, v81, v85
	v_sub_f32_e32 v84, v79, v84
	v_sub_f32_e32 v79, v81, v79
	v_add_f32_e32 v71, v71, v79
	v_sub_f32_e32 v78, v84, v78
	v_add_f32_e32 v71, v78, v71
	v_add_f32_e32 v78, v82, v83
	v_add_f32_e32 v71, v85, v71
	v_sub_f32_e32 v79, v78, v82
	v_mul_f32_e32 v71, v80, v71
	v_sub_f32_e32 v79, v83, v79
	v_add_f32_e32 v71, v79, v71
	v_mul_f32_e32 v82, 0x3f317218, v70
	v_add_f32_e32 v79, v78, v71
	v_fma_f32 v83, v70, s70, -v82
	v_mul_f32_e32 v80, v79, v79
	v_fmac_f32_e32 v83, 0xb102e308, v70
	v_sub_f32_e32 v70, v79, v78
	v_fmamk_f32 v81, v80, 0x3e9b6dac, v146
	v_sub_f32_e32 v70, v71, v70
	v_add_f32_e32 v71, v82, v83
	v_fmaak_f32 v81, v80, v81, 0x3f2aaada
	v_sub_f32_e32 v78, v71, v82
	v_ldexp_f32 v82, v79, 1
	v_mul_f32_e32 v79, v79, v80
	v_mul_f32_e32 v79, v79, v81
	v_add_f32_e32 v80, v82, v79
	v_sub_f32_e32 v81, v80, v82
	v_ldexp_f32 v70, v70, 1
	v_sub_f32_e32 v79, v79, v81
	v_add_f32_e32 v70, v70, v79
	v_add_f32_e32 v79, v80, v70
	v_sub_f32_e32 v80, v79, v80
	v_sub_f32_e32 v70, v70, v80
	v_add_f32_e32 v80, v71, v79
	v_sub_f32_e32 v81, v80, v71
	v_sub_f32_e32 v82, v80, v81
	v_sub_f32_e32 v78, v83, v78
	v_sub_f32_e32 v71, v71, v82
	v_sub_f32_e32 v79, v79, v81
	v_add_f32_e32 v71, v79, v71
	v_add_f32_e32 v79, v78, v70
	v_sub_f32_e32 v81, v79, v78
	v_sub_f32_e32 v82, v79, v81
	v_sub_f32_e32 v78, v78, v82
	v_sub_f32_e32 v70, v70, v81
	v_add_f32_e32 v71, v79, v71
	v_add_f32_e32 v70, v70, v78
	v_add_f32_e32 v78, v80, v71
	v_sub_f32_e32 v79, v78, v80
	v_sub_f32_e32 v71, v71, v79
	v_add_f32_e32 v70, v70, v71
	v_add_f32_e32 v70, v78, v70
	v_cndmask_b32_e32 v70, v147, v70, vcc
	v_cmp_lt_f32_e64 vcc, |v77|, s71
	s_nop 1
	v_cndmask_b32_e32 v70, v70, v77, vcc
	v_sub_f32_e32 v73, v73, v70
	v_lshlrev_b64 v[70:71], 15, v[98:99]
	v_lshl_add_u64 v[70:71], v[68:69], 0, v[70:71]
	global_store_dword v[70:71], v73, off
	global_load_dword v70, v[110:111], off offset:44
	v_or_b32_e32 v98, v74, v141
	s_waitcnt vmcnt(0)
	v_fmac_f32_e32 v70, v57, v66
	v_mul_f32_e64 v71, |v70|, s60
	v_fma_f32 v77, |v70|, s60, -v71
	v_rndne_f32_e32 v78, v71
	v_fma_f32 v77, |v70|, s61, v77
	v_sub_f32_e32 v71, v71, v78
	v_add_f32_e32 v71, v71, v77
	v_exp_f32_e32 v71, v71
	v_cvt_i32_f32_e32 v77, v78
	v_cmp_ngt_f32_e64 vcc, |v70|, s66
	v_min_f32_e32 v73, 0, v70
	v_ldexp_f32 v71, v71, v77
	v_cndmask_b32_e32 v71, 0, v71, vcc
	v_cmp_nlt_f32_e64 vcc, |v70|, s67
	s_nop 1
	v_cndmask_b32_e32 v77, v147, v71, vcc
	v_add_f32_e32 v78, 1.0, v77
	v_add_f32_e32 v70, -1.0, v78
	v_sub_f32_e32 v71, v70, v78
	v_add_f32_e32 v71, 1.0, v71
	v_sub_f32_e32 v70, v77, v70
	v_add_f32_e32 v79, v70, v71
	v_frexp_mant_f32_e32 v70, v78
	v_cmp_gt_f32_e32 vcc, s69, v70
	v_cvt_f64_f32_e32 v[70:71], v78
	v_frexp_exp_i32_f64_e32 v70, v[70:71]
	v_subbrev_co_u32_e32 v70, vcc, 0, v70, vcc
	v_sub_u32_e32 v71, 0, v70
	v_ldexp_f32 v78, v78, v71
	v_ldexp_f32 v71, v79, v71
	v_add_f32_e32 v79, -1.0, v78
	v_add_f32_e32 v80, 1.0, v79
	v_sub_f32_e32 v80, v78, v80
	v_add_f32_e32 v80, v71, v80
	v_add_f32_e32 v81, v79, v80
	v_sub_f32_e32 v79, v79, v81
	v_add_f32_e32 v79, v80, v79
	v_add_f32_e32 v80, 1.0, v78
	v_add_f32_e32 v82, -1.0, v80
	v_sub_f32_e32 v78, v78, v82
	v_add_f32_e32 v71, v71, v78
	v_add_f32_e32 v78, v80, v71
	v_sub_f32_e32 v80, v80, v78
	v_add_f32_e32 v71, v71, v80
	v_rcp_f32_e32 v80, v78
	v_cvt_f32_i32_e32 v70, v70
	v_cmp_neq_f32_e32 vcc, s68, v77
	v_mul_f32_e32 v82, v81, v80
	v_mul_f32_e32 v83, v78, v82
	v_fma_f32 v84, v82, v78, -v83
	v_fmac_f32_e32 v84, v82, v71
	v_add_f32_e32 v85, v83, v84
	v_sub_f32_e32 v86, v81, v85
	v_sub_f32_e32 v81, v81, v86
	v_sub_f32_e32 v83, v85, v83
	v_sub_f32_e32 v81, v81, v85
	v_add_f32_e32 v79, v79, v81
	v_sub_f32_e32 v81, v83, v84
	v_add_f32_e32 v79, v81, v79
	v_add_f32_e32 v81, v86, v79
	v_mul_f32_e32 v83, v80, v81
	v_mul_f32_e32 v84, v78, v83
	v_fma_f32 v78, v83, v78, -v84
	v_fmac_f32_e32 v78, v83, v71
	v_sub_f32_e32 v71, v86, v81
	v_add_f32_e32 v71, v79, v71
	v_add_f32_e32 v79, v84, v78
	v_sub_f32_e32 v85, v81, v79
	v_sub_f32_e32 v81, v81, v85
	v_sub_f32_e32 v84, v79, v84
	v_sub_f32_e32 v79, v81, v79
	v_add_f32_e32 v71, v71, v79
	v_sub_f32_e32 v78, v84, v78
	v_add_f32_e32 v71, v78, v71
	v_add_f32_e32 v78, v82, v83
	v_add_f32_e32 v71, v85, v71
	v_sub_f32_e32 v79, v78, v82
	v_mul_f32_e32 v71, v80, v71
	v_sub_f32_e32 v79, v83, v79
	v_add_f32_e32 v71, v79, v71
	v_mul_f32_e32 v82, 0x3f317218, v70
	v_add_f32_e32 v79, v78, v71
	v_fma_f32 v83, v70, s70, -v82
	v_mul_f32_e32 v80, v79, v79
	v_fmac_f32_e32 v83, 0xb102e308, v70
	v_sub_f32_e32 v70, v79, v78
	v_fmamk_f32 v81, v80, 0x3e9b6dac, v146
	v_sub_f32_e32 v70, v71, v70
	v_add_f32_e32 v71, v82, v83
	v_fmaak_f32 v81, v80, v81, 0x3f2aaada
	v_sub_f32_e32 v78, v71, v82
	v_ldexp_f32 v82, v79, 1
	v_mul_f32_e32 v79, v79, v80
	v_mul_f32_e32 v79, v79, v81
	v_add_f32_e32 v80, v82, v79
	v_sub_f32_e32 v81, v80, v82
	v_ldexp_f32 v70, v70, 1
	v_sub_f32_e32 v79, v79, v81
	v_add_f32_e32 v70, v70, v79
	v_add_f32_e32 v79, v80, v70
	v_sub_f32_e32 v80, v79, v80
	v_sub_f32_e32 v70, v70, v80
	v_add_f32_e32 v80, v71, v79
	v_sub_f32_e32 v81, v80, v71
	v_sub_f32_e32 v82, v80, v81
	v_sub_f32_e32 v78, v83, v78
	v_sub_f32_e32 v71, v71, v82
	v_sub_f32_e32 v79, v79, v81
	v_add_f32_e32 v71, v79, v71
	v_add_f32_e32 v79, v78, v70
	v_sub_f32_e32 v81, v79, v78
	v_sub_f32_e32 v82, v79, v81
	v_sub_f32_e32 v78, v78, v82
	v_sub_f32_e32 v70, v70, v81
	v_add_f32_e32 v71, v79, v71
	v_add_f32_e32 v70, v70, v78
	v_add_f32_e32 v78, v80, v71
	v_sub_f32_e32 v79, v78, v80
	v_sub_f32_e32 v71, v71, v79
	v_add_f32_e32 v70, v70, v71
	v_add_f32_e32 v70, v78, v70
	v_cndmask_b32_e32 v70, v147, v70, vcc
	v_cmp_lt_f32_e64 vcc, |v77|, s71
	s_nop 1
	v_cndmask_b32_e32 v70, v70, v77, vcc
	v_sub_f32_e32 v73, v73, v70
	v_lshlrev_b64 v[70:71], 15, v[98:99]
	v_lshl_add_u64 v[68:69], v[68:69], 0, v[70:71]
	global_store_dword v[68:69], v73, off

.LBB0_287:
	s_or_saveexec_b64 s[16:17], s[16:17]
	v_lshrrev_b32_e32 v68, 6, v72
	v_and_or_b32 v98, v68, 15, v74
	v_lshlrev_b64 v[72:73], 20, v[98:99]
	v_mbcnt_hi_u32_b32 v77, -1, v148
	v_lshlrev_b32_e32 v70, 2, v104
	v_lshlrev_b32_e32 v68, 1, v104
	s_xor_b64 exec, exec, s[16:17]
	s_cbranch_execz .LBB0_289
	v_mov_b32_e32 v69, s65
	v_mov_b32_e32 v71, s63
	v_cndmask_b32_e64 v79, v69, v71, s[4:5]
	v_mov_b32_e32 v69, s64
	v_mov_b32_e32 v71, s62
	v_and_b32_e32 v80, 64, v77
	v_cndmask_b32_e64 v78, v69, v71, s[4:5]
	v_xor_b32_e32 v71, 32, v77
	v_add_u32_e32 v80, 64, v80
	v_cmp_lt_i32_e32 vcc, v71, v80
	v_mul_f32_e64 v126, v46, v66
	v_mul_f32_e64 v127, v47, v66
	v_mul_f32_e64 v152, v44, v66
	v_mul_f32_e64 v153, v45, v66
	v_cndmask_b32_e32 v71, v77, v71, vcc
	v_lshlrev_b32_e32 v149, 2, v71
	v_mov_b32_e32 v71, v99
	v_lshl_add_u64 v[120:121], v[78:79], 0, v[70:71]
	global_load_dwordx4 v[44:47], v[120:121], off offset:32
	global_load_dwordx4 v[78:81], v[120:121], off
	global_load_dwordx4 v[82:85], v[120:121], off offset:224
	global_load_dwordx4 v[86:89], v[120:121], off offset:192
	v_mul_f32_e64 v158, v40, v66
	v_mul_f32_e64 v159, v41, v66
	v_mul_f32_e64 v162, v38, v66
	v_mul_f32_e64 v163, v39, v66
	global_load_dwordx4 v[38:41], v[120:121], off offset:96
	global_load_dwordx4 v[90:93], v[120:121], off offset:64
	global_load_dwordx4 v[94:97], v[120:121], off offset:160
	s_nop 0
	global_load_dwordx4 v[120:123], v[120:121], off offset:128
	v_mul_f32_e64 v50, v50, v66
	v_mul_f32_e64 v51, v51, v66
	v_mul_f32_e64 v52, v52, v66
	v_mul_f32_e64 v53, v53, v66
	v_mul_f32_e64 v186, v50, v50
	v_mul_f32_e64 v187, v51, v51
	v_mul_f32_e64 v48, v48, v66
	v_mul_f32_e64 v49, v49, v66
	v_mul_f32_e64 v42, v42, v66
	v_mul_f32_e64 v43, v43, v66
	v_mul_f32_e64 v36, v36, v66
	v_mul_f32_e64 v37, v37, v66
	v_mul_f32_e64 v34, v34, v66
	v_mul_f32_e64 v35, v35, v66
	v_mul_f32_e64 v64, v64, v66
	v_mul_f32_e64 v65, v65, v66
	v_mul_f32_e64 v62, v62, v66
	v_mul_f32_e64 v63, v63, v66
	v_mul_f32_e64 v60, v60, v66
	v_mul_f32_e64 v61, v61, v66
	v_mul_f32_e64 v58, v58, v66
	v_mul_f32_e64 v59, v59, v66
	v_mul_f32_e64 v56, v56, v66
	v_mul_f32_e64 v57, v57, v66
	v_mul_f32_e64 v54, v54, v66
	v_mul_f32_e64 v55, v55, v66
	v_mul_f32_e64 v184, v52, v52
	v_mul_f32_e64 v185, v53, v53
	v_add_f32_e32 v66, v186, v187
	v_add_f32_e32 v66, v184, v66
	v_mul_f32_e64 v182, v54, v54
	v_mul_f32_e64 v183, v55, v55
	v_add_f32_e32 v66, v185, v66
	v_add_f32_e32 v66, v182, v66
	v_mul_f32_e64 v180, v56, v56
	v_mul_f32_e64 v181, v57, v57
	v_add_f32_e32 v66, v183, v66
	v_add_f32_e32 v66, v180, v66
	v_mul_f32_e64 v178, v58, v58
	v_mul_f32_e64 v179, v59, v59
	v_add_f32_e32 v66, v181, v66
	v_add_f32_e32 v66, v178, v66
	v_mul_f32_e64 v176, v60, v60
	v_mul_f32_e64 v177, v61, v61
	v_add_f32_e32 v66, v179, v66
	v_add_f32_e32 v66, v176, v66
	v_mul_f32_e64 v174, v62, v62
	v_mul_f32_e64 v175, v63, v63
	v_add_f32_e32 v66, v177, v66
	v_add_f32_e32 v66, v174, v66
	v_mul_f32_e64 v172, v64, v64
	v_mul_f32_e64 v173, v65, v65
	v_add_f32_e32 v66, v175, v66
	v_add_f32_e32 v66, v172, v66
	v_mul_f32_e64 v170, v34, v34
	v_mul_f32_e64 v171, v35, v35
	v_add_f32_e32 v66, v173, v66
	v_add_f32_e32 v66, v170, v66
	v_mul_f32_e64 v168, v36, v36
	v_mul_f32_e64 v169, v37, v37
	v_add_f32_e32 v66, v171, v66
	v_add_f32_e32 v66, v168, v66
	v_mul_f32_e64 v164, v162, v162
	v_mul_f32_e64 v165, v163, v163
	v_add_f32_e32 v66, v169, v66
	v_add_f32_e32 v66, v164, v66
	v_mul_f32_e64 v160, v158, v158
	v_mul_f32_e64 v161, v159, v159
	v_add_f32_e32 v66, v165, v66
	v_add_f32_e32 v66, v160, v66
	v_mul_f32_e64 v156, v42, v42
	v_mul_f32_e64 v157, v43, v43
	v_add_f32_e32 v66, v161, v66
	v_add_f32_e32 v66, v156, v66
	v_mul_f32_e64 v154, v152, v152
	v_mul_f32_e64 v155, v153, v153
	v_add_f32_e32 v66, v157, v66
	v_add_f32_e32 v66, v154, v66
	v_mul_f32_e64 v150, v126, v126
	v_mul_f32_e64 v151, v127, v127
	v_add_f32_e32 v66, v155, v66
	v_add_f32_e32 v66, v150, v66
	v_mul_f32_e64 v124, v48, v48
	v_mul_f32_e64 v125, v49, v49
	v_add_f32_e32 v66, v151, v66
	v_add_f32_e32 v66, v124, v66
	v_add_f32_e32 v66, v125, v66
	ds_bpermute_b32 v71, v149, v66
	v_mov_b32_e32 v69, s57
	v_mov_b32_e32 v98, s43
	v_cndmask_b32_e64 v125, v69, v98, s[4:5]
	v_mov_b32_e32 v69, s56
	s_waitcnt lgkmcnt(0)
	v_add_f32_e32 v66, v66, v71
	v_mov_b32_e32 v98, s42
	v_fmamk_f32 v66, v66, 0x3c800000, v145
	v_cndmask_b32_e64 v124, v69, v98, s[4:5]
	v_mul_f32_e32 v69, 0x4b800000, v66
	v_cmp_gt_f32_e32 vcc, s51, v66
	v_lshl_add_u64 v[124:125], v[124:125], 0, v[72:73]
	v_lshlrev_b32_e32 v98, 7, v76
	v_cndmask_b32_e32 v66, v66, v69, vcc
	v_rsq_f32_e32 v66, v66
	v_lshl_add_u64 v[124:125], v[124:125], 0, v[98:99]
	v_mul_f32_e32 v69, 0x45800000, v66
	v_cndmask_b32_e32 v66, v66, v69, vcc
	v_mul_f32_e64 v54, v54, v66
	v_mul_f32_e64 v55, v55, v66
	v_mul_f32_e64 v34, v34, v66
	v_mul_f32_e64 v35, v35, v66
	s_waitcnt vmcnt(7)
	v_mul_f32_e64 v44, v44, v54
	v_mul_f32_e64 v45, v45, v55
	v_mul_f32_e64 v54, v56, v66
	v_mul_f32_e64 v55, v57, v66
	v_mul_f32_e64 v36, v36, v66
	v_mul_f32_e64 v37, v37, v66
	v_mul_f32_e64 v46, v46, v54
	v_mul_f32_e64 v47, v47, v55
	v_mul_f32_e64 v54, v58, v66
	v_mul_f32_e64 v55, v59, v66
	v_mul_f32_e64 v58, v62, v66
	v_mul_f32_e64 v59, v63, v66
	v_mul_f32_e64 v50, v50, v66
	v_mul_f32_e64 v51, v51, v66
	s_waitcnt vmcnt(3)
	v_mul_f32_e64 v38, v58, v38
	v_mul_f32_e64 v39, v59, v39
	v_mul_f32_e64 v58, v64, v66
	v_mul_f32_e64 v59, v65, v66
	v_mul_f32_e64 v56, v60, v66
	v_mul_f32_e64 v57, v61, v66
	v_mul_f32_e64 v40, v58, v40
	v_mul_f32_e64 v41, v59, v41
	s_waitcnt vmcnt(0)
	v_mul_f32_e64 v34, v34, v120
	v_mul_f32_e64 v35, v35, v121
	v_mul_f32_e64 v36, v36, v122
	v_mul_f32_e64 v37, v37, v123
	v_mul_f32_e64 v58, v162, v66
	v_mul_f32_e64 v59, v163, v66
	v_mul_f32_e64 v60, v158, v66
	v_mul_f32_e64 v61, v159, v66
	v_mov_b32_e32 v69, v99
	v_mul_f32_e64 v50, v78, v50
	v_mul_f32_e64 v51, v79, v51
	v_mul_f32_e64 v58, v58, v94
	v_mul_f32_e64 v59, v59, v95
	v_mul_f32_e64 v60, v60, v96
	v_mul_f32_e64 v61, v61, v97
	v_mul_f32_e64 v42, v42, v66
	v_mul_f32_e64 v43, v43, v66
	v_mul_f32_e64 v62, v152, v66
	v_mul_f32_e64 v63, v153, v66
	v_lshl_add_u64 v[78:79], v[124:125], 0, v[68:69]
	v_cvt_pk_bf16_f32 v34, v34, v35
	v_cvt_pk_bf16_f32 v35, v36, v37
	v_mul_f32_e64 v52, v52, v66
	v_mul_f32_e64 v53, v53, v66
	v_mul_f32_e64 v42, v42, v86
	v_mul_f32_e64 v43, v43, v87
	v_mul_f32_e64 v62, v62, v88
	v_mul_f32_e64 v63, v63, v89
	v_mul_f32_e64 v64, v126, v66
	v_mul_f32_e64 v65, v127, v66
	v_mul_f32_e64 v48, v48, v66
	v_mul_f32_e64 v49, v49, v66
	global_store_dwordx2 v[78:79], v[34:35], off offset:64
	v_cvt_pk_bf16_f32 v34, v58, v59
	v_cvt_pk_bf16_f32 v35, v60, v61
	v_mul_f32_e64 v52, v80, v52
	v_mul_f32_e64 v53, v81, v53
	v_mul_f32_e64 v54, v90, v54
	v_mul_f32_e64 v55, v91, v55
	v_mul_f32_e64 v56, v56, v92
	v_mul_f32_e64 v57, v57, v93
	v_mul_f32_e64 v64, v64, v82
	v_mul_f32_e64 v65, v65, v83
	v_mul_f32_e64 v48, v48, v84
	v_mul_f32_e64 v49, v49, v85
	v_cvt_pk_bf16_f32 v44, v44, v45
	v_cvt_pk_bf16_f32 v45, v46, v47
	global_store_dwordx2 v[78:79], v[34:35], off offset:80
	v_cvt_pk_bf16_f32 v34, v42, v43
	v_cvt_pk_bf16_f32 v35, v62, v63
	v_cvt_pk_bf16_f32 v50, v50, v51
	v_cvt_pk_bf16_f32 v51, v52, v53
	global_store_dwordx2 v[78:79], v[44:45], off offset:16
	v_cvt_pk_bf16_f32 v44, v54, v55
	v_cvt_pk_bf16_f32 v45, v56, v57
	v_cvt_pk_bf16_f32 v38, v38, v39
	v_cvt_pk_bf16_f32 v39, v40, v41
	global_store_dwordx2 v[78:79], v[34:35], off offset:96
	v_cvt_pk_bf16_f32 v34, v64, v65
	v_cvt_pk_bf16_f32 v35, v48, v49
	global_store_dwordx2 v[78:79], v[50:51], off
	global_store_dwordx2 v[78:79], v[44:45], off offset:32
	global_store_dwordx2 v[78:79], v[38:39], off offset:48
	global_store_dwordx2 v[78:79], v[34:35], off offset:112
.LBB0_289:
	s_or_b64 exec, exec, s[16:17]
	v_or_b32_e32 v34, v75, v142
	v_lshlrev_b32_e32 v46, 6, v34
	global_load_dwordx4 v[34:37], v46, s[44:45] offset:48
	global_load_dwordx4 v[38:41], v46, s[44:45] offset:32
	global_load_dwordx4 v[42:45], v46, s[44:45] offset:16
	s_nop 0
	global_load_dwordx4 v[46:49], v46, s[44:45]
	s_movk_i32 s2, 0x1fff
	s_waitcnt vmcnt(2)
	v_add_f32_e32 v38, v38, v39
	v_add_f32_e32 v40, v40, v41
	s_waitcnt vmcnt(0)
	v_mov_b32_e32 v50, v47
	v_mov_b32_e32 v51, v48
	v_mov_b32_e32 v47, v49
	v_mov_b32_e32 v48, v43
	v_mov_b32_e32 v49, v44
	v_mov_b32_e32 v43, v45
	v_add_f32_e64 v46, v50, v46
	v_add_f32_e64 v47, v51, v47
	v_add_f32_e64 v42, v48, v42
	v_add_f32_e64 v43, v49, v43
	v_pk_add_f32 v[46:47], v[46:47], v[46:47] op_sel:[0,1] op_sel_hi:[1,0]
	v_pk_add_f32 v[42:43], v[42:43], v[42:43] op_sel:[0,1] op_sel_hi:[1,0]
	v_mov_b32_e32 v47, v34
	v_mov_b32_e32 v43, v35
	v_mov_b32_e32 v39, v36
	v_mov_b32_e32 v41, v37
	v_add_f32_e64 v34, v46, v42
	v_add_f32_e64 v35, v47, v43
	v_add_f32_e64 v36, v38, v40
	v_add_f32_e64 v37, v39, v41
	v_bitop3_b32 v39, v75, s2, v142 bitop3:0xc8
	v_add_f32_e64 v34, v34, v36
	v_add_f32_e64 v35, v35, v37
	s_nop 0
	v_add_f32_e32 v34, v34, v35
	v_fmamk_f32 v34, v34, 0x3a800000, v145
	v_cmp_gt_f32_e32 vcc, s51, v34
	v_mul_f32_e32 v35, 0x4b800000, v34
	s_nop 0
	v_cndmask_b32_e32 v34, v34, v35, vcc
	v_rsq_f32_e32 v34, v34
	s_nop 0
	v_mul_f32_e32 v35, 0x45800000, v34
	v_cndmask_b32_e32 v38, v34, v35, vcc
	s_and_saveexec_b64 s[16:17], s[8:9]
	s_xor_b64 s[8:9], exec, s[16:17]
	s_cbranch_execz .LBB0_296
	s_andn2_b64 vcc, exec, s[14:15]
	s_mov_b64 s[14:15], -1
	s_cbranch_vccnz .LBB0_294
	s_and_saveexec_b64 s[14:15], s[6:7]
	s_cbranch_execz .LBB0_293
	global_load_dword v36, v[110:111], off
	v_lshlrev_b32_e32 v98, 2, v39
	v_lshl_add_u64 v[34:35], s[18:19], 0, v[98:99]
	v_or_b32_e32 v98, v74, v104
	s_waitcnt vmcnt(0)
	v_fmac_f32_e32 v36, v2, v38
	v_mul_f32_e64 v37, |v36|, s60
	v_fma_f32 v41, |v36|, s60, -v37
	v_rndne_f32_e32 v42, v37
	v_fma_f32 v41, |v36|, s61, v41
	v_sub_f32_e32 v37, v37, v42
	v_add_f32_e32 v37, v37, v41
	v_exp_f32_e32 v37, v37
	v_cvt_i32_f32_e32 v41, v42
	v_cmp_ngt_f32_e64 vcc, |v36|, s66
	v_min_f32_e32 v40, 0, v36
	v_ldexp_f32 v37, v37, v41
	v_cndmask_b32_e32 v37, 0, v37, vcc
	v_cmp_nlt_f32_e64 vcc, |v36|, s67
	s_nop 1
	v_cndmask_b32_e32 v41, v147, v37, vcc
	v_add_f32_e32 v42, 1.0, v41
	v_add_f32_e32 v36, -1.0, v42
	v_sub_f32_e32 v37, v36, v42
	v_add_f32_e32 v37, 1.0, v37
	v_sub_f32_e32 v36, v41, v36
	v_add_f32_e32 v43, v36, v37
	v_frexp_mant_f32_e32 v36, v42
	v_cmp_gt_f32_e32 vcc, s69, v36
	v_cvt_f64_f32_e32 v[36:37], v42
	v_frexp_exp_i32_f64_e32 v36, v[36:37]
	v_subbrev_co_u32_e32 v36, vcc, 0, v36, vcc
	v_sub_u32_e32 v37, 0, v36
	v_ldexp_f32 v42, v42, v37
	v_ldexp_f32 v37, v43, v37
	v_add_f32_e32 v43, -1.0, v42
	v_add_f32_e32 v44, 1.0, v43
	v_sub_f32_e32 v44, v42, v44
	v_add_f32_e32 v44, v37, v44
	v_add_f32_e32 v45, v43, v44
	v_sub_f32_e32 v43, v43, v45
	v_add_f32_e32 v43, v44, v43
	v_add_f32_e32 v44, 1.0, v42
	v_add_f32_e32 v46, -1.0, v44
	v_sub_f32_e32 v42, v42, v46
	v_add_f32_e32 v37, v37, v42
	v_add_f32_e32 v42, v44, v37
	v_sub_f32_e32 v44, v44, v42
	v_add_f32_e32 v37, v37, v44
	v_rcp_f32_e32 v44, v42
	v_cvt_f32_i32_e32 v36, v36
	v_cmp_neq_f32_e32 vcc, s68, v41
	v_mul_f32_e32 v46, v45, v44
	v_mul_f32_e32 v47, v42, v46
	v_fma_f32 v48, v46, v42, -v47
	v_fmac_f32_e32 v48, v46, v37
	v_add_f32_e32 v49, v47, v48
	v_sub_f32_e32 v50, v45, v49
	v_sub_f32_e32 v45, v45, v50
	v_sub_f32_e32 v47, v49, v47
	v_sub_f32_e32 v45, v45, v49
	v_add_f32_e32 v43, v43, v45
	v_sub_f32_e32 v45, v47, v48
	v_add_f32_e32 v43, v45, v43
	v_add_f32_e32 v45, v50, v43
	v_mul_f32_e32 v47, v44, v45
	v_mul_f32_e32 v48, v42, v47
	v_fma_f32 v42, v47, v42, -v48
	v_fmac_f32_e32 v42, v47, v37
	v_sub_f32_e32 v37, v50, v45
	v_add_f32_e32 v37, v43, v37
	v_add_f32_e32 v43, v48, v42
	v_sub_f32_e32 v49, v45, v43
	v_sub_f32_e32 v45, v45, v49
	v_sub_f32_e32 v48, v43, v48
	v_sub_f32_e32 v43, v45, v43
	v_add_f32_e32 v37, v37, v43
	v_sub_f32_e32 v42, v48, v42
	v_add_f32_e32 v37, v42, v37
	v_add_f32_e32 v42, v46, v47
	v_add_f32_e32 v37, v49, v37
	v_sub_f32_e32 v43, v42, v46
	v_mul_f32_e32 v37, v44, v37
	v_sub_f32_e32 v43, v47, v43
	v_add_f32_e32 v37, v43, v37
	v_mul_f32_e32 v46, 0x3f317218, v36
	v_add_f32_e32 v43, v42, v37
	v_fma_f32 v47, v36, s70, -v46
	v_mul_f32_e32 v44, v43, v43
	v_fmac_f32_e32 v47, 0xb102e308, v36
	v_sub_f32_e32 v36, v43, v42
	v_fmamk_f32 v45, v44, 0x3e9b6dac, v146
	v_sub_f32_e32 v36, v37, v36
	v_add_f32_e32 v37, v46, v47
	v_fmaak_f32 v45, v44, v45, 0x3f2aaada
	v_sub_f32_e32 v42, v37, v46
	v_ldexp_f32 v46, v43, 1
	v_mul_f32_e32 v43, v43, v44
	v_mul_f32_e32 v43, v43, v45
	v_add_f32_e32 v44, v46, v43
	v_sub_f32_e32 v45, v44, v46
	v_ldexp_f32 v36, v36, 1
	v_sub_f32_e32 v43, v43, v45
	v_add_f32_e32 v36, v36, v43
	v_add_f32_e32 v43, v44, v36
	v_sub_f32_e32 v44, v43, v44
	v_sub_f32_e32 v36, v36, v44
	v_add_f32_e32 v44, v37, v43
	v_sub_f32_e32 v45, v44, v37
	v_sub_f32_e32 v46, v44, v45
	v_sub_f32_e32 v42, v47, v42
	v_sub_f32_e32 v37, v37, v46
	v_sub_f32_e32 v43, v43, v45
	v_add_f32_e32 v37, v43, v37
	v_add_f32_e32 v43, v42, v36
	v_sub_f32_e32 v45, v43, v42
	v_sub_f32_e32 v46, v43, v45
	v_sub_f32_e32 v42, v42, v46
	v_sub_f32_e32 v36, v36, v45
	v_add_f32_e32 v37, v43, v37
	v_add_f32_e32 v36, v36, v42
	v_add_f32_e32 v42, v44, v37
	v_sub_f32_e32 v43, v42, v44
	v_sub_f32_e32 v37, v37, v43
	v_add_f32_e32 v36, v36, v37
	v_add_f32_e32 v36, v42, v36
	v_cndmask_b32_e32 v36, v147, v36, vcc
	v_cmp_lt_f32_e64 vcc, |v41|, s71
	s_nop 1
	v_cndmask_b32_e32 v36, v36, v41, vcc
	v_sub_f32_e32 v40, v40, v36
	v_lshlrev_b64 v[36:37], 15, v[98:99]
	v_lshl_add_u64 v[36:37], v[34:35], 0, v[36:37]
	global_store_dword v[36:37], v40, off
	global_load_dword v36, v[110:111], off offset:4
	v_or_b32_e32 v98, v74, v135
	s_waitcnt vmcnt(0)
	v_fmac_f32_e32 v36, v3, v38
	v_mul_f32_e64 v37, |v36|, s60
	v_fma_f32 v41, |v36|, s60, -v37
	v_rndne_f32_e32 v42, v37
	v_fma_f32 v41, |v36|, s61, v41
	v_sub_f32_e32 v37, v37, v42
	v_add_f32_e32 v37, v37, v41
	v_exp_f32_e32 v37, v37
	v_cvt_i32_f32_e32 v41, v42
	v_cmp_ngt_f32_e64 vcc, |v36|, s66
	v_min_f32_e32 v40, 0, v36
	v_ldexp_f32 v37, v37, v41
	v_cndmask_b32_e32 v37, 0, v37, vcc
	v_cmp_nlt_f32_e64 vcc, |v36|, s67
	s_nop 1
	v_cndmask_b32_e32 v41, v147, v37, vcc
	v_add_f32_e32 v42, 1.0, v41
	v_add_f32_e32 v36, -1.0, v42
	v_sub_f32_e32 v37, v36, v42
	v_add_f32_e32 v37, 1.0, v37
	v_sub_f32_e32 v36, v41, v36
	v_add_f32_e32 v43, v36, v37
	v_frexp_mant_f32_e32 v36, v42
	v_cmp_gt_f32_e32 vcc, s69, v36
	v_cvt_f64_f32_e32 v[36:37], v42
	v_frexp_exp_i32_f64_e32 v36, v[36:37]
	v_subbrev_co_u32_e32 v36, vcc, 0, v36, vcc
	v_sub_u32_e32 v37, 0, v36
	v_ldexp_f32 v42, v42, v37
	v_ldexp_f32 v37, v43, v37
	v_add_f32_e32 v43, -1.0, v42
	v_add_f32_e32 v44, 1.0, v43
	v_sub_f32_e32 v44, v42, v44
	v_add_f32_e32 v44, v37, v44
	v_add_f32_e32 v45, v43, v44
	v_sub_f32_e32 v43, v43, v45
	v_add_f32_e32 v43, v44, v43
	v_add_f32_e32 v44, 1.0, v42
	v_add_f32_e32 v46, -1.0, v44
	v_sub_f32_e32 v42, v42, v46
	v_add_f32_e32 v37, v37, v42
	v_add_f32_e32 v42, v44, v37
	v_sub_f32_e32 v44, v44, v42
	v_add_f32_e32 v37, v37, v44
	v_rcp_f32_e32 v44, v42
	v_cvt_f32_i32_e32 v36, v36
	v_cmp_neq_f32_e32 vcc, s68, v41
	v_mul_f32_e32 v46, v45, v44
	v_mul_f32_e32 v47, v42, v46
	v_fma_f32 v48, v46, v42, -v47
	v_fmac_f32_e32 v48, v46, v37
	v_add_f32_e32 v49, v47, v48
	v_sub_f32_e32 v50, v45, v49
	v_sub_f32_e32 v45, v45, v50
	v_sub_f32_e32 v47, v49, v47
	v_sub_f32_e32 v45, v45, v49
	v_add_f32_e32 v43, v43, v45
	v_sub_f32_e32 v45, v47, v48
	v_add_f32_e32 v43, v45, v43
	v_add_f32_e32 v45, v50, v43
	v_mul_f32_e32 v47, v44, v45
	v_mul_f32_e32 v48, v42, v47
	v_fma_f32 v42, v47, v42, -v48
	v_fmac_f32_e32 v42, v47, v37
	v_sub_f32_e32 v37, v50, v45
	v_add_f32_e32 v37, v43, v37
	v_add_f32_e32 v43, v48, v42
	v_sub_f32_e32 v49, v45, v43
	v_sub_f32_e32 v45, v45, v49
	v_sub_f32_e32 v48, v43, v48
	v_sub_f32_e32 v43, v45, v43
	v_add_f32_e32 v37, v37, v43
	v_sub_f32_e32 v42, v48, v42
	v_add_f32_e32 v37, v42, v37
	v_add_f32_e32 v42, v46, v47
	v_add_f32_e32 v37, v49, v37
	v_sub_f32_e32 v43, v42, v46
	v_mul_f32_e32 v37, v44, v37
	v_sub_f32_e32 v43, v47, v43
	v_add_f32_e32 v37, v43, v37
	v_mul_f32_e32 v46, 0x3f317218, v36
	v_add_f32_e32 v43, v42, v37
	v_fma_f32 v47, v36, s70, -v46
	v_mul_f32_e32 v44, v43, v43
	v_fmac_f32_e32 v47, 0xb102e308, v36
	v_sub_f32_e32 v36, v43, v42
	v_fmamk_f32 v45, v44, 0x3e9b6dac, v146
	v_sub_f32_e32 v36, v37, v36
	v_add_f32_e32 v37, v46, v47
	v_fmaak_f32 v45, v44, v45, 0x3f2aaada
	v_sub_f32_e32 v42, v37, v46
	v_ldexp_f32 v46, v43, 1
	v_mul_f32_e32 v43, v43, v44
	v_mul_f32_e32 v43, v43, v45
	v_add_f32_e32 v44, v46, v43
	v_sub_f32_e32 v45, v44, v46
	v_ldexp_f32 v36, v36, 1
	v_sub_f32_e32 v43, v43, v45
	v_add_f32_e32 v36, v36, v43
	v_add_f32_e32 v43, v44, v36
	v_sub_f32_e32 v44, v43, v44
	v_sub_f32_e32 v36, v36, v44
	v_add_f32_e32 v44, v37, v43
	v_sub_f32_e32 v45, v44, v37
	v_sub_f32_e32 v46, v44, v45
	v_sub_f32_e32 v42, v47, v42
	v_sub_f32_e32 v37, v37, v46
	v_sub_f32_e32 v43, v43, v45
	v_add_f32_e32 v37, v43, v37
	v_add_f32_e32 v43, v42, v36
	v_sub_f32_e32 v45, v43, v42
	v_sub_f32_e32 v46, v43, v45
	v_sub_f32_e32 v42, v42, v46
	v_sub_f32_e32 v36, v36, v45
	v_add_f32_e32 v37, v43, v37
	v_add_f32_e32 v36, v36, v42
	v_add_f32_e32 v42, v44, v37
	v_sub_f32_e32 v43, v42, v44
	v_sub_f32_e32 v37, v37, v43
	v_add_f32_e32 v36, v36, v37
	v_add_f32_e32 v36, v42, v36
	v_cndmask_b32_e32 v36, v147, v36, vcc
	v_cmp_lt_f32_e64 vcc, |v41|, s71
	s_nop 1
	v_cndmask_b32_e32 v36, v36, v41, vcc
	v_sub_f32_e32 v40, v40, v36
	v_lshlrev_b64 v[36:37], 15, v[98:99]
	v_lshl_add_u64 v[36:37], v[34:35], 0, v[36:37]
	global_store_dword v[36:37], v40, off
	global_load_dword v36, v[110:111], off offset:8
	v_or_b32_e32 v98, v74, v136
	s_waitcnt vmcnt(0)
	v_fmac_f32_e32 v36, v4, v38
	v_mul_f32_e64 v37, |v36|, s60
	v_fma_f32 v41, |v36|, s60, -v37
	v_rndne_f32_e32 v42, v37
	v_fma_f32 v41, |v36|, s61, v41
	v_sub_f32_e32 v37, v37, v42
	v_add_f32_e32 v37, v37, v41
	v_exp_f32_e32 v37, v37
	v_cvt_i32_f32_e32 v41, v42
	v_cmp_ngt_f32_e64 vcc, |v36|, s66
	v_min_f32_e32 v40, 0, v36
	v_ldexp_f32 v37, v37, v41
	v_cndmask_b32_e32 v37, 0, v37, vcc
	v_cmp_nlt_f32_e64 vcc, |v36|, s67
	s_nop 1
	v_cndmask_b32_e32 v41, v147, v37, vcc
	v_add_f32_e32 v42, 1.0, v41
	v_add_f32_e32 v36, -1.0, v42
	v_sub_f32_e32 v37, v36, v42
	v_add_f32_e32 v37, 1.0, v37
	v_sub_f32_e32 v36, v41, v36
	v_add_f32_e32 v43, v36, v37
	v_frexp_mant_f32_e32 v36, v42
	v_cmp_gt_f32_e32 vcc, s69, v36
	v_cvt_f64_f32_e32 v[36:37], v42
	v_frexp_exp_i32_f64_e32 v36, v[36:37]
	v_subbrev_co_u32_e32 v36, vcc, 0, v36, vcc
	v_sub_u32_e32 v37, 0, v36
	v_ldexp_f32 v42, v42, v37
	v_ldexp_f32 v37, v43, v37
	v_add_f32_e32 v43, -1.0, v42
	v_add_f32_e32 v44, 1.0, v43
	v_sub_f32_e32 v44, v42, v44
	v_add_f32_e32 v44, v37, v44
	v_add_f32_e32 v45, v43, v44
	v_sub_f32_e32 v43, v43, v45
	v_add_f32_e32 v43, v44, v43
	v_add_f32_e32 v44, 1.0, v42
	v_add_f32_e32 v46, -1.0, v44
	v_sub_f32_e32 v42, v42, v46
	v_add_f32_e32 v37, v37, v42
	v_add_f32_e32 v42, v44, v37
	v_sub_f32_e32 v44, v44, v42
	v_add_f32_e32 v37, v37, v44
	v_rcp_f32_e32 v44, v42
	v_cvt_f32_i32_e32 v36, v36
	v_cmp_neq_f32_e32 vcc, s68, v41
	v_mul_f32_e32 v46, v45, v44
	v_mul_f32_e32 v47, v42, v46
	v_fma_f32 v48, v46, v42, -v47
	v_fmac_f32_e32 v48, v46, v37
	v_add_f32_e32 v49, v47, v48
	v_sub_f32_e32 v50, v45, v49
	v_sub_f32_e32 v45, v45, v50
	v_sub_f32_e32 v47, v49, v47
	v_sub_f32_e32 v45, v45, v49
	v_add_f32_e32 v43, v43, v45
	v_sub_f32_e32 v45, v47, v48
	v_add_f32_e32 v43, v45, v43
	v_add_f32_e32 v45, v50, v43
	v_mul_f32_e32 v47, v44, v45
	v_mul_f32_e32 v48, v42, v47
	v_fma_f32 v42, v47, v42, -v48
	v_fmac_f32_e32 v42, v47, v37
	v_sub_f32_e32 v37, v50, v45
	v_add_f32_e32 v37, v43, v37
	v_add_f32_e32 v43, v48, v42
	v_sub_f32_e32 v49, v45, v43
	v_sub_f32_e32 v45, v45, v49
	v_sub_f32_e32 v48, v43, v48
	v_sub_f32_e32 v43, v45, v43
	v_add_f32_e32 v37, v37, v43
	v_sub_f32_e32 v42, v48, v42
	v_add_f32_e32 v37, v42, v37
	v_add_f32_e32 v42, v46, v47
	v_add_f32_e32 v37, v49, v37
	v_sub_f32_e32 v43, v42, v46
	v_mul_f32_e32 v37, v44, v37
	v_sub_f32_e32 v43, v47, v43
	v_add_f32_e32 v37, v43, v37
	v_mul_f32_e32 v46, 0x3f317218, v36
	v_add_f32_e32 v43, v42, v37
	v_fma_f32 v47, v36, s70, -v46
	v_mul_f32_e32 v44, v43, v43
	v_fmac_f32_e32 v47, 0xb102e308, v36
	v_sub_f32_e32 v36, v43, v42
	v_fmamk_f32 v45, v44, 0x3e9b6dac, v146
	v_sub_f32_e32 v36, v37, v36
	v_add_f32_e32 v37, v46, v47
	v_fmaak_f32 v45, v44, v45, 0x3f2aaada
	v_sub_f32_e32 v42, v37, v46
	v_ldexp_f32 v46, v43, 1
	v_mul_f32_e32 v43, v43, v44
	v_mul_f32_e32 v43, v43, v45
	v_add_f32_e32 v44, v46, v43
	v_sub_f32_e32 v45, v44, v46
	v_ldexp_f32 v36, v36, 1
	v_sub_f32_e32 v43, v43, v45
	v_add_f32_e32 v36, v36, v43
	v_add_f32_e32 v43, v44, v36
	v_sub_f32_e32 v44, v43, v44
	v_sub_f32_e32 v36, v36, v44
	v_add_f32_e32 v44, v37, v43
	v_sub_f32_e32 v45, v44, v37
	v_sub_f32_e32 v46, v44, v45
	v_sub_f32_e32 v42, v47, v42
	v_sub_f32_e32 v37, v37, v46
	v_sub_f32_e32 v43, v43, v45
	v_add_f32_e32 v37, v43, v37
	v_add_f32_e32 v43, v42, v36
	v_sub_f32_e32 v45, v43, v42
	v_sub_f32_e32 v46, v43, v45
	v_sub_f32_e32 v42, v42, v46
	v_sub_f32_e32 v36, v36, v45
	v_add_f32_e32 v37, v43, v37
	v_add_f32_e32 v36, v36, v42
	v_add_f32_e32 v42, v44, v37
	v_sub_f32_e32 v43, v42, v44
	v_sub_f32_e32 v37, v37, v43
	v_add_f32_e32 v36, v36, v37
	v_add_f32_e32 v36, v42, v36
	v_cndmask_b32_e32 v36, v147, v36, vcc
	v_cmp_lt_f32_e64 vcc, |v41|, s71
	s_nop 1
	v_cndmask_b32_e32 v36, v36, v41, vcc
	v_sub_f32_e32 v40, v40, v36
	v_lshlrev_b64 v[36:37], 15, v[98:99]
	v_lshl_add_u64 v[36:37], v[34:35], 0, v[36:37]
	global_store_dword v[36:37], v40, off
	global_load_dword v36, v[110:111], off offset:12
	v_or_b32_e32 v98, v74, v137
	s_waitcnt vmcnt(0)
	v_fmac_f32_e32 v36, v5, v38
	v_mul_f32_e64 v37, |v36|, s60
	v_fma_f32 v41, |v36|, s60, -v37
	v_rndne_f32_e32 v42, v37
	v_fma_f32 v41, |v36|, s61, v41
	v_sub_f32_e32 v37, v37, v42
	v_add_f32_e32 v37, v37, v41
	v_exp_f32_e32 v37, v37
	v_cvt_i32_f32_e32 v41, v42
	v_cmp_ngt_f32_e64 vcc, |v36|, s66
	v_min_f32_e32 v40, 0, v36
	v_ldexp_f32 v37, v37, v41
	v_cndmask_b32_e32 v37, 0, v37, vcc
	v_cmp_nlt_f32_e64 vcc, |v36|, s67
	s_nop 1
	v_cndmask_b32_e32 v41, v147, v37, vcc
	v_add_f32_e32 v42, 1.0, v41
	v_add_f32_e32 v36, -1.0, v42
	v_sub_f32_e32 v37, v36, v42
	v_add_f32_e32 v37, 1.0, v37
	v_sub_f32_e32 v36, v41, v36
	v_add_f32_e32 v43, v36, v37
	v_frexp_mant_f32_e32 v36, v42
	v_cmp_gt_f32_e32 vcc, s69, v36
	v_cvt_f64_f32_e32 v[36:37], v42
	v_frexp_exp_i32_f64_e32 v36, v[36:37]
	v_subbrev_co_u32_e32 v36, vcc, 0, v36, vcc
	v_sub_u32_e32 v37, 0, v36
	v_ldexp_f32 v42, v42, v37
	v_ldexp_f32 v37, v43, v37
	v_add_f32_e32 v43, -1.0, v42
	v_add_f32_e32 v44, 1.0, v43
	v_sub_f32_e32 v44, v42, v44
	v_add_f32_e32 v44, v37, v44
	v_add_f32_e32 v45, v43, v44
	v_sub_f32_e32 v43, v43, v45
	v_add_f32_e32 v43, v44, v43
	v_add_f32_e32 v44, 1.0, v42
	v_add_f32_e32 v46, -1.0, v44
	v_sub_f32_e32 v42, v42, v46
	v_add_f32_e32 v37, v37, v42
	v_add_f32_e32 v42, v44, v37
	v_sub_f32_e32 v44, v44, v42
	v_add_f32_e32 v37, v37, v44
	v_rcp_f32_e32 v44, v42
	v_cvt_f32_i32_e32 v36, v36
	v_cmp_neq_f32_e32 vcc, s68, v41
	v_mul_f32_e32 v46, v45, v44
	v_mul_f32_e32 v47, v42, v46
	v_fma_f32 v48, v46, v42, -v47
	v_fmac_f32_e32 v48, v46, v37
	v_add_f32_e32 v49, v47, v48
	v_sub_f32_e32 v50, v45, v49
	v_sub_f32_e32 v45, v45, v50
	v_sub_f32_e32 v47, v49, v47
	v_sub_f32_e32 v45, v45, v49
	v_add_f32_e32 v43, v43, v45
	v_sub_f32_e32 v45, v47, v48
	v_add_f32_e32 v43, v45, v43
	v_add_f32_e32 v45, v50, v43
	v_mul_f32_e32 v47, v44, v45
	v_mul_f32_e32 v48, v42, v47
	v_fma_f32 v42, v47, v42, -v48
	v_fmac_f32_e32 v42, v47, v37
	v_sub_f32_e32 v37, v50, v45
	v_add_f32_e32 v37, v43, v37
	v_add_f32_e32 v43, v48, v42
	v_sub_f32_e32 v49, v45, v43
	v_sub_f32_e32 v45, v45, v49
	v_sub_f32_e32 v48, v43, v48
	v_sub_f32_e32 v43, v45, v43
	v_add_f32_e32 v37, v37, v43
	v_sub_f32_e32 v42, v48, v42
	v_add_f32_e32 v37, v42, v37
	v_add_f32_e32 v42, v46, v47
	v_add_f32_e32 v37, v49, v37
	v_sub_f32_e32 v43, v42, v46
	v_mul_f32_e32 v37, v44, v37
	v_sub_f32_e32 v43, v47, v43
	v_add_f32_e32 v37, v43, v37
	v_mul_f32_e32 v46, 0x3f317218, v36
	v_add_f32_e32 v43, v42, v37
	v_fma_f32 v47, v36, s70, -v46
	v_mul_f32_e32 v44, v43, v43
	v_fmac_f32_e32 v47, 0xb102e308, v36
	v_sub_f32_e32 v36, v43, v42
	v_fmamk_f32 v45, v44, 0x3e9b6dac, v146
	v_sub_f32_e32 v36, v37, v36
	v_add_f32_e32 v37, v46, v47
	v_fmaak_f32 v45, v44, v45, 0x3f2aaada
	v_sub_f32_e32 v42, v37, v46
	v_ldexp_f32 v46, v43, 1
	v_mul_f32_e32 v43, v43, v44
	v_mul_f32_e32 v43, v43, v45
	v_add_f32_e32 v44, v46, v43
	v_sub_f32_e32 v45, v44, v46
	v_ldexp_f32 v36, v36, 1
	v_sub_f32_e32 v43, v43, v45
	v_add_f32_e32 v36, v36, v43
	v_add_f32_e32 v43, v44, v36
	v_sub_f32_e32 v44, v43, v44
	v_sub_f32_e32 v36, v36, v44
	v_add_f32_e32 v44, v37, v43
	v_sub_f32_e32 v45, v44, v37
	v_sub_f32_e32 v46, v44, v45
	v_sub_f32_e32 v42, v47, v42
	v_sub_f32_e32 v37, v37, v46
	v_sub_f32_e32 v43, v43, v45
	v_add_f32_e32 v37, v43, v37
	v_add_f32_e32 v43, v42, v36
	v_sub_f32_e32 v45, v43, v42
	v_sub_f32_e32 v46, v43, v45
	v_sub_f32_e32 v42, v42, v46
	v_sub_f32_e32 v36, v36, v45
	v_add_f32_e32 v37, v43, v37
	v_add_f32_e32 v36, v36, v42
	v_add_f32_e32 v42, v44, v37
	v_sub_f32_e32 v43, v42, v44
	v_sub_f32_e32 v37, v37, v43
	v_add_f32_e32 v36, v36, v37
	v_add_f32_e32 v36, v42, v36
	v_cndmask_b32_e32 v36, v147, v36, vcc
	v_cmp_lt_f32_e64 vcc, |v41|, s71
	s_nop 1
	v_cndmask_b32_e32 v36, v36, v41, vcc
	v_sub_f32_e32 v40, v40, v36
	v_lshlrev_b64 v[36:37], 15, v[98:99]
	v_lshl_add_u64 v[36:37], v[34:35], 0, v[36:37]
	global_store_dword v[36:37], v40, off
	global_load_dword v36, v[110:111], off offset:32
	v_or_b32_e32 v98, v74, v138
	s_waitcnt vmcnt(0)
	v_fmac_f32_e32 v36, v6, v38
	v_mul_f32_e64 v37, |v36|, s60
	v_fma_f32 v41, |v36|, s60, -v37
	v_rndne_f32_e32 v42, v37
	v_fma_f32 v41, |v36|, s61, v41
	v_sub_f32_e32 v37, v37, v42
	v_add_f32_e32 v37, v37, v41
	v_exp_f32_e32 v37, v37
	v_cvt_i32_f32_e32 v41, v42
	v_cmp_ngt_f32_e64 vcc, |v36|, s66
	v_min_f32_e32 v40, 0, v36
	v_ldexp_f32 v37, v37, v41
	v_cndmask_b32_e32 v37, 0, v37, vcc
	v_cmp_nlt_f32_e64 vcc, |v36|, s67
	s_nop 1
	v_cndmask_b32_e32 v41, v147, v37, vcc
	v_add_f32_e32 v42, 1.0, v41
	v_add_f32_e32 v36, -1.0, v42
	v_sub_f32_e32 v37, v36, v42
	v_add_f32_e32 v37, 1.0, v37
	v_sub_f32_e32 v36, v41, v36
	v_add_f32_e32 v43, v36, v37
	v_frexp_mant_f32_e32 v36, v42
	v_cmp_gt_f32_e32 vcc, s69, v36
	v_cvt_f64_f32_e32 v[36:37], v42
	v_frexp_exp_i32_f64_e32 v36, v[36:37]
	v_subbrev_co_u32_e32 v36, vcc, 0, v36, vcc
	v_sub_u32_e32 v37, 0, v36
	v_ldexp_f32 v42, v42, v37
	v_ldexp_f32 v37, v43, v37
	v_add_f32_e32 v43, -1.0, v42
	v_add_f32_e32 v44, 1.0, v43
	v_sub_f32_e32 v44, v42, v44
	v_add_f32_e32 v44, v37, v44
	v_add_f32_e32 v45, v43, v44
	v_sub_f32_e32 v43, v43, v45
	v_add_f32_e32 v43, v44, v43
	v_add_f32_e32 v44, 1.0, v42
	v_add_f32_e32 v46, -1.0, v44
	v_sub_f32_e32 v42, v42, v46
	v_add_f32_e32 v37, v37, v42
	v_add_f32_e32 v42, v44, v37
	v_sub_f32_e32 v44, v44, v42
	v_add_f32_e32 v37, v37, v44
	v_rcp_f32_e32 v44, v42
	v_cvt_f32_i32_e32 v36, v36
	v_cmp_neq_f32_e32 vcc, s68, v41
	v_mul_f32_e32 v46, v45, v44
	v_mul_f32_e32 v47, v42, v46
	v_fma_f32 v48, v46, v42, -v47
	v_fmac_f32_e32 v48, v46, v37
	v_add_f32_e32 v49, v47, v48
	v_sub_f32_e32 v50, v45, v49
	v_sub_f32_e32 v45, v45, v50
	v_sub_f32_e32 v47, v49, v47
	v_sub_f32_e32 v45, v45, v49
	v_add_f32_e32 v43, v43, v45
	v_sub_f32_e32 v45, v47, v48
	v_add_f32_e32 v43, v45, v43
	v_add_f32_e32 v45, v50, v43
	v_mul_f32_e32 v47, v44, v45
	v_mul_f32_e32 v48, v42, v47
	v_fma_f32 v42, v47, v42, -v48
	v_fmac_f32_e32 v42, v47, v37
	v_sub_f32_e32 v37, v50, v45
	v_add_f32_e32 v37, v43, v37
	v_add_f32_e32 v43, v48, v42
	v_sub_f32_e32 v49, v45, v43
	v_sub_f32_e32 v45, v45, v49
	v_sub_f32_e32 v48, v43, v48
	v_sub_f32_e32 v43, v45, v43
	v_add_f32_e32 v37, v37, v43
	v_sub_f32_e32 v42, v48, v42
	v_add_f32_e32 v37, v42, v37
	v_add_f32_e32 v42, v46, v47
	v_add_f32_e32 v37, v49, v37
	v_sub_f32_e32 v43, v42, v46
	v_mul_f32_e32 v37, v44, v37
	v_sub_f32_e32 v43, v47, v43
	v_add_f32_e32 v37, v43, v37
	v_mul_f32_e32 v46, 0x3f317218, v36
	v_add_f32_e32 v43, v42, v37
	v_fma_f32 v47, v36, s70, -v46
	v_mul_f32_e32 v44, v43, v43
	v_fmac_f32_e32 v47, 0xb102e308, v36
	v_sub_f32_e32 v36, v43, v42
	v_fmamk_f32 v45, v44, 0x3e9b6dac, v146
	v_sub_f32_e32 v36, v37, v36
	v_add_f32_e32 v37, v46, v47
	v_fmaak_f32 v45, v44, v45, 0x3f2aaada
	v_sub_f32_e32 v42, v37, v46
	v_ldexp_f32 v46, v43, 1
	v_mul_f32_e32 v43, v43, v44
	v_mul_f32_e32 v43, v43, v45
	v_add_f32_e32 v44, v46, v43
	v_sub_f32_e32 v45, v44, v46
	v_ldexp_f32 v36, v36, 1
	v_sub_f32_e32 v43, v43, v45
	v_add_f32_e32 v36, v36, v43
	v_add_f32_e32 v43, v44, v36
	v_sub_f32_e32 v44, v43, v44
	v_sub_f32_e32 v36, v36, v44
	v_add_f32_e32 v44, v37, v43
	v_sub_f32_e32 v45, v44, v37
	v_sub_f32_e32 v46, v44, v45
	v_sub_f32_e32 v42, v47, v42
	v_sub_f32_e32 v37, v37, v46
	v_sub_f32_e32 v43, v43, v45
	v_add_f32_e32 v37, v43, v37
	v_add_f32_e32 v43, v42, v36
	v_sub_f32_e32 v45, v43, v42
	v_sub_f32_e32 v46, v43, v45
	v_sub_f32_e32 v42, v42, v46
	v_sub_f32_e32 v36, v36, v45
	v_add_f32_e32 v37, v43, v37
	v_add_f32_e32 v36, v36, v42
	v_add_f32_e32 v42, v44, v37
	v_sub_f32_e32 v43, v42, v44
	v_sub_f32_e32 v37, v37, v43
	v_add_f32_e32 v36, v36, v37
	v_add_f32_e32 v36, v42, v36
	v_cndmask_b32_e32 v36, v147, v36, vcc
	v_cmp_lt_f32_e64 vcc, |v41|, s71
	s_nop 1
	v_cndmask_b32_e32 v36, v36, v41, vcc
	v_sub_f32_e32 v40, v40, v36
	v_lshlrev_b64 v[36:37], 15, v[98:99]
	v_lshl_add_u64 v[36:37], v[34:35], 0, v[36:37]
	global_store_dword v[36:37], v40, off
	global_load_dword v36, v[110:111], off offset:36
	v_or_b32_e32 v98, v74, v139
	s_waitcnt vmcnt(0)
	v_fmac_f32_e32 v36, v7, v38
	v_mul_f32_e64 v37, |v36|, s60
	v_fma_f32 v41, |v36|, s60, -v37
	v_rndne_f32_e32 v42, v37
	v_fma_f32 v41, |v36|, s61, v41
	v_sub_f32_e32 v37, v37, v42
	v_add_f32_e32 v37, v37, v41
	v_exp_f32_e32 v37, v37
	v_cvt_i32_f32_e32 v41, v42
	v_cmp_ngt_f32_e64 vcc, |v36|, s66
	v_min_f32_e32 v40, 0, v36
	v_ldexp_f32 v37, v37, v41
	v_cndmask_b32_e32 v37, 0, v37, vcc
	v_cmp_nlt_f32_e64 vcc, |v36|, s67
	s_nop 1
	v_cndmask_b32_e32 v41, v147, v37, vcc
	v_add_f32_e32 v42, 1.0, v41
	v_add_f32_e32 v36, -1.0, v42
	v_sub_f32_e32 v37, v36, v42
	v_add_f32_e32 v37, 1.0, v37
	v_sub_f32_e32 v36, v41, v36
	v_add_f32_e32 v43, v36, v37
	v_frexp_mant_f32_e32 v36, v42
	v_cmp_gt_f32_e32 vcc, s69, v36
	v_cvt_f64_f32_e32 v[36:37], v42
	v_frexp_exp_i32_f64_e32 v36, v[36:37]
	v_subbrev_co_u32_e32 v36, vcc, 0, v36, vcc
	v_sub_u32_e32 v37, 0, v36
	v_ldexp_f32 v42, v42, v37
	v_ldexp_f32 v37, v43, v37
	v_add_f32_e32 v43, -1.0, v42
	v_add_f32_e32 v44, 1.0, v43
	v_sub_f32_e32 v44, v42, v44
	v_add_f32_e32 v44, v37, v44
	v_add_f32_e32 v45, v43, v44
	v_sub_f32_e32 v43, v43, v45
	v_add_f32_e32 v43, v44, v43
	v_add_f32_e32 v44, 1.0, v42
	v_add_f32_e32 v46, -1.0, v44
	v_sub_f32_e32 v42, v42, v46
	v_add_f32_e32 v37, v37, v42
	v_add_f32_e32 v42, v44, v37
	v_sub_f32_e32 v44, v44, v42
	v_add_f32_e32 v37, v37, v44
	v_rcp_f32_e32 v44, v42
	v_cvt_f32_i32_e32 v36, v36
	v_cmp_neq_f32_e32 vcc, s68, v41
	v_mul_f32_e32 v46, v45, v44
	v_mul_f32_e32 v47, v42, v46
	v_fma_f32 v48, v46, v42, -v47
	v_fmac_f32_e32 v48, v46, v37
	v_add_f32_e32 v49, v47, v48
	v_sub_f32_e32 v50, v45, v49
	v_sub_f32_e32 v45, v45, v50
	v_sub_f32_e32 v47, v49, v47
	v_sub_f32_e32 v45, v45, v49
	v_add_f32_e32 v43, v43, v45
	v_sub_f32_e32 v45, v47, v48
	v_add_f32_e32 v43, v45, v43
	v_add_f32_e32 v45, v50, v43
	v_mul_f32_e32 v47, v44, v45
	v_mul_f32_e32 v48, v42, v47
	v_fma_f32 v42, v47, v42, -v48
	v_fmac_f32_e32 v42, v47, v37
	v_sub_f32_e32 v37, v50, v45
	v_add_f32_e32 v37, v43, v37
	v_add_f32_e32 v43, v48, v42
	v_sub_f32_e32 v49, v45, v43
	v_sub_f32_e32 v45, v45, v49
	v_sub_f32_e32 v48, v43, v48
	v_sub_f32_e32 v43, v45, v43
	v_add_f32_e32 v37, v37, v43
	v_sub_f32_e32 v42, v48, v42
	v_add_f32_e32 v37, v42, v37
	v_add_f32_e32 v42, v46, v47
	v_add_f32_e32 v37, v49, v37
	v_sub_f32_e32 v43, v42, v46
	v_mul_f32_e32 v37, v44, v37
	v_sub_f32_e32 v43, v47, v43
	v_add_f32_e32 v37, v43, v37
	v_mul_f32_e32 v46, 0x3f317218, v36
	v_add_f32_e32 v43, v42, v37
	v_fma_f32 v47, v36, s70, -v46
	v_mul_f32_e32 v44, v43, v43
	v_fmac_f32_e32 v47, 0xb102e308, v36
	v_sub_f32_e32 v36, v43, v42
	v_fmamk_f32 v45, v44, 0x3e9b6dac, v146
	v_sub_f32_e32 v36, v37, v36
	v_add_f32_e32 v37, v46, v47
	v_fmaak_f32 v45, v44, v45, 0x3f2aaada
	v_sub_f32_e32 v42, v37, v46
	v_ldexp_f32 v46, v43, 1
	v_mul_f32_e32 v43, v43, v44
	v_mul_f32_e32 v43, v43, v45
	v_add_f32_e32 v44, v46, v43
	v_sub_f32_e32 v45, v44, v46
	v_ldexp_f32 v36, v36, 1
	v_sub_f32_e32 v43, v43, v45
	v_add_f32_e32 v36, v36, v43
	v_add_f32_e32 v43, v44, v36
	v_sub_f32_e32 v44, v43, v44
	v_sub_f32_e32 v36, v36, v44
	v_add_f32_e32 v44, v37, v43
	v_sub_f32_e32 v45, v44, v37
	v_sub_f32_e32 v46, v44, v45
	v_sub_f32_e32 v42, v47, v42
	v_sub_f32_e32 v37, v37, v46
	v_sub_f32_e32 v43, v43, v45
	v_add_f32_e32 v37, v43, v37
	v_add_f32_e32 v43, v42, v36
	v_sub_f32_e32 v45, v43, v42
	v_sub_f32_e32 v46, v43, v45
	v_sub_f32_e32 v42, v42, v46
	v_sub_f32_e32 v36, v36, v45
	v_add_f32_e32 v37, v43, v37
	v_add_f32_e32 v36, v36, v42
	v_add_f32_e32 v42, v44, v37
	v_sub_f32_e32 v43, v42, v44
	v_sub_f32_e32 v37, v37, v43
	v_add_f32_e32 v36, v36, v37
	v_add_f32_e32 v36, v42, v36
	v_cndmask_b32_e32 v36, v147, v36, vcc
	v_cmp_lt_f32_e64 vcc, |v41|, s71
	s_nop 1
	v_cndmask_b32_e32 v36, v36, v41, vcc
	v_sub_f32_e32 v40, v40, v36
	v_lshlrev_b64 v[36:37], 15, v[98:99]
	v_lshl_add_u64 v[36:37], v[34:35], 0, v[36:37]
	global_store_dword v[36:37], v40, off
	global_load_dword v36, v[110:111], off offset:40
	v_or_b32_e32 v98, v74, v140
	s_waitcnt vmcnt(0)
	v_fmac_f32_e32 v36, v8, v38
	v_mul_f32_e64 v37, |v36|, s60
	v_fma_f32 v41, |v36|, s60, -v37
	v_rndne_f32_e32 v42, v37
	v_fma_f32 v41, |v36|, s61, v41
	v_sub_f32_e32 v37, v37, v42
	v_add_f32_e32 v37, v37, v41
	v_exp_f32_e32 v37, v37
	v_cvt_i32_f32_e32 v41, v42
	v_cmp_ngt_f32_e64 vcc, |v36|, s66
	v_min_f32_e32 v40, 0, v36
	v_ldexp_f32 v37, v37, v41
	v_cndmask_b32_e32 v37, 0, v37, vcc
	v_cmp_nlt_f32_e64 vcc, |v36|, s67
	s_nop 1
	v_cndmask_b32_e32 v41, v147, v37, vcc
	v_add_f32_e32 v42, 1.0, v41
	v_add_f32_e32 v36, -1.0, v42
	v_sub_f32_e32 v37, v36, v42
	v_add_f32_e32 v37, 1.0, v37
	v_sub_f32_e32 v36, v41, v36
	v_add_f32_e32 v43, v36, v37
	v_frexp_mant_f32_e32 v36, v42
	v_cmp_gt_f32_e32 vcc, s69, v36
	v_cvt_f64_f32_e32 v[36:37], v42
	v_frexp_exp_i32_f64_e32 v36, v[36:37]
	v_subbrev_co_u32_e32 v36, vcc, 0, v36, vcc
	v_sub_u32_e32 v37, 0, v36
	v_ldexp_f32 v42, v42, v37
	v_ldexp_f32 v37, v43, v37
	v_add_f32_e32 v43, -1.0, v42
	v_add_f32_e32 v44, 1.0, v43
	v_sub_f32_e32 v44, v42, v44
	v_add_f32_e32 v44, v37, v44
	v_add_f32_e32 v45, v43, v44
	v_sub_f32_e32 v43, v43, v45
	v_add_f32_e32 v43, v44, v43
	v_add_f32_e32 v44, 1.0, v42
	v_add_f32_e32 v46, -1.0, v44
	v_sub_f32_e32 v42, v42, v46
	v_add_f32_e32 v37, v37, v42
	v_add_f32_e32 v42, v44, v37
	v_sub_f32_e32 v44, v44, v42
	v_add_f32_e32 v37, v37, v44
	v_rcp_f32_e32 v44, v42
	v_cvt_f32_i32_e32 v36, v36
	v_cmp_neq_f32_e32 vcc, s68, v41
	v_mul_f32_e32 v46, v45, v44
	v_mul_f32_e32 v47, v42, v46
	v_fma_f32 v48, v46, v42, -v47
	v_fmac_f32_e32 v48, v46, v37
	v_add_f32_e32 v49, v47, v48
	v_sub_f32_e32 v50, v45, v49
	v_sub_f32_e32 v45, v45, v50
	v_sub_f32_e32 v47, v49, v47
	v_sub_f32_e32 v45, v45, v49
	v_add_f32_e32 v43, v43, v45
	v_sub_f32_e32 v45, v47, v48
	v_add_f32_e32 v43, v45, v43
	v_add_f32_e32 v45, v50, v43
	v_mul_f32_e32 v47, v44, v45
	v_mul_f32_e32 v48, v42, v47
	v_fma_f32 v42, v47, v42, -v48
	v_fmac_f32_e32 v42, v47, v37
	v_sub_f32_e32 v37, v50, v45
	v_add_f32_e32 v37, v43, v37
	v_add_f32_e32 v43, v48, v42
	v_sub_f32_e32 v49, v45, v43
	v_sub_f32_e32 v45, v45, v49
	v_sub_f32_e32 v48, v43, v48
	v_sub_f32_e32 v43, v45, v43
	v_add_f32_e32 v37, v37, v43
	v_sub_f32_e32 v42, v48, v42
	v_add_f32_e32 v37, v42, v37
	v_add_f32_e32 v42, v46, v47
	v_add_f32_e32 v37, v49, v37
	v_sub_f32_e32 v43, v42, v46
	v_mul_f32_e32 v37, v44, v37
	v_sub_f32_e32 v43, v47, v43
	v_add_f32_e32 v37, v43, v37
	v_mul_f32_e32 v46, 0x3f317218, v36
	v_add_f32_e32 v43, v42, v37
	v_fma_f32 v47, v36, s70, -v46
	v_mul_f32_e32 v44, v43, v43
	v_fmac_f32_e32 v47, 0xb102e308, v36
	v_sub_f32_e32 v36, v43, v42
	v_fmamk_f32 v45, v44, 0x3e9b6dac, v146
	v_sub_f32_e32 v36, v37, v36
	v_add_f32_e32 v37, v46, v47
	v_fmaak_f32 v45, v44, v45, 0x3f2aaada
	v_sub_f32_e32 v42, v37, v46
	v_ldexp_f32 v46, v43, 1
	v_mul_f32_e32 v43, v43, v44
	v_mul_f32_e32 v43, v43, v45
	v_add_f32_e32 v44, v46, v43
	v_sub_f32_e32 v45, v44, v46
	v_ldexp_f32 v36, v36, 1
	v_sub_f32_e32 v43, v43, v45
	v_add_f32_e32 v36, v36, v43
	v_add_f32_e32 v43, v44, v36
	v_sub_f32_e32 v44, v43, v44
	v_sub_f32_e32 v36, v36, v44
	v_add_f32_e32 v44, v37, v43
	v_sub_f32_e32 v45, v44, v37
	v_sub_f32_e32 v46, v44, v45
	v_sub_f32_e32 v42, v47, v42
	v_sub_f32_e32 v37, v37, v46
	v_sub_f32_e32 v43, v43, v45
	v_add_f32_e32 v37, v43, v37
	v_add_f32_e32 v43, v42, v36
	v_sub_f32_e32 v45, v43, v42
	v_sub_f32_e32 v46, v43, v45
	v_sub_f32_e32 v42, v42, v46
	v_sub_f32_e32 v36, v36, v45
	v_add_f32_e32 v37, v43, v37
	v_add_f32_e32 v36, v36, v42
	v_add_f32_e32 v42, v44, v37
	v_sub_f32_e32 v43, v42, v44
	v_sub_f32_e32 v37, v37, v43
	v_add_f32_e32 v36, v36, v37
	v_add_f32_e32 v36, v42, v36
	v_cndmask_b32_e32 v36, v147, v36, vcc
	v_cmp_lt_f32_e64 vcc, |v41|, s71
	s_nop 1
	v_cndmask_b32_e32 v36, v36, v41, vcc
	v_sub_f32_e32 v40, v40, v36
	v_lshlrev_b64 v[36:37], 15, v[98:99]
	v_lshl_add_u64 v[36:37], v[34:35], 0, v[36:37]
	global_store_dword v[36:37], v40, off
	global_load_dword v36, v[110:111], off offset:44
	v_or_b32_e32 v98, v74, v141
	s_waitcnt vmcnt(0)
	v_fmac_f32_e32 v36, v9, v38
	v_mul_f32_e64 v37, |v36|, s60
	v_fma_f32 v41, |v36|, s60, -v37
	v_rndne_f32_e32 v42, v37
	v_fma_f32 v41, |v36|, s61, v41
	v_sub_f32_e32 v37, v37, v42
	v_add_f32_e32 v37, v37, v41
	v_exp_f32_e32 v37, v37
	v_cvt_i32_f32_e32 v41, v42
	v_cmp_ngt_f32_e64 vcc, |v36|, s66
	v_min_f32_e32 v40, 0, v36
	v_ldexp_f32 v37, v37, v41
	v_cndmask_b32_e32 v37, 0, v37, vcc
	v_cmp_nlt_f32_e64 vcc, |v36|, s67
	s_nop 1
	v_cndmask_b32_e32 v41, v147, v37, vcc
	v_add_f32_e32 v42, 1.0, v41
	v_add_f32_e32 v36, -1.0, v42
	v_sub_f32_e32 v37, v36, v42
	v_add_f32_e32 v37, 1.0, v37
	v_sub_f32_e32 v36, v41, v36
	v_add_f32_e32 v43, v36, v37
	v_frexp_mant_f32_e32 v36, v42
	v_cmp_gt_f32_e32 vcc, s69, v36
	v_cvt_f64_f32_e32 v[36:37], v42
	v_frexp_exp_i32_f64_e32 v36, v[36:37]
	v_subbrev_co_u32_e32 v36, vcc, 0, v36, vcc
	v_sub_u32_e32 v37, 0, v36
	v_ldexp_f32 v42, v42, v37
	v_ldexp_f32 v37, v43, v37
	v_add_f32_e32 v43, -1.0, v42
	v_add_f32_e32 v44, 1.0, v43
	v_sub_f32_e32 v44, v42, v44
	v_add_f32_e32 v44, v37, v44
	v_add_f32_e32 v45, v43, v44
	v_sub_f32_e32 v43, v43, v45
	v_add_f32_e32 v43, v44, v43
	v_add_f32_e32 v44, 1.0, v42
	v_add_f32_e32 v46, -1.0, v44
	v_sub_f32_e32 v42, v42, v46
	v_add_f32_e32 v37, v37, v42
	v_add_f32_e32 v42, v44, v37
	v_sub_f32_e32 v44, v44, v42
	v_add_f32_e32 v37, v37, v44
	v_rcp_f32_e32 v44, v42
	v_cvt_f32_i32_e32 v36, v36
	v_cmp_neq_f32_e32 vcc, s68, v41
	v_mul_f32_e32 v46, v45, v44
	v_mul_f32_e32 v47, v42, v46
	v_fma_f32 v48, v46, v42, -v47
	v_fmac_f32_e32 v48, v46, v37
	v_add_f32_e32 v49, v47, v48
	v_sub_f32_e32 v50, v45, v49
	v_sub_f32_e32 v45, v45, v50
	v_sub_f32_e32 v47, v49, v47
	v_sub_f32_e32 v45, v45, v49
	v_add_f32_e32 v43, v43, v45
	v_sub_f32_e32 v45, v47, v48
	v_add_f32_e32 v43, v45, v43
	v_add_f32_e32 v45, v50, v43
	v_mul_f32_e32 v47, v44, v45
	v_mul_f32_e32 v48, v42, v47
	v_fma_f32 v42, v47, v42, -v48
	v_fmac_f32_e32 v42, v47, v37
	v_sub_f32_e32 v37, v50, v45
	v_add_f32_e32 v37, v43, v37
	v_add_f32_e32 v43, v48, v42
	v_sub_f32_e32 v49, v45, v43
	v_sub_f32_e32 v45, v45, v49
	v_sub_f32_e32 v48, v43, v48
	v_sub_f32_e32 v43, v45, v43
	v_add_f32_e32 v37, v37, v43
	v_sub_f32_e32 v42, v48, v42
	v_add_f32_e32 v37, v42, v37
	v_add_f32_e32 v42, v46, v47
	v_add_f32_e32 v37, v49, v37
	v_sub_f32_e32 v43, v42, v46
	v_mul_f32_e32 v37, v44, v37
	v_sub_f32_e32 v43, v47, v43
	v_add_f32_e32 v37, v43, v37
	v_mul_f32_e32 v46, 0x3f317218, v36
	v_add_f32_e32 v43, v42, v37
	v_fma_f32 v47, v36, s70, -v46
	v_mul_f32_e32 v44, v43, v43
	v_fmac_f32_e32 v47, 0xb102e308, v36
	v_sub_f32_e32 v36, v43, v42
	v_fmamk_f32 v45, v44, 0x3e9b6dac, v146
	v_sub_f32_e32 v36, v37, v36
	v_add_f32_e32 v37, v46, v47
	v_fmaak_f32 v45, v44, v45, 0x3f2aaada
	v_sub_f32_e32 v42, v37, v46
	v_ldexp_f32 v46, v43, 1
	v_mul_f32_e32 v43, v43, v44
	v_mul_f32_e32 v43, v43, v45
	v_add_f32_e32 v44, v46, v43
	v_sub_f32_e32 v45, v44, v46
	v_ldexp_f32 v36, v36, 1
	v_sub_f32_e32 v43, v43, v45
	v_add_f32_e32 v36, v36, v43
	v_add_f32_e32 v43, v44, v36
	v_sub_f32_e32 v44, v43, v44
	v_sub_f32_e32 v36, v36, v44
	v_add_f32_e32 v44, v37, v43
	v_sub_f32_e32 v45, v44, v37
	v_sub_f32_e32 v46, v44, v45
	v_sub_f32_e32 v42, v47, v42
	v_sub_f32_e32 v37, v37, v46
	v_sub_f32_e32 v43, v43, v45
	v_add_f32_e32 v37, v43, v37
	v_add_f32_e32 v43, v42, v36
	v_sub_f32_e32 v45, v43, v42
	v_sub_f32_e32 v46, v43, v45
	v_sub_f32_e32 v42, v42, v46
	v_sub_f32_e32 v36, v36, v45
	v_add_f32_e32 v37, v43, v37
	v_add_f32_e32 v36, v36, v42
	v_add_f32_e32 v42, v44, v37
	v_sub_f32_e32 v43, v42, v44
	v_sub_f32_e32 v37, v37, v43
	v_add_f32_e32 v36, v36, v37
	v_add_f32_e32 v36, v42, v36
	v_cndmask_b32_e32 v36, v147, v36, vcc
	v_cmp_lt_f32_e64 vcc, |v41|, s71
	s_nop 1
	v_cndmask_b32_e32 v36, v36, v41, vcc
	v_sub_f32_e32 v40, v40, v36
	v_lshlrev_b64 v[36:37], 15, v[98:99]
	v_lshl_add_u64 v[34:35], v[34:35], 0, v[36:37]
	global_store_dword v[34:35], v40, off

.LBB0_296:
	s_andn2_saveexec_b64 s[6:7], s[8:9]
	s_cbranch_execz .LBB0_279
	v_mov_b32_e32 v34, s65
	v_mov_b32_e32 v35, s63
	v_cndmask_b32_e64 v35, v34, v35, s[4:5]
	v_mov_b32_e32 v34, s64
	v_mov_b32_e32 v36, s62
	v_cndmask_b32_e64 v34, v34, v36, s[4:5]
	v_mov_b32_e32 v71, v99
	v_lshl_add_u64 v[80:81], v[34:35], 0, v[70:71]
	v_mul_f32_e64 v62, v10, v38
	v_mul_f32_e64 v63, v11, v38
	v_mul_f32_e64 v64, v8, v38
	v_mul_f32_e64 v65, v9, v38
	global_load_dwordx4 v[8:11], v[80:81], off offset:32
	v_mov_b32_e32 v36, s57
	v_mov_b32_e32 v37, s43
	v_mul_f32_e64 v58, v14, v38
	v_mul_f32_e64 v59, v15, v38
	v_mul_f32_e64 v60, v12, v38
	v_mul_f32_e64 v61, v13, v38
	global_load_dwordx4 v[12:15], v[80:81], off offset:64
	v_cndmask_b32_e64 v37, v36, v37, s[4:5]
	v_mov_b32_e32 v36, s56
	v_mov_b32_e32 v40, s42
	v_cndmask_b32_e64 v36, v36, v40, s[4:5]
	v_mul_f32_e64 v54, v18, v38
	v_mul_f32_e64 v55, v19, v38
	v_mul_f32_e64 v56, v16, v38
	v_mul_f32_e64 v57, v17, v38
	global_load_dwordx4 v[16:19], v[80:81], off offset:96
	v_lshl_add_u64 v[36:37], v[36:37], 0, v[72:73]
	v_lshlrev_b32_e32 v98, 7, v39
	v_lshl_add_u64 v[40:41], v[36:37], 0, v[98:99]
	v_and_b32_e32 v37, 64, v77
	v_mul_f32_e64 v50, v22, v38
	v_mul_f32_e64 v51, v23, v38
	v_mul_f32_e64 v52, v20, v38
	v_mul_f32_e64 v53, v21, v38
	global_load_dwordx4 v[20:23], v[80:81], off offset:128
	v_xor_b32_e32 v36, 32, v77
	v_add_u32_e32 v37, 64, v37
	v_cmp_lt_i32_e32 vcc, v36, v37
	v_mul_f32_e64 v46, v26, v38
	v_mul_f32_e64 v47, v27, v38
	v_mul_f32_e64 v48, v24, v38
	v_mul_f32_e64 v49, v25, v38
	global_load_dwordx4 v[24:27], v[80:81], off offset:160
	v_cndmask_b32_e32 v36, v77, v36, vcc
	v_lshlrev_b32_e32 v69, 2, v36
	global_load_dwordx4 v[34:37], v[80:81], off offset:192
	v_mul_f32_e64 v42, v32, v38
	v_mul_f32_e64 v43, v33, v38
	v_mul_f32_e64 v44, v30, v38
	v_mul_f32_e64 v45, v31, v38
	global_load_dwordx4 v[30:33], v[80:81], off offset:224
	v_mul_f32_e64 v2, v2, v38
	v_mul_f32_e64 v3, v3, v38
	global_load_dwordx4 v[80:83], v[80:81], off
	v_mul_f32_e64 v28, v28, v38
	v_mul_f32_e64 v29, v29, v38
	v_mul_f32_e64 v6, v6, v38
	v_mul_f32_e64 v7, v7, v38
	v_mul_f32_e64 v4, v4, v38
	v_mul_f32_e64 v5, v5, v38
	v_mul_f32_e64 v38, v2, v2
	v_mul_f32_e64 v39, v3, v3
	v_mul_f32_e64 v122, v4, v4
	v_mul_f32_e64 v123, v5, v5
	v_add_f32_e32 v38, v38, v39
	v_add_f32_e32 v38, v122, v38
	v_mul_f32_e64 v120, v6, v6
	v_mul_f32_e64 v121, v7, v7
	v_add_f32_e32 v38, v123, v38
	v_add_f32_e32 v38, v120, v38
	v_mul_f32_e64 v96, v64, v64
	v_mul_f32_e64 v97, v65, v65
	v_add_f32_e32 v38, v121, v38
	v_add_f32_e32 v38, v96, v38
	v_mul_f32_e64 v94, v62, v62
	v_mul_f32_e64 v95, v63, v63
	v_add_f32_e32 v38, v97, v38
	v_add_f32_e32 v38, v94, v38
	v_mul_f32_e64 v92, v60, v60
	v_mul_f32_e64 v93, v61, v61
	v_add_f32_e32 v38, v95, v38
	v_add_f32_e32 v38, v92, v38
	v_mul_f32_e64 v90, v58, v58
	v_mul_f32_e64 v91, v59, v59
	v_add_f32_e32 v38, v93, v38
	v_add_f32_e32 v38, v90, v38
	v_mul_f32_e64 v88, v56, v56
	v_mul_f32_e64 v89, v57, v57
	v_add_f32_e32 v38, v91, v38
	v_add_f32_e32 v38, v88, v38
	v_mul_f32_e64 v86, v54, v54
	v_mul_f32_e64 v87, v55, v55
	v_add_f32_e32 v38, v89, v38
	v_add_f32_e32 v38, v86, v38
	v_mul_f32_e64 v84, v52, v52
	v_mul_f32_e64 v85, v53, v53
	v_add_f32_e32 v38, v87, v38
	v_add_f32_e32 v38, v84, v38
	v_mul_f32_e64 v78, v50, v50
	v_mul_f32_e64 v79, v51, v51
	v_add_f32_e32 v38, v85, v38
	v_add_f32_e32 v38, v78, v38
	v_mul_f32_e64 v76, v48, v48
	v_mul_f32_e64 v77, v49, v49
	v_add_f32_e32 v38, v79, v38
	v_add_f32_e32 v38, v76, v38
	v_mul_f32_e64 v74, v46, v46
	v_mul_f32_e64 v75, v47, v47
	v_add_f32_e32 v38, v77, v38
	v_add_f32_e32 v38, v74, v38
	v_mul_f32_e64 v72, v28, v28
	v_mul_f32_e64 v73, v29, v29
	v_add_f32_e32 v38, v75, v38
	v_add_f32_e32 v38, v72, v38
	v_mul_f32_e64 v70, v44, v44
	v_mul_f32_e64 v71, v45, v45
	v_add_f32_e32 v38, v73, v38
	v_add_f32_e32 v38, v70, v38
	v_mul_f32_e64 v66, v42, v42
	v_mul_f32_e64 v67, v43, v43
	v_add_f32_e32 v38, v71, v38
	v_add_f32_e32 v38, v66, v38
	v_add_f32_e32 v38, v67, v38
	ds_bpermute_b32 v39, v69, v38
	v_mov_b32_e32 v69, v99
	s_waitcnt lgkmcnt(0)
	v_add_f32_e32 v38, v38, v39
	v_fmamk_f32 v38, v38, 0x3c800000, v145
	v_cmp_gt_f32_e32 vcc, s51, v38
	v_mul_f32_e32 v39, 0x4b800000, v38
	s_nop 0
	v_cndmask_b32_e32 v38, v38, v39, vcc
	v_rsq_f32_e32 v38, v38
	s_nop 0
	v_mul_f32_e32 v39, 0x45800000, v38
	v_cndmask_b32_e32 v38, v38, v39, vcc
	v_mul_f32_e64 v6, v6, v38
	v_mul_f32_e64 v7, v7, v38
	v_mul_f32_e64 v2, v2, v38
	v_mul_f32_e64 v3, v3, v38
	s_waitcnt vmcnt(7)
	v_mul_f32_e64 v6, v8, v6
	v_mul_f32_e64 v7, v9, v7
	v_mul_f32_e64 v8, v64, v38
	v_mul_f32_e64 v9, v65, v38
	v_mul_f32_e64 v4, v4, v38
	v_mul_f32_e64 v5, v5, v38
	v_mul_f32_e64 v8, v10, v8
	v_mul_f32_e64 v9, v11, v9
	v_mul_f32_e64 v10, v62, v38
	v_mul_f32_e64 v11, v63, v38
	v_mul_f32_e64 v28, v28, v38
	v_mul_f32_e64 v29, v29, v38
	s_waitcnt vmcnt(6)
	v_mul_f32_e64 v10, v12, v10
	v_mul_f32_e64 v11, v13, v11
	v_mul_f32_e64 v12, v60, v38
	v_mul_f32_e64 v13, v61, v38
	s_waitcnt vmcnt(2)
	v_mul_f32_e64 v28, v28, v36
	v_mul_f32_e64 v29, v29, v37
	v_mul_f32_e64 v12, v12, v14
	v_mul_f32_e64 v13, v13, v15
	v_mul_f32_e64 v14, v58, v38
	v_mul_f32_e64 v15, v59, v38
	s_waitcnt vmcnt(0)
	v_mul_f32_e64 v2, v80, v2
	v_mul_f32_e64 v3, v81, v3
	v_mul_f32_e64 v14, v14, v16
	v_mul_f32_e64 v15, v15, v17
	v_mul_f32_e64 v16, v56, v38
	v_mul_f32_e64 v17, v57, v38
	v_mul_f32_e64 v4, v82, v4
	v_mul_f32_e64 v5, v83, v5
	v_mul_f32_e64 v16, v16, v18
	v_mul_f32_e64 v17, v17, v19
	v_mul_f32_e64 v18, v54, v38
	v_mul_f32_e64 v19, v55, v38
	v_cvt_pk_bf16_f32 v2, v2, v3
	v_mul_f32_e64 v18, v18, v20
	v_mul_f32_e64 v19, v19, v21
	v_mul_f32_e64 v20, v52, v38
	v_mul_f32_e64 v21, v53, v38
	v_cvt_pk_bf16_f32 v3, v4, v5
	v_mul_f32_e64 v20, v20, v22
	v_mul_f32_e64 v21, v21, v23
	v_mul_f32_e64 v22, v50, v38
	v_mul_f32_e64 v23, v51, v38
	s_nop 0
	v_mul_f32_e64 v22, v22, v24
	v_mul_f32_e64 v23, v23, v25
	v_mul_f32_e64 v24, v48, v38
	v_mul_f32_e64 v25, v49, v38
	s_nop 0
	v_mul_f32_e64 v24, v24, v26
	v_mul_f32_e64 v25, v25, v27
	v_mul_f32_e64 v26, v46, v38
	v_mul_f32_e64 v27, v47, v38
	s_nop 0
	v_mul_f32_e64 v26, v26, v34
	v_mul_f32_e64 v27, v27, v35
	v_mul_f32_e64 v34, v44, v38
	v_mul_f32_e64 v35, v45, v38
	s_nop 0
	v_mul_f32_e64 v30, v34, v30
	v_mul_f32_e64 v31, v35, v31
	v_mul_f32_e64 v34, v42, v38
	v_mul_f32_e64 v35, v43, v38
	s_nop 0
	v_mul_f32_e64 v32, v34, v32
	v_mul_f32_e64 v33, v35, v33
	v_lshl_add_u64 v[34:35], v[40:41], 0, v[68:69]
	global_store_dwordx2 v[34:35], v[2:3], off
	v_cvt_pk_bf16_f32 v2, v6, v7
	v_cvt_pk_bf16_f32 v3, v8, v9
	global_store_dwordx2 v[34:35], v[2:3], off offset:16
	v_cvt_pk_bf16_f32 v2, v10, v11
	v_cvt_pk_bf16_f32 v3, v12, v13
	global_store_dwordx2 v[34:35], v[2:3], off offset:32
	v_cvt_pk_bf16_f32 v2, v14, v15
	v_cvt_pk_bf16_f32 v3, v16, v17
	global_store_dwordx2 v[34:35], v[2:3], off offset:48
	v_cvt_pk_bf16_f32 v2, v18, v19
	v_cvt_pk_bf16_f32 v3, v20, v21
	global_store_dwordx2 v[34:35], v[2:3], off offset:64
	v_cvt_pk_bf16_f32 v2, v22, v23
	v_cvt_pk_bf16_f32 v3, v24, v25
	global_store_dwordx2 v[34:35], v[2:3], off offset:80
	v_cvt_pk_bf16_f32 v2, v26, v27
	v_cvt_pk_bf16_f32 v3, v28, v29
	global_store_dwordx2 v[34:35], v[2:3], off offset:96
	v_cvt_pk_bf16_f32 v2, v30, v31
	v_cvt_pk_bf16_f32 v3, v32, v33
	global_store_dwordx2 v[34:35], v[2:3], off offset:112
	s_branch .LBB0_279

.LBB0_455:
	ds_bpermute_b32 v34, v143, v115
	s_lshl_b32 s3, s3, 9
	s_and_b32 s3, s3, 0x6000
	v_add_u32_e32 v37, s3, v116
	s_waitcnt lgkmcnt(0)
	v_add_f32_e32 v34, v115, v34
	v_div_scale_f32 v35, s[6:7], v34, v34, 1.0
	v_rcp_f32_e32 v36, v35
	v_div_scale_f32 v38, vcc, 1.0, v34, 1.0
	v_fma_f32 v39, -v35, v36, 1.0
	v_fmac_f32_e32 v36, v39, v36
	v_mul_f32_e32 v39, v38, v36
	v_fma_f32 v40, -v35, v39, v38
	v_fmac_f32_e32 v39, v40, v36
	v_fma_f32 v35, -v35, v39, v38
	v_div_fmas_f32 v35, v35, v36, v39
	v_div_fixup_f32 v34, v35, v34, 1.0
	v_ashrrev_i32_e32 v35, 3, v37
	v_bfi_b32 v36, -16, v35, s2
	v_ashrrev_i32_e32 v37, 31, v36
	v_lshlrev_b64 v[36:37], 14, v[36:37]
	v_mul_f32_e64 v18, v18, v34
	v_mul_f32_e64 v19, v19, v34
	v_mul_f32_e64 v20, v20, v34
	v_mul_f32_e64 v21, v21, v34
	v_lshl_add_u64 v[36:37], v[112:113], 0, v[36:37]
	v_cvt_pk_bf16_f32 v18, v18, v19
	v_cvt_pk_bf16_f32 v19, v20, v21
	global_store_dwordx2 v[36:37], v[18:19], off
	v_mul_f32_e64 v18, v22, v34
	v_mul_f32_e64 v19, v23, v34
	v_mul_f32_e64 v20, v24, v34
	v_mul_f32_e64 v21, v25, v34
	v_mul_f32_e64 v2, v2, v34
	v_mul_f32_e64 v3, v3, v34
	v_mul_f32_e64 v4, v4, v34
	v_mul_f32_e64 v5, v5, v34
	v_cvt_pk_bf16_f32 v18, v18, v19
	v_cvt_pk_bf16_f32 v19, v20, v21
	v_cvt_pk_bf16_f32 v2, v2, v3
	v_cvt_pk_bf16_f32 v3, v4, v5
	global_store_dwordx2 v[36:37], v[18:19], off offset:16
	v_mul_f32_e64 v18, v26, v34
	v_mul_f32_e64 v19, v27, v34
	v_mul_f32_e64 v20, v28, v34
	v_mul_f32_e64 v21, v29, v34
	global_store_dwordx2 v[36:37], v[2:3], off offset:64
	v_mul_f32_e64 v2, v6, v34
	v_mul_f32_e64 v3, v7, v34
	v_mul_f32_e64 v4, v8, v34
	v_mul_f32_e64 v5, v9, v34
	v_cvt_pk_bf16_f32 v18, v18, v19
	v_cvt_pk_bf16_f32 v19, v20, v21
	v_cvt_pk_bf16_f32 v2, v2, v3
	v_cvt_pk_bf16_f32 v3, v4, v5
	global_store_dwordx2 v[36:37], v[18:19], off offset:32
	v_mul_f32_e64 v18, v30, v34
	v_mul_f32_e64 v19, v31, v34
	v_mul_f32_e64 v20, v32, v34
	v_mul_f32_e64 v21, v33, v34
	global_store_dwordx2 v[36:37], v[2:3], off offset:80
	v_mul_f32_e64 v2, v10, v34
	v_mul_f32_e64 v3, v11, v34
	v_mul_f32_e64 v4, v12, v34
	v_mul_f32_e64 v5, v13, v34
	v_cvt_pk_bf16_f32 v18, v18, v19
	v_cvt_pk_bf16_f32 v19, v20, v21
	v_cvt_pk_bf16_f32 v2, v2, v3
	v_cvt_pk_bf16_f32 v3, v4, v5
	global_store_dwordx2 v[36:37], v[18:19], off offset:48
	global_store_dwordx2 v[36:37], v[2:3], off offset:96
	s_load_dword s3, s[0:1], 0x100
	v_mul_f32_e64 v2, v14, v34
	v_mul_f32_e64 v3, v15, v34
	v_mul_f32_e64 v4, v16, v34
	v_mul_f32_e64 v5, v17, v34
	v_cvt_pk_bf16_f32 v2, v2, v3
	v_cvt_pk_bf16_f32 v3, v4, v5
	s_waitcnt lgkmcnt(0)
	s_add_i32 s2, s2, s3
	s_cmpk_lt_i32 s2, 0x1000
	global_store_dwordx2 v[36:37], v[2:3], off offset:112
	s_cbranch_scc0 .LBB0_485

.LBB0_463:
	s_or_b64 exec, exec, s[66:67]
	s_waitcnt vmcnt(3)
	ds_write_b128 v138, v[86:89]
	s_waitcnt vmcnt(2)
	ds_write_b128 v138, v[90:93] offset:9216
	s_waitcnt vmcnt(1)
	ds_write_b128 v140, v[94:97]
	s_waitcnt vmcnt(0)
	ds_write_b128 v140, v[98:101] offset:9216
	s_and_saveexec_b64 s[66:67], s[4:5]
	v_mul_f32_e64 v4, v84, s10
	v_mul_f32_e64 v5, v85, s10
	v_mul_f32_e64 v2, v82, s10
	v_mul_f32_e64 v3, v83, s10
	ds_write_b128 v141, v[2:5] offset:36864
	s_or_b64 exec, exec, s[66:67]
	s_cmp_eq_u32 s22, s21
	s_cbranch_scc1 .LBB0_469
	s_mov_b32 s21, s13
	s_lshl_b64 s[20:21], s[20:21], 13
	s_add_u32 s22, s62, s20
	s_addc_u32 s23, s63, s21
	s_add_u32 s20, s64, s20
	s_addc_u32 s21, s65, s21
	v_lshl_add_u64 v[2:3], s[22:23], 0, v[102:103]
	v_lshl_add_u64 v[4:5], v[2:3], 0, v[104:105]
	v_lshl_add_u64 v[6:7], s[20:21], 0, v[102:103]
	v_lshl_add_u64 v[2:3], v[2:3], 0, v[106:107]
	v_lshl_add_u64 v[8:9], v[6:7], 0, v[104:105]
	global_load_dwordx4 v[86:89], v[4:5], off
	global_load_dwordx4 v[90:93], v[8:9], off
	v_lshl_add_u64 v[4:5], v[6:7], 0, v[106:107]
	global_load_dwordx4 v[94:97], v[2:3], off
	global_load_dwordx4 v[98:101], v[4:5], off
	s_and_saveexec_b64 s[20:21], s[4:5]
	s_cbranch_execz .LBB0_468
	global_load_dwordx4 v[82:85], v114, s[18:19]

.LBB0_471:
	s_xor_b32 s17, s20, 1
	s_mul_i32 s6, s17, 0x4800
	v_or_b32_e32 v34, s6, v136
	v_lshl_add_u32 v35, v137, 1, v34
	v_lshl_add_u32 v34, v139, 1, v34
	s_waitcnt vmcnt(3)
	ds_write_b128 v35, v[86:89]
	s_waitcnt vmcnt(2)
	ds_write_b128 v35, v[90:93] offset:9216
	s_waitcnt vmcnt(1)
	ds_write_b128 v34, v[94:97]
	s_waitcnt vmcnt(0)
	ds_write_b128 v34, v[98:101] offset:9216
	s_and_saveexec_b64 s[6:7], s[4:5]
	v_mul_f32_e64 v36, v84, s10
	v_mul_f32_e64 v37, v85, s10
	v_mul_f32_e64 v34, v82, s10
	v_mul_f32_e64 v35, v83, s10
	v_lshl_add_u32 v38, s17, 8, v141
	ds_write_b128 v38, v[34:37] offset:36864
	s_or_b64 exec, exec, s[6:7]
	s_add_i32 s6, s15, 2
	s_cmp_gt_i32 s6, s11
	s_cbranch_scc0 .LBB0_476

.LBB0_479:
	s_mul_i32 s6, s20, 0x4800
	v_add_u32_e32 v147, s6, v109
	ds_read_b128 v[34:37], v147
	ds_read_b128 v[38:41], v147 offset:32
	s_waitcnt lgkmcnt(1)
	v_mfma_f32_32x32x16_bf16 v[50:65], v[34:37], v[66:69], 0
	s_waitcnt lgkmcnt(0)
	v_mfma_f32_32x32x16_bf16 v[50:65], v[38:41], v[70:73], v[50:65]
	ds_read_b128 v[34:37], v147 offset:64
	ds_read_b128 v[38:41], v147 offset:96
	s_waitcnt lgkmcnt(1)
	v_mfma_f32_32x32x16_bf16 v[50:65], v[34:37], v[74:77], v[50:65]
	ds_read_b128 v[34:37], v147 offset:4608
	ds_read_b128 v[126:129], v147 offset:4640
	s_waitcnt lgkmcnt(2)
	v_mfma_f32_32x32x16_bf16 v[50:65], v[38:41], v[78:81], v[50:65]
	s_waitcnt lgkmcnt(1)
	v_mfma_f32_32x32x16_bf16 v[34:49], v[34:37], v[66:69], 0
	s_waitcnt lgkmcnt(0)
	v_mfma_f32_32x32x16_bf16 v[34:49], v[126:129], v[70:73], v[34:49]
	ds_read_b128 v[126:129], v147 offset:4672
	ds_read_b128 v[130:133], v147 offset:4704
	s_waitcnt lgkmcnt(1)
	v_mfma_f32_32x32x16_bf16 v[34:49], v[126:129], v[74:77], v[34:49]
	s_waitcnt lgkmcnt(0)
	v_mfma_f32_32x32x16_bf16 v[34:49], v[130:133], v[78:81], v[34:49]
	s_lshl_b32 s17, s20, 8
	v_or_b32_e32 v127, s17, v108
	ds_read_b128 v[128:131], v127 offset:36864
	ds_read_b128 v[148:151], v127 offset:36896
	v_add_u32_e32 v126, 32, v146
	v_cmp_lt_i32_e32 vcc, 26, v126
	s_cmp_eq_u64 vcc, exec
	s_waitcnt lgkmcnt(1)
	v_add_f32_e64 v128, v124, -v128
	v_add_f32_e64 v129, v125, -v129
	v_add_f32_e64 v130, v124, -v130
	v_add_f32_e64 v131, v125, -v131
	v_fma_f32 v50, v50, s14, v128
	v_fma_f32 v51, v51, s14, v129
	v_fma_f32 v52, v52, s14, v130
	v_fma_f32 v53, v53, s14, v131
	ds_read_b128 v[128:131], v127 offset:36928
	s_waitcnt lgkmcnt(1)
	v_add_f32_e64 v132, v124, -v148
	v_add_f32_e64 v133, v125, -v149
	s_waitcnt lgkmcnt(0)
	v_add_f32_e64 v128, v124, -v128
	v_add_f32_e64 v129, v125, -v129
	v_fma_f32 v54, v54, s14, v132
	v_fma_f32 v55, v55, s14, v133
	v_add_f32_e64 v132, v124, -v150
	v_add_f32_e64 v133, v125, -v151
	ds_read_b128 v[148:151], v127 offset:36960
	v_fma_f32 v58, v58, s14, v128
	v_fma_f32 v59, v59, s14, v129
	v_add_f32_e64 v128, v124, -v130
	v_add_f32_e64 v129, v125, -v131
	v_fma_f32 v56, v56, s14, v132
	v_fma_f32 v57, v57, s14, v133
	v_fma_f32 v60, v60, s14, v128
	v_fma_f32 v61, v61, s14, v129
	s_waitcnt lgkmcnt(0)
	v_add_f32_e64 v128, v124, -v148
	v_add_f32_e64 v129, v125, -v149
	s_nop 0
	v_fma_f32 v62, v62, s14, v128
	v_fma_f32 v63, v63, s14, v129
	v_add_f32_e64 v128, v124, -v150
	v_add_f32_e64 v129, v125, -v151
	s_nop 0
	v_fma_f32 v64, v64, s14, v128
	v_fma_f32 v65, v65, s14, v129
	s_cbranch_scc1 .LBB0_481
	v_cmp_lt_i32_e64 s[6:7], -1, v126
	v_cndmask_b32_e32 v65, v145, v65, vcc
	s_nop 0
	v_cndmask_b32_e64 v50, v145, v50, s[6:7]
	v_cmp_lt_i32_e64 s[6:7], 0, v126
	s_nop 1
	v_cndmask_b32_e64 v51, v145, v51, s[6:7]
	v_cmp_lt_i32_e64 s[6:7], 1, v126
	s_nop 1
	v_cndmask_b32_e64 v52, v145, v52, s[6:7]
	v_cmp_lt_i32_e64 s[6:7], 2, v126
	s_nop 1
	v_cndmask_b32_e64 v53, v145, v53, s[6:7]
	v_cmp_lt_i32_e64 s[6:7], 7, v126
	s_nop 1
	v_cndmask_b32_e64 v54, v145, v54, s[6:7]
	v_cmp_lt_i32_e64 s[6:7], 8, v126
	s_nop 1
	v_cndmask_b32_e64 v55, v145, v55, s[6:7]
	v_cmp_lt_i32_e64 s[6:7], 9, v126
	s_nop 1
	v_cndmask_b32_e64 v56, v145, v56, s[6:7]
	v_cmp_lt_i32_e64 s[6:7], 10, v126
	s_nop 1
	v_cndmask_b32_e64 v57, v145, v57, s[6:7]
	v_cmp_lt_i32_e64 s[6:7], 15, v126
	s_nop 1
	v_cndmask_b32_e64 v58, v145, v58, s[6:7]
	v_cmp_lt_i32_e64 s[6:7], 16, v126
	s_nop 1
	v_cndmask_b32_e64 v59, v145, v59, s[6:7]
	v_cmp_lt_i32_e64 s[6:7], 17, v126
	s_nop 1
	v_cndmask_b32_e64 v60, v145, v60, s[6:7]
	v_cmp_lt_i32_e64 s[6:7], 18, v126
	s_nop 1
	v_cndmask_b32_e64 v61, v145, v61, s[6:7]
	v_cmp_lt_i32_e64 s[6:7], 23, v126
	s_nop 1
	v_cndmask_b32_e64 v62, v145, v62, s[6:7]
	v_cmp_lt_i32_e64 s[6:7], 24, v126
	s_nop 1
	v_cndmask_b32_e64 v63, v145, v63, s[6:7]
	v_cmp_lt_i32_e64 s[6:7], 25, v126
	s_nop 1
	v_cndmask_b32_e64 v64, v145, v64, s[6:7]
.LBB0_481:
	v_add_u32_e32 v152, s17, v108
	ds_read_b128 v[126:129], v152 offset:36992
	ds_read_b128 v[148:151], v152 offset:37024
	v_cmp_lt_i32_e32 vcc, 26, v146
	s_cmp_eq_u64 vcc, exec
	s_waitcnt lgkmcnt(1)
	v_add_f32_e64 v126, v124, -v126
	v_add_f32_e64 v127, v125, -v127
	v_add_f32_e64 v128, v124, -v128
	v_add_f32_e64 v129, v125, -v129
	v_fma_f32 v132, v34, s14, v126
	v_fma_f32 v133, v35, s14, v127
	v_fma_f32 v130, v36, s14, v128
	v_fma_f32 v131, v37, s14, v129
	ds_read_b128 v[34:37], v152 offset:37056
	s_waitcnt lgkmcnt(1)
	v_add_f32_e64 v148, v124, -v148
	v_add_f32_e64 v149, v125, -v149
	s_waitcnt lgkmcnt(0)
	v_add_f32_e64 v34, v124, -v34
	v_add_f32_e64 v35, v125, -v35
	v_fma_f32 v128, v38, s14, v148
	v_fma_f32 v129, v39, s14, v149
	v_add_f32_e64 v38, v124, -v150
	v_add_f32_e64 v39, v125, -v151
	ds_read_b128 v[148:151], v152 offset:37088
	v_fma_f32 v126, v40, s14, v38
	v_fma_f32 v127, v41, s14, v39
	v_fma_f32 v40, v42, s14, v34
	v_fma_f32 v41, v43, s14, v35
	v_add_f32_e64 v34, v124, -v36
	v_add_f32_e64 v35, v125, -v37
	s_waitcnt lgkmcnt(0)
	v_add_f32_e64 v38, v124, -v150
	v_add_f32_e64 v39, v125, -v151
	v_fma_f32 v36, v44, s14, v34
	v_fma_f32 v37, v45, s14, v35
	v_add_f32_e64 v34, v124, -v148
	v_add_f32_e64 v35, v125, -v149
	v_fma_f32 v38, v48, s14, v38
	v_fma_f32 v39, v49, s14, v39
	v_fma_f32 v34, v46, s14, v34
	v_fma_f32 v35, v47, s14, v35
	s_cbranch_scc1 .LBB0_483
	v_cmp_lt_i32_e64 s[6:7], -1, v146
	v_cndmask_b32_e32 v39, v145, v39, vcc
	s_nop 0
	v_cndmask_b32_e64 v132, v145, v132, s[6:7]
	v_cmp_lt_i32_e64 s[6:7], 0, v146
	s_nop 1
	v_cndmask_b32_e64 v133, v145, v133, s[6:7]
	v_cmp_lt_i32_e64 s[6:7], 1, v146
	s_nop 1
	v_cndmask_b32_e64 v130, v145, v130, s[6:7]
	v_cmp_lt_i32_e64 s[6:7], 2, v146
	s_nop 1
	v_cndmask_b32_e64 v131, v145, v131, s[6:7]
	v_cmp_lt_i32_e64 s[6:7], 7, v146
	s_nop 1
	v_cndmask_b32_e64 v128, v145, v128, s[6:7]
	v_cmp_lt_i32_e64 s[6:7], 8, v146
	s_nop 1
	v_cndmask_b32_e64 v129, v145, v129, s[6:7]
	v_cmp_lt_i32_e64 s[6:7], 9, v146
	s_nop 1
	v_cndmask_b32_e64 v126, v145, v126, s[6:7]
	v_cmp_lt_i32_e64 s[6:7], 10, v146
	s_nop 1
	v_cndmask_b32_e64 v127, v145, v127, s[6:7]
	v_cmp_lt_i32_e64 s[6:7], 15, v146
	s_nop 1
	v_cndmask_b32_e64 v40, v145, v40, s[6:7]
	v_cmp_lt_i32_e64 s[6:7], 16, v146
	s_nop 1
	v_cndmask_b32_e64 v41, v145, v41, s[6:7]
	v_cmp_lt_i32_e64 s[6:7], 17, v146
	s_nop 1
	v_cndmask_b32_e64 v36, v145, v36, s[6:7]
	v_cmp_lt_i32_e64 s[6:7], 18, v146
	s_nop 1
	v_cndmask_b32_e64 v37, v145, v37, s[6:7]
	v_cmp_lt_i32_e64 s[6:7], 23, v146
	s_nop 1
	v_cndmask_b32_e64 v34, v145, v34, s[6:7]
	v_cmp_lt_i32_e64 s[6:7], 24, v146
	s_nop 1
	v_cndmask_b32_e64 v35, v145, v35, s[6:7]
	v_cmp_lt_i32_e64 s[6:7], 25, v146
	s_nop 1
	v_cndmask_b32_e64 v38, v145, v38, s[6:7]

.LBB0_559:
	v_or_b32_e32 v8, s18, v34
	v_lshlrev_b32_e32 v98, 12, v8
	s_waitcnt lgkmcnt(0)
	v_lshl_add_u64 v[2:3], v[30:31], 0, v[98:99]
	global_load_dwordx4 v[38:41], v[2:3], off nt
	v_add_u32_e32 v98, 8, v8
	v_lshlrev_b64 v[2:3], 12, v[98:99]
	v_add_u32_e32 v98, 16, v8
	v_lshl_add_u64 v[2:3], v[30:31], 0, v[2:3]
	v_lshlrev_b64 v[4:5], 12, v[98:99]
	v_add_u32_e32 v98, 24, v8
	global_load_dwordx4 v[26:29], v[2:3], off nt
	v_lshl_add_u64 v[2:3], v[30:31], 0, v[4:5]
	v_lshlrev_b64 v[4:5], 12, v[98:99]
	v_or_b32_e32 v98, 32, v8
	v_lshl_add_u64 v[4:5], v[30:31], 0, v[4:5]
	v_lshlrev_b64 v[6:7], 12, v[98:99]
	v_add_u32_e32 v98, 40, v8
	global_load_dwordx4 v[22:25], v[2:3], off nt
	global_load_dwordx4 v[18:21], v[4:5], off nt
	v_lshlrev_b64 v[4:5], 12, v[98:99]
	v_add_u32_e32 v98, 48, v8
	v_lshl_add_u64 v[2:3], v[30:31], 0, v[6:7]
	v_lshl_add_u64 v[4:5], v[30:31], 0, v[4:5]
	v_lshlrev_b64 v[6:7], 12, v[98:99]
	v_add_u32_e32 v98, 56, v8
	global_load_dwordx4 v[14:17], v[2:3], off nt
	global_load_dwordx4 v[10:13], v[4:5], off nt
	v_lshlrev_b64 v[4:5], 12, v[98:99]
	v_lshl_add_u64 v[2:3], v[30:31], 0, v[6:7]
	v_lshl_add_u64 v[4:5], v[30:31], 0, v[4:5]
	global_load_dwordx4 v[6:9], v[2:3], off nt
	s_nop 0
	global_load_dwordx4 v[2:5], v[4:5], off nt
	v_or_b32_e32 v36, s18, v1
	s_movk_i32 s18, 0x210
	v_mad_u32_u24 v37, v36, s18, v131
	ds_read_b128 v[42:45], v37
	v_lshlrev_b32_e32 v98, 7, v36
	s_waitcnt vmcnt(7) lgkmcnt(0)
	v_add_f32_e64 v42, v38, v42
	v_add_f32_e64 v43, v39, v43
	s_nop 0
	v_mul_f32_e32 v37, v43, v43
	v_add_f32_e64 v40, v40, v44
	v_add_f32_e64 v41, v41, v45
	v_fmac_f32_e32 v37, v42, v42
	v_fmac_f32_e32 v37, v40, v40
	v_fmac_f32_e32 v37, v41, v41
	ds_bpermute_b32 v38, v132, v37
	v_lshl_add_u64 v[44:45], v[32:33], 0, v[98:99]
	v_cvt_pk_bf16_f32 v42, v42, v43
	v_cvt_pk_bf16_f32 v43, v40, v41
	global_store_dwordx2 v[44:45], v[42:43], off
	s_waitcnt lgkmcnt(0)
	v_add_f32_e32 v37, v37, v38
	ds_bpermute_b32 v38, v133, v37
	s_waitcnt lgkmcnt(0)
	v_add_f32_e32 v37, v37, v38
	ds_bpermute_b32 v38, v134, v37
	s_waitcnt lgkmcnt(0)
	v_add_f32_e32 v37, v37, v38
	ds_bpermute_b32 v38, v135, v37
	s_waitcnt lgkmcnt(0)
	v_add_f32_e32 v37, v37, v38
	ds_bpermute_b32 v38, v136, v37
	s_and_saveexec_b64 s[18:19], s[4:5]
	s_cbranch_execz .LBB0_561
	v_or_b32_e32 v39, s8, v36
	v_lshlrev_b32_e32 v39, 6, v39
	s_waitcnt lgkmcnt(0)
	v_add_f32_e32 v98, v37, v38
	global_store_dwordx2 v39, v[98:99], s[14:15]
.LBB0_561:
	s_or_b64 exec, exec, s[18:19]
	v_mul_u32_u24_e32 v37, 0x210, v36
	v_add_u32_e32 v37, v37, v131
	s_waitcnt lgkmcnt(0)
	ds_read_b128 v[38:41], v37 offset:4224
	v_add_u32_e32 v42, 8, v36
	v_lshlrev_b32_e32 v98, 7, v42
	s_waitcnt vmcnt(7) lgkmcnt(0)
	v_add_f32_e64 v38, v26, v38
	v_add_f32_e64 v39, v27, v39
	s_nop 0
	v_mul_f32_e32 v26, v39, v39
	v_add_f32_e64 v40, v28, v40
	v_add_f32_e64 v41, v29, v41
	v_fmac_f32_e32 v26, v38, v38
	v_fmac_f32_e32 v26, v40, v40
	v_fmac_f32_e32 v26, v41, v41
	ds_bpermute_b32 v27, v132, v26
	v_cvt_pk_bf16_f32 v38, v38, v39
	v_cvt_pk_bf16_f32 v39, v40, v41
	s_waitcnt lgkmcnt(0)
	v_add_f32_e32 v27, v26, v27
	ds_bpermute_b32 v28, v133, v27
	v_or_b32_e32 v26, s8, v42
	v_lshrrev_b32_e32 v29, 3, v26
	s_waitcnt lgkmcnt(0)
	v_add_f32_e32 v27, v27, v28
	ds_bpermute_b32 v43, v134, v27
	v_and_b32_e32 v28, 0x1ffffff0, v29
	v_add_u32_e32 v28, v28, v35
	v_ashrrev_i32_e32 v29, 31, v28
	v_lshlrev_b64 v[28:29], 14, v[28:29]
	s_waitcnt lgkmcnt(0)
	v_add_f32_e32 v27, v27, v43
	ds_bpermute_b32 v44, v135, v27
	v_lshl_add_u64 v[28:29], s[92:93], 0, v[28:29]
	v_lshl_add_u64 v[42:43], v[28:29], 0, v[98:99]
	v_lshlrev_b32_e32 v98, 1, v104
	v_lshl_add_u64 v[42:43], v[42:43], 0, v[98:99]
	s_waitcnt lgkmcnt(0)
	v_add_f32_e32 v27, v27, v44
	ds_bpermute_b32 v28, v136, v27
	global_store_dwordx2 v[42:43], v[38:39], off
	s_and_saveexec_b64 s[18:19], s[4:5]
	s_cbranch_execz .LBB0_563
	v_lshlrev_b32_e32 v29, 6, v26
	s_waitcnt lgkmcnt(0)
	v_add_f32_e32 v26, v27, v28
	v_mov_b32_e32 v27, v99
	global_store_dwordx2 v29, v[26:27], s[14:15]
.LBB0_563:
	s_or_b64 exec, exec, s[18:19]
	v_add_u32_e32 v27, 16, v36
	v_or_b32_e32 v26, s8, v27
	ds_read_b128 v[38:41], v37 offset:8448
	s_waitcnt lgkmcnt(1)
	v_lshrrev_b32_e32 v28, 3, v26
	v_and_b32_e32 v28, 0x1ffffff0, v28
	v_add_u32_e32 v28, v28, v35
	v_ashrrev_i32_e32 v29, 31, v28
	v_lshlrev_b64 v[28:29], 14, v[28:29]
	s_waitcnt vmcnt(7) lgkmcnt(0)
	v_add_f32_e64 v22, v22, v38
	v_add_f32_e64 v23, v23, v39
	v_lshl_add_u64 v[28:29], s[92:93], 0, v[28:29]
	v_lshlrev_b32_e32 v38, 7, v27
	v_mov_b32_e32 v39, v99
	v_lshl_add_u64 v[28:29], v[28:29], 0, v[38:39]
	v_cvt_pk_bf16_f32 v38, v22, v23
	v_mul_f32_e32 v23, v23, v23
	v_add_f32_e64 v24, v24, v40
	v_add_f32_e64 v25, v25, v41
	v_fmac_f32_e32 v23, v22, v22
	v_fmac_f32_e32 v23, v24, v24
	v_fmac_f32_e32 v23, v25, v25
	ds_bpermute_b32 v22, v132, v23
	v_lshl_add_u64 v[28:29], v[28:29], 0, v[98:99]
	v_cvt_pk_bf16_f32 v39, v24, v25
	global_store_dwordx2 v[28:29], v[38:39], off
	s_waitcnt lgkmcnt(0)
	v_add_f32_e32 v22, v23, v22
	ds_bpermute_b32 v23, v133, v22
	s_waitcnt lgkmcnt(0)
	v_add_f32_e32 v22, v22, v23
	ds_bpermute_b32 v23, v134, v22
	s_waitcnt lgkmcnt(0)
	v_add_f32_e32 v22, v22, v23
	ds_bpermute_b32 v23, v135, v22
	s_waitcnt lgkmcnt(0)
	v_add_f32_e32 v22, v22, v23
	ds_bpermute_b32 v23, v136, v22
	s_and_saveexec_b64 s[18:19], s[4:5]
	s_cbranch_execz .LBB0_565
	v_lshlrev_b32_e32 v24, 6, v26
	s_waitcnt lgkmcnt(0)
	v_add_f32_e32 v22, v22, v23
	v_mov_b32_e32 v23, v99
	global_store_dwordx2 v24, v[22:23], s[14:15]
.LBB0_565:
	s_or_b64 exec, exec, s[18:19]
	ds_read_b128 v[24:27], v37 offset:12672
	s_waitcnt lgkmcnt(1)
	v_add_u32_e32 v23, 24, v36
	v_or_b32_e32 v22, s8, v23
	s_waitcnt vmcnt(7) lgkmcnt(0)
	v_add_f32_e64 v18, v18, v24
	v_add_f32_e64 v19, v19, v25
	v_lshrrev_b32_e32 v24, 3, v22
	v_and_b32_e32 v24, 0x1ffffff0, v24
	v_add_u32_e32 v24, v24, v35
	v_ashrrev_i32_e32 v25, 31, v24
	v_lshlrev_b64 v[24:25], 14, v[24:25]
	v_add_f32_e64 v20, v20, v26
	v_add_f32_e64 v21, v21, v27
	v_lshl_add_u64 v[24:25], s[92:93], 0, v[24:25]
	v_lshlrev_b32_e32 v26, 7, v23
	v_mov_b32_e32 v27, v99
	v_lshl_add_u64 v[24:25], v[24:25], 0, v[26:27]
	v_cvt_pk_bf16_f32 v26, v18, v19
	v_mul_f32_e32 v19, v19, v19
	v_fmac_f32_e32 v19, v18, v18
	v_fmac_f32_e32 v19, v20, v20
	v_fmac_f32_e32 v19, v21, v21
	ds_bpermute_b32 v18, v132, v19
	v_lshl_add_u64 v[24:25], v[24:25], 0, v[98:99]
	v_cvt_pk_bf16_f32 v27, v20, v21
	global_store_dwordx2 v[24:25], v[26:27], off
	s_waitcnt lgkmcnt(0)
	v_add_f32_e32 v18, v19, v18
	ds_bpermute_b32 v19, v133, v18
	s_waitcnt lgkmcnt(0)
	v_add_f32_e32 v18, v18, v19
	ds_bpermute_b32 v19, v134, v18
	s_waitcnt lgkmcnt(0)
	v_add_f32_e32 v18, v18, v19
	ds_bpermute_b32 v19, v135, v18
	s_waitcnt lgkmcnt(0)
	v_add_f32_e32 v18, v18, v19
	ds_bpermute_b32 v19, v136, v18
	s_and_saveexec_b64 s[18:19], s[4:5]
	s_cbranch_execz .LBB0_567
	v_lshlrev_b32_e32 v20, 6, v22
	s_waitcnt lgkmcnt(0)
	v_add_f32_e32 v18, v18, v19
	v_mov_b32_e32 v19, v99
	global_store_dwordx2 v20, v[18:19], s[14:15]
.LBB0_567:
	s_or_b64 exec, exec, s[18:19]
	ds_read_b128 v[20:23], v37 offset:16896
	s_waitcnt lgkmcnt(1)
	v_or_b32_e32 v19, 32, v36
	v_or_b32_e32 v18, s8, v19
	s_waitcnt vmcnt(7) lgkmcnt(0)
	v_add_f32_e64 v14, v14, v20
	v_add_f32_e64 v15, v15, v21
	v_lshrrev_b32_e32 v20, 3, v18
	v_and_b32_e32 v20, 0x1ffffff0, v20
	v_add_u32_e32 v20, v20, v35
	v_ashrrev_i32_e32 v21, 31, v20
	v_lshlrev_b64 v[20:21], 14, v[20:21]
	v_add_f32_e64 v16, v16, v22
	v_add_f32_e64 v17, v17, v23
	v_lshl_add_u64 v[20:21], s[92:93], 0, v[20:21]
	v_lshlrev_b32_e32 v22, 7, v19
	v_mov_b32_e32 v23, v99
	v_lshl_add_u64 v[20:21], v[20:21], 0, v[22:23]
	v_cvt_pk_bf16_f32 v22, v14, v15
	v_mul_f32_e32 v15, v15, v15
	v_fmac_f32_e32 v15, v14, v14
	v_fmac_f32_e32 v15, v16, v16
	v_fmac_f32_e32 v15, v17, v17
	ds_bpermute_b32 v14, v132, v15
	v_lshl_add_u64 v[20:21], v[20:21], 0, v[98:99]
	v_cvt_pk_bf16_f32 v23, v16, v17
	global_store_dwordx2 v[20:21], v[22:23], off
	s_waitcnt lgkmcnt(0)
	v_add_f32_e32 v14, v15, v14
	ds_bpermute_b32 v15, v133, v14
	s_waitcnt lgkmcnt(0)
	v_add_f32_e32 v14, v14, v15
	ds_bpermute_b32 v15, v134, v14
	s_waitcnt lgkmcnt(0)
	v_add_f32_e32 v14, v14, v15
	ds_bpermute_b32 v15, v135, v14
	s_waitcnt lgkmcnt(0)
	v_add_f32_e32 v14, v14, v15
	ds_bpermute_b32 v15, v136, v14
	s_and_saveexec_b64 s[18:19], s[4:5]
	s_cbranch_execz .LBB0_569
	v_lshlrev_b32_e32 v16, 6, v18
	s_waitcnt lgkmcnt(0)
	v_add_f32_e32 v14, v14, v15
	v_mov_b32_e32 v15, v99
	global_store_dwordx2 v16, v[14:15], s[14:15]
.LBB0_569:
	s_or_b64 exec, exec, s[18:19]
	ds_read_b128 v[16:19], v37 offset:21120
	s_waitcnt lgkmcnt(1)
	v_add_u32_e32 v15, 40, v36
	v_add_u32_e32 v14, s8, v15
	v_lshlrev_b32_e32 v15, 7, v15
	s_waitcnt vmcnt(7) lgkmcnt(0)
	v_add_f32_e64 v10, v10, v16
	v_add_f32_e64 v11, v11, v17
	v_lshrrev_b32_e32 v16, 3, v14
	v_and_b32_e32 v16, 0x1ffffff0, v16
	v_add_u32_e32 v16, v16, v35
	v_ashrrev_i32_e32 v17, 31, v16
	v_lshlrev_b64 v[16:17], 14, v[16:17]
	v_add_f32_e64 v12, v12, v18
	v_add_f32_e64 v13, v13, v19
	v_lshl_add_u64 v[16:17], s[92:93], 0, v[16:17]
	v_and_b32_e32 v18, 0x3f80, v15
	v_mov_b32_e32 v19, v99
	v_lshl_add_u64 v[16:17], v[16:17], 0, v[18:19]
	v_cvt_pk_bf16_f32 v18, v10, v11
	v_mul_f32_e32 v11, v11, v11
	v_fmac_f32_e32 v11, v10, v10
	v_fmac_f32_e32 v11, v12, v12
	v_fmac_f32_e32 v11, v13, v13
	ds_bpermute_b32 v10, v132, v11
	v_lshl_add_u64 v[16:17], v[16:17], 0, v[98:99]
	v_cvt_pk_bf16_f32 v19, v12, v13
	global_store_dwordx2 v[16:17], v[18:19], off
	s_waitcnt lgkmcnt(0)
	v_add_f32_e32 v10, v11, v10
	ds_bpermute_b32 v11, v133, v10
	s_waitcnt lgkmcnt(0)
	v_add_f32_e32 v10, v10, v11
	ds_bpermute_b32 v11, v134, v10
	s_waitcnt lgkmcnt(0)
	v_add_f32_e32 v10, v10, v11
	ds_bpermute_b32 v11, v135, v10
	s_waitcnt lgkmcnt(0)
	v_add_f32_e32 v10, v10, v11
	ds_bpermute_b32 v11, v136, v10
	s_and_saveexec_b64 s[18:19], s[4:5]
	s_cbranch_execz .LBB0_571
	v_lshlrev_b32_e32 v12, 6, v14
	s_waitcnt lgkmcnt(0)
	v_add_f32_e32 v10, v10, v11
	v_mov_b32_e32 v11, v99
	global_store_dwordx2 v12, v[10:11], s[14:15]
.LBB0_571:
	s_or_b64 exec, exec, s[18:19]
	ds_read_b128 v[12:15], v37 offset:25344
	s_waitcnt lgkmcnt(1)
	v_add_u32_e32 v11, 48, v36
	v_add_u32_e32 v10, s8, v11
	v_lshlrev_b32_e32 v11, 7, v11
	s_waitcnt vmcnt(7) lgkmcnt(0)
	v_add_f32_e64 v6, v6, v12
	v_add_f32_e64 v7, v7, v13
	v_lshrrev_b32_e32 v12, 3, v10
	v_and_b32_e32 v12, 0x1ffffff0, v12
	v_add_u32_e32 v12, v12, v35
	v_ashrrev_i32_e32 v13, 31, v12
	v_lshlrev_b64 v[12:13], 14, v[12:13]
	v_add_f32_e64 v8, v8, v14
	v_add_f32_e64 v9, v9, v15
	v_lshl_add_u64 v[12:13], s[92:93], 0, v[12:13]
	v_and_b32_e32 v14, 0x3f80, v11
	v_mov_b32_e32 v15, v99
	v_lshl_add_u64 v[12:13], v[12:13], 0, v[14:15]
	v_cvt_pk_bf16_f32 v14, v6, v7
	v_mul_f32_e32 v7, v7, v7
	v_fmac_f32_e32 v7, v6, v6
	v_fmac_f32_e32 v7, v8, v8
	v_fmac_f32_e32 v7, v9, v9
	ds_bpermute_b32 v6, v132, v7
	v_lshl_add_u64 v[12:13], v[12:13], 0, v[98:99]
	v_cvt_pk_bf16_f32 v15, v8, v9
	global_store_dwordx2 v[12:13], v[14:15], off
	s_waitcnt lgkmcnt(0)
	v_add_f32_e32 v6, v7, v6
	ds_bpermute_b32 v7, v133, v6
	s_waitcnt lgkmcnt(0)
	v_add_f32_e32 v6, v6, v7
	ds_bpermute_b32 v7, v134, v6
	s_waitcnt lgkmcnt(0)
	v_add_f32_e32 v6, v6, v7
	ds_bpermute_b32 v7, v135, v6
	s_waitcnt lgkmcnt(0)
	v_add_f32_e32 v6, v6, v7
	ds_bpermute_b32 v7, v136, v6
	s_and_saveexec_b64 s[18:19], s[4:5]
	s_cbranch_execz .LBB0_573
	v_lshlrev_b32_e32 v8, 6, v10
	s_waitcnt lgkmcnt(0)
	v_add_f32_e32 v6, v6, v7
	v_mov_b32_e32 v7, v99
	global_store_dwordx2 v8, v[6:7], s[14:15]
.LBB0_573:
	s_or_b64 exec, exec, s[18:19]
	ds_read_b128 v[8:11], v37 offset:29568
	s_waitcnt lgkmcnt(1)
	v_add_u32_e32 v7, 56, v36
	v_add_u32_e32 v6, s8, v7
	v_lshlrev_b32_e32 v7, 7, v7
	s_waitcnt vmcnt(7) lgkmcnt(0)
	v_add_f32_e64 v2, v2, v8
	v_add_f32_e64 v3, v3, v9
	v_lshrrev_b32_e32 v8, 3, v6
	v_and_b32_e32 v8, 0x1ffffff0, v8
	v_add_u32_e32 v8, v8, v35
	v_ashrrev_i32_e32 v9, 31, v8
	v_lshlrev_b64 v[8:9], 14, v[8:9]
	v_add_f32_e64 v4, v4, v10
	v_add_f32_e64 v5, v5, v11
	v_lshl_add_u64 v[8:9], s[92:93], 0, v[8:9]
	v_and_b32_e32 v10, 0x3f80, v7
	v_mov_b32_e32 v11, v99
	v_lshl_add_u64 v[8:9], v[8:9], 0, v[10:11]
	v_cvt_pk_bf16_f32 v10, v2, v3
	v_mul_f32_e32 v3, v3, v3
	v_fmac_f32_e32 v3, v2, v2
	v_fmac_f32_e32 v3, v4, v4
	v_fmac_f32_e32 v3, v5, v5
	ds_bpermute_b32 v2, v132, v3
	v_lshl_add_u64 v[8:9], v[8:9], 0, v[98:99]
	v_cvt_pk_bf16_f32 v11, v4, v5
	global_store_dwordx2 v[8:9], v[10:11], off
	s_waitcnt lgkmcnt(0)
	v_add_f32_e32 v2, v3, v2
	ds_bpermute_b32 v3, v133, v2
	s_waitcnt lgkmcnt(0)
	v_add_f32_e32 v2, v2, v3
	ds_bpermute_b32 v3, v134, v2
	s_waitcnt lgkmcnt(0)
	v_add_f32_e32 v2, v2, v3
	ds_bpermute_b32 v3, v135, v2
	s_waitcnt lgkmcnt(0)
	v_add_f32_e32 v2, v2, v3
	ds_bpermute_b32 v3, v136, v2
	s_and_saveexec_b64 s[18:19], s[4:5]
	s_cbranch_execz .LBB0_558
	v_lshlrev_b32_e32 v4, 6, v6
	s_waitcnt lgkmcnt(0)
	v_add_f32_e32 v98, v2, v3
	global_store_dwordx2 v4, v[98:99], s[14:15]
	s_branch .LBB0_558

.LBB0_679:
	s_waitcnt lgkmcnt(1)
	v_mfma_f32_32x32x16_bf16 v[50:65], v[102:105], v[106:109], v[50:65]
	s_waitcnt vmcnt(4)
	ds_write_b128 v140, v[66:69] offset:36864
	s_waitcnt vmcnt(3)
	ds_write_b128 v140, v[74:77] offset:55296
	v_mfma_f32_32x32x16_bf16 v[34:49], v[94:97], v[106:109], v[34:49]
	ds_write_b128 v142, v[70:73] offset:36864
	s_waitcnt vmcnt(2)
	ds_write_b128 v142, v[82:85] offset:55296
	s_waitcnt lgkmcnt(4)
	v_mfma_f32_32x32x16_bf16 v[18:33], v[102:105], v[98:101], v[18:33]
	ds_write_b128 v144, v[78:81] offset:36864
	s_waitcnt vmcnt(1)
	ds_write_b128 v144, v[86:89] offset:55296
	v_mfma_f32_32x32x16_bf16 v[2:17], v[94:97], v[98:101], v[2:17]
	ds_write_b128 v146, v[90:93] offset:36864
	s_waitcnt vmcnt(0)
	ds_write_b128 v146, v[110:113] offset:55296
	ds_read_b128 v[66:69], v151 offset:23072
	ds_read_b128 v[70:73], v152 offset:4640
	s_waitcnt lgkmcnt(0)
	v_mfma_f32_32x32x16_bf16 v[2:17], v[66:69], v[70:73], v[2:17]
	ds_read_b128 v[74:77], v151 offset:18464
	ds_read_b128 v[78:81], v151 offset:18496
	s_waitcnt lgkmcnt(1)
	v_mfma_f32_32x32x16_bf16 v[18:33], v[74:77], v[70:73], v[18:33]
	ds_read_b128 v[70:73], v152 offset:32
	ds_read_b128 v[82:85], v152 offset:64
	s_waitcnt lgkmcnt(1)
	v_mfma_f32_32x32x16_bf16 v[50:65], v[74:77], v[70:73], v[50:65]
	ds_read_b128 v[74:77], v151 offset:23104
	ds_read_b128 v[86:89], v152 offset:4672
	v_mfma_f32_32x32x16_bf16 v[34:49], v[66:69], v[70:73], v[34:49]
	ds_read_b128 v[66:69], v151 offset:18528
	ds_read_b128 v[70:73], v152 offset:96
	s_waitcnt lgkmcnt(4)
	v_mfma_f32_32x32x16_bf16 v[50:65], v[78:81], v[82:85], v[50:65]
	ds_read_b128 v[90:93], v151 offset:23136
	ds_read_b128 v[94:97], v152 offset:4704
	s_waitcnt lgkmcnt(0)
	s_barrier
	v_mfma_f32_32x32x16_bf16 v[34:49], v[74:77], v[82:85], v[34:49]
	ds_read_b128 v[82:85], v168 offset:55296
	ds_read_b128 v[98:101], v169 offset:36864
	v_mfma_f32_32x32x16_bf16 v[18:33], v[78:81], v[86:89], v[18:33]
	ds_read_b128 v[78:81], v168 offset:59904
	ds_read_b128 v[102:105], v169 offset:41472
	v_mfma_f32_32x32x16_bf16 v[2:17], v[74:77], v[86:89], v[2:17]
	ds_read_b128 v[74:77], v151 offset:59936
	ds_read_b128 v[86:89], v152 offset:41504
	v_mfma_f32_32x32x16_bf16 v[50:65], v[66:69], v[70:73], v[50:65]
	ds_read_b128 v[106:109], v151 offset:55328
	ds_read_b128 v[110:113], v151 offset:55360
	v_mfma_f32_32x32x16_bf16 v[34:49], v[90:93], v[70:73], v[34:49]
	ds_read_b128 v[70:73], v152 offset:36896
	ds_read_b128 v[128:131], v152 offset:36928
	v_mfma_f32_32x32x16_bf16 v[18:33], v[66:69], v[94:97], v[18:33]
	ds_read_b128 v[66:69], v151 offset:59968
	ds_read_b128 v[132:135], v152 offset:41536
	v_mfma_f32_32x32x16_bf16 v[2:17], v[90:93], v[94:97], v[2:17]
	ds_read_b128 v[90:93], v151 offset:55392
	ds_read_b128 v[94:97], v152 offset:36960
	s_waitcnt lgkmcnt(12)
	v_mfma_f32_32x32x16_bf16 v[50:65], v[82:85], v[98:101], v[50:65]
	ds_read_b128 v[172:175], v151 offset:60000
	ds_read_b128 v[176:179], v152 offset:41568
	s_waitcnt lgkmcnt(0)
	s_barrier
	s_barrier
	v_mfma_f32_32x32x16_bf16 v[34:49], v[78:81], v[98:101], v[34:49]
	v_mfma_f32_32x32x16_bf16 v[18:33], v[82:85], v[102:105], v[18:33]
	v_mfma_f32_32x32x16_bf16 v[2:17], v[78:81], v[102:105], v[2:17]
	v_mfma_f32_32x32x16_bf16 v[50:65], v[106:109], v[70:73], v[50:65]
	v_mfma_f32_32x32x16_bf16 v[34:49], v[74:77], v[70:73], v[34:49]
	v_mfma_f32_32x32x16_bf16 v[18:33], v[106:109], v[86:89], v[18:33]
	v_mfma_f32_32x32x16_bf16 v[2:17], v[74:77], v[86:89], v[2:17]
	v_mfma_f32_32x32x16_bf16 v[50:65], v[110:113], v[128:131], v[50:65]
	v_mfma_f32_32x32x16_bf16 v[34:49], v[66:69], v[128:131], v[34:49]
	v_mfma_f32_32x32x16_bf16 v[18:33], v[110:113], v[132:135], v[18:33]
	v_mfma_f32_32x32x16_bf16 v[2:17], v[66:69], v[132:135], v[2:17]
	v_add_u32_e32 v67, s50, v148
	v_cmp_gt_u32_e32 vcc, s22, v67
	v_mov_b32_e32 v66, 0
	v_mov_b32_e32 v68, 0
	v_mfma_f32_32x32x16_bf16 v[50:65], v[90:93], v[94:97], v[50:65]
	v_mfma_f32_32x32x16_bf16 v[34:49], v[172:175], v[94:97], v[34:49]
	v_mfma_f32_32x32x16_bf16 v[18:33], v[90:93], v[176:179], v[18:33]
	v_mfma_f32_32x32x16_bf16 v[2:17], v[172:175], v[176:179], v[2:17]
	s_and_saveexec_b64 s[4:5], vcc
	s_cbranch_execz .LBB0_681
	v_or_b32_e32 v67, s58, v67
	v_lshlrev_b32_e32 v67, 6, v67
	global_load_dwordx4 v[68:71], v67, s[44:45]
	global_load_dwordx4 v[72:75], v67, s[44:45] offset:16
	global_load_dwordx4 v[76:79], v67, s[44:45] offset:32
	global_load_dwordx4 v[80:83], v67, s[44:45] offset:48
	s_waitcnt vmcnt(3)
	v_mov_b32_e32 v84, v69
	v_mov_b32_e32 v85, v70
	v_mov_b32_e32 v69, v71
	s_waitcnt vmcnt(2)
	v_mov_b32_e32 v70, v73
	v_mov_b32_e32 v71, v74
	v_mov_b32_e32 v73, v75
	v_add_f32_e64 v68, v84, v68
	v_add_f32_e64 v69, v85, v69
	v_add_f32_e64 v70, v70, v72
	v_add_f32_e64 v71, v71, v73
	v_pk_add_f32 v[68:69], v[68:69], v[68:69] op_sel:[0,1] op_sel_hi:[1,0]
	v_pk_add_f32 v[70:71], v[70:71], v[70:71] op_sel:[0,1] op_sel_hi:[1,0]
	s_waitcnt vmcnt(1)
	v_add_f32_e32 v74, v76, v77
	v_add_f32_e32 v76, v78, v79
	s_waitcnt vmcnt(0)
	v_mov_b32_e32 v75, v82
	v_mov_b32_e32 v77, v83
	v_mov_b32_e32 v69, v80
	v_mov_b32_e32 v71, v81
	v_add_f32_e64 v72, v74, v76
	v_add_f32_e64 v73, v75, v77
	v_add_f32_e64 v68, v68, v70
	v_add_f32_e64 v69, v69, v71
	s_nop 0
	v_add_f32_e64 v68, v68, v72
	v_add_f32_e64 v69, v69, v73
	s_nop 0
	v_add_f32_e32 v67, v68, v69
	v_fmamk_f32 v67, v67, 0x3a800000, v170
	v_mul_f32_e32 v68, 0x4b800000, v67
	v_cmp_gt_f32_e32 vcc, s25, v67
	s_nop 1
	v_cndmask_b32_e32 v67, v67, v68, vcc
	v_rsq_f32_e32 v67, v67
	s_nop 0
	v_mul_f32_e32 v68, 0x45800000, v67
	v_cndmask_b32_e32 v68, v67, v68, vcc
.LBB0_681:
	s_or_b64 exec, exec, s[4:5]
	s_nop 6
	v_mul_f32_e64 v34, v34, v68
	v_mul_f32_e64 v35, v35, v68
	ds_write2_b32 v153, v34, v35 offset0:32 offset1:33
	v_mul_f32_e64 v34, v36, v68
	v_mul_f32_e64 v35, v37, v68
	v_mul_f32_e64 v50, v50, v68
	v_mul_f32_e64 v51, v51, v68
	ds_write2_b32 v153, v34, v35 offset0:34 offset1:35
	v_mul_f32_e64 v34, v38, v68
	v_mul_f32_e64 v35, v39, v68
	ds_write2_b32 v153, v50, v51 offset1:1
	v_mul_f32_e64 v50, v52, v68
	v_mul_f32_e64 v51, v53, v68
	ds_write2_b32 v153, v34, v35 offset0:40 offset1:41
	v_mul_f32_e64 v34, v40, v68
	v_mul_f32_e64 v35, v41, v68
	ds_write2_b32 v153, v50, v51 offset0:2 offset1:3
	v_mul_f32_e64 v50, v54, v68
	v_mul_f32_e64 v51, v55, v68
	ds_write2_b32 v153, v34, v35 offset0:42 offset1:43
	v_mul_f32_e64 v34, v42, v68
	v_mul_f32_e64 v35, v43, v68
	ds_write2_b32 v153, v50, v51 offset0:8 offset1:9
	v_mul_f32_e64 v50, v56, v68
	v_mul_f32_e64 v51, v57, v68
	ds_write2_b32 v153, v34, v35 offset0:48 offset1:49
	v_mul_f32_e64 v34, v44, v68
	v_mul_f32_e64 v35, v45, v68
	ds_write2_b32 v153, v50, v51 offset0:10 offset1:11
	v_mul_f32_e64 v50, v58, v68
	v_mul_f32_e64 v51, v59, v68
	ds_write2_b32 v153, v34, v35 offset0:50 offset1:51
	v_mul_f32_e64 v34, v46, v68
	v_mul_f32_e64 v35, v47, v68
	ds_write2_b32 v153, v50, v51 offset0:16 offset1:17
	v_mul_f32_e64 v50, v60, v68
	v_mul_f32_e64 v51, v61, v68
	ds_write2_b32 v153, v34, v35 offset0:56 offset1:57
	v_mul_f32_e64 v34, v48, v68
	v_mul_f32_e64 v35, v49, v68
	ds_write2_b32 v153, v50, v51 offset0:18 offset1:19
	v_mul_f32_e64 v50, v62, v68
	v_mul_f32_e64 v51, v63, v68
	ds_write2_b32 v153, v34, v35 offset0:58 offset1:59
	v_add_u32_e32 v34, s50, v154
	ds_write2_b32 v153, v50, v51 offset0:24 offset1:25
	v_mul_f32_e64 v50, v64, v68
	v_mul_f32_e64 v51, v65, v68
	v_cmp_gt_u32_e32 vcc, s22, v34
	ds_write2_b32 v153, v50, v51 offset0:26 offset1:27
	s_and_saveexec_b64 s[4:5], vcc
	s_cbranch_execz .LBB0_683
	v_or_b32_e32 v34, s58, v34
	v_lshlrev_b32_e32 v46, 6, v34
	global_load_dwordx4 v[34:37], v46, s[44:45]
	global_load_dwordx4 v[38:41], v46, s[44:45] offset:16
	global_load_dwordx4 v[42:45], v46, s[44:45] offset:32
	s_nop 0
	global_load_dwordx4 v[46:49], v46, s[44:45] offset:48
	s_waitcnt vmcnt(3)
	v_mov_b32_e32 v50, v35
	v_mov_b32_e32 v51, v36
	v_mov_b32_e32 v35, v37
	s_waitcnt vmcnt(2)
	v_mov_b32_e32 v36, v39
	v_mov_b32_e32 v37, v40
	v_mov_b32_e32 v39, v41
	v_add_f32_e64 v34, v50, v34
	v_add_f32_e64 v35, v51, v35
	v_add_f32_e64 v36, v36, v38
	v_add_f32_e64 v37, v37, v39
	v_pk_add_f32 v[34:35], v[34:35], v[34:35] op_sel:[0,1] op_sel_hi:[1,0]
	v_pk_add_f32 v[36:37], v[36:37], v[36:37] op_sel:[0,1] op_sel_hi:[1,0]
	s_waitcnt vmcnt(1)
	v_add_f32_e32 v40, v42, v43
	v_add_f32_e32 v42, v44, v45
	s_waitcnt vmcnt(0)
	v_mov_b32_e32 v41, v48
	v_mov_b32_e32 v43, v49
	v_mov_b32_e32 v35, v46
	v_mov_b32_e32 v37, v47
	v_add_f32_e64 v38, v40, v42
	v_add_f32_e64 v39, v41, v43
	v_add_f32_e64 v34, v34, v36
	v_add_f32_e64 v35, v35, v37
	s_nop 0
	v_add_f32_e64 v34, v34, v38
	v_add_f32_e64 v35, v35, v39
	s_nop 0
	v_add_f32_e32 v34, v34, v35
	v_fmamk_f32 v34, v34, 0x3a800000, v170
	v_mul_f32_e32 v35, 0x4b800000, v34
	v_cmp_gt_f32_e32 vcc, s25, v34
	s_nop 1
	v_cndmask_b32_e32 v34, v34, v35, vcc
	v_rsq_f32_e32 v34, v34
	s_nop 0
	v_mul_f32_e32 v35, 0x45800000, v34
	v_cndmask_b32_e32 v66, v34, v35, vcc
.LBB0_683:
	s_or_b64 exec, exec, s[4:5]
	v_mul_f32_e64 v2, v2, v66
	v_mul_f32_e64 v3, v3, v66
	ds_write2_b32 v155, v2, v3 offset0:32 offset1:33
	v_mul_f32_e64 v2, v4, v66
	v_mul_f32_e64 v3, v5, v66
	ds_write2_b32 v155, v2, v3 offset0:34 offset1:35
	v_mul_f32_e64 v2, v6, v66
	v_mul_f32_e64 v3, v7, v66
	ds_write2_b32 v155, v2, v3 offset0:40 offset1:41
	v_mul_f32_e64 v2, v8, v66
	v_mul_f32_e64 v3, v9, v66
	ds_write2_b32 v155, v2, v3 offset0:42 offset1:43
	v_mul_f32_e64 v2, v10, v66
	v_mul_f32_e64 v3, v11, v66
	ds_write2_b32 v155, v2, v3 offset0:48 offset1:49
	v_mul_f32_e64 v2, v12, v66
	v_mul_f32_e64 v3, v13, v66
	s_load_dwordx8 s[4:11], s[0:1], 0xc0
	ds_write2_b32 v155, v2, v3 offset0:50 offset1:51
	v_mul_f32_e64 v2, v14, v66
	v_mul_f32_e64 v3, v15, v66
	ds_write2_b32 v155, v2, v3 offset0:56 offset1:57
	v_mul_f32_e64 v2, v16, v66
	v_mul_f32_e64 v3, v17, v66
	ds_write2_b32 v155, v2, v3 offset0:58 offset1:59
	v_lshl_or_b32 v2, s14, 6, v114
	v_ashrrev_i32_e32 v3, 31, v2
	v_lshlrev_b64 v[8:9], 2, v[2:3]
	s_waitcnt lgkmcnt(0)
	s_mov_b64 s[4:5], s[8:9]
	v_lshl_add_u64 v[10:11], s[4:5], 0, v[8:9]
	v_mul_f32_e64 v18, v18, v66
	v_mul_f32_e64 v19, v19, v66
	v_add_co_u32_e32 v4, vcc, s24, v10
	ds_write2_b32 v155, v18, v19 offset1:1
	v_mul_f32_e64 v18, v20, v66
	v_mul_f32_e64 v19, v21, v66
	v_addc_co_u32_e32 v5, vcc, 0, v11, vcc
	ds_write2_b32 v155, v18, v19 offset0:2 offset1:3
	v_mul_f32_e64 v18, v22, v66
	v_mul_f32_e64 v19, v23, v66
	v_add_co_u32_e32 v6, vcc, s28, v10
	ds_write2_b32 v155, v18, v19 offset0:8 offset1:9
	v_mul_f32_e64 v18, v24, v66
	v_mul_f32_e64 v19, v25, v66
	v_addc_co_u32_e32 v7, vcc, 0, v11, vcc
	ds_write2_b32 v155, v18, v19 offset0:10 offset1:11
	v_mul_f32_e64 v18, v26, v66
	v_mul_f32_e64 v19, v27, v66
	v_add_co_u32_e32 v14, vcc, s22, v10
	ds_write2_b32 v155, v18, v19 offset0:16 offset1:17
	v_mul_f32_e64 v18, v28, v66
	v_mul_f32_e64 v19, v29, v66
	v_addc_co_u32_e32 v15, vcc, 0, v11, vcc
	ds_write2_b32 v155, v18, v19 offset0:18 offset1:19
	v_mul_f32_e64 v18, v30, v66
	v_mul_f32_e64 v19, v31, v66
	v_add_co_u32_e32 v16, vcc, s29, v10
	ds_write2_b32 v155, v18, v19 offset0:24 offset1:25
	v_mul_f32_e64 v18, v32, v66
	v_mul_f32_e64 v19, v33, v66
	v_addc_co_u32_e32 v17, vcc, 0, v11, vcc
	ds_write2_b32 v155, v18, v19 offset0:26 offset1:27
	s_waitcnt lgkmcnt(0)
	s_barrier
	s_mov_b64 s[6:7], s[10:11]
	global_load_dword v3, v[10:11], off
	s_nop 0
	global_load_dword v5, v[4:5], off offset:2048
	s_nop 0
	global_load_dword v7, v[6:7], off
	v_add_co_u32_e32 v10, vcc, s33, v10
	v_lshl_add_u64 v[12:13], s[6:7], 0, v[8:9]
	s_nop 0
	v_addc_co_u32_e32 v11, vcc, 0, v11, vcc
	global_load_dword v9, v[12:13], off
	global_load_dword v2, v[14:15], off offset:3072
	global_load_dword v4, v[16:17], off offset:1024
	global_load_dword v6, v[10:11], off offset:3072
	v_add_co_u32_e32 v10, vcc, s22, v12
	s_mul_i32 s4, s51, 0x7e
	s_nop 0
	v_addc_co_u32_e32 v11, vcc, 0, v13, vcc
	global_load_dword v8, v[10:11], off offset:3072
	ds_read_b32 v15, v159
	ds_read_b32 v10, v160
	ds_read_b32 v14, v161
	ds_read_b32 v11, v162
	s_add_i32 s4, s21, s4
	s_mulk_i32 s52, 0x7c
	s_sub_i32 s10, s4, s52
	v_add_lshl_u32 v16, v167, s53, 6
	s_mov_b64 s[4:5], 0
	v_mov_b32_e32 v17, v158
	v_mov_b32_e32 v18, v156
	s_waitcnt vmcnt(0)
	s_add_i32 s63, s10, -2
	s_sub_i32 s64, s22, s50
	v_min_i32_e32 v40, s64, v157
	v_add_u32_e32 v40, s63, v40
	v_lshlrev_b32_e32 v41, 1, v114
	s_mov_b32 s62, 4

.LBB0_763:
	v_or_b32_e32 v24, s16, v20
	v_add_u32_e32 v10, 8, v24
	s_waitcnt lgkmcnt(0)
	v_lshrrev_b32_e32 v8, 3, v10
	v_and_b32_e32 v8, 0xffffff0, v8
	v_add_u32_e32 v8, v8, v21
	v_ashrrev_i32_e32 v9, 31, v8
	v_lshlrev_b64 v[8:9], 14, v[8:9]
	v_lshlrev_b32_e32 v10, 7, v10
	v_lshl_add_u64 v[8:9], s[92:93], 0, v[8:9]
	v_and_b32_e32 v10, 0x3f80, v10
	v_mov_b32_e32 v11, v115
	v_add_u32_e32 v12, 16, v24
	v_lshl_add_u64 v[8:9], v[8:9], 0, v[10:11]
	v_lshrrev_b32_e32 v10, 3, v12
	v_and_b32_e32 v10, 0xffffff0, v10
	v_add_u32_e32 v10, v10, v21
	v_ashrrev_i32_e32 v11, 31, v10
	v_lshlrev_b64 v[10:11], 14, v[10:11]
	v_lshlrev_b32_e32 v12, 7, v12
	v_lshl_add_u64 v[10:11], s[92:93], 0, v[10:11]
	v_and_b32_e32 v12, 0x3f80, v12
	v_mov_b32_e32 v13, v115
	v_add_u32_e32 v14, 24, v24
	v_lshl_add_u64 v[10:11], v[10:11], 0, v[12:13]
	v_lshrrev_b32_e32 v12, 3, v14
	v_and_b32_e32 v12, 0xffffff0, v12
	v_add_u32_e32 v12, v12, v21
	v_lshlrev_b32_e32 v6, 7, v24
	v_ashrrev_i32_e32 v13, 31, v12
	v_and_b32_e32 v6, 0x2f80, v6
	v_mov_b32_e32 v7, v115
	v_lshlrev_b64 v[12:13], 14, v[12:13]
	v_lshlrev_b32_e32 v14, 7, v14
	v_lshl_add_u64 v[6:7], v[2:3], 0, v[6:7]
	v_lshl_add_u64 v[12:13], s[92:93], 0, v[12:13]
	v_and_b32_e32 v14, 0x3f80, v14
	v_mov_b32_e32 v15, v115
	v_lshl_add_u64 v[6:7], v[6:7], 0, v[114:115]
	v_lshl_add_u64 v[12:13], v[12:13], 0, v[14:15]
	v_lshl_add_u64 v[8:9], v[8:9], 0, v[114:115]
	v_lshl_add_u64 v[10:11], v[10:11], 0, v[114:115]
	v_lshl_add_u64 v[12:13], v[12:13], 0, v[114:115]
	global_load_dwordx2 v[28:29], v[6:7], off
	global_load_dwordx2 v[18:19], v[8:9], off
	global_load_dwordx2 v[16:17], v[10:11], off
	global_load_dwordx2 v[14:15], v[12:13], off
	v_add_u32_e32 v10, 40, v24
	v_lshrrev_b32_e32 v8, 3, v10
	v_and_b32_e32 v8, 0xffffff0, v8
	v_add_u32_e32 v8, v8, v21
	v_ashrrev_i32_e32 v9, 31, v8
	v_lshlrev_b64 v[8:9], 14, v[8:9]
	v_lshlrev_b32_e32 v10, 7, v10
	v_lshl_add_u64 v[8:9], s[92:93], 0, v[8:9]
	v_and_b32_e32 v10, 0x3f80, v10
	v_mov_b32_e32 v11, v115
	v_add_u32_e32 v12, 48, v24
	v_lshl_add_u64 v[8:9], v[8:9], 0, v[10:11]
	v_lshrrev_b32_e32 v10, 3, v12
	v_and_b32_e32 v10, 0xffffff0, v10
	v_add_u32_e32 v10, v10, v21
	v_ashrrev_i32_e32 v11, 31, v10
	v_lshlrev_b64 v[10:11], 14, v[10:11]
	v_lshlrev_b32_e32 v12, 7, v12
	v_lshl_add_u64 v[10:11], s[92:93], 0, v[10:11]
	v_and_b32_e32 v12, 0x3f80, v12
	v_mov_b32_e32 v13, v115
	v_lshl_add_u64 v[10:11], v[10:11], 0, v[12:13]
	v_add_u32_e32 v12, 56, v24
	v_lshl_add_u64 v[22:23], v[10:11], 0, v[114:115]
	v_lshrrev_b32_e32 v10, 3, v12
	v_and_b32_e32 v10, 0xffffff0, v10
	v_add_u32_e32 v10, v10, v21
	v_ashrrev_i32_e32 v11, 31, v10
	v_lshlrev_b64 v[10:11], 14, v[10:11]
	v_lshlrev_b32_e32 v12, 7, v12
	v_add_co_u32_e32 v6, vcc, s19, v6
	v_lshl_add_u64 v[10:11], s[92:93], 0, v[10:11]
	v_and_b32_e32 v12, 0x3f80, v12
	v_addc_co_u32_e32 v7, vcc, 0, v7, vcc
	v_lshl_add_u64 v[8:9], v[8:9], 0, v[114:115]
	v_lshl_add_u64 v[10:11], v[10:11], 0, v[12:13]
	v_lshl_add_u64 v[24:25], v[10:11], 0, v[114:115]
	global_load_dwordx2 v[12:13], v[6:7], off
	global_load_dwordx2 v[10:11], v[8:9], off
	s_nop 0
	global_load_dwordx2 v[8:9], v[22:23], off
	global_load_dwordx2 v[6:7], v[24:25], off
	v_or_b32_e32 v22, s16, v1
	v_mad_u32_u24 v23, v22, s20, v162
	ds_read_b128 v[24:27], v23
	s_waitcnt vmcnt(7)
	v_and_b32_e32 v31, 0xffff0000, v28
	v_lshlrev_b32_e32 v30, 16, v28
	v_and_b32_e32 v33, 0xffff0000, v29
	v_lshlrev_b32_e32 v32, 16, v29
	s_waitcnt lgkmcnt(0)
	v_add_f32_e64 v28, v24, v30
	v_add_f32_e64 v29, v25, v31
	v_add_f32_e64 v26, v26, v32
	v_add_f32_e64 v27, v27, v33
	v_mul_f32_e32 v23, v29, v29
	v_fmac_f32_e32 v23, v28, v28
	v_fmac_f32_e32 v23, v26, v26
	v_fmac_f32_e32 v23, v27, v27
	ds_bpermute_b32 v24, v163, v23
	v_lshlrev_b32_e32 v30, 7, v22
	v_mov_b32_e32 v31, v115
	v_lshl_add_u64 v[30:31], v[4:5], 0, v[30:31]
	v_cvt_pk_bf16_f32 v28, v28, v29
	s_waitcnt lgkmcnt(0)
	v_add_f32_e32 v23, v23, v24
	ds_bpermute_b32 v24, v164, v23
	v_cvt_pk_bf16_f32 v29, v26, v27
	global_store_dwordx2 v[30:31], v[28:29], off
	s_waitcnt lgkmcnt(0)
	v_add_f32_e32 v23, v23, v24
	ds_bpermute_b32 v24, v165, v23
	s_waitcnt lgkmcnt(0)
	v_add_f32_e32 v23, v23, v24
	ds_bpermute_b32 v24, v167, v23
	s_waitcnt lgkmcnt(0)
	v_add_f32_e32 v23, v23, v24
	ds_bpermute_b32 v24, v168, v23
	s_and_saveexec_b64 s[16:17], s[4:5]
	s_cbranch_execz .LBB0_765
	s_waitcnt lgkmcnt(0)
	v_add_f32_e32 v24, v23, v24
	v_or_b32_e32 v23, s10, v22
	v_lshlrev_b32_e32 v23, 6, v23
	v_mov_b32_e32 v25, v115
	global_store_dwordx2 v23, v[24:25], s[6:7]
.LBB0_765:
	s_or_b64 exec, exec, s[16:17]
	v_mul_u32_u24_e32 v23, 0x210, v22
	v_add_u32_e32 v23, v23, v162
	s_waitcnt lgkmcnt(0)
	ds_read_b128 v[24:27], v23 offset:4224
	s_waitcnt vmcnt(7)
	v_and_b32_e32 v29, 0xffff0000, v18
	v_lshlrev_b32_e32 v28, 16, v18
	v_and_b32_e32 v31, 0xffff0000, v19
	v_lshlrev_b32_e32 v30, 16, v19
	s_waitcnt lgkmcnt(0)
	v_add_f32_e64 v28, v24, v28
	v_add_f32_e64 v29, v25, v29
	v_add_f32_e64 v26, v26, v30
	v_add_f32_e64 v27, v27, v31
	v_mul_f32_e32 v18, v29, v29
	v_fmac_f32_e32 v18, v28, v28
	v_fmac_f32_e32 v18, v26, v26
	v_fmac_f32_e32 v18, v27, v27
	ds_bpermute_b32 v19, v163, v18
	v_add_u32_e32 v30, 8, v22
	v_cvt_pk_bf16_f32 v28, v28, v29
	v_cvt_pk_bf16_f32 v29, v26, v27
	s_waitcnt lgkmcnt(0)
	v_add_f32_e32 v19, v18, v19
	ds_bpermute_b32 v24, v164, v19
	v_or_b32_e32 v18, s10, v30
	v_lshrrev_b32_e32 v25, 3, v18
	v_lshlrev_b32_e32 v30, 7, v30
	s_waitcnt lgkmcnt(0)
	v_add_f32_e32 v19, v19, v24
	ds_bpermute_b32 v31, v165, v19
	v_and_b32_e32 v24, 0x1ffffff0, v25
	v_add_u32_e32 v24, v24, v21
	v_ashrrev_i32_e32 v25, 31, v24
	v_lshlrev_b64 v[24:25], 14, v[24:25]
	s_waitcnt lgkmcnt(0)
	v_add_f32_e32 v19, v19, v31
	ds_bpermute_b32 v32, v167, v19
	v_lshl_add_u64 v[24:25], s[92:93], 0, v[24:25]
	v_mov_b32_e32 v31, v115
	v_lshl_add_u64 v[30:31], v[24:25], 0, v[30:31]
	v_lshl_add_u64 v[30:31], v[30:31], 0, v[114:115]
	s_waitcnt lgkmcnt(0)
	v_add_f32_e32 v19, v19, v32
	ds_bpermute_b32 v24, v168, v19
	global_store_dwordx2 v[30:31], v[28:29], off
	s_and_saveexec_b64 s[16:17], s[4:5]
	s_cbranch_execz .LBB0_767
	s_waitcnt lgkmcnt(0)
	v_add_f32_e32 v24, v19, v24
	v_lshlrev_b32_e32 v18, 6, v18
	v_mov_b32_e32 v25, v115
	global_store_dwordx2 v18, v[24:25], s[6:7]
.LBB0_767:
	s_or_b64 exec, exec, s[16:17]
	s_waitcnt lgkmcnt(0)
	ds_read_b128 v[24:27], v23 offset:8448
	s_waitcnt vmcnt(7)
	v_and_b32_e32 v19, 0xffff0000, v16
	v_lshlrev_b32_e32 v18, 16, v16
	v_and_b32_e32 v29, 0xffff0000, v17
	v_lshlrev_b32_e32 v28, 16, v17
	s_waitcnt lgkmcnt(0)
	v_add_f32_e64 v24, v24, v18
	v_add_f32_e64 v25, v25, v19
	v_add_f32_e64 v26, v26, v28
	v_add_f32_e64 v27, v27, v29
	v_mul_f32_e32 v16, v25, v25
	v_fmac_f32_e32 v16, v24, v24
	v_fmac_f32_e32 v16, v26, v26
	v_fmac_f32_e32 v16, v27, v27
	ds_bpermute_b32 v17, v163, v16
	v_add_u32_e32 v28, 16, v22
	v_cvt_pk_bf16_f32 v24, v24, v25
	v_cvt_pk_bf16_f32 v25, v26, v27
	s_waitcnt lgkmcnt(0)
	v_add_f32_e32 v17, v16, v17
	ds_bpermute_b32 v18, v164, v17
	v_or_b32_e32 v16, s10, v28
	v_lshrrev_b32_e32 v19, 3, v16
	v_lshlrev_b32_e32 v28, 7, v28
	s_waitcnt lgkmcnt(0)
	v_add_f32_e32 v17, v17, v18
	ds_bpermute_b32 v29, v165, v17
	v_and_b32_e32 v18, 0x1ffffff0, v19
	v_add_u32_e32 v18, v18, v21
	v_ashrrev_i32_e32 v19, 31, v18
	v_lshlrev_b64 v[18:19], 14, v[18:19]
	s_waitcnt lgkmcnt(0)
	v_add_f32_e32 v17, v17, v29
	ds_bpermute_b32 v30, v167, v17
	v_lshl_add_u64 v[18:19], s[92:93], 0, v[18:19]
	v_mov_b32_e32 v29, v115
	v_lshl_add_u64 v[28:29], v[18:19], 0, v[28:29]
	v_lshl_add_u64 v[28:29], v[28:29], 0, v[114:115]
	s_waitcnt lgkmcnt(0)
	v_add_f32_e32 v17, v17, v30
	ds_bpermute_b32 v18, v168, v17
	global_store_dwordx2 v[28:29], v[24:25], off
	s_and_saveexec_b64 s[16:17], s[4:5]
	s_cbranch_execz .LBB0_769
	s_waitcnt lgkmcnt(0)
	v_add_f32_e32 v18, v17, v18
	v_lshlrev_b32_e32 v16, 6, v16
	v_mov_b32_e32 v19, v115
	global_store_dwordx2 v16, v[18:19], s[6:7]
.LBB0_769:
	s_or_b64 exec, exec, s[16:17]
	s_waitcnt lgkmcnt(0)
	ds_read_b128 v[16:19], v23 offset:12672
	s_waitcnt vmcnt(7)
	v_and_b32_e32 v25, 0xffff0000, v14
	v_lshlrev_b32_e32 v24, 16, v14
	v_and_b32_e32 v27, 0xffff0000, v15
	v_lshlrev_b32_e32 v26, 16, v15
	s_waitcnt lgkmcnt(0)
	v_add_f32_e64 v24, v16, v24
	v_add_f32_e64 v25, v17, v25
	v_add_f32_e64 v18, v18, v26
	v_add_f32_e64 v19, v19, v27
	v_mul_f32_e32 v14, v25, v25
	v_fmac_f32_e32 v14, v24, v24
	v_fmac_f32_e32 v14, v18, v18
	v_fmac_f32_e32 v14, v19, v19
	ds_bpermute_b32 v15, v163, v14
	v_add_u32_e32 v26, 24, v22
	v_cvt_pk_bf16_f32 v24, v24, v25
	v_cvt_pk_bf16_f32 v25, v18, v19
	s_waitcnt lgkmcnt(0)
	v_add_f32_e32 v15, v14, v15
	ds_bpermute_b32 v16, v164, v15
	v_or_b32_e32 v14, s10, v26
	v_lshrrev_b32_e32 v17, 3, v14
	v_lshlrev_b32_e32 v26, 7, v26
	s_waitcnt lgkmcnt(0)
	v_add_f32_e32 v15, v15, v16
	ds_bpermute_b32 v27, v165, v15
	v_and_b32_e32 v16, 0x1ffffff0, v17
	v_add_u32_e32 v16, v16, v21
	v_ashrrev_i32_e32 v17, 31, v16
	v_lshlrev_b64 v[16:17], 14, v[16:17]
	s_waitcnt lgkmcnt(0)
	v_add_f32_e32 v15, v15, v27
	ds_bpermute_b32 v28, v167, v15
	v_lshl_add_u64 v[16:17], s[92:93], 0, v[16:17]
	v_mov_b32_e32 v27, v115
	v_lshl_add_u64 v[26:27], v[16:17], 0, v[26:27]
	v_lshl_add_u64 v[26:27], v[26:27], 0, v[114:115]
	s_waitcnt lgkmcnt(0)
	v_add_f32_e32 v15, v15, v28
	ds_bpermute_b32 v16, v168, v15
	global_store_dwordx2 v[26:27], v[24:25], off
	s_and_saveexec_b64 s[16:17], s[4:5]
	s_cbranch_execz .LBB0_771
	s_waitcnt lgkmcnt(0)
	v_add_f32_e32 v16, v15, v16
	v_lshlrev_b32_e32 v14, 6, v14
	v_mov_b32_e32 v17, v115
	global_store_dwordx2 v14, v[16:17], s[6:7]
.LBB0_771:
	s_or_b64 exec, exec, s[16:17]
	s_waitcnt lgkmcnt(0)
	ds_read_b128 v[14:17], v23 offset:16896
	s_waitcnt vmcnt(7)
	v_and_b32_e32 v19, 0xffff0000, v12
	v_lshlrev_b32_e32 v18, 16, v12
	v_and_b32_e32 v25, 0xffff0000, v13
	v_lshlrev_b32_e32 v24, 16, v13
	s_waitcnt lgkmcnt(0)
	v_add_f32_e64 v18, v14, v18
	v_add_f32_e64 v19, v15, v19
	v_add_f32_e64 v16, v16, v24
	v_add_f32_e64 v17, v17, v25
	v_mul_f32_e32 v12, v19, v19
	v_fmac_f32_e32 v12, v18, v18
	v_fmac_f32_e32 v12, v16, v16
	v_fmac_f32_e32 v12, v17, v17
	ds_bpermute_b32 v13, v163, v12
	v_or_b32_e32 v24, 32, v22
	v_cvt_pk_bf16_f32 v18, v18, v19
	v_cvt_pk_bf16_f32 v19, v16, v17
	s_waitcnt lgkmcnt(0)
	v_add_f32_e32 v13, v12, v13
	ds_bpermute_b32 v14, v164, v13
	v_or_b32_e32 v12, s10, v24
	v_lshrrev_b32_e32 v15, 3, v12
	v_lshlrev_b32_e32 v24, 7, v24
	s_waitcnt lgkmcnt(0)
	v_add_f32_e32 v13, v13, v14
	ds_bpermute_b32 v25, v165, v13
	v_and_b32_e32 v14, 0x1ffffff0, v15
	v_add_u32_e32 v14, v14, v21
	v_ashrrev_i32_e32 v15, 31, v14
	v_lshlrev_b64 v[14:15], 14, v[14:15]
	s_waitcnt lgkmcnt(0)
	v_add_f32_e32 v13, v13, v25
	ds_bpermute_b32 v26, v167, v13
	v_lshl_add_u64 v[14:15], s[92:93], 0, v[14:15]
	v_mov_b32_e32 v25, v115
	v_lshl_add_u64 v[24:25], v[14:15], 0, v[24:25]
	v_lshl_add_u64 v[24:25], v[24:25], 0, v[114:115]
	s_waitcnt lgkmcnt(0)
	v_add_f32_e32 v13, v13, v26
	ds_bpermute_b32 v14, v168, v13
	global_store_dwordx2 v[24:25], v[18:19], off
	s_and_saveexec_b64 s[16:17], s[4:5]
	s_cbranch_execz .LBB0_773
	s_waitcnt lgkmcnt(0)
	v_add_f32_e32 v14, v13, v14
	v_lshlrev_b32_e32 v12, 6, v12
	v_mov_b32_e32 v15, v115
	global_store_dwordx2 v12, v[14:15], s[6:7]
.LBB0_773:
	s_or_b64 exec, exec, s[16:17]
	s_waitcnt lgkmcnt(0)
	ds_read_b128 v[12:15], v23 offset:21120
	s_waitcnt vmcnt(7)
	v_and_b32_e32 v17, 0xffff0000, v10
	v_lshlrev_b32_e32 v16, 16, v10
	v_and_b32_e32 v19, 0xffff0000, v11
	v_lshlrev_b32_e32 v18, 16, v11
	s_waitcnt lgkmcnt(0)
	v_add_f32_e64 v16, v12, v16
	v_add_f32_e64 v17, v13, v17
	v_add_f32_e64 v14, v14, v18
	v_add_f32_e64 v15, v15, v19
	v_mul_f32_e32 v10, v17, v17
	v_fmac_f32_e32 v10, v16, v16
	v_fmac_f32_e32 v10, v14, v14
	v_fmac_f32_e32 v10, v15, v15
	ds_bpermute_b32 v11, v163, v10
	v_add_u32_e32 v18, 40, v22
	v_cvt_pk_bf16_f32 v16, v16, v17
	v_cvt_pk_bf16_f32 v17, v14, v15
	s_waitcnt lgkmcnt(0)
	v_add_f32_e32 v11, v10, v11
	ds_bpermute_b32 v12, v164, v11
	v_add_u32_e32 v10, s10, v18
	v_lshrrev_b32_e32 v13, 3, v10
	v_and_b32_e32 v13, 0x1ffffff0, v13
	v_lshlrev_b32_e32 v18, 7, v18
	s_waitcnt lgkmcnt(0)
	v_add_f32_e32 v11, v11, v12
	ds_bpermute_b32 v19, v165, v11
	v_add_u32_e32 v12, v13, v21
	v_ashrrev_i32_e32 v13, 31, v12
	v_lshlrev_b64 v[12:13], 14, v[12:13]
	v_lshl_add_u64 v[12:13], s[92:93], 0, v[12:13]
	s_waitcnt lgkmcnt(0)
	v_add_f32_e32 v11, v11, v19
	ds_bpermute_b32 v24, v167, v11
	v_and_b32_e32 v18, 0x3f80, v18
	v_mov_b32_e32 v19, v115
	v_lshl_add_u64 v[18:19], v[12:13], 0, v[18:19]
	v_lshl_add_u64 v[18:19], v[18:19], 0, v[114:115]
	s_waitcnt lgkmcnt(0)
	v_add_f32_e32 v11, v11, v24
	ds_bpermute_b32 v12, v168, v11
	global_store_dwordx2 v[18:19], v[16:17], off
	s_and_saveexec_b64 s[16:17], s[4:5]
	s_cbranch_execz .LBB0_775
	s_waitcnt lgkmcnt(0)
	v_add_f32_e32 v12, v11, v12
	v_lshlrev_b32_e32 v10, 6, v10
	v_mov_b32_e32 v13, v115
	global_store_dwordx2 v10, v[12:13], s[6:7]
.LBB0_775:
	s_or_b64 exec, exec, s[16:17]
	s_waitcnt lgkmcnt(0)
	ds_read_b128 v[10:13], v23 offset:25344
	s_waitcnt vmcnt(7)
	v_and_b32_e32 v15, 0xffff0000, v8
	v_lshlrev_b32_e32 v14, 16, v8
	v_and_b32_e32 v17, 0xffff0000, v9
	v_lshlrev_b32_e32 v16, 16, v9
	s_waitcnt lgkmcnt(0)
	v_add_f32_e64 v14, v10, v14
	v_add_f32_e64 v15, v11, v15
	v_add_f32_e64 v12, v12, v16
	v_add_f32_e64 v13, v13, v17
	v_mul_f32_e32 v8, v15, v15
	v_fmac_f32_e32 v8, v14, v14
	v_fmac_f32_e32 v8, v12, v12
	v_fmac_f32_e32 v8, v13, v13
	ds_bpermute_b32 v9, v163, v8
	v_add_u32_e32 v16, 48, v22
	v_cvt_pk_bf16_f32 v14, v14, v15
	v_cvt_pk_bf16_f32 v15, v12, v13
	s_waitcnt lgkmcnt(0)
	v_add_f32_e32 v9, v8, v9
	ds_bpermute_b32 v10, v164, v9
	v_add_u32_e32 v8, s10, v16
	v_lshrrev_b32_e32 v11, 3, v8
	v_and_b32_e32 v11, 0x1ffffff0, v11
	v_lshlrev_b32_e32 v16, 7, v16
	s_waitcnt lgkmcnt(0)
	v_add_f32_e32 v9, v9, v10
	ds_bpermute_b32 v17, v165, v9
	v_add_u32_e32 v10, v11, v21
	v_ashrrev_i32_e32 v11, 31, v10
	v_lshlrev_b64 v[10:11], 14, v[10:11]
	v_lshl_add_u64 v[10:11], s[92:93], 0, v[10:11]
	s_waitcnt lgkmcnt(0)
	v_add_f32_e32 v9, v9, v17
	ds_bpermute_b32 v18, v167, v9
	v_and_b32_e32 v16, 0x3f80, v16
	v_mov_b32_e32 v17, v115
	v_lshl_add_u64 v[16:17], v[10:11], 0, v[16:17]
	v_lshl_add_u64 v[16:17], v[16:17], 0, v[114:115]
	s_waitcnt lgkmcnt(0)
	v_add_f32_e32 v9, v9, v18
	ds_bpermute_b32 v10, v168, v9
	global_store_dwordx2 v[16:17], v[14:15], off
	s_and_saveexec_b64 s[16:17], s[4:5]
	s_cbranch_execz .LBB0_777
	s_waitcnt lgkmcnt(0)
	v_add_f32_e32 v10, v9, v10
	v_lshlrev_b32_e32 v8, 6, v8
	v_mov_b32_e32 v11, v115
	global_store_dwordx2 v8, v[10:11], s[6:7]
.LBB0_777:
	s_or_b64 exec, exec, s[16:17]
	s_waitcnt lgkmcnt(0)
	ds_read_b128 v[8:11], v23 offset:29568
	s_waitcnt vmcnt(7)
	v_and_b32_e32 v13, 0xffff0000, v6
	v_lshlrev_b32_e32 v12, 16, v6
	v_and_b32_e32 v15, 0xffff0000, v7
	v_lshlrev_b32_e32 v14, 16, v7
	s_waitcnt lgkmcnt(0)
	v_add_f32_e64 v12, v8, v12
	v_add_f32_e64 v13, v9, v13
	v_add_f32_e64 v10, v10, v14
	v_add_f32_e64 v11, v11, v15
	v_mul_f32_e32 v6, v13, v13
	v_fmac_f32_e32 v6, v12, v12
	v_fmac_f32_e32 v6, v10, v10
	v_fmac_f32_e32 v6, v11, v11
	ds_bpermute_b32 v7, v163, v6
	v_add_u32_e32 v14, 56, v22
	v_cvt_pk_bf16_f32 v12, v12, v13
	v_cvt_pk_bf16_f32 v13, v10, v11
	s_waitcnt lgkmcnt(0)
	v_add_f32_e32 v7, v6, v7
	ds_bpermute_b32 v8, v164, v7
	v_add_u32_e32 v6, s10, v14
	v_lshrrev_b32_e32 v9, 3, v6
	v_and_b32_e32 v9, 0x1ffffff0, v9
	v_lshlrev_b32_e32 v14, 7, v14
	s_waitcnt lgkmcnt(0)
	v_add_f32_e32 v7, v7, v8
	ds_bpermute_b32 v15, v165, v7
	v_add_u32_e32 v8, v9, v21
	v_ashrrev_i32_e32 v9, 31, v8
	v_lshlrev_b64 v[8:9], 14, v[8:9]
	v_lshl_add_u64 v[8:9], s[92:93], 0, v[8:9]
	s_waitcnt lgkmcnt(0)
	v_add_f32_e32 v7, v7, v15
	ds_bpermute_b32 v16, v167, v7
	v_and_b32_e32 v14, 0x3f80, v14
	v_mov_b32_e32 v15, v115
	v_lshl_add_u64 v[14:15], v[8:9], 0, v[14:15]
	v_lshl_add_u64 v[14:15], v[14:15], 0, v[114:115]
	s_waitcnt lgkmcnt(0)
	v_add_f32_e32 v7, v7, v16
	ds_bpermute_b32 v8, v168, v7
	global_store_dwordx2 v[14:15], v[12:13], off
	s_and_saveexec_b64 s[16:17], s[4:5]
	s_cbranch_execz .LBB0_762
	s_waitcnt lgkmcnt(0)
	v_add_f32_e32 v8, v7, v8
	v_lshlrev_b32_e32 v6, 6, v6
	v_mov_b32_e32 v9, v115
	global_store_dwordx2 v6, v[8:9], s[6:7]
	s_branch .LBB0_762

.LBB0_851:
	s_and_b32 s4, s2, 0xff
	s_mul_hi_u32 s4, s4, 0x5555556
	s_mulk_i32 s4, 0xffd0
	s_mul_i32 s5, s65, 0xab
	s_add_i32 s80, s65, s4
	s_ashr_i32 s66, s80, 3
	s_lshr_b32 s4, s5, 10
	s_and_b32 s5, s65, 7
	s_and_b32 s4, s4, 56
	s_or_b32 s5, s5, s3
	s_ashr_i32 s67, s66, 31
	s_add_i32 s4, s4, s5
	s_lshl_b64 s[6:7], s[66:67], 18
	v_lshl_add_u64 v[124:125], v[100:101], 0, s[6:7]
	s_lshl_b32 s10, s4, 18
	s_movk_i32 s5, 0x2000
	v_lshl_add_u64 v[26:27], v[112:113], 0, s[10:11]
	v_add_co_u32_e32 v22, vcc, s5, v124
	v_lshl_add_u64 v[2:3], v[26:27], 0, v[114:115]
	v_lshl_add_u64 v[10:11], v[26:27], 0, v[116:117]
	v_addc_co_u32_e32 v23, vcc, 0, v125, vcc
	v_lshl_add_u64 v[18:19], v[26:27], 0, v[118:119]
	v_lshl_add_u64 v[26:27], v[26:27], 0, v[120:121]
	s_barrier
	global_load_dwordx4 v[2:5], v[2:3], off
	s_movk_i32 s5, 0x4000
	global_load_dwordx4 v[6:9], v[124:125], off
	global_load_dwordx4 v[14:17], v[22:23], off offset:-4096
	v_add_co_u32_e32 v34, vcc, s5, v124
	global_load_dwordx4 v[10:13], v[10:11], off
	s_nop 0
	v_addc_co_u32_e32 v35, vcc, 0, v125, vcc
	global_load_dwordx4 v[18:21], v[18:19], off
	s_add_u32 s6, s92, s10
	global_load_dwordx4 v[22:25], v[22:23], off
	s_addc_u32 s7, s93, 0
	global_load_dwordx4 v[26:29], v[26:27], off
	v_lshl_add_u64 v[126:127], s[6:7], 0, v[122:123]
	global_load_dwordx4 v[30:33], v[34:35], off offset:-4096
	s_mov_b64 s[6:7], 0x4000
	s_movk_i32 s5, 0x6000
	s_cmp_gt_i32 s66, 1
	s_cselect_b64 s[70:71], -1, 0
	s_cmp_eq_u32 s66, 2
	s_cselect_b64 s[68:69], -1, 0
	s_waitcnt vmcnt(7)
	ds_write_b128 v105, v[2:5]
	s_waitcnt vmcnt(6)
	ds_write_b128 v105, v[6:9] offset:18432
	s_waitcnt vmcnt(5)
	ds_write_b128 v109, v[14:17] offset:18432
	global_load_dwordx4 v[6:9], v[34:35], off
	s_waitcnt vmcnt(5)
	ds_write_b128 v109, v[10:13]
	s_waitcnt vmcnt(4)
	ds_write_b128 v111, v[18:21]
	s_waitcnt vmcnt(3)
	ds_write_b128 v111, v[22:25] offset:18432
	v_add_co_u32_e32 v22, vcc, s5, v124
	s_waitcnt vmcnt(2)
	ds_write_b128 v167, v[26:29]
	v_lshl_add_u64 v[26:27], v[126:127], 0, s[6:7]
	v_lshl_add_u64 v[2:3], v[26:27], 0, v[114:115]
	global_load_dwordx4 v[2:5], v[2:3], off
	v_addc_co_u32_e32 v23, vcc, 0, v125, vcc
	s_mov_b32 s5, 0x8000
	v_add_co_u32_e32 v38, vcc, s5, v124
	v_lshl_add_u64 v[10:11], v[26:27], 0, v[116:117]
	v_lshl_add_u64 v[18:19], v[26:27], 0, v[118:119]
	v_lshl_add_u64 v[26:27], v[26:27], 0, v[120:121]
	v_addc_co_u32_e32 v39, vcc, 0, v125, vcc
	s_waitcnt vmcnt(2)
	ds_write_b128 v167, v[30:33] offset:18432
	global_load_dwordx4 v[10:13], v[10:11], off
	s_mov_b32 s5, 0xc000
	global_load_dwordx4 v[14:17], v[22:23], off offset:-4096
	global_load_dwordx4 v[30:33], v[38:39], off offset:-4096
	s_mov_b64 s[6:7], 0x8000
	global_load_dwordx4 v[18:21], v[18:19], off
	v_add_co_u32_e32 v128, vcc, s5, v124
	global_load_dwordx4 v[22:25], v[22:23], off
	s_nop 0
	v_addc_co_u32_e32 v129, vcc, 0, v125, vcc
	global_load_dwordx4 v[26:29], v[26:27], off
	s_waitcnt lgkmcnt(0)
	s_barrier
	ds_read_b128 v[130:133], v172 offset:18432
	ds_read_b128 v[34:37], v173
	s_waitcnt lgkmcnt(0)
	v_mfma_f32_32x32x16_bf16 v[50:65], v[130:133], v[34:37], 0
	ds_read_b128 v[134:137], v172 offset:23040
	ds_read_b128 v[138:141], v173 offset:4608
	global_load_dwordx4 v[90:93], v[38:39], off
	s_mov_b32 s5, 0xa000
	global_load_dwordx4 v[66:69], v[128:129], off offset:-4096
	s_waitcnt lgkmcnt(1)
	v_mfma_f32_32x32x16_bf16 v[34:49], v[134:137], v[34:37], 0
	s_waitcnt vmcnt(9)
	ds_write_b128 v105, v[6:9] offset:55296
	s_waitcnt vmcnt(8)
	ds_write_b128 v105, v[2:5] offset:36864
	v_lshl_add_u64 v[2:3], v[126:127], 0, s[6:7]
	v_lshl_add_u64 v[4:5], v[2:3], 0, v[120:121]
	global_load_dwordx4 v[70:73], v[4:5], off
	v_add_co_u32_e32 v4, vcc, s5, v124
	s_mov_b32 s5, 0x9000
	s_nop 0
	v_addc_co_u32_e32 v5, vcc, 0, v125, vcc
	global_load_dwordx4 v[74:77], v[4:5], off
	v_lshl_add_u64 v[4:5], v[2:3], 0, v[118:119]
	global_load_dwordx4 v[78:81], v[4:5], off
	v_add_co_u32_e32 v4, vcc, s5, v124
	s_waitcnt vmcnt(10)
	ds_write_b128 v109, v[10:13] offset:36864
	v_addc_co_u32_e32 v5, vcc, 0, v125, vcc
	global_load_dwordx4 v[82:85], v[4:5], off
	v_lshl_add_u64 v[4:5], v[2:3], 0, v[116:117]
	v_lshl_add_u64 v[2:3], v[2:3], 0, v[114:115]
	global_load_dwordx4 v[86:89], v[4:5], off
	global_load_dwordx4 v[94:97], v[2:3], off
	s_waitcnt vmcnt(12)
	ds_write_b128 v109, v[14:17] offset:55296
	s_waitcnt lgkmcnt(4)
	v_mfma_f32_32x32x16_bf16 v[2:17], v[134:137], v[138:141], 0
	s_waitcnt vmcnt(10)
	ds_write_b128 v111, v[18:21] offset:36864
	s_waitcnt vmcnt(9)
	ds_write_b128 v111, v[22:25] offset:55296
	s_waitcnt vmcnt(8)
	ds_write_b128 v167, v[26:29] offset:36864
	ds_write_b128 v167, v[30:33] offset:55296
	s_mov_b32 s5, 0x10000
	s_mov_b64 s[6:7], 0xc000
	v_mfma_f32_32x32x16_bf16 v[18:33], v[130:133], v[138:141], 0
	ds_read_b128 v[142:145], v169 offset:23072
	ds_read_b128 v[146:149], v170 offset:4640
	s_waitcnt lgkmcnt(0)
	v_mfma_f32_32x32x16_bf16 v[2:17], v[142:145], v[146:149], v[2:17]
	ds_read_b128 v[130:133], v169 offset:18464
	ds_read_b128 v[134:137], v169 offset:18496
	s_waitcnt lgkmcnt(1)
	v_mfma_f32_32x32x16_bf16 v[18:33], v[130:133], v[146:149], v[18:33]
	ds_read_b128 v[138:141], v170 offset:32
	ds_read_b128 v[150:153], v170 offset:64
	s_waitcnt lgkmcnt(1)
	v_mfma_f32_32x32x16_bf16 v[50:65], v[130:133], v[138:141], v[50:65]
	ds_read_b128 v[154:157], v169 offset:23104
	ds_read_b128 v[158:161], v170 offset:4672
	v_mfma_f32_32x32x16_bf16 v[34:49], v[142:145], v[138:141], v[34:49]
	ds_read_b128 v[130:133], v169 offset:18528
	ds_read_b128 v[138:141], v170 offset:96
	s_waitcnt lgkmcnt(4)
	v_mfma_f32_32x32x16_bf16 v[50:65], v[134:137], v[150:153], v[50:65]
	ds_read_b128 v[142:145], v169 offset:23136
	ds_read_b128 v[146:149], v170 offset:4704
	s_waitcnt lgkmcnt(0)
	s_barrier
	v_mfma_f32_32x32x16_bf16 v[34:49], v[154:157], v[150:153], v[34:49]
	ds_read_b128 v[150:153], v173 offset:36864
	v_mfma_f32_32x32x16_bf16 v[18:33], v[134:137], v[158:161], v[18:33]
	ds_read_b128 v[134:137], v172 offset:55296
	v_mfma_f32_32x32x16_bf16 v[2:17], v[154:157], v[158:161], v[2:17]
	ds_read_b128 v[154:157], v172 offset:59904
	ds_read_b128 v[158:161], v173 offset:41472
	v_mfma_f32_32x32x16_bf16 v[50:65], v[130:133], v[138:141], v[50:65]
	s_waitcnt vmcnt(7)
	ds_write_b128 v105, v[90:93] offset:18432
	v_add_co_u32_e32 v90, vcc, s5, v124
	s_mov_b32 s5, 0xe000
	s_nop 0
	v_addc_co_u32_e32 v91, vcc, 0, v125, vcc
	s_waitcnt vmcnt(0)
	ds_write_b128 v105, v[94:97]
	v_mfma_f32_32x32x16_bf16 v[34:49], v[142:145], v[138:141], v[34:49]
	ds_write_b128 v109, v[86:89]
	ds_write_b128 v109, v[82:85] offset:18432
	v_lshl_add_u64 v[96:97], v[126:127], 0, s[6:7]
	v_lshl_add_u64 v[86:87], v[96:97], 0, v[116:117]
	global_load_dwordx4 v[92:95], v[128:129], off
	s_mov_b64 s[6:7], 0x10000
	global_load_dwordx4 v[86:89], v[86:87], off
	v_mfma_f32_32x32x16_bf16 v[18:33], v[130:133], v[146:149], v[18:33]
	ds_write_b128 v111, v[74:77] offset:18432
	v_add_co_u32_e32 v74, vcc, s5, v124
	ds_write_b128 v111, v[78:81]
	s_nop 0
	v_addc_co_u32_e32 v75, vcc, 0, v125, vcc
	v_lshl_add_u64 v[78:79], v[96:97], 0, v[118:119]
	v_mfma_f32_32x32x16_bf16 v[2:17], v[142:145], v[146:149], v[2:17]
	ds_write_b128 v167, v[70:73]
	v_lshl_add_u64 v[70:71], v[96:97], 0, v[120:121]
	s_mov_b32 s5, 0xd000
	v_lshl_add_u64 v[96:97], v[96:97], 0, v[114:115]
	v_add_co_u32_e32 v82, vcc, s5, v124
	global_load_dwordx4 v[128:131], v[96:97], off
	s_nop 0
	v_addc_co_u32_e32 v83, vcc, 0, v125, vcc
	global_load_dwordx4 v[74:77], v[74:75], off
	ds_write_b128 v167, v[66:69] offset:18432
	global_load_dwordx4 v[82:85], v[82:83], off
	s_waitcnt lgkmcnt(10)
	v_mfma_f32_32x32x16_bf16 v[50:65], v[134:137], v[150:153], v[50:65]
	global_load_dwordx4 v[70:73], v[70:71], off
	ds_read_b128 v[138:141], v169 offset:59936
	global_load_dwordx4 v[78:81], v[78:79], off
	ds_read_b128 v[142:145], v170 offset:41504
	global_load_dwordx4 v[66:69], v[90:91], off offset:-4096
	s_mov_b32 s5, 0x14000
	s_waitcnt lgkmcnt(11)
	v_mfma_f32_32x32x16_bf16 v[34:49], v[154:157], v[150:153], v[34:49]
	ds_read_b128 v[146:149], v169 offset:55360
	ds_read_b128 v[150:153], v170 offset:36896
	s_waitcnt lgkmcnt(12)
	v_mfma_f32_32x32x16_bf16 v[18:33], v[134:137], v[158:161], v[18:33]
	ds_read_b128 v[132:135], v169 offset:55328
	ds_read_b128 v[162:165], v170 offset:41536
	v_mfma_f32_32x32x16_bf16 v[2:17], v[154:157], v[158:161], v[2:17]
	ds_read_b128 v[154:157], v170 offset:36928
	ds_read_b128 v[158:161], v169 offset:59968
	s_waitcnt lgkmcnt(3)
	v_mfma_f32_32x32x16_bf16 v[50:65], v[132:135], v[150:153], v[50:65]
	v_mfma_f32_32x32x16_bf16 v[34:49], v[138:141], v[150:153], v[34:49]
	ds_read_b128 v[150:153], v170 offset:41568
	v_mfma_f32_32x32x16_bf16 v[18:33], v[132:135], v[142:145], v[18:33]
	ds_read_b128 v[132:135], v169 offset:55392
	v_mfma_f32_32x32x16_bf16 v[2:17], v[138:141], v[142:145], v[2:17]
	ds_read_b128 v[136:139], v170 offset:36960
	ds_read_b128 v[140:143], v169 offset:60000
	s_waitcnt lgkmcnt(0)
	s_barrier
	v_mfma_f32_32x32x16_bf16 v[50:65], v[146:149], v[154:157], v[50:65]
	v_mfma_f32_32x32x16_bf16 v[34:49], v[158:161], v[154:157], v[34:49]
	ds_read_b128 v[154:157], v173
	v_mfma_f32_32x32x16_bf16 v[18:33], v[146:149], v[162:165], v[18:33]
	ds_read_b128 v[144:147], v172 offset:18432
	v_mfma_f32_32x32x16_bf16 v[2:17], v[158:161], v[162:165], v[2:17]
	ds_read_b128 v[158:161], v172 offset:23040
	ds_read_b128 v[162:165], v173 offset:4608
	v_mfma_f32_32x32x16_bf16 v[50:65], v[132:135], v[136:139], v[50:65]
	s_waitcnt vmcnt(5)
	ds_write_b128 v105, v[128:131] offset:36864
	v_add_co_u32_e32 v128, vcc, s5, v124
	s_mov_b32 s5, 0x12000
	s_nop 0
	v_addc_co_u32_e32 v129, vcc, 0, v125, vcc
	ds_write_b128 v105, v[92:95] offset:55296
	v_mfma_f32_32x32x16_bf16 v[34:49], v[140:143], v[136:139], v[34:49]
	ds_write_b128 v109, v[86:89] offset:36864
	s_waitcnt vmcnt(3)
	ds_write_b128 v109, v[82:85] offset:55296
	v_lshl_add_u64 v[94:95], v[126:127], 0, s[6:7]
	v_lshl_add_u64 v[86:87], v[94:95], 0, v[116:117]
	global_load_dwordx4 v[86:89], v[86:87], off
	s_mov_b64 s[6:7], 0x14000
	global_load_dwordx4 v[90:93], v[90:91], off
	v_mfma_f32_32x32x16_bf16 v[18:33], v[132:135], v[150:153], v[18:33]
	ds_write_b128 v111, v[74:77] offset:55296
	v_add_co_u32_e32 v74, vcc, s5, v124
	s_mov_b32 s5, 0x11000
	s_nop 0
	v_addc_co_u32_e32 v75, vcc, 0, v125, vcc
	v_add_co_u32_e32 v82, vcc, s5, v124
	s_waitcnt vmcnt(3)
	ds_write_b128 v111, v[78:81] offset:36864
	v_mfma_f32_32x32x16_bf16 v[2:17], v[140:143], v[150:153], v[2:17]
	ds_write_b128 v167, v[70:73] offset:36864
	v_lshl_add_u64 v[70:71], v[94:95], 0, v[120:121]
	v_lshl_add_u64 v[78:79], v[94:95], 0, v[118:119]
	v_addc_co_u32_e32 v83, vcc, 0, v125, vcc
	v_lshl_add_u64 v[94:95], v[94:95], 0, v[114:115]
	global_load_dwordx4 v[82:85], v[82:83], off
	s_waitcnt vmcnt(3)
	ds_write_b128 v167, v[66:69] offset:55296
	global_load_dwordx4 v[94:97], v[94:95], off
	s_waitcnt lgkmcnt(10)
	v_mfma_f32_32x32x16_bf16 v[50:65], v[144:147], v[154:157], v[50:65]
	global_load_dwordx4 v[74:77], v[74:75], off
	ds_read_b128 v[130:133], v169 offset:23072
	global_load_dwordx4 v[70:73], v[70:71], off
	ds_read_b128 v[134:137], v170 offset:4640
	global_load_dwordx4 v[78:81], v[78:79], off
	s_mov_b32 s5, 0x18000
	global_load_dwordx4 v[66:69], v[128:129], off offset:-4096
	s_waitcnt lgkmcnt(11)
	v_mfma_f32_32x32x16_bf16 v[34:49], v[158:161], v[154:157], v[34:49]
	ds_read_b128 v[138:141], v169 offset:18464
	ds_read_b128 v[150:153], v170 offset:64
	s_waitcnt lgkmcnt(12)
	v_mfma_f32_32x32x16_bf16 v[18:33], v[144:147], v[162:165], v[18:33]
	ds_read_b128 v[146:149], v170 offset:32
	ds_read_b128 v[142:145], v169 offset:18496
	v_mfma_f32_32x32x16_bf16 v[2:17], v[158:161], v[162:165], v[2:17]
	ds_read_b128 v[154:157], v169 offset:23104
	ds_read_b128 v[158:161], v170 offset:4672
	s_waitcnt lgkmcnt(3)
	v_mfma_f32_32x32x16_bf16 v[50:65], v[138:141], v[146:149], v[50:65]
	v_mfma_f32_32x32x16_bf16 v[34:49], v[130:133], v[146:149], v[34:49]
	ds_read_b128 v[146:149], v170 offset:4704
	v_mfma_f32_32x32x16_bf16 v[18:33], v[138:141], v[134:137], v[18:33]
	ds_read_b128 v[138:141], v169 offset:23136
	v_mfma_f32_32x32x16_bf16 v[2:17], v[130:133], v[134:137], v[2:17]
	ds_read_b128 v[130:133], v169 offset:18528
	ds_read_b128 v[134:137], v170 offset:96
	s_waitcnt lgkmcnt(0)
	s_barrier
	v_mfma_f32_32x32x16_bf16 v[50:65], v[142:145], v[150:153], v[50:65]
	v_mfma_f32_32x32x16_bf16 v[34:49], v[154:157], v[150:153], v[34:49]
	ds_read_b128 v[150:153], v173 offset:36864
	v_mfma_f32_32x32x16_bf16 v[18:33], v[142:145], v[158:161], v[18:33]
	ds_read_b128 v[142:145], v172 offset:55296
	v_mfma_f32_32x32x16_bf16 v[2:17], v[154:157], v[158:161], v[2:17]
	ds_read_b128 v[154:157], v172 offset:59904
	ds_read_b128 v[158:161], v173 offset:41472
	v_mfma_f32_32x32x16_bf16 v[50:65], v[130:133], v[134:137], v[50:65]
	s_waitcnt vmcnt(4)
	ds_write_b128 v105, v[94:97]
	ds_write_b128 v105, v[90:93] offset:18432
	v_lshl_add_u64 v[94:95], v[126:127], 0, s[6:7]
	global_load_dwordx4 v[90:93], v[128:129], off
	s_mov_b64 s[6:7], 0x18000
	v_mfma_f32_32x32x16_bf16 v[34:49], v[138:141], v[134:137], v[34:49]
	ds_write_b128 v109, v[86:89]
	ds_write_b128 v109, v[82:85] offset:18432
	v_lshl_add_u64 v[86:87], v[94:95], 0, v[116:117]
	global_load_dwordx4 v[86:89], v[86:87], off
	v_mfma_f32_32x32x16_bf16 v[18:33], v[130:133], v[146:149], v[18:33]
	v_add_co_u32_e32 v130, vcc, s5, v124
	s_mov_b32 s5, 0x16000
	s_nop 0
	v_addc_co_u32_e32 v131, vcc, 0, v125, vcc
	s_waitcnt vmcnt(5)
	ds_write_b128 v111, v[74:77] offset:18432
	v_add_co_u32_e32 v74, vcc, s5, v124
	s_mov_b32 s5, 0x15000
	s_nop 0
	v_addc_co_u32_e32 v75, vcc, 0, v125, vcc
	v_add_co_u32_e32 v82, vcc, s5, v124
	s_waitcnt vmcnt(3)
	ds_write_b128 v111, v[78:81]
	v_mfma_f32_32x32x16_bf16 v[2:17], v[138:141], v[146:149], v[2:17]
	ds_write_b128 v167, v[70:73]
	v_lshl_add_u64 v[70:71], v[94:95], 0, v[120:121]
	v_lshl_add_u64 v[78:79], v[94:95], 0, v[118:119]
	v_addc_co_u32_e32 v83, vcc, 0, v125, vcc
	v_lshl_add_u64 v[94:95], v[94:95], 0, v[114:115]
	global_load_dwordx4 v[74:77], v[74:75], off
	s_waitcnt vmcnt(3)
	ds_write_b128 v167, v[66:69] offset:18432
	global_load_dwordx4 v[82:85], v[82:83], off
	s_waitcnt lgkmcnt(10)
	v_mfma_f32_32x32x16_bf16 v[50:65], v[142:145], v[150:153], v[50:65]
	global_load_dwordx4 v[94:97], v[94:95], off
	ds_read_b128 v[132:135], v169 offset:59936
	global_load_dwordx4 v[70:73], v[70:71], off
	ds_read_b128 v[136:139], v170 offset:41504
	global_load_dwordx4 v[78:81], v[78:79], off
	s_mov_b32 s5, 0x1c000
	global_load_dwordx4 v[66:69], v[130:131], off offset:-4096
	s_waitcnt lgkmcnt(11)
	v_mfma_f32_32x32x16_bf16 v[34:49], v[154:157], v[150:153], v[34:49]
	ds_read_b128 v[148:151], v170 offset:36896
	v_add_co_u32_e32 v128, vcc, s5, v124
	s_mov_b32 s5, 0x1a000
	s_nop 0
	v_addc_co_u32_e32 v129, vcc, 0, v125, vcc
	s_waitcnt lgkmcnt(11)
	v_mfma_f32_32x32x16_bf16 v[18:33], v[142:145], v[158:161], v[18:33]
	ds_read_b128 v[140:143], v169 offset:55328
	ds_read_b128 v[144:147], v169 offset:55360
	v_mfma_f32_32x32x16_bf16 v[2:17], v[154:157], v[158:161], v[2:17]
	ds_read_b128 v[156:159], v169 offset:59968
	ds_read_b128 v[152:155], v170 offset:36928
	s_waitcnt lgkmcnt(3)
	v_mfma_f32_32x32x16_bf16 v[50:65], v[140:143], v[148:151], v[50:65]
	ds_read_b128 v[160:163], v170 offset:41536
	v_mfma_f32_32x32x16_bf16 v[34:49], v[132:135], v[148:151], v[34:49]
	ds_read_b128 v[148:151], v170 offset:41568
	v_mfma_f32_32x32x16_bf16 v[18:33], v[140:143], v[136:139], v[18:33]
	ds_read_b128 v[140:143], v169 offset:60000
	v_mfma_f32_32x32x16_bf16 v[2:17], v[132:135], v[136:139], v[2:17]
	ds_read_b128 v[132:135], v169 offset:55392
	ds_read_b128 v[136:139], v170 offset:36960
	s_waitcnt lgkmcnt(0)
	s_barrier
	v_mfma_f32_32x32x16_bf16 v[50:65], v[144:147], v[152:155], v[50:65]
	v_mfma_f32_32x32x16_bf16 v[34:49], v[156:159], v[152:155], v[34:49]
	ds_read_b128 v[152:155], v173
	v_mfma_f32_32x32x16_bf16 v[18:33], v[144:147], v[160:163], v[18:33]
	ds_read_b128 v[144:147], v172 offset:18432
	v_mfma_f32_32x32x16_bf16 v[2:17], v[156:159], v[160:163], v[2:17]
	ds_read_b128 v[156:159], v172 offset:23040
	ds_read_b128 v[160:163], v173 offset:4608
	v_mfma_f32_32x32x16_bf16 v[50:65], v[132:135], v[136:139], v[50:65]
	s_waitcnt vmcnt(3)
	ds_write_b128 v105, v[94:97] offset:36864
	ds_write_b128 v105, v[90:93] offset:55296
	v_lshl_add_u64 v[94:95], v[126:127], 0, s[6:7]
	global_load_dwordx4 v[90:93], v[130:131], off
	s_mov_b64 s[6:7], 0x1c000
	v_mfma_f32_32x32x16_bf16 v[34:49], v[140:143], v[136:139], v[34:49]
	ds_write_b128 v109, v[86:89] offset:36864
	ds_write_b128 v109, v[82:85] offset:55296
	v_lshl_add_u64 v[86:87], v[94:95], 0, v[116:117]
	global_load_dwordx4 v[86:89], v[86:87], off
	v_mfma_f32_32x32x16_bf16 v[18:33], v[132:135], v[148:151], v[18:33]
	ds_write_b128 v111, v[74:77] offset:55296
	v_add_co_u32_e32 v74, vcc, s5, v124
	s_mov_b32 s5, 0x19000
	s_nop 0
	v_addc_co_u32_e32 v75, vcc, 0, v125, vcc
	v_add_co_u32_e32 v82, vcc, s5, v124
	s_waitcnt vmcnt(3)
	ds_write_b128 v111, v[78:81] offset:36864
	v_mfma_f32_32x32x16_bf16 v[2:17], v[140:143], v[148:151], v[2:17]
	ds_write_b128 v167, v[70:73] offset:36864
	v_lshl_add_u64 v[70:71], v[94:95], 0, v[120:121]
	v_lshl_add_u64 v[78:79], v[94:95], 0, v[118:119]
	v_addc_co_u32_e32 v83, vcc, 0, v125, vcc
	v_lshl_add_u64 v[94:95], v[94:95], 0, v[114:115]
	global_load_dwordx4 v[82:85], v[82:83], off
	s_waitcnt vmcnt(3)
	ds_write_b128 v167, v[66:69] offset:55296
	global_load_dwordx4 v[94:97], v[94:95], off
	s_waitcnt lgkmcnt(10)
	v_mfma_f32_32x32x16_bf16 v[50:65], v[144:147], v[152:155], v[50:65]
	global_load_dwordx4 v[74:77], v[74:75], off
	ds_read_b128 v[130:133], v169 offset:23072
	global_load_dwordx4 v[70:73], v[70:71], off
	ds_read_b128 v[134:137], v170 offset:4640
	global_load_dwordx4 v[78:81], v[78:79], off
	s_mov_b32 s5, 0x20000
	global_load_dwordx4 v[66:69], v[128:129], off offset:-4096
	s_waitcnt lgkmcnt(11)
	v_mfma_f32_32x32x16_bf16 v[34:49], v[156:159], v[152:155], v[34:49]
	ds_read_b128 v[138:141], v169 offset:18464
	ds_read_b128 v[150:153], v170 offset:64
	s_waitcnt lgkmcnt(12)
	v_mfma_f32_32x32x16_bf16 v[18:33], v[144:147], v[160:163], v[18:33]
	ds_read_b128 v[146:149], v170 offset:32
	ds_read_b128 v[142:145], v169 offset:18496
	v_mfma_f32_32x32x16_bf16 v[2:17], v[156:159], v[160:163], v[2:17]
	ds_read_b128 v[154:157], v169 offset:23104
	ds_read_b128 v[158:161], v170 offset:4672
	s_waitcnt lgkmcnt(3)
	v_mfma_f32_32x32x16_bf16 v[50:65], v[138:141], v[146:149], v[50:65]
	v_mfma_f32_32x32x16_bf16 v[34:49], v[130:133], v[146:149], v[34:49]
	ds_read_b128 v[146:149], v170 offset:4704
	v_mfma_f32_32x32x16_bf16 v[18:33], v[138:141], v[134:137], v[18:33]
	ds_read_b128 v[138:141], v169 offset:23136
	v_mfma_f32_32x32x16_bf16 v[2:17], v[130:133], v[134:137], v[2:17]
	ds_read_b128 v[130:133], v169 offset:18528
	ds_read_b128 v[134:137], v170 offset:96
	s_waitcnt lgkmcnt(0)
	s_barrier
	v_mfma_f32_32x32x16_bf16 v[50:65], v[142:145], v[150:153], v[50:65]
	v_mfma_f32_32x32x16_bf16 v[34:49], v[154:157], v[150:153], v[34:49]
	ds_read_b128 v[150:153], v173 offset:36864
	v_mfma_f32_32x32x16_bf16 v[18:33], v[142:145], v[158:161], v[18:33]
	ds_read_b128 v[142:145], v172 offset:55296
	v_mfma_f32_32x32x16_bf16 v[2:17], v[154:157], v[158:161], v[2:17]
	ds_read_b128 v[154:157], v172 offset:59904
	ds_read_b128 v[158:161], v173 offset:41472
	v_mfma_f32_32x32x16_bf16 v[50:65], v[130:133], v[134:137], v[50:65]
	s_waitcnt vmcnt(4)
	ds_write_b128 v105, v[94:97]
	ds_write_b128 v105, v[90:93] offset:18432
	v_lshl_add_u64 v[94:95], v[126:127], 0, s[6:7]
	global_load_dwordx4 v[90:93], v[128:129], off
	s_mov_b64 s[6:7], 0x20000
	v_mfma_f32_32x32x16_bf16 v[34:49], v[138:141], v[134:137], v[34:49]
	ds_write_b128 v109, v[86:89]
	ds_write_b128 v109, v[82:85] offset:18432
	v_lshl_add_u64 v[86:87], v[94:95], 0, v[116:117]
	global_load_dwordx4 v[86:89], v[86:87], off
	v_mfma_f32_32x32x16_bf16 v[18:33], v[130:133], v[146:149], v[18:33]
	v_add_co_u32_e32 v130, vcc, s5, v124
	s_mov_b32 s5, 0x1e000
	s_nop 0
	v_addc_co_u32_e32 v131, vcc, 0, v125, vcc
	s_waitcnt vmcnt(5)
	ds_write_b128 v111, v[74:77] offset:18432
	v_add_co_u32_e32 v74, vcc, s5, v124
	s_mov_b32 s5, 0x1d000
	s_nop 0
	v_addc_co_u32_e32 v75, vcc, 0, v125, vcc
	v_add_co_u32_e32 v82, vcc, s5, v124
	s_waitcnt vmcnt(3)
	ds_write_b128 v111, v[78:81]
	v_mfma_f32_32x32x16_bf16 v[2:17], v[138:141], v[146:149], v[2:17]
	ds_write_b128 v167, v[70:73]
	v_lshl_add_u64 v[70:71], v[94:95], 0, v[120:121]
	v_lshl_add_u64 v[78:79], v[94:95], 0, v[118:119]
	v_addc_co_u32_e32 v83, vcc, 0, v125, vcc
	v_lshl_add_u64 v[94:95], v[94:95], 0, v[114:115]
	global_load_dwordx4 v[74:77], v[74:75], off
	s_waitcnt vmcnt(3)
	ds_write_b128 v167, v[66:69] offset:18432
	global_load_dwordx4 v[82:85], v[82:83], off
	s_waitcnt lgkmcnt(10)
	v_mfma_f32_32x32x16_bf16 v[50:65], v[142:145], v[150:153], v[50:65]
	global_load_dwordx4 v[94:97], v[94:95], off
	ds_read_b128 v[132:135], v169 offset:59936
	global_load_dwordx4 v[70:73], v[70:71], off
	ds_read_b128 v[136:139], v170 offset:41504
	global_load_dwordx4 v[78:81], v[78:79], off
	s_mov_b32 s5, 0x24000
	global_load_dwordx4 v[66:69], v[130:131], off offset:-4096
	s_waitcnt lgkmcnt(11)
	v_mfma_f32_32x32x16_bf16 v[34:49], v[154:157], v[150:153], v[34:49]
	ds_read_b128 v[148:151], v170 offset:36896
	v_add_co_u32_e32 v128, vcc, s5, v124
	s_mov_b32 s5, 0x22000
	s_nop 0
	v_addc_co_u32_e32 v129, vcc, 0, v125, vcc
	s_waitcnt lgkmcnt(11)
	v_mfma_f32_32x32x16_bf16 v[18:33], v[142:145], v[158:161], v[18:33]
	ds_read_b128 v[140:143], v169 offset:55328
	ds_read_b128 v[144:147], v169 offset:55360
	v_mfma_f32_32x32x16_bf16 v[2:17], v[154:157], v[158:161], v[2:17]
	ds_read_b128 v[156:159], v169 offset:59968
	ds_read_b128 v[152:155], v170 offset:36928
	s_waitcnt lgkmcnt(3)
	v_mfma_f32_32x32x16_bf16 v[50:65], v[140:143], v[148:151], v[50:65]
	ds_read_b128 v[160:163], v170 offset:41536
	v_mfma_f32_32x32x16_bf16 v[34:49], v[132:135], v[148:151], v[34:49]
	ds_read_b128 v[148:151], v170 offset:41568
	v_mfma_f32_32x32x16_bf16 v[18:33], v[140:143], v[136:139], v[18:33]
	ds_read_b128 v[140:143], v169 offset:60000
	v_mfma_f32_32x32x16_bf16 v[2:17], v[132:135], v[136:139], v[2:17]
	ds_read_b128 v[132:135], v169 offset:55392
	ds_read_b128 v[136:139], v170 offset:36960
	s_waitcnt lgkmcnt(0)
	s_barrier
	v_mfma_f32_32x32x16_bf16 v[50:65], v[144:147], v[152:155], v[50:65]
	v_mfma_f32_32x32x16_bf16 v[34:49], v[156:159], v[152:155], v[34:49]
	ds_read_b128 v[152:155], v173
	v_mfma_f32_32x32x16_bf16 v[18:33], v[144:147], v[160:163], v[18:33]
	ds_read_b128 v[144:147], v172 offset:18432
	v_mfma_f32_32x32x16_bf16 v[2:17], v[156:159], v[160:163], v[2:17]
	ds_read_b128 v[156:159], v172 offset:23040
	ds_read_b128 v[160:163], v173 offset:4608
	v_mfma_f32_32x32x16_bf16 v[50:65], v[132:135], v[136:139], v[50:65]
	s_waitcnt vmcnt(3)
	ds_write_b128 v105, v[94:97] offset:36864
	ds_write_b128 v105, v[90:93] offset:55296
	v_lshl_add_u64 v[94:95], v[126:127], 0, s[6:7]
	global_load_dwordx4 v[90:93], v[130:131], off
	s_mov_b64 s[6:7], 0x24000
	v_mfma_f32_32x32x16_bf16 v[34:49], v[140:143], v[136:139], v[34:49]
	ds_write_b128 v109, v[86:89] offset:36864
	ds_write_b128 v109, v[82:85] offset:55296
	v_lshl_add_u64 v[86:87], v[94:95], 0, v[116:117]
	global_load_dwordx4 v[86:89], v[86:87], off
	v_mfma_f32_32x32x16_bf16 v[18:33], v[132:135], v[148:151], v[18:33]
	ds_write_b128 v111, v[74:77] offset:55296
	v_add_co_u32_e32 v74, vcc, s5, v124
	s_mov_b32 s5, 0x21000
	s_nop 0
	v_addc_co_u32_e32 v75, vcc, 0, v125, vcc
	v_add_co_u32_e32 v82, vcc, s5, v124
	s_waitcnt vmcnt(3)
	ds_write_b128 v111, v[78:81] offset:36864
	v_mfma_f32_32x32x16_bf16 v[2:17], v[140:143], v[148:151], v[2:17]
	ds_write_b128 v167, v[70:73] offset:36864
	v_lshl_add_u64 v[70:71], v[94:95], 0, v[120:121]
	v_lshl_add_u64 v[78:79], v[94:95], 0, v[118:119]
	v_addc_co_u32_e32 v83, vcc, 0, v125, vcc
	v_lshl_add_u64 v[94:95], v[94:95], 0, v[114:115]
	global_load_dwordx4 v[82:85], v[82:83], off
	s_waitcnt vmcnt(3)
	ds_write_b128 v167, v[66:69] offset:55296
	global_load_dwordx4 v[94:97], v[94:95], off
	s_waitcnt lgkmcnt(10)
	v_mfma_f32_32x32x16_bf16 v[50:65], v[144:147], v[152:155], v[50:65]
	global_load_dwordx4 v[74:77], v[74:75], off
	ds_read_b128 v[130:133], v169 offset:23072
	global_load_dwordx4 v[70:73], v[70:71], off
	ds_read_b128 v[134:137], v170 offset:4640
	global_load_dwordx4 v[78:81], v[78:79], off
	s_mov_b32 s5, 0x28000
	global_load_dwordx4 v[66:69], v[128:129], off offset:-4096
	s_waitcnt lgkmcnt(11)
	v_mfma_f32_32x32x16_bf16 v[34:49], v[156:159], v[152:155], v[34:49]
	ds_read_b128 v[138:141], v169 offset:18464
	ds_read_b128 v[150:153], v170 offset:64
	s_waitcnt lgkmcnt(12)
	v_mfma_f32_32x32x16_bf16 v[18:33], v[144:147], v[160:163], v[18:33]
	ds_read_b128 v[146:149], v170 offset:32
	ds_read_b128 v[142:145], v169 offset:18496
	v_mfma_f32_32x32x16_bf16 v[2:17], v[156:159], v[160:163], v[2:17]
	ds_read_b128 v[154:157], v169 offset:23104
	ds_read_b128 v[158:161], v170 offset:4672
	s_waitcnt lgkmcnt(3)
	v_mfma_f32_32x32x16_bf16 v[50:65], v[138:141], v[146:149], v[50:65]
	v_mfma_f32_32x32x16_bf16 v[34:49], v[130:133], v[146:149], v[34:49]
	ds_read_b128 v[146:149], v170 offset:4704
	v_mfma_f32_32x32x16_bf16 v[18:33], v[138:141], v[134:137], v[18:33]
	ds_read_b128 v[138:141], v169 offset:23136
	v_mfma_f32_32x32x16_bf16 v[2:17], v[130:133], v[134:137], v[2:17]
	ds_read_b128 v[130:133], v169 offset:18528
	ds_read_b128 v[134:137], v170 offset:96
	s_waitcnt lgkmcnt(0)
	s_barrier
	v_mfma_f32_32x32x16_bf16 v[50:65], v[142:145], v[150:153], v[50:65]
	v_mfma_f32_32x32x16_bf16 v[34:49], v[154:157], v[150:153], v[34:49]
	ds_read_b128 v[150:153], v173 offset:36864
	v_mfma_f32_32x32x16_bf16 v[18:33], v[142:145], v[158:161], v[18:33]
	ds_read_b128 v[142:145], v172 offset:55296
	v_mfma_f32_32x32x16_bf16 v[2:17], v[154:157], v[158:161], v[2:17]
	ds_read_b128 v[154:157], v172 offset:59904
	ds_read_b128 v[158:161], v173 offset:41472
	v_mfma_f32_32x32x16_bf16 v[50:65], v[130:133], v[134:137], v[50:65]
	s_waitcnt vmcnt(4)
	ds_write_b128 v105, v[94:97]
	ds_write_b128 v105, v[90:93] offset:18432
	v_lshl_add_u64 v[94:95], v[126:127], 0, s[6:7]
	global_load_dwordx4 v[90:93], v[128:129], off
	s_mov_b64 s[6:7], 0x28000
	v_mfma_f32_32x32x16_bf16 v[34:49], v[138:141], v[134:137], v[34:49]
	ds_write_b128 v109, v[86:89]
	ds_write_b128 v109, v[82:85] offset:18432
	v_lshl_add_u64 v[86:87], v[94:95], 0, v[116:117]
	global_load_dwordx4 v[86:89], v[86:87], off
	v_mfma_f32_32x32x16_bf16 v[18:33], v[130:133], v[146:149], v[18:33]
	v_add_co_u32_e32 v130, vcc, s5, v124
	s_mov_b32 s5, 0x26000
	s_nop 0
	v_addc_co_u32_e32 v131, vcc, 0, v125, vcc
	s_waitcnt vmcnt(5)
	ds_write_b128 v111, v[74:77] offset:18432
	v_add_co_u32_e32 v74, vcc, s5, v124
	s_mov_b32 s5, 0x25000
	s_nop 0
	v_addc_co_u32_e32 v75, vcc, 0, v125, vcc
	v_add_co_u32_e32 v82, vcc, s5, v124
	s_waitcnt vmcnt(3)
	ds_write_b128 v111, v[78:81]
	v_mfma_f32_32x32x16_bf16 v[2:17], v[138:141], v[146:149], v[2:17]
	ds_write_b128 v167, v[70:73]
	v_lshl_add_u64 v[70:71], v[94:95], 0, v[120:121]
	v_lshl_add_u64 v[78:79], v[94:95], 0, v[118:119]
	v_addc_co_u32_e32 v83, vcc, 0, v125, vcc
	v_lshl_add_u64 v[94:95], v[94:95], 0, v[114:115]
	global_load_dwordx4 v[74:77], v[74:75], off
	s_waitcnt vmcnt(3)
	ds_write_b128 v167, v[66:69] offset:18432
	global_load_dwordx4 v[82:85], v[82:83], off
	s_waitcnt lgkmcnt(10)
	v_mfma_f32_32x32x16_bf16 v[50:65], v[142:145], v[150:153], v[50:65]
	global_load_dwordx4 v[94:97], v[94:95], off
	ds_read_b128 v[132:135], v169 offset:59936
	global_load_dwordx4 v[70:73], v[70:71], off
	ds_read_b128 v[136:139], v170 offset:41504
	global_load_dwordx4 v[78:81], v[78:79], off
	s_mov_b32 s5, 0x2c000
	global_load_dwordx4 v[66:69], v[130:131], off offset:-4096
	s_waitcnt lgkmcnt(11)
	v_mfma_f32_32x32x16_bf16 v[34:49], v[154:157], v[150:153], v[34:49]
	ds_read_b128 v[148:151], v170 offset:36896
	v_add_co_u32_e32 v128, vcc, s5, v124
	s_mov_b32 s5, 0x2a000
	s_nop 0
	v_addc_co_u32_e32 v129, vcc, 0, v125, vcc
	s_waitcnt lgkmcnt(11)
	v_mfma_f32_32x32x16_bf16 v[18:33], v[142:145], v[158:161], v[18:33]
	ds_read_b128 v[140:143], v169 offset:55328
	ds_read_b128 v[144:147], v169 offset:55360
	v_mfma_f32_32x32x16_bf16 v[2:17], v[154:157], v[158:161], v[2:17]
	ds_read_b128 v[156:159], v169 offset:59968
	ds_read_b128 v[152:155], v170 offset:36928
	s_waitcnt lgkmcnt(3)
	v_mfma_f32_32x32x16_bf16 v[50:65], v[140:143], v[148:151], v[50:65]
	ds_read_b128 v[160:163], v170 offset:41536
	v_mfma_f32_32x32x16_bf16 v[34:49], v[132:135], v[148:151], v[34:49]
	ds_read_b128 v[148:151], v170 offset:41568
	v_mfma_f32_32x32x16_bf16 v[18:33], v[140:143], v[136:139], v[18:33]
	ds_read_b128 v[140:143], v169 offset:60000
	v_mfma_f32_32x32x16_bf16 v[2:17], v[132:135], v[136:139], v[2:17]
	ds_read_b128 v[132:135], v169 offset:55392
	ds_read_b128 v[136:139], v170 offset:36960
	s_waitcnt lgkmcnt(0)
	s_barrier
	v_mfma_f32_32x32x16_bf16 v[50:65], v[144:147], v[152:155], v[50:65]
	v_mfma_f32_32x32x16_bf16 v[34:49], v[156:159], v[152:155], v[34:49]
	ds_read_b128 v[152:155], v173
	v_mfma_f32_32x32x16_bf16 v[18:33], v[144:147], v[160:163], v[18:33]
	ds_read_b128 v[144:147], v172 offset:18432
	v_mfma_f32_32x32x16_bf16 v[2:17], v[156:159], v[160:163], v[2:17]
	ds_read_b128 v[156:159], v172 offset:23040
	ds_read_b128 v[160:163], v173 offset:4608
	v_mfma_f32_32x32x16_bf16 v[50:65], v[132:135], v[136:139], v[50:65]
	s_waitcnt vmcnt(3)
	ds_write_b128 v105, v[94:97] offset:36864
	ds_write_b128 v105, v[90:93] offset:55296
	v_lshl_add_u64 v[94:95], v[126:127], 0, s[6:7]
	global_load_dwordx4 v[90:93], v[130:131], off
	s_mov_b64 s[6:7], 0x2c000
	v_mfma_f32_32x32x16_bf16 v[34:49], v[140:143], v[136:139], v[34:49]
	ds_write_b128 v109, v[86:89] offset:36864
	ds_write_b128 v109, v[82:85] offset:55296
	v_lshl_add_u64 v[86:87], v[94:95], 0, v[116:117]
	global_load_dwordx4 v[86:89], v[86:87], off
	v_mfma_f32_32x32x16_bf16 v[18:33], v[132:135], v[148:151], v[18:33]
	ds_write_b128 v111, v[74:77] offset:55296
	v_add_co_u32_e32 v74, vcc, s5, v124
	s_mov_b32 s5, 0x29000
	s_nop 0
	v_addc_co_u32_e32 v75, vcc, 0, v125, vcc
	v_add_co_u32_e32 v82, vcc, s5, v124
	s_waitcnt vmcnt(3)
	ds_write_b128 v111, v[78:81] offset:36864
	v_mfma_f32_32x32x16_bf16 v[2:17], v[140:143], v[148:151], v[2:17]
	ds_write_b128 v167, v[70:73] offset:36864
	v_lshl_add_u64 v[70:71], v[94:95], 0, v[120:121]
	v_lshl_add_u64 v[78:79], v[94:95], 0, v[118:119]
	v_addc_co_u32_e32 v83, vcc, 0, v125, vcc
	v_lshl_add_u64 v[94:95], v[94:95], 0, v[114:115]
	global_load_dwordx4 v[82:85], v[82:83], off
	s_waitcnt vmcnt(3)
	ds_write_b128 v167, v[66:69] offset:55296
	global_load_dwordx4 v[94:97], v[94:95], off
	s_waitcnt lgkmcnt(10)
	v_mfma_f32_32x32x16_bf16 v[50:65], v[144:147], v[152:155], v[50:65]
	global_load_dwordx4 v[74:77], v[74:75], off
	ds_read_b128 v[130:133], v169 offset:23072
	global_load_dwordx4 v[70:73], v[70:71], off
	ds_read_b128 v[134:137], v170 offset:4640
	global_load_dwordx4 v[78:81], v[78:79], off
	s_mov_b32 s5, 0x30000
	global_load_dwordx4 v[66:69], v[128:129], off offset:-4096
	s_waitcnt lgkmcnt(11)
	v_mfma_f32_32x32x16_bf16 v[34:49], v[156:159], v[152:155], v[34:49]
	ds_read_b128 v[138:141], v169 offset:18464
	ds_read_b128 v[150:153], v170 offset:64
	s_waitcnt lgkmcnt(12)
	v_mfma_f32_32x32x16_bf16 v[18:33], v[144:147], v[160:163], v[18:33]
	ds_read_b128 v[146:149], v170 offset:32
	ds_read_b128 v[142:145], v169 offset:18496
	v_mfma_f32_32x32x16_bf16 v[2:17], v[156:159], v[160:163], v[2:17]
	ds_read_b128 v[154:157], v169 offset:23104
	ds_read_b128 v[158:161], v170 offset:4672
	s_waitcnt lgkmcnt(3)
	v_mfma_f32_32x32x16_bf16 v[50:65], v[138:141], v[146:149], v[50:65]
	v_mfma_f32_32x32x16_bf16 v[34:49], v[130:133], v[146:149], v[34:49]
	ds_read_b128 v[146:149], v170 offset:4704
	v_mfma_f32_32x32x16_bf16 v[18:33], v[138:141], v[134:137], v[18:33]
	ds_read_b128 v[138:141], v169 offset:23136
	v_mfma_f32_32x32x16_bf16 v[2:17], v[130:133], v[134:137], v[2:17]
	ds_read_b128 v[130:133], v169 offset:18528
	ds_read_b128 v[134:137], v170 offset:96
	s_waitcnt lgkmcnt(0)
	s_barrier
	v_mfma_f32_32x32x16_bf16 v[50:65], v[142:145], v[150:153], v[50:65]
	v_mfma_f32_32x32x16_bf16 v[34:49], v[154:157], v[150:153], v[34:49]
	ds_read_b128 v[150:153], v173 offset:36864
	v_mfma_f32_32x32x16_bf16 v[18:33], v[142:145], v[158:161], v[18:33]
	ds_read_b128 v[142:145], v172 offset:55296
	v_mfma_f32_32x32x16_bf16 v[2:17], v[154:157], v[158:161], v[2:17]
	ds_read_b128 v[154:157], v172 offset:59904
	ds_read_b128 v[158:161], v173 offset:41472
	v_mfma_f32_32x32x16_bf16 v[50:65], v[130:133], v[134:137], v[50:65]
	s_waitcnt vmcnt(4)
	ds_write_b128 v105, v[94:97]
	ds_write_b128 v105, v[90:93] offset:18432
	v_lshl_add_u64 v[94:95], v[126:127], 0, s[6:7]
	global_load_dwordx4 v[90:93], v[128:129], off
	s_mov_b64 s[6:7], 0x30000
	v_mfma_f32_32x32x16_bf16 v[34:49], v[138:141], v[134:137], v[34:49]
	ds_write_b128 v109, v[86:89]
	ds_write_b128 v109, v[82:85] offset:18432
	v_lshl_add_u64 v[86:87], v[94:95], 0, v[116:117]
	global_load_dwordx4 v[86:89], v[86:87], off
	v_mfma_f32_32x32x16_bf16 v[18:33], v[130:133], v[146:149], v[18:33]
	v_add_co_u32_e32 v130, vcc, s5, v124
	s_mov_b32 s5, 0x2e000
	s_nop 0
	v_addc_co_u32_e32 v131, vcc, 0, v125, vcc
	s_waitcnt vmcnt(5)
	ds_write_b128 v111, v[74:77] offset:18432
	v_add_co_u32_e32 v74, vcc, s5, v124
	s_mov_b32 s5, 0x2d000
	s_nop 0
	v_addc_co_u32_e32 v75, vcc, 0, v125, vcc
	v_add_co_u32_e32 v82, vcc, s5, v124
	s_waitcnt vmcnt(3)
	ds_write_b128 v111, v[78:81]
	v_mfma_f32_32x32x16_bf16 v[2:17], v[138:141], v[146:149], v[2:17]
	ds_write_b128 v167, v[70:73]
	v_lshl_add_u64 v[70:71], v[94:95], 0, v[120:121]
	v_lshl_add_u64 v[78:79], v[94:95], 0, v[118:119]
	v_addc_co_u32_e32 v83, vcc, 0, v125, vcc
	v_lshl_add_u64 v[94:95], v[94:95], 0, v[114:115]
	global_load_dwordx4 v[74:77], v[74:75], off
	s_waitcnt vmcnt(3)
	ds_write_b128 v167, v[66:69] offset:18432
	global_load_dwordx4 v[82:85], v[82:83], off
	s_waitcnt lgkmcnt(10)
	v_mfma_f32_32x32x16_bf16 v[50:65], v[142:145], v[150:153], v[50:65]
	global_load_dwordx4 v[94:97], v[94:95], off
	ds_read_b128 v[132:135], v169 offset:59936
	global_load_dwordx4 v[70:73], v[70:71], off
	ds_read_b128 v[136:139], v170 offset:41504
	global_load_dwordx4 v[78:81], v[78:79], off
	s_mov_b32 s5, 0x34000
	global_load_dwordx4 v[66:69], v[130:131], off offset:-4096
	s_waitcnt lgkmcnt(11)
	v_mfma_f32_32x32x16_bf16 v[34:49], v[154:157], v[150:153], v[34:49]
	ds_read_b128 v[148:151], v170 offset:36896
	v_add_co_u32_e32 v128, vcc, s5, v124
	s_mov_b32 s5, 0x32000
	s_nop 0
	v_addc_co_u32_e32 v129, vcc, 0, v125, vcc
	s_waitcnt lgkmcnt(11)
	v_mfma_f32_32x32x16_bf16 v[18:33], v[142:145], v[158:161], v[18:33]
	ds_read_b128 v[140:143], v169 offset:55328
	ds_read_b128 v[144:147], v169 offset:55360
	v_mfma_f32_32x32x16_bf16 v[2:17], v[154:157], v[158:161], v[2:17]
	ds_read_b128 v[156:159], v169 offset:59968
	ds_read_b128 v[152:155], v170 offset:36928
	s_waitcnt lgkmcnt(3)
	v_mfma_f32_32x32x16_bf16 v[50:65], v[140:143], v[148:151], v[50:65]
	ds_read_b128 v[160:163], v170 offset:41536
	v_mfma_f32_32x32x16_bf16 v[34:49], v[132:135], v[148:151], v[34:49]
	ds_read_b128 v[148:151], v170 offset:41568
	v_mfma_f32_32x32x16_bf16 v[18:33], v[140:143], v[136:139], v[18:33]
	ds_read_b128 v[140:143], v169 offset:60000
	v_mfma_f32_32x32x16_bf16 v[2:17], v[132:135], v[136:139], v[2:17]
	ds_read_b128 v[132:135], v169 offset:55392
	ds_read_b128 v[136:139], v170 offset:36960
	s_waitcnt lgkmcnt(0)
	s_barrier
	v_mfma_f32_32x32x16_bf16 v[50:65], v[144:147], v[152:155], v[50:65]
	v_mfma_f32_32x32x16_bf16 v[34:49], v[156:159], v[152:155], v[34:49]
	ds_read_b128 v[152:155], v173
	v_mfma_f32_32x32x16_bf16 v[18:33], v[144:147], v[160:163], v[18:33]
	ds_read_b128 v[144:147], v172 offset:18432
	v_mfma_f32_32x32x16_bf16 v[2:17], v[156:159], v[160:163], v[2:17]
	ds_read_b128 v[156:159], v172 offset:23040
	ds_read_b128 v[160:163], v173 offset:4608
	v_mfma_f32_32x32x16_bf16 v[50:65], v[132:135], v[136:139], v[50:65]
	s_waitcnt vmcnt(3)
	ds_write_b128 v105, v[94:97] offset:36864
	ds_write_b128 v105, v[90:93] offset:55296
	v_lshl_add_u64 v[94:95], v[126:127], 0, s[6:7]
	global_load_dwordx4 v[90:93], v[130:131], off
	s_mov_b64 s[6:7], 0x34000
	v_mfma_f32_32x32x16_bf16 v[34:49], v[140:143], v[136:139], v[34:49]
	ds_write_b128 v109, v[86:89] offset:36864
	ds_write_b128 v109, v[82:85] offset:55296
	v_lshl_add_u64 v[86:87], v[94:95], 0, v[116:117]
	global_load_dwordx4 v[86:89], v[86:87], off
	v_mfma_f32_32x32x16_bf16 v[18:33], v[132:135], v[148:151], v[18:33]
	ds_write_b128 v111, v[74:77] offset:55296
	v_add_co_u32_e32 v74, vcc, s5, v124
	s_mov_b32 s5, 0x31000
	s_nop 0
	v_addc_co_u32_e32 v75, vcc, 0, v125, vcc
	v_add_co_u32_e32 v82, vcc, s5, v124
	s_waitcnt vmcnt(3)
	ds_write_b128 v111, v[78:81] offset:36864
	v_mfma_f32_32x32x16_bf16 v[2:17], v[140:143], v[148:151], v[2:17]
	ds_write_b128 v167, v[70:73] offset:36864
	v_lshl_add_u64 v[70:71], v[94:95], 0, v[120:121]
	v_lshl_add_u64 v[78:79], v[94:95], 0, v[118:119]
	v_addc_co_u32_e32 v83, vcc, 0, v125, vcc
	v_lshl_add_u64 v[94:95], v[94:95], 0, v[114:115]
	global_load_dwordx4 v[82:85], v[82:83], off
	s_waitcnt vmcnt(3)
	ds_write_b128 v167, v[66:69] offset:55296
	global_load_dwordx4 v[94:97], v[94:95], off
	s_waitcnt lgkmcnt(10)
	v_mfma_f32_32x32x16_bf16 v[50:65], v[144:147], v[152:155], v[50:65]
	global_load_dwordx4 v[74:77], v[74:75], off
	ds_read_b128 v[130:133], v169 offset:23072
	global_load_dwordx4 v[70:73], v[70:71], off
	ds_read_b128 v[134:137], v170 offset:4640
	global_load_dwordx4 v[78:81], v[78:79], off
	s_mov_b32 s5, 0x38000
	global_load_dwordx4 v[66:69], v[128:129], off offset:-4096
	s_waitcnt lgkmcnt(11)
	v_mfma_f32_32x32x16_bf16 v[34:49], v[156:159], v[152:155], v[34:49]
	ds_read_b128 v[138:141], v169 offset:18464
	ds_read_b128 v[150:153], v170 offset:64
	s_waitcnt lgkmcnt(12)
	v_mfma_f32_32x32x16_bf16 v[18:33], v[144:147], v[160:163], v[18:33]
	ds_read_b128 v[146:149], v170 offset:32
	ds_read_b128 v[142:145], v169 offset:18496
	v_mfma_f32_32x32x16_bf16 v[2:17], v[156:159], v[160:163], v[2:17]
	ds_read_b128 v[154:157], v169 offset:23104
	ds_read_b128 v[158:161], v170 offset:4672
	s_waitcnt lgkmcnt(3)
	v_mfma_f32_32x32x16_bf16 v[50:65], v[138:141], v[146:149], v[50:65]
	v_mfma_f32_32x32x16_bf16 v[34:49], v[130:133], v[146:149], v[34:49]
	ds_read_b128 v[146:149], v170 offset:4704
	v_mfma_f32_32x32x16_bf16 v[18:33], v[138:141], v[134:137], v[18:33]
	ds_read_b128 v[138:141], v169 offset:23136
	v_mfma_f32_32x32x16_bf16 v[2:17], v[130:133], v[134:137], v[2:17]
	ds_read_b128 v[130:133], v169 offset:18528
	ds_read_b128 v[134:137], v170 offset:96
	s_waitcnt lgkmcnt(0)
	s_barrier
	v_mfma_f32_32x32x16_bf16 v[50:65], v[142:145], v[150:153], v[50:65]
	v_mfma_f32_32x32x16_bf16 v[34:49], v[154:157], v[150:153], v[34:49]
	ds_read_b128 v[150:153], v173 offset:36864
	v_mfma_f32_32x32x16_bf16 v[18:33], v[142:145], v[158:161], v[18:33]
	ds_read_b128 v[142:145], v172 offset:55296
	v_mfma_f32_32x32x16_bf16 v[2:17], v[154:157], v[158:161], v[2:17]
	ds_read_b128 v[154:157], v172 offset:59904
	ds_read_b128 v[158:161], v173 offset:41472
	v_mfma_f32_32x32x16_bf16 v[50:65], v[130:133], v[134:137], v[50:65]
	s_waitcnt vmcnt(4)
	ds_write_b128 v105, v[94:97]
	ds_write_b128 v105, v[90:93] offset:18432
	v_lshl_add_u64 v[94:95], v[126:127], 0, s[6:7]
	global_load_dwordx4 v[90:93], v[128:129], off
	s_mov_b64 s[6:7], 0x38000
	v_mfma_f32_32x32x16_bf16 v[34:49], v[138:141], v[134:137], v[34:49]
	ds_write_b128 v109, v[86:89]
	ds_write_b128 v109, v[82:85] offset:18432
	v_lshl_add_u64 v[86:87], v[94:95], 0, v[116:117]
	global_load_dwordx4 v[86:89], v[86:87], off
	v_mfma_f32_32x32x16_bf16 v[18:33], v[130:133], v[146:149], v[18:33]
	v_add_co_u32_e32 v130, vcc, s5, v124
	s_mov_b32 s5, 0x36000
	s_nop 0
	v_addc_co_u32_e32 v131, vcc, 0, v125, vcc
	s_waitcnt vmcnt(5)
	ds_write_b128 v111, v[74:77] offset:18432
	v_add_co_u32_e32 v74, vcc, s5, v124
	s_mov_b32 s5, 0x35000
	s_nop 0
	v_addc_co_u32_e32 v75, vcc, 0, v125, vcc
	v_add_co_u32_e32 v82, vcc, s5, v124
	s_waitcnt vmcnt(3)
	ds_write_b128 v111, v[78:81]
	v_mfma_f32_32x32x16_bf16 v[2:17], v[138:141], v[146:149], v[2:17]
	ds_write_b128 v167, v[70:73]
	v_lshl_add_u64 v[70:71], v[94:95], 0, v[120:121]
	v_lshl_add_u64 v[78:79], v[94:95], 0, v[118:119]
	v_addc_co_u32_e32 v83, vcc, 0, v125, vcc
	v_lshl_add_u64 v[94:95], v[94:95], 0, v[114:115]
	global_load_dwordx4 v[74:77], v[74:75], off
	s_waitcnt vmcnt(3)
	ds_write_b128 v167, v[66:69] offset:18432
	global_load_dwordx4 v[82:85], v[82:83], off
	s_waitcnt lgkmcnt(10)
	v_mfma_f32_32x32x16_bf16 v[50:65], v[142:145], v[150:153], v[50:65]
	global_load_dwordx4 v[94:97], v[94:95], off
	ds_read_b128 v[132:135], v169 offset:59936
	global_load_dwordx4 v[70:73], v[70:71], off
	ds_read_b128 v[136:139], v170 offset:41504
	global_load_dwordx4 v[78:81], v[78:79], off
	s_mov_b32 s5, 0x3c000
	global_load_dwordx4 v[66:69], v[130:131], off offset:-4096
	s_waitcnt lgkmcnt(11)
	v_mfma_f32_32x32x16_bf16 v[34:49], v[154:157], v[150:153], v[34:49]
	ds_read_b128 v[148:151], v170 offset:36896
	v_add_co_u32_e32 v128, vcc, s5, v124
	s_mov_b32 s5, 0x3a000
	s_nop 0
	v_addc_co_u32_e32 v129, vcc, 0, v125, vcc
	s_waitcnt lgkmcnt(11)
	v_mfma_f32_32x32x16_bf16 v[18:33], v[142:145], v[158:161], v[18:33]
	ds_read_b128 v[140:143], v169 offset:55328
	ds_read_b128 v[144:147], v169 offset:55360
	v_mfma_f32_32x32x16_bf16 v[2:17], v[154:157], v[158:161], v[2:17]
	ds_read_b128 v[156:159], v169 offset:59968
	ds_read_b128 v[152:155], v170 offset:36928
	s_waitcnt lgkmcnt(3)
	v_mfma_f32_32x32x16_bf16 v[50:65], v[140:143], v[148:151], v[50:65]
	ds_read_b128 v[160:163], v170 offset:41536
	v_mfma_f32_32x32x16_bf16 v[34:49], v[132:135], v[148:151], v[34:49]
	ds_read_b128 v[148:151], v170 offset:41568
	v_mfma_f32_32x32x16_bf16 v[18:33], v[140:143], v[136:139], v[18:33]
	ds_read_b128 v[140:143], v169 offset:60000
	v_mfma_f32_32x32x16_bf16 v[2:17], v[132:135], v[136:139], v[2:17]
	ds_read_b128 v[132:135], v169 offset:55392
	ds_read_b128 v[136:139], v170 offset:36960
	s_waitcnt lgkmcnt(0)
	s_barrier
	v_mfma_f32_32x32x16_bf16 v[50:65], v[144:147], v[152:155], v[50:65]
	v_mfma_f32_32x32x16_bf16 v[34:49], v[156:159], v[152:155], v[34:49]
	ds_read_b128 v[152:155], v173
	v_mfma_f32_32x32x16_bf16 v[18:33], v[144:147], v[160:163], v[18:33]
	ds_read_b128 v[144:147], v172 offset:18432
	v_mfma_f32_32x32x16_bf16 v[2:17], v[156:159], v[160:163], v[2:17]
	ds_read_b128 v[156:159], v172 offset:23040
	ds_read_b128 v[160:163], v173 offset:4608
	v_mfma_f32_32x32x16_bf16 v[50:65], v[132:135], v[136:139], v[50:65]
	s_waitcnt vmcnt(3)
	ds_write_b128 v105, v[94:97] offset:36864
	ds_write_b128 v105, v[90:93] offset:55296
	v_lshl_add_u64 v[94:95], v[126:127], 0, s[6:7]
	global_load_dwordx4 v[90:93], v[130:131], off
	s_mov_b64 s[6:7], 0x3c000
	v_mfma_f32_32x32x16_bf16 v[34:49], v[140:143], v[136:139], v[34:49]
	ds_write_b128 v109, v[86:89] offset:36864
	ds_write_b128 v109, v[82:85] offset:55296
	v_lshl_add_u64 v[86:87], v[94:95], 0, v[116:117]
	global_load_dwordx4 v[86:89], v[86:87], off
	v_mfma_f32_32x32x16_bf16 v[18:33], v[132:135], v[148:151], v[18:33]
	ds_write_b128 v111, v[74:77] offset:55296
	v_add_co_u32_e32 v74, vcc, s5, v124
	s_mov_b32 s5, 0x39000
	s_nop 0
	v_addc_co_u32_e32 v75, vcc, 0, v125, vcc
	v_add_co_u32_e32 v82, vcc, s5, v124
	s_waitcnt vmcnt(3)
	ds_write_b128 v111, v[78:81] offset:36864
	v_mfma_f32_32x32x16_bf16 v[2:17], v[140:143], v[148:151], v[2:17]
	ds_write_b128 v167, v[70:73] offset:36864
	v_lshl_add_u64 v[70:71], v[94:95], 0, v[120:121]
	v_lshl_add_u64 v[78:79], v[94:95], 0, v[118:119]
	v_addc_co_u32_e32 v83, vcc, 0, v125, vcc
	v_lshl_add_u64 v[94:95], v[94:95], 0, v[114:115]
	s_waitcnt vmcnt(2)
	ds_write_b128 v167, v[66:69] offset:55296
	global_load_dwordx4 v[66:69], v[128:129], off offset:-4096
	s_waitcnt lgkmcnt(10)
	v_mfma_f32_32x32x16_bf16 v[50:65], v[144:147], v[152:155], v[50:65]
	global_load_dwordx4 v[74:77], v[74:75], off
	ds_read_b128 v[130:133], v169 offset:23072
	global_load_dwordx4 v[78:81], v[78:79], off
	ds_read_b128 v[134:137], v170 offset:4640
	global_load_dwordx4 v[82:85], v[82:83], off
	s_mov_b32 s5, 0x3f000
	global_load_dwordx4 v[94:97], v[94:95], off
	s_waitcnt lgkmcnt(11)
	v_mfma_f32_32x32x16_bf16 v[34:49], v[156:159], v[152:155], v[34:49]
	global_load_dwordx4 v[70:73], v[70:71], off
	ds_read_b128 v[138:141], v169 offset:18464
	ds_read_b128 v[150:153], v170 offset:64
	s_waitcnt lgkmcnt(12)
	v_mfma_f32_32x32x16_bf16 v[18:33], v[144:147], v[160:163], v[18:33]
	ds_read_b128 v[142:145], v169 offset:18496
	ds_read_b128 v[146:149], v170 offset:32
	v_mfma_f32_32x32x16_bf16 v[2:17], v[156:159], v[160:163], v[2:17]
	ds_read_b128 v[154:157], v169 offset:23104
	ds_read_b128 v[158:161], v170 offset:4672
	s_waitcnt lgkmcnt(2)
	v_mfma_f32_32x32x16_bf16 v[50:65], v[138:141], v[146:149], v[50:65]
	v_mfma_f32_32x32x16_bf16 v[34:49], v[130:133], v[146:149], v[34:49]
	ds_read_b128 v[146:149], v170 offset:4704
	v_mfma_f32_32x32x16_bf16 v[18:33], v[138:141], v[134:137], v[18:33]
	ds_read_b128 v[138:141], v169 offset:23136
	v_mfma_f32_32x32x16_bf16 v[2:17], v[130:133], v[134:137], v[2:17]
	ds_read_b128 v[130:133], v169 offset:18528
	ds_read_b128 v[134:137], v170 offset:96
	s_waitcnt lgkmcnt(0)
	s_barrier
	v_mfma_f32_32x32x16_bf16 v[50:65], v[142:145], v[150:153], v[50:65]
	v_mfma_f32_32x32x16_bf16 v[34:49], v[154:157], v[150:153], v[34:49]
	ds_read_b128 v[150:153], v173 offset:36864
	v_mfma_f32_32x32x16_bf16 v[18:33], v[142:145], v[158:161], v[18:33]
	ds_read_b128 v[142:145], v172 offset:55296
	v_mfma_f32_32x32x16_bf16 v[2:17], v[154:157], v[158:161], v[2:17]
	ds_read_b128 v[154:157], v172 offset:59904
	ds_read_b128 v[158:161], v173 offset:41472
	v_mfma_f32_32x32x16_bf16 v[50:65], v[130:133], v[134:137], v[50:65]
	s_waitcnt vmcnt(1)
	ds_write_b128 v105, v[94:97]
	ds_write_b128 v105, v[90:93] offset:18432
	v_lshl_add_u64 v[94:95], v[126:127], 0, s[6:7]
	global_load_dwordx4 v[90:93], v[128:129], off
	v_mfma_f32_32x32x16_bf16 v[34:49], v[138:141], v[134:137], v[34:49]
	ds_write_b128 v109, v[86:89]
	ds_write_b128 v109, v[82:85] offset:18432
	v_lshl_add_u64 v[86:87], v[94:95], 0, v[116:117]
	global_load_dwordx4 v[86:89], v[86:87], off
	v_mfma_f32_32x32x16_bf16 v[18:33], v[130:133], v[146:149], v[18:33]
	ds_write_b128 v111, v[78:81]
	ds_write_b128 v111, v[74:77] offset:18432
	v_lshl_add_u64 v[78:79], v[94:95], 0, v[118:119]
	global_load_dwordx4 v[78:81], v[78:79], off
	v_mfma_f32_32x32x16_bf16 v[2:17], v[138:141], v[146:149], v[2:17]
	ds_write_b128 v167, v[66:69] offset:18432
	v_add_co_u32_e32 v66, vcc, s5, v124
	s_mov_b32 s5, 0x3e000
	s_nop 0
	v_addc_co_u32_e32 v67, vcc, 0, v125, vcc
	v_add_co_u32_e32 v74, vcc, s5, v124
	s_mov_b32 s5, 0x3d000
	s_nop 0
	v_addc_co_u32_e32 v75, vcc, 0, v125, vcc
	s_waitcnt vmcnt(3)
	ds_write_b128 v167, v[70:73]
	v_lshl_add_u64 v[70:71], v[94:95], 0, v[120:121]
	v_add_co_u32_e32 v82, vcc, s5, v124
	v_lshl_add_u64 v[94:95], v[94:95], 0, v[114:115]
	s_nop 0
	v_addc_co_u32_e32 v83, vcc, 0, v125, vcc
	global_load_dwordx4 v[94:97], v[94:95], off
	s_waitcnt lgkmcnt(10)
	v_mfma_f32_32x32x16_bf16 v[50:65], v[142:145], v[150:153], v[50:65]
	global_load_dwordx4 v[82:85], v[82:83], off
	ds_read_b128 v[124:127], v169 offset:59936
	global_load_dwordx4 v[74:77], v[74:75], off
	ds_read_b128 v[128:131], v170 offset:41504
	global_load_dwordx4 v[66:69], v[66:67], off
	s_nop 0
	global_load_dwordx4 v[70:73], v[70:71], off
	s_waitcnt lgkmcnt(11)
	v_mfma_f32_32x32x16_bf16 v[34:49], v[154:157], v[150:153], v[34:49]
	ds_read_b128 v[132:135], v169 offset:55328
	ds_read_b128 v[136:139], v169 offset:55360
	s_waitcnt lgkmcnt(12)
	v_mfma_f32_32x32x16_bf16 v[18:33], v[142:145], v[158:161], v[18:33]
	ds_read_b128 v[140:143], v170 offset:36896
	ds_read_b128 v[144:147], v170 offset:36928
	v_mfma_f32_32x32x16_bf16 v[2:17], v[154:157], v[158:161], v[2:17]
	ds_read_b128 v[148:151], v169 offset:59968
	ds_read_b128 v[152:155], v170 offset:41536
	s_waitcnt lgkmcnt(3)
	v_mfma_f32_32x32x16_bf16 v[50:65], v[132:135], v[140:143], v[50:65]
	v_mfma_f32_32x32x16_bf16 v[34:49], v[124:127], v[140:143], v[34:49]
	ds_read_b128 v[140:143], v170 offset:41568
	v_mfma_f32_32x32x16_bf16 v[18:33], v[132:135], v[128:131], v[18:33]
	ds_read_b128 v[132:135], v169 offset:60000
	v_mfma_f32_32x32x16_bf16 v[2:17], v[124:127], v[128:131], v[2:17]
	ds_read_b128 v[124:127], v169 offset:55392
	ds_read_b128 v[128:131], v170 offset:36960
	s_waitcnt lgkmcnt(0)
	s_barrier
	v_mfma_f32_32x32x16_bf16 v[50:65], v[136:139], v[144:147], v[50:65]
	v_mfma_f32_32x32x16_bf16 v[34:49], v[148:151], v[144:147], v[34:49]
	ds_read_b128 v[144:147], v173
	v_mfma_f32_32x32x16_bf16 v[18:33], v[136:139], v[152:155], v[18:33]
	ds_read_b128 v[136:139], v172 offset:18432
	v_mfma_f32_32x32x16_bf16 v[2:17], v[148:151], v[152:155], v[2:17]
	ds_read_b128 v[148:151], v172 offset:23040
	ds_read_b128 v[152:155], v173 offset:4608
	v_mfma_f32_32x32x16_bf16 v[50:65], v[124:127], v[128:131], v[50:65]
	s_waitcnt vmcnt(4)
	ds_write_b128 v105, v[94:97] offset:36864
	ds_write_b128 v105, v[90:93] offset:55296
	v_mfma_f32_32x32x16_bf16 v[34:49], v[132:135], v[128:131], v[34:49]
	ds_write_b128 v109, v[86:89] offset:36864
	s_waitcnt vmcnt(3)
	ds_write_b128 v109, v[82:85] offset:55296
	v_mfma_f32_32x32x16_bf16 v[18:33], v[124:127], v[140:143], v[18:33]
	ds_write_b128 v111, v[78:81] offset:36864
	s_waitcnt vmcnt(2)
	ds_write_b128 v111, v[74:77] offset:55296
	v_lshl_add_u32 v125, s4, 7, v168
	s_movk_i32 s4, 0xfe
	v_mfma_f32_32x32x16_bf16 v[2:17], v[132:135], v[140:143], v[2:17]
	s_waitcnt vmcnt(0)
	ds_write_b128 v167, v[70:73] offset:36864
	ds_write_b128 v167, v[66:69] offset:55296
	s_waitcnt lgkmcnt(10)
	v_mfma_f32_32x32x16_bf16 v[50:65], v[136:139], v[144:147], v[50:65]
	ds_read_b128 v[66:69], v169 offset:23072
	ds_read_b128 v[70:73], v170 offset:4640
	s_waitcnt lgkmcnt(11)
	v_mfma_f32_32x32x16_bf16 v[34:49], v[148:151], v[144:147], v[34:49]
	ds_read_b128 v[74:77], v169 offset:18464
	ds_read_b128 v[78:81], v169 offset:18496
	s_waitcnt lgkmcnt(12)
	v_mfma_f32_32x32x16_bf16 v[18:33], v[136:139], v[152:155], v[18:33]
	ds_read_b128 v[82:85], v170 offset:32
	ds_read_b128 v[86:89], v170 offset:64
	v_mfma_f32_32x32x16_bf16 v[2:17], v[148:151], v[152:155], v[2:17]
	ds_read_b128 v[90:93], v169 offset:23104
	ds_read_b128 v[94:97], v170 offset:4672
	s_waitcnt lgkmcnt(3)
	v_mfma_f32_32x32x16_bf16 v[50:65], v[74:77], v[82:85], v[50:65]
	v_mfma_f32_32x32x16_bf16 v[34:49], v[66:69], v[82:85], v[34:49]
	ds_read_b128 v[82:85], v170 offset:4704
	v_mfma_f32_32x32x16_bf16 v[18:33], v[74:77], v[70:73], v[18:33]
	ds_read_b128 v[74:77], v169 offset:23136
	v_mfma_f32_32x32x16_bf16 v[2:17], v[66:69], v[70:73], v[2:17]
	ds_read_b128 v[66:69], v169 offset:18528
	ds_read_b128 v[70:73], v170 offset:96
	s_waitcnt lgkmcnt(0)
	s_barrier
	v_mfma_f32_32x32x16_bf16 v[50:65], v[78:81], v[86:89], v[50:65]
	v_mfma_f32_32x32x16_bf16 v[34:49], v[90:93], v[86:89], v[34:49]
	ds_read_b128 v[86:89], v173 offset:36864
	v_mfma_f32_32x32x16_bf16 v[18:33], v[78:81], v[94:97], v[18:33]
	ds_read_b128 v[78:81], v172 offset:55296
	v_mfma_f32_32x32x16_bf16 v[2:17], v[90:93], v[94:97], v[2:17]
	ds_read_b128 v[90:93], v172 offset:59904
	ds_read_b128 v[94:97], v173 offset:41472
	v_mfma_f32_32x32x16_bf16 v[50:65], v[66:69], v[70:73], v[50:65]
	v_mfma_f32_32x32x16_bf16 v[34:49], v[74:77], v[70:73], v[34:49]
	ds_read_b128 v[70:73], v170 offset:41504
	v_mfma_f32_32x32x16_bf16 v[18:33], v[66:69], v[82:85], v[18:33]
	ds_read_b128 v[66:69], v169 offset:59936
	v_mfma_f32_32x32x16_bf16 v[2:17], v[74:77], v[82:85], v[2:17]
	ds_read_b128 v[74:77], v169 offset:55328
	ds_read_b128 v[82:85], v170 offset:36896
	s_waitcnt lgkmcnt(6)
	v_mfma_f32_32x32x16_bf16 v[50:65], v[78:81], v[86:89], v[50:65]
	s_waitcnt lgkmcnt(5)
	v_mfma_f32_32x32x16_bf16 v[34:49], v[90:93], v[86:89], v[34:49]
	ds_read_b128 v[86:89], v170 offset:36928
	s_waitcnt lgkmcnt(5)
	v_mfma_f32_32x32x16_bf16 v[18:33], v[78:81], v[94:97], v[18:33]
	ds_read_b128 v[78:81], v169 offset:55360
	v_mfma_f32_32x32x16_bf16 v[2:17], v[90:93], v[94:97], v[2:17]
	ds_read_b128 v[90:93], v169 offset:59968
	ds_read_b128 v[94:97], v170 offset:41536
	s_waitcnt lgkmcnt(4)
	v_mfma_f32_32x32x16_bf16 v[50:65], v[74:77], v[82:85], v[50:65]
	v_mfma_f32_32x32x16_bf16 v[34:49], v[66:69], v[82:85], v[34:49]
	ds_read_b128 v[82:85], v170 offset:41568
	v_mfma_f32_32x32x16_bf16 v[18:33], v[74:77], v[70:73], v[18:33]
	ds_read_b128 v[74:77], v169 offset:60000
	v_mfma_f32_32x32x16_bf16 v[2:17], v[66:69], v[70:73], v[2:17]
	ds_read_b128 v[66:69], v169 offset:55392
	ds_read_b128 v[70:73], v170 offset:36960
	s_waitcnt lgkmcnt(0)
	s_barrier
	v_mfma_f32_32x32x16_bf16 v[50:65], v[78:81], v[86:89], v[50:65]
	v_mfma_f32_32x32x16_bf16 v[34:49], v[90:93], v[86:89], v[34:49]
	v_mfma_f32_32x32x16_bf16 v[18:33], v[78:81], v[94:97], v[18:33]
	v_mfma_f32_32x32x16_bf16 v[2:17], v[90:93], v[94:97], v[2:17]
	v_mfma_f32_32x32x16_bf16 v[50:65], v[66:69], v[70:73], v[50:65]
	v_mfma_f32_32x32x16_bf16 v[34:49], v[74:77], v[70:73], v[34:49]
	v_mfma_f32_32x32x16_bf16 v[18:33], v[66:69], v[82:85], v[18:33]
	v_lshrrev_b32_e32 v66, 12, v125
	v_and_or_b32 v179, v66, s4, v103
	v_or_b32_e32 v66, v125, v1
	v_mov_b32_e32 v67, v99
	v_lshlrev_b64 v[68:69], 6, v[66:67]
	v_lshl_add_u64 v[80:81], s[44:45], 0, v[68:69]
	global_load_dwordx4 v[68:71], v[80:81], off offset:48
	v_mfma_f32_32x32x16_bf16 v[2:17], v[74:77], v[82:85], v[2:17]
	global_load_dwordx4 v[72:75], v[80:81], off offset:32
	global_load_dwordx4 v[76:79], v[80:81], off offset:16
	s_movk_i32 s4, 0x1fdf
	global_load_dwordx4 v[80:83], v[80:81], off
	v_lshlrev_b32_e32 v98, 20, v179
	v_bitop3_b32 v180, v125, s4, v1 bitop3:0xc8
	s_mov_b64 s[4:5], -1
	s_waitcnt vmcnt(2)
	v_add_f32_e32 v72, v72, v73
	v_add_f32_e32 v74, v74, v75
	v_mov_b32_e32 v73, v70
	s_waitcnt vmcnt(0)
	v_mov_b32_e32 v84, v81
	v_mov_b32_e32 v85, v82
	v_mov_b32_e32 v81, v83
	v_mov_b32_e32 v82, v77
	v_mov_b32_e32 v83, v78
	v_mov_b32_e32 v77, v79
	v_add_f32_e64 v80, v84, v80
	v_add_f32_e64 v81, v85, v81
	v_add_f32_e64 v76, v82, v76
	v_add_f32_e64 v77, v83, v77
	v_pk_add_f32 v[80:81], v[80:81], v[80:81] op_sel:[0,1] op_sel_hi:[1,0]
	v_pk_add_f32 v[76:77], v[76:77], v[76:77] op_sel:[0,1] op_sel_hi:[1,0]
	v_mov_b32_e32 v81, v68
	v_mov_b32_e32 v77, v69
	v_mov_b32_e32 v75, v71
	v_add_f32_e64 v68, v80, v76
	v_add_f32_e64 v69, v81, v77
	v_add_f32_e64 v70, v72, v74
	v_add_f32_e64 v71, v73, v75
	s_nop 0
	v_add_f32_e64 v68, v68, v70
	v_add_f32_e64 v69, v69, v71
	s_nop 0
	v_add_f32_e32 v68, v68, v69
	v_fmamk_f32 v68, v68, 0x3a800000, v174
	v_cmp_gt_f32_e32 vcc, s17, v68
	v_mul_f32_e32 v69, 0x4b800000, v68
	s_nop 0
	v_cndmask_b32_e32 v68, v68, v69, vcc
	v_rsq_f32_e32 v68, v68
	s_nop 0
	v_mul_f32_e32 v69, 0x45800000, v68
	v_cndmask_b32_e32 v124, v68, v69, vcc
	s_and_b64 vcc, exec, s[70:71]
	s_cbranch_vccz .LBB0_894
	s_cmp_lt_i32 s66, 3
	s_cbranch_scc1 .LBB0_859
	s_cmp_gt_i32 s66, 3
	s_cbranch_scc0 .LBB0_857
	s_cmp_lg_u32 s66, 4
	s_cbranch_scc0 .LBB0_856
	v_readlane_b32 s4, v231, 28
	v_readlane_b32 s5, v231, 29
	v_lshlrev_b32_e32 v70, 7, v180
	v_and_b32_e32 v70, 0xfe000, v70
	v_lshl_add_u64 v[68:69], s[4:5], 0, v[98:99]
	v_mov_b32_e32 v71, v99
	v_lshl_add_u64 v[68:69], v[68:69], 0, v[70:71]
	v_lshlrev_b32_e32 v70, 1, v108
	v_lshl_add_u64 v[68:69], v[68:69], 0, v[70:71]
	v_mul_f32_e32 v70, v50, v124
	v_cvt_pk_bf16_f32 v72, v70, s0
	v_lshlrev_b32_e32 v70, 1, v102
	v_lshl_add_u64 v[68:69], v[68:69], 0, v[70:71]
	v_mul_f32_e32 v70, v51, v124
	v_cvt_pk_bf16_f32 v70, v70, s0
	global_store_short v[68:69], v70, off offset:128
	v_mul_f32_e32 v70, v52, v124
	v_cvt_pk_bf16_f32 v70, v70, s0
	global_store_short v[68:69], v70, off offset:256
	v_mul_f32_e32 v70, v53, v124
	v_cvt_pk_bf16_f32 v70, v70, s0
	global_store_short v[68:69], v70, off offset:384
	v_mul_f32_e32 v70, v54, v124
	v_cvt_pk_bf16_f32 v70, v70, s0
	global_store_short v[68:69], v70, off offset:1024
	v_mul_f32_e32 v70, v55, v124
	v_cvt_pk_bf16_f32 v70, v70, s0
	global_store_short v[68:69], v70, off offset:1152
	v_mul_f32_e32 v70, v56, v124
	v_cvt_pk_bf16_f32 v70, v70, s0
	global_store_short v[68:69], v70, off offset:1280
	v_mul_f32_e32 v70, v57, v124
	v_cvt_pk_bf16_f32 v70, v70, s0
	global_store_short v[68:69], v70, off offset:1408
	v_mul_f32_e32 v70, v58, v124
	v_cvt_pk_bf16_f32 v70, v70, s0
	global_store_short v[68:69], v70, off offset:2048
	v_mul_f32_e32 v70, v59, v124
	v_cvt_pk_bf16_f32 v70, v70, s0
	global_store_short v[68:69], v70, off offset:2176
	v_mul_f32_e32 v70, v60, v124
	v_cvt_pk_bf16_f32 v70, v70, s0
	global_store_short v[68:69], v70, off offset:2304
	v_mul_f32_e32 v70, v61, v124
	v_cvt_pk_bf16_f32 v70, v70, s0
	global_store_short v[68:69], v70, off offset:2432
	v_mul_f32_e32 v70, v62, v124
	v_cvt_pk_bf16_f32 v70, v70, s0
	global_store_short v[68:69], v70, off offset:3072
	v_mul_f32_e32 v70, v63, v124
	v_cvt_pk_bf16_f32 v70, v70, s0
	global_store_short v[68:69], v70, off offset:3200
	v_mul_f32_e32 v70, v64, v124
	v_cvt_pk_bf16_f32 v70, v70, s0
	global_store_short v[68:69], v70, off offset:3328
	v_mul_f32_e32 v70, v65, v124
	v_cvt_pk_bf16_f32 v70, v70, s0
	global_store_short v[68:69], v72, off
	global_store_short v[68:69], v70, off offset:3456
	v_mul_f32_e32 v70, v34, v124
	v_add_co_u32_e32 v68, vcc, s13, v68
	v_cvt_pk_bf16_f32 v70, v70, s0
	s_nop 0
	v_addc_co_u32_e32 v69, vcc, 0, v69, vcc
	global_store_short v[68:69], v70, off
	v_mul_f32_e32 v70, v35, v124
	v_cvt_pk_bf16_f32 v70, v70, s0
	global_store_short v[68:69], v70, off offset:128
	v_mul_f32_e32 v70, v36, v124
	v_cvt_pk_bf16_f32 v70, v70, s0
	global_store_short v[68:69], v70, off offset:256
	v_mul_f32_e32 v70, v37, v124
	v_cvt_pk_bf16_f32 v70, v70, s0
	global_store_short v[68:69], v70, off offset:384
	v_mul_f32_e32 v70, v38, v124
	v_cvt_pk_bf16_f32 v70, v70, s0
	global_store_short v[68:69], v70, off offset:1024
	v_mul_f32_e32 v70, v39, v124
	v_cvt_pk_bf16_f32 v70, v70, s0
	global_store_short v[68:69], v70, off offset:1152
	v_mul_f32_e32 v70, v40, v124
	v_cvt_pk_bf16_f32 v70, v70, s0
	global_store_short v[68:69], v70, off offset:1280
	v_mul_f32_e32 v70, v41, v124
	v_cvt_pk_bf16_f32 v70, v70, s0
	global_store_short v[68:69], v70, off offset:1408
	v_mul_f32_e32 v70, v42, v124
	v_cvt_pk_bf16_f32 v70, v70, s0
	global_store_short v[68:69], v70, off offset:2048
	v_mul_f32_e32 v70, v43, v124
	v_cvt_pk_bf16_f32 v70, v70, s0
	global_store_short v[68:69], v70, off offset:2176
	v_mul_f32_e32 v70, v44, v124
	v_cvt_pk_bf16_f32 v70, v70, s0
	global_store_short v[68:69], v70, off offset:2304
	v_mul_f32_e32 v70, v45, v124
	v_cvt_pk_bf16_f32 v70, v70, s0
	global_store_short v[68:69], v70, off offset:2432
	v_mul_f32_e32 v70, v46, v124
	v_cvt_pk_bf16_f32 v70, v70, s0
	global_store_short v[68:69], v70, off offset:3072
	v_mul_f32_e32 v70, v47, v124
	v_cvt_pk_bf16_f32 v70, v70, s0
	global_store_short v[68:69], v70, off offset:3200
	v_mul_f32_e32 v70, v48, v124
	v_cvt_pk_bf16_f32 v70, v70, s0
	global_store_short v[68:69], v70, off offset:3328
	v_mul_f32_e32 v70, v49, v124
	v_cvt_pk_bf16_f32 v70, v70, s0
	global_store_short v[68:69], v70, off offset:3456
	s_mov_b64 s[4:5], 0

.LBB0_859:
	s_and_b64 vcc, exec, s[4:5]
	s_cbranch_vccz .LBB0_893
	v_lshl_add_u64 v[66:67], v[66:67], 2, s[54:55]
	global_load_dword v181, v[66:67], off
	s_and_b64 s[4:5], s[68:69], exec
	v_lshlrev_b32_e32 v82, 2, v104
	s_cselect_b32 s5, s39, s41
	s_cselect_b32 s4, s38, s40
	global_load_dword v206, v[106:107], off
	global_load_dwordx4 v[94:97], v82, s[4:5]
	global_load_dwordx4 v[90:93], v82, s[4:5] offset:32
	global_load_dwordx4 v[78:81], v82, s[4:5] offset:96
	global_load_dwordx4 v[86:89], v82, s[4:5] offset:64
	global_load_dwordx4 v[66:69], v82, s[4:5] offset:224
	global_load_dwordx4 v[70:73], v82, s[4:5] offset:192
	global_load_dwordx4 v[74:77], v82, s[4:5] offset:160
	s_nop 0
	global_load_dwordx4 v[82:85], v82, s[4:5] offset:128
	v_mul_f32_e64 v148, v50, v124
	v_mul_f32_e64 v149, v51, v124
	v_mul_f32_e64 v136, v52, v124
	v_mul_f32_e64 v137, v53, v124
	v_mul_f32_e64 v162, v148, v148
	v_mul_f32_e64 v163, v149, v149
	v_mul_f32_e64 v158, v136, v136
	v_mul_f32_e64 v159, v137, v137
	v_add_f32_e32 v162, v162, v163
	v_mul_f32_e64 v142, v54, v124
	v_mul_f32_e64 v143, v55, v124
	v_add_f32_e32 v158, v158, v162
	v_mul_f32_e64 v164, v142, v142
	v_mul_f32_e64 v165, v143, v143
	v_add_f32_e32 v158, v159, v158
	v_mul_f32_e64 v134, v56, v124
	v_mul_f32_e64 v135, v57, v124
	v_add_f32_e32 v158, v164, v158
	v_mul_f32_e64 v160, v134, v134
	v_mul_f32_e64 v161, v135, v135
	v_add_f32_e32 v158, v165, v158
	v_mul_f32_e64 v150, v58, v124
	v_mul_f32_e64 v151, v59, v124
	v_add_f32_e32 v158, v160, v158
	v_mul_f32_e64 v188, v150, v150
	v_mul_f32_e64 v189, v151, v151
	v_add_f32_e32 v158, v161, v158
	v_mul_f32_e64 v144, v60, v124
	v_mul_f32_e64 v145, v61, v124
	v_add_f32_e32 v158, v188, v158
	v_mul_f32_e64 v186, v144, v144
	v_mul_f32_e64 v187, v145, v145
	v_add_f32_e32 v158, v189, v158
	v_mul_f32_e64 v138, v62, v124
	v_mul_f32_e64 v139, v63, v124
	v_add_f32_e32 v158, v186, v158
	v_mul_f32_e64 v184, v138, v138
	v_mul_f32_e64 v185, v139, v139
	v_add_f32_e32 v158, v187, v158
	v_mul_f32_e64 v130, v64, v124
	v_mul_f32_e64 v131, v65, v124
	v_add_f32_e32 v158, v184, v158
	v_mul_f32_e64 v182, v130, v130
	v_mul_f32_e64 v183, v131, v131
	v_add_f32_e32 v158, v185, v158
	v_mul_f32_e64 v156, v34, v124
	v_mul_f32_e64 v157, v35, v124
	v_add_f32_e32 v158, v182, v158
	v_mul_f32_e64 v204, v156, v156
	v_mul_f32_e64 v205, v157, v157
	v_add_f32_e32 v158, v183, v158
	v_mul_f32_e64 v154, v36, v124
	v_mul_f32_e64 v155, v37, v124
	v_add_f32_e32 v158, v204, v158
	v_mul_f32_e64 v202, v154, v154
	v_mul_f32_e64 v203, v155, v155
	v_add_f32_e32 v158, v205, v158
	v_mul_f32_e64 v152, v38, v124
	v_mul_f32_e64 v153, v39, v124
	v_add_f32_e32 v158, v202, v158
	v_mul_f32_e64 v200, v152, v152
	v_mul_f32_e64 v201, v153, v153
	v_add_f32_e32 v158, v203, v158
	v_mul_f32_e64 v146, v40, v124
	v_mul_f32_e64 v147, v41, v124
	v_add_f32_e32 v158, v200, v158
	v_mul_f32_e64 v198, v146, v146
	v_mul_f32_e64 v199, v147, v147
	v_add_f32_e32 v158, v201, v158
	v_mul_f32_e64 v140, v42, v124
	v_mul_f32_e64 v141, v43, v124
	v_add_f32_e32 v158, v198, v158
	v_mul_f32_e64 v196, v140, v140
	v_mul_f32_e64 v197, v141, v141
	v_add_f32_e32 v158, v199, v158
	v_and_b32_e32 v127, 64, v175
	v_mul_f32_e64 v132, v44, v124
	v_mul_f32_e64 v133, v45, v124
	v_add_f32_e32 v158, v196, v158
	v_xor_b32_e32 v126, 32, v175
	v_add_u32_e32 v127, 64, v127
	v_mul_f32_e64 v194, v132, v132
	v_mul_f32_e64 v195, v133, v133
	v_add_f32_e32 v158, v197, v158
	v_cmp_lt_i32_e32 vcc, v126, v127
	v_mul_f32_e64 v128, v46, v124
	v_mul_f32_e64 v129, v47, v124
	v_add_f32_e32 v158, v194, v158
	v_cndmask_b32_e32 v126, v175, v126, vcc
	v_mul_f32_e64 v192, v128, v128
	v_mul_f32_e64 v193, v129, v129
	v_add_f32_e32 v158, v195, v158
	v_lshlrev_b32_e32 v207, 2, v126
	v_mul_f32_e64 v126, v48, v124
	v_mul_f32_e64 v127, v49, v124
	v_add_f32_e32 v158, v192, v158
	v_mul_f32_e64 v190, v126, v126
	v_mul_f32_e64 v191, v127, v127
	v_add_f32_e32 v158, v193, v158
	v_add_f32_e32 v158, v190, v158
	v_add_f32_e32 v183, v191, v158
	ds_bpermute_b32 v184, v207, v183
	s_waitcnt vmcnt(9)
	v_cvt_f32_i32_e32 v163, v181
	s_waitcnt vmcnt(8)
	v_mul_f32_e32 v181, v206, v163
	v_and_b32_e32 v182, 0x7fffffff, v181
	v_lshrrev_b32_e32 v158, 23, v182
	v_and_b32_e32 v159, 0x7fffff, v182
	v_cmp_nlt_f32_e64 s[76:77], |v181|, s20
	v_add_u32_e32 v161, 0xffffff88, v158
	v_or_b32_e32 v159, 0x800000, v159
	s_and_saveexec_b64 s[4:5], s[76:77]
	s_xor_b64 s[78:79], exec, s[4:5]
	s_cbranch_execz .LBB0_862
	v_mad_u64_u32 v[164:165], s[8:9], v159, s21, 0
	v_mov_b32_e32 v186, v165
	v_mov_b32_e32 v187, v99
	v_mad_u64_u32 v[186:187], s[8:9], v159, s23, v[186:187]
	v_mov_b32_e32 v188, v187
	v_mov_b32_e32 v189, v99
	v_mad_u64_u32 v[188:189], s[8:9], v159, s24, v[188:189]
	v_cmp_lt_u32_e32 vcc, 63, v161
	v_mov_b32_e32 v190, v189
	v_mov_b32_e32 v191, v99
	v_cndmask_b32_e32 v158, 0, v176, vcc
	v_mad_u64_u32 v[190:191], s[8:9], v159, s25, v[190:191]
	v_add_u32_e32 v158, v158, v161
	v_mov_b32_e32 v192, v191
	v_mov_b32_e32 v193, v99
	v_cmp_lt_u32_e64 s[4:5], 31, v158
	v_mad_u64_u32 v[192:193], s[8:9], v159, s28, v[192:193]
	s_nop 0
	v_cndmask_b32_e64 v160, 0, v177, s[4:5]
	v_mov_b32_e32 v194, v193
	v_mov_b32_e32 v195, v99
	v_add_u32_e32 v158, v160, v158
	v_mad_u64_u32 v[194:195], s[8:9], v159, s29, v[194:195]
	v_cmp_lt_u32_e64 s[6:7], 31, v158
	v_mov_b32_e32 v196, v195
	v_mov_b32_e32 v197, v99
	v_cndmask_b32_e64 v160, 0, v177, s[6:7]
	v_mad_u64_u32 v[196:197], s[8:9], v159, s33, v[196:197]
	v_add_u32_e32 v158, v160, v158
	v_cndmask_b32_e32 v160, v194, v190, vcc
	v_cndmask_b32_e32 v162, v196, v192, vcc
	v_cndmask_b32_e32 v185, v197, v194, vcc
	v_cndmask_b32_e64 v165, v162, v160, s[4:5]
	v_cndmask_b32_e64 v162, v185, v162, s[4:5]
	v_cndmask_b32_e32 v185, v192, v188, vcc
	v_cndmask_b32_e64 v160, v160, v185, s[4:5]
	v_sub_u32_e32 v187, 32, v158
	v_cmp_eq_u32_e64 s[8:9], 0, v158
	v_cndmask_b32_e32 v158, v190, v186, vcc
	v_cndmask_b32_e64 v162, v162, v165, s[6:7]
	v_cndmask_b32_e64 v165, v165, v160, s[6:7]
	v_cndmask_b32_e64 v185, v185, v158, s[4:5]
	v_alignbit_b32 v189, v162, v165, v187
	v_cndmask_b32_e64 v160, v160, v185, s[6:7]
	v_cndmask_b32_e32 v164, v188, v164, vcc
	v_cndmask_b32_e64 v162, v189, v162, s[8:9]
	v_alignbit_b32 v186, v165, v160, v187
	v_cndmask_b32_e64 v158, v158, v164, s[4:5]
	v_cndmask_b32_e64 v165, v186, v165, s[8:9]
	v_bfe_u32 v190, v162, 29, 1
	v_cndmask_b32_e64 v158, v185, v158, s[6:7]
	v_alignbit_b32 v186, v162, v165, 30
	v_sub_u32_e32 v191, 0, v190
	v_alignbit_b32 v164, v160, v158, v187
	v_xor_b32_e32 v186, v186, v191
	v_cndmask_b32_e64 v160, v164, v160, s[8:9]
	v_alignbit_b32 v164, v165, v160, 30
	v_ffbh_u32_e32 v165, v186
	v_min_u32_e32 v165, 32, v165
	v_alignbit_b32 v158, v160, v158, 30
	v_xor_b32_e32 v164, v164, v191
	v_sub_u32_e32 v185, 31, v165
	v_xor_b32_e32 v158, v158, v191
	v_alignbit_b32 v186, v186, v164, v185
	v_alignbit_b32 v158, v164, v158, v185
	v_alignbit_b32 v160, v186, v158, 9
	v_ffbh_u32_e32 v164, v160
	v_min_u32_e32 v164, 32, v164
	v_lshrrev_b32_e32 v189, 29, v162
	v_not_b32_e32 v185, v164
	v_alignbit_b32 v158, v160, v158, v185
	v_lshlrev_b32_e32 v160, 31, v189
	v_or_b32_e32 v185, 0x33000000, v160
	v_add_lshl_u32 v164, v164, v165, 23
	v_lshrrev_b32_e32 v158, 9, v158
	v_sub_u32_e32 v164, v185, v164
	v_or_b32_e32 v160, 0.5, v160
	v_lshlrev_b32_e32 v165, 23, v165
	v_or_b32_e32 v158, v164, v158
	v_lshrrev_b32_e32 v164, 9, v186
	v_sub_u32_e32 v160, v160, v165
	v_or_b32_e32 v160, v164, v160
	v_mul_f32_e32 v164, 0x3fc90fda, v160
	v_fma_f32 v165, v160, s50, -v164
	v_fmac_f32_e32 v165, 0x33a22168, v160
	v_fmac_f32_e32 v165, 0x3fc90fda, v158
	v_lshrrev_b32_e32 v160, 30, v162
	v_add_f32_e32 v158, v164, v165
	v_add_u32_e32 v185, v190, v160

.LBB0_892:
	s_or_b64 exec, exec, s[4:5]
	s_waitcnt lgkmcnt(0)
	v_add_f32_e32 v183, v183, v184
	v_fmamk_f32 v183, v183, 0x3c800000, v174
	v_mul_f32_e32 v184, 0x4b800000, v183
	v_cmp_gt_f32_e32 vcc, s17, v183
	s_and_b64 s[4:5], s[68:69], exec
	v_readlane_b32 s4, v231, 10
	v_cndmask_b32_e32 v183, v183, v184, vcc
	v_rsq_f32_e32 v183, v183
	v_readlane_b32 s5, v231, 27
	s_cselect_b32 s5, s4, s5
	v_readlane_b32 s4, v231, 14
	v_mul_f32_e32 v184, 0x45800000, v183
	v_cndmask_b32_e32 v184, v183, v184, vcc
	v_mul_f32_e64 v130, v130, v184
	v_mul_f32_e64 v131, v131, v184
	v_mul_f32_e64 v136, v136, v184
	v_mul_f32_e64 v137, v137, v184
	v_mul_f32_e64 v80, v130, v80
	v_mul_f32_e64 v81, v131, v81
	v_mul_f32_e64 v130, v156, v184
	v_mul_f32_e64 v131, v157, v184
	v_mul_f32_e64 v96, v96, v136
	v_mul_f32_e64 v97, v97, v137
	v_mul_f32_e64 v82, v130, v82
	v_mul_f32_e64 v83, v131, v83
	v_mul_f32_e64 v130, v154, v184
	v_mul_f32_e64 v131, v155, v184
	v_mul_f32_e64 v136, v142, v184
	v_mul_f32_e64 v137, v143, v184
	v_mul_f32_e64 v134, v134, v184
	v_mul_f32_e64 v135, v135, v184
	v_mul_f32_e64 v84, v130, v84
	v_mul_f32_e64 v85, v131, v85
	v_mul_f32_e64 v130, v152, v184
	v_mul_f32_e64 v131, v153, v184
	v_mul_f32_e64 v90, v90, v136
	v_mul_f32_e64 v91, v91, v137
	v_mul_f32_e64 v92, v92, v134
	v_mul_f32_e64 v93, v93, v135
	v_mul_f32_e64 v134, v150, v184
	v_mul_f32_e64 v135, v151, v184
	v_mul_f32_e64 v74, v130, v74
	v_mul_f32_e64 v75, v131, v75
	v_mul_f32_e64 v130, v146, v184
	v_mul_f32_e64 v131, v147, v184
	v_mul_f32_e64 v128, v128, v184
	v_mul_f32_e64 v129, v129, v184
	v_lshlrev_b32_e32 v136, 30, v189
	v_lshlrev_b32_e32 v137, 30, v185
	v_mul_f32_e64 v86, v86, v134
	v_mul_f32_e64 v87, v87, v135
	v_mul_f32_e64 v134, v144, v184
	v_mul_f32_e64 v135, v145, v184
	v_mul_f32_e64 v76, v130, v76
	v_mul_f32_e64 v77, v131, v77
	v_mul_f32_e64 v130, v140, v184
	v_mul_f32_e64 v131, v141, v184
	v_mul_f32_e64 v66, v128, v66
	v_mul_f32_e64 v67, v129, v67
	v_mul_f32_e64 v128, v158, v158
	v_mul_f32_e64 v129, v159, v159
	v_and_b32_e32 v150, 0x80000000, v136
	v_and_b32_e32 v151, 0x80000000, v137
	v_mov_b64_e32 v[136:137], s[18:19]
	v_mul_f32_e64 v88, v134, v88
	v_mul_f32_e64 v89, v135, v89
	v_mul_f32_e64 v134, v138, v184
	v_mul_f32_e64 v135, v139, v184
	v_mul_f32_e64 v70, v130, v70
	v_mul_f32_e64 v71, v131, v71
	v_mul_f32_e64 v130, v132, v184
	v_mul_f32_e64 v131, v133, v184
	v_mov_b64_e32 v[132:133], s[12:13]
	v_fma_f32 v138, v128, s22, v136
	v_fma_f32 v139, v129, s22, v136
	v_mul_f32_e64 v78, v134, v78
	v_mul_f32_e64 v79, v135, v79
	v_fma_f32 v134, v128, s16, v132
	v_fma_f32 v135, v129, s16, v132
	v_fma_f32 v138, v128, v138, s60
	v_fma_f32 v139, v129, v139, s60
	v_fma_f32 v134, v128, v134, s64
	v_fma_f32 v135, v129, v135, s64
	v_fma_f32 v138, v128, v138, s62
	v_fma_f32 v139, v129, v139, s62
	v_and_b32_e32 v140, 1, v189
	v_fma_f32 v138, v128, v138, 1.0
	v_fma_f32 v139, v129, v139, 1.0
	v_mul_f32_e64 v128, v128, v134
	v_mul_f32_e64 v129, v129, v135
	v_and_b32_e32 v141, 1, v185
	v_fma_f32 v128, v158, v128, v158
	v_fma_f32 v129, v159, v129, v159
	v_cmp_eq_u32_e32 vcc, 0, v140
	v_lshlrev_b32_e32 v146, 30, v192
	v_lshlrev_b32_e32 v147, 30, v186
	v_cndmask_b32_e64 v129, -v129, v139, vcc
	v_cmp_eq_u32_e32 vcc, 0, v141
	v_mul_f32_e64 v72, v130, v72
	v_mul_f32_e64 v73, v131, v73
	v_mul_f32_e64 v130, v160, v160
	v_mul_f32_e64 v131, v161, v161
	v_cndmask_b32_e64 v128, -v128, v138, vcc
	v_xor_b32_e32 v134, v188, v187
	v_xor_b32_e32 v135, v182, v181
	v_and_b32_e32 v138, 0x80000000, v146
	v_and_b32_e32 v139, 0x80000000, v147
	v_xor_b32_e32 v140, v134, v138
	v_xor_b32_e32 v141, v135, v139
	v_fma_f32 v134, v130, s16, v132
	v_fma_f32 v135, v131, s16, v132
	v_fma_f32 v138, v130, s22, v136
	v_fma_f32 v139, v131, s22, v136
	v_mul_f32_e64 v148, v148, v184
	v_mul_f32_e64 v149, v149, v184
	v_fma_f32 v134, v130, v134, s64
	v_fma_f32 v135, v131, v135, s64
	v_fma_f32 v138, v130, v138, s60
	v_fma_f32 v139, v131, v139, s60
	v_readlane_b32 s6, v231, 26
	v_mul_f32_e64 v94, v94, v148
	v_mul_f32_e64 v95, v95, v149
	v_and_b32_e32 v148, 1, v192
	v_mul_f32_e64 v134, v130, v134
	v_mul_f32_e64 v135, v131, v135
	v_fma_f32 v138, v130, v138, s62
	v_fma_f32 v139, v131, v139, s62
	s_cselect_b32 s4, s4, s6
	v_and_b32_e32 v149, 1, v186
	v_fma_f32 v134, v160, v134, v160
	v_fma_f32 v135, v161, v135, v161
	v_fma_f32 v130, v130, v138, 1.0
	v_fma_f32 v131, v131, v139, 1.0
	v_cmp_eq_u32_e64 s[6:7], 0, v148
	v_lshl_add_u64 v[200:201], s[4:5], 0, v[98:99]
	v_cmp_class_f32_e64 vcc, v187, s63
	v_cndmask_b32_e64 v131, v131, v135, s[6:7]
	v_cmp_eq_u32_e64 s[6:7], 0, v149
	v_cmp_class_f32_e64 s[4:5], v181, s63
	v_xor_b32_e32 v131, v140, v131
	v_cndmask_b32_e64 v130, v130, v134, s[6:7]
	v_xor_b32_e32 v130, v141, v130
	v_xor_b32_e32 v129, v150, v129
	v_xor_b32_e32 v128, v151, v128
	v_cndmask_b32_e32 v131, v178, v131, vcc
	v_cndmask_b32_e64 v130, v178, v130, s[4:5]
	v_mul_f32_e64 v126, v126, v184
	v_mul_f32_e64 v127, v127, v184
	v_cndmask_b32_e32 v129, v178, v129, vcc
	v_cndmask_b32_e64 v128, v178, v128, s[4:5]
	v_mul_f32_e64 v134, v90, v130
	v_mul_f32_e64 v135, v91, v131
	v_mul_f32_e64 v68, v126, v68
	v_mul_f32_e64 v69, v127, v69
	v_mul_f32_e64 v126, v162, v162
	v_mul_f32_e64 v127, v163, v163
	v_fma_f32 v134, v94, v128, -v134
	v_fma_f32 v135, v95, v129, -v135
	v_mul_f32_e64 v94, v94, v130
	v_mul_f32_e64 v95, v95, v131
	v_fma_f32 v138, v126, s16, v132
	v_fma_f32 v139, v127, s16, v132
	v_fma_f32 v90, v90, v128, v94
	v_fma_f32 v91, v91, v129, v95
	v_fma_f32 v94, v126, s22, v136
	v_fma_f32 v95, v127, s22, v136
	v_fma_f32 v128, v126, v138, s64
	v_fma_f32 v129, v127, v139, s64
	v_fma_f32 v94, v126, v94, s60
	v_fma_f32 v95, v127, v95, s60
	v_and_b32_e32 v144, 1, v197
	v_fma_f32 v94, v126, v94, s62
	v_fma_f32 v95, v127, v95, s62
	v_and_b32_e32 v145, 1, v193
	v_fma_f32 v94, v126, v94, 1.0
	v_fma_f32 v95, v127, v95, 1.0
	v_mul_f32_e64 v126, v126, v128
	v_mul_f32_e64 v127, v127, v129
	v_cmp_eq_u32_e32 vcc, 0, v144
	v_fma_f32 v126, v162, v126, v162
	v_fma_f32 v127, v163, v127, v163
	v_mul_f32_e64 v140, v164, v164
	v_mul_f32_e64 v141, v165, v165
	v_cndmask_b32_e64 v95, -v127, v95, vcc
	v_cmp_eq_u32_e32 vcc, 0, v145
	v_fma_f32 v128, v140, s22, v136
	v_fma_f32 v129, v141, s22, v136
	v_and_b32_e32 v148, 1, v198
	v_cndmask_b32_e64 v94, -v126, v94, vcc
	v_fma_f32 v126, v140, s16, v132
	v_fma_f32 v127, v141, s16, v132
	v_fma_f32 v128, v140, v128, s60
	v_fma_f32 v129, v141, v129, s60
	v_fma_f32 v126, v140, v126, s64
	v_fma_f32 v127, v141, v127, s64
	v_fma_f32 v128, v140, v128, s62
	v_fma_f32 v129, v141, v129, s62
	v_mul_f32_e64 v126, v140, v126
	v_mul_f32_e64 v127, v141, v127
	v_lshlrev_b32_e32 v142, 30, v197
	v_lshlrev_b32_e32 v143, 30, v193
	v_and_b32_e32 v149, 1, v194
	v_fma_f32 v126, v164, v126, v164
	v_fma_f32 v127, v165, v127, v165
	v_fma_f32 v128, v140, v128, 1.0
	v_fma_f32 v129, v141, v129, 1.0
	v_cmp_eq_u32_e64 s[6:7], 0, v148
	v_lshlrev_b32_e32 v146, 30, v198
	v_lshlrev_b32_e32 v147, 30, v194
	v_and_b32_e32 v130, 0x80000000, v142
	v_and_b32_e32 v131, 0x80000000, v143
	v_cndmask_b32_e64 v127, v129, v127, s[6:7]
	v_cmp_eq_u32_e64 s[6:7], 0, v149
	v_xor_b32_e32 v95, v130, v95
	v_xor_b32_e32 v94, v131, v94
	v_cndmask_b32_e64 v126, v128, v126, s[6:7]
	v_and_b32_e32 v128, 0x80000000, v146
	v_and_b32_e32 v129, 0x80000000, v147
	v_xor_b32_e32 v130, v196, v195
	v_xor_b32_e32 v131, v191, v190
	v_xor_b32_e32 v128, v130, v128
	v_xor_b32_e32 v129, v131, v129
	v_cmp_class_f32_e64 vcc, v195, s63
	v_cmp_class_f32_e64 s[4:5], v190, s63
	v_xor_b32_e32 v127, v128, v127
	v_xor_b32_e32 v126, v129, v126
	v_cndmask_b32_e32 v127, v178, v127, vcc
	v_cndmask_b32_e64 v126, v178, v126, s[4:5]
	v_cndmask_b32_e32 v95, v178, v95, vcc
	v_cndmask_b32_e64 v94, v178, v94, s[4:5]
	v_mul_f32_e64 v128, v92, v126
	v_mul_f32_e64 v129, v93, v127
	v_lshlrev_b32_e32 v202, 7, v180
	v_mov_b32_e32 v203, v99
	v_fma_f32 v128, v96, v94, -v128
	v_fma_f32 v129, v97, v95, -v129
	v_mul_f32_e64 v96, v96, v126
	v_mul_f32_e64 v97, v97, v127
	v_lshl_add_u64 v[200:201], v[200:201], 0, v[202:203]
	v_fma_f32 v92, v92, v94, v96
	v_fma_f32 v93, v93, v95, v97
	v_lshlrev_b32_e32 v94, 1, v104
	v_mov_b32_e32 v95, v99
	v_lshl_add_u64 v[94:95], v[200:201], 0, v[94:95]
	v_cvt_pk_bf16_f32 v78, v78, v79
	v_cvt_pk_bf16_f32 v79, v80, v81
	v_cvt_pk_bf16_f32 v96, v134, v135
	v_cvt_pk_bf16_f32 v97, v128, v129
	v_cvt_pk_bf16_f32 v90, v90, v91
	v_cvt_pk_bf16_f32 v91, v92, v93
	v_cvt_pk_bf16_f32 v86, v86, v87
	v_cvt_pk_bf16_f32 v87, v88, v89
	global_store_dwordx2 v[94:95], v[78:79], off offset:48
	v_cvt_pk_bf16_f32 v78, v82, v83
	v_cvt_pk_bf16_f32 v79, v84, v85
	v_cvt_pk_bf16_f32 v74, v74, v75
	v_cvt_pk_bf16_f32 v75, v76, v77
	v_cvt_pk_bf16_f32 v70, v70, v71
	v_cvt_pk_bf16_f32 v71, v72, v73
	v_cvt_pk_bf16_f32 v66, v66, v67
	v_cvt_pk_bf16_f32 v67, v68, v69
	global_store_dwordx2 v[94:95], v[96:97], off
	global_store_dwordx2 v[94:95], v[90:91], off offset:16
	global_store_dwordx2 v[94:95], v[86:87], off offset:32
	global_store_dwordx2 v[94:95], v[78:79], off offset:64
	global_store_dwordx2 v[94:95], v[74:75], off offset:80
	global_store_dwordx2 v[94:95], v[70:71], off offset:96
	global_store_dwordx2 v[94:95], v[66:67], off offset:112

.LBB0_894:
	s_and_b32 s6, s80, -8
	v_add_u32_e32 v66, s6, v179
	v_ashrrev_i32_e32 v67, 31, v66
	v_lshlrev_b64 v[66:67], 20, v[66:67]
	s_and_b64 vcc, exec, s[4:5]
	v_lshl_add_u64 v[68:69], s[56:57], 0, v[66:67]
	v_lshlrev_b32_e32 v66, 1, v104
	s_cbranch_vccz .LBB0_896
	v_lshlrev_b32_e32 v70, 7, v180
	v_mov_b32_e32 v71, v99
	v_lshl_add_u64 v[70:71], v[68:69], 0, v[70:71]
	v_mov_b32_e32 v67, v99
	v_mul_f32_e64 v50, v50, v124
	v_mul_f32_e64 v51, v51, v124
	v_mul_f32_e64 v52, v52, v124
	v_mul_f32_e64 v53, v53, v124
	v_mul_f32_e64 v34, v34, v124
	v_mul_f32_e64 v35, v35, v124
	v_mul_f32_e64 v36, v36, v124
	v_mul_f32_e64 v37, v37, v124
	v_lshl_add_u64 v[70:71], v[70:71], 0, v[66:67]
	v_cvt_pk_bf16_f32 v50, v50, v51
	v_cvt_pk_bf16_f32 v51, v52, v53
	v_cvt_pk_bf16_f32 v34, v34, v35
	v_cvt_pk_bf16_f32 v35, v36, v37
	global_store_dwordx2 v[70:71], v[50:51], off
	v_mul_f32_e64 v50, v54, v124
	v_mul_f32_e64 v51, v55, v124
	v_mul_f32_e64 v52, v56, v124
	v_mul_f32_e64 v53, v57, v124
	global_store_dwordx2 v[70:71], v[34:35], off offset:64
	v_mul_f32_e64 v34, v38, v124
	v_mul_f32_e64 v35, v39, v124
	v_mul_f32_e64 v36, v40, v124
	v_mul_f32_e64 v37, v41, v124
	v_cvt_pk_bf16_f32 v50, v50, v51
	v_cvt_pk_bf16_f32 v51, v52, v53
	v_cvt_pk_bf16_f32 v34, v34, v35
	v_cvt_pk_bf16_f32 v35, v36, v37
	global_store_dwordx2 v[70:71], v[50:51], off offset:16
	v_mul_f32_e64 v50, v58, v124
	v_mul_f32_e64 v51, v59, v124
	v_mul_f32_e64 v52, v60, v124
	v_mul_f32_e64 v53, v61, v124
	global_store_dwordx2 v[70:71], v[34:35], off offset:80
	v_mul_f32_e64 v34, v42, v124
	v_mul_f32_e64 v35, v43, v124
	v_mul_f32_e64 v36, v44, v124
	v_mul_f32_e64 v37, v45, v124
	v_cvt_pk_bf16_f32 v50, v50, v51
	v_cvt_pk_bf16_f32 v51, v52, v53
	v_cvt_pk_bf16_f32 v34, v34, v35
	v_cvt_pk_bf16_f32 v35, v36, v37
	global_store_dwordx2 v[70:71], v[50:51], off offset:32
	v_mul_f32_e64 v50, v62, v124
	v_mul_f32_e64 v51, v63, v124
	v_mul_f32_e64 v52, v64, v124
	v_mul_f32_e64 v53, v65, v124
	global_store_dwordx2 v[70:71], v[34:35], off offset:96
	v_mul_f32_e64 v34, v46, v124
	v_mul_f32_e64 v35, v47, v124
	v_mul_f32_e64 v36, v48, v124
	v_mul_f32_e64 v37, v49, v124
	v_cvt_pk_bf16_f32 v50, v50, v51
	v_cvt_pk_bf16_f32 v51, v52, v53
	v_cvt_pk_bf16_f32 v34, v34, v35
	v_cvt_pk_bf16_f32 v35, v36, v37
	global_store_dwordx2 v[70:71], v[50:51], off offset:48
	global_store_dwordx2 v[70:71], v[34:35], off offset:112
.LBB0_896:
	v_or_b32_e32 v34, v125, v171
	v_lshlrev_b32_e32 v35, 6, v34
	global_load_dwordx4 v[36:39], v35, s[44:45] offset:48
	global_load_dwordx4 v[40:43], v35, s[44:45] offset:32
	global_load_dwordx4 v[44:47], v35, s[44:45] offset:16
	global_load_dwordx4 v[48:51], v35, s[44:45]
	s_movk_i32 s4, 0x1fff
	v_bitop3_b32 v71, v125, s4, v171 bitop3:0xc8
	s_mov_b64 s[4:5], -1
	s_waitcnt vmcnt(2)
	v_add_f32_e32 v40, v40, v41
	v_add_f32_e32 v42, v42, v43
	s_waitcnt vmcnt(0)
	v_mov_b32_e32 v52, v49
	v_mov_b32_e32 v53, v50
	v_mov_b32_e32 v49, v51
	v_mov_b32_e32 v50, v45
	v_mov_b32_e32 v51, v46
	v_mov_b32_e32 v45, v47
	v_add_f32_e64 v48, v52, v48
	v_add_f32_e64 v49, v53, v49
	v_add_f32_e64 v44, v50, v44
	v_add_f32_e64 v45, v51, v45
	v_pk_add_f32 v[48:49], v[48:49], v[48:49] op_sel:[0,1] op_sel_hi:[1,0]
	v_pk_add_f32 v[44:45], v[44:45], v[44:45] op_sel:[0,1] op_sel_hi:[1,0]
	v_mov_b32_e32 v49, v36
	v_mov_b32_e32 v45, v37
	v_mov_b32_e32 v41, v38
	v_mov_b32_e32 v43, v39
	v_add_f32_e64 v36, v48, v44
	v_add_f32_e64 v37, v49, v45
	v_add_f32_e64 v38, v40, v42
	v_add_f32_e64 v39, v41, v43
	s_nop 0
	v_add_f32_e64 v36, v36, v38
	v_add_f32_e64 v37, v37, v39
	s_nop 0
	v_add_f32_e32 v35, v36, v37
	v_fmamk_f32 v35, v35, 0x3a800000, v174
	v_cmp_gt_f32_e32 vcc, s17, v35
	v_mul_f32_e32 v36, 0x4b800000, v35
	s_nop 0
	v_cndmask_b32_e32 v35, v35, v36, vcc
	v_rsq_f32_e32 v35, v35
	s_nop 0
	v_mul_f32_e32 v36, 0x45800000, v35
	v_cndmask_b32_e32 v70, v35, v36, vcc
	s_andn2_b64 vcc, exec, s[70:71]
	s_cbranch_vccnz .LBB0_902
	s_cmp_lt_i32 s66, 3
	s_cbranch_scc1 .LBB0_905
	s_cmp_gt_i32 s66, 3
	s_cbranch_scc0 .LBB0_903
	s_cmp_lg_u32 s66, 4
	s_cbranch_scc0 .LBB0_901
	v_readlane_b32 s4, v231, 28
	v_readlane_b32 s5, v231, 29
	v_lshlrev_b32_e32 v35, 7, v71
	v_and_b32_e32 v38, 0xfe000, v35
	v_lshl_add_u64 v[36:37], s[4:5], 0, v[98:99]
	v_mov_b32_e32 v39, v99
	v_lshl_add_u64 v[36:37], v[36:37], 0, v[38:39]
	v_lshlrev_b32_e32 v38, 1, v110
	v_lshl_add_u64 v[36:37], v[36:37], 0, v[38:39]
	v_mul_f32_e32 v35, v18, v70
	v_lshlrev_b32_e32 v38, 1, v102
	v_cvt_pk_bf16_f32 v35, v35, s0
	v_lshl_add_u64 v[36:37], v[36:37], 0, v[38:39]
	global_store_short v[36:37], v35, off
	v_mul_f32_e32 v35, v19, v70
	v_cvt_pk_bf16_f32 v35, v35, s0
	global_store_short v[36:37], v35, off offset:128
	v_mul_f32_e32 v35, v20, v70
	v_cvt_pk_bf16_f32 v35, v35, s0
	global_store_short v[36:37], v35, off offset:256
	v_mul_f32_e32 v35, v21, v70
	v_cvt_pk_bf16_f32 v35, v35, s0
	global_store_short v[36:37], v35, off offset:384
	v_mul_f32_e32 v35, v22, v70
	v_cvt_pk_bf16_f32 v35, v35, s0
	global_store_short v[36:37], v35, off offset:1024
	v_mul_f32_e32 v35, v23, v70
	v_cvt_pk_bf16_f32 v35, v35, s0
	global_store_short v[36:37], v35, off offset:1152
	v_mul_f32_e32 v35, v24, v70
	v_cvt_pk_bf16_f32 v35, v35, s0
	global_store_short v[36:37], v35, off offset:1280
	v_mul_f32_e32 v35, v25, v70
	v_cvt_pk_bf16_f32 v35, v35, s0
	global_store_short v[36:37], v35, off offset:1408
	v_mul_f32_e32 v35, v26, v70
	v_cvt_pk_bf16_f32 v35, v35, s0
	global_store_short v[36:37], v35, off offset:2048
	v_mul_f32_e32 v35, v27, v70
	v_cvt_pk_bf16_f32 v35, v35, s0
	global_store_short v[36:37], v35, off offset:2176
	v_mul_f32_e32 v35, v28, v70
	v_cvt_pk_bf16_f32 v35, v35, s0
	global_store_short v[36:37], v35, off offset:2304
	v_mul_f32_e32 v35, v29, v70
	v_cvt_pk_bf16_f32 v35, v35, s0
	global_store_short v[36:37], v35, off offset:2432
	v_mul_f32_e32 v35, v30, v70
	v_cvt_pk_bf16_f32 v35, v35, s0
	global_store_short v[36:37], v35, off offset:3072
	v_mul_f32_e32 v35, v31, v70
	v_cvt_pk_bf16_f32 v35, v35, s0
	global_store_short v[36:37], v35, off offset:3200
	v_mul_f32_e32 v35, v32, v70
	v_cvt_pk_bf16_f32 v35, v35, s0
	global_store_short v[36:37], v35, off offset:3328
	v_mul_f32_e32 v35, v33, v70
	v_cvt_pk_bf16_f32 v35, v35, s0
	global_store_short v[36:37], v35, off offset:3456
	v_mul_f32_e32 v35, v2, v70
	v_add_co_u32_e32 v36, vcc, s13, v36
	v_cvt_pk_bf16_f32 v35, v35, s0
	s_nop 0
	v_addc_co_u32_e32 v37, vcc, 0, v37, vcc
	global_store_short v[36:37], v35, off
	v_mul_f32_e32 v35, v3, v70
	v_cvt_pk_bf16_f32 v35, v35, s0
	global_store_short v[36:37], v35, off offset:128
	v_mul_f32_e32 v35, v4, v70
	v_cvt_pk_bf16_f32 v35, v35, s0
	global_store_short v[36:37], v35, off offset:256
	v_mul_f32_e32 v35, v5, v70
	v_cvt_pk_bf16_f32 v35, v35, s0
	global_store_short v[36:37], v35, off offset:384
	v_mul_f32_e32 v35, v6, v70
	v_cvt_pk_bf16_f32 v35, v35, s0
	global_store_short v[36:37], v35, off offset:1024
	v_mul_f32_e32 v35, v7, v70
	v_cvt_pk_bf16_f32 v35, v35, s0
	global_store_short v[36:37], v35, off offset:1152
	v_mul_f32_e32 v35, v8, v70
	v_cvt_pk_bf16_f32 v35, v35, s0
	global_store_short v[36:37], v35, off offset:1280
	v_mul_f32_e32 v35, v9, v70
	v_cvt_pk_bf16_f32 v35, v35, s0
	global_store_short v[36:37], v35, off offset:1408
	v_mul_f32_e32 v35, v10, v70
	v_cvt_pk_bf16_f32 v35, v35, s0
	global_store_short v[36:37], v35, off offset:2048
	v_mul_f32_e32 v35, v11, v70
	v_cvt_pk_bf16_f32 v35, v35, s0
	global_store_short v[36:37], v35, off offset:2176
	v_mul_f32_e32 v35, v12, v70
	v_cvt_pk_bf16_f32 v35, v35, s0
	global_store_short v[36:37], v35, off offset:2304
	v_mul_f32_e32 v35, v13, v70
	v_cvt_pk_bf16_f32 v35, v35, s0
	global_store_short v[36:37], v35, off offset:2432
	v_mul_f32_e32 v35, v14, v70
	v_cvt_pk_bf16_f32 v35, v35, s0
	global_store_short v[36:37], v35, off offset:3072
	v_mul_f32_e32 v35, v15, v70
	v_cvt_pk_bf16_f32 v35, v35, s0
	global_store_short v[36:37], v35, off offset:3200
	v_mul_f32_e32 v35, v16, v70
	v_cvt_pk_bf16_f32 v35, v35, s0
	global_store_short v[36:37], v35, off offset:3328
	v_mul_f32_e32 v35, v17, v70
	v_cvt_pk_bf16_f32 v35, v35, s0
	global_store_short v[36:37], v35, off offset:3456
	s_mov_b64 s[4:5], 0

.LBB0_905:
	s_and_b64 vcc, exec, s[4:5]
	s_cbranch_vccz .LBB0_939
	v_lshlrev_b32_e32 v34, 2, v34
	global_load_dword v67, v34, s[54:55]
	s_and_b64 s[4:5], s[68:69], exec
	v_lshlrev_b32_e32 v50, 2, v104
	s_cselect_b32 s5, s39, s41
	s_cselect_b32 s4, s38, s40
	global_load_dword v162, v[106:107], off
	global_load_dwordx4 v[62:65], v50, s[4:5]
	global_load_dwordx4 v[58:61], v50, s[4:5] offset:32
	global_load_dwordx4 v[46:49], v50, s[4:5] offset:96
	global_load_dwordx4 v[54:57], v50, s[4:5] offset:64
	global_load_dwordx4 v[34:37], v50, s[4:5] offset:224
	global_load_dwordx4 v[38:41], v50, s[4:5] offset:192
	global_load_dwordx4 v[42:45], v50, s[4:5] offset:160
	s_nop 0
	global_load_dwordx4 v[50:53], v50, s[4:5] offset:128
	v_mul_f32_e64 v94, v18, v70
	v_mul_f32_e64 v95, v19, v70
	v_mul_f32_e64 v82, v20, v70
	v_mul_f32_e64 v83, v21, v70
	v_mul_f32_e64 v134, v94, v94
	v_mul_f32_e64 v135, v95, v95
	v_mul_f32_e64 v130, v82, v82
	v_mul_f32_e64 v131, v83, v83
	v_add_f32_e32 v134, v134, v135
	v_mul_f32_e64 v88, v22, v70
	v_mul_f32_e64 v89, v23, v70
	v_add_f32_e32 v130, v130, v134
	v_mul_f32_e64 v136, v88, v88
	v_mul_f32_e64 v137, v89, v89
	v_add_f32_e32 v130, v131, v130
	v_mul_f32_e64 v80, v24, v70
	v_mul_f32_e64 v81, v25, v70
	v_add_f32_e32 v130, v136, v130
	v_mul_f32_e64 v132, v80, v80
	v_mul_f32_e64 v133, v81, v81
	v_add_f32_e32 v130, v137, v130
	v_mul_f32_e64 v96, v26, v70
	v_mul_f32_e64 v97, v27, v70
	v_add_f32_e32 v130, v132, v130
	v_mul_f32_e64 v144, v96, v96
	v_mul_f32_e64 v145, v97, v97
	v_add_f32_e32 v130, v133, v130
	v_mul_f32_e64 v90, v28, v70
	v_mul_f32_e64 v91, v29, v70
	v_add_f32_e32 v130, v144, v130
	v_mul_f32_e64 v142, v90, v90
	v_mul_f32_e64 v143, v91, v91
	v_add_f32_e32 v130, v145, v130
	v_mul_f32_e64 v84, v30, v70
	v_mul_f32_e64 v85, v31, v70
	v_add_f32_e32 v130, v142, v130
	v_mul_f32_e64 v140, v84, v84
	v_mul_f32_e64 v141, v85, v85
	v_add_f32_e32 v130, v143, v130
	v_mul_f32_e64 v76, v32, v70
	v_mul_f32_e64 v77, v33, v70
	v_add_f32_e32 v130, v140, v130
	v_mul_f32_e64 v138, v76, v76
	v_mul_f32_e64 v139, v77, v77
	v_add_f32_e32 v130, v141, v130
	v_mul_f32_e64 v128, v2, v70
	v_mul_f32_e64 v129, v3, v70
	v_add_f32_e32 v130, v138, v130
	v_mul_f32_e64 v160, v128, v128
	v_mul_f32_e64 v161, v129, v129
	v_add_f32_e32 v130, v139, v130
	v_mul_f32_e64 v126, v4, v70
	v_mul_f32_e64 v127, v5, v70
	v_add_f32_e32 v130, v160, v130
	v_mul_f32_e64 v158, v126, v126
	v_mul_f32_e64 v159, v127, v127
	v_add_f32_e32 v130, v161, v130
	v_mul_f32_e64 v124, v6, v70
	v_mul_f32_e64 v125, v7, v70
	v_add_f32_e32 v130, v158, v130
	v_mul_f32_e64 v156, v124, v124
	v_mul_f32_e64 v157, v125, v125
	v_add_f32_e32 v130, v159, v130
	v_mul_f32_e64 v92, v8, v70
	v_mul_f32_e64 v93, v9, v70
	v_add_f32_e32 v130, v156, v130
	v_mul_f32_e64 v154, v92, v92
	v_mul_f32_e64 v155, v93, v93
	v_add_f32_e32 v130, v157, v130
	v_mul_f32_e64 v86, v10, v70
	v_mul_f32_e64 v87, v11, v70
	v_add_f32_e32 v130, v154, v130
	v_mul_f32_e64 v152, v86, v86
	v_mul_f32_e64 v153, v87, v87
	v_add_f32_e32 v130, v155, v130
	v_and_b32_e32 v73, 64, v175
	v_mul_f32_e64 v78, v12, v70
	v_mul_f32_e64 v79, v13, v70
	v_add_f32_e32 v130, v152, v130
	v_xor_b32_e32 v72, 32, v175
	v_add_u32_e32 v73, 64, v73
	v_mul_f32_e64 v150, v78, v78
	v_mul_f32_e64 v151, v79, v79
	v_add_f32_e32 v130, v153, v130
	v_cmp_lt_i32_e32 vcc, v72, v73
	v_mul_f32_e64 v74, v14, v70
	v_mul_f32_e64 v75, v15, v70
	v_add_f32_e32 v130, v150, v130
	v_cndmask_b32_e32 v72, v175, v72, vcc
	v_mul_f32_e64 v148, v74, v74
	v_mul_f32_e64 v149, v75, v75
	v_add_f32_e32 v130, v151, v130
	v_lshlrev_b32_e32 v163, 2, v72
	v_mul_f32_e64 v72, v16, v70
	v_mul_f32_e64 v73, v17, v70
	v_add_f32_e32 v130, v148, v130
	v_mul_f32_e64 v146, v72, v72
	v_mul_f32_e64 v147, v73, v73
	v_add_f32_e32 v130, v149, v130
	s_waitcnt vmcnt(9)
	v_cvt_f32_i32_e32 v135, v67
	v_add_f32_e32 v67, v146, v130
	v_add_f32_e32 v139, v147, v67
	ds_bpermute_b32 v140, v163, v139
	s_waitcnt vmcnt(8)
	v_mul_f32_e32 v67, v162, v135
	v_and_b32_e32 v138, 0x7fffffff, v67
	v_lshrrev_b32_e32 v130, 23, v138
	v_and_b32_e32 v131, 0x7fffff, v138
	v_cmp_nlt_f32_e64 s[66:67], |v67|, s20
	v_add_u32_e32 v133, 0xffffff88, v130
	v_or_b32_e32 v131, 0x800000, v131
	s_and_saveexec_b64 s[4:5], s[66:67]
	s_xor_b64 s[70:71], exec, s[4:5]
	s_cbranch_execz .LBB0_908
	v_mad_u64_u32 v[136:137], s[8:9], v131, s21, 0
	v_mov_b32_e32 v142, v137
	v_mov_b32_e32 v143, v99
	v_mad_u64_u32 v[142:143], s[8:9], v131, s23, v[142:143]
	v_mov_b32_e32 v144, v143
	v_mov_b32_e32 v145, v99
	v_mad_u64_u32 v[144:145], s[8:9], v131, s24, v[144:145]
	v_cmp_lt_u32_e32 vcc, 63, v133
	v_mov_b32_e32 v146, v145
	v_mov_b32_e32 v147, v99
	v_cndmask_b32_e32 v130, 0, v176, vcc
	v_mad_u64_u32 v[146:147], s[8:9], v131, s25, v[146:147]
	v_add_u32_e32 v130, v130, v133
	v_mov_b32_e32 v148, v147
	v_mov_b32_e32 v149, v99
	v_cmp_lt_u32_e64 s[4:5], 31, v130
	v_mad_u64_u32 v[148:149], s[8:9], v131, s28, v[148:149]
	s_nop 0
	v_cndmask_b32_e64 v132, 0, v177, s[4:5]
	v_mov_b32_e32 v150, v149
	v_mov_b32_e32 v151, v99
	v_add_u32_e32 v130, v132, v130
	v_mad_u64_u32 v[150:151], s[8:9], v131, s29, v[150:151]
	v_cmp_lt_u32_e64 s[6:7], 31, v130
	v_mov_b32_e32 v152, v151
	v_mov_b32_e32 v153, v99
	v_cndmask_b32_e64 v132, 0, v177, s[6:7]
	v_mad_u64_u32 v[152:153], s[8:9], v131, s33, v[152:153]
	v_add_u32_e32 v130, v132, v130
	v_cndmask_b32_e32 v132, v150, v146, vcc
	v_cndmask_b32_e32 v134, v152, v148, vcc
	v_cndmask_b32_e32 v141, v153, v150, vcc
	v_cndmask_b32_e64 v137, v134, v132, s[4:5]
	v_cndmask_b32_e64 v134, v141, v134, s[4:5]
	v_cndmask_b32_e32 v141, v148, v144, vcc
	v_cndmask_b32_e64 v132, v132, v141, s[4:5]
	v_sub_u32_e32 v143, 32, v130
	v_cmp_eq_u32_e64 s[8:9], 0, v130
	v_cndmask_b32_e32 v130, v146, v142, vcc
	v_cndmask_b32_e64 v134, v134, v137, s[6:7]
	v_cndmask_b32_e64 v137, v137, v132, s[6:7]
	v_cndmask_b32_e64 v141, v141, v130, s[4:5]
	v_alignbit_b32 v145, v134, v137, v143
	v_cndmask_b32_e64 v132, v132, v141, s[6:7]
	v_cndmask_b32_e32 v136, v144, v136, vcc
	v_cndmask_b32_e64 v134, v145, v134, s[8:9]
	v_alignbit_b32 v142, v137, v132, v143
	v_cndmask_b32_e64 v130, v130, v136, s[4:5]
	v_cndmask_b32_e64 v137, v142, v137, s[8:9]
	v_bfe_u32 v146, v134, 29, 1
	v_cndmask_b32_e64 v130, v141, v130, s[6:7]
	v_alignbit_b32 v142, v134, v137, 30
	v_sub_u32_e32 v147, 0, v146
	v_alignbit_b32 v136, v132, v130, v143
	v_xor_b32_e32 v142, v142, v147
	v_cndmask_b32_e64 v132, v136, v132, s[8:9]
	v_alignbit_b32 v136, v137, v132, 30
	v_ffbh_u32_e32 v137, v142
	v_min_u32_e32 v137, 32, v137
	v_alignbit_b32 v130, v132, v130, 30
	v_xor_b32_e32 v136, v136, v147
	v_sub_u32_e32 v141, 31, v137
	v_xor_b32_e32 v130, v130, v147
	v_alignbit_b32 v142, v142, v136, v141
	v_alignbit_b32 v130, v136, v130, v141
	v_alignbit_b32 v132, v142, v130, 9
	v_ffbh_u32_e32 v136, v132
	v_min_u32_e32 v136, 32, v136
	v_lshrrev_b32_e32 v145, 29, v134
	v_not_b32_e32 v141, v136
	v_alignbit_b32 v130, v132, v130, v141
	v_lshlrev_b32_e32 v132, 31, v145
	v_or_b32_e32 v141, 0x33000000, v132
	v_add_lshl_u32 v136, v136, v137, 23
	v_lshrrev_b32_e32 v130, 9, v130
	v_sub_u32_e32 v136, v141, v136
	v_or_b32_e32 v132, 0.5, v132
	v_lshlrev_b32_e32 v137, 23, v137
	v_or_b32_e32 v130, v136, v130
	v_lshrrev_b32_e32 v136, 9, v142
	v_sub_u32_e32 v132, v132, v137
	v_or_b32_e32 v132, v136, v132
	v_mul_f32_e32 v136, 0x3fc90fda, v132
	v_fma_f32 v137, v132, s50, -v136
	v_fmac_f32_e32 v137, 0x33a22168, v132
	v_fmac_f32_e32 v137, 0x3fc90fda, v130
	v_lshrrev_b32_e32 v132, 30, v134
	v_add_f32_e32 v130, v136, v137
	v_add_u32_e32 v141, v146, v132

.LBB0_938:
	s_or_b64 exec, exec, s[4:5]
	s_waitcnt lgkmcnt(0)
	v_add_f32_e32 v139, v139, v140
	v_fmamk_f32 v139, v139, 0x3c800000, v174
	v_mul_f32_e32 v140, 0x4b800000, v139
	v_cmp_gt_f32_e32 vcc, s17, v139
	s_and_b64 s[4:5], s[68:69], exec
	v_readlane_b32 s4, v231, 10
	v_cndmask_b32_e32 v139, v139, v140, vcc
	v_readlane_b32 s5, v231, 27
	v_rsq_f32_e32 v139, v139
	s_cselect_b32 s5, s4, s5
	v_readlane_b32 s4, v231, 14
	v_readlane_b32 s6, v231, 26
	s_cselect_b32 s4, s4, s6
	v_lshl_add_u64 v[156:157], s[4:5], 0, v[98:99]
	v_lshlrev_b32_e32 v98, 7, v71
	v_lshl_add_u64 v[156:157], v[156:157], 0, v[98:99]
	v_mul_f32_e32 v98, 0x45800000, v139
	v_cndmask_b32_e32 v98, v139, v98, vcc
	v_mul_f32_e64 v76, v76, v98
	v_mul_f32_e64 v77, v77, v98
	v_mul_f32_e64 v82, v82, v98
	v_mul_f32_e64 v83, v83, v98
	v_mul_f32_e64 v48, v76, v48
	v_mul_f32_e64 v49, v77, v49
	v_mul_f32_e64 v76, v128, v98
	v_mul_f32_e64 v77, v129, v98
	v_mul_f32_e64 v64, v64, v82
	v_mul_f32_e64 v65, v65, v83
	v_mul_f32_e64 v50, v76, v50
	v_mul_f32_e64 v51, v77, v51
	v_mul_f32_e64 v76, v126, v98
	v_mul_f32_e64 v77, v127, v98
	v_mul_f32_e64 v82, v88, v98
	v_mul_f32_e64 v83, v89, v98
	v_mul_f32_e64 v80, v80, v98
	v_mul_f32_e64 v81, v81, v98
	v_mul_f32_e64 v52, v76, v52
	v_mul_f32_e64 v53, v77, v53
	v_mul_f32_e64 v76, v124, v98
	v_mul_f32_e64 v77, v125, v98
	v_mul_f32_e64 v58, v58, v82
	v_mul_f32_e64 v59, v59, v83
	v_mul_f32_e64 v60, v60, v80
	v_mul_f32_e64 v61, v61, v81
	v_mul_f32_e64 v80, v96, v98
	v_mul_f32_e64 v81, v97, v98
	v_mul_f32_e64 v42, v76, v42
	v_mul_f32_e64 v43, v77, v43
	v_mul_f32_e64 v76, v92, v98
	v_mul_f32_e64 v77, v93, v98
	v_mul_f32_e64 v74, v74, v98
	v_mul_f32_e64 v75, v75, v98
	v_lshlrev_b32_e32 v82, 30, v145
	v_lshlrev_b32_e32 v83, 30, v141
	v_mul_f32_e64 v54, v54, v80
	v_mul_f32_e64 v55, v55, v81
	v_mul_f32_e64 v80, v90, v98
	v_mul_f32_e64 v81, v91, v98
	v_mul_f32_e64 v44, v76, v44
	v_mul_f32_e64 v45, v77, v45
	v_mul_f32_e64 v76, v86, v98
	v_mul_f32_e64 v77, v87, v98
	v_mul_f32_e64 v34, v74, v34
	v_mul_f32_e64 v35, v75, v35
	v_mul_f32_e64 v74, v130, v130
	v_mul_f32_e64 v75, v131, v131
	v_and_b32_e32 v96, 0x80000000, v82
	v_and_b32_e32 v97, 0x80000000, v83
	v_mov_b64_e32 v[82:83], s[18:19]
	v_mul_f32_e64 v56, v80, v56
	v_mul_f32_e64 v57, v81, v57
	v_mul_f32_e64 v80, v84, v98
	v_mul_f32_e64 v81, v85, v98
	v_mul_f32_e64 v38, v76, v38
	v_mul_f32_e64 v39, v77, v39
	v_mul_f32_e64 v76, v78, v98
	v_mul_f32_e64 v77, v79, v98
	v_mov_b64_e32 v[78:79], s[12:13]
	v_fma_f32 v84, v74, s22, v82
	v_fma_f32 v85, v75, s22, v82
	v_mul_f32_e64 v46, v80, v46
	v_mul_f32_e64 v47, v81, v47
	v_fma_f32 v80, v74, s16, v78
	v_fma_f32 v81, v75, s16, v78
	v_fma_f32 v84, v74, v84, s60
	v_fma_f32 v85, v75, v85, s60
	v_fma_f32 v80, v74, v80, s64
	v_fma_f32 v81, v75, v81, s64
	v_fma_f32 v84, v74, v84, s62
	v_fma_f32 v85, v75, v85, s62
	v_and_b32_e32 v86, 1, v145
	v_fma_f32 v84, v74, v84, 1.0
	v_fma_f32 v85, v75, v85, 1.0
	v_mul_f32_e64 v74, v74, v80
	v_mul_f32_e64 v75, v75, v81
	v_and_b32_e32 v87, 1, v141
	v_fma_f32 v74, v130, v74, v130
	v_fma_f32 v75, v131, v75, v131
	v_cmp_eq_u32_e32 vcc, 0, v86
	v_lshlrev_b32_e32 v92, 30, v148
	v_lshlrev_b32_e32 v93, 30, v142
	v_cndmask_b32_e64 v75, -v75, v85, vcc
	v_cmp_eq_u32_e32 vcc, 0, v87
	v_mul_f32_e64 v40, v76, v40
	v_mul_f32_e64 v41, v77, v41
	v_mul_f32_e64 v76, v132, v132
	v_mul_f32_e64 v77, v133, v133
	v_cndmask_b32_e64 v74, -v74, v84, vcc
	v_cmp_class_f32_e64 s[4:5], v67, s63
	v_xor_b32_e32 v80, v144, v143
	v_xor_b32_e32 v67, v138, v67
	v_and_b32_e32 v81, 0x80000000, v92
	v_and_b32_e32 v84, 0x80000000, v93
	v_xor_b32_e32 v86, v80, v81
	v_xor_b32_e32 v67, v67, v84
	v_fma_f32 v80, v76, s16, v78
	v_fma_f32 v81, v77, s16, v78
	v_fma_f32 v84, v76, s22, v82
	v_fma_f32 v85, v77, s22, v82
	v_mul_f32_e64 v94, v94, v98
	v_mul_f32_e64 v95, v95, v98
	v_fma_f32 v80, v76, v80, s64
	v_fma_f32 v81, v77, v81, s64
	v_fma_f32 v84, v76, v84, s60
	v_fma_f32 v85, v77, v85, s60
	v_mul_f32_e64 v62, v62, v94
	v_mul_f32_e64 v63, v63, v95
	v_and_b32_e32 v94, 1, v148
	v_mul_f32_e64 v80, v76, v80
	v_mul_f32_e64 v81, v77, v81
	v_fma_f32 v84, v76, v84, s62
	v_fma_f32 v85, v77, v85, s62
	v_and_b32_e32 v95, 1, v142
	v_fma_f32 v80, v132, v80, v132
	v_fma_f32 v81, v133, v81, v133
	v_fma_f32 v76, v76, v84, 1.0
	v_fma_f32 v77, v77, v85, 1.0
	v_cmp_eq_u32_e64 s[6:7], 0, v94
	v_cmp_class_f32_e64 vcc, v143, s63
	v_xor_b32_e32 v75, v96, v75
	v_cndmask_b32_e64 v77, v77, v81, s[6:7]
	v_cmp_eq_u32_e64 s[6:7], 0, v95
	v_xor_b32_e32 v77, v86, v77
	v_xor_b32_e32 v74, v97, v74
	v_cndmask_b32_e64 v76, v76, v80, s[6:7]
	v_xor_b32_e32 v67, v67, v76
	v_cndmask_b32_e32 v77, v178, v77, vcc
	v_cndmask_b32_e64 v76, v178, v67, s[4:5]
	v_mul_f32_e64 v72, v72, v98
	v_mul_f32_e64 v73, v73, v98
	v_cndmask_b32_e32 v75, v178, v75, vcc
	v_cndmask_b32_e64 v74, v178, v74, s[4:5]
	v_mul_f32_e64 v80, v58, v76
	v_mul_f32_e64 v81, v59, v77
	v_mul_f32_e64 v36, v72, v36
	v_mul_f32_e64 v37, v73, v37
	v_mul_f32_e64 v72, v134, v134
	v_mul_f32_e64 v73, v135, v135
	v_fma_f32 v80, v62, v74, -v80
	v_fma_f32 v81, v63, v75, -v81
	v_mul_f32_e64 v62, v62, v76
	v_mul_f32_e64 v63, v63, v77
	v_fma_f32 v84, v72, s16, v78
	v_fma_f32 v85, v73, s16, v78
	v_fma_f32 v58, v58, v74, v62
	v_fma_f32 v59, v59, v75, v63
	v_fma_f32 v62, v72, s22, v82
	v_fma_f32 v63, v73, s22, v82
	v_fma_f32 v74, v72, v84, s64
	v_fma_f32 v75, v73, v85, s64
	v_fma_f32 v62, v72, v62, s60
	v_fma_f32 v63, v73, v63, s60
	v_and_b32_e32 v90, 1, v153
	v_fma_f32 v62, v72, v62, s62
	v_fma_f32 v63, v73, v63, s62
	v_and_b32_e32 v91, 1, v149
	v_fma_f32 v62, v72, v62, 1.0
	v_fma_f32 v63, v73, v63, 1.0
	v_mul_f32_e64 v72, v72, v74
	v_mul_f32_e64 v73, v73, v75
	v_cmp_eq_u32_e32 vcc, 0, v90
	v_fma_f32 v72, v134, v72, v134
	v_fma_f32 v73, v135, v73, v135
	v_mul_f32_e64 v86, v136, v136
	v_mul_f32_e64 v87, v137, v137
	v_cndmask_b32_e64 v63, -v73, v63, vcc
	v_cmp_eq_u32_e32 vcc, 0, v91
	v_fma_f32 v74, v86, s22, v82
	v_fma_f32 v75, v87, s22, v82
	v_and_b32_e32 v93, 1, v154
	v_cndmask_b32_e64 v62, -v72, v62, vcc
	v_fma_f32 v72, v86, s16, v78
	v_fma_f32 v73, v87, s16, v78
	v_fma_f32 v74, v86, v74, s60
	v_fma_f32 v75, v87, v75, s60
	v_fma_f32 v72, v86, v72, s64
	v_fma_f32 v73, v87, v73, s64
	v_fma_f32 v74, v86, v74, s62
	v_fma_f32 v75, v87, v75, s62
	v_mul_f32_e64 v72, v86, v72
	v_mul_f32_e64 v73, v87, v73
	v_lshlrev_b32_e32 v88, 30, v153
	v_and_b32_e32 v94, 1, v150
	v_fma_f32 v72, v136, v72, v136
	v_fma_f32 v73, v137, v73, v137
	v_fma_f32 v74, v86, v74, 1.0
	v_fma_f32 v75, v87, v75, 1.0
	v_cmp_eq_u32_e64 s[6:7], 0, v93
	v_lshlrev_b32_e32 v67, 30, v154
	v_lshlrev_b32_e32 v92, 30, v150
	v_and_b32_e32 v76, 0x80000000, v88
	v_cndmask_b32_e64 v73, v75, v73, s[6:7]
	v_cmp_eq_u32_e64 s[6:7], 0, v94
	v_xor_b32_e32 v63, v76, v63
	v_and_b32_e32 v67, 0x80000000, v67
	v_cndmask_b32_e64 v72, v74, v72, s[6:7]
	v_and_b32_e32 v74, 0x80000000, v92
	v_xor_b32_e32 v75, v152, v151
	v_xor_b32_e32 v76, v147, v146
	v_lshlrev_b32_e32 v89, 30, v149
	v_xor_b32_e32 v67, v75, v67
	v_xor_b32_e32 v74, v76, v74
	v_and_b32_e32 v77, 0x80000000, v89
	v_cmp_class_f32_e64 vcc, v151, s63
	v_cmp_class_f32_e64 s[4:5], v146, s63
	v_xor_b32_e32 v67, v67, v73
	v_xor_b32_e32 v72, v74, v72
	v_xor_b32_e32 v62, v77, v62
	v_cndmask_b32_e32 v73, v178, v67, vcc
	v_cndmask_b32_e64 v72, v178, v72, s[4:5]
	v_cndmask_b32_e32 v63, v178, v63, vcc
	v_cndmask_b32_e64 v62, v178, v62, s[4:5]
	v_mul_f32_e64 v74, v60, v72
	v_mul_f32_e64 v75, v61, v73
	v_mov_b32_e32 v67, v99
	v_fma_f32 v74, v64, v62, -v74
	v_fma_f32 v75, v65, v63, -v75
	v_mul_f32_e64 v64, v64, v72
	v_mul_f32_e64 v65, v65, v73
	v_cvt_pk_bf16_f32 v46, v46, v47
	v_fma_f32 v60, v60, v62, v64
	v_fma_f32 v61, v61, v63, v65
	v_lshl_add_u64 v[62:63], v[156:157], 0, v[66:67]
	v_cvt_pk_bf16_f32 v47, v48, v49
	v_cvt_pk_bf16_f32 v64, v80, v81
	v_cvt_pk_bf16_f32 v65, v74, v75
	v_cvt_pk_bf16_f32 v58, v58, v59
	v_cvt_pk_bf16_f32 v59, v60, v61
	v_cvt_pk_bf16_f32 v54, v54, v55
	v_cvt_pk_bf16_f32 v55, v56, v57
	global_store_dwordx2 v[62:63], v[46:47], off offset:48
	v_cvt_pk_bf16_f32 v46, v50, v51
	v_cvt_pk_bf16_f32 v47, v52, v53
	v_cvt_pk_bf16_f32 v42, v42, v43
	v_cvt_pk_bf16_f32 v43, v44, v45
	v_cvt_pk_bf16_f32 v38, v38, v39
	v_cvt_pk_bf16_f32 v39, v40, v41
	v_cvt_pk_bf16_f32 v34, v34, v35
	v_cvt_pk_bf16_f32 v35, v36, v37
	global_store_dwordx2 v[62:63], v[64:65], off
	global_store_dwordx2 v[62:63], v[58:59], off offset:16
	global_store_dwordx2 v[62:63], v[54:55], off offset:32
	global_store_dwordx2 v[62:63], v[46:47], off offset:64
	global_store_dwordx2 v[62:63], v[42:43], off offset:80
	global_store_dwordx2 v[62:63], v[38:39], off offset:96
	global_store_dwordx2 v[62:63], v[34:35], off offset:112

.LBB0_940:
	v_lshlrev_b32_e32 v98, 7, v71
	v_lshl_add_u64 v[34:35], v[68:69], 0, v[98:99]
	v_mov_b32_e32 v67, v99
	v_mul_f32_e64 v18, v18, v70
	v_mul_f32_e64 v19, v19, v70
	v_mul_f32_e64 v20, v20, v70
	v_mul_f32_e64 v21, v21, v70
	v_mul_f32_e64 v2, v2, v70
	v_mul_f32_e64 v3, v3, v70
	v_mul_f32_e64 v4, v4, v70
	v_mul_f32_e64 v5, v5, v70
	v_lshl_add_u64 v[34:35], v[34:35], 0, v[66:67]
	v_cvt_pk_bf16_f32 v18, v18, v19
	v_cvt_pk_bf16_f32 v19, v20, v21
	v_cvt_pk_bf16_f32 v2, v2, v3
	v_cvt_pk_bf16_f32 v3, v4, v5
	global_store_dwordx2 v[34:35], v[18:19], off
	v_mul_f32_e64 v18, v22, v70
	v_mul_f32_e64 v19, v23, v70
	v_mul_f32_e64 v20, v24, v70
	v_mul_f32_e64 v21, v25, v70
	global_store_dwordx2 v[34:35], v[2:3], off offset:64
	v_mul_f32_e64 v2, v6, v70
	v_mul_f32_e64 v3, v7, v70
	v_mul_f32_e64 v4, v8, v70
	v_mul_f32_e64 v5, v9, v70
	v_cvt_pk_bf16_f32 v18, v18, v19
	v_cvt_pk_bf16_f32 v19, v20, v21
	v_cvt_pk_bf16_f32 v2, v2, v3
	v_cvt_pk_bf16_f32 v3, v4, v5
	global_store_dwordx2 v[34:35], v[18:19], off offset:16
	v_mul_f32_e64 v18, v26, v70
	v_mul_f32_e64 v19, v27, v70
	v_mul_f32_e64 v20, v28, v70
	v_mul_f32_e64 v21, v29, v70
	global_store_dwordx2 v[34:35], v[2:3], off offset:80
	v_mul_f32_e64 v2, v10, v70
	v_mul_f32_e64 v3, v11, v70
	v_mul_f32_e64 v4, v12, v70
	v_mul_f32_e64 v5, v13, v70
	v_cvt_pk_bf16_f32 v18, v18, v19
	v_cvt_pk_bf16_f32 v19, v20, v21
	v_cvt_pk_bf16_f32 v2, v2, v3
	v_cvt_pk_bf16_f32 v3, v4, v5
	global_store_dwordx2 v[34:35], v[18:19], off offset:32
	v_mul_f32_e64 v18, v30, v70
	v_mul_f32_e64 v19, v31, v70
	v_mul_f32_e64 v20, v32, v70
	v_mul_f32_e64 v21, v33, v70
	global_store_dwordx2 v[34:35], v[2:3], off offset:96
	v_mul_f32_e64 v2, v14, v70
	v_mul_f32_e64 v3, v15, v70
	v_mul_f32_e64 v4, v16, v70
	v_mul_f32_e64 v5, v17, v70
	v_cvt_pk_bf16_f32 v18, v18, v19
	v_cvt_pk_bf16_f32 v19, v20, v21
	v_cvt_pk_bf16_f32 v2, v2, v3
	v_cvt_pk_bf16_f32 v3, v4, v5
	global_store_dwordx2 v[34:35], v[18:19], off offset:48
	global_store_dwordx2 v[34:35], v[2:3], off offset:112
	s_branch .LBB0_850

.LBB0_943:
	s_or_b64 exec, exec, s[4:5]
	s_waitcnt lgkmcnt(0)
	v_add_f32_e32 v76, v76, v77
	v_fmamk_f32 v76, v76, 0x3c800000, v156
	v_mul_f32_e32 v77, 0x4b800000, v76
	v_cmp_gt_f32_e32 vcc, s20, v76
	v_cmp_class_f32_e64 s[4:5], v74, s65
	s_nop 0
	v_cndmask_b32_e32 v76, v76, v77, vcc
	v_rsq_f32_e32 v92, v76
	v_lshlrev_b64 v[76:77], 11, v[98:99]
	v_lshl_add_u64 v[76:77], s[42:43], 0, v[76:77]
	v_lshl_add_u64 v[76:77], v[144:145], 1, v[76:77]
	v_mul_f32_e32 v93, 0x45800000, v92
	v_cndmask_b32_e32 v92, v92, v93, vcc
	v_mul_f32_e64 v8, v8, v92
	v_mul_f32_e64 v9, v9, v92
	v_mul_f32_e64 v24, v24, v92
	v_mul_f32_e64 v25, v25, v92
	v_mul_f32_e64 v8, v8, v44
	v_mul_f32_e64 v9, v9, v45
	v_mul_f32_e64 v16, v16, v92
	v_mul_f32_e64 v17, v17, v92
	v_lshlrev_b32_e32 v44, 30, v82
	v_lshlrev_b32_e32 v45, 30, v78
	v_mul_f32_e64 v24, v60, v24
	v_mul_f32_e64 v25, v61, v25
	v_mul_f32_e64 v20, v20, v92
	v_mul_f32_e64 v21, v21, v92
	v_mul_f32_e64 v12, v12, v92
	v_mul_f32_e64 v13, v13, v92
	v_mul_f32_e64 v16, v16, v36
	v_mul_f32_e64 v17, v17, v37
	v_mul_f32_e64 v36, v28, v28
	v_mul_f32_e64 v37, v29, v29
	v_and_b32_e32 v60, 0x80000000, v44
	v_and_b32_e32 v61, 0x80000000, v45
	v_mov_b64_e32 v[44:45], s[46:47]
	v_mul_f32_e64 v20, v20, v46
	v_mul_f32_e64 v21, v21, v47
	v_mul_f32_e64 v6, v6, v92
	v_mul_f32_e64 v7, v7, v92
	v_mul_f32_e64 v12, v12, v40
	v_mul_f32_e64 v13, v13, v41
	v_mov_b64_e32 v[40:41], s[18:19]
	v_fma_f32 v46, v36, s60, v44
	v_fma_f32 v47, v37, s60, v44
	v_mul_f32_e64 v6, v6, v42
	v_mul_f32_e64 v7, v7, v43
	v_fma_f32 v42, v36, s22, v40
	v_fma_f32 v43, v37, s22, v40
	v_fma_f32 v46, v36, v46, s62
	v_fma_f32 v47, v37, v47, s62
	v_mul_f32_e64 v26, v26, v92
	v_mul_f32_e64 v27, v27, v92
	v_fma_f32 v46, v36, v46, s64
	v_fma_f32 v47, v37, v47, s64
	v_fma_f32 v42, v36, v42, s66
	v_fma_f32 v43, v37, v43, s66
	v_mul_f32_e64 v26, v54, v26
	v_mul_f32_e64 v27, v55, v27
	v_mul_f32_e64 v10, v10, v92
	v_mul_f32_e64 v11, v11, v92
	v_lshlrev_b32_e32 v54, 30, v85
	v_lshlrev_b32_e32 v55, 30, v79
	v_fma_f32 v46, v36, v46, 1.0
	v_fma_f32 v47, v37, v47, 1.0
	v_mul_f32_e64 v36, v36, v42
	v_mul_f32_e64 v37, v37, v43
	v_mul_f32_e64 v10, v10, v38
	v_mul_f32_e64 v11, v11, v39
	v_mul_f32_e64 v38, v30, v30
	v_mul_f32_e64 v39, v31, v31
	v_fma_f32 v28, v28, v36, v28
	v_fma_f32 v29, v29, v37, v29
	v_xor_b32_e32 v36, v81, v80
	v_xor_b32_e32 v37, v75, v74
	v_and_b32_e32 v42, 0x80000000, v54
	v_and_b32_e32 v43, 0x80000000, v55
	v_xor_b32_e32 v42, v36, v42
	v_xor_b32_e32 v43, v37, v43
	v_fma_f32 v36, v38, s22, v40
	v_fma_f32 v37, v39, s22, v40
	v_mul_f32_e64 v22, v22, v92
	v_mul_f32_e64 v23, v23, v92
	v_fma_f32 v36, v38, v36, s66
	v_fma_f32 v37, v39, v37, s66
	v_mul_f32_e64 v22, v22, v56
	v_mul_f32_e64 v23, v23, v57
	v_mul_f32_e64 v36, v38, v36
	v_mul_f32_e64 v37, v39, v37
	v_mul_f32_e64 v4, v4, v92
	v_mul_f32_e64 v5, v5, v92
	v_fma_f32 v30, v30, v36, v30
	v_fma_f32 v31, v31, v37, v31
	v_fma_f32 v36, v38, s60, v44
	v_fma_f32 v37, v39, s60, v44
	v_and_b32_e32 v56, 1, v85
	v_fma_f32 v36, v38, v36, s62
	v_fma_f32 v37, v39, v37, s62
	v_mul_f32_e64 v4, v4, v52
	v_mul_f32_e64 v5, v5, v53
	v_fma_f32 v36, v38, v36, s64
	v_fma_f32 v37, v39, v37, s64
	v_and_b32_e32 v52, 1, v82
	v_and_b32_e32 v57, 1, v79
	v_fma_f32 v36, v38, v36, 1.0
	v_fma_f32 v37, v39, v37, 1.0
	v_cmp_eq_u32_e64 s[6:7], 0, v56
	v_and_b32_e32 v53, 1, v78
	v_cmp_eq_u32_e32 vcc, 0, v52
	v_cndmask_b32_e64 v31, v37, v31, s[6:7]
	v_cmp_eq_u32_e64 s[6:7], 0, v57
	v_mul_f32_e64 v68, v68, v92
	v_mul_f32_e64 v69, v69, v92
	v_cndmask_b32_e64 v29, -v29, v47, vcc
	v_cmp_eq_u32_e32 vcc, 0, v53
	v_cndmask_b32_e64 v30, v36, v30, s[6:7]
	v_mul_f32_e64 v72, v72, v92
	v_mul_f32_e64 v73, v73, v92
	v_mul_f32_e64 v64, v64, v68
	v_mul_f32_e64 v65, v65, v69
	v_mul_f32_e64 v68, v70, v92
	v_mul_f32_e64 v69, v71, v92
	v_cndmask_b32_e64 v28, -v28, v46, vcc
	v_cmp_class_f32_e64 vcc, v80, s65
	v_xor_b32_e32 v31, v42, v31
	v_xor_b32_e32 v30, v43, v30
	v_mul_f32_e64 v62, v62, v72
	v_mul_f32_e64 v63, v63, v73
	v_mul_f32_e64 v58, v58, v68
	v_mul_f32_e64 v59, v59, v69
	v_mul_f32_e64 v14, v14, v92
	v_mul_f32_e64 v15, v15, v92
	v_xor_b32_e32 v29, v60, v29
	v_xor_b32_e32 v28, v61, v28
	v_cndmask_b32_e32 v31, v160, v31, vcc
	v_cndmask_b32_e64 v30, v160, v30, s[4:5]
	v_mul_f32_e64 v14, v14, v34
	v_mul_f32_e64 v15, v15, v35
	v_mul_f32_e64 v34, v32, v32
	v_mul_f32_e64 v35, v33, v33
	v_cndmask_b32_e32 v29, v160, v29, vcc
	v_cndmask_b32_e64 v28, v160, v28, s[4:5]
	v_mul_f32_e64 v36, v58, v30
	v_mul_f32_e64 v37, v59, v31
	v_mul_f32_e64 v30, v62, v30
	v_mul_f32_e64 v31, v63, v31
	v_fma_f32 v36, v62, v28, -v36
	v_fma_f32 v37, v63, v29, -v37
	v_fma_f32 v28, v58, v28, v30
	v_fma_f32 v29, v59, v29, v31
	v_fma_f32 v30, v34, s60, v44
	v_fma_f32 v31, v35, s60, v44
	v_fma_f32 v38, v34, s22, v40
	v_fma_f32 v39, v35, s22, v40
	v_fma_f32 v30, v34, v30, s62
	v_fma_f32 v31, v35, v31, s62
	v_mul_f32_e64 v2, v2, v92
	v_mul_f32_e64 v3, v3, v92
	v_fma_f32 v30, v34, v30, s64
	v_fma_f32 v31, v35, v31, s64
	v_fma_f32 v38, v34, v38, s66
	v_fma_f32 v39, v35, v39, s66
	v_mul_f32_e64 v2, v2, v50
	v_mul_f32_e64 v3, v3, v51
	v_and_b32_e32 v50, 1, v90
	v_fma_f32 v30, v34, v30, 1.0
	v_fma_f32 v31, v35, v31, 1.0
	v_mul_f32_e64 v34, v34, v38
	v_mul_f32_e64 v35, v35, v39
	v_and_b32_e32 v51, 1, v86
	v_fma_f32 v32, v32, v34, v32
	v_fma_f32 v33, v33, v35, v33
	v_cmp_eq_u32_e32 vcc, 0, v50
	v_mul_f32_e64 v42, v66, v66
	v_mul_f32_e64 v43, v67, v67
	v_and_b32_e32 v52, 1, v91
	v_cndmask_b32_e64 v31, -v33, v31, vcc
	v_cmp_eq_u32_e32 vcc, 0, v51
	v_fma_f32 v34, v42, s60, v44
	v_fma_f32 v35, v43, s60, v44
	v_and_b32_e32 v53, 1, v87
	v_cndmask_b32_e64 v30, -v32, v30, vcc
	v_fma_f32 v32, v42, s22, v40
	v_fma_f32 v33, v43, s22, v40
	v_fma_f32 v34, v42, v34, s62
	v_fma_f32 v35, v43, v35, s62
	v_fma_f32 v32, v42, v32, s66
	v_fma_f32 v33, v43, v33, s66
	v_fma_f32 v34, v42, v34, s64
	v_fma_f32 v35, v43, v35, s64
	v_mul_f32_e64 v32, v42, v32
	v_mul_f32_e64 v33, v43, v33
	v_fma_f32 v34, v42, v34, 1.0
	v_fma_f32 v35, v43, v35, 1.0
	v_fma_f32 v32, v66, v32, v66
	v_fma_f32 v33, v67, v33, v67
	v_cmp_eq_u32_e64 s[6:7], 0, v52
	v_lshlrev_b32_e32 v46, 30, v91
	v_lshlrev_b32_e32 v47, 30, v87
	v_cndmask_b32_e64 v33, v35, v33, s[6:7]
	v_cmp_eq_u32_e64 s[6:7], 0, v53
	v_mul_f32_e64 v18, v18, v92
	v_mul_f32_e64 v19, v19, v92
	v_and_b32_e32 v35, 0x80000000, v47
	v_cndmask_b32_e64 v32, v34, v32, s[6:7]
	v_and_b32_e32 v34, 0x80000000, v46
	v_xor_b32_e32 v38, v89, v88
	v_xor_b32_e32 v39, v84, v83
	v_mul_f32_e64 v18, v18, v48
	v_mul_f32_e64 v19, v19, v49
	v_lshlrev_b32_e32 v48, 30, v90
	v_lshlrev_b32_e32 v49, 30, v86
	v_xor_b32_e32 v34, v38, v34
	v_xor_b32_e32 v35, v39, v35
	v_and_b32_e32 v48, 0x80000000, v48
	v_and_b32_e32 v49, 0x80000000, v49
	v_cmp_class_f32_e64 vcc, v88, s65
	v_cmp_class_f32_e64 s[4:5], v83, s65
	v_xor_b32_e32 v33, v34, v33
	v_xor_b32_e32 v32, v35, v32
	v_xor_b32_e32 v31, v48, v31
	v_xor_b32_e32 v30, v49, v30
	v_cndmask_b32_e32 v33, v160, v33, vcc
	v_cndmask_b32_e64 v32, v160, v32, s[4:5]
	v_cndmask_b32_e32 v31, v160, v31, vcc
	v_cndmask_b32_e64 v30, v160, v30, s[4:5]
	v_mul_f32_e64 v34, v24, v32
	v_mul_f32_e64 v35, v25, v33
	v_mul_f32_e64 v32, v64, v32
	v_mul_f32_e64 v33, v65, v33
	v_lshlrev_b32_e32 v98, 1, v104
	v_fma_f32 v34, v64, v30, -v34
	v_fma_f32 v35, v65, v31, -v35
	v_fma_f32 v24, v24, v30, v32
	v_fma_f32 v25, v25, v31, v33
	v_lshl_add_u64 v[30:31], v[76:77], 0, v[98:99]
	v_cvt_pk_bf16_f32 v2, v2, v3
	v_cvt_pk_bf16_f32 v3, v4, v5
	global_store_dwordx2 v[30:31], v[2:3], off offset:64
	v_cvt_pk_bf16_f32 v2, v6, v7
	v_cvt_pk_bf16_f32 v3, v8, v9
	global_store_dwordx2 v[30:31], v[2:3], off offset:80
	v_cvt_pk_bf16_f32 v2, v10, v11
	v_cvt_pk_bf16_f32 v3, v12, v13
	v_cvt_pk_bf16_f32 v32, v36, v37
	v_cvt_pk_bf16_f32 v33, v34, v35
	v_cvt_pk_bf16_f32 v28, v28, v29
	v_cvt_pk_bf16_f32 v29, v24, v25
	v_cvt_pk_bf16_f32 v24, v26, v27
	v_cvt_pk_bf16_f32 v25, v22, v23
	v_cvt_pk_bf16_f32 v20, v20, v21
	v_cvt_pk_bf16_f32 v21, v18, v19
	global_store_dwordx2 v[30:31], v[2:3], off offset:96
	v_cvt_pk_bf16_f32 v2, v14, v15
	v_cvt_pk_bf16_f32 v3, v16, v17
	global_store_dwordx2 v[30:31], v[32:33], off
	global_store_dwordx2 v[30:31], v[28:29], off offset:16
	global_store_dwordx2 v[30:31], v[24:25], off offset:32
	global_store_dwordx2 v[30:31], v[20:21], off offset:48
	global_store_dwordx2 v[30:31], v[2:3], off offset:112

.LBB0_945:
	s_and_b32 s4, s2, 0xffff
	s_mul_hi_u32 s5, s4, 0x38e38e4
	s_mulk_i32 s5, 0xffb8
	s_mul_i32 s6, s4, 0xe38f
	s_add_i32 s4, s2, s5
	s_lshr_b32 s5, s6, 19
	s_and_b32 s6, s5, 0x1ff8
	s_and_b32 s5, s2, 7
	s_ashr_i32 s4, s4, 3
	s_or_b32 s5, s5, s3
	s_add_i32 s6, s6, s5
	s_ashr_i32 s5, s4, 31
	s_lshl_b64 s[8:9], s[4:5], 18
	v_lshl_add_u64 v[144:145], v[100:101], 0, s[8:9]
	s_lshl_b32 s16, s6, 18
	s_movk_i32 s5, 0x2000
	v_lshl_add_u64 v[146:147], v[102:103], 0, s[16:17]
	v_add_co_u32_e32 v22, vcc, s5, v144
	v_lshl_add_u64 v[2:3], v[146:147], 0, v[136:137]
	v_lshl_add_u64 v[10:11], v[146:147], 0, v[138:139]
	v_addc_co_u32_e32 v23, vcc, 0, v145, vcc
	v_lshl_add_u64 v[18:19], v[146:147], 0, v[140:141]
	v_lshl_add_u64 v[26:27], v[146:147], 0, v[142:143]
	s_barrier
	global_load_dwordx4 v[2:5], v[2:3], off
	s_movk_i32 s5, 0x4000
	global_load_dwordx4 v[6:9], v[144:145], off
	global_load_dwordx4 v[14:17], v[22:23], off offset:-4096
	v_add_co_u32_e32 v34, vcc, s5, v144
	global_load_dwordx4 v[10:13], v[10:11], off
	s_nop 0
	v_addc_co_u32_e32 v35, vcc, 0, v145, vcc
	global_load_dwordx4 v[18:21], v[18:19], off
	s_mov_b64 s[8:9], 0x4000
	global_load_dwordx4 v[22:25], v[22:23], off
	s_movk_i32 s5, 0x6000
	global_load_dwordx4 v[26:29], v[26:27], off
	v_lshl_add_u32 v98, s6, 7, v115
	global_load_dwordx4 v[30:33], v[34:35], off offset:-4096
	s_waitcnt vmcnt(7)
	ds_write_b128 v105, v[2:5]
	s_waitcnt vmcnt(6)
	ds_write_b128 v105, v[6:9] offset:18432
	s_waitcnt vmcnt(5)
	ds_write_b128 v109, v[14:17] offset:18432
	global_load_dwordx4 v[6:9], v[34:35], off
	s_waitcnt vmcnt(5)
	ds_write_b128 v109, v[10:13]
	s_waitcnt vmcnt(4)
	ds_write_b128 v111, v[18:21]
	s_waitcnt vmcnt(3)
	ds_write_b128 v111, v[22:25] offset:18432
	v_add_co_u32_e32 v22, vcc, s5, v144
	s_waitcnt vmcnt(2)
	ds_write_b128 v113, v[26:29]
	v_lshl_add_u64 v[26:27], v[146:147], 0, s[8:9]
	v_lshl_add_u64 v[2:3], v[26:27], 0, v[136:137]
	global_load_dwordx4 v[2:5], v[2:3], off
	v_addc_co_u32_e32 v23, vcc, 0, v145, vcc
	s_mov_b32 s5, 0x8000
	v_add_co_u32_e32 v38, vcc, s5, v144
	v_lshl_add_u64 v[10:11], v[26:27], 0, v[138:139]
	v_lshl_add_u64 v[18:19], v[26:27], 0, v[140:141]
	v_lshl_add_u64 v[26:27], v[26:27], 0, v[142:143]
	v_addc_co_u32_e32 v39, vcc, 0, v145, vcc
	s_waitcnt vmcnt(2)
	ds_write_b128 v113, v[30:33] offset:18432
	global_load_dwordx4 v[10:13], v[10:11], off
	s_mov_b32 s5, 0xc000
	global_load_dwordx4 v[14:17], v[22:23], off offset:-4096
	global_load_dwordx4 v[30:33], v[38:39], off offset:-4096
	s_mov_b64 s[8:9], 0x8000
	global_load_dwordx4 v[18:21], v[18:19], off
	v_add_co_u32_e32 v148, vcc, s5, v144
	global_load_dwordx4 v[22:25], v[22:23], off
	s_nop 0
	v_addc_co_u32_e32 v149, vcc, 0, v145, vcc
	global_load_dwordx4 v[26:29], v[26:27], off
	s_waitcnt lgkmcnt(0)
	s_barrier
	ds_read_b128 v[150:153], v154 offset:18432
	ds_read_b128 v[34:37], v155
	s_waitcnt lgkmcnt(0)
	v_mfma_f32_32x32x16_bf16 v[50:65], v[150:153], v[34:37], 0
	ds_read_b128 v[162:165], v154 offset:23040
	ds_read_b128 v[168:171], v155 offset:4608
	global_load_dwordx4 v[90:93], v[38:39], off
	s_mov_b32 s5, 0xa000
	global_load_dwordx4 v[66:69], v[148:149], off offset:-4096
	s_waitcnt lgkmcnt(1)
	v_mfma_f32_32x32x16_bf16 v[34:49], v[162:165], v[34:37], 0
	s_waitcnt vmcnt(9)
	ds_write_b128 v105, v[6:9] offset:55296
	s_waitcnt vmcnt(8)
	ds_write_b128 v105, v[2:5] offset:36864
	v_lshl_add_u64 v[2:3], v[146:147], 0, s[8:9]
	v_lshl_add_u64 v[4:5], v[2:3], 0, v[142:143]
	global_load_dwordx4 v[70:73], v[4:5], off
	v_add_co_u32_e32 v4, vcc, s5, v144
	s_mov_b32 s5, 0x9000
	s_nop 0
	v_addc_co_u32_e32 v5, vcc, 0, v145, vcc
	global_load_dwordx4 v[74:77], v[4:5], off
	v_lshl_add_u64 v[4:5], v[2:3], 0, v[140:141]
	global_load_dwordx4 v[78:81], v[4:5], off
	v_add_co_u32_e32 v4, vcc, s5, v144
	s_waitcnt vmcnt(10)
	ds_write_b128 v109, v[10:13] offset:36864
	v_addc_co_u32_e32 v5, vcc, 0, v145, vcc
	global_load_dwordx4 v[82:85], v[4:5], off
	v_lshl_add_u64 v[4:5], v[2:3], 0, v[138:139]
	v_lshl_add_u64 v[2:3], v[2:3], 0, v[136:137]
	global_load_dwordx4 v[86:89], v[4:5], off
	global_load_dwordx4 v[94:97], v[2:3], off
	s_waitcnt vmcnt(12)
	ds_write_b128 v109, v[14:17] offset:55296
	s_waitcnt lgkmcnt(4)
	v_mfma_f32_32x32x16_bf16 v[2:17], v[162:165], v[168:171], 0
	s_waitcnt vmcnt(10)
	ds_write_b128 v111, v[18:21] offset:36864
	s_waitcnt vmcnt(9)
	ds_write_b128 v111, v[22:25] offset:55296
	s_waitcnt vmcnt(8)
	ds_write_b128 v113, v[26:29] offset:36864
	ds_write_b128 v113, v[30:33] offset:55296
	s_mov_b32 s5, 0x10000
	s_mov_b64 s[8:9], 0xc000
	v_mfma_f32_32x32x16_bf16 v[18:33], v[150:153], v[168:171], 0
	ds_read_b128 v[172:175], v117 offset:23072
	ds_read_b128 v[176:179], v119 offset:4640
	s_waitcnt lgkmcnt(0)
	v_mfma_f32_32x32x16_bf16 v[2:17], v[172:175], v[176:179], v[2:17]
	ds_read_b128 v[150:153], v117 offset:18464
	ds_read_b128 v[162:165], v117 offset:18496
	s_waitcnt lgkmcnt(1)
	v_mfma_f32_32x32x16_bf16 v[18:33], v[150:153], v[176:179], v[18:33]
	ds_read_b128 v[168:171], v119 offset:32
	ds_read_b128 v[180:183], v119 offset:64
	s_waitcnt lgkmcnt(1)
	v_mfma_f32_32x32x16_bf16 v[50:65], v[150:153], v[168:171], v[50:65]
	ds_read_b128 v[184:187], v117 offset:23104
	ds_read_b128 v[188:191], v119 offset:4672
	v_mfma_f32_32x32x16_bf16 v[34:49], v[172:175], v[168:171], v[34:49]
	ds_read_b128 v[150:153], v117 offset:18528
	ds_read_b128 v[168:171], v119 offset:96
	s_waitcnt lgkmcnt(4)
	v_mfma_f32_32x32x16_bf16 v[50:65], v[162:165], v[180:183], v[50:65]
	ds_read_b128 v[172:175], v117 offset:23136
	ds_read_b128 v[176:179], v119 offset:4704
	s_waitcnt lgkmcnt(0)
	s_barrier
	v_mfma_f32_32x32x16_bf16 v[34:49], v[184:187], v[180:183], v[34:49]
	ds_read_b128 v[180:183], v155 offset:36864
	v_mfma_f32_32x32x16_bf16 v[18:33], v[162:165], v[188:191], v[18:33]
	ds_read_b128 v[162:165], v154 offset:55296
	v_mfma_f32_32x32x16_bf16 v[2:17], v[184:187], v[188:191], v[2:17]
	ds_read_b128 v[184:187], v154 offset:59904
	ds_read_b128 v[188:191], v155 offset:41472
	v_mfma_f32_32x32x16_bf16 v[50:65], v[150:153], v[168:171], v[50:65]
	s_waitcnt vmcnt(7)
	ds_write_b128 v105, v[90:93] offset:18432
	v_add_co_u32_e32 v90, vcc, s5, v144
	s_mov_b32 s5, 0xe000
	s_nop 0
	v_addc_co_u32_e32 v91, vcc, 0, v145, vcc
	s_waitcnt vmcnt(0)
	ds_write_b128 v105, v[94:97]
	v_mfma_f32_32x32x16_bf16 v[34:49], v[172:175], v[168:171], v[34:49]
	ds_write_b128 v109, v[86:89]
	ds_write_b128 v109, v[82:85] offset:18432
	v_lshl_add_u64 v[96:97], v[146:147], 0, s[8:9]
	v_lshl_add_u64 v[86:87], v[96:97], 0, v[138:139]
	global_load_dwordx4 v[92:95], v[148:149], off
	s_mov_b64 s[8:9], 0x10000
	global_load_dwordx4 v[86:89], v[86:87], off
	v_mfma_f32_32x32x16_bf16 v[18:33], v[150:153], v[176:179], v[18:33]
	ds_write_b128 v111, v[74:77] offset:18432
	v_add_co_u32_e32 v74, vcc, s5, v144
	ds_write_b128 v111, v[78:81]
	s_nop 0
	v_addc_co_u32_e32 v75, vcc, 0, v145, vcc
	v_lshl_add_u64 v[78:79], v[96:97], 0, v[140:141]
	v_mfma_f32_32x32x16_bf16 v[2:17], v[172:175], v[176:179], v[2:17]
	ds_write_b128 v113, v[70:73]
	v_lshl_add_u64 v[70:71], v[96:97], 0, v[142:143]
	s_mov_b32 s5, 0xd000
	v_lshl_add_u64 v[96:97], v[96:97], 0, v[136:137]
	v_add_co_u32_e32 v82, vcc, s5, v144
	global_load_dwordx4 v[148:151], v[96:97], off
	s_nop 0
	v_addc_co_u32_e32 v83, vcc, 0, v145, vcc
	global_load_dwordx4 v[74:77], v[74:75], off
	ds_write_b128 v113, v[66:69] offset:18432
	global_load_dwordx4 v[82:85], v[82:83], off
	s_waitcnt lgkmcnt(10)
	v_mfma_f32_32x32x16_bf16 v[50:65], v[162:165], v[180:183], v[50:65]
	global_load_dwordx4 v[70:73], v[70:71], off
	ds_read_b128 v[168:171], v117 offset:59936
	global_load_dwordx4 v[78:81], v[78:79], off
	ds_read_b128 v[172:175], v119 offset:41504
	global_load_dwordx4 v[66:69], v[90:91], off offset:-4096
	s_mov_b32 s5, 0x14000
	s_waitcnt lgkmcnt(11)
	v_mfma_f32_32x32x16_bf16 v[34:49], v[184:187], v[180:183], v[34:49]
	ds_read_b128 v[176:179], v117 offset:55360
	ds_read_b128 v[180:183], v119 offset:36896
	s_waitcnt lgkmcnt(12)
	v_mfma_f32_32x32x16_bf16 v[18:33], v[162:165], v[188:191], v[18:33]
	ds_read_b128 v[162:165], v117 offset:55328
	ds_read_b128 v[192:195], v119 offset:41536
	v_mfma_f32_32x32x16_bf16 v[2:17], v[184:187], v[188:191], v[2:17]
	ds_read_b128 v[184:187], v119 offset:36928
	ds_read_b128 v[188:191], v117 offset:59968
	s_waitcnt lgkmcnt(3)
	v_mfma_f32_32x32x16_bf16 v[50:65], v[162:165], v[180:183], v[50:65]
	v_mfma_f32_32x32x16_bf16 v[34:49], v[168:171], v[180:183], v[34:49]
	ds_read_b128 v[180:183], v119 offset:41568
	v_mfma_f32_32x32x16_bf16 v[18:33], v[162:165], v[172:175], v[18:33]
	ds_read_b128 v[162:165], v117 offset:55392
	v_mfma_f32_32x32x16_bf16 v[2:17], v[168:171], v[172:175], v[2:17]
	ds_read_b128 v[168:171], v119 offset:36960
	ds_read_b128 v[172:175], v117 offset:60000
	s_waitcnt lgkmcnt(0)
	s_barrier
	v_mfma_f32_32x32x16_bf16 v[50:65], v[176:179], v[184:187], v[50:65]
	v_mfma_f32_32x32x16_bf16 v[34:49], v[188:191], v[184:187], v[34:49]
	ds_read_b128 v[184:187], v155
	v_mfma_f32_32x32x16_bf16 v[18:33], v[176:179], v[192:195], v[18:33]
	ds_read_b128 v[176:179], v154 offset:18432
	v_mfma_f32_32x32x16_bf16 v[2:17], v[188:191], v[192:195], v[2:17]
	ds_read_b128 v[188:191], v154 offset:23040
	ds_read_b128 v[192:195], v155 offset:4608
	v_mfma_f32_32x32x16_bf16 v[50:65], v[162:165], v[168:171], v[50:65]
	s_waitcnt vmcnt(5)
	ds_write_b128 v105, v[148:151] offset:36864
	v_add_co_u32_e32 v148, vcc, s5, v144
	s_mov_b32 s5, 0x12000
	s_nop 0
	v_addc_co_u32_e32 v149, vcc, 0, v145, vcc
	ds_write_b128 v105, v[92:95] offset:55296
	v_mfma_f32_32x32x16_bf16 v[34:49], v[172:175], v[168:171], v[34:49]
	ds_write_b128 v109, v[86:89] offset:36864
	s_waitcnt vmcnt(3)
	ds_write_b128 v109, v[82:85] offset:55296
	v_lshl_add_u64 v[94:95], v[146:147], 0, s[8:9]
	v_lshl_add_u64 v[86:87], v[94:95], 0, v[138:139]
	global_load_dwordx4 v[86:89], v[86:87], off
	s_mov_b64 s[8:9], 0x14000
	global_load_dwordx4 v[90:93], v[90:91], off
	v_mfma_f32_32x32x16_bf16 v[18:33], v[162:165], v[180:183], v[18:33]
	ds_write_b128 v111, v[74:77] offset:55296
	v_add_co_u32_e32 v74, vcc, s5, v144
	s_mov_b32 s5, 0x11000
	s_nop 0
	v_addc_co_u32_e32 v75, vcc, 0, v145, vcc
	v_add_co_u32_e32 v82, vcc, s5, v144
	s_waitcnt vmcnt(3)
	ds_write_b128 v111, v[78:81] offset:36864
	v_mfma_f32_32x32x16_bf16 v[2:17], v[172:175], v[180:183], v[2:17]
	ds_write_b128 v113, v[70:73] offset:36864
	v_lshl_add_u64 v[70:71], v[94:95], 0, v[142:143]
	v_lshl_add_u64 v[78:79], v[94:95], 0, v[140:141]
	v_addc_co_u32_e32 v83, vcc, 0, v145, vcc
	v_lshl_add_u64 v[94:95], v[94:95], 0, v[136:137]
	global_load_dwordx4 v[82:85], v[82:83], off
	s_waitcnt vmcnt(3)
	ds_write_b128 v113, v[66:69] offset:55296
	global_load_dwordx4 v[94:97], v[94:95], off
	s_waitcnt lgkmcnt(10)
	v_mfma_f32_32x32x16_bf16 v[50:65], v[176:179], v[184:187], v[50:65]
	global_load_dwordx4 v[74:77], v[74:75], off
	ds_read_b128 v[150:153], v117 offset:23072
	global_load_dwordx4 v[70:73], v[70:71], off
	ds_read_b128 v[162:165], v119 offset:4640
	global_load_dwordx4 v[78:81], v[78:79], off
	s_mov_b32 s5, 0x18000
	global_load_dwordx4 v[66:69], v[148:149], off offset:-4096
	s_waitcnt lgkmcnt(11)
	v_mfma_f32_32x32x16_bf16 v[34:49], v[188:191], v[184:187], v[34:49]
	ds_read_b128 v[168:171], v117 offset:18464
	ds_read_b128 v[172:175], v117 offset:18496
	s_waitcnt lgkmcnt(12)
	v_mfma_f32_32x32x16_bf16 v[18:33], v[176:179], v[192:195], v[18:33]
	ds_read_b128 v[176:179], v119 offset:32
	ds_read_b128 v[180:183], v119 offset:64
	v_mfma_f32_32x32x16_bf16 v[2:17], v[188:191], v[192:195], v[2:17]
	ds_read_b128 v[184:187], v117 offset:23104
	ds_read_b128 v[188:191], v119 offset:4672
	s_waitcnt lgkmcnt(3)
	v_mfma_f32_32x32x16_bf16 v[50:65], v[168:171], v[176:179], v[50:65]
	v_mfma_f32_32x32x16_bf16 v[34:49], v[150:153], v[176:179], v[34:49]
	ds_read_b128 v[176:179], v119 offset:4704
	v_mfma_f32_32x32x16_bf16 v[18:33], v[168:171], v[162:165], v[18:33]
	ds_read_b128 v[168:171], v117 offset:23136
	v_mfma_f32_32x32x16_bf16 v[2:17], v[150:153], v[162:165], v[2:17]
	ds_read_b128 v[150:153], v117 offset:18528
	ds_read_b128 v[162:165], v119 offset:96
	s_waitcnt lgkmcnt(0)
	s_barrier
	v_mfma_f32_32x32x16_bf16 v[50:65], v[172:175], v[180:183], v[50:65]
	v_mfma_f32_32x32x16_bf16 v[34:49], v[184:187], v[180:183], v[34:49]
	ds_read_b128 v[180:183], v155 offset:36864
	v_mfma_f32_32x32x16_bf16 v[18:33], v[172:175], v[188:191], v[18:33]
	ds_read_b128 v[172:175], v154 offset:55296
	v_mfma_f32_32x32x16_bf16 v[2:17], v[184:187], v[188:191], v[2:17]
	ds_read_b128 v[184:187], v154 offset:59904
	ds_read_b128 v[188:191], v155 offset:41472
	v_mfma_f32_32x32x16_bf16 v[50:65], v[150:153], v[162:165], v[50:65]
	s_waitcnt vmcnt(4)
	ds_write_b128 v105, v[94:97]
	ds_write_b128 v105, v[90:93] offset:18432
	v_lshl_add_u64 v[94:95], v[146:147], 0, s[8:9]
	global_load_dwordx4 v[90:93], v[148:149], off
	s_mov_b64 s[8:9], 0x18000
	v_mfma_f32_32x32x16_bf16 v[34:49], v[168:171], v[162:165], v[34:49]
	ds_write_b128 v109, v[86:89]
	ds_write_b128 v109, v[82:85] offset:18432
	v_lshl_add_u64 v[86:87], v[94:95], 0, v[138:139]
	global_load_dwordx4 v[86:89], v[86:87], off
	v_mfma_f32_32x32x16_bf16 v[18:33], v[150:153], v[176:179], v[18:33]
	v_add_co_u32_e32 v150, vcc, s5, v144
	s_mov_b32 s5, 0x16000
	s_nop 0
	v_addc_co_u32_e32 v151, vcc, 0, v145, vcc
	s_waitcnt vmcnt(5)
	ds_write_b128 v111, v[74:77] offset:18432
	v_add_co_u32_e32 v74, vcc, s5, v144
	s_mov_b32 s5, 0x15000
	s_nop 0
	v_addc_co_u32_e32 v75, vcc, 0, v145, vcc
	v_add_co_u32_e32 v82, vcc, s5, v144
	s_waitcnt vmcnt(3)
	ds_write_b128 v111, v[78:81]
	v_mfma_f32_32x32x16_bf16 v[2:17], v[168:171], v[176:179], v[2:17]
	ds_write_b128 v113, v[70:73]
	v_lshl_add_u64 v[70:71], v[94:95], 0, v[142:143]
	v_lshl_add_u64 v[78:79], v[94:95], 0, v[140:141]
	v_addc_co_u32_e32 v83, vcc, 0, v145, vcc
	v_lshl_add_u64 v[94:95], v[94:95], 0, v[136:137]
	global_load_dwordx4 v[74:77], v[74:75], off
	s_waitcnt vmcnt(3)
	ds_write_b128 v113, v[66:69] offset:18432
	global_load_dwordx4 v[82:85], v[82:83], off
	s_waitcnt lgkmcnt(10)
	v_mfma_f32_32x32x16_bf16 v[50:65], v[172:175], v[180:183], v[50:65]
	global_load_dwordx4 v[94:97], v[94:95], off
	ds_read_b128 v[162:165], v117 offset:59936
	global_load_dwordx4 v[70:73], v[70:71], off
	ds_read_b128 v[168:171], v119 offset:41504
	global_load_dwordx4 v[78:81], v[78:79], off
	s_mov_b32 s5, 0x1c000
	global_load_dwordx4 v[66:69], v[150:151], off offset:-4096
	s_waitcnt lgkmcnt(11)
	v_mfma_f32_32x32x16_bf16 v[34:49], v[184:187], v[180:183], v[34:49]
	ds_read_b128 v[176:179], v117 offset:55360
	ds_read_b128 v[180:183], v119 offset:36896
	v_add_co_u32_e32 v148, vcc, s5, v144
	s_mov_b32 s5, 0x1a000
	s_nop 0
	v_addc_co_u32_e32 v149, vcc, 0, v145, vcc
	s_waitcnt lgkmcnt(12)
	v_mfma_f32_32x32x16_bf16 v[18:33], v[172:175], v[188:191], v[18:33]
	ds_read_b128 v[172:175], v117 offset:55328
	ds_read_b128 v[192:195], v119 offset:41536
	v_mfma_f32_32x32x16_bf16 v[2:17], v[184:187], v[188:191], v[2:17]
	ds_read_b128 v[188:191], v117 offset:59968
	ds_read_b128 v[184:187], v119 offset:36928
	s_waitcnt lgkmcnt(3)
	v_mfma_f32_32x32x16_bf16 v[50:65], v[172:175], v[180:183], v[50:65]
	v_mfma_f32_32x32x16_bf16 v[34:49], v[162:165], v[180:183], v[34:49]
	ds_read_b128 v[180:183], v119 offset:41568
	v_mfma_f32_32x32x16_bf16 v[18:33], v[172:175], v[168:171], v[18:33]
	ds_read_b128 v[172:175], v117 offset:60000
	v_mfma_f32_32x32x16_bf16 v[2:17], v[162:165], v[168:171], v[2:17]
	ds_read_b128 v[162:165], v117 offset:55392
	ds_read_b128 v[168:171], v119 offset:36960
	s_waitcnt lgkmcnt(0)
	s_barrier
	v_mfma_f32_32x32x16_bf16 v[50:65], v[176:179], v[184:187], v[50:65]
	v_mfma_f32_32x32x16_bf16 v[34:49], v[188:191], v[184:187], v[34:49]
	ds_read_b128 v[184:187], v155
	v_mfma_f32_32x32x16_bf16 v[18:33], v[176:179], v[192:195], v[18:33]
	ds_read_b128 v[176:179], v154 offset:18432
	v_mfma_f32_32x32x16_bf16 v[2:17], v[188:191], v[192:195], v[2:17]
	ds_read_b128 v[188:191], v154 offset:23040
	ds_read_b128 v[192:195], v155 offset:4608
	v_mfma_f32_32x32x16_bf16 v[50:65], v[162:165], v[168:171], v[50:65]
	s_waitcnt vmcnt(3)
	ds_write_b128 v105, v[94:97] offset:36864
	ds_write_b128 v105, v[90:93] offset:55296
	v_lshl_add_u64 v[94:95], v[146:147], 0, s[8:9]
	global_load_dwordx4 v[90:93], v[150:151], off
	s_mov_b64 s[8:9], 0x1c000
	v_mfma_f32_32x32x16_bf16 v[34:49], v[172:175], v[168:171], v[34:49]
	ds_write_b128 v109, v[86:89] offset:36864
	ds_write_b128 v109, v[82:85] offset:55296
	v_lshl_add_u64 v[86:87], v[94:95], 0, v[138:139]
	global_load_dwordx4 v[86:89], v[86:87], off
	v_mfma_f32_32x32x16_bf16 v[18:33], v[162:165], v[180:183], v[18:33]
	ds_write_b128 v111, v[74:77] offset:55296
	v_add_co_u32_e32 v74, vcc, s5, v144
	s_mov_b32 s5, 0x19000
	s_nop 0
	v_addc_co_u32_e32 v75, vcc, 0, v145, vcc
	v_add_co_u32_e32 v82, vcc, s5, v144
	s_waitcnt vmcnt(3)
	ds_write_b128 v111, v[78:81] offset:36864
	v_mfma_f32_32x32x16_bf16 v[2:17], v[172:175], v[180:183], v[2:17]
	ds_write_b128 v113, v[70:73] offset:36864
	v_lshl_add_u64 v[70:71], v[94:95], 0, v[142:143]
	v_lshl_add_u64 v[78:79], v[94:95], 0, v[140:141]
	v_addc_co_u32_e32 v83, vcc, 0, v145, vcc
	v_lshl_add_u64 v[94:95], v[94:95], 0, v[136:137]
	global_load_dwordx4 v[82:85], v[82:83], off
	s_waitcnt vmcnt(3)
	ds_write_b128 v113, v[66:69] offset:55296
	global_load_dwordx4 v[94:97], v[94:95], off
	s_waitcnt lgkmcnt(10)
	v_mfma_f32_32x32x16_bf16 v[50:65], v[176:179], v[184:187], v[50:65]
	global_load_dwordx4 v[74:77], v[74:75], off
	ds_read_b128 v[150:153], v117 offset:23072
	global_load_dwordx4 v[70:73], v[70:71], off
	ds_read_b128 v[162:165], v119 offset:4640
	global_load_dwordx4 v[78:81], v[78:79], off
	s_mov_b32 s5, 0x20000
	global_load_dwordx4 v[66:69], v[148:149], off offset:-4096
	s_waitcnt lgkmcnt(11)
	v_mfma_f32_32x32x16_bf16 v[34:49], v[188:191], v[184:187], v[34:49]
	ds_read_b128 v[168:171], v117 offset:18464
	ds_read_b128 v[172:175], v117 offset:18496
	s_waitcnt lgkmcnt(12)
	v_mfma_f32_32x32x16_bf16 v[18:33], v[176:179], v[192:195], v[18:33]
	ds_read_b128 v[176:179], v119 offset:32
	ds_read_b128 v[180:183], v119 offset:64
	v_mfma_f32_32x32x16_bf16 v[2:17], v[188:191], v[192:195], v[2:17]
	ds_read_b128 v[184:187], v117 offset:23104
	ds_read_b128 v[188:191], v119 offset:4672
	s_waitcnt lgkmcnt(3)
	v_mfma_f32_32x32x16_bf16 v[50:65], v[168:171], v[176:179], v[50:65]
	v_mfma_f32_32x32x16_bf16 v[34:49], v[150:153], v[176:179], v[34:49]
	ds_read_b128 v[176:179], v119 offset:4704
	v_mfma_f32_32x32x16_bf16 v[18:33], v[168:171], v[162:165], v[18:33]
	ds_read_b128 v[168:171], v117 offset:23136
	v_mfma_f32_32x32x16_bf16 v[2:17], v[150:153], v[162:165], v[2:17]
	ds_read_b128 v[150:153], v117 offset:18528
	ds_read_b128 v[162:165], v119 offset:96
	s_waitcnt lgkmcnt(0)
	s_barrier
	v_mfma_f32_32x32x16_bf16 v[50:65], v[172:175], v[180:183], v[50:65]
	v_mfma_f32_32x32x16_bf16 v[34:49], v[184:187], v[180:183], v[34:49]
	ds_read_b128 v[180:183], v155 offset:36864
	v_mfma_f32_32x32x16_bf16 v[18:33], v[172:175], v[188:191], v[18:33]
	ds_read_b128 v[172:175], v154 offset:55296
	v_mfma_f32_32x32x16_bf16 v[2:17], v[184:187], v[188:191], v[2:17]
	ds_read_b128 v[184:187], v154 offset:59904
	ds_read_b128 v[188:191], v155 offset:41472
	v_mfma_f32_32x32x16_bf16 v[50:65], v[150:153], v[162:165], v[50:65]
	s_waitcnt vmcnt(4)
	ds_write_b128 v105, v[94:97]
	ds_write_b128 v105, v[90:93] offset:18432
	v_lshl_add_u64 v[94:95], v[146:147], 0, s[8:9]
	global_load_dwordx4 v[90:93], v[148:149], off
	s_mov_b64 s[8:9], 0x20000
	v_mfma_f32_32x32x16_bf16 v[34:49], v[168:171], v[162:165], v[34:49]
	ds_write_b128 v109, v[86:89]
	ds_write_b128 v109, v[82:85] offset:18432
	v_lshl_add_u64 v[86:87], v[94:95], 0, v[138:139]
	global_load_dwordx4 v[86:89], v[86:87], off
	v_mfma_f32_32x32x16_bf16 v[18:33], v[150:153], v[176:179], v[18:33]
	v_add_co_u32_e32 v150, vcc, s5, v144
	s_mov_b32 s5, 0x1e000
	s_nop 0
	v_addc_co_u32_e32 v151, vcc, 0, v145, vcc
	s_waitcnt vmcnt(5)
	ds_write_b128 v111, v[74:77] offset:18432
	v_add_co_u32_e32 v74, vcc, s5, v144
	s_mov_b32 s5, 0x1d000
	s_nop 0
	v_addc_co_u32_e32 v75, vcc, 0, v145, vcc
	v_add_co_u32_e32 v82, vcc, s5, v144
	s_waitcnt vmcnt(3)
	ds_write_b128 v111, v[78:81]
	v_mfma_f32_32x32x16_bf16 v[2:17], v[168:171], v[176:179], v[2:17]
	ds_write_b128 v113, v[70:73]
	v_lshl_add_u64 v[70:71], v[94:95], 0, v[142:143]
	v_lshl_add_u64 v[78:79], v[94:95], 0, v[140:141]
	v_addc_co_u32_e32 v83, vcc, 0, v145, vcc
	v_lshl_add_u64 v[94:95], v[94:95], 0, v[136:137]
	global_load_dwordx4 v[74:77], v[74:75], off
	s_waitcnt vmcnt(3)
	ds_write_b128 v113, v[66:69] offset:18432
	global_load_dwordx4 v[82:85], v[82:83], off
	s_waitcnt lgkmcnt(10)
	v_mfma_f32_32x32x16_bf16 v[50:65], v[172:175], v[180:183], v[50:65]
	global_load_dwordx4 v[94:97], v[94:95], off
	ds_read_b128 v[162:165], v117 offset:59936
	global_load_dwordx4 v[70:73], v[70:71], off
	ds_read_b128 v[168:171], v119 offset:41504
	global_load_dwordx4 v[78:81], v[78:79], off
	s_mov_b32 s5, 0x24000
	global_load_dwordx4 v[66:69], v[150:151], off offset:-4096
	s_waitcnt lgkmcnt(11)
	v_mfma_f32_32x32x16_bf16 v[34:49], v[184:187], v[180:183], v[34:49]
	ds_read_b128 v[176:179], v117 offset:55360
	ds_read_b128 v[180:183], v119 offset:36896
	v_add_co_u32_e32 v148, vcc, s5, v144
	s_mov_b32 s5, 0x22000
	s_nop 0
	v_addc_co_u32_e32 v149, vcc, 0, v145, vcc
	s_waitcnt lgkmcnt(12)
	v_mfma_f32_32x32x16_bf16 v[18:33], v[172:175], v[188:191], v[18:33]
	ds_read_b128 v[172:175], v117 offset:55328
	ds_read_b128 v[192:195], v119 offset:41536
	v_mfma_f32_32x32x16_bf16 v[2:17], v[184:187], v[188:191], v[2:17]
	ds_read_b128 v[188:191], v117 offset:59968
	ds_read_b128 v[184:187], v119 offset:36928
	s_waitcnt lgkmcnt(3)
	v_mfma_f32_32x32x16_bf16 v[50:65], v[172:175], v[180:183], v[50:65]
	v_mfma_f32_32x32x16_bf16 v[34:49], v[162:165], v[180:183], v[34:49]
	ds_read_b128 v[180:183], v119 offset:41568
	v_mfma_f32_32x32x16_bf16 v[18:33], v[172:175], v[168:171], v[18:33]
	ds_read_b128 v[172:175], v117 offset:60000
	v_mfma_f32_32x32x16_bf16 v[2:17], v[162:165], v[168:171], v[2:17]
	ds_read_b128 v[162:165], v117 offset:55392
	ds_read_b128 v[168:171], v119 offset:36960
	s_waitcnt lgkmcnt(0)
	s_barrier
	v_mfma_f32_32x32x16_bf16 v[50:65], v[176:179], v[184:187], v[50:65]
	v_mfma_f32_32x32x16_bf16 v[34:49], v[188:191], v[184:187], v[34:49]
	ds_read_b128 v[184:187], v155
	v_mfma_f32_32x32x16_bf16 v[18:33], v[176:179], v[192:195], v[18:33]
	ds_read_b128 v[176:179], v154 offset:18432
	v_mfma_f32_32x32x16_bf16 v[2:17], v[188:191], v[192:195], v[2:17]
	ds_read_b128 v[188:191], v154 offset:23040
	ds_read_b128 v[192:195], v155 offset:4608
	v_mfma_f32_32x32x16_bf16 v[50:65], v[162:165], v[168:171], v[50:65]
	s_waitcnt vmcnt(3)
	ds_write_b128 v105, v[94:97] offset:36864
	ds_write_b128 v105, v[90:93] offset:55296
	v_lshl_add_u64 v[94:95], v[146:147], 0, s[8:9]
	global_load_dwordx4 v[90:93], v[150:151], off
	s_mov_b64 s[8:9], 0x24000
	v_mfma_f32_32x32x16_bf16 v[34:49], v[172:175], v[168:171], v[34:49]
	ds_write_b128 v109, v[86:89] offset:36864
	ds_write_b128 v109, v[82:85] offset:55296
	v_lshl_add_u64 v[86:87], v[94:95], 0, v[138:139]
	global_load_dwordx4 v[86:89], v[86:87], off
	v_mfma_f32_32x32x16_bf16 v[18:33], v[162:165], v[180:183], v[18:33]
	ds_write_b128 v111, v[74:77] offset:55296
	v_add_co_u32_e32 v74, vcc, s5, v144
	s_mov_b32 s5, 0x21000
	s_nop 0
	v_addc_co_u32_e32 v75, vcc, 0, v145, vcc
	v_add_co_u32_e32 v82, vcc, s5, v144
	s_waitcnt vmcnt(3)
	ds_write_b128 v111, v[78:81] offset:36864
	v_mfma_f32_32x32x16_bf16 v[2:17], v[172:175], v[180:183], v[2:17]
	ds_write_b128 v113, v[70:73] offset:36864
	v_lshl_add_u64 v[70:71], v[94:95], 0, v[142:143]
	v_lshl_add_u64 v[78:79], v[94:95], 0, v[140:141]
	v_addc_co_u32_e32 v83, vcc, 0, v145, vcc
	v_lshl_add_u64 v[94:95], v[94:95], 0, v[136:137]
	global_load_dwordx4 v[82:85], v[82:83], off
	s_waitcnt vmcnt(3)
	ds_write_b128 v113, v[66:69] offset:55296
	global_load_dwordx4 v[94:97], v[94:95], off
	s_waitcnt lgkmcnt(10)
	v_mfma_f32_32x32x16_bf16 v[50:65], v[176:179], v[184:187], v[50:65]
	global_load_dwordx4 v[74:77], v[74:75], off
	ds_read_b128 v[150:153], v117 offset:23072
	global_load_dwordx4 v[70:73], v[70:71], off
	ds_read_b128 v[162:165], v119 offset:4640
	global_load_dwordx4 v[78:81], v[78:79], off
	s_mov_b32 s5, 0x28000
	global_load_dwordx4 v[66:69], v[148:149], off offset:-4096
	s_waitcnt lgkmcnt(11)
	v_mfma_f32_32x32x16_bf16 v[34:49], v[188:191], v[184:187], v[34:49]
	ds_read_b128 v[168:171], v117 offset:18464
	ds_read_b128 v[172:175], v117 offset:18496
	s_waitcnt lgkmcnt(12)
	v_mfma_f32_32x32x16_bf16 v[18:33], v[176:179], v[192:195], v[18:33]
	ds_read_b128 v[176:179], v119 offset:32
	ds_read_b128 v[180:183], v119 offset:64
	v_mfma_f32_32x32x16_bf16 v[2:17], v[188:191], v[192:195], v[2:17]
	ds_read_b128 v[184:187], v117 offset:23104
	ds_read_b128 v[188:191], v119 offset:4672
	s_waitcnt lgkmcnt(3)
	v_mfma_f32_32x32x16_bf16 v[50:65], v[168:171], v[176:179], v[50:65]
	v_mfma_f32_32x32x16_bf16 v[34:49], v[150:153], v[176:179], v[34:49]
	ds_read_b128 v[176:179], v119 offset:4704
	v_mfma_f32_32x32x16_bf16 v[18:33], v[168:171], v[162:165], v[18:33]
	ds_read_b128 v[168:171], v117 offset:23136
	v_mfma_f32_32x32x16_bf16 v[2:17], v[150:153], v[162:165], v[2:17]
	ds_read_b128 v[150:153], v117 offset:18528
	ds_read_b128 v[162:165], v119 offset:96
	s_waitcnt lgkmcnt(0)
	s_barrier
	v_mfma_f32_32x32x16_bf16 v[50:65], v[172:175], v[180:183], v[50:65]
	v_mfma_f32_32x32x16_bf16 v[34:49], v[184:187], v[180:183], v[34:49]
	ds_read_b128 v[180:183], v155 offset:36864
	v_mfma_f32_32x32x16_bf16 v[18:33], v[172:175], v[188:191], v[18:33]
	ds_read_b128 v[172:175], v154 offset:55296
	v_mfma_f32_32x32x16_bf16 v[2:17], v[184:187], v[188:191], v[2:17]
	ds_read_b128 v[184:187], v154 offset:59904
	ds_read_b128 v[188:191], v155 offset:41472
	v_mfma_f32_32x32x16_bf16 v[50:65], v[150:153], v[162:165], v[50:65]
	s_waitcnt vmcnt(4)
	ds_write_b128 v105, v[94:97]
	ds_write_b128 v105, v[90:93] offset:18432
	v_lshl_add_u64 v[94:95], v[146:147], 0, s[8:9]
	global_load_dwordx4 v[90:93], v[148:149], off
	s_mov_b64 s[8:9], 0x28000
	v_mfma_f32_32x32x16_bf16 v[34:49], v[168:171], v[162:165], v[34:49]
	ds_write_b128 v109, v[86:89]
	ds_write_b128 v109, v[82:85] offset:18432
	v_lshl_add_u64 v[86:87], v[94:95], 0, v[138:139]
	global_load_dwordx4 v[86:89], v[86:87], off
	v_mfma_f32_32x32x16_bf16 v[18:33], v[150:153], v[176:179], v[18:33]
	v_add_co_u32_e32 v150, vcc, s5, v144
	s_mov_b32 s5, 0x26000
	s_nop 0
	v_addc_co_u32_e32 v151, vcc, 0, v145, vcc
	s_waitcnt vmcnt(5)
	ds_write_b128 v111, v[74:77] offset:18432
	v_add_co_u32_e32 v74, vcc, s5, v144
	s_mov_b32 s5, 0x25000
	s_nop 0
	v_addc_co_u32_e32 v75, vcc, 0, v145, vcc
	v_add_co_u32_e32 v82, vcc, s5, v144
	s_waitcnt vmcnt(3)
	ds_write_b128 v111, v[78:81]
	v_mfma_f32_32x32x16_bf16 v[2:17], v[168:171], v[176:179], v[2:17]
	ds_write_b128 v113, v[70:73]
	v_lshl_add_u64 v[70:71], v[94:95], 0, v[142:143]
	v_lshl_add_u64 v[78:79], v[94:95], 0, v[140:141]
	v_addc_co_u32_e32 v83, vcc, 0, v145, vcc
	v_lshl_add_u64 v[94:95], v[94:95], 0, v[136:137]
	global_load_dwordx4 v[74:77], v[74:75], off
	s_waitcnt vmcnt(3)
	ds_write_b128 v113, v[66:69] offset:18432
	global_load_dwordx4 v[82:85], v[82:83], off
	s_waitcnt lgkmcnt(10)
	v_mfma_f32_32x32x16_bf16 v[50:65], v[172:175], v[180:183], v[50:65]
	global_load_dwordx4 v[94:97], v[94:95], off
	ds_read_b128 v[162:165], v117 offset:59936
	global_load_dwordx4 v[70:73], v[70:71], off
	ds_read_b128 v[168:171], v119 offset:41504
	global_load_dwordx4 v[78:81], v[78:79], off
	s_mov_b32 s5, 0x2c000
	global_load_dwordx4 v[66:69], v[150:151], off offset:-4096
	s_waitcnt lgkmcnt(11)
	v_mfma_f32_32x32x16_bf16 v[34:49], v[184:187], v[180:183], v[34:49]
	ds_read_b128 v[176:179], v117 offset:55360
	ds_read_b128 v[180:183], v119 offset:36896
	v_add_co_u32_e32 v148, vcc, s5, v144
	s_mov_b32 s5, 0x2a000
	s_nop 0
	v_addc_co_u32_e32 v149, vcc, 0, v145, vcc
	s_waitcnt lgkmcnt(12)
	v_mfma_f32_32x32x16_bf16 v[18:33], v[172:175], v[188:191], v[18:33]
	ds_read_b128 v[172:175], v117 offset:55328
	ds_read_b128 v[192:195], v119 offset:41536
	v_mfma_f32_32x32x16_bf16 v[2:17], v[184:187], v[188:191], v[2:17]
	ds_read_b128 v[188:191], v117 offset:59968
	ds_read_b128 v[184:187], v119 offset:36928
	s_waitcnt lgkmcnt(3)
	v_mfma_f32_32x32x16_bf16 v[50:65], v[172:175], v[180:183], v[50:65]
	v_mfma_f32_32x32x16_bf16 v[34:49], v[162:165], v[180:183], v[34:49]
	ds_read_b128 v[180:183], v119 offset:41568
	v_mfma_f32_32x32x16_bf16 v[18:33], v[172:175], v[168:171], v[18:33]
	ds_read_b128 v[172:175], v117 offset:60000
	v_mfma_f32_32x32x16_bf16 v[2:17], v[162:165], v[168:171], v[2:17]
	ds_read_b128 v[162:165], v117 offset:55392
	ds_read_b128 v[168:171], v119 offset:36960
	s_waitcnt lgkmcnt(0)
	s_barrier
	v_mfma_f32_32x32x16_bf16 v[50:65], v[176:179], v[184:187], v[50:65]
	v_mfma_f32_32x32x16_bf16 v[34:49], v[188:191], v[184:187], v[34:49]
	ds_read_b128 v[184:187], v155
	v_mfma_f32_32x32x16_bf16 v[18:33], v[176:179], v[192:195], v[18:33]
	ds_read_b128 v[176:179], v154 offset:18432
	v_mfma_f32_32x32x16_bf16 v[2:17], v[188:191], v[192:195], v[2:17]
	ds_read_b128 v[188:191], v154 offset:23040
	ds_read_b128 v[192:195], v155 offset:4608
	v_mfma_f32_32x32x16_bf16 v[50:65], v[162:165], v[168:171], v[50:65]
	s_waitcnt vmcnt(3)
	ds_write_b128 v105, v[94:97] offset:36864
	ds_write_b128 v105, v[90:93] offset:55296
	v_lshl_add_u64 v[94:95], v[146:147], 0, s[8:9]
	global_load_dwordx4 v[90:93], v[150:151], off
	s_mov_b64 s[8:9], 0x2c000
	v_mfma_f32_32x32x16_bf16 v[34:49], v[172:175], v[168:171], v[34:49]
	ds_write_b128 v109, v[86:89] offset:36864
	ds_write_b128 v109, v[82:85] offset:55296
	v_lshl_add_u64 v[86:87], v[94:95], 0, v[138:139]
	global_load_dwordx4 v[86:89], v[86:87], off
	v_mfma_f32_32x32x16_bf16 v[18:33], v[162:165], v[180:183], v[18:33]
	ds_write_b128 v111, v[74:77] offset:55296
	v_add_co_u32_e32 v74, vcc, s5, v144
	s_mov_b32 s5, 0x29000
	s_nop 0
	v_addc_co_u32_e32 v75, vcc, 0, v145, vcc
	v_add_co_u32_e32 v82, vcc, s5, v144
	s_waitcnt vmcnt(3)
	ds_write_b128 v111, v[78:81] offset:36864
	v_mfma_f32_32x32x16_bf16 v[2:17], v[172:175], v[180:183], v[2:17]
	ds_write_b128 v113, v[70:73] offset:36864
	v_lshl_add_u64 v[70:71], v[94:95], 0, v[142:143]
	v_lshl_add_u64 v[78:79], v[94:95], 0, v[140:141]
	v_addc_co_u32_e32 v83, vcc, 0, v145, vcc
	v_lshl_add_u64 v[94:95], v[94:95], 0, v[136:137]
	global_load_dwordx4 v[82:85], v[82:83], off
	s_waitcnt vmcnt(3)
	ds_write_b128 v113, v[66:69] offset:55296
	global_load_dwordx4 v[94:97], v[94:95], off
	s_waitcnt lgkmcnt(10)
	v_mfma_f32_32x32x16_bf16 v[50:65], v[176:179], v[184:187], v[50:65]
	global_load_dwordx4 v[74:77], v[74:75], off
	ds_read_b128 v[150:153], v117 offset:23072
	global_load_dwordx4 v[70:73], v[70:71], off
	ds_read_b128 v[162:165], v119 offset:4640
	global_load_dwordx4 v[78:81], v[78:79], off
	s_mov_b32 s5, 0x30000
	global_load_dwordx4 v[66:69], v[148:149], off offset:-4096
	s_waitcnt lgkmcnt(11)
	v_mfma_f32_32x32x16_bf16 v[34:49], v[188:191], v[184:187], v[34:49]
	ds_read_b128 v[168:171], v117 offset:18464
	ds_read_b128 v[172:175], v117 offset:18496
	s_waitcnt lgkmcnt(12)
	v_mfma_f32_32x32x16_bf16 v[18:33], v[176:179], v[192:195], v[18:33]
	ds_read_b128 v[176:179], v119 offset:32
	ds_read_b128 v[180:183], v119 offset:64
	v_mfma_f32_32x32x16_bf16 v[2:17], v[188:191], v[192:195], v[2:17]
	ds_read_b128 v[184:187], v117 offset:23104
	ds_read_b128 v[188:191], v119 offset:4672
	s_waitcnt lgkmcnt(3)
	v_mfma_f32_32x32x16_bf16 v[50:65], v[168:171], v[176:179], v[50:65]
	v_mfma_f32_32x32x16_bf16 v[34:49], v[150:153], v[176:179], v[34:49]
	ds_read_b128 v[176:179], v119 offset:4704
	v_mfma_f32_32x32x16_bf16 v[18:33], v[168:171], v[162:165], v[18:33]
	ds_read_b128 v[168:171], v117 offset:23136
	v_mfma_f32_32x32x16_bf16 v[2:17], v[150:153], v[162:165], v[2:17]
	ds_read_b128 v[150:153], v117 offset:18528
	ds_read_b128 v[162:165], v119 offset:96
	s_waitcnt lgkmcnt(0)
	s_barrier
	v_mfma_f32_32x32x16_bf16 v[50:65], v[172:175], v[180:183], v[50:65]
	v_mfma_f32_32x32x16_bf16 v[34:49], v[184:187], v[180:183], v[34:49]
	ds_read_b128 v[180:183], v155 offset:36864
	v_mfma_f32_32x32x16_bf16 v[18:33], v[172:175], v[188:191], v[18:33]
	ds_read_b128 v[172:175], v154 offset:55296
	v_mfma_f32_32x32x16_bf16 v[2:17], v[184:187], v[188:191], v[2:17]
	ds_read_b128 v[184:187], v154 offset:59904
	ds_read_b128 v[188:191], v155 offset:41472
	v_mfma_f32_32x32x16_bf16 v[50:65], v[150:153], v[162:165], v[50:65]
	s_waitcnt vmcnt(4)
	ds_write_b128 v105, v[94:97]
	ds_write_b128 v105, v[90:93] offset:18432
	v_lshl_add_u64 v[94:95], v[146:147], 0, s[8:9]
	global_load_dwordx4 v[90:93], v[148:149], off
	s_mov_b64 s[8:9], 0x30000
	v_mfma_f32_32x32x16_bf16 v[34:49], v[168:171], v[162:165], v[34:49]
	ds_write_b128 v109, v[86:89]
	ds_write_b128 v109, v[82:85] offset:18432
	v_lshl_add_u64 v[86:87], v[94:95], 0, v[138:139]
	global_load_dwordx4 v[86:89], v[86:87], off
	v_mfma_f32_32x32x16_bf16 v[18:33], v[150:153], v[176:179], v[18:33]
	v_add_co_u32_e32 v150, vcc, s5, v144
	s_mov_b32 s5, 0x2e000
	s_nop 0
	v_addc_co_u32_e32 v151, vcc, 0, v145, vcc
	s_waitcnt vmcnt(5)
	ds_write_b128 v111, v[74:77] offset:18432
	v_add_co_u32_e32 v74, vcc, s5, v144
	s_mov_b32 s5, 0x2d000
	s_nop 0
	v_addc_co_u32_e32 v75, vcc, 0, v145, vcc
	v_add_co_u32_e32 v82, vcc, s5, v144
	s_waitcnt vmcnt(3)
	ds_write_b128 v111, v[78:81]
	v_mfma_f32_32x32x16_bf16 v[2:17], v[168:171], v[176:179], v[2:17]
	ds_write_b128 v113, v[70:73]
	v_lshl_add_u64 v[70:71], v[94:95], 0, v[142:143]
	v_lshl_add_u64 v[78:79], v[94:95], 0, v[140:141]
	v_addc_co_u32_e32 v83, vcc, 0, v145, vcc
	v_lshl_add_u64 v[94:95], v[94:95], 0, v[136:137]
	global_load_dwordx4 v[74:77], v[74:75], off
	s_waitcnt vmcnt(3)
	ds_write_b128 v113, v[66:69] offset:18432
	global_load_dwordx4 v[82:85], v[82:83], off
	s_waitcnt lgkmcnt(10)
	v_mfma_f32_32x32x16_bf16 v[50:65], v[172:175], v[180:183], v[50:65]
	global_load_dwordx4 v[94:97], v[94:95], off
	ds_read_b128 v[162:165], v117 offset:59936
	global_load_dwordx4 v[70:73], v[70:71], off
	ds_read_b128 v[168:171], v119 offset:41504
	global_load_dwordx4 v[78:81], v[78:79], off
	s_mov_b32 s5, 0x34000
	global_load_dwordx4 v[66:69], v[150:151], off offset:-4096
	s_waitcnt lgkmcnt(11)
	v_mfma_f32_32x32x16_bf16 v[34:49], v[184:187], v[180:183], v[34:49]
	ds_read_b128 v[176:179], v117 offset:55360
	ds_read_b128 v[180:183], v119 offset:36896
	v_add_co_u32_e32 v148, vcc, s5, v144
	s_mov_b32 s5, 0x32000
	s_nop 0
	v_addc_co_u32_e32 v149, vcc, 0, v145, vcc
	s_waitcnt lgkmcnt(12)
	v_mfma_f32_32x32x16_bf16 v[18:33], v[172:175], v[188:191], v[18:33]
	ds_read_b128 v[172:175], v117 offset:55328
	ds_read_b128 v[192:195], v119 offset:41536
	v_mfma_f32_32x32x16_bf16 v[2:17], v[184:187], v[188:191], v[2:17]
	ds_read_b128 v[188:191], v117 offset:59968
	ds_read_b128 v[184:187], v119 offset:36928
	s_waitcnt lgkmcnt(3)
	v_mfma_f32_32x32x16_bf16 v[50:65], v[172:175], v[180:183], v[50:65]
	v_mfma_f32_32x32x16_bf16 v[34:49], v[162:165], v[180:183], v[34:49]
	ds_read_b128 v[180:183], v119 offset:41568
	v_mfma_f32_32x32x16_bf16 v[18:33], v[172:175], v[168:171], v[18:33]
	ds_read_b128 v[172:175], v117 offset:60000
	v_mfma_f32_32x32x16_bf16 v[2:17], v[162:165], v[168:171], v[2:17]
	ds_read_b128 v[162:165], v117 offset:55392
	ds_read_b128 v[168:171], v119 offset:36960
	s_waitcnt lgkmcnt(0)
	s_barrier
	v_mfma_f32_32x32x16_bf16 v[50:65], v[176:179], v[184:187], v[50:65]
	v_mfma_f32_32x32x16_bf16 v[34:49], v[188:191], v[184:187], v[34:49]
	ds_read_b128 v[184:187], v155
	v_mfma_f32_32x32x16_bf16 v[18:33], v[176:179], v[192:195], v[18:33]
	ds_read_b128 v[176:179], v154 offset:18432
	v_mfma_f32_32x32x16_bf16 v[2:17], v[188:191], v[192:195], v[2:17]
	ds_read_b128 v[188:191], v154 offset:23040
	ds_read_b128 v[192:195], v155 offset:4608
	v_mfma_f32_32x32x16_bf16 v[50:65], v[162:165], v[168:171], v[50:65]
	s_waitcnt vmcnt(3)
	ds_write_b128 v105, v[94:97] offset:36864
	ds_write_b128 v105, v[90:93] offset:55296
	v_lshl_add_u64 v[94:95], v[146:147], 0, s[8:9]
	global_load_dwordx4 v[90:93], v[150:151], off
	s_mov_b64 s[8:9], 0x34000
	v_mfma_f32_32x32x16_bf16 v[34:49], v[172:175], v[168:171], v[34:49]
	ds_write_b128 v109, v[86:89] offset:36864
	ds_write_b128 v109, v[82:85] offset:55296
	v_lshl_add_u64 v[86:87], v[94:95], 0, v[138:139]
	global_load_dwordx4 v[86:89], v[86:87], off
	v_mfma_f32_32x32x16_bf16 v[18:33], v[162:165], v[180:183], v[18:33]
	ds_write_b128 v111, v[74:77] offset:55296
	v_add_co_u32_e32 v74, vcc, s5, v144
	s_mov_b32 s5, 0x31000
	s_nop 0
	v_addc_co_u32_e32 v75, vcc, 0, v145, vcc
	v_add_co_u32_e32 v82, vcc, s5, v144
	s_waitcnt vmcnt(3)
	ds_write_b128 v111, v[78:81] offset:36864
	v_mfma_f32_32x32x16_bf16 v[2:17], v[172:175], v[180:183], v[2:17]
	ds_write_b128 v113, v[70:73] offset:36864
	v_lshl_add_u64 v[70:71], v[94:95], 0, v[142:143]
	v_lshl_add_u64 v[78:79], v[94:95], 0, v[140:141]
	v_addc_co_u32_e32 v83, vcc, 0, v145, vcc
	v_lshl_add_u64 v[94:95], v[94:95], 0, v[136:137]
	global_load_dwordx4 v[82:85], v[82:83], off
	s_waitcnt vmcnt(3)
	ds_write_b128 v113, v[66:69] offset:55296
	global_load_dwordx4 v[94:97], v[94:95], off
	s_waitcnt lgkmcnt(10)
	v_mfma_f32_32x32x16_bf16 v[50:65], v[176:179], v[184:187], v[50:65]
	global_load_dwordx4 v[74:77], v[74:75], off
	ds_read_b128 v[150:153], v117 offset:23072
	global_load_dwordx4 v[70:73], v[70:71], off
	ds_read_b128 v[162:165], v119 offset:4640
	global_load_dwordx4 v[78:81], v[78:79], off
	s_mov_b32 s5, 0x38000
	global_load_dwordx4 v[66:69], v[148:149], off offset:-4096
	s_waitcnt lgkmcnt(11)
	v_mfma_f32_32x32x16_bf16 v[34:49], v[188:191], v[184:187], v[34:49]
	ds_read_b128 v[168:171], v117 offset:18464
	ds_read_b128 v[172:175], v117 offset:18496
	s_waitcnt lgkmcnt(12)
	v_mfma_f32_32x32x16_bf16 v[18:33], v[176:179], v[192:195], v[18:33]
	ds_read_b128 v[176:179], v119 offset:32
	ds_read_b128 v[180:183], v119 offset:64
	v_mfma_f32_32x32x16_bf16 v[2:17], v[188:191], v[192:195], v[2:17]
	ds_read_b128 v[184:187], v117 offset:23104
	ds_read_b128 v[188:191], v119 offset:4672
	s_waitcnt lgkmcnt(3)
	v_mfma_f32_32x32x16_bf16 v[50:65], v[168:171], v[176:179], v[50:65]
	v_mfma_f32_32x32x16_bf16 v[34:49], v[150:153], v[176:179], v[34:49]
	ds_read_b128 v[176:179], v119 offset:4704
	v_mfma_f32_32x32x16_bf16 v[18:33], v[168:171], v[162:165], v[18:33]
	ds_read_b128 v[168:171], v117 offset:23136
	v_mfma_f32_32x32x16_bf16 v[2:17], v[150:153], v[162:165], v[2:17]
	ds_read_b128 v[150:153], v117 offset:18528
	ds_read_b128 v[162:165], v119 offset:96
	s_waitcnt lgkmcnt(0)
	s_barrier
	v_mfma_f32_32x32x16_bf16 v[50:65], v[172:175], v[180:183], v[50:65]
	v_mfma_f32_32x32x16_bf16 v[34:49], v[184:187], v[180:183], v[34:49]
	ds_read_b128 v[180:183], v155 offset:36864
	v_mfma_f32_32x32x16_bf16 v[18:33], v[172:175], v[188:191], v[18:33]
	ds_read_b128 v[172:175], v154 offset:55296
	v_mfma_f32_32x32x16_bf16 v[2:17], v[184:187], v[188:191], v[2:17]
	ds_read_b128 v[184:187], v154 offset:59904
	ds_read_b128 v[188:191], v155 offset:41472
	v_mfma_f32_32x32x16_bf16 v[50:65], v[150:153], v[162:165], v[50:65]
	s_waitcnt vmcnt(4)
	ds_write_b128 v105, v[94:97]
	ds_write_b128 v105, v[90:93] offset:18432
	v_lshl_add_u64 v[94:95], v[146:147], 0, s[8:9]
	global_load_dwordx4 v[90:93], v[148:149], off
	s_mov_b64 s[8:9], 0x38000
	v_mfma_f32_32x32x16_bf16 v[34:49], v[168:171], v[162:165], v[34:49]
	ds_write_b128 v109, v[86:89]
	ds_write_b128 v109, v[82:85] offset:18432
	v_lshl_add_u64 v[86:87], v[94:95], 0, v[138:139]
	global_load_dwordx4 v[86:89], v[86:87], off
	v_mfma_f32_32x32x16_bf16 v[18:33], v[150:153], v[176:179], v[18:33]
	v_add_co_u32_e32 v150, vcc, s5, v144
	s_mov_b32 s5, 0x36000
	s_nop 0
	v_addc_co_u32_e32 v151, vcc, 0, v145, vcc
	s_waitcnt vmcnt(5)
	ds_write_b128 v111, v[74:77] offset:18432
	v_add_co_u32_e32 v74, vcc, s5, v144
	s_mov_b32 s5, 0x35000
	s_nop 0
	v_addc_co_u32_e32 v75, vcc, 0, v145, vcc
	v_add_co_u32_e32 v82, vcc, s5, v144
	s_waitcnt vmcnt(3)
	ds_write_b128 v111, v[78:81]
	v_mfma_f32_32x32x16_bf16 v[2:17], v[168:171], v[176:179], v[2:17]
	ds_write_b128 v113, v[70:73]
	v_lshl_add_u64 v[70:71], v[94:95], 0, v[142:143]
	v_lshl_add_u64 v[78:79], v[94:95], 0, v[140:141]
	v_addc_co_u32_e32 v83, vcc, 0, v145, vcc
	v_lshl_add_u64 v[94:95], v[94:95], 0, v[136:137]
	global_load_dwordx4 v[74:77], v[74:75], off
	s_waitcnt vmcnt(3)
	ds_write_b128 v113, v[66:69] offset:18432
	global_load_dwordx4 v[82:85], v[82:83], off
	s_waitcnt lgkmcnt(10)
	v_mfma_f32_32x32x16_bf16 v[50:65], v[172:175], v[180:183], v[50:65]
	global_load_dwordx4 v[94:97], v[94:95], off
	ds_read_b128 v[162:165], v117 offset:59936
	global_load_dwordx4 v[70:73], v[70:71], off
	ds_read_b128 v[168:171], v119 offset:41504
	global_load_dwordx4 v[78:81], v[78:79], off
	s_mov_b32 s5, 0x3c000
	global_load_dwordx4 v[66:69], v[150:151], off offset:-4096
	s_waitcnt lgkmcnt(11)
	v_mfma_f32_32x32x16_bf16 v[34:49], v[184:187], v[180:183], v[34:49]
	ds_read_b128 v[176:179], v117 offset:55360
	ds_read_b128 v[180:183], v119 offset:36896
	v_add_co_u32_e32 v148, vcc, s5, v144
	s_mov_b32 s5, 0x3a000
	s_nop 0
	v_addc_co_u32_e32 v149, vcc, 0, v145, vcc
	s_waitcnt lgkmcnt(12)
	v_mfma_f32_32x32x16_bf16 v[18:33], v[172:175], v[188:191], v[18:33]
	ds_read_b128 v[172:175], v117 offset:55328
	ds_read_b128 v[192:195], v119 offset:41536
	v_mfma_f32_32x32x16_bf16 v[2:17], v[184:187], v[188:191], v[2:17]
	ds_read_b128 v[188:191], v117 offset:59968
	ds_read_b128 v[184:187], v119 offset:36928
	s_waitcnt lgkmcnt(3)
	v_mfma_f32_32x32x16_bf16 v[50:65], v[172:175], v[180:183], v[50:65]
	v_mfma_f32_32x32x16_bf16 v[34:49], v[162:165], v[180:183], v[34:49]
	ds_read_b128 v[180:183], v119 offset:41568
	v_mfma_f32_32x32x16_bf16 v[18:33], v[172:175], v[168:171], v[18:33]
	ds_read_b128 v[172:175], v117 offset:60000
	v_mfma_f32_32x32x16_bf16 v[2:17], v[162:165], v[168:171], v[2:17]
	ds_read_b128 v[162:165], v117 offset:55392
	ds_read_b128 v[168:171], v119 offset:36960
	s_waitcnt lgkmcnt(0)
	s_barrier
	v_mfma_f32_32x32x16_bf16 v[50:65], v[176:179], v[184:187], v[50:65]
	v_mfma_f32_32x32x16_bf16 v[34:49], v[188:191], v[184:187], v[34:49]
	ds_read_b128 v[184:187], v155
	v_mfma_f32_32x32x16_bf16 v[18:33], v[176:179], v[192:195], v[18:33]
	ds_read_b128 v[176:179], v154 offset:18432
	v_mfma_f32_32x32x16_bf16 v[2:17], v[188:191], v[192:195], v[2:17]
	ds_read_b128 v[188:191], v154 offset:23040
	ds_read_b128 v[192:195], v155 offset:4608
	v_mfma_f32_32x32x16_bf16 v[50:65], v[162:165], v[168:171], v[50:65]
	s_waitcnt vmcnt(3)
	ds_write_b128 v105, v[94:97] offset:36864
	ds_write_b128 v105, v[90:93] offset:55296
	v_lshl_add_u64 v[94:95], v[146:147], 0, s[8:9]
	global_load_dwordx4 v[90:93], v[150:151], off
	s_mov_b64 s[8:9], 0x3c000
	v_mfma_f32_32x32x16_bf16 v[34:49], v[172:175], v[168:171], v[34:49]
	ds_write_b128 v109, v[86:89] offset:36864
	ds_write_b128 v109, v[82:85] offset:55296
	v_lshl_add_u64 v[86:87], v[94:95], 0, v[138:139]
	global_load_dwordx4 v[86:89], v[86:87], off
	v_mfma_f32_32x32x16_bf16 v[18:33], v[162:165], v[180:183], v[18:33]
	ds_write_b128 v111, v[74:77] offset:55296
	v_add_co_u32_e32 v74, vcc, s5, v144
	s_mov_b32 s5, 0x39000
	s_nop 0
	v_addc_co_u32_e32 v75, vcc, 0, v145, vcc
	v_add_co_u32_e32 v82, vcc, s5, v144
	s_waitcnt vmcnt(3)
	ds_write_b128 v111, v[78:81] offset:36864
	v_mfma_f32_32x32x16_bf16 v[2:17], v[172:175], v[180:183], v[2:17]
	ds_write_b128 v113, v[70:73] offset:36864
	v_lshl_add_u64 v[70:71], v[94:95], 0, v[142:143]
	v_lshl_add_u64 v[78:79], v[94:95], 0, v[140:141]
	v_addc_co_u32_e32 v83, vcc, 0, v145, vcc
	v_lshl_add_u64 v[94:95], v[94:95], 0, v[136:137]
	s_waitcnt vmcnt(2)
	ds_write_b128 v113, v[66:69] offset:55296
	global_load_dwordx4 v[66:69], v[148:149], off offset:-4096
	s_waitcnt lgkmcnt(10)
	v_mfma_f32_32x32x16_bf16 v[50:65], v[176:179], v[184:187], v[50:65]
	global_load_dwordx4 v[74:77], v[74:75], off
	ds_read_b128 v[150:153], v117 offset:23072
	global_load_dwordx4 v[78:81], v[78:79], off
	ds_read_b128 v[162:165], v119 offset:4640
	global_load_dwordx4 v[82:85], v[82:83], off
	s_mov_b32 s5, 0x3f000
	global_load_dwordx4 v[94:97], v[94:95], off
	s_waitcnt lgkmcnt(11)
	v_mfma_f32_32x32x16_bf16 v[34:49], v[188:191], v[184:187], v[34:49]
	global_load_dwordx4 v[70:73], v[70:71], off
	ds_read_b128 v[168:171], v117 offset:18464
	ds_read_b128 v[172:175], v117 offset:18496
	s_waitcnt lgkmcnt(12)
	v_mfma_f32_32x32x16_bf16 v[18:33], v[176:179], v[192:195], v[18:33]
	ds_read_b128 v[176:179], v119 offset:32
	ds_read_b128 v[180:183], v119 offset:64
	v_mfma_f32_32x32x16_bf16 v[2:17], v[188:191], v[192:195], v[2:17]
	ds_read_b128 v[184:187], v117 offset:23104
	ds_read_b128 v[188:191], v119 offset:4672
	s_waitcnt lgkmcnt(3)
	v_mfma_f32_32x32x16_bf16 v[50:65], v[168:171], v[176:179], v[50:65]
	v_mfma_f32_32x32x16_bf16 v[34:49], v[150:153], v[176:179], v[34:49]
	ds_read_b128 v[176:179], v119 offset:4704
	v_mfma_f32_32x32x16_bf16 v[18:33], v[168:171], v[162:165], v[18:33]
	ds_read_b128 v[168:171], v117 offset:23136
	v_mfma_f32_32x32x16_bf16 v[2:17], v[150:153], v[162:165], v[2:17]
	ds_read_b128 v[150:153], v117 offset:18528
	ds_read_b128 v[162:165], v119 offset:96
	s_waitcnt lgkmcnt(0)
	s_barrier
	v_mfma_f32_32x32x16_bf16 v[50:65], v[172:175], v[180:183], v[50:65]
	v_mfma_f32_32x32x16_bf16 v[34:49], v[184:187], v[180:183], v[34:49]
	ds_read_b128 v[180:183], v155 offset:36864
	v_mfma_f32_32x32x16_bf16 v[18:33], v[172:175], v[188:191], v[18:33]
	ds_read_b128 v[172:175], v154 offset:55296
	v_mfma_f32_32x32x16_bf16 v[2:17], v[184:187], v[188:191], v[2:17]
	ds_read_b128 v[184:187], v154 offset:59904
	ds_read_b128 v[188:191], v155 offset:41472
	v_mfma_f32_32x32x16_bf16 v[50:65], v[150:153], v[162:165], v[50:65]
	s_waitcnt vmcnt(1)
	ds_write_b128 v105, v[94:97]
	ds_write_b128 v105, v[90:93] offset:18432
	v_lshl_add_u64 v[94:95], v[146:147], 0, s[8:9]
	global_load_dwordx4 v[90:93], v[148:149], off
	v_mfma_f32_32x32x16_bf16 v[34:49], v[168:171], v[162:165], v[34:49]
	ds_write_b128 v109, v[86:89]
	ds_write_b128 v109, v[82:85] offset:18432
	v_lshl_add_u64 v[86:87], v[94:95], 0, v[138:139]
	global_load_dwordx4 v[86:89], v[86:87], off
	v_mfma_f32_32x32x16_bf16 v[18:33], v[150:153], v[176:179], v[18:33]
	ds_write_b128 v111, v[78:81]
	ds_write_b128 v111, v[74:77] offset:18432
	v_lshl_add_u64 v[78:79], v[94:95], 0, v[140:141]
	global_load_dwordx4 v[78:81], v[78:79], off
	v_mfma_f32_32x32x16_bf16 v[2:17], v[168:171], v[176:179], v[2:17]
	ds_write_b128 v113, v[66:69] offset:18432
	v_add_co_u32_e32 v66, vcc, s5, v144
	s_mov_b32 s5, 0x3e000
	s_nop 0
	v_addc_co_u32_e32 v67, vcc, 0, v145, vcc
	v_add_co_u32_e32 v74, vcc, s5, v144
	s_mov_b32 s5, 0x3d000
	s_nop 0
	v_addc_co_u32_e32 v75, vcc, 0, v145, vcc
	s_waitcnt vmcnt(3)
	ds_write_b128 v113, v[70:73]
	v_lshl_add_u64 v[70:71], v[94:95], 0, v[142:143]
	v_add_co_u32_e32 v82, vcc, s5, v144
	v_lshl_add_u64 v[94:95], v[94:95], 0, v[136:137]
	s_nop 0
	v_addc_co_u32_e32 v83, vcc, 0, v145, vcc
	global_load_dwordx4 v[94:97], v[94:95], off
	s_waitcnt lgkmcnt(10)
	v_mfma_f32_32x32x16_bf16 v[50:65], v[172:175], v[180:183], v[50:65]
	global_load_dwordx4 v[74:77], v[74:75], off
	ds_read_b128 v[144:147], v117 offset:59936
	global_load_dwordx4 v[82:85], v[82:83], off
	ds_read_b128 v[148:151], v119 offset:41504
	global_load_dwordx4 v[66:69], v[66:67], off
	s_nop 0
	global_load_dwordx4 v[70:73], v[70:71], off
	s_waitcnt lgkmcnt(11)
	v_mfma_f32_32x32x16_bf16 v[34:49], v[184:187], v[180:183], v[34:49]
	ds_read_b128 v[162:165], v117 offset:55328
	ds_read_b128 v[168:171], v117 offset:55360
	s_waitcnt lgkmcnt(12)
	v_mfma_f32_32x32x16_bf16 v[18:33], v[172:175], v[188:191], v[18:33]
	ds_read_b128 v[172:175], v119 offset:36896
	ds_read_b128 v[176:179], v119 offset:36928
	v_mfma_f32_32x32x16_bf16 v[2:17], v[184:187], v[188:191], v[2:17]
	ds_read_b128 v[180:183], v117 offset:59968
	ds_read_b128 v[184:187], v119 offset:41536
	s_waitcnt lgkmcnt(3)
	v_mfma_f32_32x32x16_bf16 v[50:65], v[162:165], v[172:175], v[50:65]
	v_mfma_f32_32x32x16_bf16 v[34:49], v[144:147], v[172:175], v[34:49]
	ds_read_b128 v[172:175], v119 offset:41568
	v_mfma_f32_32x32x16_bf16 v[18:33], v[162:165], v[148:151], v[18:33]
	ds_read_b128 v[162:165], v117 offset:60000
	v_mfma_f32_32x32x16_bf16 v[2:17], v[144:147], v[148:151], v[2:17]
	ds_read_b128 v[144:147], v117 offset:55392
	ds_read_b128 v[148:151], v119 offset:36960
	s_waitcnt lgkmcnt(0)
	s_barrier
	v_mfma_f32_32x32x16_bf16 v[50:65], v[168:171], v[176:179], v[50:65]
	v_mfma_f32_32x32x16_bf16 v[34:49], v[180:183], v[176:179], v[34:49]
	ds_read_b128 v[176:179], v155
	v_mfma_f32_32x32x16_bf16 v[18:33], v[168:171], v[184:187], v[18:33]
	ds_read_b128 v[168:171], v154 offset:18432
	v_mfma_f32_32x32x16_bf16 v[2:17], v[180:183], v[184:187], v[2:17]
	ds_read_b128 v[180:183], v154 offset:23040
	ds_read_b128 v[184:187], v155 offset:4608
	v_mfma_f32_32x32x16_bf16 v[50:65], v[144:147], v[148:151], v[50:65]
	s_waitcnt vmcnt(4)
	ds_write_b128 v105, v[94:97] offset:36864
	ds_write_b128 v105, v[90:93] offset:55296
	v_mfma_f32_32x32x16_bf16 v[34:49], v[162:165], v[148:151], v[34:49]
	ds_write_b128 v109, v[86:89] offset:36864
	s_waitcnt vmcnt(2)
	ds_write_b128 v109, v[82:85] offset:55296
	v_mfma_f32_32x32x16_bf16 v[18:33], v[144:147], v[172:175], v[18:33]
	ds_write_b128 v111, v[78:81] offset:36864
	ds_write_b128 v111, v[74:77] offset:55296
	v_lshl_or_b32 v144, s4, 7, v1
	s_movk_i32 s4, 0x3ff
	v_cmp_lt_i32_e64 s[6:7], s4, v144
	s_movk_i32 s4, 0x400
	v_cmp_eq_u32_e64 s[4:5], s4, v144
	v_mfma_f32_32x32x16_bf16 v[2:17], v[162:165], v[172:175], v[2:17]
	s_waitcnt vmcnt(0)
	ds_write_b128 v113, v[70:73] offset:36864
	ds_write_b128 v113, v[66:69] offset:55296
	s_waitcnt lgkmcnt(10)
	v_mfma_f32_32x32x16_bf16 v[50:65], v[168:171], v[176:179], v[50:65]
	ds_read_b128 v[66:69], v117 offset:23072
	ds_read_b128 v[70:73], v119 offset:4640
	s_waitcnt lgkmcnt(11)
	v_mfma_f32_32x32x16_bf16 v[34:49], v[180:183], v[176:179], v[34:49]
	ds_read_b128 v[74:77], v117 offset:18464
	ds_read_b128 v[78:81], v117 offset:18496
	s_waitcnt lgkmcnt(12)
	v_mfma_f32_32x32x16_bf16 v[18:33], v[168:171], v[184:187], v[18:33]
	ds_read_b128 v[82:85], v119 offset:32
	ds_read_b128 v[86:89], v119 offset:64
	v_mfma_f32_32x32x16_bf16 v[2:17], v[180:183], v[184:187], v[2:17]
	ds_read_b128 v[90:93], v117 offset:23104
	ds_read_b128 v[94:97], v119 offset:4672
	s_waitcnt lgkmcnt(3)
	v_mfma_f32_32x32x16_bf16 v[50:65], v[74:77], v[82:85], v[50:65]
	v_mfma_f32_32x32x16_bf16 v[34:49], v[66:69], v[82:85], v[34:49]
	ds_read_b128 v[82:85], v119 offset:4704
	v_mfma_f32_32x32x16_bf16 v[18:33], v[74:77], v[70:73], v[18:33]
	ds_read_b128 v[74:77], v117 offset:23136
	v_mfma_f32_32x32x16_bf16 v[2:17], v[66:69], v[70:73], v[2:17]
	ds_read_b128 v[66:69], v117 offset:18528
	ds_read_b128 v[70:73], v119 offset:96
	s_waitcnt lgkmcnt(0)
	s_barrier
	v_mfma_f32_32x32x16_bf16 v[50:65], v[78:81], v[86:89], v[50:65]
	v_mfma_f32_32x32x16_bf16 v[34:49], v[90:93], v[86:89], v[34:49]
	ds_read_b128 v[86:89], v155 offset:36864
	v_mfma_f32_32x32x16_bf16 v[18:33], v[78:81], v[94:97], v[18:33]
	ds_read_b128 v[78:81], v154 offset:55296
	v_mfma_f32_32x32x16_bf16 v[2:17], v[90:93], v[94:97], v[2:17]
	ds_read_b128 v[90:93], v154 offset:59904
	ds_read_b128 v[94:97], v155 offset:41472
	v_mfma_f32_32x32x16_bf16 v[50:65], v[66:69], v[70:73], v[50:65]
	v_mfma_f32_32x32x16_bf16 v[34:49], v[74:77], v[70:73], v[34:49]
	ds_read_b128 v[70:73], v119 offset:41504
	v_mfma_f32_32x32x16_bf16 v[18:33], v[66:69], v[82:85], v[18:33]
	ds_read_b128 v[66:69], v117 offset:59936
	v_mfma_f32_32x32x16_bf16 v[2:17], v[74:77], v[82:85], v[2:17]
	ds_read_b128 v[74:77], v117 offset:55328
	ds_read_b128 v[82:85], v119 offset:36896
	s_waitcnt lgkmcnt(6)
	v_mfma_f32_32x32x16_bf16 v[50:65], v[78:81], v[86:89], v[50:65]
	s_waitcnt lgkmcnt(5)
	v_mfma_f32_32x32x16_bf16 v[34:49], v[90:93], v[86:89], v[34:49]
	ds_read_b128 v[86:89], v119 offset:36928
	s_waitcnt lgkmcnt(5)
	v_mfma_f32_32x32x16_bf16 v[18:33], v[78:81], v[94:97], v[18:33]
	ds_read_b128 v[78:81], v117 offset:55360
	v_mfma_f32_32x32x16_bf16 v[2:17], v[90:93], v[94:97], v[2:17]
	ds_read_b128 v[90:93], v117 offset:59968
	ds_read_b128 v[94:97], v119 offset:41536
	s_waitcnt lgkmcnt(4)
	v_mfma_f32_32x32x16_bf16 v[50:65], v[74:77], v[82:85], v[50:65]
	v_mfma_f32_32x32x16_bf16 v[34:49], v[66:69], v[82:85], v[34:49]
	ds_read_b128 v[82:85], v119 offset:41568
	v_mfma_f32_32x32x16_bf16 v[18:33], v[74:77], v[70:73], v[18:33]
	ds_read_b128 v[74:77], v117 offset:60000
	v_mfma_f32_32x32x16_bf16 v[2:17], v[66:69], v[70:73], v[2:17]
	ds_read_b128 v[66:69], v117 offset:55392
	ds_read_b128 v[70:73], v119 offset:36960
	s_waitcnt lgkmcnt(0)
	s_barrier
	v_mfma_f32_32x32x16_bf16 v[50:65], v[78:81], v[86:89], v[50:65]
	v_mfma_f32_32x32x16_bf16 v[34:49], v[90:93], v[86:89], v[34:49]
	v_mfma_f32_32x32x16_bf16 v[18:33], v[78:81], v[94:97], v[18:33]
	v_lshlrev_b32_e32 v78, 6, v98
	v_mfma_f32_32x32x16_bf16 v[2:17], v[90:93], v[94:97], v[2:17]
	v_mfma_f32_32x32x16_bf16 v[50:65], v[66:69], v[70:73], v[50:65]
	v_mfma_f32_32x32x16_bf16 v[34:49], v[74:77], v[70:73], v[34:49]
	global_load_dwordx4 v[70:73], v78, s[44:45] offset:32
	s_waitcnt vmcnt(0)
	v_add_f32_e32 v70, v70, v71
	v_mfma_f32_32x32x16_bf16 v[18:33], v[66:69], v[82:85], v[18:33]
	global_load_dwordx4 v[66:69], v78, s[44:45] offset:48
	v_add_f32_e32 v72, v72, v73
	s_waitcnt vmcnt(0)
	v_mov_b32_e32 v71, v68
	v_mfma_f32_32x32x16_bf16 v[2:17], v[74:77], v[82:85], v[2:17]
	global_load_dwordx4 v[74:77], v78, s[44:45] offset:16
	v_mov_b32_e32 v73, v69
	global_load_dwordx4 v[78:81], v78, s[44:45]
	v_add_f32_e64 v68, v70, v72
	v_add_f32_e64 v69, v71, v73
	s_waitcnt vmcnt(0)
	v_mov_b32_e32 v82, v79
	v_mov_b32_e32 v83, v80
	v_mov_b32_e32 v79, v81
	v_mov_b32_e32 v80, v75
	v_mov_b32_e32 v81, v76
	v_mov_b32_e32 v75, v77
	v_add_f32_e64 v78, v82, v78
	v_add_f32_e64 v79, v83, v79
	v_add_f32_e64 v74, v80, v74
	v_add_f32_e64 v75, v81, v75
	v_pk_add_f32 v[78:79], v[78:79], v[78:79] op_sel:[0,1] op_sel_hi:[1,0]
	v_pk_add_f32 v[74:75], v[74:75], v[74:75] op_sel:[0,1] op_sel_hi:[1,0]
	v_mov_b32_e32 v79, v66
	v_mov_b32_e32 v75, v67
	v_add_f32_e64 v66, v78, v74
	v_add_f32_e64 v67, v79, v75
	s_nop 0
	v_add_f32_e64 v66, v66, v68
	v_add_f32_e64 v67, v67, v69
	s_nop 0
	v_add_f32_e32 v66, v66, v67
	v_fmamk_f32 v66, v66, 0x3a800000, v156
	v_cmp_gt_f32_e32 vcc, s20, v66
	v_mul_f32_e32 v67, 0x4b800000, v66
	s_nop 0
	v_cndmask_b32_e32 v66, v66, v67, vcc
	v_rsq_f32_e32 v66, v66
	s_nop 0
	v_mul_f32_e32 v67, 0x45800000, v66
	v_cndmask_b32_e32 v146, v66, v67, vcc
	s_and_saveexec_b64 s[8:9], s[6:7]
	s_xor_b64 s[8:9], exec, s[8:9]
	s_cbranch_execz .LBB0_949
	s_and_saveexec_b64 s[10:11], s[4:5]
	s_cbranch_execz .LBB0_948
	global_load_dword v42, v[120:121], off
	s_waitcnt vmcnt(0)
	v_fmac_f32_e32 v42, v50, v146
	v_mul_f32_e32 v42, 0xbfb8aa3b, v42
	v_exp_f32_e32 v42, v42
	s_nop 0
	v_add_f32_e32 v42, 1.0, v42
	v_div_scale_f32 v43, s[12:13], v42, v42, 1.0
	v_rcp_f32_e32 v44, v43
	v_readlane_b32 s12, v231, 30
	v_readlane_b32 s13, v231, 31
	v_fma_f32 v45, -v43, v44, 1.0
	v_fmac_f32_e32 v44, v45, v44
	v_div_scale_f32 v45, vcc, 1.0, v42, 1.0
	v_mul_f32_e32 v46, v45, v44
	v_fma_f32 v47, -v43, v46, v45
	v_fmac_f32_e32 v46, v47, v44
	v_fma_f32 v43, -v43, v46, v45
	v_div_fmas_f32 v43, v43, v44, v46
	v_div_fixup_f32 v46, v43, v42, 1.0
	v_mov_b64_e32 v[42:43], s[12:13]
	v_mad_u64_u32 v[42:43], s[12:13], v98, s21, v[42:43]
	v_lshlrev_b32_e32 v44, 2, v104
	v_mov_b32_e32 v45, v99
	v_lshl_add_u64 v[44:45], v[42:43], 0, v[44:45]
	global_store_dword v[44:45], v46, off
	global_load_dword v46, v[120:121], off offset:4
	s_waitcnt vmcnt(0)
	v_fmac_f32_e32 v46, v51, v146
	v_mul_f32_e32 v46, 0xbfb8aa3b, v46
	v_exp_f32_e32 v46, v46
	s_nop 0
	v_add_f32_e32 v46, 1.0, v46
	v_div_scale_f32 v47, s[12:13], v46, v46, 1.0
	v_rcp_f32_e32 v48, v47
	s_nop 0
	v_fma_f32 v49, -v47, v48, 1.0
	v_fmac_f32_e32 v48, v49, v48
	v_div_scale_f32 v49, vcc, 1.0, v46, 1.0
	v_mul_f32_e32 v50, v49, v48
	v_fma_f32 v51, -v47, v50, v49
	v_fmac_f32_e32 v50, v51, v48
	v_fma_f32 v47, -v47, v50, v49
	v_div_fmas_f32 v47, v47, v48, v50
	v_div_fixup_f32 v46, v47, v46, 1.0
	global_store_dword v[44:45], v46, off offset:4
	global_load_dword v46, v[120:121], off offset:8
	s_waitcnt vmcnt(0)
	v_fmac_f32_e32 v46, v52, v146
	v_mul_f32_e32 v46, 0xbfb8aa3b, v46
	v_exp_f32_e32 v46, v46
	s_nop 0
	v_add_f32_e32 v46, 1.0, v46
	v_div_scale_f32 v47, s[12:13], v46, v46, 1.0
	v_rcp_f32_e32 v48, v47
	s_nop 0
	v_fma_f32 v49, -v47, v48, 1.0
	v_fmac_f32_e32 v48, v49, v48
	v_div_scale_f32 v49, vcc, 1.0, v46, 1.0
	v_mul_f32_e32 v50, v49, v48
	v_fma_f32 v51, -v47, v50, v49
	v_fmac_f32_e32 v50, v51, v48
	v_fma_f32 v47, -v47, v50, v49
	v_div_fmas_f32 v47, v47, v48, v50
	v_div_fixup_f32 v46, v47, v46, 1.0
	global_store_dword v[44:45], v46, off offset:8
	global_load_dword v46, v[122:123], off
	s_waitcnt vmcnt(0)
	v_fmac_f32_e32 v46, v53, v146
	v_mul_f32_e32 v46, 0xbfb8aa3b, v46
	v_exp_f32_e32 v46, v46
	s_nop 0
	v_add_f32_e32 v46, 1.0, v46
	v_div_scale_f32 v47, s[12:13], v46, v46, 1.0
	v_rcp_f32_e32 v48, v47
	s_nop 0
	v_fma_f32 v49, -v47, v48, 1.0
	v_fmac_f32_e32 v48, v49, v48
	v_div_scale_f32 v49, vcc, 1.0, v46, 1.0
	v_mul_f32_e32 v50, v49, v48
	v_fma_f32 v51, -v47, v50, v49
	v_fmac_f32_e32 v50, v51, v48
	v_fma_f32 v47, -v47, v50, v49
	v_div_fmas_f32 v47, v47, v48, v50
	v_div_fixup_f32 v48, v47, v46, 1.0
	v_lshlrev_b32_e32 v46, 2, v108
	v_mov_b32_e32 v47, v99
	v_lshl_add_u64 v[46:47], v[42:43], 0, v[46:47]
	global_store_dword v[46:47], v48, off
	global_load_dword v46, v[120:121], off offset:32
	s_waitcnt vmcnt(0)
	v_fmac_f32_e32 v46, v54, v146
	v_mul_f32_e32 v46, 0xbfb8aa3b, v46
	v_exp_f32_e32 v46, v46
	s_nop 0
	v_add_f32_e32 v46, 1.0, v46
	v_div_scale_f32 v47, s[12:13], v46, v46, 1.0
	v_rcp_f32_e32 v48, v47
	s_nop 0
	v_fma_f32 v49, -v47, v48, 1.0
	v_fmac_f32_e32 v48, v49, v48
	v_div_scale_f32 v49, vcc, 1.0, v46, 1.0
	v_mul_f32_e32 v50, v49, v48
	v_fma_f32 v51, -v47, v50, v49
	v_fmac_f32_e32 v50, v51, v48
	v_fma_f32 v47, -v47, v50, v49
	v_div_fmas_f32 v47, v47, v48, v50
	v_div_fixup_f32 v46, v47, v46, 1.0
	global_store_dword v[44:45], v46, off offset:32
	global_load_dword v46, v[120:121], off offset:36
	s_waitcnt vmcnt(0)
	v_fmac_f32_e32 v46, v55, v146
	v_mul_f32_e32 v46, 0xbfb8aa3b, v46
	v_exp_f32_e32 v46, v46
	s_nop 0
	v_add_f32_e32 v46, 1.0, v46
	v_div_scale_f32 v47, s[12:13], v46, v46, 1.0
	v_rcp_f32_e32 v48, v47
	s_nop 0
	v_fma_f32 v49, -v47, v48, 1.0
	v_fmac_f32_e32 v48, v49, v48
	v_div_scale_f32 v49, vcc, 1.0, v46, 1.0
	v_mul_f32_e32 v50, v49, v48
	v_fma_f32 v51, -v47, v50, v49
	v_fmac_f32_e32 v50, v51, v48
	v_fma_f32 v47, -v47, v50, v49
	v_div_fmas_f32 v47, v47, v48, v50
	v_div_fixup_f32 v46, v47, v46, 1.0
	global_store_dword v[44:45], v46, off offset:36
	global_load_dword v46, v[120:121], off offset:40
	s_waitcnt vmcnt(0)
	v_fmac_f32_e32 v46, v56, v146
	v_mul_f32_e32 v46, 0xbfb8aa3b, v46
	v_exp_f32_e32 v46, v46
	s_nop 0
	v_add_f32_e32 v46, 1.0, v46
	v_div_scale_f32 v47, s[12:13], v46, v46, 1.0
	v_rcp_f32_e32 v48, v47
	s_nop 0
	v_fma_f32 v49, -v47, v48, 1.0
	v_fmac_f32_e32 v48, v49, v48
	v_div_scale_f32 v49, vcc, 1.0, v46, 1.0
	v_mul_f32_e32 v50, v49, v48
	v_fma_f32 v51, -v47, v50, v49
	v_fmac_f32_e32 v50, v51, v48
	v_fma_f32 v47, -v47, v50, v49
	v_div_fmas_f32 v47, v47, v48, v50
	v_div_fixup_f32 v46, v47, v46, 1.0
	global_store_dword v[44:45], v46, off offset:40
	global_load_dword v46, v[124:125], off
	s_waitcnt vmcnt(0)
	v_fmac_f32_e32 v46, v57, v146
	v_mul_f32_e32 v46, 0xbfb8aa3b, v46
	v_exp_f32_e32 v46, v46
	s_nop 0
	v_add_f32_e32 v46, 1.0, v46
	v_div_scale_f32 v47, s[12:13], v46, v46, 1.0
	v_rcp_f32_e32 v48, v47
	s_nop 0
	v_fma_f32 v49, -v47, v48, 1.0
	v_fmac_f32_e32 v48, v49, v48
	v_div_scale_f32 v49, vcc, 1.0, v46, 1.0
	v_mul_f32_e32 v50, v49, v48
	v_fma_f32 v51, -v47, v50, v49
	v_fmac_f32_e32 v50, v51, v48
	v_fma_f32 v47, -v47, v50, v49
	v_div_fmas_f32 v47, v47, v48, v50
	v_div_fixup_f32 v48, v47, v46, 1.0
	v_lshlrev_b32_e32 v46, 2, v110
	v_mov_b32_e32 v47, v99
	v_lshl_add_u64 v[46:47], v[42:43], 0, v[46:47]
	global_store_dword v[46:47], v48, off
	global_load_dword v46, v[120:121], off offset:64
	s_waitcnt vmcnt(0)
	v_fmac_f32_e32 v46, v58, v146
	v_mul_f32_e32 v46, 0xbfb8aa3b, v46
	v_exp_f32_e32 v46, v46
	s_nop 0
	v_add_f32_e32 v46, 1.0, v46
	v_div_scale_f32 v47, s[12:13], v46, v46, 1.0
	v_rcp_f32_e32 v48, v47
	s_nop 0
	v_fma_f32 v49, -v47, v48, 1.0
	v_fmac_f32_e32 v48, v49, v48
	v_div_scale_f32 v49, vcc, 1.0, v46, 1.0
	v_mul_f32_e32 v50, v49, v48
	v_fma_f32 v51, -v47, v50, v49
	v_fmac_f32_e32 v50, v51, v48
	v_fma_f32 v47, -v47, v50, v49
	v_div_fmas_f32 v47, v47, v48, v50
	v_div_fixup_f32 v46, v47, v46, 1.0
	global_store_dword v[44:45], v46, off offset:64
	global_load_dword v46, v[120:121], off offset:68
	s_waitcnt vmcnt(0)
	v_fmac_f32_e32 v46, v59, v146
	v_mul_f32_e32 v46, 0xbfb8aa3b, v46
	v_exp_f32_e32 v46, v46
	s_nop 0
	v_add_f32_e32 v46, 1.0, v46
	v_div_scale_f32 v47, s[12:13], v46, v46, 1.0
	v_rcp_f32_e32 v48, v47
	s_nop 0
	v_fma_f32 v49, -v47, v48, 1.0
	v_fmac_f32_e32 v48, v49, v48
	v_div_scale_f32 v49, vcc, 1.0, v46, 1.0
	v_mul_f32_e32 v50, v49, v48
	v_fma_f32 v51, -v47, v50, v49
	v_fmac_f32_e32 v50, v51, v48
	v_fma_f32 v47, -v47, v50, v49
	v_div_fmas_f32 v47, v47, v48, v50
	v_div_fixup_f32 v46, v47, v46, 1.0
	global_store_dword v[44:45], v46, off offset:68
	global_load_dword v46, v[120:121], off offset:72
	s_waitcnt vmcnt(0)
	v_fmac_f32_e32 v46, v60, v146
	v_mul_f32_e32 v46, 0xbfb8aa3b, v46
	v_exp_f32_e32 v46, v46
	s_nop 0
	v_add_f32_e32 v46, 1.0, v46
	v_div_scale_f32 v47, s[12:13], v46, v46, 1.0
	v_rcp_f32_e32 v48, v47
	s_nop 0
	v_fma_f32 v49, -v47, v48, 1.0
	v_fmac_f32_e32 v48, v49, v48
	v_div_scale_f32 v49, vcc, 1.0, v46, 1.0
	v_mul_f32_e32 v50, v49, v48
	v_fma_f32 v51, -v47, v50, v49
	v_fmac_f32_e32 v50, v51, v48
	v_fma_f32 v47, -v47, v50, v49
	v_div_fmas_f32 v47, v47, v48, v50
	v_div_fixup_f32 v46, v47, v46, 1.0
	global_store_dword v[44:45], v46, off offset:72
	global_load_dword v46, v[126:127], off
	s_waitcnt vmcnt(0)
	v_fmac_f32_e32 v46, v61, v146
	v_mul_f32_e32 v46, 0xbfb8aa3b, v46
	v_exp_f32_e32 v46, v46
	s_nop 0
	v_add_f32_e32 v46, 1.0, v46
	v_div_scale_f32 v47, s[12:13], v46, v46, 1.0
	v_rcp_f32_e32 v48, v47
	s_nop 0
	v_fma_f32 v49, -v47, v48, 1.0
	v_fmac_f32_e32 v48, v49, v48
	v_div_scale_f32 v49, vcc, 1.0, v46, 1.0
	v_mul_f32_e32 v50, v49, v48
	v_fma_f32 v51, -v47, v50, v49
	v_fmac_f32_e32 v50, v51, v48
	v_fma_f32 v47, -v47, v50, v49
	v_div_fmas_f32 v47, v47, v48, v50
	v_div_fixup_f32 v48, v47, v46, 1.0
	v_lshlrev_b32_e32 v46, 2, v112
	v_mov_b32_e32 v47, v99
	v_lshl_add_u64 v[46:47], v[42:43], 0, v[46:47]
	global_store_dword v[46:47], v48, off
	global_load_dword v46, v[120:121], off offset:96
	s_waitcnt vmcnt(0)
	v_fmac_f32_e32 v46, v62, v146
	v_mul_f32_e32 v46, 0xbfb8aa3b, v46
	v_exp_f32_e32 v46, v46
	s_nop 0
	v_add_f32_e32 v46, 1.0, v46
	v_div_scale_f32 v47, s[12:13], v46, v46, 1.0
	v_rcp_f32_e32 v48, v47
	s_nop 0
	v_fma_f32 v49, -v47, v48, 1.0
	v_fmac_f32_e32 v48, v49, v48
	v_div_scale_f32 v49, vcc, 1.0, v46, 1.0
	v_mul_f32_e32 v50, v49, v48
	v_fma_f32 v51, -v47, v50, v49
	v_fmac_f32_e32 v50, v51, v48
	v_fma_f32 v47, -v47, v50, v49
	v_div_fmas_f32 v47, v47, v48, v50
	v_div_fixup_f32 v46, v47, v46, 1.0
	global_store_dword v[44:45], v46, off offset:96
	global_load_dword v46, v[120:121], off offset:100
	s_waitcnt vmcnt(0)
	v_fmac_f32_e32 v46, v63, v146
	v_mul_f32_e32 v46, 0xbfb8aa3b, v46
	v_exp_f32_e32 v46, v46
	s_nop 0
	v_add_f32_e32 v46, 1.0, v46
	v_div_scale_f32 v47, s[12:13], v46, v46, 1.0
	v_rcp_f32_e32 v48, v47
	s_nop 0
	v_fma_f32 v49, -v47, v48, 1.0
	v_fmac_f32_e32 v48, v49, v48
	v_div_scale_f32 v49, vcc, 1.0, v46, 1.0
	v_mul_f32_e32 v50, v49, v48
	v_fma_f32 v51, -v47, v50, v49
	v_fmac_f32_e32 v50, v51, v48
	v_fma_f32 v47, -v47, v50, v49
	v_div_fmas_f32 v47, v47, v48, v50
	v_div_fixup_f32 v46, v47, v46, 1.0
	global_store_dword v[44:45], v46, off offset:100
	global_load_dword v46, v[120:121], off offset:104
	s_waitcnt vmcnt(0)
	v_fmac_f32_e32 v46, v64, v146
	v_mul_f32_e32 v46, 0xbfb8aa3b, v46
	v_exp_f32_e32 v46, v46
	s_nop 0
	v_add_f32_e32 v46, 1.0, v46
	v_div_scale_f32 v47, s[12:13], v46, v46, 1.0
	v_rcp_f32_e32 v48, v47
	s_nop 0
	v_fma_f32 v49, -v47, v48, 1.0
	v_fmac_f32_e32 v48, v49, v48
	v_div_scale_f32 v49, vcc, 1.0, v46, 1.0
	v_mul_f32_e32 v50, v49, v48
	v_fma_f32 v51, -v47, v50, v49
	v_fmac_f32_e32 v50, v51, v48
	v_fma_f32 v47, -v47, v50, v49
	v_div_fmas_f32 v47, v47, v48, v50
	v_div_fixup_f32 v46, v47, v46, 1.0
	global_store_dword v[44:45], v46, off offset:104
	global_load_dword v46, v[128:129], off
	s_waitcnt vmcnt(0)
	v_fmac_f32_e32 v46, v65, v146
	v_mul_f32_e32 v46, 0xbfb8aa3b, v46
	v_exp_f32_e32 v46, v46
	s_nop 0
	v_add_f32_e32 v46, 1.0, v46
	v_div_scale_f32 v47, s[12:13], v46, v46, 1.0
	v_rcp_f32_e32 v48, v47
	s_nop 0
	v_fma_f32 v49, -v47, v48, 1.0
	v_fmac_f32_e32 v48, v49, v48
	v_div_scale_f32 v49, vcc, 1.0, v46, 1.0
	v_mul_f32_e32 v50, v49, v48
	v_fma_f32 v51, -v47, v50, v49
	v_fmac_f32_e32 v50, v51, v48
	v_fma_f32 v47, -v47, v50, v49
	v_div_fmas_f32 v47, v47, v48, v50
	v_div_fixup_f32 v48, v47, v46, 1.0
	v_lshlrev_b32_e32 v46, 2, v114
	v_mov_b32_e32 v47, v99
	v_lshl_add_u64 v[46:47], v[42:43], 0, v[46:47]
	global_store_dword v[46:47], v48, off
	global_load_dword v46, v[120:121], off offset:128
	s_waitcnt vmcnt(0)
	v_fmac_f32_e32 v46, v34, v146
	v_mul_f32_e32 v34, 0xbfb8aa3b, v46
	v_exp_f32_e32 v34, v34
	s_nop 0
	v_add_f32_e32 v34, 1.0, v34
	v_div_scale_f32 v46, s[12:13], v34, v34, 1.0
	v_rcp_f32_e32 v47, v46
	s_nop 0
	v_fma_f32 v48, -v46, v47, 1.0
	v_fmac_f32_e32 v47, v48, v47
	v_div_scale_f32 v48, vcc, 1.0, v34, 1.0
	v_mul_f32_e32 v49, v48, v47
	v_fma_f32 v50, -v46, v49, v48
	v_fmac_f32_e32 v49, v50, v47
	v_fma_f32 v46, -v46, v49, v48
	v_div_fmas_f32 v46, v46, v47, v49
	v_div_fixup_f32 v34, v46, v34, 1.0
	global_store_dword v[44:45], v34, off offset:128
	global_load_dword v34, v[120:121], off offset:132
	s_waitcnt vmcnt(0)
	v_fmac_f32_e32 v34, v35, v146
	v_mul_f32_e32 v34, 0xbfb8aa3b, v34
	v_exp_f32_e32 v34, v34
	s_nop 0
	v_add_f32_e32 v34, 1.0, v34
	v_div_scale_f32 v35, s[12:13], v34, v34, 1.0
	v_rcp_f32_e32 v46, v35
	s_nop 0
	v_fma_f32 v47, -v35, v46, 1.0
	v_fmac_f32_e32 v46, v47, v46
	v_div_scale_f32 v47, vcc, 1.0, v34, 1.0
	v_mul_f32_e32 v48, v47, v46
	v_fma_f32 v49, -v35, v48, v47
	v_fmac_f32_e32 v48, v49, v46
	v_fma_f32 v35, -v35, v48, v47
	v_div_fmas_f32 v35, v35, v46, v48
	v_div_fixup_f32 v34, v35, v34, 1.0
	global_store_dword v[44:45], v34, off offset:132
	global_load_dword v34, v[120:121], off offset:136
	s_waitcnt vmcnt(0)
	v_fmac_f32_e32 v34, v36, v146
	v_mul_f32_e32 v34, 0xbfb8aa3b, v34
	v_exp_f32_e32 v34, v34
	s_nop 0
	v_add_f32_e32 v34, 1.0, v34
	v_div_scale_f32 v35, s[12:13], v34, v34, 1.0
	v_rcp_f32_e32 v36, v35
	s_nop 0
	v_fma_f32 v46, -v35, v36, 1.0
	v_fmac_f32_e32 v36, v46, v36
	v_div_scale_f32 v46, vcc, 1.0, v34, 1.0
	v_mul_f32_e32 v47, v46, v36
	v_fma_f32 v48, -v35, v47, v46
	v_fmac_f32_e32 v47, v48, v36
	v_fma_f32 v35, -v35, v47, v46
	v_div_fmas_f32 v35, v35, v36, v47
	v_div_fixup_f32 v34, v35, v34, 1.0
	global_store_dword v[44:45], v34, off offset:136
	global_load_dword v34, v[130:131], off
	s_waitcnt vmcnt(0)
	v_fmac_f32_e32 v34, v37, v146
	v_mul_f32_e32 v34, 0xbfb8aa3b, v34
	v_exp_f32_e32 v34, v34
	s_nop 0
	v_add_f32_e32 v34, 1.0, v34
	v_div_scale_f32 v35, s[12:13], v34, v34, 1.0
	v_rcp_f32_e32 v36, v35
	s_nop 0
	v_fma_f32 v37, -v35, v36, 1.0
	v_fmac_f32_e32 v36, v37, v36
	v_div_scale_f32 v37, vcc, 1.0, v34, 1.0
	v_mul_f32_e32 v46, v37, v36
	v_fma_f32 v47, -v35, v46, v37
	v_fmac_f32_e32 v46, v47, v36
	v_fma_f32 v35, -v35, v46, v37
	v_div_fmas_f32 v35, v35, v36, v46
	v_div_fixup_f32 v36, v35, v34, 1.0
	v_lshlrev_b32_e32 v34, 2, v116
	v_mov_b32_e32 v35, v99
	v_lshl_add_u64 v[34:35], v[42:43], 0, v[34:35]
	global_store_dword v[34:35], v36, off
	global_load_dword v34, v[120:121], off offset:160
	s_waitcnt vmcnt(0)
	v_fmac_f32_e32 v34, v38, v146
	v_mul_f32_e32 v34, 0xbfb8aa3b, v34
	v_exp_f32_e32 v34, v34
	s_nop 0
	v_add_f32_e32 v34, 1.0, v34
	v_div_scale_f32 v35, s[12:13], v34, v34, 1.0
	v_rcp_f32_e32 v36, v35
	s_nop 0
	v_fma_f32 v37, -v35, v36, 1.0
	v_fmac_f32_e32 v36, v37, v36
	v_div_scale_f32 v37, vcc, 1.0, v34, 1.0
	v_mul_f32_e32 v38, v37, v36
	v_fma_f32 v46, -v35, v38, v37
	v_fmac_f32_e32 v38, v46, v36
	v_fma_f32 v35, -v35, v38, v37
	v_div_fmas_f32 v35, v35, v36, v38
	v_div_fixup_f32 v34, v35, v34, 1.0
	global_store_dword v[44:45], v34, off offset:160
	global_load_dword v34, v[120:121], off offset:164
	s_waitcnt vmcnt(0)
	v_fmac_f32_e32 v34, v39, v146
	v_mul_f32_e32 v34, 0xbfb8aa3b, v34
	v_exp_f32_e32 v34, v34
	s_nop 0
	v_add_f32_e32 v34, 1.0, v34
	v_div_scale_f32 v35, s[12:13], v34, v34, 1.0
	v_rcp_f32_e32 v36, v35
	s_nop 0
	v_fma_f32 v37, -v35, v36, 1.0
	v_fmac_f32_e32 v36, v37, v36
	v_div_scale_f32 v37, vcc, 1.0, v34, 1.0
	v_mul_f32_e32 v38, v37, v36
	v_fma_f32 v39, -v35, v38, v37
	v_fmac_f32_e32 v38, v39, v36
	v_fma_f32 v35, -v35, v38, v37
	v_div_fmas_f32 v35, v35, v36, v38
	v_div_fixup_f32 v34, v35, v34, 1.0
	global_store_dword v[44:45], v34, off offset:164
	global_load_dword v34, v[120:121], off offset:168
	s_waitcnt vmcnt(0)
	v_fmac_f32_e32 v34, v40, v146
	v_mul_f32_e32 v34, 0xbfb8aa3b, v34
	v_exp_f32_e32 v34, v34
	s_nop 0
	v_add_f32_e32 v34, 1.0, v34
	v_div_scale_f32 v35, s[12:13], v34, v34, 1.0
	v_rcp_f32_e32 v36, v35
	s_nop 0
	v_fma_f32 v37, -v35, v36, 1.0
	v_fmac_f32_e32 v36, v37, v36
	v_div_scale_f32 v37, vcc, 1.0, v34, 1.0
	v_mul_f32_e32 v38, v37, v36
	v_fma_f32 v39, -v35, v38, v37
	v_fmac_f32_e32 v38, v39, v36
	v_fma_f32 v35, -v35, v38, v37
	v_div_fmas_f32 v35, v35, v36, v38
	v_div_fixup_f32 v34, v35, v34, 1.0
	global_store_dword v[44:45], v34, off offset:168
	global_load_dword v34, v[132:133], off
	s_waitcnt vmcnt(0)
	v_fmac_f32_e32 v34, v41, v146
	v_mul_f32_e32 v34, 0xbfb8aa3b, v34
	v_exp_f32_e32 v34, v34
	s_nop 0
	v_add_f32_e32 v34, 1.0, v34
	v_div_scale_f32 v35, s[12:13], v34, v34, 1.0
	v_rcp_f32_e32 v36, v35
	s_nop 0
	v_fma_f32 v37, -v35, v36, 1.0
	v_fmac_f32_e32 v36, v37, v36
	v_div_scale_f32 v37, vcc, 1.0, v34, 1.0
	v_mul_f32_e32 v38, v37, v36
	v_fma_f32 v39, -v35, v38, v37
	v_fmac_f32_e32 v38, v39, v36
	v_fma_f32 v35, -v35, v38, v37
	v_div_fmas_f32 v35, v35, v36, v38
	v_div_fixup_f32 v36, v35, v34, 1.0
	v_lshlrev_b32_e32 v34, 2, v118
	v_mov_b32_e32 v35, v99
	v_lshl_add_u64 v[34:35], v[42:43], 0, v[34:35]
	global_store_dword v[34:35], v36, off

.LBB0_949:
	s_or_saveexec_b64 s[68:69], s[8:9]
	v_ashrrev_i32_e32 v145, 31, v144
	v_lshlrev_b32_e32 v162, 2, v98
	v_mbcnt_hi_u32_b32 v161, -1, v157
	s_xor_b64 exec, exec, s[68:69]
	s_cbranch_execz .LBB0_983
	global_load_dword v163, v162, s[54:55]
	global_load_dword v190, v[106:107], off
	global_load_dwordx4 v[94:97], v[134:135], off
	global_load_dwordx4 v[90:93], v[134:135], off offset:32
	global_load_dwordx4 v[78:81], v[134:135], off offset:96
	global_load_dwordx4 v[86:89], v[134:135], off offset:64
	global_load_dwordx4 v[66:69], v[134:135], off offset:224
	global_load_dwordx4 v[70:73], v[134:135], off offset:192
	global_load_dwordx4 v[74:77], v[134:135], off offset:160
	global_load_dwordx4 v[82:85], v[134:135], off offset:128
	v_and_b32_e32 v147, 64, v161
	v_mul_f32_e64 v152, v50, v146
	v_mul_f32_e64 v153, v51, v146
	v_mul_f32_e64 v148, v52, v146
	v_mul_f32_e64 v149, v53, v146
	v_mul_f32_e64 v50, v64, v146
	v_mul_f32_e64 v51, v65, v146
	v_mul_f32_e64 v64, v152, v152
	v_mul_f32_e64 v65, v153, v153
	v_mul_f32_e64 v150, v54, v146
	v_mul_f32_e64 v151, v55, v146
	v_mul_f32_e64 v54, v60, v146
	v_mul_f32_e64 v55, v61, v146
	v_mul_f32_e64 v60, v148, v148
	v_mul_f32_e64 v61, v149, v149
	v_add_f32_e32 v64, v64, v65
	v_add_f32_e32 v60, v60, v64
	v_mul_f32_e64 v56, v56, v146
	v_mul_f32_e64 v57, v57, v146
	v_mul_f32_e64 v52, v62, v146
	v_mul_f32_e64 v53, v63, v146
	v_mul_f32_e64 v58, v58, v146
	v_mul_f32_e64 v59, v59, v146
	v_mul_f32_e64 v48, v48, v146
	v_mul_f32_e64 v49, v49, v146
	v_mul_f32_e64 v46, v46, v146
	v_mul_f32_e64 v47, v47, v146
	v_mul_f32_e64 v44, v44, v146
	v_mul_f32_e64 v45, v45, v146
	v_mul_f32_e64 v42, v42, v146
	v_mul_f32_e64 v43, v43, v146
	v_mul_f32_e64 v40, v40, v146
	v_mul_f32_e64 v41, v41, v146
	v_mul_f32_e64 v38, v38, v146
	v_mul_f32_e64 v39, v39, v146
	v_mul_f32_e64 v36, v36, v146
	v_mul_f32_e64 v37, v37, v146
	v_mul_f32_e64 v34, v34, v146
	v_mul_f32_e64 v35, v35, v146
	v_add_u32_e32 v191, 64, v147
	v_mul_f32_e64 v146, v150, v150
	v_mul_f32_e64 v147, v151, v151
	v_add_f32_e32 v60, v61, v60
	v_add_f32_e32 v60, v146, v60
	v_mul_f32_e64 v62, v56, v56
	v_mul_f32_e64 v63, v57, v57
	v_add_f32_e32 v60, v147, v60
	v_add_f32_e32 v60, v62, v60
	v_mul_f32_e64 v172, v58, v58
	v_mul_f32_e64 v173, v59, v59
	v_add_f32_e32 v60, v63, v60
	v_add_f32_e32 v60, v172, v60
	v_mul_f32_e64 v170, v54, v54
	v_mul_f32_e64 v171, v55, v55
	v_add_f32_e32 v60, v173, v60
	v_add_f32_e32 v60, v170, v60
	v_mul_f32_e64 v168, v52, v52
	v_mul_f32_e64 v169, v53, v53
	v_add_f32_e32 v60, v171, v60
	v_add_f32_e32 v60, v168, v60
	v_mul_f32_e64 v164, v50, v50
	v_mul_f32_e64 v165, v51, v51
	v_add_f32_e32 v60, v169, v60
	v_add_f32_e32 v60, v164, v60
	v_mul_f32_e64 v188, v34, v34
	v_mul_f32_e64 v189, v35, v35
	v_add_f32_e32 v60, v165, v60
	v_add_f32_e32 v60, v188, v60
	v_mul_f32_e64 v186, v36, v36
	v_mul_f32_e64 v187, v37, v37
	v_add_f32_e32 v60, v189, v60
	v_add_f32_e32 v60, v186, v60
	v_mul_f32_e64 v184, v38, v38
	v_mul_f32_e64 v185, v39, v39
	v_add_f32_e32 v60, v187, v60
	v_add_f32_e32 v60, v184, v60
	v_mul_f32_e64 v182, v40, v40
	v_mul_f32_e64 v183, v41, v41
	v_add_f32_e32 v60, v185, v60
	v_add_f32_e32 v60, v182, v60
	v_mul_f32_e64 v180, v42, v42
	v_mul_f32_e64 v181, v43, v43
	v_add_f32_e32 v60, v183, v60
	v_add_f32_e32 v60, v180, v60
	v_mul_f32_e64 v178, v44, v44
	v_mul_f32_e64 v179, v45, v45
	v_add_f32_e32 v60, v181, v60
	v_add_f32_e32 v60, v178, v60
	v_mul_f32_e64 v176, v46, v46
	v_mul_f32_e64 v177, v47, v47
	v_add_f32_e32 v60, v179, v60
	v_xor_b32_e32 v167, 32, v161
	v_add_f32_e32 v60, v176, v60
	v_mul_f32_e64 v174, v48, v48
	v_mul_f32_e64 v175, v49, v49
	v_cmp_lt_i32_e32 vcc, v167, v191
	v_add_f32_e32 v60, v177, v60
	v_add_f32_e32 v60, v174, v60
	v_cndmask_b32_e32 v167, v161, v167, vcc
	v_lshlrev_b32_e32 v167, 2, v167
	v_add_f32_e32 v165, v175, v60
	ds_bpermute_b32 v167, v167, v165
	s_waitcnt vmcnt(9)
	v_cvt_f32_i32_e32 v65, v163
	s_waitcnt vmcnt(8)
	v_mul_f32_e32 v163, v190, v65
	v_and_b32_e32 v164, 0x7fffffff, v163
	v_lshrrev_b32_e32 v60, 23, v164
	v_and_b32_e32 v61, 0x7fffff, v164
	v_cmp_nlt_f32_e64 s[70:71], |v163|, s23
	v_add_u32_e32 v63, 0xffffff88, v60
	v_or_b32_e32 v61, 0x800000, v61
	s_and_saveexec_b64 s[8:9], s[70:71]
	s_xor_b64 s[76:77], exec, s[8:9]
	s_cbranch_execz .LBB0_952
	v_mad_u64_u32 v[146:147], s[12:13], v61, s24, 0
	v_mov_b32_e32 v168, v147
	v_mov_b32_e32 v169, v99
	v_mad_u64_u32 v[168:169], s[12:13], v61, s25, v[168:169]
	v_mov_b32_e32 v170, v169
	v_mov_b32_e32 v171, v99
	v_mad_u64_u32 v[170:171], s[12:13], v61, s28, v[170:171]
	v_cmp_lt_u32_e32 vcc, 63, v63
	v_mov_b32_e32 v172, v171
	v_mov_b32_e32 v173, v99
	v_cndmask_b32_e32 v60, 0, v158, vcc
	v_mad_u64_u32 v[172:173], s[12:13], v61, s29, v[172:173]
	v_add_u32_e32 v60, v60, v63
	v_mov_b32_e32 v174, v173
	v_mov_b32_e32 v175, v99
	v_cmp_lt_u32_e64 s[8:9], 31, v60
	v_mad_u64_u32 v[174:175], s[12:13], v61, s33, v[174:175]
	s_nop 0
	v_cndmask_b32_e64 v62, 0, v159, s[8:9]
	v_mov_b32_e32 v176, v175
	v_mov_b32_e32 v177, v99
	v_add_u32_e32 v60, v62, v60
	v_mad_u64_u32 v[176:177], s[12:13], v61, s47, v[176:177]
	v_cmp_lt_u32_e64 s[10:11], 31, v60
	v_mov_b32_e32 v178, v177
	v_mov_b32_e32 v179, v99
	v_cndmask_b32_e64 v62, 0, v159, s[10:11]
	v_mad_u64_u32 v[178:179], s[12:13], v61, s50, v[178:179]
	v_add_u32_e32 v60, v62, v60
	v_cndmask_b32_e32 v62, v176, v172, vcc
	v_cndmask_b32_e32 v64, v178, v174, vcc
	v_cndmask_b32_e32 v169, v179, v176, vcc
	v_cndmask_b32_e64 v147, v64, v62, s[8:9]
	v_cndmask_b32_e64 v64, v169, v64, s[8:9]
	v_cndmask_b32_e32 v169, v174, v170, vcc
	v_cndmask_b32_e64 v62, v62, v169, s[8:9]
	v_sub_u32_e32 v171, 32, v60
	v_cmp_eq_u32_e64 s[12:13], 0, v60
	v_cndmask_b32_e32 v60, v172, v168, vcc
	v_cndmask_b32_e64 v64, v64, v147, s[10:11]
	v_cndmask_b32_e64 v147, v147, v62, s[10:11]
	v_cndmask_b32_e64 v168, v169, v60, s[8:9]
	v_alignbit_b32 v173, v64, v147, v171
	v_cndmask_b32_e64 v62, v62, v168, s[10:11]
	v_cndmask_b32_e32 v146, v170, v146, vcc
	v_cndmask_b32_e64 v64, v173, v64, s[12:13]
	v_alignbit_b32 v169, v147, v62, v171
	v_cndmask_b32_e64 v60, v60, v146, s[8:9]
	v_cndmask_b32_e64 v147, v169, v147, s[12:13]
	v_bfe_u32 v173, v64, 29, 1
	v_cndmask_b32_e64 v60, v168, v60, s[10:11]
	v_alignbit_b32 v169, v64, v147, 30
	v_sub_u32_e32 v174, 0, v173
	v_alignbit_b32 v146, v62, v60, v171
	v_xor_b32_e32 v169, v169, v174
	v_cndmask_b32_e64 v62, v146, v62, s[12:13]
	v_alignbit_b32 v146, v147, v62, 30
	v_ffbh_u32_e32 v147, v169
	v_min_u32_e32 v147, 32, v147
	v_alignbit_b32 v60, v62, v60, 30
	v_xor_b32_e32 v146, v146, v174
	v_sub_u32_e32 v168, 31, v147
	v_xor_b32_e32 v60, v60, v174
	v_alignbit_b32 v169, v169, v146, v168
	v_alignbit_b32 v60, v146, v60, v168
	v_alignbit_b32 v62, v169, v60, 9
	v_ffbh_u32_e32 v146, v62
	v_min_u32_e32 v146, 32, v146
	v_lshrrev_b32_e32 v172, 29, v64
	v_not_b32_e32 v168, v146
	v_alignbit_b32 v60, v62, v60, v168
	v_lshlrev_b32_e32 v62, 31, v172
	v_or_b32_e32 v168, 0x33000000, v62
	v_add_lshl_u32 v146, v146, v147, 23
	v_lshrrev_b32_e32 v60, 9, v60
	v_sub_u32_e32 v146, v168, v146
	v_or_b32_e32 v62, 0.5, v62
	v_lshlrev_b32_e32 v147, 23, v147
	v_or_b32_e32 v60, v146, v60
	v_lshrrev_b32_e32 v146, 9, v169
	v_sub_u32_e32 v62, v62, v147
	v_or_b32_e32 v62, v146, v62
	v_mul_f32_e32 v146, 0x3fc90fda, v62
	v_fma_f32 v147, v62, s51, -v146
	v_fmac_f32_e32 v147, 0x33a22168, v62
	v_fmac_f32_e32 v147, 0x3fc90fda, v60
	v_lshrrev_b32_e32 v62, 30, v64
	v_add_f32_e32 v60, v146, v147
	v_add_u32_e32 v168, v173, v62

.LBB0_982:
	s_or_b64 exec, exec, s[8:9]
	s_waitcnt lgkmcnt(0)
	v_add_f32_e32 v165, v165, v167
	v_fmamk_f32 v165, v165, 0x3c800000, v156
	v_mul_f32_e32 v167, 0x4b800000, v165
	v_cmp_gt_f32_e32 vcc, s20, v165
	v_cmp_class_f32_e64 s[8:9], v163, s65
	v_lshlrev_b64 v[182:183], 11, v[98:99]
	v_cndmask_b32_e32 v165, v165, v167, vcc
	v_rsq_f32_e32 v165, v165
	v_lshl_add_u64 v[182:183], s[42:43], 0, v[182:183]
	v_lshl_add_u64 v[182:183], v[144:145], 1, v[182:183]
	v_mul_f32_e32 v167, 0x45800000, v165
	v_cndmask_b32_e32 v184, v165, v167, vcc
	v_mul_f32_e64 v40, v40, v184
	v_mul_f32_e64 v41, v41, v184
	v_mul_f32_e64 v56, v56, v184
	v_mul_f32_e64 v57, v57, v184
	v_mul_f32_e64 v40, v40, v76
	v_mul_f32_e64 v41, v41, v77
	v_mul_f32_e64 v48, v48, v184
	v_mul_f32_e64 v49, v49, v184
	v_lshlrev_b32_e32 v76, 30, v172
	v_lshlrev_b32_e32 v77, 30, v168
	v_mul_f32_e64 v56, v92, v56
	v_mul_f32_e64 v57, v93, v57
	v_mul_f32_e64 v52, v52, v184
	v_mul_f32_e64 v53, v53, v184
	v_mul_f32_e64 v44, v44, v184
	v_mul_f32_e64 v45, v45, v184
	v_mul_f32_e64 v48, v48, v68
	v_mul_f32_e64 v49, v49, v69
	v_mul_f32_e64 v68, v60, v60
	v_mul_f32_e64 v69, v61, v61
	v_and_b32_e32 v92, 0x80000000, v76
	v_and_b32_e32 v93, 0x80000000, v77
	v_mov_b64_e32 v[76:77], s[46:47]
	v_mul_f32_e64 v52, v52, v78
	v_mul_f32_e64 v53, v53, v79
	v_mul_f32_e64 v38, v38, v184
	v_mul_f32_e64 v39, v39, v184
	v_mul_f32_e64 v44, v44, v72
	v_mul_f32_e64 v45, v45, v73
	v_mov_b64_e32 v[72:73], s[18:19]
	v_fma_f32 v78, v68, s60, v76
	v_fma_f32 v79, v69, s60, v76
	v_mul_f32_e64 v38, v38, v74
	v_mul_f32_e64 v39, v39, v75
	v_fma_f32 v74, v68, s22, v72
	v_fma_f32 v75, v69, s22, v72
	v_fma_f32 v78, v68, v78, s62
	v_fma_f32 v79, v69, v79, s62
	v_mul_f32_e64 v58, v58, v184
	v_mul_f32_e64 v59, v59, v184
	v_fma_f32 v78, v68, v78, s64
	v_fma_f32 v79, v69, v79, s64
	v_fma_f32 v74, v68, v74, s66
	v_fma_f32 v75, v69, v75, s66
	v_mul_f32_e64 v58, v86, v58
	v_mul_f32_e64 v59, v87, v59
	v_mul_f32_e64 v42, v42, v184
	v_mul_f32_e64 v43, v43, v184
	v_lshlrev_b32_e32 v86, 30, v175
	v_lshlrev_b32_e32 v87, 30, v169
	v_fma_f32 v78, v68, v78, 1.0
	v_fma_f32 v79, v69, v79, 1.0
	v_mul_f32_e64 v68, v68, v74
	v_mul_f32_e64 v69, v69, v75
	v_mul_f32_e64 v42, v42, v70
	v_mul_f32_e64 v43, v43, v71
	v_mul_f32_e64 v70, v62, v62
	v_mul_f32_e64 v71, v63, v63
	v_fma_f32 v60, v60, v68, v60
	v_fma_f32 v61, v61, v69, v61
	v_xor_b32_e32 v68, v171, v170
	v_xor_b32_e32 v69, v164, v163
	v_and_b32_e32 v74, 0x80000000, v86
	v_and_b32_e32 v75, 0x80000000, v87
	v_xor_b32_e32 v74, v68, v74
	v_xor_b32_e32 v75, v69, v75
	v_fma_f32 v68, v70, s22, v72
	v_fma_f32 v69, v71, s22, v72
	v_mul_f32_e64 v54, v54, v184
	v_mul_f32_e64 v55, v55, v184
	v_fma_f32 v68, v70, v68, s66
	v_fma_f32 v69, v71, v69, s66
	v_mul_f32_e64 v54, v54, v88
	v_mul_f32_e64 v55, v55, v89
	v_mul_f32_e64 v68, v70, v68
	v_mul_f32_e64 v69, v71, v69
	v_mul_f32_e64 v36, v36, v184
	v_mul_f32_e64 v37, v37, v184
	v_fma_f32 v62, v62, v68, v62
	v_fma_f32 v63, v63, v69, v63
	v_fma_f32 v68, v70, s60, v76
	v_fma_f32 v69, v71, s60, v76
	v_and_b32_e32 v88, 1, v175
	v_fma_f32 v68, v70, v68, s62
	v_fma_f32 v69, v71, v69, s62
	v_mul_f32_e64 v36, v36, v84
	v_mul_f32_e64 v37, v37, v85
	v_fma_f32 v68, v70, v68, s64
	v_fma_f32 v69, v71, v69, s64
	v_and_b32_e32 v84, 1, v172
	v_and_b32_e32 v89, 1, v169
	v_fma_f32 v68, v70, v68, 1.0
	v_fma_f32 v69, v71, v69, 1.0
	v_cmp_eq_u32_e64 s[10:11], 0, v88
	v_and_b32_e32 v85, 1, v168
	v_cmp_eq_u32_e32 vcc, 0, v84
	v_cndmask_b32_e64 v63, v69, v63, s[10:11]
	v_cmp_eq_u32_e64 s[10:11], 0, v89
	v_mul_f32_e64 v148, v148, v184
	v_mul_f32_e64 v149, v149, v184
	v_cndmask_b32_e64 v61, -v61, v79, vcc
	v_cmp_eq_u32_e32 vcc, 0, v85
	v_cndmask_b32_e64 v62, v68, v62, s[10:11]
	v_mul_f32_e64 v152, v152, v184
	v_mul_f32_e64 v153, v153, v184
	v_mul_f32_e64 v96, v96, v148
	v_mul_f32_e64 v97, v97, v149
	v_mul_f32_e64 v148, v150, v184
	v_mul_f32_e64 v149, v151, v184
	v_cndmask_b32_e64 v60, -v60, v78, vcc
	v_cmp_class_f32_e64 vcc, v170, s65
	v_xor_b32_e32 v63, v74, v63
	v_xor_b32_e32 v62, v75, v62
	v_mul_f32_e64 v94, v94, v152
	v_mul_f32_e64 v95, v95, v153
	v_mul_f32_e64 v90, v90, v148
	v_mul_f32_e64 v91, v91, v149
	v_mul_f32_e64 v46, v46, v184
	v_mul_f32_e64 v47, v47, v184
	v_xor_b32_e32 v61, v92, v61
	v_xor_b32_e32 v60, v93, v60
	v_cndmask_b32_e32 v63, v160, v63, vcc
	v_cndmask_b32_e64 v62, v160, v62, s[8:9]
	v_mul_f32_e64 v46, v46, v66
	v_mul_f32_e64 v47, v47, v67
	v_mul_f32_e64 v66, v64, v64
	v_mul_f32_e64 v67, v65, v65
	v_cndmask_b32_e32 v61, v160, v61, vcc
	v_cndmask_b32_e64 v60, v160, v60, s[8:9]
	v_mul_f32_e64 v68, v90, v62
	v_mul_f32_e64 v69, v91, v63
	v_mul_f32_e64 v62, v94, v62
	v_mul_f32_e64 v63, v95, v63
	v_fma_f32 v68, v94, v60, -v68
	v_fma_f32 v69, v95, v61, -v69
	v_fma_f32 v60, v90, v60, v62
	v_fma_f32 v61, v91, v61, v63
	v_fma_f32 v62, v66, s60, v76
	v_fma_f32 v63, v67, s60, v76
	v_fma_f32 v70, v66, s22, v72
	v_fma_f32 v71, v67, s22, v72
	v_fma_f32 v62, v66, v62, s62
	v_fma_f32 v63, v67, v63, s62
	v_mul_f32_e64 v34, v34, v184
	v_mul_f32_e64 v35, v35, v184
	v_fma_f32 v62, v66, v62, s64
	v_fma_f32 v63, v67, v63, s64
	v_fma_f32 v70, v66, v70, s66
	v_fma_f32 v71, v67, v71, s66
	v_mul_f32_e64 v34, v34, v82
	v_mul_f32_e64 v35, v35, v83
	v_and_b32_e32 v82, 1, v180
	v_fma_f32 v62, v66, v62, 1.0
	v_fma_f32 v63, v67, v63, 1.0
	v_mul_f32_e64 v66, v66, v70
	v_mul_f32_e64 v67, v67, v71
	v_and_b32_e32 v83, 1, v176
	v_fma_f32 v64, v64, v66, v64
	v_fma_f32 v65, v65, v67, v65
	v_cmp_eq_u32_e32 vcc, 0, v82
	v_mul_f32_e64 v74, v146, v146
	v_mul_f32_e64 v75, v147, v147
	v_and_b32_e32 v84, 1, v181
	v_cndmask_b32_e64 v63, -v65, v63, vcc
	v_cmp_eq_u32_e32 vcc, 0, v83
	v_fma_f32 v66, v74, s60, v76
	v_fma_f32 v67, v75, s60, v76
	v_and_b32_e32 v85, 1, v177
	v_cndmask_b32_e64 v62, -v64, v62, vcc
	v_fma_f32 v64, v74, s22, v72
	v_fma_f32 v65, v75, s22, v72
	v_fma_f32 v66, v74, v66, s62
	v_fma_f32 v67, v75, v67, s62
	v_fma_f32 v64, v74, v64, s66
	v_fma_f32 v65, v75, v65, s66
	v_fma_f32 v66, v74, v66, s64
	v_fma_f32 v67, v75, v67, s64
	v_mul_f32_e64 v64, v74, v64
	v_mul_f32_e64 v65, v75, v65
	v_fma_f32 v66, v74, v66, 1.0
	v_fma_f32 v67, v75, v67, 1.0
	v_fma_f32 v64, v146, v64, v146
	v_fma_f32 v65, v147, v65, v147
	v_cmp_eq_u32_e64 s[10:11], 0, v84
	v_lshlrev_b32_e32 v78, 30, v181
	v_lshlrev_b32_e32 v79, 30, v177
	v_cndmask_b32_e64 v65, v67, v65, s[10:11]
	v_cmp_eq_u32_e64 s[10:11], 0, v85
	v_mul_f32_e64 v50, v50, v184
	v_mul_f32_e64 v51, v51, v184
	v_and_b32_e32 v67, 0x80000000, v79
	v_cndmask_b32_e64 v64, v66, v64, s[10:11]
	v_and_b32_e32 v66, 0x80000000, v78
	v_xor_b32_e32 v70, v179, v178
	v_xor_b32_e32 v71, v174, v173
	v_mul_f32_e64 v50, v50, v80
	v_mul_f32_e64 v51, v51, v81
	v_lshlrev_b32_e32 v80, 30, v180
	v_lshlrev_b32_e32 v81, 30, v176
	v_xor_b32_e32 v66, v70, v66
	v_xor_b32_e32 v67, v71, v67
	v_and_b32_e32 v80, 0x80000000, v80
	v_and_b32_e32 v81, 0x80000000, v81
	v_cmp_class_f32_e64 vcc, v178, s65
	v_cmp_class_f32_e64 s[8:9], v173, s65
	v_xor_b32_e32 v65, v66, v65
	v_xor_b32_e32 v64, v67, v64
	v_xor_b32_e32 v63, v80, v63
	v_xor_b32_e32 v62, v81, v62
	v_cndmask_b32_e32 v65, v160, v65, vcc
	v_cndmask_b32_e64 v64, v160, v64, s[8:9]
	v_cndmask_b32_e32 v63, v160, v63, vcc
	v_cndmask_b32_e64 v62, v160, v62, s[8:9]
	v_mul_f32_e64 v66, v56, v64
	v_mul_f32_e64 v67, v57, v65
	v_mul_f32_e64 v64, v96, v64
	v_mul_f32_e64 v65, v97, v65
	v_fma_f32 v66, v96, v62, -v66
	v_fma_f32 v67, v97, v63, -v67
	v_fma_f32 v56, v56, v62, v64
	v_fma_f32 v57, v57, v63, v65
	v_lshlrev_b32_e32 v62, 1, v104
	v_mov_b32_e32 v63, v99
	v_lshl_add_u64 v[62:63], v[182:183], 0, v[62:63]
	v_cvt_pk_bf16_f32 v34, v34, v35
	v_cvt_pk_bf16_f32 v35, v36, v37
	global_store_dwordx2 v[62:63], v[34:35], off offset:64
	v_cvt_pk_bf16_f32 v34, v38, v39
	v_cvt_pk_bf16_f32 v35, v40, v41
	global_store_dwordx2 v[62:63], v[34:35], off offset:80
	v_cvt_pk_bf16_f32 v34, v42, v43
	v_cvt_pk_bf16_f32 v35, v44, v45
	v_cvt_pk_bf16_f32 v64, v68, v69
	v_cvt_pk_bf16_f32 v65, v66, v67
	v_cvt_pk_bf16_f32 v60, v60, v61
	v_cvt_pk_bf16_f32 v61, v56, v57
	v_cvt_pk_bf16_f32 v56, v58, v59
	v_cvt_pk_bf16_f32 v57, v54, v55
	v_cvt_pk_bf16_f32 v52, v52, v53
	v_cvt_pk_bf16_f32 v53, v50, v51
	global_store_dwordx2 v[62:63], v[34:35], off offset:96
	v_cvt_pk_bf16_f32 v34, v46, v47
	v_cvt_pk_bf16_f32 v35, v48, v49
	global_store_dwordx2 v[62:63], v[64:65], off
	global_store_dwordx2 v[62:63], v[60:61], off offset:16
	global_store_dwordx2 v[62:63], v[56:57], off offset:32
	global_store_dwordx2 v[62:63], v[52:53], off offset:48
	global_store_dwordx2 v[62:63], v[34:35], off offset:112
.LBB0_983:
	s_or_b64 exec, exec, s[68:69]
	v_or_b32_e32 v98, 32, v98
	v_lshlrev_b32_e32 v46, 6, v98
	global_load_dwordx4 v[34:37], v46, s[44:45] offset:48
	global_load_dwordx4 v[38:41], v46, s[44:45] offset:32
	global_load_dwordx4 v[42:45], v46, s[44:45] offset:16
	s_nop 0
	global_load_dwordx4 v[46:49], v46, s[44:45]
	s_waitcnt vmcnt(2)
	v_add_f32_e32 v38, v38, v39
	v_add_f32_e32 v40, v40, v41
	s_waitcnt vmcnt(0)
	v_mov_b32_e32 v50, v47
	v_mov_b32_e32 v51, v48
	v_mov_b32_e32 v47, v49
	v_mov_b32_e32 v48, v43
	v_mov_b32_e32 v49, v44
	v_mov_b32_e32 v43, v45
	v_add_f32_e64 v46, v50, v46
	v_add_f32_e64 v47, v51, v47
	v_add_f32_e64 v42, v48, v42
	v_add_f32_e64 v43, v49, v43
	v_pk_add_f32 v[46:47], v[46:47], v[46:47] op_sel:[0,1] op_sel_hi:[1,0]
	v_pk_add_f32 v[42:43], v[42:43], v[42:43] op_sel:[0,1] op_sel_hi:[1,0]
	v_mov_b32_e32 v47, v34
	v_mov_b32_e32 v43, v35
	v_mov_b32_e32 v39, v36
	v_mov_b32_e32 v41, v37
	v_add_f32_e64 v34, v46, v42
	v_add_f32_e64 v35, v47, v43
	v_add_f32_e64 v36, v38, v40
	v_add_f32_e64 v37, v39, v41
	s_nop 0
	v_add_f32_e64 v34, v34, v36
	v_add_f32_e64 v35, v35, v37
	s_nop 0
	v_add_f32_e32 v34, v34, v35
	v_fmamk_f32 v34, v34, 0x3a800000, v156
	v_cmp_gt_f32_e32 vcc, s20, v34
	v_mul_f32_e32 v35, 0x4b800000, v34
	s_nop 0
	v_cndmask_b32_e32 v34, v34, v35, vcc
	v_rsq_f32_e32 v34, v34
	s_nop 0
	v_mul_f32_e32 v35, 0x45800000, v34
	v_cndmask_b32_e32 v66, v34, v35, vcc
	s_and_saveexec_b64 s[8:9], s[6:7]
	s_xor_b64 s[6:7], exec, s[8:9]
	s_cbranch_execz .LBB0_987
	s_and_saveexec_b64 s[8:9], s[4:5]
	s_cbranch_execz .LBB0_986
	global_load_dword v10, v[120:121], off
	s_waitcnt vmcnt(0)
	v_fmac_f32_e32 v10, v18, v66
	v_mul_f32_e32 v10, 0xbfb8aa3b, v10
	v_exp_f32_e32 v10, v10
	s_nop 0
	v_add_f32_e32 v10, 1.0, v10
	v_div_scale_f32 v11, s[4:5], v10, v10, 1.0
	v_rcp_f32_e32 v12, v11
	v_readlane_b32 s4, v231, 30
	v_readlane_b32 s5, v231, 31
	v_fma_f32 v13, -v11, v12, 1.0
	v_fmac_f32_e32 v12, v13, v12
	v_div_scale_f32 v13, vcc, 1.0, v10, 1.0
	v_mul_f32_e32 v14, v13, v12
	v_fma_f32 v15, -v11, v14, v13
	v_fmac_f32_e32 v14, v15, v12
	v_fma_f32 v11, -v11, v14, v13
	v_div_fmas_f32 v11, v11, v12, v14
	v_div_fixup_f32 v14, v11, v10, 1.0
	v_mov_b64_e32 v[10:11], s[4:5]
	v_mad_u64_u32 v[10:11], s[4:5], v98, s21, v[10:11]
	v_lshlrev_b32_e32 v98, 2, v104
	v_lshl_add_u64 v[12:13], v[10:11], 0, v[98:99]
	global_store_dword v[12:13], v14, off
	global_load_dword v14, v[120:121], off offset:4
	v_lshlrev_b32_e32 v98, 2, v108
	s_waitcnt vmcnt(0)
	v_fmac_f32_e32 v14, v19, v66
	v_mul_f32_e32 v14, 0xbfb8aa3b, v14
	v_exp_f32_e32 v14, v14
	s_nop 0
	v_add_f32_e32 v14, 1.0, v14
	v_div_scale_f32 v15, s[4:5], v14, v14, 1.0
	v_rcp_f32_e32 v16, v15
	s_nop 0
	v_fma_f32 v17, -v15, v16, 1.0
	v_fmac_f32_e32 v16, v17, v16
	v_div_scale_f32 v17, vcc, 1.0, v14, 1.0
	v_mul_f32_e32 v18, v17, v16
	v_fma_f32 v19, -v15, v18, v17
	v_fmac_f32_e32 v18, v19, v16
	v_fma_f32 v15, -v15, v18, v17
	v_div_fmas_f32 v15, v15, v16, v18
	v_div_fixup_f32 v14, v15, v14, 1.0
	global_store_dword v[12:13], v14, off offset:4
	global_load_dword v14, v[120:121], off offset:8
	s_waitcnt vmcnt(0)
	v_fmac_f32_e32 v14, v20, v66
	v_mul_f32_e32 v14, 0xbfb8aa3b, v14
	v_exp_f32_e32 v14, v14
	s_nop 0
	v_add_f32_e32 v14, 1.0, v14
	v_div_scale_f32 v15, s[4:5], v14, v14, 1.0
	v_rcp_f32_e32 v16, v15
	s_nop 0
	v_fma_f32 v17, -v15, v16, 1.0
	v_fmac_f32_e32 v16, v17, v16
	v_div_scale_f32 v17, vcc, 1.0, v14, 1.0
	v_mul_f32_e32 v18, v17, v16
	v_fma_f32 v19, -v15, v18, v17
	v_fmac_f32_e32 v18, v19, v16
	v_fma_f32 v15, -v15, v18, v17
	v_div_fmas_f32 v15, v15, v16, v18
	v_div_fixup_f32 v14, v15, v14, 1.0
	global_store_dword v[12:13], v14, off offset:8
	global_load_dword v14, v[122:123], off
	s_waitcnt vmcnt(0)
	v_fmac_f32_e32 v14, v21, v66
	v_mul_f32_e32 v14, 0xbfb8aa3b, v14
	v_exp_f32_e32 v14, v14
	s_nop 0
	v_add_f32_e32 v14, 1.0, v14
	v_div_scale_f32 v15, s[4:5], v14, v14, 1.0
	v_rcp_f32_e32 v16, v15
	s_nop 0
	v_fma_f32 v17, -v15, v16, 1.0
	v_fmac_f32_e32 v16, v17, v16
	v_div_scale_f32 v17, vcc, 1.0, v14, 1.0
	v_mul_f32_e32 v18, v17, v16
	v_fma_f32 v19, -v15, v18, v17
	v_fmac_f32_e32 v18, v19, v16
	v_fma_f32 v15, -v15, v18, v17
	v_div_fmas_f32 v15, v15, v16, v18
	v_div_fixup_f32 v16, v15, v14, 1.0
	v_lshl_add_u64 v[14:15], v[10:11], 0, v[98:99]
	global_store_dword v[14:15], v16, off
	global_load_dword v14, v[120:121], off offset:32
	v_lshlrev_b32_e32 v98, 2, v110
	s_waitcnt vmcnt(0)
	v_fmac_f32_e32 v14, v22, v66
	v_mul_f32_e32 v14, 0xbfb8aa3b, v14
	v_exp_f32_e32 v14, v14
	s_nop 0
	v_add_f32_e32 v14, 1.0, v14
	v_div_scale_f32 v15, s[4:5], v14, v14, 1.0
	v_rcp_f32_e32 v16, v15
	s_nop 0
	v_fma_f32 v17, -v15, v16, 1.0
	v_fmac_f32_e32 v16, v17, v16
	v_div_scale_f32 v17, vcc, 1.0, v14, 1.0
	v_mul_f32_e32 v18, v17, v16
	v_fma_f32 v19, -v15, v18, v17
	v_fmac_f32_e32 v18, v19, v16
	v_fma_f32 v15, -v15, v18, v17
	v_div_fmas_f32 v15, v15, v16, v18
	v_div_fixup_f32 v14, v15, v14, 1.0
	global_store_dword v[12:13], v14, off offset:32
	global_load_dword v14, v[120:121], off offset:36
	s_waitcnt vmcnt(0)
	v_fmac_f32_e32 v14, v23, v66
	v_mul_f32_e32 v14, 0xbfb8aa3b, v14
	v_exp_f32_e32 v14, v14
	s_nop 0
	v_add_f32_e32 v14, 1.0, v14
	v_div_scale_f32 v15, s[4:5], v14, v14, 1.0
	v_rcp_f32_e32 v16, v15
	s_nop 0
	v_fma_f32 v17, -v15, v16, 1.0
	v_fmac_f32_e32 v16, v17, v16
	v_div_scale_f32 v17, vcc, 1.0, v14, 1.0
	v_mul_f32_e32 v18, v17, v16
	v_fma_f32 v19, -v15, v18, v17
	v_fmac_f32_e32 v18, v19, v16
	v_fma_f32 v15, -v15, v18, v17
	v_div_fmas_f32 v15, v15, v16, v18
	v_div_fixup_f32 v14, v15, v14, 1.0
	global_store_dword v[12:13], v14, off offset:36
	global_load_dword v14, v[120:121], off offset:40
	s_waitcnt vmcnt(0)
	v_fmac_f32_e32 v14, v24, v66
	v_mul_f32_e32 v14, 0xbfb8aa3b, v14
	v_exp_f32_e32 v14, v14
	s_nop 0
	v_add_f32_e32 v14, 1.0, v14
	v_div_scale_f32 v15, s[4:5], v14, v14, 1.0
	v_rcp_f32_e32 v16, v15
	s_nop 0
	v_fma_f32 v17, -v15, v16, 1.0
	v_fmac_f32_e32 v16, v17, v16
	v_div_scale_f32 v17, vcc, 1.0, v14, 1.0
	v_mul_f32_e32 v18, v17, v16
	v_fma_f32 v19, -v15, v18, v17
	v_fmac_f32_e32 v18, v19, v16
	v_fma_f32 v15, -v15, v18, v17
	v_div_fmas_f32 v15, v15, v16, v18
	v_div_fixup_f32 v14, v15, v14, 1.0
	global_store_dword v[12:13], v14, off offset:40
	global_load_dword v14, v[124:125], off
	s_waitcnt vmcnt(0)
	v_fmac_f32_e32 v14, v25, v66
	v_mul_f32_e32 v14, 0xbfb8aa3b, v14
	v_exp_f32_e32 v14, v14
	s_nop 0
	v_add_f32_e32 v14, 1.0, v14
	v_div_scale_f32 v15, s[4:5], v14, v14, 1.0
	v_rcp_f32_e32 v16, v15
	s_nop 0
	v_fma_f32 v17, -v15, v16, 1.0
	v_fmac_f32_e32 v16, v17, v16
	v_div_scale_f32 v17, vcc, 1.0, v14, 1.0
	v_mul_f32_e32 v18, v17, v16
	v_fma_f32 v19, -v15, v18, v17
	v_fmac_f32_e32 v18, v19, v16
	v_fma_f32 v15, -v15, v18, v17
	v_div_fmas_f32 v15, v15, v16, v18
	v_div_fixup_f32 v16, v15, v14, 1.0
	v_lshl_add_u64 v[14:15], v[10:11], 0, v[98:99]
	global_store_dword v[14:15], v16, off
	global_load_dword v14, v[120:121], off offset:64
	v_lshlrev_b32_e32 v98, 2, v112
	s_waitcnt vmcnt(0)
	v_fmac_f32_e32 v14, v26, v66
	v_mul_f32_e32 v14, 0xbfb8aa3b, v14
	v_exp_f32_e32 v14, v14
	s_nop 0
	v_add_f32_e32 v14, 1.0, v14
	v_div_scale_f32 v15, s[4:5], v14, v14, 1.0
	v_rcp_f32_e32 v16, v15
	s_nop 0
	v_fma_f32 v17, -v15, v16, 1.0
	v_fmac_f32_e32 v16, v17, v16
	v_div_scale_f32 v17, vcc, 1.0, v14, 1.0
	v_mul_f32_e32 v18, v17, v16
	v_fma_f32 v19, -v15, v18, v17
	v_fmac_f32_e32 v18, v19, v16
	v_fma_f32 v15, -v15, v18, v17
	v_div_fmas_f32 v15, v15, v16, v18
	v_div_fixup_f32 v14, v15, v14, 1.0
	global_store_dword v[12:13], v14, off offset:64
	global_load_dword v14, v[120:121], off offset:68
	s_waitcnt vmcnt(0)
	v_fmac_f32_e32 v14, v27, v66
	v_mul_f32_e32 v14, 0xbfb8aa3b, v14
	v_exp_f32_e32 v14, v14
	s_nop 0
	v_add_f32_e32 v14, 1.0, v14
	v_div_scale_f32 v15, s[4:5], v14, v14, 1.0
	v_rcp_f32_e32 v16, v15
	s_nop 0
	v_fma_f32 v17, -v15, v16, 1.0
	v_fmac_f32_e32 v16, v17, v16
	v_div_scale_f32 v17, vcc, 1.0, v14, 1.0
	v_mul_f32_e32 v18, v17, v16
	v_fma_f32 v19, -v15, v18, v17
	v_fmac_f32_e32 v18, v19, v16
	v_fma_f32 v15, -v15, v18, v17
	v_div_fmas_f32 v15, v15, v16, v18
	v_div_fixup_f32 v14, v15, v14, 1.0
	global_store_dword v[12:13], v14, off offset:68
	global_load_dword v14, v[120:121], off offset:72
	s_waitcnt vmcnt(0)
	v_fmac_f32_e32 v14, v28, v66
	v_mul_f32_e32 v14, 0xbfb8aa3b, v14
	v_exp_f32_e32 v14, v14
	s_nop 0
	v_add_f32_e32 v14, 1.0, v14
	v_div_scale_f32 v15, s[4:5], v14, v14, 1.0
	v_rcp_f32_e32 v16, v15
	s_nop 0
	v_fma_f32 v17, -v15, v16, 1.0
	v_fmac_f32_e32 v16, v17, v16
	v_div_scale_f32 v17, vcc, 1.0, v14, 1.0
	v_mul_f32_e32 v18, v17, v16
	v_fma_f32 v19, -v15, v18, v17
	v_fmac_f32_e32 v18, v19, v16
	v_fma_f32 v15, -v15, v18, v17
	v_div_fmas_f32 v15, v15, v16, v18
	v_div_fixup_f32 v14, v15, v14, 1.0
	global_store_dword v[12:13], v14, off offset:72
	global_load_dword v14, v[126:127], off
	s_waitcnt vmcnt(0)
	v_fmac_f32_e32 v14, v29, v66
	v_mul_f32_e32 v14, 0xbfb8aa3b, v14
	v_exp_f32_e32 v14, v14
	s_nop 0
	v_add_f32_e32 v14, 1.0, v14
	v_div_scale_f32 v15, s[4:5], v14, v14, 1.0
	v_rcp_f32_e32 v16, v15
	s_nop 0
	v_fma_f32 v17, -v15, v16, 1.0
	v_fmac_f32_e32 v16, v17, v16
	v_div_scale_f32 v17, vcc, 1.0, v14, 1.0
	v_mul_f32_e32 v18, v17, v16
	v_fma_f32 v19, -v15, v18, v17
	v_fmac_f32_e32 v18, v19, v16
	v_fma_f32 v15, -v15, v18, v17
	v_div_fmas_f32 v15, v15, v16, v18
	v_div_fixup_f32 v16, v15, v14, 1.0
	v_lshl_add_u64 v[14:15], v[10:11], 0, v[98:99]
	global_store_dword v[14:15], v16, off
	global_load_dword v14, v[120:121], off offset:96
	v_lshlrev_b32_e32 v98, 2, v114
	s_waitcnt vmcnt(0)
	v_fmac_f32_e32 v14, v30, v66
	v_mul_f32_e32 v14, 0xbfb8aa3b, v14
	v_exp_f32_e32 v14, v14
	s_nop 0
	v_add_f32_e32 v14, 1.0, v14
	v_div_scale_f32 v15, s[4:5], v14, v14, 1.0
	v_rcp_f32_e32 v16, v15
	s_nop 0
	v_fma_f32 v17, -v15, v16, 1.0
	v_fmac_f32_e32 v16, v17, v16
	v_div_scale_f32 v17, vcc, 1.0, v14, 1.0
	v_mul_f32_e32 v18, v17, v16
	v_fma_f32 v19, -v15, v18, v17
	v_fmac_f32_e32 v18, v19, v16
	v_fma_f32 v15, -v15, v18, v17
	v_div_fmas_f32 v15, v15, v16, v18
	v_div_fixup_f32 v14, v15, v14, 1.0
	global_store_dword v[12:13], v14, off offset:96
	global_load_dword v14, v[120:121], off offset:100
	s_waitcnt vmcnt(0)
	v_fmac_f32_e32 v14, v31, v66
	v_mul_f32_e32 v14, 0xbfb8aa3b, v14
	v_exp_f32_e32 v14, v14
	s_nop 0
	v_add_f32_e32 v14, 1.0, v14
	v_div_scale_f32 v15, s[4:5], v14, v14, 1.0
	v_rcp_f32_e32 v16, v15
	s_nop 0
	v_fma_f32 v17, -v15, v16, 1.0
	v_fmac_f32_e32 v16, v17, v16
	v_div_scale_f32 v17, vcc, 1.0, v14, 1.0
	v_mul_f32_e32 v18, v17, v16
	v_fma_f32 v19, -v15, v18, v17
	v_fmac_f32_e32 v18, v19, v16
	v_fma_f32 v15, -v15, v18, v17
	v_div_fmas_f32 v15, v15, v16, v18
	v_div_fixup_f32 v14, v15, v14, 1.0
	global_store_dword v[12:13], v14, off offset:100
	global_load_dword v14, v[120:121], off offset:104
	s_waitcnt vmcnt(0)
	v_fmac_f32_e32 v14, v32, v66
	v_mul_f32_e32 v14, 0xbfb8aa3b, v14
	v_exp_f32_e32 v14, v14
	s_nop 0
	v_add_f32_e32 v14, 1.0, v14
	v_div_scale_f32 v15, s[4:5], v14, v14, 1.0
	v_rcp_f32_e32 v16, v15
	s_nop 0
	v_fma_f32 v17, -v15, v16, 1.0
	v_fmac_f32_e32 v16, v17, v16
	v_div_scale_f32 v17, vcc, 1.0, v14, 1.0
	v_mul_f32_e32 v18, v17, v16
	v_fma_f32 v19, -v15, v18, v17
	v_fmac_f32_e32 v18, v19, v16
	v_fma_f32 v15, -v15, v18, v17
	v_div_fmas_f32 v15, v15, v16, v18
	v_div_fixup_f32 v14, v15, v14, 1.0
	global_store_dword v[12:13], v14, off offset:104
	global_load_dword v14, v[128:129], off
	s_waitcnt vmcnt(0)
	v_fmac_f32_e32 v14, v33, v66
	v_mul_f32_e32 v14, 0xbfb8aa3b, v14
	v_exp_f32_e32 v14, v14
	s_nop 0
	v_add_f32_e32 v14, 1.0, v14
	v_div_scale_f32 v15, s[4:5], v14, v14, 1.0
	v_rcp_f32_e32 v16, v15
	s_nop 0
	v_fma_f32 v17, -v15, v16, 1.0
	v_fmac_f32_e32 v16, v17, v16
	v_div_scale_f32 v17, vcc, 1.0, v14, 1.0
	v_mul_f32_e32 v18, v17, v16
	v_fma_f32 v19, -v15, v18, v17
	v_fmac_f32_e32 v18, v19, v16
	v_fma_f32 v15, -v15, v18, v17
	v_div_fmas_f32 v15, v15, v16, v18
	v_div_fixup_f32 v16, v15, v14, 1.0
	v_lshl_add_u64 v[14:15], v[10:11], 0, v[98:99]
	global_store_dword v[14:15], v16, off
	global_load_dword v14, v[120:121], off offset:128
	v_lshlrev_b32_e32 v98, 2, v116
	s_waitcnt vmcnt(0)
	v_fmac_f32_e32 v14, v2, v66
	v_mul_f32_e32 v2, 0xbfb8aa3b, v14
	v_exp_f32_e32 v2, v2
	s_nop 0
	v_add_f32_e32 v2, 1.0, v2
	v_div_scale_f32 v14, s[4:5], v2, v2, 1.0
	v_rcp_f32_e32 v15, v14
	s_nop 0
	v_fma_f32 v16, -v14, v15, 1.0
	v_fmac_f32_e32 v15, v16, v15
	v_div_scale_f32 v16, vcc, 1.0, v2, 1.0
	v_mul_f32_e32 v17, v16, v15
	v_fma_f32 v18, -v14, v17, v16
	v_fmac_f32_e32 v17, v18, v15
	v_fma_f32 v14, -v14, v17, v16
	v_div_fmas_f32 v14, v14, v15, v17
	v_div_fixup_f32 v2, v14, v2, 1.0
	global_store_dword v[12:13], v2, off offset:128
	global_load_dword v2, v[120:121], off offset:132
	s_waitcnt vmcnt(0)
	v_fmac_f32_e32 v2, v3, v66
	v_mul_f32_e32 v2, 0xbfb8aa3b, v2
	v_exp_f32_e32 v2, v2
	s_nop 0
	v_add_f32_e32 v2, 1.0, v2
	v_div_scale_f32 v3, s[4:5], v2, v2, 1.0
	v_rcp_f32_e32 v14, v3
	s_nop 0
	v_fma_f32 v15, -v3, v14, 1.0
	v_fmac_f32_e32 v14, v15, v14
	v_div_scale_f32 v15, vcc, 1.0, v2, 1.0
	v_mul_f32_e32 v16, v15, v14
	v_fma_f32 v17, -v3, v16, v15
	v_fmac_f32_e32 v16, v17, v14
	v_fma_f32 v3, -v3, v16, v15
	v_div_fmas_f32 v3, v3, v14, v16
	v_div_fixup_f32 v2, v3, v2, 1.0
	global_store_dword v[12:13], v2, off offset:132
	global_load_dword v2, v[120:121], off offset:136
	s_waitcnt vmcnt(0)
	v_fmac_f32_e32 v2, v4, v66
	v_mul_f32_e32 v2, 0xbfb8aa3b, v2
	v_exp_f32_e32 v2, v2
	s_nop 0
	v_add_f32_e32 v2, 1.0, v2
	v_div_scale_f32 v3, s[4:5], v2, v2, 1.0
	v_rcp_f32_e32 v4, v3
	s_nop 0
	v_fma_f32 v14, -v3, v4, 1.0
	v_fmac_f32_e32 v4, v14, v4
	v_div_scale_f32 v14, vcc, 1.0, v2, 1.0
	v_mul_f32_e32 v15, v14, v4
	v_fma_f32 v16, -v3, v15, v14
	v_fmac_f32_e32 v15, v16, v4
	v_fma_f32 v3, -v3, v15, v14
	v_div_fmas_f32 v3, v3, v4, v15
	v_div_fixup_f32 v2, v3, v2, 1.0
	global_store_dword v[12:13], v2, off offset:136
	global_load_dword v2, v[130:131], off
	s_waitcnt vmcnt(0)
	v_fmac_f32_e32 v2, v5, v66
	v_mul_f32_e32 v2, 0xbfb8aa3b, v2
	v_exp_f32_e32 v2, v2
	s_nop 0
	v_add_f32_e32 v2, 1.0, v2
	v_div_scale_f32 v3, s[4:5], v2, v2, 1.0
	v_rcp_f32_e32 v4, v3
	s_nop 0
	v_fma_f32 v5, -v3, v4, 1.0
	v_fmac_f32_e32 v4, v5, v4
	v_div_scale_f32 v5, vcc, 1.0, v2, 1.0
	v_mul_f32_e32 v14, v5, v4
	v_fma_f32 v15, -v3, v14, v5
	v_fmac_f32_e32 v14, v15, v4
	v_fma_f32 v3, -v3, v14, v5
	v_div_fmas_f32 v3, v3, v4, v14
	v_div_fixup_f32 v4, v3, v2, 1.0
	v_lshl_add_u64 v[2:3], v[10:11], 0, v[98:99]
	global_store_dword v[2:3], v4, off
	global_load_dword v2, v[120:121], off offset:160
	v_lshlrev_b32_e32 v98, 2, v118
	s_waitcnt vmcnt(0)
	v_fmac_f32_e32 v2, v6, v66
	v_mul_f32_e32 v2, 0xbfb8aa3b, v2
	v_exp_f32_e32 v2, v2
	s_nop 0
	v_add_f32_e32 v2, 1.0, v2
	v_div_scale_f32 v3, s[4:5], v2, v2, 1.0
	v_rcp_f32_e32 v4, v3
	s_nop 0
	v_fma_f32 v5, -v3, v4, 1.0
	v_fmac_f32_e32 v4, v5, v4
	v_div_scale_f32 v5, vcc, 1.0, v2, 1.0
	v_mul_f32_e32 v6, v5, v4
	v_fma_f32 v14, -v3, v6, v5
	v_fmac_f32_e32 v6, v14, v4
	v_fma_f32 v3, -v3, v6, v5
	v_div_fmas_f32 v3, v3, v4, v6
	v_div_fixup_f32 v2, v3, v2, 1.0
	global_store_dword v[12:13], v2, off offset:160
	global_load_dword v2, v[120:121], off offset:164
	s_waitcnt vmcnt(0)
	v_fmac_f32_e32 v2, v7, v66
	v_mul_f32_e32 v2, 0xbfb8aa3b, v2
	v_exp_f32_e32 v2, v2
	s_nop 0
	v_add_f32_e32 v2, 1.0, v2
	v_div_scale_f32 v3, s[4:5], v2, v2, 1.0
	v_rcp_f32_e32 v4, v3
	s_nop 0
	v_fma_f32 v5, -v3, v4, 1.0
	v_fmac_f32_e32 v4, v5, v4
	v_div_scale_f32 v5, vcc, 1.0, v2, 1.0
	v_mul_f32_e32 v6, v5, v4
	v_fma_f32 v7, -v3, v6, v5
	v_fmac_f32_e32 v6, v7, v4
	v_fma_f32 v3, -v3, v6, v5
	v_div_fmas_f32 v3, v3, v4, v6
	v_div_fixup_f32 v2, v3, v2, 1.0
	global_store_dword v[12:13], v2, off offset:164
	global_load_dword v2, v[120:121], off offset:168
	s_waitcnt vmcnt(0)
	v_fmac_f32_e32 v2, v8, v66
	v_mul_f32_e32 v2, 0xbfb8aa3b, v2
	v_exp_f32_e32 v2, v2
	s_nop 0
	v_add_f32_e32 v2, 1.0, v2
	v_div_scale_f32 v3, s[4:5], v2, v2, 1.0
	v_rcp_f32_e32 v4, v3
	s_nop 0
	v_fma_f32 v5, -v3, v4, 1.0
	v_fmac_f32_e32 v4, v5, v4
	v_div_scale_f32 v5, vcc, 1.0, v2, 1.0
	v_mul_f32_e32 v6, v5, v4
	v_fma_f32 v7, -v3, v6, v5
	v_fmac_f32_e32 v6, v7, v4
	v_fma_f32 v3, -v3, v6, v5
	v_div_fmas_f32 v3, v3, v4, v6
	v_div_fixup_f32 v2, v3, v2, 1.0
	global_store_dword v[12:13], v2, off offset:168
	global_load_dword v2, v[132:133], off
	s_waitcnt vmcnt(0)
	v_fmac_f32_e32 v2, v9, v66
	v_mul_f32_e32 v2, 0xbfb8aa3b, v2
	v_exp_f32_e32 v2, v2
	s_nop 0
	v_add_f32_e32 v2, 1.0, v2
	v_div_scale_f32 v3, s[4:5], v2, v2, 1.0
	v_rcp_f32_e32 v4, v3
	s_nop 0
	v_fma_f32 v5, -v3, v4, 1.0
	v_fmac_f32_e32 v4, v5, v4
	v_div_scale_f32 v5, vcc, 1.0, v2, 1.0
	v_mul_f32_e32 v6, v5, v4
	v_fma_f32 v7, -v3, v6, v5
	v_fmac_f32_e32 v6, v7, v4
	v_fma_f32 v3, -v3, v6, v5
	v_div_fmas_f32 v3, v3, v4, v6
	v_div_fixup_f32 v4, v3, v2, 1.0
	v_lshl_add_u64 v[2:3], v[10:11], 0, v[98:99]
	global_store_dword v[2:3], v4, off

.LBB0_988:
	global_load_dword v146, v162, s[54:55] offset:128
	global_load_dword v147, v[106:107], off
	global_load_dwordx4 v[62:65], v[134:135], off
	global_load_dwordx4 v[58:61], v[134:135], off offset:32
	global_load_dwordx4 v[46:49], v[134:135], off offset:96
	global_load_dwordx4 v[54:57], v[134:135], off offset:64
	global_load_dwordx4 v[34:37], v[134:135], off offset:224
	global_load_dwordx4 v[38:41], v[134:135], off offset:192
	global_load_dwordx4 v[42:45], v[134:135], off offset:160
	global_load_dwordx4 v[50:53], v[134:135], off offset:128
	v_and_b32_e32 v67, 64, v161
	v_mul_f32_e64 v72, v18, v66
	v_mul_f32_e64 v73, v19, v66
	v_mul_f32_e64 v68, v20, v66
	v_mul_f32_e64 v69, v21, v66
	v_mul_f32_e64 v18, v32, v66
	v_mul_f32_e64 v19, v33, v66
	v_mul_f32_e64 v32, v72, v72
	v_mul_f32_e64 v33, v73, v73
	v_mul_f32_e64 v70, v22, v66
	v_mul_f32_e64 v71, v23, v66
	v_mul_f32_e64 v22, v28, v66
	v_mul_f32_e64 v23, v29, v66
	v_mul_f32_e64 v28, v68, v68
	v_mul_f32_e64 v29, v69, v69
	v_add_f32_e32 v32, v32, v33
	v_add_f32_e32 v28, v28, v32
	v_mul_f32_e64 v24, v24, v66
	v_mul_f32_e64 v25, v25, v66
	v_mul_f32_e64 v20, v30, v66
	v_mul_f32_e64 v21, v31, v66
	v_mul_f32_e64 v26, v26, v66
	v_mul_f32_e64 v27, v27, v66
	v_mul_f32_e64 v16, v16, v66
	v_mul_f32_e64 v17, v17, v66
	v_mul_f32_e64 v14, v14, v66
	v_mul_f32_e64 v15, v15, v66
	v_mul_f32_e64 v12, v12, v66
	v_mul_f32_e64 v13, v13, v66
	v_mul_f32_e64 v10, v10, v66
	v_mul_f32_e64 v11, v11, v66
	v_mul_f32_e64 v8, v8, v66
	v_mul_f32_e64 v9, v9, v66
	v_mul_f32_e64 v6, v6, v66
	v_mul_f32_e64 v7, v7, v66
	v_mul_f32_e64 v4, v4, v66
	v_mul_f32_e64 v5, v5, v66
	v_mul_f32_e64 v2, v2, v66
	v_mul_f32_e64 v3, v3, v66
	v_add_u32_e32 v149, 64, v67
	v_mul_f32_e64 v66, v70, v70
	v_mul_f32_e64 v67, v71, v71
	v_add_f32_e32 v28, v29, v28
	v_add_f32_e32 v28, v66, v28
	v_mul_f32_e64 v30, v24, v24
	v_mul_f32_e64 v31, v25, v25
	v_add_f32_e32 v28, v67, v28
	v_add_f32_e32 v28, v30, v28
	v_mul_f32_e64 v80, v26, v26
	v_mul_f32_e64 v81, v27, v27
	v_add_f32_e32 v28, v31, v28
	v_add_f32_e32 v28, v80, v28
	v_mul_f32_e64 v78, v22, v22
	v_mul_f32_e64 v79, v23, v23
	v_add_f32_e32 v28, v81, v28
	v_add_f32_e32 v28, v78, v28
	v_mul_f32_e64 v76, v20, v20
	v_mul_f32_e64 v77, v21, v21
	v_add_f32_e32 v28, v79, v28
	v_add_f32_e32 v28, v76, v28
	v_mul_f32_e64 v74, v18, v18
	v_mul_f32_e64 v75, v19, v19
	v_add_f32_e32 v28, v77, v28
	v_add_f32_e32 v28, v74, v28
	v_mul_f32_e64 v96, v2, v2
	v_mul_f32_e64 v97, v3, v3
	v_add_f32_e32 v28, v75, v28
	v_add_f32_e32 v28, v96, v28
	v_mul_f32_e64 v94, v4, v4
	v_mul_f32_e64 v95, v5, v5
	v_add_f32_e32 v28, v97, v28
	v_add_f32_e32 v28, v94, v28
	v_mul_f32_e64 v92, v6, v6
	v_mul_f32_e64 v93, v7, v7
	v_add_f32_e32 v28, v95, v28
	v_add_f32_e32 v28, v92, v28
	v_mul_f32_e64 v90, v8, v8
	v_mul_f32_e64 v91, v9, v9
	v_add_f32_e32 v28, v93, v28
	v_add_f32_e32 v28, v90, v28
	v_mul_f32_e64 v88, v10, v10
	v_mul_f32_e64 v89, v11, v11
	v_add_f32_e32 v28, v91, v28
	v_add_f32_e32 v28, v88, v28
	v_mul_f32_e64 v86, v12, v12
	v_mul_f32_e64 v87, v13, v13
	v_add_f32_e32 v28, v89, v28
	v_add_f32_e32 v28, v86, v28
	v_mul_f32_e64 v84, v14, v14
	v_mul_f32_e64 v85, v15, v15
	v_add_f32_e32 v28, v87, v28
	v_xor_b32_e32 v148, 32, v161
	v_add_f32_e32 v28, v84, v28
	v_mul_f32_e64 v82, v16, v16
	v_mul_f32_e64 v83, v17, v17
	v_cmp_lt_i32_e32 vcc, v148, v149
	v_add_f32_e32 v28, v85, v28
	v_add_f32_e32 v28, v82, v28
	v_cndmask_b32_e32 v148, v161, v148, vcc
	v_lshlrev_b32_e32 v148, 2, v148
	v_add_f32_e32 v76, v83, v28
	ds_bpermute_b32 v77, v148, v76
	s_waitcnt vmcnt(9)
	v_cvt_f32_i32_e32 v33, v146
	s_waitcnt vmcnt(8)
	v_mul_f32_e32 v74, v147, v33
	v_and_b32_e32 v75, 0x7fffffff, v74
	v_lshrrev_b32_e32 v28, 23, v75
	v_and_b32_e32 v29, 0x7fffff, v75
	v_cmp_nlt_f32_e64 s[12:13], |v74|, s23
	v_add_u32_e32 v31, 0xffffff88, v28
	v_or_b32_e32 v29, 0x800000, v29
	s_and_saveexec_b64 s[4:5], s[12:13]
	s_xor_b64 s[68:69], exec, s[4:5]
	s_cbranch_execz .LBB0_990
	v_mad_u64_u32 v[66:67], s[8:9], v29, s24, 0
	v_mov_b32_e32 v78, v67
	v_mov_b32_e32 v79, v99
	v_mad_u64_u32 v[78:79], s[8:9], v29, s25, v[78:79]
	v_mov_b32_e32 v80, v79
	v_mov_b32_e32 v81, v99
	v_mad_u64_u32 v[80:81], s[8:9], v29, s28, v[80:81]
	v_cmp_lt_u32_e32 vcc, 63, v31
	v_mov_b32_e32 v82, v81
	v_mov_b32_e32 v83, v99
	v_cndmask_b32_e32 v28, 0, v158, vcc
	v_mad_u64_u32 v[82:83], s[8:9], v29, s29, v[82:83]
	v_add_u32_e32 v28, v28, v31
	v_mov_b32_e32 v84, v83
	v_mov_b32_e32 v85, v99
	v_cmp_lt_u32_e64 s[4:5], 31, v28
	v_mad_u64_u32 v[84:85], s[8:9], v29, s33, v[84:85]
	s_nop 0
	v_cndmask_b32_e64 v30, 0, v159, s[4:5]
	v_mov_b32_e32 v86, v85
	v_mov_b32_e32 v87, v99
	v_add_u32_e32 v28, v30, v28
	v_mad_u64_u32 v[86:87], s[8:9], v29, s47, v[86:87]
	v_cmp_lt_u32_e64 s[6:7], 31, v28
	v_mov_b32_e32 v88, v87
	v_mov_b32_e32 v89, v99
	v_cndmask_b32_e64 v30, 0, v159, s[6:7]
	v_mad_u64_u32 v[88:89], s[8:9], v29, s50, v[88:89]
	v_add_u32_e32 v28, v30, v28
	v_cndmask_b32_e32 v30, v86, v82, vcc
	v_cndmask_b32_e32 v32, v88, v84, vcc
	v_cndmask_b32_e32 v79, v89, v86, vcc
	v_cndmask_b32_e64 v67, v32, v30, s[4:5]
	v_cndmask_b32_e64 v32, v79, v32, s[4:5]
	v_cndmask_b32_e32 v79, v84, v80, vcc
	v_cndmask_b32_e64 v30, v30, v79, s[4:5]
	v_sub_u32_e32 v81, 32, v28
	v_cmp_eq_u32_e64 s[8:9], 0, v28
	v_cndmask_b32_e32 v28, v82, v78, vcc
	v_cndmask_b32_e64 v32, v32, v67, s[6:7]
	v_cndmask_b32_e64 v67, v67, v30, s[6:7]
	v_cndmask_b32_e64 v78, v79, v28, s[4:5]
	v_alignbit_b32 v83, v32, v67, v81
	v_cndmask_b32_e64 v30, v30, v78, s[6:7]
	v_cndmask_b32_e32 v66, v80, v66, vcc
	v_cndmask_b32_e64 v32, v83, v32, s[8:9]
	v_alignbit_b32 v79, v67, v30, v81
	v_cndmask_b32_e64 v28, v28, v66, s[4:5]
	v_cndmask_b32_e64 v67, v79, v67, s[8:9]
	v_bfe_u32 v83, v32, 29, 1
	v_cndmask_b32_e64 v28, v78, v28, s[6:7]
	v_alignbit_b32 v79, v32, v67, 30
	v_sub_u32_e32 v84, 0, v83
	v_alignbit_b32 v66, v30, v28, v81
	v_xor_b32_e32 v79, v79, v84
	v_cndmask_b32_e64 v30, v66, v30, s[8:9]
	v_alignbit_b32 v66, v67, v30, 30
	v_ffbh_u32_e32 v67, v79
	v_min_u32_e32 v67, 32, v67
	v_alignbit_b32 v28, v30, v28, 30
	v_xor_b32_e32 v66, v66, v84
	v_sub_u32_e32 v78, 31, v67
	v_xor_b32_e32 v28, v28, v84
	v_alignbit_b32 v79, v79, v66, v78
	v_alignbit_b32 v28, v66, v28, v78
	v_alignbit_b32 v30, v79, v28, 9
	v_ffbh_u32_e32 v66, v30
	v_min_u32_e32 v66, 32, v66
	v_lshrrev_b32_e32 v82, 29, v32
	v_not_b32_e32 v78, v66
	v_alignbit_b32 v28, v30, v28, v78
	v_lshlrev_b32_e32 v30, 31, v82
	v_or_b32_e32 v78, 0x33000000, v30
	v_add_lshl_u32 v66, v66, v67, 23
	v_lshrrev_b32_e32 v28, 9, v28
	v_sub_u32_e32 v66, v78, v66
	v_or_b32_e32 v30, 0.5, v30
	v_lshlrev_b32_e32 v67, 23, v67
	v_or_b32_e32 v28, v66, v28
	v_lshrrev_b32_e32 v66, 9, v79
	v_sub_u32_e32 v30, v30, v67
	v_or_b32_e32 v30, v66, v30
	v_mul_f32_e32 v66, 0x3fc90fda, v30
	v_fma_f32 v67, v30, s51, -v66
	v_fmac_f32_e32 v67, 0x33a22168, v30
	v_fmac_f32_e32 v67, 0x3fc90fda, v28
	v_lshrrev_b32_e32 v30, 30, v32
	v_add_f32_e32 v28, v66, v67
	v_add_u32_e32 v78, v83, v30

.LBB0_1093:
	s_and_b32 s33, s28, 1
	s_bfe_u32 s29, s28, 0x20001
	s_lshl_b32 s4, s33, 23
	s_add_u32 s18, s56, s4
	s_addc_u32 s19, s57, 0
	s_cmp_eq_u32 s33, 0
	s_cselect_b64 s[6:7], -1, 0
	s_and_b64 s[4:5], s[6:7], exec
	s_cselect_b32 s23, s65, s67
	s_cselect_b32 s22, s64, s66
	s_lshl_b32 s51, s29, 9
	s_and_b32 s16, s3, 0xffffff80
	v_or_b32_e32 v2, s51, v1
	v_or_b32_e32 v119, s16, v126
	v_lshlrev_b32_e32 v114, 2, v2
	v_mul_hi_i32 v3, v119, s24
	v_lshl_add_u64 v[32:33], s[22:23], 0, v[114:115]
	v_cmp_gt_i32_e64 s[4:5], s21, v119
	v_add_u32_e32 v139, v3, v119
	v_lshlrev_b32_e32 v114, 1, v2
	v_mov_b32_e32 v4, 0
	v_mov_b32_e32 v5, 0
	v_mov_b32_e32 v6, 0
	v_mov_b32_e32 v7, 0
	s_waitcnt vmcnt(63) expcnt(7) lgkmcnt(15)
	s_barrier
	s_and_saveexec_b64 s[8:9], s[4:5]
	s_cbranch_execz .LBB0_1095
	v_lshrrev_b32_e32 v2, 31, v139
	v_ashrrev_i32_e32 v3, 8, v139
	v_add_u32_e32 v2, v3, v2
	v_mul_i32_i24_e32 v4, 0xfffffe01, v2
	v_ashrrev_i32_e32 v3, 31, v2
	v_add_lshl_u32 v4, v4, v119, 4
	v_ashrrev_i32_e32 v5, 31, v4
	v_lshlrev_b64 v[2:3], 20, v[2:3]
	v_lshl_add_u64 v[2:3], s[18:19], 0, v[2:3]
	v_lshlrev_b64 v[4:5], 7, v[4:5]
	v_lshl_add_u64 v[2:3], v[2:3], 0, v[4:5]
	v_lshl_add_u64 v[2:3], v[2:3], 0, v[114:115]
	global_load_dwordx4 v[2:5], v[2:3], off
	s_nop 0
	global_load_dwordx4 v[6:9], v[32:33], off
	global_load_dwordx4 v[10:13], v[32:33], off offset:16
	s_waitcnt vmcnt(2)
	v_and_b32_e32 v15, 0xffff0000, v2
	v_lshlrev_b32_e32 v14, 16, v2
	v_and_b32_e32 v17, 0xffff0000, v3
	v_lshlrev_b32_e32 v16, 16, v3
	v_and_b32_e32 v3, 0xffff0000, v4
	v_lshlrev_b32_e32 v2, 16, v4
	v_and_b32_e32 v19, 0xffff0000, v5
	v_lshlrev_b32_e32 v18, 16, v5
	s_waitcnt vmcnt(1)
	v_add_f32_e64 v4, v6, v14
	v_add_f32_e64 v5, v7, v15
	v_add_f32_e64 v6, v8, v16
	v_add_f32_e64 v7, v9, v17
	s_waitcnt vmcnt(0)
	v_add_f32_e64 v2, v10, v2
	v_add_f32_e64 v3, v11, v3
	v_add_f32_e64 v8, v12, v18
	v_add_f32_e64 v9, v13, v19
	v_cvt_pk_bf16_f32 v4, v4, v5
	v_cvt_pk_bf16_f32 v5, v6, v7
	v_cvt_pk_bf16_f32 v6, v2, v3
	v_cvt_pk_bf16_f32 v7, v8, v9
.LBB0_1095:
	s_or_b64 exec, exec, s[8:9]
	s_bfe_u32 s50, s28, 0x10003
	s_and_b64 s[6:7], s[6:7], exec
	s_cselect_b32 s6, s27, s31
	s_cselect_b32 s7, s26, s30
	s_lshl_b32 s8, s29, 17
	s_lshl_b32 s9, s50, 19
	s_or_b32 s8, s8, s9
	s_add_u32 s8, s7, s8
	s_addc_u32 s9, s6, 0
	global_load_dwordx4 v[8:11], v116, s[8:9]
	v_add_u32_e32 v121, s16, v127
	v_mul_hi_i32 v2, v121, s24
	v_cmp_gt_i32_e64 s[6:7], s21, v121
	v_mov_b32_e32 v12, 0
	v_add_u32_e32 v142, v2, v121
	v_mov_b32_e32 v16, 0
	v_mov_b32_e32 v17, 0
	v_mov_b32_e32 v18, 0
	v_mov_b32_e32 v19, 0
	s_and_saveexec_b64 s[10:11], s[6:7]
	s_cbranch_execz .LBB0_1097
	v_lshrrev_b32_e32 v2, 31, v142
	v_ashrrev_i32_e32 v3, 8, v142
	v_add_u32_e32 v2, v3, v2
	v_mul_i32_i24_e32 v13, 0xfffffe01, v2
	v_ashrrev_i32_e32 v3, 31, v2
	v_add_lshl_u32 v14, v13, v121, 4
	v_ashrrev_i32_e32 v15, 31, v14
	v_lshlrev_b64 v[2:3], 20, v[2:3]
	v_lshl_add_u64 v[2:3], s[18:19], 0, v[2:3]
	v_lshlrev_b64 v[14:15], 7, v[14:15]
	v_lshl_add_u64 v[2:3], v[2:3], 0, v[14:15]
	v_lshl_add_u64 v[2:3], v[2:3], 0, v[114:115]
	global_load_dwordx4 v[14:17], v[2:3], off
	global_load_dwordx4 v[18:21], v[32:33], off
	global_load_dwordx4 v[22:25], v[32:33], off offset:16
	s_waitcnt vmcnt(2)
	v_and_b32_e32 v3, 0xffff0000, v14
	v_lshlrev_b32_e32 v2, 16, v14
	v_and_b32_e32 v27, 0xffff0000, v15
	v_lshlrev_b32_e32 v26, 16, v15
	v_and_b32_e32 v15, 0xffff0000, v16
	v_lshlrev_b32_e32 v14, 16, v16
	v_and_b32_e32 v29, 0xffff0000, v17
	v_lshlrev_b32_e32 v28, 16, v17
	s_waitcnt vmcnt(1)
	v_add_f32_e64 v2, v18, v2
	v_add_f32_e64 v3, v19, v3
	v_add_f32_e64 v18, v20, v26
	v_add_f32_e64 v19, v21, v27
	s_waitcnt vmcnt(0)
	v_add_f32_e64 v14, v22, v14
	v_add_f32_e64 v15, v23, v15
	v_add_f32_e64 v20, v24, v28
	v_add_f32_e64 v21, v25, v29
	v_cvt_pk_bf16_f32 v16, v2, v3
	v_cvt_pk_bf16_f32 v17, v18, v19
	v_cvt_pk_bf16_f32 v18, v14, v15
	v_cvt_pk_bf16_f32 v19, v20, v21
.LBB0_1097:
	s_or_b64 exec, exec, s[10:11]
	v_lshl_add_u64 v[122:123], s[8:9], 0, v[116:117]
	v_add_co_u32_e32 v2, vcc, 0x1000, v122
	v_add_u32_e32 v140, s16, v128
	s_nop 0
	v_addc_co_u32_e32 v3, vcc, 0, v123, vcc
	global_load_dwordx4 v[20:23], v[2:3], off
	v_mul_hi_i32 v2, v140, s24
	v_cmp_gt_i32_e64 s[8:9], s21, v140
	v_add_u32_e32 v143, v2, v140
	v_mov_b32_e32 v13, 0
	v_mov_b32_e32 v14, 0
	v_mov_b32_e32 v15, 0
	s_and_saveexec_b64 s[10:11], s[8:9]
	s_cbranch_execz .LBB0_1099
	v_lshrrev_b32_e32 v2, 31, v143
	v_ashrrev_i32_e32 v3, 8, v143
	v_add_u32_e32 v2, v3, v2
	v_mul_i32_i24_e32 v12, 0xfffffe01, v2
	v_ashrrev_i32_e32 v3, 31, v2
	v_add_lshl_u32 v12, v12, v140, 4
	v_ashrrev_i32_e32 v13, 31, v12
	v_lshlrev_b64 v[2:3], 20, v[2:3]
	v_lshl_add_u64 v[2:3], s[18:19], 0, v[2:3]
	v_lshlrev_b64 v[12:13], 7, v[12:13]
	v_lshl_add_u64 v[2:3], v[2:3], 0, v[12:13]
	v_lshl_add_u64 v[2:3], v[2:3], 0, v[114:115]
	global_load_dwordx4 v[12:15], v[2:3], off
	global_load_dwordx4 v[24:27], v[32:33], off
	global_load_dwordx4 v[28:31], v[32:33], off offset:16
	s_waitcnt vmcnt(2)
	v_and_b32_e32 v3, 0xffff0000, v12
	v_lshlrev_b32_e32 v2, 16, v12
	v_and_b32_e32 v35, 0xffff0000, v13
	v_lshlrev_b32_e32 v34, 16, v13
	v_and_b32_e32 v13, 0xffff0000, v14
	v_lshlrev_b32_e32 v12, 16, v14
	v_and_b32_e32 v37, 0xffff0000, v15
	v_lshlrev_b32_e32 v36, 16, v15
	s_waitcnt vmcnt(1)
	v_add_f32_e64 v2, v24, v2
	v_add_f32_e64 v3, v25, v3
	v_add_f32_e64 v14, v26, v34
	v_add_f32_e64 v15, v27, v35
	s_waitcnt vmcnt(0)
	v_add_f32_e64 v24, v28, v12
	v_add_f32_e64 v25, v29, v13
	v_add_f32_e64 v26, v30, v36
	v_add_f32_e64 v27, v31, v37
	v_cvt_pk_bf16_f32 v12, v2, v3
	v_cvt_pk_bf16_f32 v13, v14, v15
	v_cvt_pk_bf16_f32 v14, v24, v25
	v_cvt_pk_bf16_f32 v15, v26, v27
.LBB0_1099:
	s_or_b64 exec, exec, s[10:11]
	v_add_co_u32_e32 v2, vcc, 0x2000, v122
	v_add_u32_e32 v141, s16, v129
	s_nop 0
	v_addc_co_u32_e32 v3, vcc, 0, v123, vcc
	global_load_dwordx4 v[24:27], v[2:3], off
	v_mul_hi_i32 v3, v141, s24
	v_cmp_gt_i32_e64 s[10:11], s21, v141
	v_mov_b32_e32 v2, 0
	v_add_u32_e32 v144, v3, v141
	v_mov_b32_e32 v28, 0
	v_mov_b32_e32 v29, 0
	v_mov_b32_e32 v30, 0
	v_mov_b32_e32 v31, 0
	s_and_saveexec_b64 s[46:47], s[10:11]
	s_cbranch_execz .LBB0_1101
	v_lshrrev_b32_e32 v3, 31, v144
	v_ashrrev_i32_e32 v28, 8, v144
	v_add_u32_e32 v28, v28, v3
	v_mul_i32_i24_e32 v3, 0xfffffe01, v28
	v_ashrrev_i32_e32 v29, 31, v28
	v_add_lshl_u32 v30, v3, v141, 4
	v_ashrrev_i32_e32 v31, 31, v30
	v_lshlrev_b64 v[28:29], 20, v[28:29]
	v_lshl_add_u64 v[28:29], s[18:19], 0, v[28:29]
	v_lshlrev_b64 v[30:31], 7, v[30:31]
	v_lshl_add_u64 v[28:29], v[28:29], 0, v[30:31]
	v_lshl_add_u64 v[28:29], v[28:29], 0, v[114:115]
	global_load_dwordx4 v[28:31], v[28:29], off
	s_nop 0
	global_load_dwordx4 v[34:37], v[32:33], off
	global_load_dwordx4 v[38:41], v[32:33], off offset:16
	s_waitcnt vmcnt(2)
	v_and_b32_e32 v33, 0xffff0000, v28
	v_lshlrev_b32_e32 v32, 16, v28
	v_and_b32_e32 v43, 0xffff0000, v29
	v_lshlrev_b32_e32 v42, 16, v29
	v_and_b32_e32 v29, 0xffff0000, v30
	v_lshlrev_b32_e32 v28, 16, v30
	v_and_b32_e32 v45, 0xffff0000, v31
	v_lshlrev_b32_e32 v44, 16, v31
	s_waitcnt vmcnt(1)
	v_add_f32_e64 v30, v34, v32
	v_add_f32_e64 v31, v35, v33
	v_add_f32_e64 v32, v36, v42
	v_add_f32_e64 v33, v37, v43
	s_waitcnt vmcnt(0)
	v_add_f32_e64 v34, v38, v28
	v_add_f32_e64 v35, v39, v29
	v_add_f32_e64 v36, v40, v44
	v_add_f32_e64 v37, v41, v45
	v_cvt_pk_bf16_f32 v28, v30, v31
	v_cvt_pk_bf16_f32 v29, v32, v33
	v_cvt_pk_bf16_f32 v30, v34, v35
	v_cvt_pk_bf16_f32 v31, v36, v37
.LBB0_1101:
	s_or_b64 exec, exec, s[46:47]
	v_add_co_u32_e32 v32, vcc, 0x3000, v122
	v_mov_b32_e32 v3, 0
	s_nop 0
	v_addc_co_u32_e32 v33, vcc, 0, v123, vcc
	global_load_dwordx4 v[32:35], v[32:33], off
	ds_write_b128 v130, v[4:7]
	s_waitcnt vmcnt(3)
	ds_write_b128 v130, v[8:11] offset:18432
	ds_write_b128 v131, v[16:19]
	s_waitcnt vmcnt(2)
	ds_write_b128 v131, v[20:23] offset:18432
	ds_write_b128 v132, v[12:15]
	s_waitcnt vmcnt(1)
	ds_write_b128 v132, v[24:27] offset:18432
	ds_write_b128 v133, v[28:31]
	v_add_u32_e32 v5, s51, v1
	v_lshlrev_b32_e32 v114, 2, v5
	v_mov_b32_e32 v4, 0
	v_lshl_add_u64 v[124:125], s[22:23], 0, v[114:115]
	v_lshlrev_b32_e32 v114, 1, v5
	v_mov_b32_e32 v5, 0
	s_waitcnt vmcnt(0)
	ds_write_b128 v133, v[32:35] offset:18432
	s_and_saveexec_b64 s[22:23], s[4:5]
	s_cbranch_execz .LBB0_1103
	v_lshrrev_b32_e32 v2, 31, v139
	v_ashrrev_i32_e32 v3, 8, v139
	v_add_u32_e32 v2, v3, v2
	v_mul_i32_i24_e32 v4, 0xfffffe01, v2
	v_ashrrev_i32_e32 v3, 31, v2
	v_add_lshl_u32 v4, v4, v119, 4
	v_ashrrev_i32_e32 v5, 31, v4
	v_lshlrev_b64 v[2:3], 20, v[2:3]
	v_lshl_add_u64 v[2:3], s[18:19], 0, v[2:3]
	v_lshlrev_b64 v[4:5], 7, v[4:5]
	v_lshl_add_u64 v[2:3], v[2:3], 0, v[4:5]
	v_lshl_add_u64 v[2:3], v[2:3], 0, v[114:115]
	global_load_dwordx4 v[2:5], v[2:3], off offset:128
	s_nop 0
	global_load_dwordx4 v[6:9], v[124:125], off offset:256
	global_load_dwordx4 v[10:13], v[124:125], off offset:272
	s_waitcnt vmcnt(2)
	v_and_b32_e32 v15, 0xffff0000, v2
	v_lshlrev_b32_e32 v14, 16, v2
	v_and_b32_e32 v17, 0xffff0000, v3
	v_lshlrev_b32_e32 v16, 16, v3
	v_and_b32_e32 v3, 0xffff0000, v4
	v_lshlrev_b32_e32 v2, 16, v4
	v_and_b32_e32 v19, 0xffff0000, v5
	v_lshlrev_b32_e32 v18, 16, v5
	s_waitcnt vmcnt(1)
	v_add_f32_e64 v4, v6, v14
	v_add_f32_e64 v5, v7, v15
	v_add_f32_e64 v6, v8, v16
	v_add_f32_e64 v7, v9, v17
	s_waitcnt vmcnt(0)
	v_add_f32_e64 v8, v10, v2
	v_add_f32_e64 v9, v11, v3
	v_add_f32_e64 v10, v12, v18
	v_add_f32_e64 v11, v13, v19
	v_cvt_pk_bf16_f32 v2, v4, v5
	v_cvt_pk_bf16_f32 v3, v6, v7
	v_cvt_pk_bf16_f32 v4, v8, v9
	v_cvt_pk_bf16_f32 v5, v10, v11
.LBB0_1103:
	s_or_b64 exec, exec, s[22:23]
	v_add_co_u32_e32 v6, vcc, 0x4000, v122
	v_mov_b32_e32 v26, 0
	s_nop 0
	v_addc_co_u32_e32 v7, vcc, 0, v123, vcc
	global_load_dwordx4 v[22:25], v[6:7], off
	v_mov_b32_e32 v30, 0
	v_mov_b32_e32 v31, 0
	v_mov_b32_e32 v32, 0
	v_mov_b32_e32 v33, 0
	s_and_saveexec_b64 s[22:23], s[6:7]
	s_cbranch_execz .LBB0_1105
	v_lshrrev_b32_e32 v6, 31, v142
	v_ashrrev_i32_e32 v7, 8, v142
	v_add_u32_e32 v6, v7, v6
	v_mul_i32_i24_e32 v8, 0xfffffe01, v6
	v_ashrrev_i32_e32 v7, 31, v6
	v_add_lshl_u32 v8, v8, v121, 4
	v_ashrrev_i32_e32 v9, 31, v8
	v_lshlrev_b64 v[6:7], 20, v[6:7]
	v_lshl_add_u64 v[6:7], s[18:19], 0, v[6:7]
	v_lshlrev_b64 v[8:9], 7, v[8:9]
	v_lshl_add_u64 v[6:7], v[6:7], 0, v[8:9]
	v_lshl_add_u64 v[6:7], v[6:7], 0, v[114:115]
	global_load_dwordx4 v[6:9], v[6:7], off offset:128
	s_nop 0
	global_load_dwordx4 v[10:13], v[124:125], off offset:256
	global_load_dwordx4 v[14:17], v[124:125], off offset:272
	s_waitcnt vmcnt(2)
	v_and_b32_e32 v19, 0xffff0000, v6
	v_lshlrev_b32_e32 v18, 16, v6
	v_and_b32_e32 v21, 0xffff0000, v7
	v_lshlrev_b32_e32 v20, 16, v7
	v_and_b32_e32 v7, 0xffff0000, v8
	v_lshlrev_b32_e32 v6, 16, v8
	v_and_b32_e32 v29, 0xffff0000, v9
	v_lshlrev_b32_e32 v28, 16, v9
	s_waitcnt vmcnt(1)
	v_add_f32_e64 v8, v10, v18
	v_add_f32_e64 v9, v11, v19
	v_add_f32_e64 v10, v12, v20
	v_add_f32_e64 v11, v13, v21
	s_waitcnt vmcnt(0)
	v_add_f32_e64 v6, v14, v6
	v_add_f32_e64 v7, v15, v7
	v_add_f32_e64 v12, v16, v28
	v_add_f32_e64 v13, v17, v29
	v_cvt_pk_bf16_f32 v30, v8, v9
	v_cvt_pk_bf16_f32 v31, v10, v11
	v_cvt_pk_bf16_f32 v32, v6, v7
	v_cvt_pk_bf16_f32 v33, v12, v13
.LBB0_1105:
	s_or_b64 exec, exec, s[22:23]
	v_add_co_u32_e32 v6, vcc, 0x5000, v122
	v_mov_b32_e32 v27, 0
	s_nop 0
	v_addc_co_u32_e32 v7, vcc, 0, v123, vcc
	global_load_dwordx4 v[34:37], v[6:7], off
	v_mov_b32_e32 v28, 0
	v_mov_b32_e32 v29, 0
	s_and_saveexec_b64 s[22:23], s[8:9]
	s_cbranch_execz .LBB0_1107
	v_lshrrev_b32_e32 v6, 31, v143
	v_ashrrev_i32_e32 v7, 8, v143
	v_add_u32_e32 v6, v7, v6
	v_mul_i32_i24_e32 v8, 0xfffffe01, v6
	v_ashrrev_i32_e32 v7, 31, v6
	v_add_lshl_u32 v8, v8, v140, 4
	v_ashrrev_i32_e32 v9, 31, v8
	v_lshlrev_b64 v[6:7], 20, v[6:7]
	v_lshl_add_u64 v[6:7], s[18:19], 0, v[6:7]
	v_lshlrev_b64 v[8:9], 7, v[8:9]
	v_lshl_add_u64 v[6:7], v[6:7], 0, v[8:9]
	v_lshl_add_u64 v[6:7], v[6:7], 0, v[114:115]
	global_load_dwordx4 v[6:9], v[6:7], off offset:128
	s_nop 0
	global_load_dwordx4 v[10:13], v[124:125], off offset:256
	global_load_dwordx4 v[14:17], v[124:125], off offset:272
	s_waitcnt vmcnt(2)
	v_and_b32_e32 v19, 0xffff0000, v6
	v_lshlrev_b32_e32 v18, 16, v6
	v_and_b32_e32 v21, 0xffff0000, v7
	v_lshlrev_b32_e32 v20, 16, v7
	v_and_b32_e32 v7, 0xffff0000, v8
	v_lshlrev_b32_e32 v6, 16, v8
	v_and_b32_e32 v27, 0xffff0000, v9
	v_lshlrev_b32_e32 v26, 16, v9
	s_waitcnt vmcnt(1)
	v_add_f32_e64 v8, v10, v18
	v_add_f32_e64 v9, v11, v19
	v_add_f32_e64 v10, v12, v20
	v_add_f32_e64 v11, v13, v21
	s_waitcnt vmcnt(0)
	v_add_f32_e64 v6, v14, v6
	v_add_f32_e64 v7, v15, v7
	v_add_f32_e64 v12, v16, v26
	v_add_f32_e64 v13, v17, v27
	v_cvt_pk_bf16_f32 v26, v8, v9
	v_cvt_pk_bf16_f32 v27, v10, v11
	v_cvt_pk_bf16_f32 v28, v6, v7
	v_cvt_pk_bf16_f32 v29, v12, v13
.LBB0_1107:
	s_or_b64 exec, exec, s[22:23]
	v_add_co_u32_e32 v6, vcc, 0x6000, v122
	v_mov_b32_e32 v70, 0
	s_nop 0
	v_addc_co_u32_e32 v7, vcc, 0, v123, vcc
	global_load_dwordx4 v[38:41], v[6:7], off
	v_mov_b32_e32 v42, 0
	v_mov_b32_e32 v43, 0
	v_mov_b32_e32 v44, 0
	v_mov_b32_e32 v45, 0
	s_and_saveexec_b64 s[22:23], s[10:11]
	s_cbranch_execz .LBB0_1109
	v_lshrrev_b32_e32 v6, 31, v144
	v_ashrrev_i32_e32 v7, 8, v144
	v_add_u32_e32 v6, v7, v6
	v_mul_i32_i24_e32 v8, 0xfffffe01, v6
	v_ashrrev_i32_e32 v7, 31, v6
	v_add_lshl_u32 v8, v8, v141, 4
	v_ashrrev_i32_e32 v9, 31, v8
	v_lshlrev_b64 v[6:7], 20, v[6:7]
	v_lshl_add_u64 v[6:7], s[18:19], 0, v[6:7]
	v_lshlrev_b64 v[8:9], 7, v[8:9]
	v_lshl_add_u64 v[6:7], v[6:7], 0, v[8:9]
	v_lshl_add_u64 v[6:7], v[6:7], 0, v[114:115]
	global_load_dwordx4 v[6:9], v[6:7], off offset:128
	s_nop 0
	global_load_dwordx4 v[10:13], v[124:125], off offset:256
	global_load_dwordx4 v[14:17], v[124:125], off offset:272
	s_waitcnt vmcnt(2)
	v_and_b32_e32 v19, 0xffff0000, v6
	v_lshlrev_b32_e32 v18, 16, v6
	v_and_b32_e32 v21, 0xffff0000, v7
	v_lshlrev_b32_e32 v20, 16, v7
	v_and_b32_e32 v7, 0xffff0000, v8
	v_lshlrev_b32_e32 v6, 16, v8
	v_and_b32_e32 v43, 0xffff0000, v9
	v_lshlrev_b32_e32 v42, 16, v9
	s_waitcnt vmcnt(1)
	v_add_f32_e64 v8, v10, v18
	v_add_f32_e64 v9, v11, v19
	v_add_f32_e64 v10, v12, v20
	v_add_f32_e64 v11, v13, v21
	s_waitcnt vmcnt(0)
	v_add_f32_e64 v6, v14, v6
	v_add_f32_e64 v7, v15, v7
	v_add_f32_e64 v12, v16, v42
	v_add_f32_e64 v13, v17, v43
	v_cvt_pk_bf16_f32 v42, v8, v9
	v_cvt_pk_bf16_f32 v43, v10, v11
	v_cvt_pk_bf16_f32 v44, v6, v7
	v_cvt_pk_bf16_f32 v45, v12, v13
.LBB0_1109:
	s_or_b64 exec, exec, s[22:23]
	v_add_co_u32_e32 v6, vcc, 0x7000, v122
	v_mov_b32_e32 v71, 0
	s_nop 0
	v_addc_co_u32_e32 v7, vcc, 0, v123, vcc
	global_load_dwordx4 v[46:49], v[6:7], off
	s_waitcnt lgkmcnt(0)
	s_barrier
	ds_read_b128 v[10:13], v137 offset:18432
	ds_read_b128 v[18:21], v138
	ds_read_b128 v[6:9], v137 offset:23040
	ds_read_b128 v[14:17], v138 offset:4608
	v_mov_b32_e32 v72, 0
	v_mov_b32_e32 v73, 0
	ds_write_b128 v130, v[2:5] offset:36864
	s_waitcnt vmcnt(3)
	ds_write_b128 v130, v[22:25] offset:55296
	ds_write_b128 v131, v[30:33] offset:36864
	s_waitcnt vmcnt(2)
	ds_write_b128 v131, v[34:37] offset:55296
	ds_write_b128 v132, v[26:29] offset:36864
	s_waitcnt vmcnt(1)
	ds_write_b128 v132, v[38:41] offset:55296
	ds_write_b128 v133, v[42:45] offset:36864
	s_waitcnt vmcnt(0)
	ds_write_b128 v133, v[46:49] offset:55296
	s_and_saveexec_b64 s[22:23], s[4:5]
	s_cbranch_execz .LBB0_1111
	v_lshrrev_b32_e32 v2, 31, v139
	v_ashrrev_i32_e32 v3, 8, v139
	v_add_u32_e32 v2, v3, v2
	v_mul_i32_i24_e32 v4, 0xfffffe01, v2
	v_ashrrev_i32_e32 v3, 31, v2
	v_add_lshl_u32 v4, v4, v119, 4
	v_ashrrev_i32_e32 v5, 31, v4
	v_lshlrev_b64 v[2:3], 20, v[2:3]
	v_lshl_add_u64 v[2:3], s[18:19], 0, v[2:3]
	v_lshlrev_b64 v[4:5], 7, v[4:5]
	v_lshl_add_u64 v[2:3], v[2:3], 0, v[4:5]
	v_lshl_add_u64 v[2:3], v[2:3], 0, v[114:115]
	global_load_dwordx4 v[2:5], v[2:3], off offset:256
	s_nop 0
	global_load_dwordx4 v[22:25], v[124:125], off offset:512
	global_load_dwordx4 v[26:29], v[124:125], off offset:528
	s_waitcnt vmcnt(2)
	v_and_b32_e32 v31, 0xffff0000, v2
	v_lshlrev_b32_e32 v30, 16, v2
	v_and_b32_e32 v33, 0xffff0000, v3
	v_lshlrev_b32_e32 v32, 16, v3
	v_and_b32_e32 v3, 0xffff0000, v4
	v_lshlrev_b32_e32 v2, 16, v4
	v_and_b32_e32 v35, 0xffff0000, v5
	v_lshlrev_b32_e32 v34, 16, v5
	s_waitcnt vmcnt(1)
	v_add_f32_e64 v4, v22, v30
	v_add_f32_e64 v5, v23, v31
	v_add_f32_e64 v22, v24, v32
	v_add_f32_e64 v23, v25, v33
	s_waitcnt vmcnt(0)
	v_add_f32_e64 v2, v26, v2
	v_add_f32_e64 v3, v27, v3
	v_add_f32_e64 v24, v28, v34
	v_add_f32_e64 v25, v29, v35
	v_cvt_pk_bf16_f32 v70, v4, v5
	v_cvt_pk_bf16_f32 v71, v22, v23
	v_cvt_pk_bf16_f32 v72, v2, v3
	v_cvt_pk_bf16_f32 v73, v24, v25
.LBB0_1111:
	s_or_b64 exec, exec, s[22:23]
	v_add_co_u32_e32 v2, vcc, 0x8000, v122
	v_mov_b32_e32 v94, 0
	s_nop 0
	v_addc_co_u32_e32 v3, vcc, 0, v123, vcc
	global_load_dwordx4 v[90:93], v[2:3], off
	v_mov_b32_e32 v98, 0
	v_mov_b32_e32 v99, 0
	v_mov_b32_e32 v100, 0
	v_mov_b32_e32 v101, 0
	s_and_saveexec_b64 s[22:23], s[6:7]
	s_cbranch_execz .LBB0_1113
	v_lshrrev_b32_e32 v2, 31, v142
	v_ashrrev_i32_e32 v3, 8, v142
	v_add_u32_e32 v2, v3, v2
	v_mul_i32_i24_e32 v4, 0xfffffe01, v2
	v_ashrrev_i32_e32 v3, 31, v2
	v_add_lshl_u32 v4, v4, v121, 4
	v_ashrrev_i32_e32 v5, 31, v4
	v_lshlrev_b64 v[2:3], 20, v[2:3]
	v_lshl_add_u64 v[2:3], s[18:19], 0, v[2:3]
	v_lshlrev_b64 v[4:5], 7, v[4:5]
	v_lshl_add_u64 v[2:3], v[2:3], 0, v[4:5]
	v_lshl_add_u64 v[2:3], v[2:3], 0, v[114:115]
	global_load_dwordx4 v[2:5], v[2:3], off offset:256
	s_nop 0
	global_load_dwordx4 v[22:25], v[124:125], off offset:512
	global_load_dwordx4 v[26:29], v[124:125], off offset:528
	s_waitcnt vmcnt(2)
	v_and_b32_e32 v31, 0xffff0000, v2
	v_lshlrev_b32_e32 v30, 16, v2
	v_and_b32_e32 v33, 0xffff0000, v3
	v_lshlrev_b32_e32 v32, 16, v3
	v_and_b32_e32 v3, 0xffff0000, v4
	v_lshlrev_b32_e32 v2, 16, v4
	v_and_b32_e32 v35, 0xffff0000, v5
	v_lshlrev_b32_e32 v34, 16, v5
	s_waitcnt vmcnt(1)
	v_add_f32_e64 v4, v22, v30
	v_add_f32_e64 v5, v23, v31
	v_add_f32_e64 v22, v24, v32
	v_add_f32_e64 v23, v25, v33
	s_waitcnt vmcnt(0)
	v_add_f32_e64 v2, v26, v2
	v_add_f32_e64 v3, v27, v3
	v_add_f32_e64 v24, v28, v34
	v_add_f32_e64 v25, v29, v35
	v_cvt_pk_bf16_f32 v98, v4, v5
	v_cvt_pk_bf16_f32 v99, v22, v23
	v_cvt_pk_bf16_f32 v100, v2, v3
	v_cvt_pk_bf16_f32 v101, v24, v25
.LBB0_1113:
	s_or_b64 exec, exec, s[22:23]
	v_add_co_u32_e32 v2, vcc, 0x9000, v122
	v_mov_b32_e32 v95, 0
	s_nop 0
	v_addc_co_u32_e32 v3, vcc, 0, v123, vcc
	global_load_dwordx4 v[102:105], v[2:3], off
	v_mov_b32_e32 v96, 0
	v_mov_b32_e32 v97, 0
	s_and_saveexec_b64 s[22:23], s[8:9]
	s_cbranch_execz .LBB0_1115
	v_lshrrev_b32_e32 v2, 31, v143
	v_ashrrev_i32_e32 v3, 8, v143
	v_add_u32_e32 v2, v3, v2
	v_mul_i32_i24_e32 v4, 0xfffffe01, v2
	v_ashrrev_i32_e32 v3, 31, v2
	v_add_lshl_u32 v4, v4, v140, 4
	v_ashrrev_i32_e32 v5, 31, v4
	v_lshlrev_b64 v[2:3], 20, v[2:3]
	v_lshl_add_u64 v[2:3], s[18:19], 0, v[2:3]
	v_lshlrev_b64 v[4:5], 7, v[4:5]
	v_lshl_add_u64 v[2:3], v[2:3], 0, v[4:5]
	v_lshl_add_u64 v[2:3], v[2:3], 0, v[114:115]
	global_load_dwordx4 v[2:5], v[2:3], off offset:256
	s_nop 0
	global_load_dwordx4 v[22:25], v[124:125], off offset:512
	global_load_dwordx4 v[26:29], v[124:125], off offset:528
	s_waitcnt vmcnt(2)
	v_and_b32_e32 v31, 0xffff0000, v2
	v_lshlrev_b32_e32 v30, 16, v2
	v_and_b32_e32 v33, 0xffff0000, v3
	v_lshlrev_b32_e32 v32, 16, v3
	v_and_b32_e32 v3, 0xffff0000, v4
	v_lshlrev_b32_e32 v2, 16, v4
	v_and_b32_e32 v35, 0xffff0000, v5
	v_lshlrev_b32_e32 v34, 16, v5
	s_waitcnt vmcnt(1)
	v_add_f32_e64 v4, v22, v30
	v_add_f32_e64 v5, v23, v31
	v_add_f32_e64 v22, v24, v32
	v_add_f32_e64 v23, v25, v33
	s_waitcnt vmcnt(0)
	v_add_f32_e64 v2, v26, v2
	v_add_f32_e64 v3, v27, v3
	v_add_f32_e64 v24, v28, v34
	v_add_f32_e64 v25, v29, v35
	v_cvt_pk_bf16_f32 v94, v4, v5
	v_cvt_pk_bf16_f32 v95, v22, v23
	v_cvt_pk_bf16_f32 v96, v2, v3
	v_cvt_pk_bf16_f32 v97, v24, v25
.LBB0_1115:
	s_or_b64 exec, exec, s[22:23]
	v_add_co_u32_e32 v2, vcc, 0xa000, v122
	v_mov_b32_e32 v68, 0
	s_nop 0
	v_addc_co_u32_e32 v3, vcc, 0, v123, vcc
	global_load_dwordx4 v[106:109], v[2:3], off
	v_mov_b32_e32 v110, 0
	v_mov_b32_e32 v111, 0
	v_mov_b32_e32 v112, 0
	v_mov_b32_e32 v113, 0
	s_and_saveexec_b64 s[22:23], s[10:11]
	s_cbranch_execz .LBB0_1117
	v_lshrrev_b32_e32 v2, 31, v144
	v_ashrrev_i32_e32 v3, 8, v144
	v_add_u32_e32 v2, v3, v2
	v_mul_i32_i24_e32 v4, 0xfffffe01, v2
	v_ashrrev_i32_e32 v3, 31, v2
	v_add_lshl_u32 v4, v4, v141, 4
	v_ashrrev_i32_e32 v5, 31, v4
	v_lshlrev_b64 v[2:3], 20, v[2:3]
	v_lshl_add_u64 v[2:3], s[18:19], 0, v[2:3]
	v_lshlrev_b64 v[4:5], 7, v[4:5]
	v_lshl_add_u64 v[2:3], v[2:3], 0, v[4:5]
	v_lshl_add_u64 v[2:3], v[2:3], 0, v[114:115]
	global_load_dwordx4 v[2:5], v[2:3], off offset:256
	s_nop 0
	global_load_dwordx4 v[22:25], v[124:125], off offset:512
	global_load_dwordx4 v[26:29], v[124:125], off offset:528
	s_waitcnt vmcnt(2)
	v_and_b32_e32 v31, 0xffff0000, v2
	v_lshlrev_b32_e32 v30, 16, v2
	v_and_b32_e32 v33, 0xffff0000, v3
	v_lshlrev_b32_e32 v32, 16, v3
	v_and_b32_e32 v3, 0xffff0000, v4
	v_lshlrev_b32_e32 v2, 16, v4
	v_and_b32_e32 v35, 0xffff0000, v5
	v_lshlrev_b32_e32 v34, 16, v5
	s_waitcnt vmcnt(1)
	v_add_f32_e64 v4, v22, v30
	v_add_f32_e64 v5, v23, v31
	v_add_f32_e64 v22, v24, v32
	v_add_f32_e64 v23, v25, v33
	s_waitcnt vmcnt(0)
	v_add_f32_e64 v2, v26, v2
	v_add_f32_e64 v3, v27, v3
	v_add_f32_e64 v24, v28, v34
	v_add_f32_e64 v25, v29, v35
	v_cvt_pk_bf16_f32 v110, v4, v5
	v_cvt_pk_bf16_f32 v111, v22, v23
	v_cvt_pk_bf16_f32 v112, v2, v3
	v_cvt_pk_bf16_f32 v113, v24, v25
.LBB0_1117:
	s_or_b64 exec, exec, s[22:23]
	v_add_co_u32_e32 v66, vcc, 0xb000, v122
	s_waitcnt lgkmcnt(10)
	v_mfma_f32_32x32x16_bf16 v[34:49], v[10:13], v[18:21], 0
	v_addc_co_u32_e32 v67, vcc, 0, v123, vcc
	global_load_dwordx4 v[180:183], v[66:67], off
	ds_read_b128 v[78:81], v135 offset:23072
	ds_read_b128 v[82:85], v136 offset:4640
	v_mov_b32_e32 v69, 0
	s_waitcnt lgkmcnt(11)
	v_mfma_f32_32x32x16_bf16 v[50:65], v[6:9], v[18:21], 0
	ds_read_b128 v[74:77], v135 offset:18464
	ds_read_b128 v[146:149], v135 offset:18496
	s_waitcnt lgkmcnt(12)
	v_mfma_f32_32x32x16_bf16 v[18:33], v[10:13], v[14:17], 0
	ds_read_b128 v[86:89], v136 offset:32
	ds_read_b128 v[150:153], v136 offset:64
	v_mfma_f32_32x32x16_bf16 v[2:17], v[6:9], v[14:17], 0
	ds_read_b128 v[154:157], v135 offset:23104
	ds_read_b128 v[158:161], v136 offset:4672
	s_waitcnt lgkmcnt(3)
	v_mfma_f32_32x32x16_bf16 v[34:49], v[74:77], v[86:89], v[34:49]
	ds_read_b128 v[162:165], v135 offset:18528
	ds_read_b128 v[168:171], v136 offset:96
	v_mfma_f32_32x32x16_bf16 v[50:65], v[78:81], v[86:89], v[50:65]
	ds_read_b128 v[172:175], v135 offset:23136
	ds_read_b128 v[176:179], v136 offset:4704
	s_waitcnt lgkmcnt(0)
	s_barrier
	v_mfma_f32_32x32x16_bf16 v[18:33], v[74:77], v[82:85], v[18:33]
	ds_read_b128 v[74:77], v137 offset:55296
	ds_read_b128 v[86:89], v138 offset:36864
	v_mfma_f32_32x32x16_bf16 v[2:17], v[78:81], v[82:85], v[2:17]
	ds_read_b128 v[78:81], v137 offset:59904
	ds_read_b128 v[82:85], v138 offset:41472
	v_mfma_f32_32x32x16_bf16 v[34:49], v[146:149], v[150:153], v[34:49]
	ds_write_b128 v130, v[70:73]
	s_waitcnt vmcnt(3)
	ds_write_b128 v130, v[90:93] offset:18432
	v_mov_b32_e32 v70, 0
	v_mov_b32_e32 v71, 0
	v_mfma_f32_32x32x16_bf16 v[50:65], v[154:157], v[150:153], v[50:65]
	ds_write_b128 v131, v[98:101]
	s_waitcnt vmcnt(2)
	ds_write_b128 v131, v[102:105] offset:18432
	v_mfma_f32_32x32x16_bf16 v[18:33], v[146:149], v[158:161], v[18:33]
	ds_write_b128 v132, v[94:97]
	s_waitcnt vmcnt(1)
	ds_write_b128 v132, v[106:109] offset:18432
	v_mfma_f32_32x32x16_bf16 v[2:17], v[154:157], v[158:161], v[2:17]
	ds_write_b128 v133, v[110:113]
	s_waitcnt vmcnt(0)
	ds_write_b128 v133, v[180:183] offset:18432
	v_mfma_f32_32x32x16_bf16 v[34:49], v[162:165], v[168:171], v[34:49]
	v_mfma_f32_32x32x16_bf16 v[50:65], v[172:175], v[168:171], v[50:65]
	v_mfma_f32_32x32x16_bf16 v[18:33], v[162:165], v[176:179], v[18:33]
	v_mfma_f32_32x32x16_bf16 v[2:17], v[172:175], v[176:179], v[2:17]
	s_and_saveexec_b64 s[22:23], s[4:5]
	s_cbranch_execz .LBB0_1119
	v_lshrrev_b32_e32 v66, 31, v139
	v_ashrrev_i32_e32 v67, 8, v139
	v_add_u32_e32 v66, v67, v66
	v_mul_i32_i24_e32 v68, 0xfffffe01, v66
	v_ashrrev_i32_e32 v67, 31, v66
	v_add_lshl_u32 v68, v68, v119, 4
	v_ashrrev_i32_e32 v69, 31, v68
	v_lshlrev_b64 v[66:67], 20, v[66:67]
	v_lshl_add_u64 v[66:67], s[18:19], 0, v[66:67]
	v_lshlrev_b64 v[68:69], 7, v[68:69]
	v_lshl_add_u64 v[66:67], v[66:67], 0, v[68:69]
	v_lshl_add_u64 v[66:67], v[66:67], 0, v[114:115]
	global_load_dwordx4 v[66:69], v[66:67], off offset:384
	s_nop 0
	global_load_dwordx4 v[70:73], v[124:125], off offset:768
	global_load_dwordx4 v[90:93], v[124:125], off offset:784
	s_waitcnt vmcnt(2)
	v_and_b32_e32 v95, 0xffff0000, v66
	v_lshlrev_b32_e32 v94, 16, v66
	v_and_b32_e32 v97, 0xffff0000, v67
	v_lshlrev_b32_e32 v96, 16, v67
	v_and_b32_e32 v67, 0xffff0000, v68
	v_lshlrev_b32_e32 v66, 16, v68
	v_and_b32_e32 v99, 0xffff0000, v69
	v_lshlrev_b32_e32 v98, 16, v69
	s_waitcnt vmcnt(1)
	v_add_f32_e64 v68, v70, v94
	v_add_f32_e64 v69, v71, v95
	v_add_f32_e64 v70, v72, v96
	v_add_f32_e64 v71, v73, v97
	s_waitcnt vmcnt(0)
	v_add_f32_e64 v66, v90, v66
	v_add_f32_e64 v67, v91, v67
	v_add_f32_e64 v72, v92, v98
	v_add_f32_e64 v73, v93, v99
	v_cvt_pk_bf16_f32 v68, v68, v69
	v_cvt_pk_bf16_f32 v69, v70, v71
	v_cvt_pk_bf16_f32 v70, v66, v67
	v_cvt_pk_bf16_f32 v71, v72, v73
.LBB0_1119:
	s_or_b64 exec, exec, s[22:23]
	v_add_co_u32_e32 v66, vcc, 0xc000, v122
	v_mov_b32_e32 v94, 0
	s_nop 0
	v_addc_co_u32_e32 v67, vcc, 0, v123, vcc
	global_load_dwordx4 v[90:93], v[66:67], off
	v_mov_b32_e32 v98, 0
	v_mov_b32_e32 v99, 0
	v_mov_b32_e32 v100, 0
	v_mov_b32_e32 v101, 0
	s_and_saveexec_b64 s[22:23], s[6:7]
	s_cbranch_execz .LBB0_1121
	v_lshrrev_b32_e32 v66, 31, v142
	v_ashrrev_i32_e32 v67, 8, v142
	v_add_u32_e32 v66, v67, v66
	v_mul_i32_i24_e32 v72, 0xfffffe01, v66
	v_ashrrev_i32_e32 v67, 31, v66
	v_add_lshl_u32 v72, v72, v121, 4
	v_ashrrev_i32_e32 v73, 31, v72
	v_lshlrev_b64 v[66:67], 20, v[66:67]
	v_lshl_add_u64 v[66:67], s[18:19], 0, v[66:67]
	v_lshlrev_b64 v[72:73], 7, v[72:73]
	v_lshl_add_u64 v[66:67], v[66:67], 0, v[72:73]
	v_lshl_add_u64 v[66:67], v[66:67], 0, v[114:115]
	global_load_dwordx4 v[96:99], v[66:67], off offset:384
	global_load_dwordx4 v[100:103], v[124:125], off offset:768
	global_load_dwordx4 v[104:107], v[124:125], off offset:784
	s_waitcnt vmcnt(2)
	v_and_b32_e32 v67, 0xffff0000, v96
	v_lshlrev_b32_e32 v66, 16, v96
	v_and_b32_e32 v73, 0xffff0000, v97
	v_lshlrev_b32_e32 v72, 16, v97
	v_and_b32_e32 v97, 0xffff0000, v98
	v_lshlrev_b32_e32 v96, 16, v98
	v_and_b32_e32 v109, 0xffff0000, v99
	v_lshlrev_b32_e32 v108, 16, v99
	s_waitcnt vmcnt(1)
	v_add_f32_e64 v66, v100, v66
	v_add_f32_e64 v67, v101, v67
	v_add_f32_e64 v72, v102, v72
	v_add_f32_e64 v73, v103, v73
	s_waitcnt vmcnt(0)
	v_add_f32_e64 v96, v104, v96
	v_add_f32_e64 v97, v105, v97
	v_add_f32_e64 v102, v106, v108
	v_add_f32_e64 v103, v107, v109
	v_cvt_pk_bf16_f32 v98, v66, v67
	v_cvt_pk_bf16_f32 v99, v72, v73
	v_cvt_pk_bf16_f32 v100, v96, v97
	v_cvt_pk_bf16_f32 v101, v102, v103
.LBB0_1121:
	s_or_b64 exec, exec, s[22:23]
	v_add_co_u32_e32 v66, vcc, 0xd000, v122
	v_mov_b32_e32 v95, 0
	s_nop 0
	v_addc_co_u32_e32 v67, vcc, 0, v123, vcc
	global_load_dwordx4 v[102:105], v[66:67], off
	v_mov_b32_e32 v96, 0
	v_mov_b32_e32 v97, 0
	s_and_saveexec_b64 s[22:23], s[8:9]
	s_cbranch_execz .LBB0_1123
	v_lshrrev_b32_e32 v66, 31, v143
	v_ashrrev_i32_e32 v67, 8, v143
	v_add_u32_e32 v66, v67, v66
	v_mul_i32_i24_e32 v72, 0xfffffe01, v66
	v_ashrrev_i32_e32 v67, 31, v66
	v_add_lshl_u32 v72, v72, v140, 4
	v_ashrrev_i32_e32 v73, 31, v72
	v_lshlrev_b64 v[66:67], 20, v[66:67]
	v_lshl_add_u64 v[66:67], s[18:19], 0, v[66:67]
	v_lshlrev_b64 v[72:73], 7, v[72:73]
	v_lshl_add_u64 v[66:67], v[66:67], 0, v[72:73]
	v_lshl_add_u64 v[66:67], v[66:67], 0, v[114:115]
	global_load_dwordx4 v[94:97], v[66:67], off offset:384
	global_load_dwordx4 v[106:109], v[124:125], off offset:768
	global_load_dwordx4 v[110:113], v[124:125], off offset:784
	s_waitcnt vmcnt(2)
	v_and_b32_e32 v67, 0xffff0000, v94
	v_lshlrev_b32_e32 v66, 16, v94
	v_and_b32_e32 v73, 0xffff0000, v95
	v_lshlrev_b32_e32 v72, 16, v95
	v_and_b32_e32 v95, 0xffff0000, v96
	v_lshlrev_b32_e32 v94, 16, v96
	v_and_b32_e32 v147, 0xffff0000, v97
	v_lshlrev_b32_e32 v146, 16, v97
	s_waitcnt vmcnt(1)
	v_add_f32_e64 v66, v106, v66
	v_add_f32_e64 v67, v107, v67
	v_add_f32_e64 v72, v108, v72
	v_add_f32_e64 v73, v109, v73
	s_waitcnt vmcnt(0)
	v_add_f32_e64 v96, v110, v94
	v_add_f32_e64 v97, v111, v95
	v_add_f32_e64 v106, v112, v146
	v_add_f32_e64 v107, v113, v147
	v_cvt_pk_bf16_f32 v94, v66, v67
	v_cvt_pk_bf16_f32 v95, v72, v73
	v_cvt_pk_bf16_f32 v96, v96, v97
	v_cvt_pk_bf16_f32 v97, v106, v107
.LBB0_1123:
	s_or_b64 exec, exec, s[22:23]
	v_add_co_u32_e32 v66, vcc, 0xe000, v122
	v_mov_b32_e32 v110, 0
	s_nop 0
	v_addc_co_u32_e32 v67, vcc, 0, v123, vcc
	global_load_dwordx4 v[106:109], v[66:67], off
	v_mov_b32_e32 v66, 0
	v_mov_b32_e32 v111, 0
	v_mov_b32_e32 v112, 0
	v_mov_b32_e32 v113, 0
	s_and_saveexec_b64 s[22:23], s[10:11]
	s_cbranch_execz .LBB0_1125
	v_lshrrev_b32_e32 v67, 31, v144
	v_ashrrev_i32_e32 v72, 8, v144
	v_add_u32_e32 v72, v72, v67
	v_mul_i32_i24_e32 v67, 0xfffffe01, v72
	v_ashrrev_i32_e32 v73, 31, v72
	v_add_lshl_u32 v110, v67, v141, 4
	v_ashrrev_i32_e32 v111, 31, v110
	v_lshlrev_b64 v[72:73], 20, v[72:73]
	v_lshl_add_u64 v[72:73], s[18:19], 0, v[72:73]
	v_lshlrev_b64 v[110:111], 7, v[110:111]
	v_lshl_add_u64 v[72:73], v[72:73], 0, v[110:111]
	v_lshl_add_u64 v[72:73], v[72:73], 0, v[114:115]
	global_load_dwordx4 v[110:113], v[72:73], off offset:384
	global_load_dwordx4 v[146:149], v[124:125], off offset:768
	global_load_dwordx4 v[150:153], v[124:125], off offset:784
	s_waitcnt vmcnt(2)
	v_and_b32_e32 v73, 0xffff0000, v110
	v_lshlrev_b32_e32 v72, 16, v110
	v_and_b32_e32 v155, 0xffff0000, v111
	v_lshlrev_b32_e32 v154, 16, v111
	v_and_b32_e32 v111, 0xffff0000, v112
	v_lshlrev_b32_e32 v110, 16, v112
	v_and_b32_e32 v157, 0xffff0000, v113
	v_lshlrev_b32_e32 v156, 16, v113
	s_waitcnt vmcnt(1)
	v_add_f32_e64 v72, v146, v72
	v_add_f32_e64 v73, v147, v73
	v_add_f32_e64 v112, v148, v154
	v_add_f32_e64 v113, v149, v155
	s_waitcnt vmcnt(0)
	v_add_f32_e64 v146, v150, v110
	v_add_f32_e64 v147, v151, v111
	v_add_f32_e64 v148, v152, v156
	v_add_f32_e64 v149, v153, v157
	v_cvt_pk_bf16_f32 v110, v72, v73
	v_cvt_pk_bf16_f32 v111, v112, v113
	v_cvt_pk_bf16_f32 v112, v146, v147
	v_cvt_pk_bf16_f32 v113, v148, v149
.LBB0_1125:
	s_or_b64 exec, exec, s[22:23]
	s_waitcnt lgkmcnt(10)
	v_mfma_f32_32x32x16_bf16 v[34:49], v[74:77], v[86:89], v[34:49]
	ds_read_b128 v[146:149], v135 offset:59936
	ds_read_b128 v[150:153], v136 offset:41504
	v_mov_b32_e32 v67, 0
	s_waitcnt lgkmcnt(11)
	v_mfma_f32_32x32x16_bf16 v[50:65], v[78:81], v[86:89], v[50:65]
	ds_read_b128 v[86:89], v135 offset:55328
	ds_read_b128 v[154:157], v135 offset:55360
	s_waitcnt lgkmcnt(12)
	v_mfma_f32_32x32x16_bf16 v[18:33], v[74:77], v[82:85], v[18:33]
	ds_read_b128 v[72:75], v136 offset:36896
	ds_read_b128 v[158:161], v136 offset:36928
	v_mfma_f32_32x32x16_bf16 v[2:17], v[78:81], v[82:85], v[2:17]
	ds_read_b128 v[162:165], v135 offset:59968
	ds_read_b128 v[168:171], v136 offset:41536
	s_waitcnt lgkmcnt(3)
	v_mfma_f32_32x32x16_bf16 v[34:49], v[86:89], v[72:75], v[34:49]
	ds_read_b128 v[172:175], v135 offset:55392
	ds_read_b128 v[176:179], v136 offset:36960
	v_mfma_f32_32x32x16_bf16 v[50:65], v[146:149], v[72:75], v[50:65]
	v_add_co_u32_e32 v72, vcc, 0xf000, v122
	ds_read_b128 v[180:183], v135 offset:60000
	s_nop 0
	v_addc_co_u32_e32 v73, vcc, 0, v123, vcc
	global_load_dwordx4 v[188:191], v[72:73], off
	ds_read_b128 v[184:187], v136 offset:41568
	v_mfma_f32_32x32x16_bf16 v[18:33], v[86:89], v[150:153], v[18:33]
	s_waitcnt lgkmcnt(0)
	s_barrier
	ds_read_b128 v[72:75], v137 offset:18432
	ds_read_b128 v[84:87], v138
	v_mfma_f32_32x32x16_bf16 v[2:17], v[146:149], v[150:153], v[2:17]
	ds_read_b128 v[76:79], v137 offset:23040
	ds_read_b128 v[80:83], v138 offset:4608
	v_mfma_f32_32x32x16_bf16 v[34:49], v[154:157], v[158:161], v[34:49]
	ds_write_b128 v130, v[68:71] offset:36864
	s_waitcnt vmcnt(3)
	ds_write_b128 v130, v[90:93] offset:55296
	v_mov_b32_e32 v68, 0
	v_mov_b32_e32 v69, 0
	v_mfma_f32_32x32x16_bf16 v[50:65], v[162:165], v[158:161], v[50:65]
	ds_write_b128 v131, v[98:101] offset:36864
	s_waitcnt vmcnt(2)
	ds_write_b128 v131, v[102:105] offset:55296
	v_mfma_f32_32x32x16_bf16 v[18:33], v[154:157], v[168:171], v[18:33]
	ds_write_b128 v132, v[94:97] offset:36864
	s_waitcnt vmcnt(1)
	ds_write_b128 v132, v[106:109] offset:55296
	v_mfma_f32_32x32x16_bf16 v[2:17], v[162:165], v[168:171], v[2:17]
	ds_write_b128 v133, v[110:113] offset:36864
	s_waitcnt vmcnt(0)
	ds_write_b128 v133, v[188:191] offset:55296
	v_mfma_f32_32x32x16_bf16 v[34:49], v[172:175], v[176:179], v[34:49]
	v_mfma_f32_32x32x16_bf16 v[50:65], v[180:183], v[176:179], v[50:65]
	v_mfma_f32_32x32x16_bf16 v[18:33], v[172:175], v[184:187], v[18:33]
	v_mfma_f32_32x32x16_bf16 v[2:17], v[180:183], v[184:187], v[2:17]
	s_and_saveexec_b64 s[22:23], s[4:5]
	s_cbranch_execz .LBB0_1127
	v_lshrrev_b32_e32 v66, 31, v139
	v_ashrrev_i32_e32 v67, 8, v139
	v_add_u32_e32 v66, v67, v66
	v_mul_i32_i24_e32 v68, 0xfffffe01, v66
	v_ashrrev_i32_e32 v67, 31, v66
	v_add_lshl_u32 v68, v68, v119, 4
	v_ashrrev_i32_e32 v69, 31, v68
	v_lshlrev_b64 v[66:67], 20, v[66:67]
	v_lshl_add_u64 v[66:67], s[18:19], 0, v[66:67]
	v_lshlrev_b64 v[68:69], 7, v[68:69]
	v_lshl_add_u64 v[66:67], v[66:67], 0, v[68:69]
	v_lshl_add_u64 v[66:67], v[66:67], 0, v[114:115]
	global_load_dwordx4 v[66:69], v[66:67], off offset:512
	s_nop 0
	global_load_dwordx4 v[88:91], v[124:125], off offset:1024
	global_load_dwordx4 v[92:95], v[124:125], off offset:1040
	s_waitcnt vmcnt(2)
	v_and_b32_e32 v71, 0xffff0000, v66
	v_lshlrev_b32_e32 v70, 16, v66
	v_and_b32_e32 v97, 0xffff0000, v67
	v_lshlrev_b32_e32 v96, 16, v67
	v_and_b32_e32 v67, 0xffff0000, v68
	v_lshlrev_b32_e32 v66, 16, v68
	v_and_b32_e32 v99, 0xffff0000, v69
	v_lshlrev_b32_e32 v98, 16, v69
	s_waitcnt vmcnt(1)
	v_add_f32_e64 v68, v88, v70
	v_add_f32_e64 v69, v89, v71
	v_add_f32_e64 v70, v90, v96
	v_add_f32_e64 v71, v91, v97
	s_waitcnt vmcnt(0)
	v_add_f32_e64 v88, v92, v66
	v_add_f32_e64 v89, v93, v67
	v_add_f32_e64 v90, v94, v98
	v_add_f32_e64 v91, v95, v99
	v_cvt_pk_bf16_f32 v66, v68, v69
	v_cvt_pk_bf16_f32 v67, v70, v71
	v_cvt_pk_bf16_f32 v68, v88, v89
	v_cvt_pk_bf16_f32 v69, v90, v91
.LBB0_1127:
	s_or_b64 exec, exec, s[22:23]
	v_add_co_u32_e32 v70, vcc, 0x10000, v122
	v_mov_b32_e32 v94, 0
	s_nop 0
	v_addc_co_u32_e32 v71, vcc, 0, v123, vcc
	global_load_dwordx4 v[90:93], v[70:71], off
	v_mov_b32_e32 v98, 0
	v_mov_b32_e32 v99, 0
	v_mov_b32_e32 v100, 0
	v_mov_b32_e32 v101, 0
	s_and_saveexec_b64 s[22:23], s[6:7]
	s_cbranch_execz .LBB0_1129
	v_lshrrev_b32_e32 v70, 31, v142
	v_ashrrev_i32_e32 v71, 8, v142
	v_add_u32_e32 v70, v71, v70
	v_mul_i32_i24_e32 v88, 0xfffffe01, v70
	v_ashrrev_i32_e32 v71, 31, v70
	v_add_lshl_u32 v88, v88, v121, 4
	v_ashrrev_i32_e32 v89, 31, v88
	v_lshlrev_b64 v[70:71], 20, v[70:71]
	v_lshl_add_u64 v[70:71], s[18:19], 0, v[70:71]
	v_lshlrev_b64 v[88:89], 7, v[88:89]
	v_lshl_add_u64 v[70:71], v[70:71], 0, v[88:89]
	v_lshl_add_u64 v[70:71], v[70:71], 0, v[114:115]
	global_load_dwordx4 v[96:99], v[70:71], off offset:512
	global_load_dwordx4 v[100:103], v[124:125], off offset:1024
	global_load_dwordx4 v[104:107], v[124:125], off offset:1040
	s_waitcnt vmcnt(2)
	v_and_b32_e32 v71, 0xffff0000, v96
	v_lshlrev_b32_e32 v70, 16, v96
	v_and_b32_e32 v89, 0xffff0000, v97
	v_lshlrev_b32_e32 v88, 16, v97
	v_and_b32_e32 v97, 0xffff0000, v98
	v_lshlrev_b32_e32 v96, 16, v98
	v_and_b32_e32 v109, 0xffff0000, v99
	v_lshlrev_b32_e32 v108, 16, v99
	s_waitcnt vmcnt(1)
	v_add_f32_e64 v70, v100, v70
	v_add_f32_e64 v71, v101, v71
	v_add_f32_e64 v88, v102, v88
	v_add_f32_e64 v89, v103, v89
	s_waitcnt vmcnt(0)
	v_add_f32_e64 v96, v104, v96
	v_add_f32_e64 v97, v105, v97
	v_add_f32_e64 v102, v106, v108
	v_add_f32_e64 v103, v107, v109
	v_cvt_pk_bf16_f32 v98, v70, v71
	v_cvt_pk_bf16_f32 v99, v88, v89
	v_cvt_pk_bf16_f32 v100, v96, v97
	v_cvt_pk_bf16_f32 v101, v102, v103
.LBB0_1129:
	s_or_b64 exec, exec, s[22:23]
	v_add_co_u32_e32 v70, vcc, 0x11000, v122
	v_mov_b32_e32 v95, 0
	s_nop 0
	v_addc_co_u32_e32 v71, vcc, 0, v123, vcc
	global_load_dwordx4 v[102:105], v[70:71], off
	v_mov_b32_e32 v96, 0
	v_mov_b32_e32 v97, 0
	s_and_saveexec_b64 s[22:23], s[8:9]
	s_cbranch_execz .LBB0_1131
	v_lshrrev_b32_e32 v70, 31, v143
	v_ashrrev_i32_e32 v71, 8, v143
	v_add_u32_e32 v70, v71, v70
	v_mul_i32_i24_e32 v88, 0xfffffe01, v70
	v_ashrrev_i32_e32 v71, 31, v70
	v_add_lshl_u32 v88, v88, v140, 4
	v_ashrrev_i32_e32 v89, 31, v88
	v_lshlrev_b64 v[70:71], 20, v[70:71]
	v_lshl_add_u64 v[70:71], s[18:19], 0, v[70:71]
	v_lshlrev_b64 v[88:89], 7, v[88:89]
	v_lshl_add_u64 v[70:71], v[70:71], 0, v[88:89]
	v_lshl_add_u64 v[70:71], v[70:71], 0, v[114:115]
	global_load_dwordx4 v[94:97], v[70:71], off offset:512
	global_load_dwordx4 v[106:109], v[124:125], off offset:1024
	global_load_dwordx4 v[110:113], v[124:125], off offset:1040
	s_waitcnt vmcnt(2)
	v_and_b32_e32 v71, 0xffff0000, v94
	v_lshlrev_b32_e32 v70, 16, v94
	v_and_b32_e32 v89, 0xffff0000, v95
	v_lshlrev_b32_e32 v88, 16, v95
	v_and_b32_e32 v95, 0xffff0000, v96
	v_lshlrev_b32_e32 v94, 16, v96
	v_and_b32_e32 v147, 0xffff0000, v97
	v_lshlrev_b32_e32 v146, 16, v97
	s_waitcnt vmcnt(1)
	v_add_f32_e64 v70, v106, v70
	v_add_f32_e64 v71, v107, v71
	v_add_f32_e64 v88, v108, v88
	v_add_f32_e64 v89, v109, v89
	s_waitcnt vmcnt(0)
	v_add_f32_e64 v96, v110, v94
	v_add_f32_e64 v97, v111, v95
	v_add_f32_e64 v106, v112, v146
	v_add_f32_e64 v107, v113, v147
	v_cvt_pk_bf16_f32 v94, v70, v71
	v_cvt_pk_bf16_f32 v95, v88, v89
	v_cvt_pk_bf16_f32 v96, v96, v97
	v_cvt_pk_bf16_f32 v97, v106, v107
.LBB0_1131:
	s_or_b64 exec, exec, s[22:23]
	v_add_co_u32_e32 v70, vcc, 0x12000, v122
	v_mov_b32_e32 v110, 0
	s_nop 0
	v_addc_co_u32_e32 v71, vcc, 0, v123, vcc
	global_load_dwordx4 v[106:109], v[70:71], off
	v_mov_b32_e32 v70, 0
	v_mov_b32_e32 v111, 0
	v_mov_b32_e32 v112, 0
	v_mov_b32_e32 v113, 0
	s_and_saveexec_b64 s[22:23], s[10:11]
	s_cbranch_execz .LBB0_1133
	v_lshrrev_b32_e32 v71, 31, v144
	v_ashrrev_i32_e32 v88, 8, v144
	v_add_u32_e32 v88, v88, v71
	v_mul_i32_i24_e32 v71, 0xfffffe01, v88
	v_ashrrev_i32_e32 v89, 31, v88
	v_add_lshl_u32 v110, v71, v141, 4
	v_ashrrev_i32_e32 v111, 31, v110
	v_lshlrev_b64 v[88:89], 20, v[88:89]
	v_lshl_add_u64 v[88:89], s[18:19], 0, v[88:89]
	v_lshlrev_b64 v[110:111], 7, v[110:111]
	v_lshl_add_u64 v[88:89], v[88:89], 0, v[110:111]
	v_lshl_add_u64 v[88:89], v[88:89], 0, v[114:115]
	global_load_dwordx4 v[110:113], v[88:89], off offset:512
	global_load_dwordx4 v[146:149], v[124:125], off offset:1024
	global_load_dwordx4 v[150:153], v[124:125], off offset:1040
	s_waitcnt vmcnt(2)
	v_and_b32_e32 v89, 0xffff0000, v110
	v_lshlrev_b32_e32 v88, 16, v110
	v_and_b32_e32 v155, 0xffff0000, v111
	v_lshlrev_b32_e32 v154, 16, v111
	v_and_b32_e32 v111, 0xffff0000, v112
	v_lshlrev_b32_e32 v110, 16, v112
	v_and_b32_e32 v157, 0xffff0000, v113
	v_lshlrev_b32_e32 v156, 16, v113
	s_waitcnt vmcnt(1)
	v_add_f32_e64 v88, v146, v88
	v_add_f32_e64 v89, v147, v89
	v_add_f32_e64 v112, v148, v154
	v_add_f32_e64 v113, v149, v155
	s_waitcnt vmcnt(0)
	v_add_f32_e64 v146, v150, v110
	v_add_f32_e64 v147, v151, v111
	v_add_f32_e64 v148, v152, v156
	v_add_f32_e64 v149, v153, v157
	v_cvt_pk_bf16_f32 v110, v88, v89
	v_cvt_pk_bf16_f32 v111, v112, v113
	v_cvt_pk_bf16_f32 v112, v146, v147
	v_cvt_pk_bf16_f32 v113, v148, v149
.LBB0_1133:
	s_or_b64 exec, exec, s[22:23]
	s_waitcnt lgkmcnt(10)
	v_mfma_f32_32x32x16_bf16 v[34:49], v[72:75], v[84:87], v[34:49]
	ds_read_b128 v[146:149], v135 offset:23072
	ds_read_b128 v[150:153], v136 offset:4640
	v_mov_b32_e32 v71, 0
	s_waitcnt lgkmcnt(11)
	v_mfma_f32_32x32x16_bf16 v[50:65], v[76:79], v[84:87], v[50:65]
	ds_read_b128 v[84:87], v135 offset:18464
	ds_read_b128 v[154:157], v135 offset:18496
	s_waitcnt lgkmcnt(12)
	v_mfma_f32_32x32x16_bf16 v[18:33], v[72:75], v[80:83], v[18:33]
	ds_read_b128 v[72:75], v136 offset:32
	ds_read_b128 v[158:161], v136 offset:64
	v_mfma_f32_32x32x16_bf16 v[2:17], v[76:79], v[80:83], v[2:17]
	ds_read_b128 v[162:165], v135 offset:23104
	ds_read_b128 v[168:171], v136 offset:4672
	s_waitcnt lgkmcnt(3)
	v_mfma_f32_32x32x16_bf16 v[34:49], v[84:87], v[72:75], v[34:49]
	ds_read_b128 v[172:175], v135 offset:18528
	ds_read_b128 v[176:179], v136 offset:96
	v_mfma_f32_32x32x16_bf16 v[50:65], v[146:149], v[72:75], v[50:65]
	v_add_co_u32_e32 v72, vcc, 0x13000, v122
	ds_read_b128 v[180:183], v135 offset:23136
	s_nop 0
	v_addc_co_u32_e32 v73, vcc, 0, v123, vcc
	global_load_dwordx4 v[188:191], v[72:73], off
	ds_read_b128 v[184:187], v136 offset:4704
	v_mfma_f32_32x32x16_bf16 v[18:33], v[84:87], v[150:153], v[18:33]
	s_waitcnt lgkmcnt(0)
	s_barrier
	ds_read_b128 v[74:77], v137 offset:55296
	ds_read_b128 v[86:89], v138 offset:36864
	v_mov_b32_e32 v72, 0
	v_mov_b32_e32 v73, 0
	v_mfma_f32_32x32x16_bf16 v[2:17], v[146:149], v[150:153], v[2:17]
	ds_read_b128 v[78:81], v137 offset:59904
	ds_read_b128 v[82:85], v138 offset:41472
	v_mfma_f32_32x32x16_bf16 v[34:49], v[154:157], v[158:161], v[34:49]
	ds_write_b128 v130, v[66:69]
	s_waitcnt vmcnt(3)
	ds_write_b128 v130, v[90:93] offset:18432
	v_mfma_f32_32x32x16_bf16 v[50:65], v[162:165], v[158:161], v[50:65]
	ds_write_b128 v131, v[98:101]
	s_waitcnt vmcnt(2)
	ds_write_b128 v131, v[102:105] offset:18432
	v_mfma_f32_32x32x16_bf16 v[18:33], v[154:157], v[168:171], v[18:33]
	ds_write_b128 v132, v[94:97]
	s_waitcnt vmcnt(1)
	ds_write_b128 v132, v[106:109] offset:18432
	v_mfma_f32_32x32x16_bf16 v[2:17], v[162:165], v[168:171], v[2:17]
	ds_write_b128 v133, v[110:113]
	s_waitcnt vmcnt(0)
	ds_write_b128 v133, v[188:191] offset:18432
	v_mfma_f32_32x32x16_bf16 v[34:49], v[172:175], v[176:179], v[34:49]
	v_mfma_f32_32x32x16_bf16 v[50:65], v[180:183], v[176:179], v[50:65]
	v_mfma_f32_32x32x16_bf16 v[18:33], v[172:175], v[184:187], v[18:33]
	v_mfma_f32_32x32x16_bf16 v[2:17], v[180:183], v[184:187], v[2:17]
	s_and_saveexec_b64 s[22:23], s[4:5]
	s_cbranch_execz .LBB0_1135
	v_lshrrev_b32_e32 v66, 31, v139
	v_ashrrev_i32_e32 v67, 8, v139
	v_add_u32_e32 v66, v67, v66
	v_mul_i32_i24_e32 v68, 0xfffffe01, v66
	v_ashrrev_i32_e32 v67, 31, v66
	v_add_lshl_u32 v68, v68, v119, 4
	v_ashrrev_i32_e32 v69, 31, v68
	v_lshlrev_b64 v[66:67], 20, v[66:67]
	v_lshl_add_u64 v[66:67], s[18:19], 0, v[66:67]
	v_lshlrev_b64 v[68:69], 7, v[68:69]
	v_lshl_add_u64 v[66:67], v[66:67], 0, v[68:69]
	v_lshl_add_u64 v[66:67], v[66:67], 0, v[114:115]
	global_load_dwordx4 v[66:69], v[66:67], off offset:640
	s_nop 0
	global_load_dwordx4 v[70:73], v[124:125], off offset:1280
	global_load_dwordx4 v[90:93], v[124:125], off offset:1296
	s_waitcnt vmcnt(2)
	v_and_b32_e32 v95, 0xffff0000, v66
	v_lshlrev_b32_e32 v94, 16, v66
	v_and_b32_e32 v97, 0xffff0000, v67
	v_lshlrev_b32_e32 v96, 16, v67
	v_and_b32_e32 v67, 0xffff0000, v68
	v_lshlrev_b32_e32 v66, 16, v68
	v_and_b32_e32 v99, 0xffff0000, v69
	v_lshlrev_b32_e32 v98, 16, v69
	s_waitcnt vmcnt(1)
	v_add_f32_e64 v68, v70, v94
	v_add_f32_e64 v69, v71, v95
	v_add_f32_e64 v72, v72, v96
	v_add_f32_e64 v73, v73, v97
	s_waitcnt vmcnt(0)
	v_add_f32_e64 v66, v90, v66
	v_add_f32_e64 v67, v91, v67
	v_add_f32_e64 v90, v92, v98
	v_add_f32_e64 v91, v93, v99
	v_cvt_pk_bf16_f32 v70, v68, v69
	v_cvt_pk_bf16_f32 v71, v72, v73
	v_cvt_pk_bf16_f32 v72, v66, v67
	v_cvt_pk_bf16_f32 v73, v90, v91
.LBB0_1135:
	s_or_b64 exec, exec, s[22:23]
	v_add_co_u32_e32 v66, vcc, 0x14000, v122
	v_mov_b32_e32 v94, 0
	s_nop 0
	v_addc_co_u32_e32 v67, vcc, 0, v123, vcc
	global_load_dwordx4 v[90:93], v[66:67], off
	v_mov_b32_e32 v98, 0
	v_mov_b32_e32 v99, 0
	v_mov_b32_e32 v100, 0
	v_mov_b32_e32 v101, 0
	s_and_saveexec_b64 s[22:23], s[6:7]
	s_cbranch_execz .LBB0_1137
	v_lshrrev_b32_e32 v66, 31, v142
	v_ashrrev_i32_e32 v67, 8, v142
	v_add_u32_e32 v66, v67, v66
	v_mul_i32_i24_e32 v68, 0xfffffe01, v66
	v_ashrrev_i32_e32 v67, 31, v66
	v_add_lshl_u32 v68, v68, v121, 4
	v_ashrrev_i32_e32 v69, 31, v68
	v_lshlrev_b64 v[66:67], 20, v[66:67]
	v_lshl_add_u64 v[66:67], s[18:19], 0, v[66:67]
	v_lshlrev_b64 v[68:69], 7, v[68:69]
	v_lshl_add_u64 v[66:67], v[66:67], 0, v[68:69]
	v_lshl_add_u64 v[66:67], v[66:67], 0, v[114:115]
	global_load_dwordx4 v[66:69], v[66:67], off offset:640
	s_nop 0
	global_load_dwordx4 v[96:99], v[124:125], off offset:1280
	global_load_dwordx4 v[100:103], v[124:125], off offset:1296
	s_waitcnt vmcnt(2)
	v_and_b32_e32 v105, 0xffff0000, v66
	v_lshlrev_b32_e32 v104, 16, v66
	v_and_b32_e32 v107, 0xffff0000, v67
	v_lshlrev_b32_e32 v106, 16, v67
	v_and_b32_e32 v67, 0xffff0000, v68
	v_lshlrev_b32_e32 v66, 16, v68
	v_and_b32_e32 v109, 0xffff0000, v69
	v_lshlrev_b32_e32 v108, 16, v69
	s_waitcnt vmcnt(1)
	v_add_f32_e64 v68, v96, v104
	v_add_f32_e64 v69, v97, v105
	v_add_f32_e64 v96, v98, v106
	v_add_f32_e64 v97, v99, v107
	s_waitcnt vmcnt(0)
	v_add_f32_e64 v66, v100, v66
	v_add_f32_e64 v67, v101, v67
	v_add_f32_e64 v102, v102, v108
	v_add_f32_e64 v103, v103, v109
	v_cvt_pk_bf16_f32 v98, v68, v69
	v_cvt_pk_bf16_f32 v99, v96, v97
	v_cvt_pk_bf16_f32 v100, v66, v67
	v_cvt_pk_bf16_f32 v101, v102, v103
.LBB0_1137:
	s_or_b64 exec, exec, s[22:23]
	v_add_co_u32_e32 v66, vcc, 0x15000, v122
	v_mov_b32_e32 v95, 0
	s_nop 0
	v_addc_co_u32_e32 v67, vcc, 0, v123, vcc
	global_load_dwordx4 v[102:105], v[66:67], off
	v_mov_b32_e32 v96, 0
	v_mov_b32_e32 v97, 0
	s_and_saveexec_b64 s[22:23], s[8:9]
	s_cbranch_execz .LBB0_1139
	v_lshrrev_b32_e32 v66, 31, v143
	v_ashrrev_i32_e32 v67, 8, v143
	v_add_u32_e32 v66, v67, v66
	v_mul_i32_i24_e32 v68, 0xfffffe01, v66
	v_ashrrev_i32_e32 v67, 31, v66
	v_add_lshl_u32 v68, v68, v140, 4
	v_ashrrev_i32_e32 v69, 31, v68
	v_lshlrev_b64 v[66:67], 20, v[66:67]
	v_lshl_add_u64 v[66:67], s[18:19], 0, v[66:67]
	v_lshlrev_b64 v[68:69], 7, v[68:69]
	v_lshl_add_u64 v[66:67], v[66:67], 0, v[68:69]
	v_lshl_add_u64 v[66:67], v[66:67], 0, v[114:115]
	global_load_dwordx4 v[66:69], v[66:67], off offset:640
	s_nop 0
	global_load_dwordx4 v[94:97], v[124:125], off offset:1280
	global_load_dwordx4 v[106:109], v[124:125], off offset:1296
	s_waitcnt vmcnt(2)
	v_and_b32_e32 v111, 0xffff0000, v66
	v_lshlrev_b32_e32 v110, 16, v66
	v_and_b32_e32 v113, 0xffff0000, v67
	v_lshlrev_b32_e32 v112, 16, v67
	v_and_b32_e32 v67, 0xffff0000, v68
	v_lshlrev_b32_e32 v66, 16, v68
	v_and_b32_e32 v147, 0xffff0000, v69
	v_lshlrev_b32_e32 v146, 16, v69
	s_waitcnt vmcnt(1)
	v_add_f32_e64 v68, v94, v110
	v_add_f32_e64 v69, v95, v111
	v_add_f32_e64 v96, v96, v112
	v_add_f32_e64 v97, v97, v113
	s_waitcnt vmcnt(0)
	v_add_f32_e64 v66, v106, v66
	v_add_f32_e64 v67, v107, v67
	v_add_f32_e64 v106, v108, v146
	v_add_f32_e64 v107, v109, v147
	v_cvt_pk_bf16_f32 v94, v68, v69
	v_cvt_pk_bf16_f32 v95, v96, v97
	v_cvt_pk_bf16_f32 v96, v66, v67
	v_cvt_pk_bf16_f32 v97, v106, v107
.LBB0_1139:
	s_or_b64 exec, exec, s[22:23]
	v_add_co_u32_e32 v66, vcc, 0x16000, v122
	v_mov_b32_e32 v68, 0
	s_nop 0
	v_addc_co_u32_e32 v67, vcc, 0, v123, vcc
	global_load_dwordx4 v[106:109], v[66:67], off
	v_mov_b32_e32 v110, 0
	v_mov_b32_e32 v111, 0
	v_mov_b32_e32 v112, 0
	v_mov_b32_e32 v113, 0
	s_and_saveexec_b64 s[22:23], s[10:11]
	s_cbranch_execz .LBB0_1141
	v_lshrrev_b32_e32 v66, 31, v144
	v_ashrrev_i32_e32 v67, 8, v144
	v_add_u32_e32 v66, v67, v66
	v_mul_i32_i24_e32 v69, 0xfffffe01, v66
	v_ashrrev_i32_e32 v67, 31, v66
	v_add_lshl_u32 v110, v69, v141, 4
	v_ashrrev_i32_e32 v111, 31, v110
	v_lshlrev_b64 v[66:67], 20, v[66:67]
	v_lshl_add_u64 v[66:67], s[18:19], 0, v[66:67]
	v_lshlrev_b64 v[110:111], 7, v[110:111]
	v_lshl_add_u64 v[66:67], v[66:67], 0, v[110:111]
	v_lshl_add_u64 v[66:67], v[66:67], 0, v[114:115]
	global_load_dwordx4 v[110:113], v[66:67], off offset:640
	global_load_dwordx4 v[146:149], v[124:125], off offset:1280
	global_load_dwordx4 v[150:153], v[124:125], off offset:1296
	s_waitcnt vmcnt(2)
	v_and_b32_e32 v67, 0xffff0000, v110
	v_lshlrev_b32_e32 v66, 16, v110
	v_and_b32_e32 v155, 0xffff0000, v111
	v_lshlrev_b32_e32 v154, 16, v111
	v_and_b32_e32 v111, 0xffff0000, v112
	v_lshlrev_b32_e32 v110, 16, v112
	v_and_b32_e32 v157, 0xffff0000, v113
	v_lshlrev_b32_e32 v156, 16, v113
	s_waitcnt vmcnt(1)
	v_add_f32_e64 v66, v146, v66
	v_add_f32_e64 v67, v147, v67
	v_add_f32_e64 v112, v148, v154
	v_add_f32_e64 v113, v149, v155
	s_waitcnt vmcnt(0)
	v_add_f32_e64 v146, v150, v110
	v_add_f32_e64 v147, v151, v111
	v_add_f32_e64 v148, v152, v156
	v_add_f32_e64 v149, v153, v157
	v_cvt_pk_bf16_f32 v110, v66, v67
	v_cvt_pk_bf16_f32 v111, v112, v113
	v_cvt_pk_bf16_f32 v112, v146, v147
	v_cvt_pk_bf16_f32 v113, v148, v149
.LBB0_1141:
	s_or_b64 exec, exec, s[22:23]
	v_add_co_u32_e32 v66, vcc, 0x17000, v122
	s_waitcnt lgkmcnt(10)
	v_mfma_f32_32x32x16_bf16 v[34:49], v[74:77], v[86:89], v[34:49]
	v_addc_co_u32_e32 v67, vcc, 0, v123, vcc
	global_load_dwordx4 v[188:191], v[66:67], off
	ds_read_b128 v[146:149], v135 offset:59936
	ds_read_b128 v[150:153], v136 offset:41504
	v_mov_b32_e32 v69, 0
	s_waitcnt lgkmcnt(11)
	v_mfma_f32_32x32x16_bf16 v[50:65], v[78:81], v[86:89], v[50:65]
	ds_read_b128 v[86:89], v135 offset:55328
	ds_read_b128 v[154:157], v135 offset:55360
	s_waitcnt lgkmcnt(12)
	v_mfma_f32_32x32x16_bf16 v[18:33], v[74:77], v[82:85], v[18:33]
	ds_read_b128 v[74:77], v136 offset:36896
	ds_read_b128 v[158:161], v136 offset:36928
	v_mfma_f32_32x32x16_bf16 v[2:17], v[78:81], v[82:85], v[2:17]
	ds_read_b128 v[162:165], v135 offset:59968
	ds_read_b128 v[168:171], v136 offset:41536
	s_waitcnt lgkmcnt(3)
	v_mfma_f32_32x32x16_bf16 v[34:49], v[86:89], v[74:77], v[34:49]
	ds_read_b128 v[172:175], v135 offset:55392
	ds_read_b128 v[176:179], v136 offset:36960
	v_mfma_f32_32x32x16_bf16 v[50:65], v[146:149], v[74:77], v[50:65]
	ds_read_b128 v[180:183], v135 offset:60000
	ds_read_b128 v[184:187], v136 offset:41568
	s_waitcnt lgkmcnt(0)
	s_barrier
	v_mfma_f32_32x32x16_bf16 v[18:33], v[86:89], v[150:153], v[18:33]
	ds_read_b128 v[74:77], v137 offset:18432
	ds_read_b128 v[86:89], v138
	v_mfma_f32_32x32x16_bf16 v[2:17], v[146:149], v[150:153], v[2:17]
	ds_read_b128 v[78:81], v137 offset:23040
	ds_read_b128 v[82:85], v138 offset:4608
	v_mfma_f32_32x32x16_bf16 v[34:49], v[154:157], v[158:161], v[34:49]
	ds_write_b128 v130, v[70:73] offset:36864
	s_waitcnt vmcnt(3)
	ds_write_b128 v130, v[90:93] offset:55296
	v_mov_b32_e32 v70, 0
	v_mov_b32_e32 v71, 0
	v_mfma_f32_32x32x16_bf16 v[50:65], v[162:165], v[158:161], v[50:65]
	ds_write_b128 v131, v[98:101] offset:36864
	s_waitcnt vmcnt(2)
	ds_write_b128 v131, v[102:105] offset:55296
	v_mfma_f32_32x32x16_bf16 v[18:33], v[154:157], v[168:171], v[18:33]
	ds_write_b128 v132, v[94:97] offset:36864
	s_waitcnt vmcnt(1)
	ds_write_b128 v132, v[106:109] offset:55296
	v_mfma_f32_32x32x16_bf16 v[2:17], v[162:165], v[168:171], v[2:17]
	ds_write_b128 v133, v[110:113] offset:36864
	s_waitcnt vmcnt(0)
	ds_write_b128 v133, v[188:191] offset:55296
	v_mfma_f32_32x32x16_bf16 v[34:49], v[172:175], v[176:179], v[34:49]
	v_mfma_f32_32x32x16_bf16 v[50:65], v[180:183], v[176:179], v[50:65]
	v_mfma_f32_32x32x16_bf16 v[18:33], v[172:175], v[184:187], v[18:33]
	v_mfma_f32_32x32x16_bf16 v[2:17], v[180:183], v[184:187], v[2:17]
	s_and_saveexec_b64 s[22:23], s[4:5]
	s_cbranch_execz .LBB0_1143
	v_lshrrev_b32_e32 v66, 31, v139
	v_ashrrev_i32_e32 v67, 8, v139
	v_add_u32_e32 v66, v67, v66
	v_mul_i32_i24_e32 v68, 0xfffffe01, v66
	v_ashrrev_i32_e32 v67, 31, v66
	v_add_lshl_u32 v68, v68, v119, 4
	v_ashrrev_i32_e32 v69, 31, v68
	v_lshlrev_b64 v[66:67], 20, v[66:67]
	v_lshl_add_u64 v[66:67], s[18:19], 0, v[66:67]
	v_lshlrev_b64 v[68:69], 7, v[68:69]
	v_lshl_add_u64 v[66:67], v[66:67], 0, v[68:69]
	v_lshl_add_u64 v[66:67], v[66:67], 0, v[114:115]
	global_load_dwordx4 v[66:69], v[66:67], off offset:768
	s_nop 0
	global_load_dwordx4 v[70:73], v[124:125], off offset:1536
	global_load_dwordx4 v[90:93], v[124:125], off offset:1552
	s_waitcnt vmcnt(2)
	v_and_b32_e32 v95, 0xffff0000, v66
	v_lshlrev_b32_e32 v94, 16, v66
	v_and_b32_e32 v97, 0xffff0000, v67
	v_lshlrev_b32_e32 v96, 16, v67
	v_and_b32_e32 v67, 0xffff0000, v68
	v_lshlrev_b32_e32 v66, 16, v68
	v_and_b32_e32 v99, 0xffff0000, v69
	v_lshlrev_b32_e32 v98, 16, v69
	s_waitcnt vmcnt(1)
	v_add_f32_e64 v68, v70, v94
	v_add_f32_e64 v69, v71, v95
	v_add_f32_e64 v70, v72, v96
	v_add_f32_e64 v71, v73, v97
	s_waitcnt vmcnt(0)
	v_add_f32_e64 v66, v90, v66
	v_add_f32_e64 v67, v91, v67
	v_add_f32_e64 v72, v92, v98
	v_add_f32_e64 v73, v93, v99
	v_cvt_pk_bf16_f32 v68, v68, v69
	v_cvt_pk_bf16_f32 v69, v70, v71
	v_cvt_pk_bf16_f32 v70, v66, v67
	v_cvt_pk_bf16_f32 v71, v72, v73
.LBB0_1143:
	s_or_b64 exec, exec, s[22:23]
	v_add_co_u32_e32 v66, vcc, 0x18000, v122
	v_mov_b32_e32 v94, 0
	s_nop 0
	v_addc_co_u32_e32 v67, vcc, 0, v123, vcc
	global_load_dwordx4 v[90:93], v[66:67], off
	v_mov_b32_e32 v98, 0
	v_mov_b32_e32 v99, 0
	v_mov_b32_e32 v100, 0
	v_mov_b32_e32 v101, 0
	s_and_saveexec_b64 s[22:23], s[6:7]
	s_cbranch_execz .LBB0_1145
	v_lshrrev_b32_e32 v66, 31, v142
	v_ashrrev_i32_e32 v67, 8, v142
	v_add_u32_e32 v66, v67, v66
	v_mul_i32_i24_e32 v72, 0xfffffe01, v66
	v_ashrrev_i32_e32 v67, 31, v66
	v_add_lshl_u32 v72, v72, v121, 4
	v_ashrrev_i32_e32 v73, 31, v72
	v_lshlrev_b64 v[66:67], 20, v[66:67]
	v_lshl_add_u64 v[66:67], s[18:19], 0, v[66:67]
	v_lshlrev_b64 v[72:73], 7, v[72:73]
	v_lshl_add_u64 v[66:67], v[66:67], 0, v[72:73]
	v_lshl_add_u64 v[66:67], v[66:67], 0, v[114:115]
	global_load_dwordx4 v[96:99], v[66:67], off offset:768
	global_load_dwordx4 v[100:103], v[124:125], off offset:1536
	global_load_dwordx4 v[104:107], v[124:125], off offset:1552
	s_waitcnt vmcnt(2)
	v_and_b32_e32 v67, 0xffff0000, v96
	v_lshlrev_b32_e32 v66, 16, v96
	v_and_b32_e32 v73, 0xffff0000, v97
	v_lshlrev_b32_e32 v72, 16, v97
	v_and_b32_e32 v97, 0xffff0000, v98
	v_lshlrev_b32_e32 v96, 16, v98
	v_and_b32_e32 v109, 0xffff0000, v99
	v_lshlrev_b32_e32 v108, 16, v99
	s_waitcnt vmcnt(1)
	v_add_f32_e64 v66, v100, v66
	v_add_f32_e64 v67, v101, v67
	v_add_f32_e64 v72, v102, v72
	v_add_f32_e64 v73, v103, v73
	s_waitcnt vmcnt(0)
	v_add_f32_e64 v96, v104, v96
	v_add_f32_e64 v97, v105, v97
	v_add_f32_e64 v102, v106, v108
	v_add_f32_e64 v103, v107, v109
	v_cvt_pk_bf16_f32 v98, v66, v67
	v_cvt_pk_bf16_f32 v99, v72, v73
	v_cvt_pk_bf16_f32 v100, v96, v97
	v_cvt_pk_bf16_f32 v101, v102, v103
.LBB0_1145:
	s_or_b64 exec, exec, s[22:23]
	v_add_co_u32_e32 v66, vcc, 0x19000, v122
	v_mov_b32_e32 v95, 0
	s_nop 0
	v_addc_co_u32_e32 v67, vcc, 0, v123, vcc
	global_load_dwordx4 v[102:105], v[66:67], off
	v_mov_b32_e32 v96, 0
	v_mov_b32_e32 v97, 0
	s_and_saveexec_b64 s[22:23], s[8:9]
	s_cbranch_execz .LBB0_1147
	v_lshrrev_b32_e32 v66, 31, v143
	v_ashrrev_i32_e32 v67, 8, v143
	v_add_u32_e32 v66, v67, v66
	v_mul_i32_i24_e32 v72, 0xfffffe01, v66
	v_ashrrev_i32_e32 v67, 31, v66
	v_add_lshl_u32 v72, v72, v140, 4
	v_ashrrev_i32_e32 v73, 31, v72
	v_lshlrev_b64 v[66:67], 20, v[66:67]
	v_lshl_add_u64 v[66:67], s[18:19], 0, v[66:67]
	v_lshlrev_b64 v[72:73], 7, v[72:73]
	v_lshl_add_u64 v[66:67], v[66:67], 0, v[72:73]
	v_lshl_add_u64 v[66:67], v[66:67], 0, v[114:115]
	global_load_dwordx4 v[94:97], v[66:67], off offset:768
	global_load_dwordx4 v[106:109], v[124:125], off offset:1536
	global_load_dwordx4 v[110:113], v[124:125], off offset:1552
	s_waitcnt vmcnt(2)
	v_and_b32_e32 v67, 0xffff0000, v94
	v_lshlrev_b32_e32 v66, 16, v94
	v_and_b32_e32 v73, 0xffff0000, v95
	v_lshlrev_b32_e32 v72, 16, v95
	v_and_b32_e32 v95, 0xffff0000, v96
	v_lshlrev_b32_e32 v94, 16, v96
	v_and_b32_e32 v147, 0xffff0000, v97
	v_lshlrev_b32_e32 v146, 16, v97
	s_waitcnt vmcnt(1)
	v_add_f32_e64 v66, v106, v66
	v_add_f32_e64 v67, v107, v67
	v_add_f32_e64 v72, v108, v72
	v_add_f32_e64 v73, v109, v73
	s_waitcnt vmcnt(0)
	v_add_f32_e64 v96, v110, v94
	v_add_f32_e64 v97, v111, v95
	v_add_f32_e64 v106, v112, v146
	v_add_f32_e64 v107, v113, v147
	v_cvt_pk_bf16_f32 v94, v66, v67
	v_cvt_pk_bf16_f32 v95, v72, v73
	v_cvt_pk_bf16_f32 v96, v96, v97
	v_cvt_pk_bf16_f32 v97, v106, v107
.LBB0_1147:
	s_or_b64 exec, exec, s[22:23]
	v_add_co_u32_e32 v66, vcc, 0x1a000, v122
	v_mov_b32_e32 v110, 0
	s_nop 0
	v_addc_co_u32_e32 v67, vcc, 0, v123, vcc
	global_load_dwordx4 v[106:109], v[66:67], off
	v_mov_b32_e32 v66, 0
	v_mov_b32_e32 v111, 0
	v_mov_b32_e32 v112, 0
	v_mov_b32_e32 v113, 0
	s_and_saveexec_b64 s[22:23], s[10:11]
	s_cbranch_execz .LBB0_1149
	v_lshrrev_b32_e32 v67, 31, v144
	v_ashrrev_i32_e32 v72, 8, v144
	v_add_u32_e32 v72, v72, v67
	v_mul_i32_i24_e32 v67, 0xfffffe01, v72
	v_ashrrev_i32_e32 v73, 31, v72
	v_add_lshl_u32 v110, v67, v141, 4
	v_ashrrev_i32_e32 v111, 31, v110
	v_lshlrev_b64 v[72:73], 20, v[72:73]
	v_lshl_add_u64 v[72:73], s[18:19], 0, v[72:73]
	v_lshlrev_b64 v[110:111], 7, v[110:111]
	v_lshl_add_u64 v[72:73], v[72:73], 0, v[110:111]
	v_lshl_add_u64 v[72:73], v[72:73], 0, v[114:115]
	global_load_dwordx4 v[110:113], v[72:73], off offset:768
	global_load_dwordx4 v[146:149], v[124:125], off offset:1536
	global_load_dwordx4 v[150:153], v[124:125], off offset:1552
	s_waitcnt vmcnt(2)
	v_and_b32_e32 v73, 0xffff0000, v110
	v_lshlrev_b32_e32 v72, 16, v110
	v_and_b32_e32 v155, 0xffff0000, v111
	v_lshlrev_b32_e32 v154, 16, v111
	v_and_b32_e32 v111, 0xffff0000, v112
	v_lshlrev_b32_e32 v110, 16, v112
	v_and_b32_e32 v157, 0xffff0000, v113
	v_lshlrev_b32_e32 v156, 16, v113
	s_waitcnt vmcnt(1)
	v_add_f32_e64 v72, v146, v72
	v_add_f32_e64 v73, v147, v73
	v_add_f32_e64 v112, v148, v154
	v_add_f32_e64 v113, v149, v155
	s_waitcnt vmcnt(0)
	v_add_f32_e64 v146, v150, v110
	v_add_f32_e64 v147, v151, v111
	v_add_f32_e64 v148, v152, v156
	v_add_f32_e64 v149, v153, v157
	v_cvt_pk_bf16_f32 v110, v72, v73
	v_cvt_pk_bf16_f32 v111, v112, v113
	v_cvt_pk_bf16_f32 v112, v146, v147
	v_cvt_pk_bf16_f32 v113, v148, v149
.LBB0_1149:
	s_or_b64 exec, exec, s[22:23]
	s_waitcnt lgkmcnt(10)
	v_mfma_f32_32x32x16_bf16 v[34:49], v[74:77], v[86:89], v[34:49]
	ds_read_b128 v[146:149], v135 offset:23072
	ds_read_b128 v[150:153], v136 offset:4640
	v_mov_b32_e32 v67, 0
	s_waitcnt lgkmcnt(11)
	v_mfma_f32_32x32x16_bf16 v[50:65], v[78:81], v[86:89], v[50:65]
	ds_read_b128 v[86:89], v135 offset:18464
	ds_read_b128 v[154:157], v135 offset:18496
	s_waitcnt lgkmcnt(12)
	v_mfma_f32_32x32x16_bf16 v[18:33], v[74:77], v[82:85], v[18:33]
	ds_read_b128 v[72:75], v136 offset:32
	ds_read_b128 v[158:161], v136 offset:64
	v_mfma_f32_32x32x16_bf16 v[2:17], v[78:81], v[82:85], v[2:17]
	ds_read_b128 v[162:165], v135 offset:23104
	ds_read_b128 v[168:171], v136 offset:4672
	s_waitcnt lgkmcnt(3)
	v_mfma_f32_32x32x16_bf16 v[34:49], v[86:89], v[72:75], v[34:49]
	ds_read_b128 v[172:175], v135 offset:18528
	ds_read_b128 v[176:179], v136 offset:96
	v_mfma_f32_32x32x16_bf16 v[50:65], v[146:149], v[72:75], v[50:65]
	v_add_co_u32_e32 v72, vcc, 0x1b000, v122
	ds_read_b128 v[180:183], v135 offset:23136
	s_nop 0
	v_addc_co_u32_e32 v73, vcc, 0, v123, vcc
	global_load_dwordx4 v[188:191], v[72:73], off
	ds_read_b128 v[184:187], v136 offset:4704
	v_mfma_f32_32x32x16_bf16 v[18:33], v[86:89], v[150:153], v[18:33]
	s_waitcnt lgkmcnt(0)
	s_barrier
	ds_read_b128 v[72:75], v137 offset:55296
	ds_read_b128 v[84:87], v138 offset:36864
	v_mfma_f32_32x32x16_bf16 v[2:17], v[146:149], v[150:153], v[2:17]
	ds_read_b128 v[76:79], v137 offset:59904
	ds_read_b128 v[80:83], v138 offset:41472
	v_mfma_f32_32x32x16_bf16 v[34:49], v[154:157], v[158:161], v[34:49]
	ds_write_b128 v130, v[68:71]
	s_waitcnt vmcnt(3)
	ds_write_b128 v130, v[90:93] offset:18432
	v_mov_b32_e32 v68, 0
	v_mov_b32_e32 v69, 0
	v_mfma_f32_32x32x16_bf16 v[50:65], v[162:165], v[158:161], v[50:65]
	ds_write_b128 v131, v[98:101]
	s_waitcnt vmcnt(2)
	ds_write_b128 v131, v[102:105] offset:18432
	v_mfma_f32_32x32x16_bf16 v[18:33], v[154:157], v[168:171], v[18:33]
	ds_write_b128 v132, v[94:97]
	s_waitcnt vmcnt(1)
	ds_write_b128 v132, v[106:109] offset:18432
	v_mfma_f32_32x32x16_bf16 v[2:17], v[162:165], v[168:171], v[2:17]
	ds_write_b128 v133, v[110:113]
	s_waitcnt vmcnt(0)
	ds_write_b128 v133, v[188:191] offset:18432
	v_mfma_f32_32x32x16_bf16 v[34:49], v[172:175], v[176:179], v[34:49]
	v_mfma_f32_32x32x16_bf16 v[50:65], v[180:183], v[176:179], v[50:65]
	v_mfma_f32_32x32x16_bf16 v[18:33], v[172:175], v[184:187], v[18:33]
	v_mfma_f32_32x32x16_bf16 v[2:17], v[180:183], v[184:187], v[2:17]
	s_and_saveexec_b64 s[22:23], s[4:5]
	s_cbranch_execz .LBB0_1151
	v_lshrrev_b32_e32 v66, 31, v139
	v_ashrrev_i32_e32 v67, 8, v139
	v_add_u32_e32 v66, v67, v66
	v_mul_i32_i24_e32 v68, 0xfffffe01, v66
	v_ashrrev_i32_e32 v67, 31, v66
	v_add_lshl_u32 v68, v68, v119, 4
	v_ashrrev_i32_e32 v69, 31, v68
	v_lshlrev_b64 v[66:67], 20, v[66:67]
	v_lshl_add_u64 v[66:67], s[18:19], 0, v[66:67]
	v_lshlrev_b64 v[68:69], 7, v[68:69]
	v_lshl_add_u64 v[66:67], v[66:67], 0, v[68:69]
	v_lshl_add_u64 v[66:67], v[66:67], 0, v[114:115]
	global_load_dwordx4 v[66:69], v[66:67], off offset:896
	s_nop 0
	global_load_dwordx4 v[88:91], v[124:125], off offset:1792
	global_load_dwordx4 v[92:95], v[124:125], off offset:1808
	s_waitcnt vmcnt(2)
	v_and_b32_e32 v71, 0xffff0000, v66
	v_lshlrev_b32_e32 v70, 16, v66
	v_and_b32_e32 v97, 0xffff0000, v67
	v_lshlrev_b32_e32 v96, 16, v67
	v_and_b32_e32 v67, 0xffff0000, v68
	v_lshlrev_b32_e32 v66, 16, v68
	v_and_b32_e32 v99, 0xffff0000, v69
	v_lshlrev_b32_e32 v98, 16, v69
	s_waitcnt vmcnt(1)
	v_add_f32_e64 v68, v88, v70
	v_add_f32_e64 v69, v89, v71
	v_add_f32_e64 v70, v90, v96
	v_add_f32_e64 v71, v91, v97
	s_waitcnt vmcnt(0)
	v_add_f32_e64 v88, v92, v66
	v_add_f32_e64 v89, v93, v67
	v_add_f32_e64 v90, v94, v98
	v_add_f32_e64 v91, v95, v99
	v_cvt_pk_bf16_f32 v66, v68, v69
	v_cvt_pk_bf16_f32 v67, v70, v71
	v_cvt_pk_bf16_f32 v68, v88, v89
	v_cvt_pk_bf16_f32 v69, v90, v91
.LBB0_1151:
	s_or_b64 exec, exec, s[22:23]
	v_add_co_u32_e32 v70, vcc, 0x1c000, v122
	v_mov_b32_e32 v92, 0
	s_nop 0
	v_addc_co_u32_e32 v71, vcc, 0, v123, vcc
	global_load_dwordx4 v[88:91], v[70:71], off
	v_mov_b32_e32 v96, 0
	v_mov_b32_e32 v97, 0
	v_mov_b32_e32 v98, 0
	v_mov_b32_e32 v99, 0
	s_and_saveexec_b64 s[4:5], s[6:7]
	s_cbranch_execz .LBB0_1153
	v_lshrrev_b32_e32 v70, 31, v142
	v_ashrrev_i32_e32 v71, 8, v142
	v_add_u32_e32 v70, v71, v70
	v_mul_i32_i24_e32 v93, 0xfffffe01, v70
	v_ashrrev_i32_e32 v71, 31, v70
	v_add_lshl_u32 v94, v93, v121, 4
	v_ashrrev_i32_e32 v95, 31, v94
	v_lshlrev_b64 v[70:71], 20, v[70:71]
	v_lshl_add_u64 v[70:71], s[18:19], 0, v[70:71]
	v_lshlrev_b64 v[94:95], 7, v[94:95]
	v_lshl_add_u64 v[70:71], v[70:71], 0, v[94:95]
	v_lshl_add_u64 v[70:71], v[70:71], 0, v[114:115]
	global_load_dwordx4 v[94:97], v[70:71], off offset:896
	global_load_dwordx4 v[98:101], v[124:125], off offset:1792
	global_load_dwordx4 v[102:105], v[124:125], off offset:1808
	s_waitcnt vmcnt(2)
	v_and_b32_e32 v71, 0xffff0000, v94
	v_lshlrev_b32_e32 v70, 16, v94
	v_and_b32_e32 v107, 0xffff0000, v95
	v_lshlrev_b32_e32 v106, 16, v95
	v_and_b32_e32 v95, 0xffff0000, v96
	v_lshlrev_b32_e32 v94, 16, v96
	v_and_b32_e32 v109, 0xffff0000, v97
	v_lshlrev_b32_e32 v108, 16, v97
	s_waitcnt vmcnt(1)
	v_add_f32_e64 v70, v98, v70
	v_add_f32_e64 v71, v99, v71
	v_add_f32_e64 v98, v100, v106
	v_add_f32_e64 v99, v101, v107
	s_waitcnt vmcnt(0)
	v_add_f32_e64 v94, v102, v94
	v_add_f32_e64 v95, v103, v95
	v_add_f32_e64 v100, v104, v108
	v_add_f32_e64 v101, v105, v109
	v_cvt_pk_bf16_f32 v96, v70, v71
	v_cvt_pk_bf16_f32 v97, v98, v99
	v_cvt_pk_bf16_f32 v98, v94, v95
	v_cvt_pk_bf16_f32 v99, v100, v101
.LBB0_1153:
	s_or_b64 exec, exec, s[4:5]
	v_add_co_u32_e32 v70, vcc, 0x1d000, v122
	v_mov_b32_e32 v93, 0
	s_nop 0
	v_addc_co_u32_e32 v71, vcc, 0, v123, vcc
	global_load_dwordx4 v[100:103], v[70:71], off
	v_mov_b32_e32 v94, 0
	v_mov_b32_e32 v95, 0
	s_and_saveexec_b64 s[4:5], s[8:9]
	s_cbranch_execz .LBB0_1155
	v_lshrrev_b32_e32 v70, 31, v143
	v_ashrrev_i32_e32 v71, 8, v143
	v_add_u32_e32 v70, v71, v70
	v_mul_i32_i24_e32 v92, 0xfffffe01, v70
	v_ashrrev_i32_e32 v71, 31, v70
	v_add_lshl_u32 v92, v92, v140, 4
	v_ashrrev_i32_e32 v93, 31, v92
	v_lshlrev_b64 v[70:71], 20, v[70:71]
	v_lshl_add_u64 v[70:71], s[18:19], 0, v[70:71]
	v_lshlrev_b64 v[92:93], 7, v[92:93]
	v_lshl_add_u64 v[70:71], v[70:71], 0, v[92:93]
	v_lshl_add_u64 v[70:71], v[70:71], 0, v[114:115]
	global_load_dwordx4 v[92:95], v[70:71], off offset:896
	global_load_dwordx4 v[104:107], v[124:125], off offset:1792
	global_load_dwordx4 v[108:111], v[124:125], off offset:1808
	s_waitcnt vmcnt(2)
	v_and_b32_e32 v71, 0xffff0000, v92
	v_lshlrev_b32_e32 v70, 16, v92
	v_and_b32_e32 v113, 0xffff0000, v93
	v_lshlrev_b32_e32 v112, 16, v93
	v_and_b32_e32 v93, 0xffff0000, v94
	v_lshlrev_b32_e32 v92, 16, v94
	v_and_b32_e32 v143, 0xffff0000, v95
	v_lshlrev_b32_e32 v142, 16, v95
	s_waitcnt vmcnt(1)
	v_add_f32_e64 v70, v104, v70
	v_add_f32_e64 v71, v105, v71
	v_add_f32_e64 v94, v106, v112
	v_add_f32_e64 v95, v107, v113
	s_waitcnt vmcnt(0)
	v_add_f32_e64 v104, v108, v92
	v_add_f32_e64 v105, v109, v93
	v_add_f32_e64 v106, v110, v142
	v_add_f32_e64 v107, v111, v143
	v_cvt_pk_bf16_f32 v92, v70, v71
	v_cvt_pk_bf16_f32 v93, v94, v95
	v_cvt_pk_bf16_f32 v94, v104, v105
	v_cvt_pk_bf16_f32 v95, v106, v107
.LBB0_1155:
	s_or_b64 exec, exec, s[4:5]
	v_add_co_u32_e32 v70, vcc, 0x1e000, v122
	v_mov_b32_e32 v108, 0
	s_nop 0
	v_addc_co_u32_e32 v71, vcc, 0, v123, vcc
	global_load_dwordx4 v[104:107], v[70:71], off
	v_mov_b32_e32 v109, 0
	v_mov_b32_e32 v110, 0
	v_mov_b32_e32 v111, 0
	s_and_saveexec_b64 s[4:5], s[10:11]
	s_cbranch_execz .LBB0_1092
	v_lshrrev_b32_e32 v70, 31, v144
	v_ashrrev_i32_e32 v71, 8, v144
	v_add_u32_e32 v70, v71, v70
	v_mul_i32_i24_e32 v108, 0xfffffe01, v70
	v_ashrrev_i32_e32 v71, 31, v70
	v_add_lshl_u32 v108, v108, v141, 4
	v_ashrrev_i32_e32 v109, 31, v108
	v_lshlrev_b64 v[70:71], 20, v[70:71]
	v_lshl_add_u64 v[70:71], s[18:19], 0, v[70:71]
	v_lshlrev_b64 v[108:109], 7, v[108:109]
	v_lshl_add_u64 v[70:71], v[70:71], 0, v[108:109]
	v_lshl_add_u64 v[70:71], v[70:71], 0, v[114:115]
	global_load_dwordx4 v[108:111], v[70:71], off offset:896
	global_load_dwordx4 v[140:143], v[124:125], off offset:1792
	global_load_dwordx4 v[144:147], v[124:125], off offset:1808
	s_waitcnt vmcnt(2)
	v_and_b32_e32 v71, 0xffff0000, v108
	v_lshlrev_b32_e32 v70, 16, v108
	v_and_b32_e32 v113, 0xffff0000, v109
	v_lshlrev_b32_e32 v112, 16, v109
	v_and_b32_e32 v109, 0xffff0000, v110
	v_lshlrev_b32_e32 v108, 16, v110
	v_and_b32_e32 v125, 0xffff0000, v111
	v_lshlrev_b32_e32 v124, 16, v111
	s_waitcnt vmcnt(1)
	v_add_f32_e64 v70, v140, v70
	v_add_f32_e64 v71, v141, v71
	v_add_f32_e64 v110, v142, v112
	v_add_f32_e64 v111, v143, v113
	s_waitcnt vmcnt(0)
	v_add_f32_e64 v112, v144, v108
	v_add_f32_e64 v113, v145, v109
	v_add_f32_e64 v124, v146, v124
	v_add_f32_e64 v125, v147, v125
	v_cvt_pk_bf16_f32 v108, v70, v71
	v_cvt_pk_bf16_f32 v109, v110, v111
	v_cvt_pk_bf16_f32 v110, v112, v113
	v_cvt_pk_bf16_f32 v111, v124, v125
	s_branch .LBB0_1092

.LBB0_1228:
	s_or_b64 exec, exec, s[6:7]
	s_waitcnt lgkmcnt(0)
	v_add_f32_e32 v78, v78, v79
	v_fmamk_f32 v78, v78, 0x3c800000, v159
	v_mul_f32_e32 v79, 0x4b800000, v78
	v_cmp_gt_f32_e32 vcc, s0, v78
	v_ashrrev_i32_e32 v69, 31, v68
	v_ashrrev_i32_e32 v67, 31, v66
	v_cndmask_b32_e32 v78, v78, v79, vcc
	v_rsq_f32_e32 v78, v78
	v_lshlrev_b64 v[68:69], 16, v[68:69]
	v_lshl_add_u64 v[68:69], s[26:27], 0, v[68:69]
	v_lshlrev_b64 v[66:67], 7, v[66:67]
	v_lshl_add_u64 v[66:67], v[68:69], 0, v[66:67]
	v_mul_f32_e32 v68, 0x45800000, v78
	v_cndmask_b32_e32 v68, v78, v68, vcc
	v_mul_f32_e64 v8, v8, v68
	v_mul_f32_e64 v9, v9, v68
	v_mul_f32_e64 v12, v12, v68
	v_mul_f32_e64 v13, v13, v68
	s_mov_b32 s6, 0x3c0881c4
	v_mul_f32_e64 v22, v22, v68
	v_mul_f32_e64 v23, v23, v68
	v_mul_f32_e64 v8, v8, v44
	v_mul_f32_e64 v9, v9, v45
	v_mul_f32_e64 v12, v12, v40
	v_mul_f32_e64 v13, v13, v41
	v_mul_f32_e64 v16, v16, v68
	v_mul_f32_e64 v17, v17, v68
	v_lshlrev_b32_e32 v44, 30, v86
	v_lshlrev_b32_e32 v45, 30, v82
	v_mov_b64_e32 v[40:41], s[6:7]
	s_mov_b32 s6, 0xbab64f3b
	v_mul_f32_e64 v22, v58, v22
	v_mul_f32_e64 v23, v59, v23
	v_mul_f32_e64 v2, v2, v68
	v_mul_f32_e64 v3, v3, v68
	v_mul_f32_e64 v16, v16, v36
	v_mul_f32_e64 v17, v17, v37
	v_mul_f32_e64 v36, v70, v70
	v_mul_f32_e64 v37, v71, v71
	v_and_b32_e32 v58, 0x80000000, v44
	v_and_b32_e32 v59, 0x80000000, v45
	v_mov_b64_e32 v[44:45], s[6:7]
	v_mul_f32_e64 v2, v2, v46
	v_mul_f32_e64 v3, v3, v47
	v_mul_f32_e64 v6, v6, v68
	v_mul_f32_e64 v7, v7, v68
	v_fma_f32 v46, v36, s80, v44
	v_fma_f32 v47, v37, s80, v44
	v_mul_f32_e64 v6, v6, v42
	v_mul_f32_e64 v7, v7, v43
	v_fma_f32 v42, v36, s76, v40
	v_fma_f32 v43, v37, s76, v40
	v_fma_f32 v46, v36, v46, s82
	v_fma_f32 v47, v37, v47, s82
	v_mul_f32_e64 v4, v4, v68
	v_mul_f32_e64 v5, v5, v68
	v_fma_f32 v46, v36, v46, s84
	v_fma_f32 v47, v37, v47, s84
	v_fma_f32 v42, v36, v42, s86
	v_fma_f32 v43, v37, v43, s86
	v_mul_f32_e64 v4, v4, v48
	v_mul_f32_e64 v5, v5, v49
	v_and_b32_e32 v48, 1, v86
	v_fma_f32 v46, v36, v46, 1.0
	v_fma_f32 v47, v37, v47, 1.0
	v_mul_f32_e64 v36, v36, v42
	v_mul_f32_e64 v37, v37, v43
	v_mul_f32_e64 v26, v26, v68
	v_mul_f32_e64 v27, v27, v68
	v_and_b32_e32 v49, 1, v82
	v_fma_f32 v36, v70, v36, v70
	v_fma_f32 v37, v71, v37, v71
	v_cmp_eq_u32_e32 vcc, 0, v48
	v_mul_f32_e64 v26, v54, v26
	v_mul_f32_e64 v27, v55, v27
	v_mul_f32_e64 v10, v10, v68
	v_mul_f32_e64 v11, v11, v68
	v_lshlrev_b32_e32 v54, 30, v89
	v_lshlrev_b32_e32 v55, 30, v83
	v_cndmask_b32_e64 v37, -v37, v47, vcc
	v_cmp_eq_u32_e32 vcc, 0, v49
	v_mul_f32_e64 v10, v10, v38
	v_mul_f32_e64 v11, v11, v39
	v_mul_f32_e64 v38, v72, v72
	v_mul_f32_e64 v39, v73, v73
	v_cndmask_b32_e64 v36, -v36, v46, vcc
	v_xor_b32_e32 v42, v85, v84
	v_xor_b32_e32 v43, v81, v80
	v_and_b32_e32 v46, 0x80000000, v54
	v_and_b32_e32 v47, 0x80000000, v55
	v_xor_b32_e32 v48, v42, v46
	v_xor_b32_e32 v49, v43, v47
	v_fma_f32 v42, v38, s76, v40
	v_fma_f32 v43, v39, s76, v40
	v_fma_f32 v46, v38, s80, v44
	v_fma_f32 v47, v39, s80, v44
	v_mul_f32_e64 v28, v28, v68
	v_mul_f32_e64 v29, v29, v68
	v_fma_f32 v42, v38, v42, s86
	v_fma_f32 v43, v39, v43, s86
	v_fma_f32 v46, v38, v46, s82
	v_fma_f32 v47, v39, v47, s82
	v_mul_f32_e64 v28, v28, v56
	v_mul_f32_e64 v29, v29, v57
	v_and_b32_e32 v56, 1, v89
	v_mul_f32_e64 v42, v38, v42
	v_mul_f32_e64 v43, v39, v43
	v_fma_f32 v46, v38, v46, s84
	v_fma_f32 v47, v39, v47, s84
	v_and_b32_e32 v57, 1, v83
	v_fma_f32 v42, v72, v42, v72
	v_fma_f32 v43, v73, v43, v73
	v_fma_f32 v38, v38, v46, 1.0
	v_fma_f32 v39, v39, v47, 1.0
	v_cmp_eq_u32_e64 s[8:9], 0, v56
	v_cmp_class_f32_e64 vcc, v84, s29
	v_cmp_class_f32_e64 s[6:7], v80, s29
	v_cndmask_b32_e64 v39, v39, v43, s[8:9]
	v_cmp_eq_u32_e64 s[8:9], 0, v57
	v_xor_b32_e32 v39, v48, v39
	v_mul_f32_e64 v18, v18, v68
	v_mul_f32_e64 v19, v19, v68
	v_cndmask_b32_e64 v38, v38, v42, s[8:9]
	v_xor_b32_e32 v38, v49, v38
	v_xor_b32_e32 v37, v58, v37
	v_xor_b32_e32 v36, v59, v36
	v_cndmask_b32_e32 v39, v167, v39, vcc
	v_cndmask_b32_e64 v38, v167, v38, s[6:7]
	v_mul_f32_e64 v18, v62, v18
	v_mul_f32_e64 v19, v63, v19
	v_mul_f32_e64 v14, v14, v68
	v_mul_f32_e64 v15, v15, v68
	v_cndmask_b32_e32 v37, v167, v37, vcc
	v_cndmask_b32_e64 v36, v167, v36, s[6:7]
	v_mul_f32_e64 v42, v22, v38
	v_mul_f32_e64 v43, v23, v39
	v_mul_f32_e64 v14, v14, v34
	v_mul_f32_e64 v15, v15, v35
	v_mul_f32_e64 v34, v74, v74
	v_mul_f32_e64 v35, v75, v75
	v_fma_f32 v42, v18, v36, -v42
	v_fma_f32 v43, v19, v37, -v43
	v_mul_f32_e64 v18, v18, v38
	v_mul_f32_e64 v19, v19, v39
	v_fma_f32 v46, v34, s76, v40
	v_fma_f32 v47, v35, s76, v40
	v_fma_f32 v18, v22, v36, v18
	v_fma_f32 v19, v23, v37, v19
	v_fma_f32 v22, v34, s80, v44
	v_fma_f32 v23, v35, s80, v44
	v_mul_f32_e64 v32, v32, v68
	v_mul_f32_e64 v33, v33, v68
	v_fma_f32 v22, v34, v22, s82
	v_fma_f32 v23, v35, v23, s82
	v_fma_f32 v36, v34, v46, s86
	v_fma_f32 v37, v35, v47, s86
	v_fma_f32 v22, v34, v22, s84
	v_fma_f32 v23, v35, v23, s84
	v_mul_f32_e64 v32, v32, v52
	v_mul_f32_e64 v33, v33, v53
	v_and_b32_e32 v52, 1, v94
	v_fma_f32 v22, v34, v22, 1.0
	v_fma_f32 v23, v35, v23, 1.0
	v_mul_f32_e64 v34, v34, v36
	v_mul_f32_e64 v35, v35, v37
	v_and_b32_e32 v53, 1, v90
	v_fma_f32 v34, v74, v34, v74
	v_fma_f32 v35, v75, v35, v75
	v_cmp_eq_u32_e32 vcc, 0, v52
	v_mul_f32_e64 v48, v76, v76
	v_mul_f32_e64 v49, v77, v77
	v_mul_f32_e64 v30, v30, v68
	v_mul_f32_e64 v31, v31, v68
	v_cndmask_b32_e64 v23, -v35, v23, vcc
	v_cmp_eq_u32_e32 vcc, 0, v53
	v_fma_f32 v36, v48, s80, v44
	v_fma_f32 v37, v49, s80, v44
	v_and_b32_e32 v56, 1, v95
	v_cndmask_b32_e64 v22, -v34, v22, vcc
	v_fma_f32 v34, v48, s76, v40
	v_fma_f32 v35, v49, s76, v40
	v_fma_f32 v36, v48, v36, s82
	v_fma_f32 v37, v49, v37, s82
	v_fma_f32 v34, v48, v34, s86
	v_fma_f32 v35, v49, v35, s86
	v_fma_f32 v36, v48, v36, s84
	v_fma_f32 v37, v49, v37, s84
	v_mul_f32_e64 v34, v48, v34
	v_mul_f32_e64 v35, v49, v35
	v_mul_f32_e64 v30, v30, v50
	v_mul_f32_e64 v31, v31, v51
	v_lshlrev_b32_e32 v50, 30, v94
	v_lshlrev_b32_e32 v51, 30, v90
	v_and_b32_e32 v57, 1, v91
	v_fma_f32 v34, v76, v34, v76
	v_fma_f32 v35, v77, v35, v77
	v_fma_f32 v36, v48, v36, 1.0
	v_fma_f32 v37, v49, v37, 1.0
	v_cmp_eq_u32_e64 s[8:9], 0, v56
	v_lshlrev_b32_e32 v54, 30, v95
	v_lshlrev_b32_e32 v55, 30, v91
	v_and_b32_e32 v38, 0x80000000, v50
	v_and_b32_e32 v39, 0x80000000, v51
	v_cndmask_b32_e64 v35, v37, v35, s[8:9]
	v_cmp_eq_u32_e64 s[8:9], 0, v57
	v_xor_b32_e32 v23, v38, v23
	v_xor_b32_e32 v22, v39, v22
	v_cndmask_b32_e64 v34, v36, v34, s[8:9]
	v_and_b32_e32 v36, 0x80000000, v54
	v_and_b32_e32 v37, 0x80000000, v55
	v_xor_b32_e32 v38, v93, v92
	v_xor_b32_e32 v39, v88, v87
	v_xor_b32_e32 v36, v38, v36
	v_xor_b32_e32 v37, v39, v37
	v_mul_f32_e64 v24, v24, v68
	v_mul_f32_e64 v25, v25, v68
	v_cmp_class_f32_e64 vcc, v92, s29
	v_cmp_class_f32_e64 s[6:7], v87, s29
	v_xor_b32_e32 v35, v36, v35
	v_xor_b32_e32 v34, v37, v34
	v_mul_f32_e64 v20, v20, v68
	v_mul_f32_e64 v21, v21, v68
	v_mul_f32_e64 v24, v60, v24
	v_mul_f32_e64 v25, v61, v25
	v_cndmask_b32_e32 v35, v167, v35, vcc
	v_cndmask_b32_e64 v34, v167, v34, s[6:7]
	v_mul_f32_e64 v20, v64, v20
	v_mul_f32_e64 v21, v65, v21
	v_cndmask_b32_e32 v23, v167, v23, vcc
	v_cndmask_b32_e64 v22, v167, v22, s[6:7]
	v_mul_f32_e64 v36, v24, v34
	v_mul_f32_e64 v37, v25, v35
	v_cvt_pk_bf16_f32 v2, v2, v3
	v_fma_f32 v36, v20, v22, -v36
	v_fma_f32 v37, v21, v23, -v37
	v_mul_f32_e64 v20, v20, v34
	v_mul_f32_e64 v21, v21, v35
	v_cvt_pk_bf16_f32 v3, v4, v5
	v_fma_f32 v20, v24, v22, v20
	v_fma_f32 v21, v25, v23, v21
	v_lshlrev_b32_e32 v22, 1, v142
	v_mov_b32_e32 v23, v137
	v_lshl_add_u64 v[22:23], v[66:67], 0, v[22:23]
	v_cvt_pk_bf16_f32 v18, v18, v19
	v_cvt_pk_bf16_f32 v19, v20, v21
	global_store_dwordx2 v[22:23], v[2:3], off offset:64
	v_cvt_pk_bf16_f32 v2, v6, v7
	v_cvt_pk_bf16_f32 v3, v8, v9
	global_store_dwordx2 v[22:23], v[18:19], off offset:16
	v_cvt_pk_bf16_f32 v18, v26, v27
	v_cvt_pk_bf16_f32 v19, v28, v29
	global_store_dwordx2 v[22:23], v[2:3], off offset:80
	v_cvt_pk_bf16_f32 v2, v10, v11
	v_cvt_pk_bf16_f32 v3, v12, v13
	v_cvt_pk_bf16_f32 v24, v42, v43
	v_cvt_pk_bf16_f32 v25, v36, v37
	global_store_dwordx2 v[22:23], v[18:19], off offset:32
	v_cvt_pk_bf16_f32 v18, v30, v31
	v_cvt_pk_bf16_f32 v19, v32, v33
	global_store_dwordx2 v[22:23], v[2:3], off offset:96
	v_cvt_pk_bf16_f32 v2, v14, v15
	v_cvt_pk_bf16_f32 v3, v16, v17
	global_store_dwordx2 v[22:23], v[24:25], off
	global_store_dwordx2 v[22:23], v[18:19], off offset:48
	global_store_dwordx2 v[22:23], v[2:3], off offset:112

.LBB0_1231:
	s_and_b32 s12, s2, 1
	s_and_b32 s78, s85, 0xffffff80
	s_lshl_b32 s16, s12, 24
	v_or_b32_e32 v110, s78, v1
	v_lshl_add_u64 v[128:129], v[138:139], 0, s[16:17]
	v_cmp_gt_i32_e64 s[6:7], s20, v110
	v_ashrrev_i32_e32 v111, 31, v110
	v_mov_b32_e32 v5, 0
	v_mov_b32_e32 v4, 0
	v_mov_b32_e32 v3, 0
	v_mov_b32_e32 v2, 0
	s_waitcnt vmcnt(63) expcnt(7) lgkmcnt(15)
	s_barrier
	s_and_saveexec_b64 s[8:9], s[6:7]
	s_cbranch_execz .LBB0_1265
	v_lshlrev_b64 v[2:3], 10, v[110:111]
	v_lshl_add_u64 v[14:15], v[128:129], 0, v[2:3]
	global_load_dwordx4 v[2:5], v[14:15], off offset:16
	global_load_dwordx4 v[16:19], v[14:15], off
	v_add_co_u32_e32 v8, vcc, 0x400000, v14
	v_lshl_add_u64 v[6:7], v[14:15], 0, s[18:19]
	s_nop 0
	v_addc_co_u32_e32 v9, vcc, 0, v15, vcc
	global_load_dwordx4 v[20:23], v[8:9], off
	s_nop 0
	global_load_dwordx4 v[6:9], v[6:7], off offset:16
	v_add_co_u32_e32 v12, vcc, 0x800000, v14
	s_waitcnt vmcnt(2)
	v_add_f32_e64 v10, v16, 0
	v_add_f32_e64 v11, v17, 0
	v_addc_co_u32_e32 v13, vcc, 0, v15, vcc
	s_waitcnt vmcnt(1)
	v_add_f32_e64 v16, v10, v20
	v_add_f32_e64 v17, v11, v21
	v_lshl_add_u64 v[10:11], v[14:15], 0, s[22:23]
	global_load_dwordx4 v[24:27], v[12:13], off
	s_nop 0
	global_load_dwordx4 v[10:13], v[10:11], off offset:16
	s_waitcnt vmcnt(1)
	v_add_f32_e64 v20, v16, v24
	v_add_f32_e64 v21, v17, v25
	v_lshl_add_u64 v[16:17], v[14:15], 0, s[30:31]
	v_add_co_u32_e32 v14, vcc, 0xc00000, v14
	s_nop 1
	v_addc_co_u32_e32 v15, vcc, 0, v15, vcc
	global_load_dwordx4 v[28:31], v[14:15], off
	s_nop 0
	global_load_dwordx4 v[14:17], v[16:17], off offset:16
	s_waitcnt vmcnt(1)
	v_add_f32_e64 v20, v20, v28
	v_add_f32_e64 v21, v21, v29
	s_nop 0
	v_mul_f32_e32 v24, 0x3d372713, v20
	v_mul_f32_e32 v24, v20, v24
	v_fma_f32 v24, v20, v24, v20
	v_mul_f32_e32 v24, 0x3f4c422a, v24
	v_cmp_nlt_f32_e64 s[10:11], |v24|, s21
	s_and_saveexec_b64 s[74:75], s[10:11]
	s_xor_b64 s[10:11], exec, s[74:75]
	s_cbranch_execz .LBB0_1234
	v_add_f32_e64 v25, |v24|, |v24|
	v_mul_f32_e32 v28, 0x3fb8aa3b, v25
	v_rndne_f32_e32 v29, v28
	v_sub_f32_e32 v32, v28, v29
	v_fma_f32 v28, v25, s50, -v28
	v_fmac_f32_e32 v28, 0x32a5705f, v25
	v_add_f32_e32 v28, v32, v28
	v_cvt_i32_f32_e32 v29, v29
	v_exp_f32_e32 v28, v28
	v_cmp_ngt_f32_e32 vcc, s51, v25
	v_ldexp_f32 v28, v28, v29
	s_nop 0
	v_cndmask_b32_e32 v28, 0, v28, vcc
	v_cmp_nlt_f32_e32 vcc, s83, v25
	s_nop 1
	v_cndmask_b32_e32 v25, v160, v28, vcc
	v_add_f32_e32 v25, 1.0, v25
	v_rcp_f32_e32 v25, v25
	s_nop 0
	v_fma_f32 v25, v25, -2.0, 1.0
.LBB0_1234:
	s_andn2_saveexec_b64 s[10:11], s[10:11]
	v_mul_f32_e32 v25, v24, v24
	v_fmamk_f32 v28, v25, 0xbbbac73d, v158
	v_fmaak_f32 v28, v25, v28, 0xbd5c1c4e
	v_fmaak_f32 v28, v25, v28, 0x3e088382
	v_fmaak_f32 v28, v25, v28, 0xbeaaaa99
	v_mul_f32_e64 v28, |v24|, v28
	v_fma_f32 v25, v25, v28, |v24|
	s_or_b64 exec, exec, s[10:11]
	v_add_f32_e64 v18, v18, 0
	v_add_f32_e64 v19, v19, 0
	s_nop 0
	v_add_f32_e64 v18, v18, v22
	v_add_f32_e64 v19, v19, v23
	v_mul_f32_e32 v22, 0x3d372713, v21
	v_mul_f32_e32 v22, v21, v22
	v_fma_f32 v22, v21, v22, v21
	v_add_f32_e64 v18, v18, v26
	v_add_f32_e64 v19, v19, v27
	v_mul_f32_e32 v22, 0x3f4c422a, v22
	v_add_f32_e64 v18, v18, v30
	v_add_f32_e64 v19, v19, v31
	v_cmp_nlt_f32_e64 s[10:11], |v22|, s21
	s_and_saveexec_b64 s[74:75], s[10:11]
	s_xor_b64 s[10:11], exec, s[74:75]
	s_cbranch_execz .LBB0_1238
	v_add_f32_e64 v23, |v22|, |v22|
	v_mul_f32_e32 v26, 0x3fb8aa3b, v23
	v_rndne_f32_e32 v27, v26
	v_sub_f32_e32 v28, v26, v27
	v_fma_f32 v26, v23, s50, -v26
	v_fmac_f32_e32 v26, 0x32a5705f, v23
	v_add_f32_e32 v26, v28, v26
	v_cvt_i32_f32_e32 v27, v27
	v_exp_f32_e32 v26, v26
	v_cmp_ngt_f32_e32 vcc, s51, v23
	v_ldexp_f32 v26, v26, v27
	s_nop 0
	v_cndmask_b32_e32 v26, 0, v26, vcc
	v_cmp_nlt_f32_e32 vcc, s83, v23
	s_nop 1
	v_cndmask_b32_e32 v23, v160, v26, vcc
	v_add_f32_e32 v23, 1.0, v23
	v_rcp_f32_e32 v23, v23
	s_nop 0
	v_fma_f32 v23, v23, -2.0, 1.0

.LBB0_1246:
	s_andn2_saveexec_b64 s[10:11], s[10:11]
	v_mul_f32_e32 v29, v28, v28
	v_fmamk_f32 v30, v29, 0xbbbac73d, v158
	v_fmaak_f32 v30, v29, v30, 0xbd5c1c4e
	v_fmaak_f32 v30, v29, v30, 0x3e088382
	v_fmaak_f32 v30, v29, v30, 0xbeaaaa99
	v_mul_f32_e64 v30, |v28|, v30
	v_fma_f32 v29, v29, v30, |v28|
	s_or_b64 exec, exec, s[10:11]
	v_add_f32_e64 v2, v2, 0
	v_add_f32_e64 v3, v3, 0
	s_nop 0
	v_add_f32_e64 v2, v2, v6
	v_add_f32_e64 v3, v3, v7
	s_nop 0
	v_add_f32_e64 v2, v2, v10
	v_add_f32_e64 v3, v3, v11
	s_waitcnt vmcnt(0)
	v_add_f32_e64 v6, v2, v14
	v_add_f32_e64 v7, v3, v15
	s_nop 0
	v_mul_f32_e32 v2, 0x3d372713, v6
	v_mul_f32_e32 v2, v6, v2
	v_fma_f32 v2, v6, v2, v6
	v_mul_f32_e32 v2, 0x3f4c422a, v2
	v_cmp_nlt_f32_e64 s[10:11], |v2|, s21
	s_and_saveexec_b64 s[74:75], s[10:11]
	s_xor_b64 s[10:11], exec, s[74:75]
	s_cbranch_execz .LBB0_1250
	v_add_f32_e64 v3, |v2|, |v2|
	v_mul_f32_e32 v10, 0x3fb8aa3b, v3
	v_rndne_f32_e32 v11, v10
	v_sub_f32_e32 v14, v10, v11
	v_fma_f32 v10, v3, s50, -v10
	v_fmac_f32_e32 v10, 0x32a5705f, v3
	v_add_f32_e32 v10, v14, v10
	v_cvt_i32_f32_e32 v11, v11
	v_exp_f32_e32 v10, v10
	v_cmp_ngt_f32_e32 vcc, s51, v3
	v_ldexp_f32 v10, v10, v11
	s_nop 0
	v_cndmask_b32_e32 v10, 0, v10, vcc
	v_cmp_nlt_f32_e32 vcc, s83, v3
	s_nop 1
	v_cndmask_b32_e32 v3, v160, v10, vcc
	v_add_f32_e32 v3, 1.0, v3
	v_rcp_f32_e32 v3, v3
	s_nop 0
	v_fma_f32 v3, v3, -2.0, 1.0
.LBB0_1250:
	s_andn2_saveexec_b64 s[10:11], s[10:11]
	v_mul_f32_e32 v3, v2, v2
	v_fmamk_f32 v10, v3, 0xbbbac73d, v158
	v_fmaak_f32 v10, v3, v10, 0xbd5c1c4e
	v_fmaak_f32 v10, v3, v10, 0x3e088382
	v_fmaak_f32 v10, v3, v10, 0xbeaaaa99
	v_mul_f32_e64 v10, |v2|, v10
	v_fma_f32 v3, v3, v10, |v2|
	s_or_b64 exec, exec, s[10:11]
	v_add_f32_e64 v4, v4, 0
	v_add_f32_e64 v5, v5, 0
	s_nop 0
	v_add_f32_e64 v4, v4, v8
	v_add_f32_e64 v5, v5, v9
	v_mul_f32_e32 v8, 0x3d372713, v7
	v_mul_f32_e32 v8, v7, v8
	v_fma_f32 v8, v7, v8, v7
	v_add_f32_e64 v4, v4, v12
	v_add_f32_e64 v5, v5, v13
	v_mul_f32_e32 v8, 0x3f4c422a, v8
	v_add_f32_e64 v4, v4, v16
	v_add_f32_e64 v5, v5, v17
	v_cmp_nlt_f32_e64 s[10:11], |v8|, s21
	s_and_saveexec_b64 s[74:75], s[10:11]
	s_xor_b64 s[10:11], exec, s[74:75]
	s_cbranch_execz .LBB0_1254
	v_add_f32_e64 v9, |v8|, |v8|
	v_mul_f32_e32 v10, 0x3fb8aa3b, v9
	v_rndne_f32_e32 v11, v10
	v_sub_f32_e32 v12, v10, v11
	v_fma_f32 v10, v9, s50, -v10
	v_fmac_f32_e32 v10, 0x32a5705f, v9
	v_add_f32_e32 v10, v12, v10
	v_cvt_i32_f32_e32 v11, v11
	v_exp_f32_e32 v10, v10
	v_cmp_ngt_f32_e32 vcc, s51, v9
	v_ldexp_f32 v10, v10, v11
	s_nop 0
	v_cndmask_b32_e32 v10, 0, v10, vcc
	v_cmp_nlt_f32_e32 vcc, s83, v9
	s_nop 1
	v_cndmask_b32_e32 v9, v160, v10, vcc
	v_add_f32_e32 v9, 1.0, v9
	v_rcp_f32_e32 v9, v9
	s_nop 0
	v_fma_f32 v9, v9, -2.0, 1.0

.LBB0_1265:
	s_or_b64 exec, exec, s[8:9]
	s_cmp_lg_u32 s12, 0
	v_readlane_b32 s8, v231, 4
	v_readlane_b32 s10, v231, 6
	s_cselect_b64 s[88:89], -1, 0
	s_cmp_eq_u32 s12, 0
	v_readlane_b32 s9, v231, 5
	v_readlane_b32 s11, v231, 7
	s_cselect_b32 s11, s9, s11
	s_cselect_b32 s10, s8, s10
	v_add_u32_e32 v112, s78, v141
	v_cmp_gt_i32_e64 s[8:9], s20, v112
	v_mov_b32_e32 v13, 0
	global_load_dwordx4 v[6:9], v136, s[10:11]
	v_ashrrev_i32_e32 v113, 31, v112
	v_mov_b32_e32 v12, 0
	v_mov_b32_e32 v11, 0
	v_mov_b32_e32 v10, 0
	s_and_saveexec_b64 s[12:13], s[8:9]
	s_cbranch_execz .LBB0_1299
	v_lshlrev_b64 v[10:11], 10, v[112:113]
	v_lshl_add_u64 v[22:23], v[128:129], 0, v[10:11]
	global_load_dwordx4 v[10:13], v[22:23], off offset:16
	global_load_dwordx4 v[24:27], v[22:23], off
	v_add_co_u32_e32 v16, vcc, 0x400000, v22
	v_lshl_add_u64 v[14:15], v[22:23], 0, s[18:19]
	s_nop 0
	v_addc_co_u32_e32 v17, vcc, 0, v23, vcc
	global_load_dwordx4 v[28:31], v[16:17], off
	s_nop 0
	global_load_dwordx4 v[14:17], v[14:15], off offset:16
	v_add_co_u32_e32 v20, vcc, 0x800000, v22
	s_waitcnt vmcnt(2)
	v_add_f32_e64 v18, v24, 0
	v_add_f32_e64 v19, v25, 0
	v_addc_co_u32_e32 v21, vcc, 0, v23, vcc
	s_waitcnt vmcnt(1)
	v_add_f32_e64 v24, v18, v28
	v_add_f32_e64 v25, v19, v29
	v_lshl_add_u64 v[18:19], v[22:23], 0, s[22:23]
	global_load_dwordx4 v[32:35], v[20:21], off
	s_nop 0
	global_load_dwordx4 v[18:21], v[18:19], off offset:16
	s_waitcnt vmcnt(1)
	v_add_f32_e64 v28, v24, v32
	v_add_f32_e64 v29, v25, v33
	v_lshl_add_u64 v[24:25], v[22:23], 0, s[30:31]
	v_add_co_u32_e32 v22, vcc, 0xc00000, v22
	s_nop 1
	v_addc_co_u32_e32 v23, vcc, 0, v23, vcc
	global_load_dwordx4 v[36:39], v[22:23], off
	s_nop 0
	global_load_dwordx4 v[22:25], v[24:25], off offset:16
	s_waitcnt vmcnt(1)
	v_add_f32_e64 v28, v28, v36
	v_add_f32_e64 v29, v29, v37
	s_nop 0
	v_mul_f32_e32 v32, 0x3d372713, v28
	v_mul_f32_e32 v32, v28, v32
	v_fma_f32 v32, v28, v32, v28
	v_mul_f32_e32 v32, 0x3f4c422a, v32
	v_cmp_nlt_f32_e64 s[74:75], |v32|, s21
	s_and_saveexec_b64 s[90:91], s[74:75]
	s_xor_b64 s[74:75], exec, s[90:91]
	s_cbranch_execz .LBB0_1268
	v_add_f32_e64 v33, |v32|, |v32|
	v_mul_f32_e32 v36, 0x3fb8aa3b, v33
	v_rndne_f32_e32 v37, v36
	v_sub_f32_e32 v40, v36, v37
	v_fma_f32 v36, v33, s50, -v36
	v_fmac_f32_e32 v36, 0x32a5705f, v33
	v_add_f32_e32 v36, v40, v36
	v_cvt_i32_f32_e32 v37, v37
	v_exp_f32_e32 v36, v36
	v_cmp_ngt_f32_e32 vcc, s51, v33
	v_ldexp_f32 v36, v36, v37
	s_nop 0
	v_cndmask_b32_e32 v36, 0, v36, vcc
	v_cmp_nlt_f32_e32 vcc, s83, v33
	s_nop 1
	v_cndmask_b32_e32 v33, v160, v36, vcc
	v_add_f32_e32 v33, 1.0, v33
	v_rcp_f32_e32 v33, v33
	s_nop 0
	v_fma_f32 v33, v33, -2.0, 1.0
.LBB0_1268:
	s_andn2_saveexec_b64 s[74:75], s[74:75]
	v_mul_f32_e32 v33, v32, v32
	v_fmamk_f32 v36, v33, 0xbbbac73d, v158
	v_fmaak_f32 v36, v33, v36, 0xbd5c1c4e
	v_fmaak_f32 v36, v33, v36, 0x3e088382
	v_fmaak_f32 v36, v33, v36, 0xbeaaaa99
	v_mul_f32_e64 v36, |v32|, v36
	v_fma_f32 v33, v33, v36, |v32|
	s_or_b64 exec, exec, s[74:75]
	v_add_f32_e64 v26, v26, 0
	v_add_f32_e64 v27, v27, 0
	s_nop 0
	v_add_f32_e64 v26, v26, v30
	v_add_f32_e64 v27, v27, v31
	v_mul_f32_e32 v30, 0x3d372713, v29
	v_mul_f32_e32 v30, v29, v30
	v_fma_f32 v30, v29, v30, v29
	v_add_f32_e64 v26, v26, v34
	v_add_f32_e64 v27, v27, v35
	v_mul_f32_e32 v30, 0x3f4c422a, v30
	v_add_f32_e64 v26, v26, v38
	v_add_f32_e64 v27, v27, v39
	v_cmp_nlt_f32_e64 s[74:75], |v30|, s21
	s_and_saveexec_b64 s[90:91], s[74:75]
	s_xor_b64 s[74:75], exec, s[90:91]
	s_cbranch_execz .LBB0_1272
	v_add_f32_e64 v31, |v30|, |v30|
	v_mul_f32_e32 v34, 0x3fb8aa3b, v31
	v_rndne_f32_e32 v35, v34
	v_sub_f32_e32 v36, v34, v35
	v_fma_f32 v34, v31, s50, -v34
	v_fmac_f32_e32 v34, 0x32a5705f, v31
	v_add_f32_e32 v34, v36, v34
	v_cvt_i32_f32_e32 v35, v35
	v_exp_f32_e32 v34, v34
	v_cmp_ngt_f32_e32 vcc, s51, v31
	v_ldexp_f32 v34, v34, v35
	s_nop 0
	v_cndmask_b32_e32 v34, 0, v34, vcc
	v_cmp_nlt_f32_e32 vcc, s83, v31
	s_nop 1
	v_cndmask_b32_e32 v31, v160, v34, vcc
	v_add_f32_e32 v31, 1.0, v31
	v_rcp_f32_e32 v31, v31
	s_nop 0
	v_fma_f32 v31, v31, -2.0, 1.0

.LBB0_1280:
	s_andn2_saveexec_b64 s[74:75], s[74:75]
	v_mul_f32_e32 v37, v36, v36
	v_fmamk_f32 v38, v37, 0xbbbac73d, v158
	v_fmaak_f32 v38, v37, v38, 0xbd5c1c4e
	v_fmaak_f32 v38, v37, v38, 0x3e088382
	v_fmaak_f32 v38, v37, v38, 0xbeaaaa99
	v_mul_f32_e64 v38, |v36|, v38
	v_fma_f32 v37, v37, v38, |v36|
	s_or_b64 exec, exec, s[74:75]
	v_add_f32_e64 v10, v10, 0
	v_add_f32_e64 v11, v11, 0
	s_nop 0
	v_add_f32_e64 v10, v10, v14
	v_add_f32_e64 v11, v11, v15
	s_nop 0
	v_add_f32_e64 v10, v10, v18
	v_add_f32_e64 v11, v11, v19
	s_waitcnt vmcnt(0)
	v_add_f32_e64 v14, v10, v22
	v_add_f32_e64 v15, v11, v23
	s_nop 0
	v_mul_f32_e32 v10, 0x3d372713, v14
	v_mul_f32_e32 v10, v14, v10
	v_fma_f32 v10, v14, v10, v14
	v_mul_f32_e32 v10, 0x3f4c422a, v10
	v_cmp_nlt_f32_e64 s[74:75], |v10|, s21
	s_and_saveexec_b64 s[90:91], s[74:75]
	s_xor_b64 s[74:75], exec, s[90:91]
	s_cbranch_execz .LBB0_1284
	v_add_f32_e64 v11, |v10|, |v10|
	v_mul_f32_e32 v18, 0x3fb8aa3b, v11
	v_rndne_f32_e32 v19, v18
	v_sub_f32_e32 v22, v18, v19
	v_fma_f32 v18, v11, s50, -v18
	v_fmac_f32_e32 v18, 0x32a5705f, v11
	v_add_f32_e32 v18, v22, v18
	v_cvt_i32_f32_e32 v19, v19
	v_exp_f32_e32 v18, v18
	v_cmp_ngt_f32_e32 vcc, s51, v11
	v_ldexp_f32 v18, v18, v19
	s_nop 0
	v_cndmask_b32_e32 v18, 0, v18, vcc
	v_cmp_nlt_f32_e32 vcc, s83, v11
	s_nop 1
	v_cndmask_b32_e32 v11, v160, v18, vcc
	v_add_f32_e32 v11, 1.0, v11
	v_rcp_f32_e32 v11, v11
	s_nop 0
	v_fma_f32 v11, v11, -2.0, 1.0
.LBB0_1284:
	s_andn2_saveexec_b64 s[74:75], s[74:75]
	v_mul_f32_e32 v11, v10, v10
	v_fmamk_f32 v18, v11, 0xbbbac73d, v158
	v_fmaak_f32 v18, v11, v18, 0xbd5c1c4e
	v_fmaak_f32 v18, v11, v18, 0x3e088382
	v_fmaak_f32 v18, v11, v18, 0xbeaaaa99
	v_mul_f32_e64 v18, |v10|, v18
	v_fma_f32 v11, v11, v18, |v10|
	s_or_b64 exec, exec, s[74:75]
	v_add_f32_e64 v12, v12, 0
	v_add_f32_e64 v13, v13, 0
	s_nop 0
	v_add_f32_e64 v12, v12, v16
	v_add_f32_e64 v13, v13, v17
	v_mul_f32_e32 v16, 0x3d372713, v15
	v_mul_f32_e32 v16, v15, v16
	v_fma_f32 v16, v15, v16, v15
	v_add_f32_e64 v12, v12, v20
	v_add_f32_e64 v13, v13, v21
	v_mul_f32_e32 v16, 0x3f4c422a, v16
	v_add_f32_e64 v12, v12, v24
	v_add_f32_e64 v13, v13, v25
	v_cmp_nlt_f32_e64 s[74:75], |v16|, s21
	s_and_saveexec_b64 s[90:91], s[74:75]
	s_xor_b64 s[74:75], exec, s[90:91]
	s_cbranch_execz .LBB0_1288
	v_add_f32_e64 v17, |v16|, |v16|
	v_mul_f32_e32 v18, 0x3fb8aa3b, v17
	v_rndne_f32_e32 v19, v18
	v_sub_f32_e32 v20, v18, v19
	v_fma_f32 v18, v17, s50, -v18
	v_fmac_f32_e32 v18, 0x32a5705f, v17
	v_add_f32_e32 v18, v20, v18
	v_cvt_i32_f32_e32 v19, v19
	v_exp_f32_e32 v18, v18
	v_cmp_ngt_f32_e32 vcc, s51, v17
	v_ldexp_f32 v18, v18, v19
	s_nop 0
	v_cndmask_b32_e32 v18, 0, v18, vcc
	v_cmp_nlt_f32_e32 vcc, s83, v17
	s_nop 1
	v_cndmask_b32_e32 v17, v160, v18, vcc
	v_add_f32_e32 v17, 1.0, v17
	v_rcp_f32_e32 v17, v17
	s_nop 0
	v_fma_f32 v17, v17, -2.0, 1.0

.LBB0_1299:
	s_or_b64 exec, exec, s[12:13]
	v_lshl_add_u64 v[148:149], s[10:11], 0, v[136:137]
	v_add_co_u32_e32 v14, vcc, 0x1000, v148
	v_add_u32_e32 v120, s78, v143
	s_nop 0
	v_addc_co_u32_e32 v15, vcc, 0, v149, vcc
	global_load_dwordx4 v[14:17], v[14:15], off
	v_cmp_gt_i32_e64 s[10:11], s20, v120
	v_mov_b32_e32 v21, 0
	v_ashrrev_i32_e32 v121, 31, v120
	v_mov_b32_e32 v20, 0
	v_mov_b32_e32 v19, 0
	v_mov_b32_e32 v18, 0
	s_and_saveexec_b64 s[12:13], s[10:11]
	s_cbranch_execz .LBB0_1333
	v_lshlrev_b64 v[18:19], 10, v[120:121]
	v_lshl_add_u64 v[30:31], v[128:129], 0, v[18:19]
	global_load_dwordx4 v[18:21], v[30:31], off offset:16
	global_load_dwordx4 v[32:35], v[30:31], off
	v_add_co_u32_e32 v24, vcc, 0x400000, v30
	v_lshl_add_u64 v[22:23], v[30:31], 0, s[18:19]
	s_nop 0
	v_addc_co_u32_e32 v25, vcc, 0, v31, vcc
	global_load_dwordx4 v[36:39], v[24:25], off
	s_nop 0
	global_load_dwordx4 v[22:25], v[22:23], off offset:16
	v_add_co_u32_e32 v28, vcc, 0x800000, v30
	s_waitcnt vmcnt(2)
	v_add_f32_e64 v26, v32, 0
	v_add_f32_e64 v27, v33, 0
	v_addc_co_u32_e32 v29, vcc, 0, v31, vcc
	s_waitcnt vmcnt(1)
	v_add_f32_e64 v32, v26, v36
	v_add_f32_e64 v33, v27, v37
	v_lshl_add_u64 v[26:27], v[30:31], 0, s[22:23]
	global_load_dwordx4 v[40:43], v[28:29], off
	s_nop 0
	global_load_dwordx4 v[26:29], v[26:27], off offset:16
	s_waitcnt vmcnt(1)
	v_add_f32_e64 v36, v32, v40
	v_add_f32_e64 v37, v33, v41
	v_lshl_add_u64 v[32:33], v[30:31], 0, s[30:31]
	v_add_co_u32_e32 v30, vcc, 0xc00000, v30
	s_nop 1
	v_addc_co_u32_e32 v31, vcc, 0, v31, vcc
	global_load_dwordx4 v[44:47], v[30:31], off
	s_nop 0
	global_load_dwordx4 v[30:33], v[32:33], off offset:16
	s_waitcnt vmcnt(1)
	v_add_f32_e64 v36, v36, v44
	v_add_f32_e64 v37, v37, v45
	s_nop 0
	v_mul_f32_e32 v40, 0x3d372713, v36
	v_mul_f32_e32 v40, v36, v40
	v_fma_f32 v40, v36, v40, v36
	v_mul_f32_e32 v40, 0x3f4c422a, v40
	v_cmp_nlt_f32_e64 s[74:75], |v40|, s21
	s_and_saveexec_b64 s[90:91], s[74:75]
	s_xor_b64 s[74:75], exec, s[90:91]
	s_cbranch_execz .LBB0_1302
	v_add_f32_e64 v41, |v40|, |v40|
	v_mul_f32_e32 v44, 0x3fb8aa3b, v41
	v_rndne_f32_e32 v45, v44
	v_sub_f32_e32 v48, v44, v45
	v_fma_f32 v44, v41, s50, -v44
	v_fmac_f32_e32 v44, 0x32a5705f, v41
	v_add_f32_e32 v44, v48, v44
	v_cvt_i32_f32_e32 v45, v45
	v_exp_f32_e32 v44, v44
	v_cmp_ngt_f32_e32 vcc, s51, v41
	v_ldexp_f32 v44, v44, v45
	s_nop 0
	v_cndmask_b32_e32 v44, 0, v44, vcc
	v_cmp_nlt_f32_e32 vcc, s83, v41
	s_nop 1
	v_cndmask_b32_e32 v41, v160, v44, vcc
	v_add_f32_e32 v41, 1.0, v41
	v_rcp_f32_e32 v41, v41
	s_nop 0
	v_fma_f32 v41, v41, -2.0, 1.0
.LBB0_1302:
	s_andn2_saveexec_b64 s[74:75], s[74:75]
	v_mul_f32_e32 v41, v40, v40
	v_fmamk_f32 v44, v41, 0xbbbac73d, v158
	v_fmaak_f32 v44, v41, v44, 0xbd5c1c4e
	v_fmaak_f32 v44, v41, v44, 0x3e088382
	v_fmaak_f32 v44, v41, v44, 0xbeaaaa99
	v_mul_f32_e64 v44, |v40|, v44
	v_fma_f32 v41, v41, v44, |v40|
	s_or_b64 exec, exec, s[74:75]
	v_add_f32_e64 v34, v34, 0
	v_add_f32_e64 v35, v35, 0
	s_nop 0
	v_add_f32_e64 v34, v34, v38
	v_add_f32_e64 v35, v35, v39
	v_mul_f32_e32 v38, 0x3d372713, v37
	v_mul_f32_e32 v38, v37, v38
	v_fma_f32 v38, v37, v38, v37
	v_add_f32_e64 v34, v34, v42
	v_add_f32_e64 v35, v35, v43
	v_mul_f32_e32 v38, 0x3f4c422a, v38
	v_add_f32_e64 v34, v34, v46
	v_add_f32_e64 v35, v35, v47
	v_cmp_nlt_f32_e64 s[74:75], |v38|, s21
	s_and_saveexec_b64 s[90:91], s[74:75]
	s_xor_b64 s[74:75], exec, s[90:91]
	s_cbranch_execz .LBB0_1306
	v_add_f32_e64 v39, |v38|, |v38|
	v_mul_f32_e32 v42, 0x3fb8aa3b, v39
	v_rndne_f32_e32 v43, v42
	v_sub_f32_e32 v44, v42, v43
	v_fma_f32 v42, v39, s50, -v42
	v_fmac_f32_e32 v42, 0x32a5705f, v39
	v_add_f32_e32 v42, v44, v42
	v_cvt_i32_f32_e32 v43, v43
	v_exp_f32_e32 v42, v42
	v_cmp_ngt_f32_e32 vcc, s51, v39
	v_ldexp_f32 v42, v42, v43
	s_nop 0
	v_cndmask_b32_e32 v42, 0, v42, vcc
	v_cmp_nlt_f32_e32 vcc, s83, v39
	s_nop 1
	v_cndmask_b32_e32 v39, v160, v42, vcc
	v_add_f32_e32 v39, 1.0, v39
	v_rcp_f32_e32 v39, v39
	s_nop 0
	v_fma_f32 v39, v39, -2.0, 1.0

.LBB0_1314:
	s_andn2_saveexec_b64 s[74:75], s[74:75]
	v_mul_f32_e32 v45, v44, v44
	v_fmamk_f32 v46, v45, 0xbbbac73d, v158
	v_fmaak_f32 v46, v45, v46, 0xbd5c1c4e
	v_fmaak_f32 v46, v45, v46, 0x3e088382
	v_fmaak_f32 v46, v45, v46, 0xbeaaaa99
	v_mul_f32_e64 v46, |v44|, v46
	v_fma_f32 v45, v45, v46, |v44|
	s_or_b64 exec, exec, s[74:75]
	v_add_f32_e64 v18, v18, 0
	v_add_f32_e64 v19, v19, 0
	s_nop 0
	v_add_f32_e64 v18, v18, v22
	v_add_f32_e64 v19, v19, v23
	s_nop 0
	v_add_f32_e64 v18, v18, v26
	v_add_f32_e64 v19, v19, v27
	s_waitcnt vmcnt(0)
	v_add_f32_e64 v22, v18, v30
	v_add_f32_e64 v23, v19, v31
	s_nop 0
	v_mul_f32_e32 v18, 0x3d372713, v22
	v_mul_f32_e32 v18, v22, v18
	v_fma_f32 v18, v22, v18, v22
	v_mul_f32_e32 v18, 0x3f4c422a, v18
	v_cmp_nlt_f32_e64 s[74:75], |v18|, s21
	s_and_saveexec_b64 s[90:91], s[74:75]
	s_xor_b64 s[74:75], exec, s[90:91]
	s_cbranch_execz .LBB0_1318
	v_add_f32_e64 v19, |v18|, |v18|
	v_mul_f32_e32 v26, 0x3fb8aa3b, v19
	v_rndne_f32_e32 v27, v26
	v_sub_f32_e32 v30, v26, v27
	v_fma_f32 v26, v19, s50, -v26
	v_fmac_f32_e32 v26, 0x32a5705f, v19
	v_add_f32_e32 v26, v30, v26
	v_cvt_i32_f32_e32 v27, v27
	v_exp_f32_e32 v26, v26
	v_cmp_ngt_f32_e32 vcc, s51, v19
	v_ldexp_f32 v26, v26, v27
	s_nop 0
	v_cndmask_b32_e32 v26, 0, v26, vcc
	v_cmp_nlt_f32_e32 vcc, s83, v19
	s_nop 1
	v_cndmask_b32_e32 v19, v160, v26, vcc
	v_add_f32_e32 v19, 1.0, v19
	v_rcp_f32_e32 v19, v19
	s_nop 0
	v_fma_f32 v19, v19, -2.0, 1.0
.LBB0_1318:
	s_andn2_saveexec_b64 s[74:75], s[74:75]
	v_mul_f32_e32 v19, v18, v18
	v_fmamk_f32 v26, v19, 0xbbbac73d, v158
	v_fmaak_f32 v26, v19, v26, 0xbd5c1c4e
	v_fmaak_f32 v26, v19, v26, 0x3e088382
	v_fmaak_f32 v26, v19, v26, 0xbeaaaa99
	v_mul_f32_e64 v26, |v18|, v26
	v_fma_f32 v19, v19, v26, |v18|
	s_or_b64 exec, exec, s[74:75]
	v_add_f32_e64 v20, v20, 0
	v_add_f32_e64 v21, v21, 0
	s_nop 0
	v_add_f32_e64 v20, v20, v24
	v_add_f32_e64 v21, v21, v25
	v_mul_f32_e32 v24, 0x3d372713, v23
	v_mul_f32_e32 v24, v23, v24
	v_fma_f32 v24, v23, v24, v23
	v_add_f32_e64 v20, v20, v28
	v_add_f32_e64 v21, v21, v29
	v_mul_f32_e32 v24, 0x3f4c422a, v24
	v_add_f32_e64 v20, v20, v32
	v_add_f32_e64 v21, v21, v33
	v_cmp_nlt_f32_e64 s[74:75], |v24|, s21
	s_and_saveexec_b64 s[90:91], s[74:75]
	s_xor_b64 s[74:75], exec, s[90:91]
	s_cbranch_execz .LBB0_1322
	v_add_f32_e64 v25, |v24|, |v24|
	v_mul_f32_e32 v26, 0x3fb8aa3b, v25
	v_rndne_f32_e32 v27, v26
	v_sub_f32_e32 v28, v26, v27
	v_fma_f32 v26, v25, s50, -v26
	v_fmac_f32_e32 v26, 0x32a5705f, v25
	v_add_f32_e32 v26, v28, v26
	v_cvt_i32_f32_e32 v27, v27
	v_exp_f32_e32 v26, v26
	v_cmp_ngt_f32_e32 vcc, s51, v25
	v_ldexp_f32 v26, v26, v27
	s_nop 0
	v_cndmask_b32_e32 v26, 0, v26, vcc
	v_cmp_nlt_f32_e32 vcc, s83, v25
	s_nop 1
	v_cndmask_b32_e32 v25, v160, v26, vcc
	v_add_f32_e32 v25, 1.0, v25
	v_rcp_f32_e32 v25, v25
	s_nop 0
	v_fma_f32 v25, v25, -2.0, 1.0

.LBB0_1333:
	s_or_b64 exec, exec, s[12:13]
	v_add_co_u32_e32 v22, vcc, 0x2000, v148
	v_add_u32_e32 v130, s78, v150
	s_nop 0
	v_addc_co_u32_e32 v23, vcc, 0, v149, vcc
	global_load_dwordx4 v[22:25], v[22:23], off
	v_cmp_gt_i32_e64 s[12:13], s20, v130
	v_mov_b32_e32 v29, 0
	v_ashrrev_i32_e32 v131, 31, v130
	v_mov_b32_e32 v28, 0
	v_mov_b32_e32 v27, 0
	v_mov_b32_e32 v26, 0
	s_and_saveexec_b64 s[90:91], s[12:13]
	s_cbranch_execz .LBB0_1367
	v_lshlrev_b64 v[26:27], 10, v[130:131]
	v_lshl_add_u64 v[38:39], v[128:129], 0, v[26:27]
	global_load_dwordx4 v[26:29], v[38:39], off offset:16
	global_load_dwordx4 v[40:43], v[38:39], off
	v_add_co_u32_e32 v32, vcc, 0x400000, v38
	v_lshl_add_u64 v[30:31], v[38:39], 0, s[18:19]
	s_nop 0
	v_addc_co_u32_e32 v33, vcc, 0, v39, vcc
	global_load_dwordx4 v[44:47], v[32:33], off
	s_nop 0
	global_load_dwordx4 v[30:33], v[30:31], off offset:16
	v_add_co_u32_e32 v36, vcc, 0x800000, v38
	s_waitcnt vmcnt(2)
	v_add_f32_e64 v34, v40, 0
	v_add_f32_e64 v35, v41, 0
	v_addc_co_u32_e32 v37, vcc, 0, v39, vcc
	s_waitcnt vmcnt(1)
	v_add_f32_e64 v40, v34, v44
	v_add_f32_e64 v41, v35, v45
	v_lshl_add_u64 v[34:35], v[38:39], 0, s[22:23]
	global_load_dwordx4 v[48:51], v[36:37], off
	s_nop 0
	global_load_dwordx4 v[34:37], v[34:35], off offset:16
	s_waitcnt vmcnt(1)
	v_add_f32_e64 v44, v40, v48
	v_add_f32_e64 v45, v41, v49
	v_lshl_add_u64 v[40:41], v[38:39], 0, s[30:31]
	v_add_co_u32_e32 v38, vcc, 0xc00000, v38
	s_nop 1
	v_addc_co_u32_e32 v39, vcc, 0, v39, vcc
	global_load_dwordx4 v[52:55], v[38:39], off
	s_nop 0
	global_load_dwordx4 v[38:41], v[40:41], off offset:16
	s_waitcnt vmcnt(1)
	v_add_f32_e64 v44, v44, v52
	v_add_f32_e64 v45, v45, v53
	s_nop 0
	v_mul_f32_e32 v48, 0x3d372713, v44
	v_mul_f32_e32 v48, v44, v48
	v_fma_f32 v48, v44, v48, v44
	v_mul_f32_e32 v48, 0x3f4c422a, v48
	v_cmp_nlt_f32_e64 s[74:75], |v48|, s21
	s_and_saveexec_b64 vcc, s[74:75]
	s_xor_b64 s[74:75], exec, vcc
	s_cbranch_execz .LBB0_1336
	v_add_f32_e64 v49, |v48|, |v48|
	v_mul_f32_e32 v52, 0x3fb8aa3b, v49
	v_rndne_f32_e32 v53, v52
	v_sub_f32_e32 v56, v52, v53
	v_fma_f32 v52, v49, s50, -v52
	v_fmac_f32_e32 v52, 0x32a5705f, v49
	v_add_f32_e32 v52, v56, v52
	v_cvt_i32_f32_e32 v53, v53
	v_exp_f32_e32 v52, v52
	v_cmp_ngt_f32_e32 vcc, s51, v49
	v_ldexp_f32 v52, v52, v53
	s_nop 0
	v_cndmask_b32_e32 v52, 0, v52, vcc
	v_cmp_nlt_f32_e32 vcc, s83, v49
	s_nop 1
	v_cndmask_b32_e32 v49, v160, v52, vcc
	v_add_f32_e32 v49, 1.0, v49
	v_rcp_f32_e32 v49, v49
	s_nop 0
	v_fma_f32 v49, v49, -2.0, 1.0
.LBB0_1336:
	s_andn2_saveexec_b64 s[74:75], s[74:75]
	v_mul_f32_e32 v49, v48, v48
	v_fmamk_f32 v52, v49, 0xbbbac73d, v158
	v_fmaak_f32 v52, v49, v52, 0xbd5c1c4e
	v_fmaak_f32 v52, v49, v52, 0x3e088382
	v_fmaak_f32 v52, v49, v52, 0xbeaaaa99
	v_mul_f32_e64 v52, |v48|, v52
	v_fma_f32 v49, v49, v52, |v48|
	s_or_b64 exec, exec, s[74:75]
	v_add_f32_e64 v42, v42, 0
	v_add_f32_e64 v43, v43, 0
	s_nop 0
	v_add_f32_e64 v42, v42, v46
	v_add_f32_e64 v43, v43, v47
	v_mul_f32_e32 v46, 0x3d372713, v45
	v_mul_f32_e32 v46, v45, v46
	v_fma_f32 v46, v45, v46, v45
	v_add_f32_e64 v42, v42, v50
	v_add_f32_e64 v43, v43, v51
	v_mul_f32_e32 v46, 0x3f4c422a, v46
	v_add_f32_e64 v42, v42, v54
	v_add_f32_e64 v43, v43, v55
	v_cmp_nlt_f32_e64 s[58:59], |v46|, s21
	s_and_saveexec_b64 s[74:75], s[58:59]
	s_xor_b64 s[74:75], exec, s[74:75]
	s_cbranch_execz .LBB0_1340
	v_add_f32_e64 v47, |v46|, |v46|
	v_mul_f32_e32 v50, 0x3fb8aa3b, v47
	v_rndne_f32_e32 v51, v50
	v_sub_f32_e32 v52, v50, v51
	v_fma_f32 v50, v47, s50, -v50
	v_fmac_f32_e32 v50, 0x32a5705f, v47
	v_add_f32_e32 v50, v52, v50
	v_cvt_i32_f32_e32 v51, v51
	v_exp_f32_e32 v50, v50
	v_cmp_ngt_f32_e32 vcc, s51, v47
	v_ldexp_f32 v50, v50, v51
	s_nop 0
	v_cndmask_b32_e32 v50, 0, v50, vcc
	v_cmp_nlt_f32_e32 vcc, s83, v47
	s_nop 1
	v_cndmask_b32_e32 v47, v160, v50, vcc
	v_add_f32_e32 v47, 1.0, v47
	v_rcp_f32_e32 v47, v47
	s_nop 0
	v_fma_f32 v47, v47, -2.0, 1.0

.LBB0_1348:
	s_andn2_saveexec_b64 s[74:75], s[74:75]
	v_mul_f32_e32 v53, v52, v52
	v_fmamk_f32 v54, v53, 0xbbbac73d, v158
	v_fmaak_f32 v54, v53, v54, 0xbd5c1c4e
	v_fmaak_f32 v54, v53, v54, 0x3e088382
	v_fmaak_f32 v54, v53, v54, 0xbeaaaa99
	v_mul_f32_e64 v54, |v52|, v54
	v_fma_f32 v53, v53, v54, |v52|
	s_or_b64 exec, exec, s[74:75]
	v_add_f32_e64 v26, v26, 0
	v_add_f32_e64 v27, v27, 0
	s_nop 0
	v_add_f32_e64 v26, v26, v30
	v_add_f32_e64 v27, v27, v31
	s_nop 0
	v_add_f32_e64 v26, v26, v34
	v_add_f32_e64 v27, v27, v35
	s_waitcnt vmcnt(0)
	v_add_f32_e64 v30, v26, v38
	v_add_f32_e64 v31, v27, v39
	s_nop 0
	v_mul_f32_e32 v26, 0x3d372713, v30
	v_mul_f32_e32 v26, v30, v26
	v_fma_f32 v26, v30, v26, v30
	v_mul_f32_e32 v26, 0x3f4c422a, v26
	v_cmp_nlt_f32_e64 s[58:59], |v26|, s21
	s_and_saveexec_b64 s[74:75], s[58:59]
	s_xor_b64 s[74:75], exec, s[74:75]
	s_cbranch_execz .LBB0_1352
	v_add_f32_e64 v27, |v26|, |v26|
	v_mul_f32_e32 v34, 0x3fb8aa3b, v27
	v_rndne_f32_e32 v35, v34
	v_sub_f32_e32 v38, v34, v35
	v_fma_f32 v34, v27, s50, -v34
	v_fmac_f32_e32 v34, 0x32a5705f, v27
	v_add_f32_e32 v34, v38, v34
	v_cvt_i32_f32_e32 v35, v35
	v_exp_f32_e32 v34, v34
	v_cmp_ngt_f32_e32 vcc, s51, v27
	v_ldexp_f32 v34, v34, v35
	s_nop 0
	v_cndmask_b32_e32 v34, 0, v34, vcc
	v_cmp_nlt_f32_e32 vcc, s83, v27
	s_nop 1
	v_cndmask_b32_e32 v27, v160, v34, vcc
	v_add_f32_e32 v27, 1.0, v27
	v_rcp_f32_e32 v27, v27
	s_nop 0
	v_fma_f32 v27, v27, -2.0, 1.0
.LBB0_1352:
	s_andn2_saveexec_b64 s[74:75], s[74:75]
	v_mul_f32_e32 v27, v26, v26
	v_fmamk_f32 v34, v27, 0xbbbac73d, v158
	v_fmaak_f32 v34, v27, v34, 0xbd5c1c4e
	v_fmaak_f32 v34, v27, v34, 0x3e088382
	v_fmaak_f32 v34, v27, v34, 0xbeaaaa99
	v_mul_f32_e64 v34, |v26|, v34
	v_fma_f32 v27, v27, v34, |v26|
	s_or_b64 exec, exec, s[74:75]
	v_add_f32_e64 v28, v28, 0
	v_add_f32_e64 v29, v29, 0
	s_nop 0
	v_add_f32_e64 v28, v28, v32
	v_add_f32_e64 v29, v29, v33
	v_mul_f32_e32 v32, 0x3d372713, v31
	v_mul_f32_e32 v32, v31, v32
	v_fma_f32 v32, v31, v32, v31
	v_add_f32_e64 v28, v28, v36
	v_add_f32_e64 v29, v29, v37
	v_mul_f32_e32 v32, 0x3f4c422a, v32
	v_add_f32_e64 v28, v28, v40
	v_add_f32_e64 v29, v29, v41
	v_cmp_nlt_f32_e64 s[58:59], |v32|, s21
	s_and_saveexec_b64 s[74:75], s[58:59]
	s_xor_b64 s[74:75], exec, s[74:75]
	s_cbranch_execz .LBB0_1356
	v_add_f32_e64 v33, |v32|, |v32|
	v_mul_f32_e32 v34, 0x3fb8aa3b, v33
	v_rndne_f32_e32 v35, v34
	v_sub_f32_e32 v36, v34, v35
	v_fma_f32 v34, v33, s50, -v34
	v_fmac_f32_e32 v34, 0x32a5705f, v33
	v_add_f32_e32 v34, v36, v34
	v_cvt_i32_f32_e32 v35, v35
	v_exp_f32_e32 v34, v34
	v_cmp_ngt_f32_e32 vcc, s51, v33
	v_ldexp_f32 v34, v34, v35
	s_nop 0
	v_cndmask_b32_e32 v34, 0, v34, vcc
	v_cmp_nlt_f32_e32 vcc, s83, v33
	s_nop 1
	v_cndmask_b32_e32 v33, v160, v34, vcc
	v_add_f32_e32 v33, 1.0, v33
	v_rcp_f32_e32 v33, v33
	s_nop 0
	v_fma_f32 v33, v33, -2.0, 1.0

.LBB0_1367:
	s_or_b64 exec, exec, s[90:91]
	v_add_co_u32_e32 v30, vcc, 0x3000, v148
	s_nop 1
	v_addc_co_u32_e32 v31, vcc, 0, v149, vcc
	global_load_dwordx4 v[30:33], v[30:31], off
	ds_write_b128 v151, v[2:5]
	s_waitcnt vmcnt(3)
	ds_write_b128 v151, v[6:9] offset:18432
	ds_write_b128 v152, v[10:13]
	s_waitcnt vmcnt(2)
	ds_write_b128 v152, v[14:17] offset:18432
	ds_write_b128 v153, v[18:21]
	s_waitcnt vmcnt(1)
	ds_write_b128 v153, v[22:25] offset:18432
	ds_write_b128 v154, v[26:29]
	v_mov_b32_e32 v21, 0
	v_mov_b32_e32 v20, 0
	v_mov_b32_e32 v19, 0
	v_mov_b32_e32 v18, 0
	s_waitcnt vmcnt(0)
	ds_write_b128 v154, v[30:33] offset:18432
	s_and_saveexec_b64 s[90:91], s[6:7]
	s_cbranch_execz .LBB0_1401
	v_lshlrev_b64 v[2:3], 10, v[110:111]
	v_lshl_add_u64 v[14:15], v[128:129], 0, v[2:3]
	global_load_dwordx4 v[2:5], v[14:15], off offset:272
	global_load_dwordx4 v[16:19], v[14:15], off offset:256
	v_add_co_u32_e32 v8, vcc, 0x400000, v14
	v_lshl_add_u64 v[6:7], v[14:15], 0, s[46:47]
	s_nop 0
	v_addc_co_u32_e32 v9, vcc, 0, v15, vcc
	global_load_dwordx4 v[20:23], v[8:9], off offset:256
	s_nop 0
	global_load_dwordx4 v[6:9], v[6:7], off offset:16
	v_add_co_u32_e32 v12, vcc, 0x800000, v14
	s_waitcnt vmcnt(2)
	v_add_f32_e64 v10, v16, 0
	v_add_f32_e64 v11, v17, 0
	v_addc_co_u32_e32 v13, vcc, 0, v15, vcc
	s_waitcnt vmcnt(1)
	v_add_f32_e64 v16, v10, v20
	v_add_f32_e64 v17, v11, v21
	v_lshl_add_u64 v[10:11], v[14:15], 0, s[56:57]
	global_load_dwordx4 v[24:27], v[12:13], off offset:256
	s_nop 0
	global_load_dwordx4 v[10:13], v[10:11], off offset:16
	s_waitcnt vmcnt(1)
	v_add_f32_e64 v20, v16, v24
	v_add_f32_e64 v21, v17, v25
	v_lshl_add_u64 v[16:17], v[14:15], 0, s[60:61]
	v_add_co_u32_e32 v14, vcc, 0xc00000, v14
	s_nop 1
	v_addc_co_u32_e32 v15, vcc, 0, v15, vcc
	global_load_dwordx4 v[28:31], v[14:15], off offset:256
	s_nop 0
	global_load_dwordx4 v[14:17], v[16:17], off offset:16
	s_waitcnt vmcnt(1)
	v_add_f32_e64 v20, v20, v28
	v_add_f32_e64 v21, v21, v29
	s_nop 0
	v_mul_f32_e32 v24, 0x3d372713, v20
	v_mul_f32_e32 v24, v20, v24
	v_fma_f32 v24, v20, v24, v20
	v_mul_f32_e32 v24, 0x3f4c422a, v24
	v_cmp_nlt_f32_e64 s[58:59], |v24|, s21
	s_and_saveexec_b64 s[74:75], s[58:59]
	s_xor_b64 s[74:75], exec, s[74:75]
	s_cbranch_execz .LBB0_1370
	v_add_f32_e64 v25, |v24|, |v24|
	v_mul_f32_e32 v28, 0x3fb8aa3b, v25
	v_rndne_f32_e32 v29, v28
	v_sub_f32_e32 v32, v28, v29
	v_fma_f32 v28, v25, s50, -v28
	v_fmac_f32_e32 v28, 0x32a5705f, v25
	v_add_f32_e32 v28, v32, v28
	v_cvt_i32_f32_e32 v29, v29
	v_exp_f32_e32 v28, v28
	v_cmp_ngt_f32_e32 vcc, s51, v25
	v_ldexp_f32 v28, v28, v29
	s_nop 0
	v_cndmask_b32_e32 v28, 0, v28, vcc
	v_cmp_nlt_f32_e32 vcc, s83, v25
	s_nop 1
	v_cndmask_b32_e32 v25, v160, v28, vcc
	v_add_f32_e32 v25, 1.0, v25
	v_rcp_f32_e32 v25, v25
	s_nop 0
	v_fma_f32 v25, v25, -2.0, 1.0
.LBB0_1370:
	s_andn2_saveexec_b64 s[74:75], s[74:75]
	v_mul_f32_e32 v25, v24, v24
	v_fmamk_f32 v28, v25, 0xbbbac73d, v158
	v_fmaak_f32 v28, v25, v28, 0xbd5c1c4e
	v_fmaak_f32 v28, v25, v28, 0x3e088382
	v_fmaak_f32 v28, v25, v28, 0xbeaaaa99
	v_mul_f32_e64 v28, |v24|, v28
	v_fma_f32 v25, v25, v28, |v24|
	s_or_b64 exec, exec, s[74:75]
	v_add_f32_e64 v18, v18, 0
	v_add_f32_e64 v19, v19, 0
	s_nop 0
	v_add_f32_e64 v18, v18, v22
	v_add_f32_e64 v19, v19, v23
	v_mul_f32_e32 v22, 0x3d372713, v21
	v_mul_f32_e32 v22, v21, v22
	v_fma_f32 v22, v21, v22, v21
	v_add_f32_e64 v18, v18, v26
	v_add_f32_e64 v19, v19, v27
	v_mul_f32_e32 v22, 0x3f4c422a, v22
	v_add_f32_e64 v18, v18, v30
	v_add_f32_e64 v19, v19, v31
	v_cmp_nlt_f32_e64 s[58:59], |v22|, s21
	s_and_saveexec_b64 s[74:75], s[58:59]
	s_xor_b64 s[74:75], exec, s[74:75]
	s_cbranch_execz .LBB0_1374
	v_add_f32_e64 v23, |v22|, |v22|
	v_mul_f32_e32 v26, 0x3fb8aa3b, v23
	v_rndne_f32_e32 v27, v26
	v_sub_f32_e32 v28, v26, v27
	v_fma_f32 v26, v23, s50, -v26
	v_fmac_f32_e32 v26, 0x32a5705f, v23
	v_add_f32_e32 v26, v28, v26
	v_cvt_i32_f32_e32 v27, v27
	v_exp_f32_e32 v26, v26
	v_cmp_ngt_f32_e32 vcc, s51, v23
	v_ldexp_f32 v26, v26, v27
	s_nop 0
	v_cndmask_b32_e32 v26, 0, v26, vcc
	v_cmp_nlt_f32_e32 vcc, s83, v23
	s_nop 1
	v_cndmask_b32_e32 v23, v160, v26, vcc
	v_add_f32_e32 v23, 1.0, v23
	v_rcp_f32_e32 v23, v23
	s_nop 0
	v_fma_f32 v23, v23, -2.0, 1.0

.LBB0_1382:
	s_andn2_saveexec_b64 s[74:75], s[74:75]
	v_mul_f32_e32 v29, v28, v28
	v_fmamk_f32 v30, v29, 0xbbbac73d, v158
	v_fmaak_f32 v30, v29, v30, 0xbd5c1c4e
	v_fmaak_f32 v30, v29, v30, 0x3e088382
	v_fmaak_f32 v30, v29, v30, 0xbeaaaa99
	v_mul_f32_e64 v30, |v28|, v30
	v_fma_f32 v29, v29, v30, |v28|
	s_or_b64 exec, exec, s[74:75]
	v_add_f32_e64 v2, v2, 0
	v_add_f32_e64 v3, v3, 0
	s_nop 0
	v_add_f32_e64 v2, v2, v6
	v_add_f32_e64 v3, v3, v7
	s_nop 0
	v_add_f32_e64 v2, v2, v10
	v_add_f32_e64 v3, v3, v11
	s_waitcnt vmcnt(0)
	v_add_f32_e64 v2, v2, v14
	v_add_f32_e64 v3, v3, v15
	s_nop 0
	v_mul_f32_e32 v6, 0x3d372713, v2
	v_mul_f32_e32 v6, v2, v6
	v_fma_f32 v6, v2, v6, v2
	v_mul_f32_e32 v6, 0x3f4c422a, v6
	v_cmp_nlt_f32_e64 s[58:59], |v6|, s21
	s_and_saveexec_b64 s[74:75], s[58:59]
	s_xor_b64 s[74:75], exec, s[74:75]
	s_cbranch_execz .LBB0_1386
	v_add_f32_e64 v7, |v6|, |v6|
	v_mul_f32_e32 v10, 0x3fb8aa3b, v7
	v_rndne_f32_e32 v11, v10
	v_sub_f32_e32 v14, v10, v11
	v_fma_f32 v10, v7, s50, -v10
	v_fmac_f32_e32 v10, 0x32a5705f, v7
	v_add_f32_e32 v10, v14, v10
	v_cvt_i32_f32_e32 v11, v11
	v_exp_f32_e32 v10, v10
	v_cmp_ngt_f32_e32 vcc, s51, v7
	v_ldexp_f32 v10, v10, v11
	s_nop 0
	v_cndmask_b32_e32 v10, 0, v10, vcc
	v_cmp_nlt_f32_e32 vcc, s83, v7
	s_nop 1
	v_cndmask_b32_e32 v7, v160, v10, vcc
	v_add_f32_e32 v7, 1.0, v7
	v_rcp_f32_e32 v7, v7
	s_nop 0
	v_fma_f32 v7, v7, -2.0, 1.0
.LBB0_1386:
	s_andn2_saveexec_b64 s[74:75], s[74:75]
	v_mul_f32_e32 v7, v6, v6
	v_fmamk_f32 v10, v7, 0xbbbac73d, v158
	v_fmaak_f32 v10, v7, v10, 0xbd5c1c4e
	v_fmaak_f32 v10, v7, v10, 0x3e088382
	v_fmaak_f32 v10, v7, v10, 0xbeaaaa99
	v_mul_f32_e64 v10, |v6|, v10
	v_fma_f32 v7, v7, v10, |v6|
	s_or_b64 exec, exec, s[74:75]
	v_add_f32_e64 v4, v4, 0
	v_add_f32_e64 v5, v5, 0
	s_nop 0
	v_add_f32_e64 v4, v4, v8
	v_add_f32_e64 v5, v5, v9
	v_mul_f32_e32 v8, 0x3d372713, v3
	v_mul_f32_e32 v8, v3, v8
	v_fma_f32 v8, v3, v8, v3
	v_add_f32_e64 v4, v4, v12
	v_add_f32_e64 v5, v5, v13
	v_mul_f32_e32 v8, 0x3f4c422a, v8
	v_add_f32_e64 v4, v4, v16
	v_add_f32_e64 v5, v5, v17
	v_cmp_nlt_f32_e64 s[58:59], |v8|, s21
	s_and_saveexec_b64 s[74:75], s[58:59]
	s_xor_b64 s[74:75], exec, s[74:75]
	s_cbranch_execz .LBB0_1390
	v_add_f32_e64 v9, |v8|, |v8|
	v_mul_f32_e32 v10, 0x3fb8aa3b, v9
	v_rndne_f32_e32 v11, v10
	v_sub_f32_e32 v12, v10, v11
	v_fma_f32 v10, v9, s50, -v10
	v_fmac_f32_e32 v10, 0x32a5705f, v9
	v_add_f32_e32 v10, v12, v10
	v_cvt_i32_f32_e32 v11, v11
	v_exp_f32_e32 v10, v10
	v_cmp_ngt_f32_e32 vcc, s51, v9
	v_ldexp_f32 v10, v10, v11
	s_nop 0
	v_cndmask_b32_e32 v10, 0, v10, vcc
	v_cmp_nlt_f32_e32 vcc, s83, v9
	s_nop 1
	v_cndmask_b32_e32 v9, v160, v10, vcc
	v_add_f32_e32 v9, 1.0, v9
	v_rcp_f32_e32 v9, v9
	s_nop 0
	v_fma_f32 v9, v9, -2.0, 1.0

.LBB0_1401:
	s_or_b64 exec, exec, s[90:91]
	v_add_co_u32_e32 v2, vcc, 0x4000, v148
	v_mov_b32_e32 v29, 0
	s_nop 0
	v_addc_co_u32_e32 v3, vcc, 0, v149, vcc
	global_load_dwordx4 v[22:25], v[2:3], off
	v_mov_b32_e32 v28, 0
	v_mov_b32_e32 v27, 0
	v_mov_b32_e32 v26, 0
	s_and_saveexec_b64 s[90:91], s[8:9]
	s_cbranch_execz .LBB0_1435
	v_lshlrev_b64 v[2:3], 10, v[112:113]
	v_lshl_add_u64 v[14:15], v[128:129], 0, v[2:3]
	global_load_dwordx4 v[2:5], v[14:15], off offset:272
	global_load_dwordx4 v[26:29], v[14:15], off offset:256
	v_add_co_u32_e32 v8, vcc, 0x400000, v14
	v_lshl_add_u64 v[6:7], v[14:15], 0, s[46:47]
	s_nop 0
	v_addc_co_u32_e32 v9, vcc, 0, v15, vcc
	global_load_dwordx4 v[30:33], v[8:9], off offset:256
	s_nop 0
	global_load_dwordx4 v[6:9], v[6:7], off offset:16
	v_add_co_u32_e32 v12, vcc, 0x800000, v14
	s_waitcnt vmcnt(2)
	v_add_f32_e64 v10, v26, 0
	v_add_f32_e64 v11, v27, 0
	v_addc_co_u32_e32 v13, vcc, 0, v15, vcc
	s_waitcnt vmcnt(1)
	v_add_f32_e64 v16, v10, v30
	v_add_f32_e64 v17, v11, v31
	v_lshl_add_u64 v[10:11], v[14:15], 0, s[56:57]
	global_load_dwordx4 v[34:37], v[12:13], off offset:256
	s_nop 0
	global_load_dwordx4 v[10:13], v[10:11], off offset:16
	s_waitcnt vmcnt(1)
	v_add_f32_e64 v26, v16, v34
	v_add_f32_e64 v27, v17, v35
	v_lshl_add_u64 v[16:17], v[14:15], 0, s[60:61]
	v_add_co_u32_e32 v14, vcc, 0xc00000, v14
	s_nop 1
	v_addc_co_u32_e32 v15, vcc, 0, v15, vcc
	global_load_dwordx4 v[38:41], v[14:15], off offset:256
	s_nop 0
	global_load_dwordx4 v[14:17], v[16:17], off offset:16
	s_waitcnt vmcnt(1)
	v_add_f32_e64 v26, v26, v38
	v_add_f32_e64 v27, v27, v39
	s_nop 0
	v_mul_f32_e32 v30, 0x3d372713, v26
	v_mul_f32_e32 v30, v26, v30
	v_fma_f32 v30, v26, v30, v26
	v_mul_f32_e32 v30, 0x3f4c422a, v30
	v_cmp_nlt_f32_e64 s[58:59], |v30|, s21
	s_and_saveexec_b64 s[74:75], s[58:59]
	s_xor_b64 s[74:75], exec, s[74:75]
	s_cbranch_execz .LBB0_1404
	v_add_f32_e64 v31, |v30|, |v30|
	v_mul_f32_e32 v34, 0x3fb8aa3b, v31
	v_rndne_f32_e32 v35, v34
	v_sub_f32_e32 v38, v34, v35
	v_fma_f32 v34, v31, s50, -v34
	v_fmac_f32_e32 v34, 0x32a5705f, v31
	v_add_f32_e32 v34, v38, v34
	v_cvt_i32_f32_e32 v35, v35
	v_exp_f32_e32 v34, v34
	v_cmp_ngt_f32_e32 vcc, s51, v31
	v_ldexp_f32 v34, v34, v35
	s_nop 0
	v_cndmask_b32_e32 v34, 0, v34, vcc
	v_cmp_nlt_f32_e32 vcc, s83, v31
	s_nop 1
	v_cndmask_b32_e32 v31, v160, v34, vcc
	v_add_f32_e32 v31, 1.0, v31
	v_rcp_f32_e32 v31, v31
	s_nop 0
	v_fma_f32 v31, v31, -2.0, 1.0
.LBB0_1404:
	s_andn2_saveexec_b64 s[74:75], s[74:75]
	v_mul_f32_e32 v31, v30, v30
	v_fmamk_f32 v34, v31, 0xbbbac73d, v158
	v_fmaak_f32 v34, v31, v34, 0xbd5c1c4e
	v_fmaak_f32 v34, v31, v34, 0x3e088382
	v_fmaak_f32 v34, v31, v34, 0xbeaaaa99
	v_mul_f32_e64 v34, |v30|, v34
	v_fma_f32 v31, v31, v34, |v30|
	s_or_b64 exec, exec, s[74:75]
	v_add_f32_e64 v28, v28, 0
	v_add_f32_e64 v29, v29, 0
	s_nop 0
	v_add_f32_e64 v28, v28, v32
	v_add_f32_e64 v29, v29, v33
	v_mul_f32_e32 v32, 0x3d372713, v27
	v_mul_f32_e32 v32, v27, v32
	v_fma_f32 v32, v27, v32, v27
	v_add_f32_e64 v28, v28, v36
	v_add_f32_e64 v29, v29, v37
	v_mul_f32_e32 v32, 0x3f4c422a, v32
	v_add_f32_e64 v28, v28, v40
	v_add_f32_e64 v29, v29, v41
	v_cmp_nlt_f32_e64 s[58:59], |v32|, s21
	s_and_saveexec_b64 s[74:75], s[58:59]
	s_xor_b64 s[74:75], exec, s[74:75]
	s_cbranch_execz .LBB0_1408
	v_add_f32_e64 v33, |v32|, |v32|
	v_mul_f32_e32 v34, 0x3fb8aa3b, v33
	v_rndne_f32_e32 v35, v34
	v_sub_f32_e32 v36, v34, v35
	v_fma_f32 v34, v33, s50, -v34
	v_fmac_f32_e32 v34, 0x32a5705f, v33
	v_add_f32_e32 v34, v36, v34
	v_cvt_i32_f32_e32 v35, v35
	v_exp_f32_e32 v34, v34
	v_cmp_ngt_f32_e32 vcc, s51, v33
	v_ldexp_f32 v34, v34, v35
	s_nop 0
	v_cndmask_b32_e32 v34, 0, v34, vcc
	v_cmp_nlt_f32_e32 vcc, s83, v33
	s_nop 1
	v_cndmask_b32_e32 v33, v160, v34, vcc
	v_add_f32_e32 v33, 1.0, v33
	v_rcp_f32_e32 v33, v33
	s_nop 0
	v_fma_f32 v33, v33, -2.0, 1.0

.LBB0_1416:
	s_andn2_saveexec_b64 s[74:75], s[74:75]
	v_mul_f32_e32 v37, v36, v36
	v_fmamk_f32 v38, v37, 0xbbbac73d, v158
	v_fmaak_f32 v38, v37, v38, 0xbd5c1c4e
	v_fmaak_f32 v38, v37, v38, 0x3e088382
	v_fmaak_f32 v38, v37, v38, 0xbeaaaa99
	v_mul_f32_e64 v38, |v36|, v38
	v_fma_f32 v37, v37, v38, |v36|
	s_or_b64 exec, exec, s[74:75]
	v_add_f32_e64 v2, v2, 0
	v_add_f32_e64 v3, v3, 0
	s_nop 0
	v_add_f32_e64 v2, v2, v6
	v_add_f32_e64 v3, v3, v7
	s_nop 0
	v_add_f32_e64 v2, v2, v10
	v_add_f32_e64 v3, v3, v11
	s_waitcnt vmcnt(0)
	v_add_f32_e64 v2, v2, v14
	v_add_f32_e64 v3, v3, v15
	s_nop 0
	v_mul_f32_e32 v6, 0x3d372713, v2
	v_mul_f32_e32 v6, v2, v6
	v_fma_f32 v6, v2, v6, v2
	v_mul_f32_e32 v6, 0x3f4c422a, v6
	v_cmp_nlt_f32_e64 s[58:59], |v6|, s21
	s_and_saveexec_b64 s[74:75], s[58:59]
	s_xor_b64 s[74:75], exec, s[74:75]
	s_cbranch_execz .LBB0_1420
	v_add_f32_e64 v7, |v6|, |v6|
	v_mul_f32_e32 v10, 0x3fb8aa3b, v7
	v_rndne_f32_e32 v11, v10
	v_sub_f32_e32 v14, v10, v11
	v_fma_f32 v10, v7, s50, -v10
	v_fmac_f32_e32 v10, 0x32a5705f, v7
	v_add_f32_e32 v10, v14, v10
	v_cvt_i32_f32_e32 v11, v11
	v_exp_f32_e32 v10, v10
	v_cmp_ngt_f32_e32 vcc, s51, v7
	v_ldexp_f32 v10, v10, v11
	s_nop 0
	v_cndmask_b32_e32 v10, 0, v10, vcc
	v_cmp_nlt_f32_e32 vcc, s83, v7
	s_nop 1
	v_cndmask_b32_e32 v7, v160, v10, vcc
	v_add_f32_e32 v7, 1.0, v7
	v_rcp_f32_e32 v7, v7
	s_nop 0
	v_fma_f32 v7, v7, -2.0, 1.0

.LBB0_1435:
	s_or_b64 exec, exec, s[90:91]
	v_add_co_u32_e32 v2, vcc, 0x5000, v148
	v_mov_b32_e32 v37, 0
	s_nop 0
	v_addc_co_u32_e32 v3, vcc, 0, v149, vcc
	global_load_dwordx4 v[30:33], v[2:3], off
	v_mov_b32_e32 v36, 0
	v_mov_b32_e32 v35, 0
	v_mov_b32_e32 v34, 0
	s_and_saveexec_b64 s[90:91], s[10:11]
	s_cbranch_execz .LBB0_1469
	v_lshlrev_b64 v[2:3], 10, v[120:121]
	v_lshl_add_u64 v[14:15], v[128:129], 0, v[2:3]
	global_load_dwordx4 v[2:5], v[14:15], off offset:272
	global_load_dwordx4 v[34:37], v[14:15], off offset:256
	v_add_co_u32_e32 v8, vcc, 0x400000, v14
	v_lshl_add_u64 v[6:7], v[14:15], 0, s[46:47]
	s_nop 0
	v_addc_co_u32_e32 v9, vcc, 0, v15, vcc
	global_load_dwordx4 v[38:41], v[8:9], off offset:256
	s_nop 0
	global_load_dwordx4 v[6:9], v[6:7], off offset:16
	v_add_co_u32_e32 v12, vcc, 0x800000, v14
	s_waitcnt vmcnt(2)
	v_add_f32_e64 v10, v34, 0
	v_add_f32_e64 v11, v35, 0
	v_addc_co_u32_e32 v13, vcc, 0, v15, vcc
	s_waitcnt vmcnt(1)
	v_add_f32_e64 v16, v10, v38
	v_add_f32_e64 v17, v11, v39
	v_lshl_add_u64 v[10:11], v[14:15], 0, s[56:57]
	global_load_dwordx4 v[42:45], v[12:13], off offset:256
	s_nop 0
	global_load_dwordx4 v[10:13], v[10:11], off offset:16
	s_waitcnt vmcnt(1)
	v_add_f32_e64 v34, v16, v42
	v_add_f32_e64 v35, v17, v43
	v_lshl_add_u64 v[16:17], v[14:15], 0, s[60:61]
	v_add_co_u32_e32 v14, vcc, 0xc00000, v14
	s_nop 1
	v_addc_co_u32_e32 v15, vcc, 0, v15, vcc
	global_load_dwordx4 v[46:49], v[14:15], off offset:256
	s_nop 0
	global_load_dwordx4 v[14:17], v[16:17], off offset:16
	s_waitcnt vmcnt(1)
	v_add_f32_e64 v34, v34, v46
	v_add_f32_e64 v35, v35, v47
	s_nop 0
	v_mul_f32_e32 v38, 0x3d372713, v34
	v_mul_f32_e32 v38, v34, v38
	v_fma_f32 v38, v34, v38, v34
	v_mul_f32_e32 v38, 0x3f4c422a, v38
	v_cmp_nlt_f32_e64 s[58:59], |v38|, s21
	s_and_saveexec_b64 s[74:75], s[58:59]
	s_xor_b64 s[74:75], exec, s[74:75]
	s_cbranch_execz .LBB0_1438
	v_add_f32_e64 v39, |v38|, |v38|
	v_mul_f32_e32 v42, 0x3fb8aa3b, v39
	v_rndne_f32_e32 v43, v42
	v_sub_f32_e32 v46, v42, v43
	v_fma_f32 v42, v39, s50, -v42
	v_fmac_f32_e32 v42, 0x32a5705f, v39
	v_add_f32_e32 v42, v46, v42
	v_cvt_i32_f32_e32 v43, v43
	v_exp_f32_e32 v42, v42
	v_cmp_ngt_f32_e32 vcc, s51, v39
	v_ldexp_f32 v42, v42, v43
	s_nop 0
	v_cndmask_b32_e32 v42, 0, v42, vcc
	v_cmp_nlt_f32_e32 vcc, s83, v39
	s_nop 1
	v_cndmask_b32_e32 v39, v160, v42, vcc
	v_add_f32_e32 v39, 1.0, v39
	v_rcp_f32_e32 v39, v39
	s_nop 0
	v_fma_f32 v39, v39, -2.0, 1.0
.LBB0_1438:
	s_andn2_saveexec_b64 s[74:75], s[74:75]
	v_mul_f32_e32 v39, v38, v38
	v_fmamk_f32 v42, v39, 0xbbbac73d, v158
	v_fmaak_f32 v42, v39, v42, 0xbd5c1c4e
	v_fmaak_f32 v42, v39, v42, 0x3e088382
	v_fmaak_f32 v42, v39, v42, 0xbeaaaa99
	v_mul_f32_e64 v42, |v38|, v42
	v_fma_f32 v39, v39, v42, |v38|
	s_or_b64 exec, exec, s[74:75]
	v_add_f32_e64 v36, v36, 0
	v_add_f32_e64 v37, v37, 0
	s_nop 0
	v_add_f32_e64 v36, v36, v40
	v_add_f32_e64 v37, v37, v41
	v_mul_f32_e32 v40, 0x3d372713, v35
	v_mul_f32_e32 v40, v35, v40
	v_fma_f32 v40, v35, v40, v35
	v_add_f32_e64 v36, v36, v44
	v_add_f32_e64 v37, v37, v45
	v_mul_f32_e32 v40, 0x3f4c422a, v40
	v_add_f32_e64 v36, v36, v48
	v_add_f32_e64 v37, v37, v49
	v_cmp_nlt_f32_e64 s[58:59], |v40|, s21
	s_and_saveexec_b64 s[74:75], s[58:59]
	s_xor_b64 s[74:75], exec, s[74:75]
	s_cbranch_execz .LBB0_1442
	v_add_f32_e64 v41, |v40|, |v40|
	v_mul_f32_e32 v42, 0x3fb8aa3b, v41
	v_rndne_f32_e32 v43, v42
	v_sub_f32_e32 v44, v42, v43
	v_fma_f32 v42, v41, s50, -v42
	v_fmac_f32_e32 v42, 0x32a5705f, v41
	v_add_f32_e32 v42, v44, v42
	v_cvt_i32_f32_e32 v43, v43
	v_exp_f32_e32 v42, v42
	v_cmp_ngt_f32_e32 vcc, s51, v41
	v_ldexp_f32 v42, v42, v43
	s_nop 0
	v_cndmask_b32_e32 v42, 0, v42, vcc
	v_cmp_nlt_f32_e32 vcc, s83, v41
	s_nop 1
	v_cndmask_b32_e32 v41, v160, v42, vcc
	v_add_f32_e32 v41, 1.0, v41
	v_rcp_f32_e32 v41, v41
	s_nop 0
	v_fma_f32 v41, v41, -2.0, 1.0

.LBB0_1450:
	s_andn2_saveexec_b64 s[74:75], s[74:75]
	v_mul_f32_e32 v45, v44, v44
	v_fmamk_f32 v46, v45, 0xbbbac73d, v158
	v_fmaak_f32 v46, v45, v46, 0xbd5c1c4e
	v_fmaak_f32 v46, v45, v46, 0x3e088382
	v_fmaak_f32 v46, v45, v46, 0xbeaaaa99
	v_mul_f32_e64 v46, |v44|, v46
	v_fma_f32 v45, v45, v46, |v44|
	s_or_b64 exec, exec, s[74:75]
	v_add_f32_e64 v2, v2, 0
	v_add_f32_e64 v3, v3, 0
	s_nop 0
	v_add_f32_e64 v2, v2, v6
	v_add_f32_e64 v3, v3, v7
	s_nop 0
	v_add_f32_e64 v2, v2, v10
	v_add_f32_e64 v3, v3, v11
	s_waitcnt vmcnt(0)
	v_add_f32_e64 v2, v2, v14
	v_add_f32_e64 v3, v3, v15
	s_nop 0
	v_mul_f32_e32 v6, 0x3d372713, v2
	v_mul_f32_e32 v6, v2, v6
	v_fma_f32 v6, v2, v6, v2
	v_mul_f32_e32 v6, 0x3f4c422a, v6
	v_cmp_nlt_f32_e64 s[58:59], |v6|, s21
	s_and_saveexec_b64 s[74:75], s[58:59]
	s_xor_b64 s[74:75], exec, s[74:75]
	s_cbranch_execz .LBB0_1454
	v_add_f32_e64 v7, |v6|, |v6|
	v_mul_f32_e32 v10, 0x3fb8aa3b, v7
	v_rndne_f32_e32 v11, v10
	v_sub_f32_e32 v14, v10, v11
	v_fma_f32 v10, v7, s50, -v10
	v_fmac_f32_e32 v10, 0x32a5705f, v7
	v_add_f32_e32 v10, v14, v10
	v_cvt_i32_f32_e32 v11, v11
	v_exp_f32_e32 v10, v10
	v_cmp_ngt_f32_e32 vcc, s51, v7
	v_ldexp_f32 v10, v10, v11
	s_nop 0
	v_cndmask_b32_e32 v10, 0, v10, vcc
	v_cmp_nlt_f32_e32 vcc, s83, v7
	s_nop 1
	v_cndmask_b32_e32 v7, v160, v10, vcc
	v_add_f32_e32 v7, 1.0, v7
	v_rcp_f32_e32 v7, v7
	s_nop 0
	v_fma_f32 v7, v7, -2.0, 1.0

.LBB0_1469:
	s_or_b64 exec, exec, s[90:91]
	v_add_co_u32_e32 v2, vcc, 0x6000, v148
	v_mov_b32_e32 v45, 0
	s_nop 0
	v_addc_co_u32_e32 v3, vcc, 0, v149, vcc
	global_load_dwordx4 v[38:41], v[2:3], off
	v_mov_b32_e32 v44, 0
	v_mov_b32_e32 v43, 0
	v_mov_b32_e32 v42, 0
	s_and_saveexec_b64 s[90:91], s[12:13]
	s_cbranch_execz .LBB0_1503
	v_lshlrev_b64 v[2:3], 10, v[130:131]
	v_lshl_add_u64 v[14:15], v[128:129], 0, v[2:3]
	global_load_dwordx4 v[2:5], v[14:15], off offset:272
	global_load_dwordx4 v[42:45], v[14:15], off offset:256
	v_add_co_u32_e32 v8, vcc, 0x400000, v14
	v_lshl_add_u64 v[6:7], v[14:15], 0, s[46:47]
	s_nop 0
	v_addc_co_u32_e32 v9, vcc, 0, v15, vcc
	global_load_dwordx4 v[46:49], v[8:9], off offset:256
	s_nop 0
	global_load_dwordx4 v[6:9], v[6:7], off offset:16
	v_add_co_u32_e32 v12, vcc, 0x800000, v14
	s_waitcnt vmcnt(2)
	v_add_f32_e64 v10, v42, 0
	v_add_f32_e64 v11, v43, 0
	v_addc_co_u32_e32 v13, vcc, 0, v15, vcc
	s_waitcnt vmcnt(1)
	v_add_f32_e64 v16, v10, v46
	v_add_f32_e64 v17, v11, v47
	v_lshl_add_u64 v[10:11], v[14:15], 0, s[56:57]
	global_load_dwordx4 v[50:53], v[12:13], off offset:256
	s_nop 0
	global_load_dwordx4 v[10:13], v[10:11], off offset:16
	s_waitcnt vmcnt(1)
	v_add_f32_e64 v42, v16, v50
	v_add_f32_e64 v43, v17, v51
	v_lshl_add_u64 v[16:17], v[14:15], 0, s[60:61]
	v_add_co_u32_e32 v14, vcc, 0xc00000, v14
	s_nop 1
	v_addc_co_u32_e32 v15, vcc, 0, v15, vcc
	global_load_dwordx4 v[54:57], v[14:15], off offset:256
	s_nop 0
	global_load_dwordx4 v[14:17], v[16:17], off offset:16
	s_waitcnt vmcnt(1)
	v_add_f32_e64 v42, v42, v54
	v_add_f32_e64 v43, v43, v55
	s_nop 0
	v_mul_f32_e32 v46, 0x3d372713, v42
	v_mul_f32_e32 v46, v42, v46
	v_fma_f32 v46, v42, v46, v42
	v_mul_f32_e32 v46, 0x3f4c422a, v46
	v_cmp_nlt_f32_e64 s[58:59], |v46|, s21
	s_and_saveexec_b64 s[74:75], s[58:59]
	s_xor_b64 s[74:75], exec, s[74:75]
	s_cbranch_execz .LBB0_1472
	v_add_f32_e64 v47, |v46|, |v46|
	v_mul_f32_e32 v50, 0x3fb8aa3b, v47
	v_rndne_f32_e32 v51, v50
	v_sub_f32_e32 v54, v50, v51
	v_fma_f32 v50, v47, s50, -v50
	v_fmac_f32_e32 v50, 0x32a5705f, v47
	v_add_f32_e32 v50, v54, v50
	v_cvt_i32_f32_e32 v51, v51
	v_exp_f32_e32 v50, v50
	v_cmp_ngt_f32_e32 vcc, s51, v47
	v_ldexp_f32 v50, v50, v51
	s_nop 0
	v_cndmask_b32_e32 v50, 0, v50, vcc
	v_cmp_nlt_f32_e32 vcc, s83, v47
	s_nop 1
	v_cndmask_b32_e32 v47, v160, v50, vcc
	v_add_f32_e32 v47, 1.0, v47
	v_rcp_f32_e32 v47, v47
	s_nop 0
	v_fma_f32 v47, v47, -2.0, 1.0
.LBB0_1472:
	s_andn2_saveexec_b64 s[74:75], s[74:75]
	v_mul_f32_e32 v47, v46, v46
	v_fmamk_f32 v50, v47, 0xbbbac73d, v158
	v_fmaak_f32 v50, v47, v50, 0xbd5c1c4e
	v_fmaak_f32 v50, v47, v50, 0x3e088382
	v_fmaak_f32 v50, v47, v50, 0xbeaaaa99
	v_mul_f32_e64 v50, |v46|, v50
	v_fma_f32 v47, v47, v50, |v46|
	s_or_b64 exec, exec, s[74:75]
	v_add_f32_e64 v44, v44, 0
	v_add_f32_e64 v45, v45, 0
	s_nop 0
	v_add_f32_e64 v44, v44, v48
	v_add_f32_e64 v45, v45, v49
	v_mul_f32_e32 v48, 0x3d372713, v43
	v_mul_f32_e32 v48, v43, v48
	v_fma_f32 v48, v43, v48, v43
	v_add_f32_e64 v44, v44, v52
	v_add_f32_e64 v45, v45, v53
	v_mul_f32_e32 v48, 0x3f4c422a, v48
	v_add_f32_e64 v44, v44, v56
	v_add_f32_e64 v45, v45, v57
	v_cmp_nlt_f32_e64 s[58:59], |v48|, s21
	s_and_saveexec_b64 s[74:75], s[58:59]
	s_xor_b64 s[74:75], exec, s[74:75]
	s_cbranch_execz .LBB0_1476
	v_add_f32_e64 v49, |v48|, |v48|
	v_mul_f32_e32 v50, 0x3fb8aa3b, v49
	v_rndne_f32_e32 v51, v50
	v_sub_f32_e32 v52, v50, v51
	v_fma_f32 v50, v49, s50, -v50
	v_fmac_f32_e32 v50, 0x32a5705f, v49
	v_add_f32_e32 v50, v52, v50
	v_cvt_i32_f32_e32 v51, v51
	v_exp_f32_e32 v50, v50
	v_cmp_ngt_f32_e32 vcc, s51, v49
	v_ldexp_f32 v50, v50, v51
	s_nop 0
	v_cndmask_b32_e32 v50, 0, v50, vcc
	v_cmp_nlt_f32_e32 vcc, s83, v49
	s_nop 1
	v_cndmask_b32_e32 v49, v160, v50, vcc
	v_add_f32_e32 v49, 1.0, v49
	v_rcp_f32_e32 v49, v49
	s_nop 0
	v_fma_f32 v49, v49, -2.0, 1.0

.LBB0_1484:
	s_andn2_saveexec_b64 s[74:75], s[74:75]
	v_mul_f32_e32 v53, v52, v52
	v_fmamk_f32 v54, v53, 0xbbbac73d, v158
	v_fmaak_f32 v54, v53, v54, 0xbd5c1c4e
	v_fmaak_f32 v54, v53, v54, 0x3e088382
	v_fmaak_f32 v54, v53, v54, 0xbeaaaa99
	v_mul_f32_e64 v54, |v52|, v54
	v_fma_f32 v53, v53, v54, |v52|
	s_or_b64 exec, exec, s[74:75]
	v_add_f32_e64 v2, v2, 0
	v_add_f32_e64 v3, v3, 0
	s_nop 0
	v_add_f32_e64 v2, v2, v6
	v_add_f32_e64 v3, v3, v7
	s_nop 0
	v_add_f32_e64 v2, v2, v10
	v_add_f32_e64 v3, v3, v11
	s_waitcnt vmcnt(0)
	v_add_f32_e64 v2, v2, v14
	v_add_f32_e64 v3, v3, v15
	s_nop 0
	v_mul_f32_e32 v6, 0x3d372713, v2
	v_mul_f32_e32 v6, v2, v6
	v_fma_f32 v6, v2, v6, v2
	v_mul_f32_e32 v6, 0x3f4c422a, v6
	v_cmp_nlt_f32_e64 s[58:59], |v6|, s21
	s_and_saveexec_b64 s[74:75], s[58:59]
	s_xor_b64 s[74:75], exec, s[74:75]
	s_cbranch_execz .LBB0_1488
	v_add_f32_e64 v7, |v6|, |v6|
	v_mul_f32_e32 v10, 0x3fb8aa3b, v7
	v_rndne_f32_e32 v11, v10
	v_sub_f32_e32 v14, v10, v11
	v_fma_f32 v10, v7, s50, -v10
	v_fmac_f32_e32 v10, 0x32a5705f, v7
	v_add_f32_e32 v10, v14, v10
	v_cvt_i32_f32_e32 v11, v11
	v_exp_f32_e32 v10, v10
	v_cmp_ngt_f32_e32 vcc, s51, v7
	v_ldexp_f32 v10, v10, v11
	s_nop 0
	v_cndmask_b32_e32 v10, 0, v10, vcc
	v_cmp_nlt_f32_e32 vcc, s83, v7
	s_nop 1
	v_cndmask_b32_e32 v7, v160, v10, vcc
	v_add_f32_e32 v7, 1.0, v7
	v_rcp_f32_e32 v7, v7
	s_nop 0
	v_fma_f32 v7, v7, -2.0, 1.0

.LBB0_1503:
	s_or_b64 exec, exec, s[90:91]
	v_add_co_u32_e32 v2, vcc, 0x7000, v148
	v_mov_b32_e32 v85, 0
	s_nop 0
	v_addc_co_u32_e32 v3, vcc, 0, v149, vcc
	global_load_dwordx4 v[46:49], v[2:3], off
	s_waitcnt lgkmcnt(0)
	s_barrier
	ds_read_b128 v[2:5], v161 offset:18432
	ds_read_b128 v[10:13], v162
	ds_read_b128 v[6:9], v161 offset:23040
	ds_read_b128 v[14:17], v162 offset:4608
	v_mov_b32_e32 v84, 0
	v_mov_b32_e32 v83, 0
	v_mov_b32_e32 v82, 0
	ds_write_b128 v151, v[18:21] offset:36864
	s_waitcnt vmcnt(3)
	ds_write_b128 v151, v[22:25] offset:55296
	ds_write_b128 v152, v[26:29] offset:36864
	s_waitcnt vmcnt(2)
	ds_write_b128 v152, v[30:33] offset:55296
	ds_write_b128 v153, v[34:37] offset:36864
	s_waitcnt vmcnt(1)
	ds_write_b128 v153, v[38:41] offset:55296
	ds_write_b128 v154, v[42:45] offset:36864
	s_waitcnt vmcnt(0)
	ds_write_b128 v154, v[46:49] offset:55296
	s_and_saveexec_b64 s[90:91], s[6:7]
	s_cbranch_execz .LBB0_1537
	v_lshlrev_b64 v[18:19], 10, v[110:111]
	v_lshl_add_u64 v[30:31], v[128:129], 0, v[18:19]
	global_load_dwordx4 v[18:21], v[30:31], off offset:528
	global_load_dwordx4 v[32:35], v[30:31], off offset:512
	v_add_co_u32_e32 v24, vcc, 0x400000, v30
	v_lshl_add_u64 v[22:23], v[30:31], 0, s[62:63]
	s_nop 0
	v_addc_co_u32_e32 v25, vcc, 0, v31, vcc
	global_load_dwordx4 v[36:39], v[24:25], off offset:512
	s_nop 0
	global_load_dwordx4 v[22:25], v[22:23], off offset:16
	v_add_co_u32_e32 v28, vcc, 0x800000, v30
	s_waitcnt vmcnt(2)
	v_add_f32_e64 v26, v32, 0
	v_add_f32_e64 v27, v33, 0
	v_addc_co_u32_e32 v29, vcc, 0, v31, vcc
	s_waitcnt vmcnt(1)
	v_add_f32_e64 v32, v26, v36
	v_add_f32_e64 v33, v27, v37
	v_lshl_add_u64 v[26:27], v[30:31], 0, s[64:65]
	global_load_dwordx4 v[40:43], v[28:29], off offset:512
	s_nop 0
	global_load_dwordx4 v[26:29], v[26:27], off offset:16
	s_waitcnt vmcnt(1)
	v_add_f32_e64 v36, v32, v40
	v_add_f32_e64 v37, v33, v41
	v_lshl_add_u64 v[32:33], v[30:31], 0, s[66:67]
	v_add_co_u32_e32 v30, vcc, 0xc00000, v30
	s_nop 1
	v_addc_co_u32_e32 v31, vcc, 0, v31, vcc
	global_load_dwordx4 v[44:47], v[30:31], off offset:512
	s_nop 0
	global_load_dwordx4 v[30:33], v[32:33], off offset:16
	s_waitcnt vmcnt(1)
	v_add_f32_e64 v36, v36, v44
	v_add_f32_e64 v37, v37, v45
	s_nop 0
	v_mul_f32_e32 v40, 0x3d372713, v36
	v_mul_f32_e32 v40, v36, v40
	v_fma_f32 v40, v36, v40, v36
	v_mul_f32_e32 v40, 0x3f4c422a, v40
	v_cmp_nlt_f32_e64 s[58:59], |v40|, s21
	s_and_saveexec_b64 s[74:75], s[58:59]
	s_xor_b64 s[74:75], exec, s[74:75]
	s_cbranch_execz .LBB0_1506
	v_add_f32_e64 v41, |v40|, |v40|
	v_mul_f32_e32 v44, 0x3fb8aa3b, v41
	v_rndne_f32_e32 v45, v44
	v_sub_f32_e32 v48, v44, v45
	v_fma_f32 v44, v41, s50, -v44
	v_fmac_f32_e32 v44, 0x32a5705f, v41
	v_add_f32_e32 v44, v48, v44
	v_cvt_i32_f32_e32 v45, v45
	v_exp_f32_e32 v44, v44
	v_cmp_ngt_f32_e32 vcc, s51, v41
	v_ldexp_f32 v44, v44, v45
	s_nop 0
	v_cndmask_b32_e32 v44, 0, v44, vcc
	v_cmp_nlt_f32_e32 vcc, s83, v41
	s_nop 1
	v_cndmask_b32_e32 v41, v160, v44, vcc
	v_add_f32_e32 v41, 1.0, v41
	v_rcp_f32_e32 v41, v41
	s_nop 0
	v_fma_f32 v41, v41, -2.0, 1.0
.LBB0_1506:
	s_andn2_saveexec_b64 s[74:75], s[74:75]
	v_mul_f32_e32 v41, v40, v40
	v_fmamk_f32 v44, v41, 0xbbbac73d, v158
	v_fmaak_f32 v44, v41, v44, 0xbd5c1c4e
	v_fmaak_f32 v44, v41, v44, 0x3e088382
	v_fmaak_f32 v44, v41, v44, 0xbeaaaa99
	v_mul_f32_e64 v44, |v40|, v44
	v_fma_f32 v41, v41, v44, |v40|
	s_or_b64 exec, exec, s[74:75]
	v_add_f32_e64 v34, v34, 0
	v_add_f32_e64 v35, v35, 0
	s_nop 0
	v_add_f32_e64 v34, v34, v38
	v_add_f32_e64 v35, v35, v39
	v_mul_f32_e32 v38, 0x3d372713, v37
	v_mul_f32_e32 v38, v37, v38
	v_fma_f32 v38, v37, v38, v37
	v_add_f32_e64 v34, v34, v42
	v_add_f32_e64 v35, v35, v43
	v_mul_f32_e32 v38, 0x3f4c422a, v38
	v_add_f32_e64 v34, v34, v46
	v_add_f32_e64 v35, v35, v47
	v_cmp_nlt_f32_e64 s[58:59], |v38|, s21
	s_and_saveexec_b64 s[74:75], s[58:59]
	s_xor_b64 s[74:75], exec, s[74:75]
	s_cbranch_execz .LBB0_1510
	v_add_f32_e64 v39, |v38|, |v38|
	v_mul_f32_e32 v42, 0x3fb8aa3b, v39
	v_rndne_f32_e32 v43, v42
	v_sub_f32_e32 v44, v42, v43
	v_fma_f32 v42, v39, s50, -v42
	v_fmac_f32_e32 v42, 0x32a5705f, v39
	v_add_f32_e32 v42, v44, v42
	v_cvt_i32_f32_e32 v43, v43
	v_exp_f32_e32 v42, v42
	v_cmp_ngt_f32_e32 vcc, s51, v39
	v_ldexp_f32 v42, v42, v43
	s_nop 0
	v_cndmask_b32_e32 v42, 0, v42, vcc
	v_cmp_nlt_f32_e32 vcc, s83, v39
	s_nop 1
	v_cndmask_b32_e32 v39, v160, v42, vcc
	v_add_f32_e32 v39, 1.0, v39
	v_rcp_f32_e32 v39, v39
	s_nop 0
	v_fma_f32 v39, v39, -2.0, 1.0

.LBB0_1518:
	s_andn2_saveexec_b64 s[74:75], s[74:75]
	v_mul_f32_e32 v45, v44, v44
	v_fmamk_f32 v46, v45, 0xbbbac73d, v158
	v_fmaak_f32 v46, v45, v46, 0xbd5c1c4e
	v_fmaak_f32 v46, v45, v46, 0x3e088382
	v_fmaak_f32 v46, v45, v46, 0xbeaaaa99
	v_mul_f32_e64 v46, |v44|, v46
	v_fma_f32 v45, v45, v46, |v44|
	s_or_b64 exec, exec, s[74:75]
	v_add_f32_e64 v18, v18, 0
	v_add_f32_e64 v19, v19, 0
	s_nop 0
	v_add_f32_e64 v18, v18, v22
	v_add_f32_e64 v19, v19, v23
	s_nop 0
	v_add_f32_e64 v18, v18, v26
	v_add_f32_e64 v19, v19, v27
	s_waitcnt vmcnt(0)
	v_add_f32_e64 v18, v18, v30
	v_add_f32_e64 v19, v19, v31
	s_nop 0
	v_mul_f32_e32 v22, 0x3d372713, v18
	v_mul_f32_e32 v22, v18, v22
	v_fma_f32 v22, v18, v22, v18
	v_mul_f32_e32 v22, 0x3f4c422a, v22
	v_cmp_nlt_f32_e64 s[58:59], |v22|, s21
	s_and_saveexec_b64 s[74:75], s[58:59]
	s_xor_b64 s[74:75], exec, s[74:75]
	s_cbranch_execz .LBB0_1522
	v_add_f32_e64 v23, |v22|, |v22|
	v_mul_f32_e32 v26, 0x3fb8aa3b, v23
	v_rndne_f32_e32 v27, v26
	v_sub_f32_e32 v30, v26, v27
	v_fma_f32 v26, v23, s50, -v26
	v_fmac_f32_e32 v26, 0x32a5705f, v23
	v_add_f32_e32 v26, v30, v26
	v_cvt_i32_f32_e32 v27, v27
	v_exp_f32_e32 v26, v26
	v_cmp_ngt_f32_e32 vcc, s51, v23
	v_ldexp_f32 v26, v26, v27
	s_nop 0
	v_cndmask_b32_e32 v26, 0, v26, vcc
	v_cmp_nlt_f32_e32 vcc, s83, v23
	s_nop 1
	v_cndmask_b32_e32 v23, v160, v26, vcc
	v_add_f32_e32 v23, 1.0, v23
	v_rcp_f32_e32 v23, v23
	s_nop 0
	v_fma_f32 v23, v23, -2.0, 1.0
.LBB0_1522:
	s_andn2_saveexec_b64 s[74:75], s[74:75]
	v_mul_f32_e32 v23, v22, v22
	v_fmamk_f32 v26, v23, 0xbbbac73d, v158
	v_fmaak_f32 v26, v23, v26, 0xbd5c1c4e
	v_fmaak_f32 v26, v23, v26, 0x3e088382
	v_fmaak_f32 v26, v23, v26, 0xbeaaaa99
	v_mul_f32_e64 v26, |v22|, v26
	v_fma_f32 v23, v23, v26, |v22|
	s_or_b64 exec, exec, s[74:75]
	v_add_f32_e64 v20, v20, 0
	v_add_f32_e64 v21, v21, 0
	s_nop 0
	v_add_f32_e64 v20, v20, v24
	v_add_f32_e64 v21, v21, v25
	v_mul_f32_e32 v24, 0x3d372713, v19
	v_mul_f32_e32 v24, v19, v24
	v_fma_f32 v24, v19, v24, v19
	v_add_f32_e64 v20, v20, v28
	v_add_f32_e64 v21, v21, v29
	v_mul_f32_e32 v24, 0x3f4c422a, v24
	v_add_f32_e64 v20, v20, v32
	v_add_f32_e64 v21, v21, v33
	v_cmp_nlt_f32_e64 s[58:59], |v24|, s21
	s_and_saveexec_b64 s[74:75], s[58:59]
	s_xor_b64 s[74:75], exec, s[74:75]
	s_cbranch_execz .LBB0_1526
	v_add_f32_e64 v25, |v24|, |v24|
	v_mul_f32_e32 v26, 0x3fb8aa3b, v25
	v_rndne_f32_e32 v27, v26
	v_sub_f32_e32 v28, v26, v27
	v_fma_f32 v26, v25, s50, -v26
	v_fmac_f32_e32 v26, 0x32a5705f, v25
	v_add_f32_e32 v26, v28, v26
	v_cvt_i32_f32_e32 v27, v27
	v_exp_f32_e32 v26, v26
	v_cmp_ngt_f32_e32 vcc, s51, v25
	v_ldexp_f32 v26, v26, v27
	s_nop 0
	v_cndmask_b32_e32 v26, 0, v26, vcc
	v_cmp_nlt_f32_e32 vcc, s83, v25
	s_nop 1
	v_cndmask_b32_e32 v25, v160, v26, vcc
	v_add_f32_e32 v25, 1.0, v25
	v_rcp_f32_e32 v25, v25
	s_nop 0
	v_fma_f32 v25, v25, -2.0, 1.0

.LBB0_1537:
	s_or_b64 exec, exec, s[90:91]
	v_add_co_u32_e32 v18, vcc, 0x8000, v148
	v_mov_b32_e32 v93, 0
	s_nop 0
	v_addc_co_u32_e32 v19, vcc, 0, v149, vcc
	global_load_dwordx4 v[86:89], v[18:19], off
	v_mov_b32_e32 v92, 0
	v_mov_b32_e32 v91, 0
	v_mov_b32_e32 v90, 0
	s_and_saveexec_b64 s[90:91], s[8:9]
	s_cbranch_execz .LBB0_1571
	v_lshlrev_b64 v[18:19], 10, v[112:113]
	v_lshl_add_u64 v[30:31], v[128:129], 0, v[18:19]
	global_load_dwordx4 v[18:21], v[30:31], off offset:528
	global_load_dwordx4 v[32:35], v[30:31], off offset:512
	v_add_co_u32_e32 v24, vcc, 0x400000, v30
	v_lshl_add_u64 v[22:23], v[30:31], 0, s[62:63]
	s_nop 0
	v_addc_co_u32_e32 v25, vcc, 0, v31, vcc
	global_load_dwordx4 v[36:39], v[24:25], off offset:512
	s_nop 0
	global_load_dwordx4 v[22:25], v[22:23], off offset:16
	v_add_co_u32_e32 v28, vcc, 0x800000, v30
	s_waitcnt vmcnt(2)
	v_add_f32_e64 v26, v32, 0
	v_add_f32_e64 v27, v33, 0
	v_addc_co_u32_e32 v29, vcc, 0, v31, vcc
	s_waitcnt vmcnt(1)
	v_add_f32_e64 v32, v26, v36
	v_add_f32_e64 v33, v27, v37
	v_lshl_add_u64 v[26:27], v[30:31], 0, s[64:65]
	global_load_dwordx4 v[40:43], v[28:29], off offset:512
	s_nop 0
	global_load_dwordx4 v[26:29], v[26:27], off offset:16
	s_waitcnt vmcnt(1)
	v_add_f32_e64 v36, v32, v40
	v_add_f32_e64 v37, v33, v41
	v_lshl_add_u64 v[32:33], v[30:31], 0, s[66:67]
	v_add_co_u32_e32 v30, vcc, 0xc00000, v30
	s_nop 1
	v_addc_co_u32_e32 v31, vcc, 0, v31, vcc
	global_load_dwordx4 v[44:47], v[30:31], off offset:512
	s_nop 0
	global_load_dwordx4 v[30:33], v[32:33], off offset:16
	s_waitcnt vmcnt(1)
	v_add_f32_e64 v36, v36, v44
	v_add_f32_e64 v37, v37, v45
	s_nop 0
	v_mul_f32_e32 v40, 0x3d372713, v36
	v_mul_f32_e32 v40, v36, v40
	v_fma_f32 v40, v36, v40, v36
	v_mul_f32_e32 v40, 0x3f4c422a, v40
	v_cmp_nlt_f32_e64 s[58:59], |v40|, s21
	s_and_saveexec_b64 s[74:75], s[58:59]
	s_xor_b64 s[74:75], exec, s[74:75]
	s_cbranch_execz .LBB0_1540
	v_add_f32_e64 v41, |v40|, |v40|
	v_mul_f32_e32 v44, 0x3fb8aa3b, v41
	v_rndne_f32_e32 v45, v44
	v_sub_f32_e32 v48, v44, v45
	v_fma_f32 v44, v41, s50, -v44
	v_fmac_f32_e32 v44, 0x32a5705f, v41
	v_add_f32_e32 v44, v48, v44
	v_cvt_i32_f32_e32 v45, v45
	v_exp_f32_e32 v44, v44
	v_cmp_ngt_f32_e32 vcc, s51, v41
	v_ldexp_f32 v44, v44, v45
	s_nop 0
	v_cndmask_b32_e32 v44, 0, v44, vcc
	v_cmp_nlt_f32_e32 vcc, s83, v41
	s_nop 1
	v_cndmask_b32_e32 v41, v160, v44, vcc
	v_add_f32_e32 v41, 1.0, v41
	v_rcp_f32_e32 v41, v41
	s_nop 0
	v_fma_f32 v41, v41, -2.0, 1.0

.LBB0_1571:
	s_or_b64 exec, exec, s[90:91]
	v_add_co_u32_e32 v18, vcc, 0x9000, v148
	v_mov_b32_e32 v101, 0
	s_nop 0
	v_addc_co_u32_e32 v19, vcc, 0, v149, vcc
	global_load_dwordx4 v[94:97], v[18:19], off
	v_mov_b32_e32 v100, 0
	v_mov_b32_e32 v99, 0
	v_mov_b32_e32 v98, 0
	s_and_saveexec_b64 s[90:91], s[10:11]
	s_cbranch_execz .LBB0_1605
	v_lshlrev_b64 v[18:19], 10, v[120:121]
	v_lshl_add_u64 v[30:31], v[128:129], 0, v[18:19]
	global_load_dwordx4 v[18:21], v[30:31], off offset:528
	global_load_dwordx4 v[32:35], v[30:31], off offset:512
	v_add_co_u32_e32 v24, vcc, 0x400000, v30
	v_lshl_add_u64 v[22:23], v[30:31], 0, s[62:63]
	s_nop 0
	v_addc_co_u32_e32 v25, vcc, 0, v31, vcc
	global_load_dwordx4 v[36:39], v[24:25], off offset:512
	s_nop 0
	global_load_dwordx4 v[22:25], v[22:23], off offset:16
	v_add_co_u32_e32 v28, vcc, 0x800000, v30
	s_waitcnt vmcnt(2)
	v_add_f32_e64 v26, v32, 0
	v_add_f32_e64 v27, v33, 0
	v_addc_co_u32_e32 v29, vcc, 0, v31, vcc
	s_waitcnt vmcnt(1)
	v_add_f32_e64 v32, v26, v36
	v_add_f32_e64 v33, v27, v37
	v_lshl_add_u64 v[26:27], v[30:31], 0, s[64:65]
	global_load_dwordx4 v[40:43], v[28:29], off offset:512
	s_nop 0
	global_load_dwordx4 v[26:29], v[26:27], off offset:16
	s_waitcnt vmcnt(1)
	v_add_f32_e64 v36, v32, v40
	v_add_f32_e64 v37, v33, v41
	v_lshl_add_u64 v[32:33], v[30:31], 0, s[66:67]
	v_add_co_u32_e32 v30, vcc, 0xc00000, v30
	s_nop 1
	v_addc_co_u32_e32 v31, vcc, 0, v31, vcc
	global_load_dwordx4 v[44:47], v[30:31], off offset:512
	s_nop 0
	global_load_dwordx4 v[30:33], v[32:33], off offset:16
	s_waitcnt vmcnt(1)
	v_add_f32_e64 v36, v36, v44
	v_add_f32_e64 v37, v37, v45
	s_nop 0
	v_mul_f32_e32 v40, 0x3d372713, v36
	v_mul_f32_e32 v40, v36, v40
	v_fma_f32 v40, v36, v40, v36
	v_mul_f32_e32 v40, 0x3f4c422a, v40
	v_cmp_nlt_f32_e64 s[58:59], |v40|, s21
	s_and_saveexec_b64 s[74:75], s[58:59]
	s_xor_b64 s[74:75], exec, s[74:75]
	s_cbranch_execz .LBB0_1574
	v_add_f32_e64 v41, |v40|, |v40|
	v_mul_f32_e32 v44, 0x3fb8aa3b, v41
	v_rndne_f32_e32 v45, v44
	v_sub_f32_e32 v48, v44, v45
	v_fma_f32 v44, v41, s50, -v44
	v_fmac_f32_e32 v44, 0x32a5705f, v41
	v_add_f32_e32 v44, v48, v44
	v_cvt_i32_f32_e32 v45, v45
	v_exp_f32_e32 v44, v44
	v_cmp_ngt_f32_e32 vcc, s51, v41
	v_ldexp_f32 v44, v44, v45
	s_nop 0
	v_cndmask_b32_e32 v44, 0, v44, vcc
	v_cmp_nlt_f32_e32 vcc, s83, v41
	s_nop 1
	v_cndmask_b32_e32 v41, v160, v44, vcc
	v_add_f32_e32 v41, 1.0, v41
	v_rcp_f32_e32 v41, v41
	s_nop 0
	v_fma_f32 v41, v41, -2.0, 1.0

.LBB0_1605:
	s_or_b64 exec, exec, s[90:91]
	v_add_co_u32_e32 v18, vcc, 0xa000, v148
	v_mov_b32_e32 v109, 0
	s_nop 0
	v_addc_co_u32_e32 v19, vcc, 0, v149, vcc
	global_load_dwordx4 v[102:105], v[18:19], off
	v_mov_b32_e32 v108, 0
	v_mov_b32_e32 v107, 0
	v_mov_b32_e32 v106, 0
	s_and_saveexec_b64 s[90:91], s[12:13]
	s_cbranch_execz .LBB0_1639
	v_lshlrev_b64 v[18:19], 10, v[130:131]
	v_lshl_add_u64 v[30:31], v[128:129], 0, v[18:19]
	global_load_dwordx4 v[18:21], v[30:31], off offset:528
	global_load_dwordx4 v[32:35], v[30:31], off offset:512
	v_add_co_u32_e32 v24, vcc, 0x400000, v30
	v_lshl_add_u64 v[22:23], v[30:31], 0, s[62:63]
	s_nop 0
	v_addc_co_u32_e32 v25, vcc, 0, v31, vcc
	global_load_dwordx4 v[36:39], v[24:25], off offset:512
	s_nop 0
	global_load_dwordx4 v[22:25], v[22:23], off offset:16
	v_add_co_u32_e32 v28, vcc, 0x800000, v30
	s_waitcnt vmcnt(2)
	v_add_f32_e64 v26, v32, 0
	v_add_f32_e64 v27, v33, 0
	v_addc_co_u32_e32 v29, vcc, 0, v31, vcc
	s_waitcnt vmcnt(1)
	v_add_f32_e64 v32, v26, v36
	v_add_f32_e64 v33, v27, v37
	v_lshl_add_u64 v[26:27], v[30:31], 0, s[64:65]
	global_load_dwordx4 v[40:43], v[28:29], off offset:512
	s_nop 0
	global_load_dwordx4 v[26:29], v[26:27], off offset:16
	s_waitcnt vmcnt(1)
	v_add_f32_e64 v36, v32, v40
	v_add_f32_e64 v37, v33, v41
	v_lshl_add_u64 v[32:33], v[30:31], 0, s[66:67]
	v_add_co_u32_e32 v30, vcc, 0xc00000, v30
	s_nop 1
	v_addc_co_u32_e32 v31, vcc, 0, v31, vcc
	global_load_dwordx4 v[44:47], v[30:31], off offset:512
	s_nop 0
	global_load_dwordx4 v[30:33], v[32:33], off offset:16
	s_waitcnt vmcnt(1)
	v_add_f32_e64 v36, v36, v44
	v_add_f32_e64 v37, v37, v45
	s_nop 0
	v_mul_f32_e32 v40, 0x3d372713, v36
	v_mul_f32_e32 v40, v36, v40
	v_fma_f32 v40, v36, v40, v36
	v_mul_f32_e32 v40, 0x3f4c422a, v40
	v_cmp_nlt_f32_e64 s[58:59], |v40|, s21
	s_and_saveexec_b64 s[74:75], s[58:59]
	s_xor_b64 s[74:75], exec, s[74:75]
	s_cbranch_execz .LBB0_1608
	v_add_f32_e64 v41, |v40|, |v40|
	v_mul_f32_e32 v44, 0x3fb8aa3b, v41
	v_rndne_f32_e32 v45, v44
	v_sub_f32_e32 v48, v44, v45
	v_fma_f32 v44, v41, s50, -v44
	v_fmac_f32_e32 v44, 0x32a5705f, v41
	v_add_f32_e32 v44, v48, v44
	v_cvt_i32_f32_e32 v45, v45
	v_exp_f32_e32 v44, v44
	v_cmp_ngt_f32_e32 vcc, s51, v41
	v_ldexp_f32 v44, v44, v45
	s_nop 0
	v_cndmask_b32_e32 v44, 0, v44, vcc
	v_cmp_nlt_f32_e32 vcc, s83, v41
	s_nop 1
	v_cndmask_b32_e32 v41, v160, v44, vcc
	v_add_f32_e32 v41, 1.0, v41
	v_rcp_f32_e32 v41, v41
	s_nop 0
	v_fma_f32 v41, v41, -2.0, 1.0

.LBB0_1639:
	s_or_b64 exec, exec, s[90:91]
	v_add_co_u32_e32 v18, vcc, 0xb000, v148
	s_waitcnt lgkmcnt(10)
	v_mfma_f32_32x32x16_bf16 v[34:49], v[2:5], v[10:13], 0
	v_addc_co_u32_e32 v19, vcc, 0, v149, vcc
	global_load_dwordx4 v[114:117], v[18:19], off
	ds_read_b128 v[66:69], v156 offset:23072
	ds_read_b128 v[70:73], v157 offset:4640
	s_waitcnt lgkmcnt(11)
	v_mfma_f32_32x32x16_bf16 v[50:65], v[6:9], v[10:13], 0
	ds_read_b128 v[74:77], v156 offset:18464
	ds_read_b128 v[78:81], v156 offset:18496
	s_waitcnt lgkmcnt(12)
	v_mfma_f32_32x32x16_bf16 v[18:33], v[2:5], v[14:17], 0
	ds_read_b128 v[122:125], v157 offset:32
	ds_read_b128 v[132:135], v157 offset:64
	v_mfma_f32_32x32x16_bf16 v[2:17], v[6:9], v[14:17], 0
	ds_read_b128 v[168:171], v156 offset:23104
	ds_read_b128 v[172:175], v157 offset:4672
	s_waitcnt lgkmcnt(3)
	v_mfma_f32_32x32x16_bf16 v[34:49], v[74:77], v[122:125], v[34:49]
	ds_read_b128 v[176:179], v157 offset:96
	ds_read_b128 v[180:183], v156 offset:23136
	v_mfma_f32_32x32x16_bf16 v[50:65], v[66:69], v[122:125], v[50:65]
	ds_read_b128 v[122:125], v156 offset:18528
	ds_read_b128 v[184:187], v157 offset:4704
	s_waitcnt lgkmcnt(0)
	s_barrier
	v_mfma_f32_32x32x16_bf16 v[18:33], v[74:77], v[70:73], v[18:33]
	ds_read_b128 v[74:77], v161 offset:59904
	v_mfma_f32_32x32x16_bf16 v[2:17], v[66:69], v[70:73], v[2:17]
	ds_read_b128 v[66:69], v161 offset:55296
	ds_read_b128 v[70:73], v162 offset:36864
	v_mfma_f32_32x32x16_bf16 v[34:49], v[78:81], v[132:135], v[34:49]
	v_mfma_f32_32x32x16_bf16 v[50:65], v[168:171], v[132:135], v[50:65]
	v_mfma_f32_32x32x16_bf16 v[18:33], v[78:81], v[172:175], v[18:33]
	ds_read_b128 v[78:81], v162 offset:41472
	ds_write_b128 v151, v[82:85]
	v_mov_b32_e32 v85, 0
	v_mov_b32_e32 v84, 0
	v_mov_b32_e32 v83, 0
	v_mov_b32_e32 v82, 0
	v_mfma_f32_32x32x16_bf16 v[2:17], v[168:171], v[172:175], v[2:17]
	s_waitcnt vmcnt(3)
	ds_write_b128 v151, v[86:89] offset:18432
	ds_write_b128 v152, v[90:93]
	v_mfma_f32_32x32x16_bf16 v[34:49], v[122:125], v[176:179], v[34:49]
	s_waitcnt vmcnt(2)
	ds_write_b128 v152, v[94:97] offset:18432
	ds_write_b128 v153, v[98:101]
	v_mfma_f32_32x32x16_bf16 v[50:65], v[180:183], v[176:179], v[50:65]
	s_waitcnt vmcnt(1)
	ds_write_b128 v153, v[102:105] offset:18432
	ds_write_b128 v154, v[106:109]
	v_mfma_f32_32x32x16_bf16 v[18:33], v[122:125], v[184:187], v[18:33]
	s_waitcnt vmcnt(0)
	ds_write_b128 v154, v[114:117] offset:18432
	v_mfma_f32_32x32x16_bf16 v[2:17], v[180:183], v[184:187], v[2:17]
	s_and_saveexec_b64 s[90:91], s[6:7]
	s_cbranch_execz .LBB0_1673
	v_lshlrev_b64 v[82:83], 10, v[110:111]
	v_lshl_add_u64 v[94:95], v[128:129], 0, v[82:83]
	global_load_dwordx4 v[82:85], v[94:95], off offset:784
	global_load_dwordx4 v[96:99], v[94:95], off offset:768
	v_add_co_u32_e32 v88, vcc, 0x400000, v94
	v_lshl_add_u64 v[86:87], v[94:95], 0, s[68:69]
	s_nop 0
	v_addc_co_u32_e32 v89, vcc, 0, v95, vcc
	global_load_dwordx4 v[100:103], v[88:89], off offset:768
	s_nop 0
	global_load_dwordx4 v[86:89], v[86:87], off offset:16
	v_add_co_u32_e32 v92, vcc, 0x800000, v94
	s_waitcnt vmcnt(2)
	v_add_f32_e64 v90, v96, 0
	v_add_f32_e64 v91, v97, 0
	v_addc_co_u32_e32 v93, vcc, 0, v95, vcc
	s_waitcnt vmcnt(1)
	v_add_f32_e64 v96, v90, v100
	v_add_f32_e64 v97, v91, v101
	v_lshl_add_u64 v[90:91], v[94:95], 0, s[70:71]
	global_load_dwordx4 v[104:107], v[92:93], off offset:768
	s_nop 0
	global_load_dwordx4 v[90:93], v[90:91], off offset:16
	s_waitcnt vmcnt(1)
	v_add_f32_e64 v100, v96, v104
	v_add_f32_e64 v101, v97, v105
	v_lshl_add_u64 v[96:97], v[94:95], 0, s[72:73]
	v_add_co_u32_e32 v94, vcc, 0xc00000, v94
	s_nop 1
	v_addc_co_u32_e32 v95, vcc, 0, v95, vcc
	global_load_dwordx4 v[108:111], v[94:95], off offset:768
	s_nop 0
	global_load_dwordx4 v[94:97], v[96:97], off offset:16
	s_waitcnt vmcnt(1)
	v_add_f32_e64 v100, v100, v108
	v_add_f32_e64 v101, v101, v109
	s_nop 0
	v_mul_f32_e32 v104, 0x3d372713, v100
	v_mul_f32_e32 v104, v100, v104
	v_fma_f32 v104, v100, v104, v100
	v_mul_f32_e32 v104, 0x3f4c422a, v104
	v_cmp_nlt_f32_e64 s[6:7], |v104|, s21
	s_and_saveexec_b64 s[58:59], s[6:7]
	s_xor_b64 s[6:7], exec, s[58:59]
	s_cbranch_execz .LBB0_1642
	v_add_f32_e64 v105, |v104|, |v104|
	v_mul_f32_e32 v108, 0x3fb8aa3b, v105
	v_rndne_f32_e32 v109, v108
	v_sub_f32_e32 v114, v108, v109
	v_fma_f32 v108, v105, s50, -v108
	v_fmac_f32_e32 v108, 0x32a5705f, v105
	v_add_f32_e32 v108, v114, v108
	v_cvt_i32_f32_e32 v109, v109
	v_exp_f32_e32 v108, v108
	v_cmp_ngt_f32_e32 vcc, s51, v105
	v_ldexp_f32 v108, v108, v109
	s_nop 0
	v_cndmask_b32_e32 v108, 0, v108, vcc
	v_cmp_nlt_f32_e32 vcc, s83, v105
	s_nop 1
	v_cndmask_b32_e32 v105, v160, v108, vcc
	v_add_f32_e32 v105, 1.0, v105
	v_rcp_f32_e32 v105, v105
	s_nop 0
	v_fma_f32 v105, v105, -2.0, 1.0
.LBB0_1642:
	s_andn2_saveexec_b64 s[6:7], s[6:7]
	v_mul_f32_e32 v105, v104, v104
	v_fmamk_f32 v108, v105, 0xbbbac73d, v158
	v_fmaak_f32 v108, v105, v108, 0xbd5c1c4e
	v_fmaak_f32 v108, v105, v108, 0x3e088382
	v_fmaak_f32 v108, v105, v108, 0xbeaaaa99
	v_mul_f32_e64 v108, |v104|, v108
	v_fma_f32 v105, v105, v108, |v104|
	s_or_b64 exec, exec, s[6:7]
	v_add_f32_e64 v98, v98, 0
	v_add_f32_e64 v99, v99, 0
	s_nop 0
	v_add_f32_e64 v98, v98, v102
	v_add_f32_e64 v99, v99, v103
	v_mul_f32_e32 v102, 0x3d372713, v101
	v_mul_f32_e32 v102, v101, v102
	v_fma_f32 v102, v101, v102, v101
	v_add_f32_e64 v98, v98, v106
	v_add_f32_e64 v99, v99, v107
	v_mul_f32_e32 v102, 0x3f4c422a, v102
	v_add_f32_e64 v98, v98, v110
	v_add_f32_e64 v99, v99, v111
	v_cmp_nlt_f32_e64 s[6:7], |v102|, s21
	s_and_saveexec_b64 s[58:59], s[6:7]
	s_xor_b64 s[6:7], exec, s[58:59]
	s_cbranch_execz .LBB0_1646
	v_add_f32_e64 v103, |v102|, |v102|
	v_mul_f32_e32 v106, 0x3fb8aa3b, v103
	v_rndne_f32_e32 v107, v106
	v_sub_f32_e32 v108, v106, v107
	v_fma_f32 v106, v103, s50, -v106
	v_fmac_f32_e32 v106, 0x32a5705f, v103
	v_add_f32_e32 v106, v108, v106
	v_cvt_i32_f32_e32 v107, v107
	v_exp_f32_e32 v106, v106
	v_cmp_ngt_f32_e32 vcc, s51, v103
	v_ldexp_f32 v106, v106, v107
	s_nop 0
	v_cndmask_b32_e32 v106, 0, v106, vcc
	v_cmp_nlt_f32_e32 vcc, s83, v103
	s_nop 1
	v_cndmask_b32_e32 v103, v160, v106, vcc
	v_add_f32_e32 v103, 1.0, v103
	v_rcp_f32_e32 v103, v103
	s_nop 0
	v_fma_f32 v103, v103, -2.0, 1.0

.LBB0_1654:
	s_andn2_saveexec_b64 s[6:7], s[6:7]
	v_mul_f32_e32 v109, v108, v108
	v_fmamk_f32 v110, v109, 0xbbbac73d, v158
	v_fmaak_f32 v110, v109, v110, 0xbd5c1c4e
	v_fmaak_f32 v110, v109, v110, 0x3e088382
	v_fmaak_f32 v110, v109, v110, 0xbeaaaa99
	v_mul_f32_e64 v110, |v108|, v110
	v_fma_f32 v109, v109, v110, |v108|
	s_or_b64 exec, exec, s[6:7]
	v_add_f32_e64 v82, v82, 0
	v_add_f32_e64 v83, v83, 0
	s_nop 0
	v_add_f32_e64 v82, v82, v86
	v_add_f32_e64 v83, v83, v87
	s_nop 0
	v_add_f32_e64 v82, v82, v90
	v_add_f32_e64 v83, v83, v91
	s_waitcnt vmcnt(0)
	v_add_f32_e64 v86, v82, v94
	v_add_f32_e64 v87, v83, v95
	s_nop 0
	v_mul_f32_e32 v82, 0x3d372713, v86
	v_mul_f32_e32 v82, v86, v82
	v_fma_f32 v82, v86, v82, v86
	v_mul_f32_e32 v82, 0x3f4c422a, v82
	v_cmp_nlt_f32_e64 s[6:7], |v82|, s21
	s_and_saveexec_b64 s[58:59], s[6:7]
	s_xor_b64 s[6:7], exec, s[58:59]
	s_cbranch_execz .LBB0_1658
	v_add_f32_e64 v83, |v82|, |v82|
	v_mul_f32_e32 v90, 0x3fb8aa3b, v83
	v_rndne_f32_e32 v91, v90
	v_sub_f32_e32 v94, v90, v91
	v_fma_f32 v90, v83, s50, -v90
	v_fmac_f32_e32 v90, 0x32a5705f, v83
	v_add_f32_e32 v90, v94, v90
	v_cvt_i32_f32_e32 v91, v91
	v_exp_f32_e32 v90, v90
	v_cmp_ngt_f32_e32 vcc, s51, v83
	v_ldexp_f32 v90, v90, v91
	s_nop 0
	v_cndmask_b32_e32 v90, 0, v90, vcc
	v_cmp_nlt_f32_e32 vcc, s83, v83
	s_nop 1
	v_cndmask_b32_e32 v83, v160, v90, vcc
	v_add_f32_e32 v83, 1.0, v83
	v_rcp_f32_e32 v83, v83
	s_nop 0
	v_fma_f32 v83, v83, -2.0, 1.0
.LBB0_1658:
	s_andn2_saveexec_b64 s[6:7], s[6:7]
	v_mul_f32_e32 v83, v82, v82
	v_fmamk_f32 v90, v83, 0xbbbac73d, v158
	v_fmaak_f32 v90, v83, v90, 0xbd5c1c4e
	v_fmaak_f32 v90, v83, v90, 0x3e088382
	v_fmaak_f32 v90, v83, v90, 0xbeaaaa99
	v_mul_f32_e64 v90, |v82|, v90
	v_fma_f32 v83, v83, v90, |v82|
	s_or_b64 exec, exec, s[6:7]
	v_add_f32_e64 v84, v84, 0
	v_add_f32_e64 v85, v85, 0
	s_nop 0
	v_add_f32_e64 v84, v84, v88
	v_add_f32_e64 v85, v85, v89
	v_mul_f32_e32 v88, 0x3d372713, v87
	v_mul_f32_e32 v88, v87, v88
	v_fma_f32 v88, v87, v88, v87
	v_add_f32_e64 v84, v84, v92
	v_add_f32_e64 v85, v85, v93
	v_mul_f32_e32 v88, 0x3f4c422a, v88
	v_add_f32_e64 v84, v84, v96
	v_add_f32_e64 v85, v85, v97
	v_cmp_nlt_f32_e64 s[6:7], |v88|, s21
	s_and_saveexec_b64 s[58:59], s[6:7]
	s_xor_b64 s[6:7], exec, s[58:59]
	s_cbranch_execz .LBB0_1662
	v_add_f32_e64 v89, |v88|, |v88|
	v_mul_f32_e32 v90, 0x3fb8aa3b, v89
	v_rndne_f32_e32 v91, v90
	v_sub_f32_e32 v92, v90, v91
	v_fma_f32 v90, v89, s50, -v90
	v_fmac_f32_e32 v90, 0x32a5705f, v89
	v_add_f32_e32 v90, v92, v90
	v_cvt_i32_f32_e32 v91, v91
	v_exp_f32_e32 v90, v90
	v_cmp_ngt_f32_e32 vcc, s51, v89
	v_ldexp_f32 v90, v90, v91
	s_nop 0
	v_cndmask_b32_e32 v90, 0, v90, vcc
	v_cmp_nlt_f32_e32 vcc, s83, v89
	s_nop 1
	v_cndmask_b32_e32 v89, v160, v90, vcc
	v_add_f32_e32 v89, 1.0, v89
	v_rcp_f32_e32 v89, v89
	s_nop 0
	v_fma_f32 v89, v89, -2.0, 1.0

.LBB0_1673:
	s_or_b64 exec, exec, s[90:91]
	v_add_co_u32_e32 v86, vcc, 0xc000, v148
	v_mov_b32_e32 v93, 0
	s_nop 0
	v_addc_co_u32_e32 v87, vcc, 0, v149, vcc
	global_load_dwordx4 v[86:89], v[86:87], off
	v_mov_b32_e32 v92, 0
	v_mov_b32_e32 v91, 0
	v_mov_b32_e32 v90, 0
	s_and_saveexec_b64 s[6:7], s[8:9]
	s_cbranch_execz .LBB0_1707
	v_lshlrev_b64 v[90:91], 10, v[112:113]
	v_lshl_add_u64 v[102:103], v[128:129], 0, v[90:91]
	global_load_dwordx4 v[90:93], v[102:103], off offset:784
	global_load_dwordx4 v[104:107], v[102:103], off offset:768
	v_add_co_u32_e32 v96, vcc, 0x400000, v102
	v_lshl_add_u64 v[94:95], v[102:103], 0, s[68:69]
	s_nop 0
	v_addc_co_u32_e32 v97, vcc, 0, v103, vcc
	global_load_dwordx4 v[108:111], v[96:97], off offset:768
	s_nop 0
	global_load_dwordx4 v[94:97], v[94:95], off offset:16
	v_add_co_u32_e32 v100, vcc, 0x800000, v102
	s_waitcnt vmcnt(2)
	v_add_f32_e64 v98, v104, 0
	v_add_f32_e64 v99, v105, 0
	v_addc_co_u32_e32 v101, vcc, 0, v103, vcc
	s_waitcnt vmcnt(1)
	v_add_f32_e64 v104, v98, v108
	v_add_f32_e64 v105, v99, v109
	v_lshl_add_u64 v[98:99], v[102:103], 0, s[70:71]
	global_load_dwordx4 v[112:115], v[100:101], off offset:768
	s_nop 0
	global_load_dwordx4 v[98:101], v[98:99], off offset:16
	s_waitcnt vmcnt(1)
	v_add_f32_e64 v108, v104, v112
	v_add_f32_e64 v109, v105, v113
	v_lshl_add_u64 v[104:105], v[102:103], 0, s[72:73]
	v_add_co_u32_e32 v102, vcc, 0xc00000, v102
	s_nop 1
	v_addc_co_u32_e32 v103, vcc, 0, v103, vcc
	global_load_dwordx4 v[116:119], v[102:103], off offset:768
	s_nop 0
	global_load_dwordx4 v[102:105], v[104:105], off offset:16
	s_waitcnt vmcnt(1)
	v_add_f32_e64 v108, v108, v116
	v_add_f32_e64 v109, v109, v117
	s_nop 0
	v_mul_f32_e32 v112, 0x3d372713, v108
	v_mul_f32_e32 v112, v108, v112
	v_fma_f32 v112, v108, v112, v108
	v_mul_f32_e32 v112, 0x3f4c422a, v112
	v_cmp_nlt_f32_e64 s[8:9], |v112|, s21
	s_and_saveexec_b64 s[58:59], s[8:9]
	s_xor_b64 s[8:9], exec, s[58:59]
	s_cbranch_execz .LBB0_1676
	v_add_f32_e64 v113, |v112|, |v112|
	v_mul_f32_e32 v116, 0x3fb8aa3b, v113
	v_rndne_f32_e32 v117, v116
	v_sub_f32_e32 v122, v116, v117
	v_fma_f32 v116, v113, s50, -v116
	v_fmac_f32_e32 v116, 0x32a5705f, v113
	v_add_f32_e32 v116, v122, v116
	v_cvt_i32_f32_e32 v117, v117
	v_exp_f32_e32 v116, v116
	v_cmp_ngt_f32_e32 vcc, s51, v113
	v_ldexp_f32 v116, v116, v117
	s_nop 0
	v_cndmask_b32_e32 v116, 0, v116, vcc
	v_cmp_nlt_f32_e32 vcc, s83, v113
	s_nop 1
	v_cndmask_b32_e32 v113, v160, v116, vcc
	v_add_f32_e32 v113, 1.0, v113
	v_rcp_f32_e32 v113, v113
	s_nop 0
	v_fma_f32 v113, v113, -2.0, 1.0
.LBB0_1676:
	s_andn2_saveexec_b64 s[8:9], s[8:9]
	v_mul_f32_e32 v113, v112, v112
	v_fmamk_f32 v116, v113, 0xbbbac73d, v158
	v_fmaak_f32 v116, v113, v116, 0xbd5c1c4e
	v_fmaak_f32 v116, v113, v116, 0x3e088382
	v_fmaak_f32 v116, v113, v116, 0xbeaaaa99
	v_mul_f32_e64 v116, |v112|, v116
	v_fma_f32 v113, v113, v116, |v112|
	s_or_b64 exec, exec, s[8:9]
	v_add_f32_e64 v106, v106, 0
	v_add_f32_e64 v107, v107, 0
	s_nop 0
	v_add_f32_e64 v106, v106, v110
	v_add_f32_e64 v107, v107, v111
	v_mul_f32_e32 v110, 0x3d372713, v109
	v_mul_f32_e32 v110, v109, v110
	v_fma_f32 v110, v109, v110, v109
	v_add_f32_e64 v106, v106, v114
	v_add_f32_e64 v107, v107, v115
	v_mul_f32_e32 v110, 0x3f4c422a, v110
	v_add_f32_e64 v106, v106, v118
	v_add_f32_e64 v107, v107, v119
	v_cmp_nlt_f32_e64 s[8:9], |v110|, s21
	s_and_saveexec_b64 s[58:59], s[8:9]
	s_xor_b64 s[8:9], exec, s[58:59]
	s_cbranch_execz .LBB0_1680
	v_add_f32_e64 v111, |v110|, |v110|
	v_mul_f32_e32 v114, 0x3fb8aa3b, v111
	v_rndne_f32_e32 v115, v114
	v_sub_f32_e32 v116, v114, v115
	v_fma_f32 v114, v111, s50, -v114
	v_fmac_f32_e32 v114, 0x32a5705f, v111
	v_add_f32_e32 v114, v116, v114
	v_cvt_i32_f32_e32 v115, v115
	v_exp_f32_e32 v114, v114
	v_cmp_ngt_f32_e32 vcc, s51, v111
	v_ldexp_f32 v114, v114, v115
	s_nop 0
	v_cndmask_b32_e32 v114, 0, v114, vcc
	v_cmp_nlt_f32_e32 vcc, s83, v111
	s_nop 1
	v_cndmask_b32_e32 v111, v160, v114, vcc
	v_add_f32_e32 v111, 1.0, v111
	v_rcp_f32_e32 v111, v111
	s_nop 0
	v_fma_f32 v111, v111, -2.0, 1.0

.LBB0_1688:
	s_andn2_saveexec_b64 s[8:9], s[8:9]
	v_mul_f32_e32 v117, v116, v116
	v_fmamk_f32 v118, v117, 0xbbbac73d, v158
	v_fmaak_f32 v118, v117, v118, 0xbd5c1c4e
	v_fmaak_f32 v118, v117, v118, 0x3e088382
	v_fmaak_f32 v118, v117, v118, 0xbeaaaa99
	v_mul_f32_e64 v118, |v116|, v118
	v_fma_f32 v117, v117, v118, |v116|
	s_or_b64 exec, exec, s[8:9]
	v_add_f32_e64 v90, v90, 0
	v_add_f32_e64 v91, v91, 0
	s_nop 0
	v_add_f32_e64 v90, v90, v94
	v_add_f32_e64 v91, v91, v95
	s_nop 0
	v_add_f32_e64 v90, v90, v98
	v_add_f32_e64 v91, v91, v99
	s_waitcnt vmcnt(0)
	v_add_f32_e64 v94, v90, v102
	v_add_f32_e64 v95, v91, v103
	s_nop 0
	v_mul_f32_e32 v90, 0x3d372713, v94
	v_mul_f32_e32 v90, v94, v90
	v_fma_f32 v90, v94, v90, v94
	v_mul_f32_e32 v90, 0x3f4c422a, v90
	v_cmp_nlt_f32_e64 s[8:9], |v90|, s21
	s_and_saveexec_b64 s[58:59], s[8:9]
	s_xor_b64 s[8:9], exec, s[58:59]
	s_cbranch_execz .LBB0_1692
	v_add_f32_e64 v91, |v90|, |v90|
	v_mul_f32_e32 v98, 0x3fb8aa3b, v91
	v_rndne_f32_e32 v99, v98
	v_sub_f32_e32 v102, v98, v99
	v_fma_f32 v98, v91, s50, -v98
	v_fmac_f32_e32 v98, 0x32a5705f, v91
	v_add_f32_e32 v98, v102, v98
	v_cvt_i32_f32_e32 v99, v99
	v_exp_f32_e32 v98, v98
	v_cmp_ngt_f32_e32 vcc, s51, v91
	v_ldexp_f32 v98, v98, v99
	s_nop 0
	v_cndmask_b32_e32 v98, 0, v98, vcc
	v_cmp_nlt_f32_e32 vcc, s83, v91
	s_nop 1
	v_cndmask_b32_e32 v91, v160, v98, vcc
	v_add_f32_e32 v91, 1.0, v91
	v_rcp_f32_e32 v91, v91
	s_nop 0
	v_fma_f32 v91, v91, -2.0, 1.0
.LBB0_1692:
	s_andn2_saveexec_b64 s[8:9], s[8:9]
	v_mul_f32_e32 v91, v90, v90
	v_fmamk_f32 v98, v91, 0xbbbac73d, v158
	v_fmaak_f32 v98, v91, v98, 0xbd5c1c4e
	v_fmaak_f32 v98, v91, v98, 0x3e088382
	v_fmaak_f32 v98, v91, v98, 0xbeaaaa99
	v_mul_f32_e64 v98, |v90|, v98
	v_fma_f32 v91, v91, v98, |v90|
	s_or_b64 exec, exec, s[8:9]
	v_add_f32_e64 v92, v92, 0
	v_add_f32_e64 v93, v93, 0
	s_nop 0
	v_add_f32_e64 v92, v92, v96
	v_add_f32_e64 v93, v93, v97
	v_mul_f32_e32 v96, 0x3d372713, v95
	v_mul_f32_e32 v96, v95, v96
	v_fma_f32 v96, v95, v96, v95
	v_add_f32_e64 v92, v92, v100
	v_add_f32_e64 v93, v93, v101
	v_mul_f32_e32 v96, 0x3f4c422a, v96
	v_add_f32_e64 v92, v92, v104
	v_add_f32_e64 v93, v93, v105
	v_cmp_nlt_f32_e64 s[8:9], |v96|, s21
	s_and_saveexec_b64 s[58:59], s[8:9]
	s_xor_b64 s[8:9], exec, s[58:59]
	s_cbranch_execz .LBB0_1696
	v_add_f32_e64 v97, |v96|, |v96|
	v_mul_f32_e32 v98, 0x3fb8aa3b, v97
	v_rndne_f32_e32 v99, v98
	v_sub_f32_e32 v100, v98, v99
	v_fma_f32 v98, v97, s50, -v98
	v_fmac_f32_e32 v98, 0x32a5705f, v97
	v_add_f32_e32 v98, v100, v98
	v_cvt_i32_f32_e32 v99, v99
	v_exp_f32_e32 v98, v98
	v_cmp_ngt_f32_e32 vcc, s51, v97
	v_ldexp_f32 v98, v98, v99
	s_nop 0
	v_cndmask_b32_e32 v98, 0, v98, vcc
	v_cmp_nlt_f32_e32 vcc, s83, v97
	s_nop 1
	v_cndmask_b32_e32 v97, v160, v98, vcc
	v_add_f32_e32 v97, 1.0, v97
	v_rcp_f32_e32 v97, v97
	s_nop 0
	v_fma_f32 v97, v97, -2.0, 1.0

.LBB0_1707:
	s_or_b64 exec, exec, s[6:7]
	v_add_co_u32_e32 v94, vcc, 0xd000, v148
	v_mov_b32_e32 v101, 0
	s_nop 0
	v_addc_co_u32_e32 v95, vcc, 0, v149, vcc
	global_load_dwordx4 v[94:97], v[94:95], off
	v_mov_b32_e32 v100, 0
	v_mov_b32_e32 v99, 0
	v_mov_b32_e32 v98, 0
	s_and_saveexec_b64 s[6:7], s[10:11]
	s_cbranch_execz .LBB0_1741
	v_lshlrev_b64 v[98:99], 10, v[120:121]
	v_lshl_add_u64 v[110:111], v[128:129], 0, v[98:99]
	global_load_dwordx4 v[98:101], v[110:111], off offset:784
	global_load_dwordx4 v[112:115], v[110:111], off offset:768
	v_add_co_u32_e32 v104, vcc, 0x400000, v110
	v_lshl_add_u64 v[102:103], v[110:111], 0, s[68:69]
	s_nop 0
	v_addc_co_u32_e32 v105, vcc, 0, v111, vcc
	global_load_dwordx4 v[116:119], v[104:105], off offset:768
	s_nop 0
	global_load_dwordx4 v[102:105], v[102:103], off offset:16
	v_add_co_u32_e32 v108, vcc, 0x800000, v110
	s_waitcnt vmcnt(2)
	v_add_f32_e64 v106, v112, 0
	v_add_f32_e64 v107, v113, 0
	v_addc_co_u32_e32 v109, vcc, 0, v111, vcc
	s_waitcnt vmcnt(1)
	v_add_f32_e64 v112, v106, v116
	v_add_f32_e64 v113, v107, v117
	v_lshl_add_u64 v[106:107], v[110:111], 0, s[70:71]
	global_load_dwordx4 v[120:123], v[108:109], off offset:768
	s_nop 0
	global_load_dwordx4 v[106:109], v[106:107], off offset:16
	s_waitcnt vmcnt(1)
	v_add_f32_e64 v116, v112, v120
	v_add_f32_e64 v117, v113, v121
	v_lshl_add_u64 v[112:113], v[110:111], 0, s[72:73]
	v_add_co_u32_e32 v110, vcc, 0xc00000, v110
	s_nop 1
	v_addc_co_u32_e32 v111, vcc, 0, v111, vcc
	global_load_dwordx4 v[124:127], v[110:111], off offset:768
	s_nop 0
	global_load_dwordx4 v[110:113], v[112:113], off offset:16
	s_waitcnt vmcnt(1)
	v_add_f32_e64 v116, v116, v124
	v_add_f32_e64 v117, v117, v125
	s_nop 0
	v_mul_f32_e32 v120, 0x3d372713, v116
	v_mul_f32_e32 v120, v116, v120
	v_fma_f32 v120, v116, v120, v116
	v_mul_f32_e32 v120, 0x3f4c422a, v120
	v_cmp_nlt_f32_e64 s[8:9], |v120|, s21
	s_and_saveexec_b64 s[10:11], s[8:9]
	s_xor_b64 s[8:9], exec, s[10:11]
	s_cbranch_execz .LBB0_1710
	v_add_f32_e64 v121, |v120|, |v120|
	v_mul_f32_e32 v124, 0x3fb8aa3b, v121
	v_rndne_f32_e32 v125, v124
	v_sub_f32_e32 v132, v124, v125
	v_fma_f32 v124, v121, s50, -v124
	v_fmac_f32_e32 v124, 0x32a5705f, v121
	v_add_f32_e32 v124, v132, v124
	v_cvt_i32_f32_e32 v125, v125
	v_exp_f32_e32 v124, v124
	v_cmp_ngt_f32_e32 vcc, s51, v121
	v_ldexp_f32 v124, v124, v125
	s_nop 0
	v_cndmask_b32_e32 v124, 0, v124, vcc
	v_cmp_nlt_f32_e32 vcc, s83, v121
	s_nop 1
	v_cndmask_b32_e32 v121, v160, v124, vcc
	v_add_f32_e32 v121, 1.0, v121
	v_rcp_f32_e32 v121, v121
	s_nop 0
	v_fma_f32 v121, v121, -2.0, 1.0
.LBB0_1710:
	s_andn2_saveexec_b64 s[8:9], s[8:9]
	v_mul_f32_e32 v121, v120, v120
	v_fmamk_f32 v124, v121, 0xbbbac73d, v158
	v_fmaak_f32 v124, v121, v124, 0xbd5c1c4e
	v_fmaak_f32 v124, v121, v124, 0x3e088382
	v_fmaak_f32 v124, v121, v124, 0xbeaaaa99
	v_mul_f32_e64 v124, |v120|, v124
	v_fma_f32 v121, v121, v124, |v120|
	s_or_b64 exec, exec, s[8:9]
	v_add_f32_e64 v114, v114, 0
	v_add_f32_e64 v115, v115, 0
	s_nop 0
	v_add_f32_e64 v114, v114, v118
	v_add_f32_e64 v115, v115, v119
	v_mul_f32_e32 v118, 0x3d372713, v117
	v_mul_f32_e32 v118, v117, v118
	v_fma_f32 v118, v117, v118, v117
	v_add_f32_e64 v114, v114, v122
	v_add_f32_e64 v115, v115, v123
	v_mul_f32_e32 v118, 0x3f4c422a, v118
	v_add_f32_e64 v114, v114, v126
	v_add_f32_e64 v115, v115, v127
	v_cmp_nlt_f32_e64 s[8:9], |v118|, s21
	s_and_saveexec_b64 s[10:11], s[8:9]
	s_xor_b64 s[8:9], exec, s[10:11]
	s_cbranch_execz .LBB0_1714
	v_add_f32_e64 v119, |v118|, |v118|
	v_mul_f32_e32 v122, 0x3fb8aa3b, v119
	v_rndne_f32_e32 v123, v122
	v_sub_f32_e32 v124, v122, v123
	v_fma_f32 v122, v119, s50, -v122
	v_fmac_f32_e32 v122, 0x32a5705f, v119
	v_add_f32_e32 v122, v124, v122
	v_cvt_i32_f32_e32 v123, v123
	v_exp_f32_e32 v122, v122
	v_cmp_ngt_f32_e32 vcc, s51, v119
	v_ldexp_f32 v122, v122, v123
	s_nop 0
	v_cndmask_b32_e32 v122, 0, v122, vcc
	v_cmp_nlt_f32_e32 vcc, s83, v119
	s_nop 1
	v_cndmask_b32_e32 v119, v160, v122, vcc
	v_add_f32_e32 v119, 1.0, v119
	v_rcp_f32_e32 v119, v119
	s_nop 0
	v_fma_f32 v119, v119, -2.0, 1.0

.LBB0_1722:
	s_andn2_saveexec_b64 s[8:9], s[8:9]
	v_mul_f32_e32 v125, v124, v124
	v_fmamk_f32 v126, v125, 0xbbbac73d, v158
	v_fmaak_f32 v126, v125, v126, 0xbd5c1c4e
	v_fmaak_f32 v126, v125, v126, 0x3e088382
	v_fmaak_f32 v126, v125, v126, 0xbeaaaa99
	v_mul_f32_e64 v126, |v124|, v126
	v_fma_f32 v125, v125, v126, |v124|
	s_or_b64 exec, exec, s[8:9]
	v_add_f32_e64 v98, v98, 0
	v_add_f32_e64 v99, v99, 0
	s_nop 0
	v_add_f32_e64 v98, v98, v102
	v_add_f32_e64 v99, v99, v103
	s_nop 0
	v_add_f32_e64 v98, v98, v106
	v_add_f32_e64 v99, v99, v107
	s_waitcnt vmcnt(0)
	v_add_f32_e64 v102, v98, v110
	v_add_f32_e64 v103, v99, v111
	s_nop 0
	v_mul_f32_e32 v98, 0x3d372713, v102
	v_mul_f32_e32 v98, v102, v98
	v_fma_f32 v98, v102, v98, v102
	v_mul_f32_e32 v98, 0x3f4c422a, v98
	v_cmp_nlt_f32_e64 s[8:9], |v98|, s21
	s_and_saveexec_b64 s[10:11], s[8:9]
	s_xor_b64 s[8:9], exec, s[10:11]
	s_cbranch_execz .LBB0_1726
	v_add_f32_e64 v99, |v98|, |v98|
	v_mul_f32_e32 v106, 0x3fb8aa3b, v99
	v_rndne_f32_e32 v107, v106
	v_sub_f32_e32 v110, v106, v107
	v_fma_f32 v106, v99, s50, -v106
	v_fmac_f32_e32 v106, 0x32a5705f, v99
	v_add_f32_e32 v106, v110, v106
	v_cvt_i32_f32_e32 v107, v107
	v_exp_f32_e32 v106, v106
	v_cmp_ngt_f32_e32 vcc, s51, v99
	v_ldexp_f32 v106, v106, v107
	s_nop 0
	v_cndmask_b32_e32 v106, 0, v106, vcc
	v_cmp_nlt_f32_e32 vcc, s83, v99
	s_nop 1
	v_cndmask_b32_e32 v99, v160, v106, vcc
	v_add_f32_e32 v99, 1.0, v99
	v_rcp_f32_e32 v99, v99
	s_nop 0
	v_fma_f32 v99, v99, -2.0, 1.0
.LBB0_1726:
	s_andn2_saveexec_b64 s[8:9], s[8:9]
	v_mul_f32_e32 v99, v98, v98
	v_fmamk_f32 v106, v99, 0xbbbac73d, v158
	v_fmaak_f32 v106, v99, v106, 0xbd5c1c4e
	v_fmaak_f32 v106, v99, v106, 0x3e088382
	v_fmaak_f32 v106, v99, v106, 0xbeaaaa99
	v_mul_f32_e64 v106, |v98|, v106
	v_fma_f32 v99, v99, v106, |v98|
	s_or_b64 exec, exec, s[8:9]
	v_add_f32_e64 v100, v100, 0
	v_add_f32_e64 v101, v101, 0
	s_nop 0
	v_add_f32_e64 v100, v100, v104
	v_add_f32_e64 v101, v101, v105
	v_mul_f32_e32 v104, 0x3d372713, v103
	v_mul_f32_e32 v104, v103, v104
	v_fma_f32 v104, v103, v104, v103
	v_add_f32_e64 v100, v100, v108
	v_add_f32_e64 v101, v101, v109
	v_mul_f32_e32 v104, 0x3f4c422a, v104
	v_add_f32_e64 v100, v100, v112
	v_add_f32_e64 v101, v101, v113
	v_cmp_nlt_f32_e64 s[8:9], |v104|, s21
	s_and_saveexec_b64 s[10:11], s[8:9]
	s_xor_b64 s[8:9], exec, s[10:11]
	s_cbranch_execz .LBB0_1730
	v_add_f32_e64 v105, |v104|, |v104|
	v_mul_f32_e32 v106, 0x3fb8aa3b, v105
	v_rndne_f32_e32 v107, v106
	v_sub_f32_e32 v108, v106, v107
	v_fma_f32 v106, v105, s50, -v106
	v_fmac_f32_e32 v106, 0x32a5705f, v105
	v_add_f32_e32 v106, v108, v106
	v_cvt_i32_f32_e32 v107, v107
	v_exp_f32_e32 v106, v106
	v_cmp_ngt_f32_e32 vcc, s51, v105
	v_ldexp_f32 v106, v106, v107
	s_nop 0
	v_cndmask_b32_e32 v106, 0, v106, vcc
	v_cmp_nlt_f32_e32 vcc, s83, v105
	s_nop 1
	v_cndmask_b32_e32 v105, v160, v106, vcc
	v_add_f32_e32 v105, 1.0, v105
	v_rcp_f32_e32 v105, v105
	s_nop 0
	v_fma_f32 v105, v105, -2.0, 1.0

.LBB0_1741:
	s_or_b64 exec, exec, s[6:7]
	v_add_co_u32_e32 v102, vcc, 0xe000, v148
	v_mov_b32_e32 v109, 0
	s_nop 0
	v_addc_co_u32_e32 v103, vcc, 0, v149, vcc
	global_load_dwordx4 v[102:105], v[102:103], off
	v_mov_b32_e32 v108, 0
	v_mov_b32_e32 v107, 0
	v_mov_b32_e32 v106, 0
	s_and_saveexec_b64 s[6:7], s[12:13]
	s_cbranch_execz .LBB0_1775
	v_lshlrev_b64 v[106:107], 10, v[130:131]
	v_lshl_add_u64 v[118:119], v[128:129], 0, v[106:107]
	global_load_dwordx4 v[106:109], v[118:119], off offset:784
	global_load_dwordx4 v[120:123], v[118:119], off offset:768
	v_add_co_u32_e32 v112, vcc, 0x400000, v118
	v_lshl_add_u64 v[110:111], v[118:119], 0, s[68:69]
	s_nop 0
	v_addc_co_u32_e32 v113, vcc, 0, v119, vcc
	global_load_dwordx4 v[124:127], v[112:113], off offset:768
	s_nop 0
	global_load_dwordx4 v[110:113], v[110:111], off offset:16
	v_add_co_u32_e32 v116, vcc, 0x800000, v118
	s_waitcnt vmcnt(2)
	v_add_f32_e64 v114, v120, 0
	v_add_f32_e64 v115, v121, 0
	v_addc_co_u32_e32 v117, vcc, 0, v119, vcc
	s_waitcnt vmcnt(1)
	v_add_f32_e64 v120, v114, v124
	v_add_f32_e64 v121, v115, v125
	v_lshl_add_u64 v[114:115], v[118:119], 0, s[70:71]
	global_load_dwordx4 v[128:131], v[116:117], off offset:768
	s_nop 0
	global_load_dwordx4 v[114:117], v[114:115], off offset:16
	s_waitcnt vmcnt(1)
	v_add_f32_e64 v124, v120, v128
	v_add_f32_e64 v125, v121, v129
	v_lshl_add_u64 v[120:121], v[118:119], 0, s[72:73]
	v_add_co_u32_e32 v118, vcc, 0xc00000, v118
	s_nop 1
	v_addc_co_u32_e32 v119, vcc, 0, v119, vcc
	global_load_dwordx4 v[132:135], v[118:119], off offset:768
	s_nop 0
	global_load_dwordx4 v[118:121], v[120:121], off offset:16
	s_waitcnt vmcnt(1)
	v_add_f32_e64 v124, v124, v132
	v_add_f32_e64 v125, v125, v133
	s_nop 0
	v_mul_f32_e32 v128, 0x3d372713, v124
	v_mul_f32_e32 v128, v124, v128
	v_fma_f32 v128, v124, v128, v124
	v_mul_f32_e32 v128, 0x3f4c422a, v128
	v_cmp_nlt_f32_e64 s[8:9], |v128|, s21
	s_and_saveexec_b64 s[10:11], s[8:9]
	s_xor_b64 s[8:9], exec, s[10:11]
	s_cbranch_execz .LBB0_1744
	v_add_f32_e64 v129, |v128|, |v128|
	v_mul_f32_e32 v132, 0x3fb8aa3b, v129
	v_rndne_f32_e32 v133, v132
	v_sub_f32_e32 v168, v132, v133
	v_fma_f32 v132, v129, s50, -v132
	v_fmac_f32_e32 v132, 0x32a5705f, v129
	v_add_f32_e32 v132, v168, v132
	v_cvt_i32_f32_e32 v133, v133
	v_exp_f32_e32 v132, v132
	v_cmp_ngt_f32_e32 vcc, s51, v129
	v_ldexp_f32 v132, v132, v133
	s_nop 0
	v_cndmask_b32_e32 v132, 0, v132, vcc
	v_cmp_nlt_f32_e32 vcc, s83, v129
	s_nop 1
	v_cndmask_b32_e32 v129, v160, v132, vcc
	v_add_f32_e32 v129, 1.0, v129
	v_rcp_f32_e32 v129, v129
	s_nop 0
	v_fma_f32 v129, v129, -2.0, 1.0
.LBB0_1744:
	s_andn2_saveexec_b64 s[8:9], s[8:9]
	v_mul_f32_e32 v129, v128, v128
	v_fmamk_f32 v132, v129, 0xbbbac73d, v158
	v_fmaak_f32 v132, v129, v132, 0xbd5c1c4e
	v_fmaak_f32 v132, v129, v132, 0x3e088382
	v_fmaak_f32 v132, v129, v132, 0xbeaaaa99
	v_mul_f32_e64 v132, |v128|, v132
	v_fma_f32 v129, v129, v132, |v128|
	s_or_b64 exec, exec, s[8:9]
	v_add_f32_e64 v122, v122, 0
	v_add_f32_e64 v123, v123, 0
	s_nop 0
	v_add_f32_e64 v122, v122, v126
	v_add_f32_e64 v123, v123, v127
	v_mul_f32_e32 v126, 0x3d372713, v125
	v_mul_f32_e32 v126, v125, v126
	v_fma_f32 v126, v125, v126, v125
	v_add_f32_e64 v122, v122, v130
	v_add_f32_e64 v123, v123, v131
	v_mul_f32_e32 v126, 0x3f4c422a, v126
	v_add_f32_e64 v122, v122, v134
	v_add_f32_e64 v123, v123, v135
	v_cmp_nlt_f32_e64 s[8:9], |v126|, s21
	s_and_saveexec_b64 s[10:11], s[8:9]
	s_xor_b64 s[8:9], exec, s[10:11]
	s_cbranch_execz .LBB0_1748
	v_add_f32_e64 v127, |v126|, |v126|
	v_mul_f32_e32 v130, 0x3fb8aa3b, v127
	v_rndne_f32_e32 v131, v130
	v_sub_f32_e32 v132, v130, v131
	v_fma_f32 v130, v127, s50, -v130
	v_fmac_f32_e32 v130, 0x32a5705f, v127
	v_add_f32_e32 v130, v132, v130
	v_cvt_i32_f32_e32 v131, v131
	v_exp_f32_e32 v130, v130
	v_cmp_ngt_f32_e32 vcc, s51, v127
	v_ldexp_f32 v130, v130, v131
	s_nop 0
	v_cndmask_b32_e32 v130, 0, v130, vcc
	v_cmp_nlt_f32_e32 vcc, s83, v127
	s_nop 1
	v_cndmask_b32_e32 v127, v160, v130, vcc
	v_add_f32_e32 v127, 1.0, v127
	v_rcp_f32_e32 v127, v127
	s_nop 0
	v_fma_f32 v127, v127, -2.0, 1.0

.LBB0_1756:
	s_andn2_saveexec_b64 s[8:9], s[8:9]
	v_mul_f32_e32 v133, v132, v132
	v_fmamk_f32 v134, v133, 0xbbbac73d, v158
	v_fmaak_f32 v134, v133, v134, 0xbd5c1c4e
	v_fmaak_f32 v134, v133, v134, 0x3e088382
	v_fmaak_f32 v134, v133, v134, 0xbeaaaa99
	v_mul_f32_e64 v134, |v132|, v134
	v_fma_f32 v133, v133, v134, |v132|
	s_or_b64 exec, exec, s[8:9]
	v_add_f32_e64 v106, v106, 0
	v_add_f32_e64 v107, v107, 0
	s_nop 0
	v_add_f32_e64 v106, v106, v110
	v_add_f32_e64 v107, v107, v111
	s_nop 0
	v_add_f32_e64 v106, v106, v114
	v_add_f32_e64 v107, v107, v115
	s_waitcnt vmcnt(0)
	v_add_f32_e64 v110, v106, v118
	v_add_f32_e64 v111, v107, v119
	s_nop 0
	v_mul_f32_e32 v106, 0x3d372713, v110
	v_mul_f32_e32 v106, v110, v106
	v_fma_f32 v106, v110, v106, v110
	v_mul_f32_e32 v106, 0x3f4c422a, v106
	v_cmp_nlt_f32_e64 s[8:9], |v106|, s21
	s_and_saveexec_b64 s[10:11], s[8:9]
	s_xor_b64 s[8:9], exec, s[10:11]
	s_cbranch_execz .LBB0_1760
	v_add_f32_e64 v107, |v106|, |v106|
	v_mul_f32_e32 v114, 0x3fb8aa3b, v107
	v_rndne_f32_e32 v115, v114
	v_sub_f32_e32 v118, v114, v115
	v_fma_f32 v114, v107, s50, -v114
	v_fmac_f32_e32 v114, 0x32a5705f, v107
	v_add_f32_e32 v114, v118, v114
	v_cvt_i32_f32_e32 v115, v115
	v_exp_f32_e32 v114, v114
	v_cmp_ngt_f32_e32 vcc, s51, v107
	v_ldexp_f32 v114, v114, v115
	s_nop 0
	v_cndmask_b32_e32 v114, 0, v114, vcc
	v_cmp_nlt_f32_e32 vcc, s83, v107
	s_nop 1
	v_cndmask_b32_e32 v107, v160, v114, vcc
	v_add_f32_e32 v107, 1.0, v107
	v_rcp_f32_e32 v107, v107
	s_nop 0
	v_fma_f32 v107, v107, -2.0, 1.0
.LBB0_1760:
	s_andn2_saveexec_b64 s[8:9], s[8:9]
	v_mul_f32_e32 v107, v106, v106
	v_fmamk_f32 v114, v107, 0xbbbac73d, v158
	v_fmaak_f32 v114, v107, v114, 0xbd5c1c4e
	v_fmaak_f32 v114, v107, v114, 0x3e088382
	v_fmaak_f32 v114, v107, v114, 0xbeaaaa99
	v_mul_f32_e64 v114, |v106|, v114
	v_fma_f32 v107, v107, v114, |v106|
	s_or_b64 exec, exec, s[8:9]
	v_add_f32_e64 v108, v108, 0
	v_add_f32_e64 v109, v109, 0
	s_nop 0
	v_add_f32_e64 v108, v108, v112
	v_add_f32_e64 v109, v109, v113
	v_mul_f32_e32 v112, 0x3d372713, v111
	v_mul_f32_e32 v112, v111, v112
	v_fma_f32 v112, v111, v112, v111
	v_add_f32_e64 v108, v108, v116
	v_add_f32_e64 v109, v109, v117
	v_mul_f32_e32 v112, 0x3f4c422a, v112
	v_add_f32_e64 v108, v108, v120
	v_add_f32_e64 v109, v109, v121
	v_cmp_nlt_f32_e64 s[8:9], |v112|, s21
	s_and_saveexec_b64 s[10:11], s[8:9]
	s_xor_b64 s[8:9], exec, s[10:11]
	s_cbranch_execz .LBB0_1764
	v_add_f32_e64 v113, |v112|, |v112|
	v_mul_f32_e32 v114, 0x3fb8aa3b, v113
	v_rndne_f32_e32 v115, v114
	v_sub_f32_e32 v116, v114, v115
	v_fma_f32 v114, v113, s50, -v114
	v_fmac_f32_e32 v114, 0x32a5705f, v113
	v_add_f32_e32 v114, v116, v114
	v_cvt_i32_f32_e32 v115, v115
	v_exp_f32_e32 v114, v114
	v_cmp_ngt_f32_e32 vcc, s51, v113
	v_ldexp_f32 v114, v114, v115
	s_nop 0
	v_cndmask_b32_e32 v114, 0, v114, vcc
	v_cmp_nlt_f32_e32 vcc, s83, v113
	s_nop 1
	v_cndmask_b32_e32 v113, v160, v114, vcc
	v_add_f32_e32 v113, 1.0, v113
	v_rcp_f32_e32 v113, v113
	s_nop 0
	v_fma_f32 v113, v113, -2.0, 1.0

.LBB0_1779:
	s_andn2_b64 vcc, exec, s[6:7]
	s_cbranch_vccnz .LBB0_1813
	v_mul_f32_e32 v76, v35, v35
	v_fmac_f32_e32 v76, v34, v34
	v_fmac_f32_e32 v76, v36, v36
	v_fmac_f32_e32 v76, v37, v37
	v_fmac_f32_e32 v76, v38, v38
	v_fmac_f32_e32 v76, v39, v39
	v_fmac_f32_e32 v76, v40, v40
	v_fmac_f32_e32 v76, v41, v41
	v_fmac_f32_e32 v76, v42, v42
	v_fmac_f32_e32 v76, v43, v43
	v_fmac_f32_e32 v76, v44, v44
	v_fmac_f32_e32 v76, v45, v45
	v_fmac_f32_e32 v76, v46, v46
	v_fmac_f32_e32 v76, v47, v47
	v_fmac_f32_e32 v76, v48, v48
	v_fmac_f32_e32 v76, v49, v49
	v_fmac_f32_e32 v76, v50, v50
	v_fmac_f32_e32 v76, v51, v51
	v_fmac_f32_e32 v76, v52, v52
	v_fmac_f32_e32 v76, v53, v53
	v_fmac_f32_e32 v76, v54, v54
	v_fmac_f32_e32 v76, v55, v55
	v_mul_f32_e64 v74, v56, v56
	v_mul_f32_e64 v75, v57, v57
	v_mul_f32_e64 v72, v58, v58
	v_mul_f32_e64 v73, v59, v59
	v_add_f32_e32 v74, v74, v76
	v_add_f32_e32 v74, v75, v74
	v_lshlrev_b32_e32 v66, 12, v100
	v_add_f32_e32 v72, v72, v74
	v_and_b32_e32 v66, 0xffffe000, v66
	v_mul_f32_e64 v70, v60, v60
	v_mul_f32_e64 v71, v61, v61
	v_add_f32_e32 v72, v73, v72
	v_lshl_add_u32 v66, v98, 4, v66
	v_add_f32_e32 v70, v70, v72
	v_ashrrev_i32_e32 v67, 31, v66
	v_mul_f32_e64 v68, v62, v62
	v_mul_f32_e64 v69, v63, v63
	v_add_f32_e32 v70, v71, v70
	v_lshl_add_u64 v[66:67], v[66:67], 2, s[54:55]
	v_add_f32_e32 v68, v68, v70
	global_load_dword v99, v[66:67], off offset:124
	v_mul_f32_e64 v66, v64, v64
	v_mul_f32_e64 v67, v65, v65
	v_add_f32_e32 v68, v69, v68
	v_add_f32_e32 v66, v66, v68
	v_add_f32_e32 v111, v67, v66
	v_and_b32_e32 v67, 64, v163
	v_xor_b32_e32 v66, 32, v163
	v_add_u32_e32 v67, 64, v67
	v_cmp_lt_i32_e32 vcc, v66, v67
	s_waitcnt vmcnt(0)
	v_cvt_f32_i32_e32 v99, v99
	v_cndmask_b32_e32 v66, v163, v66, vcc
	v_lshlrev_b32_e32 v66, 2, v66
	ds_bpermute_b32 v112, v66, v111
	global_load_dwordx4 v[94:97], v[146:147], off
	global_load_dwordx4 v[90:93], v[146:147], off offset:32
	global_load_dwordx4 v[86:89], v[146:147], off offset:64
	global_load_dwordx4 v[82:85], v[146:147], off offset:96
	global_load_dwordx4 v[78:81], v[146:147], off offset:128
	global_load_dwordx4 v[74:77], v[146:147], off offset:160
	global_load_dwordx4 v[70:73], v[146:147], off offset:192
	global_load_dwordx4 v[66:69], v[146:147], off offset:224
	global_load_dword v101, v[144:145], off
	s_waitcnt vmcnt(0)
	v_mul_f32_e32 v113, v101, v99
	v_and_b32_e32 v114, 0x7fffffff, v113
	v_lshrrev_b32_e32 v101, 23, v114
	v_and_b32_e32 v102, 0x7fffff, v114
	v_cmp_nlt_f32_e64 s[74:75], |v113|, s96
	v_add_u32_e32 v103, 0xffffff88, v101
	v_or_b32_e32 v101, 0x800000, v102
	s_and_saveexec_b64 s[6:7], s[74:75]
	s_xor_b64 s[78:79], exec, s[6:7]
	s_cbranch_execz .LBB0_1782
	v_cmp_lt_u32_e32 vcc, 63, v103
	v_mov_b32_e32 v107, v137
	v_mov_b32_e32 v109, v137
	v_cndmask_b32_e32 v102, 0, v164, vcc
	v_add_u32_e32 v102, v102, v103
	v_cmp_lt_u32_e64 s[6:7], 31, v102
	v_mov_b32_e32 v117, v137
	v_mov_b32_e32 v119, v137
	v_cndmask_b32_e64 v104, 0, v165, s[6:7]
	v_add_u32_e32 v102, v104, v102
	v_cmp_lt_u32_e64 s[8:9], 31, v102
	v_mov_b32_e32 v121, v137
	v_mov_b32_e32 v123, v137
	v_cndmask_b32_e64 v104, 0, v165, s[8:9]
	v_add_u32_e32 v102, v104, v102
	v_mad_u64_u32 v[104:105], s[10:11], v101, s97, 0
	v_mov_b32_e32 v106, v105
	v_mad_u64_u32 v[106:107], s[10:11], v101, s3, v[106:107]
	v_mov_b32_e32 v108, v107
	v_mad_u64_u32 v[108:109], s[10:11], v101, s81, v[108:109]
	v_mov_b32_e32 v116, v109
	v_mad_u64_u32 v[116:117], s[10:11], v101, s14, v[116:117]
	v_mov_b32_e32 v118, v117
	v_mad_u64_u32 v[118:119], s[10:11], v101, s15, v[118:119]
	v_mov_b32_e32 v120, v119
	v_mad_u64_u32 v[120:121], s[10:11], v101, s94, v[120:121]
	v_mov_b32_e32 v122, v121
	v_mad_u64_u32 v[122:123], s[10:11], v101, s95, v[122:123]
	v_cndmask_b32_e32 v105, v120, v116, vcc
	v_cndmask_b32_e32 v107, v122, v118, vcc
	v_cndmask_b32_e32 v115, v123, v120, vcc
	v_cndmask_b32_e64 v109, v107, v105, s[6:7]
	v_cndmask_b32_e64 v107, v115, v107, s[6:7]
	v_cndmask_b32_e32 v115, v118, v108, vcc
	v_cndmask_b32_e64 v105, v105, v115, s[6:7]
	v_sub_u32_e32 v117, 32, v102
	v_cmp_eq_u32_e64 s[10:11], 0, v102
	v_cndmask_b32_e32 v102, v116, v106, vcc
	v_cndmask_b32_e64 v107, v107, v109, s[8:9]
	v_cndmask_b32_e64 v109, v109, v105, s[8:9]
	v_cndmask_b32_e64 v106, v115, v102, s[6:7]
	v_alignbit_b32 v118, v107, v109, v117
	v_cndmask_b32_e64 v105, v105, v106, s[8:9]
	v_cndmask_b32_e64 v107, v118, v107, s[10:11]
	v_alignbit_b32 v115, v109, v105, v117
	v_cndmask_b32_e32 v104, v108, v104, vcc
	v_cndmask_b32_e64 v109, v115, v109, s[10:11]
	v_bfe_u32 v118, v107, 29, 1
	v_cndmask_b32_e64 v102, v102, v104, s[6:7]
	v_alignbit_b32 v115, v107, v109, 30
	v_sub_u32_e32 v119, 0, v118
	v_cndmask_b32_e64 v102, v106, v102, s[8:9]
	v_xor_b32_e32 v115, v115, v119
	v_alignbit_b32 v104, v105, v102, v117
	v_cndmask_b32_e64 v104, v104, v105, s[10:11]
	v_ffbh_u32_e32 v106, v115
	v_alignbit_b32 v105, v109, v104, 30
	v_min_u32_e32 v106, 32, v106
	v_alignbit_b32 v102, v104, v102, 30
	v_xor_b32_e32 v105, v105, v119
	v_sub_u32_e32 v108, 31, v106
	v_xor_b32_e32 v102, v102, v119
	v_alignbit_b32 v109, v115, v105, v108
	v_alignbit_b32 v102, v105, v102, v108
	v_alignbit_b32 v104, v109, v102, 9
	v_ffbh_u32_e32 v105, v104
	v_min_u32_e32 v105, 32, v105
	v_lshrrev_b32_e32 v116, 29, v107
	v_not_b32_e32 v108, v105
	v_alignbit_b32 v102, v104, v102, v108
	v_lshlrev_b32_e32 v104, 31, v116
	v_or_b32_e32 v108, 0x33000000, v104
	v_add_lshl_u32 v105, v105, v106, 23
	v_lshrrev_b32_e32 v102, 9, v102
	v_sub_u32_e32 v105, v108, v105
	v_or_b32_e32 v104, 0.5, v104
	v_lshlrev_b32_e32 v106, 23, v106
	v_or_b32_e32 v102, v105, v102
	v_lshrrev_b32_e32 v105, 9, v109
	v_sub_u32_e32 v104, v104, v106
	v_or_b32_e32 v104, v105, v104
	v_mul_f32_e32 v105, 0x3fc90fda, v104
	v_fma_f32 v106, v104, s24, -v105
	v_fmac_f32_e32 v106, 0x33a22168, v104
	v_fmac_f32_e32 v106, 0x3fc90fda, v102
	v_lshrrev_b32_e32 v104, 30, v107
	v_add_f32_e32 v102, v105, v106
	v_add_u32_e32 v115, v118, v104

.LBB0_1812:
	s_or_b64 exec, exec, s[6:7]
	s_waitcnt lgkmcnt(0)
	v_add_f32_e32 v111, v111, v112
	v_fmamk_f32 v111, v111, 0x3c800000, v159
	v_mul_f32_e32 v112, 0x4b800000, v111
	v_cmp_gt_f32_e32 vcc, s0, v111
	v_ashrrev_i32_e32 v101, 31, v100
	v_ashrrev_i32_e32 v99, 31, v98
	v_cndmask_b32_e32 v111, v111, v112, vcc
	v_rsq_f32_e32 v111, v111
	v_lshlrev_b64 v[100:101], 16, v[100:101]
	v_lshl_add_u64 v[100:101], s[26:27], 0, v[100:101]
	v_lshlrev_b64 v[98:99], 7, v[98:99]
	v_lshl_add_u64 v[98:99], v[100:101], 0, v[98:99]
	v_mul_f32_e32 v100, 0x45800000, v111
	v_cndmask_b32_e32 v100, v111, v100, vcc
	v_mul_f32_e64 v56, v56, v100
	v_mul_f32_e64 v57, v57, v100
	v_mul_f32_e64 v60, v60, v100
	v_mul_f32_e64 v61, v61, v100
	s_mov_b32 s6, 0x3c0881c4
	v_mul_f32_e64 v38, v38, v100
	v_mul_f32_e64 v39, v39, v100
	v_mul_f32_e64 v56, v56, v76
	v_mul_f32_e64 v57, v57, v77
	v_mul_f32_e64 v60, v60, v72
	v_mul_f32_e64 v61, v61, v73
	v_mul_f32_e64 v64, v64, v100
	v_mul_f32_e64 v65, v65, v100
	v_lshlrev_b32_e32 v76, 30, v119
	v_lshlrev_b32_e32 v77, 30, v115
	v_mov_b64_e32 v[72:73], s[6:7]
	s_mov_b32 s6, 0xbab64f3b
	v_mul_f32_e64 v38, v90, v38
	v_mul_f32_e64 v39, v91, v39
	v_mul_f32_e64 v50, v50, v100
	v_mul_f32_e64 v51, v51, v100
	v_mul_f32_e64 v64, v64, v68
	v_mul_f32_e64 v65, v65, v69
	v_mul_f32_e64 v68, v102, v102
	v_mul_f32_e64 v69, v103, v103
	v_and_b32_e32 v90, 0x80000000, v76
	v_and_b32_e32 v91, 0x80000000, v77
	v_mov_b64_e32 v[76:77], s[6:7]
	v_mul_f32_e64 v50, v50, v78
	v_mul_f32_e64 v51, v51, v79
	v_mul_f32_e64 v54, v54, v100
	v_mul_f32_e64 v55, v55, v100
	v_fma_f32 v78, v68, s80, v76
	v_fma_f32 v79, v69, s80, v76
	v_mul_f32_e64 v54, v54, v74
	v_mul_f32_e64 v55, v55, v75
	v_fma_f32 v74, v68, s76, v72
	v_fma_f32 v75, v69, s76, v72
	v_fma_f32 v78, v68, v78, s82
	v_fma_f32 v79, v69, v79, s82
	v_mul_f32_e64 v52, v52, v100
	v_mul_f32_e64 v53, v53, v100
	v_fma_f32 v78, v68, v78, s84
	v_fma_f32 v79, v69, v79, s84
	v_fma_f32 v74, v68, v74, s86
	v_fma_f32 v75, v69, v75, s86
	v_mul_f32_e64 v52, v52, v80
	v_mul_f32_e64 v53, v53, v81
	v_and_b32_e32 v80, 1, v119
	v_fma_f32 v78, v68, v78, 1.0
	v_fma_f32 v79, v69, v79, 1.0
	v_mul_f32_e64 v68, v68, v74
	v_mul_f32_e64 v69, v69, v75
	v_mul_f32_e64 v42, v42, v100
	v_mul_f32_e64 v43, v43, v100
	v_and_b32_e32 v81, 1, v115
	v_fma_f32 v68, v102, v68, v102
	v_fma_f32 v69, v103, v69, v103
	v_cmp_eq_u32_e32 vcc, 0, v80
	v_mul_f32_e64 v42, v86, v42
	v_mul_f32_e64 v43, v87, v43
	v_mul_f32_e64 v58, v58, v100
	v_mul_f32_e64 v59, v59, v100
	v_lshlrev_b32_e32 v86, 30, v122
	v_lshlrev_b32_e32 v87, 30, v116
	v_cndmask_b32_e64 v69, -v69, v79, vcc
	v_cmp_eq_u32_e32 vcc, 0, v81
	v_mul_f32_e64 v58, v58, v70
	v_mul_f32_e64 v59, v59, v71
	v_mul_f32_e64 v70, v104, v104
	v_mul_f32_e64 v71, v105, v105
	v_cndmask_b32_e64 v68, -v68, v78, vcc
	v_xor_b32_e32 v74, v118, v117
	v_xor_b32_e32 v75, v114, v113
	v_and_b32_e32 v78, 0x80000000, v86
	v_and_b32_e32 v79, 0x80000000, v87
	v_xor_b32_e32 v80, v74, v78
	v_xor_b32_e32 v81, v75, v79
	v_fma_f32 v74, v70, s76, v72
	v_fma_f32 v75, v71, s76, v72
	v_fma_f32 v78, v70, s80, v76
	v_fma_f32 v79, v71, s80, v76
	v_mul_f32_e64 v44, v44, v100
	v_mul_f32_e64 v45, v45, v100
	v_fma_f32 v74, v70, v74, s86
	v_fma_f32 v75, v71, v75, s86
	v_fma_f32 v78, v70, v78, s82
	v_fma_f32 v79, v71, v79, s82
	v_mul_f32_e64 v44, v44, v88
	v_mul_f32_e64 v45, v45, v89
	v_and_b32_e32 v88, 1, v122
	v_mul_f32_e64 v74, v70, v74
	v_mul_f32_e64 v75, v71, v75
	v_fma_f32 v78, v70, v78, s84
	v_fma_f32 v79, v71, v79, s84
	v_and_b32_e32 v89, 1, v116
	v_fma_f32 v74, v104, v74, v104
	v_fma_f32 v75, v105, v75, v105
	v_fma_f32 v70, v70, v78, 1.0
	v_fma_f32 v71, v71, v79, 1.0
	v_cmp_eq_u32_e64 s[8:9], 0, v88
	v_cmp_class_f32_e64 vcc, v117, s29
	v_cmp_class_f32_e64 s[6:7], v113, s29
	v_cndmask_b32_e64 v71, v71, v75, s[8:9]
	v_cmp_eq_u32_e64 s[8:9], 0, v89
	v_xor_b32_e32 v71, v80, v71
	v_mul_f32_e64 v34, v34, v100
	v_mul_f32_e64 v35, v35, v100
	v_cndmask_b32_e64 v70, v70, v74, s[8:9]
	v_xor_b32_e32 v70, v81, v70
	v_xor_b32_e32 v69, v90, v69
	v_xor_b32_e32 v68, v91, v68
	v_cndmask_b32_e32 v71, v167, v71, vcc
	v_cndmask_b32_e64 v70, v167, v70, s[6:7]
	v_mul_f32_e64 v34, v94, v34
	v_mul_f32_e64 v35, v95, v35
	v_mul_f32_e64 v62, v62, v100
	v_mul_f32_e64 v63, v63, v100
	v_cndmask_b32_e32 v69, v167, v69, vcc
	v_cndmask_b32_e64 v68, v167, v68, s[6:7]
	v_mul_f32_e64 v74, v38, v70
	v_mul_f32_e64 v75, v39, v71
	v_mul_f32_e64 v62, v62, v66
	v_mul_f32_e64 v63, v63, v67
	v_mul_f32_e64 v66, v106, v106
	v_mul_f32_e64 v67, v107, v107
	v_fma_f32 v74, v34, v68, -v74
	v_fma_f32 v75, v35, v69, -v75
	v_mul_f32_e64 v34, v34, v70
	v_mul_f32_e64 v35, v35, v71
	v_fma_f32 v78, v66, s76, v72
	v_fma_f32 v79, v67, s76, v72
	v_fma_f32 v34, v38, v68, v34
	v_fma_f32 v35, v39, v69, v35
	v_fma_f32 v38, v66, s80, v76
	v_fma_f32 v39, v67, s80, v76
	v_mul_f32_e64 v48, v48, v100
	v_mul_f32_e64 v49, v49, v100
	v_fma_f32 v38, v66, v38, s82
	v_fma_f32 v39, v67, v39, s82
	v_fma_f32 v68, v66, v78, s86
	v_fma_f32 v69, v67, v79, s86
	v_fma_f32 v38, v66, v38, s84
	v_fma_f32 v39, v67, v39, s84
	v_mul_f32_e64 v48, v48, v84
	v_mul_f32_e64 v49, v49, v85
	v_and_b32_e32 v84, 1, v127
	v_fma_f32 v38, v66, v38, 1.0
	v_fma_f32 v39, v67, v39, 1.0
	v_mul_f32_e64 v66, v66, v68
	v_mul_f32_e64 v67, v67, v69
	v_and_b32_e32 v85, 1, v123
	v_fma_f32 v66, v106, v66, v106
	v_fma_f32 v67, v107, v67, v107
	v_cmp_eq_u32_e32 vcc, 0, v84
	v_mul_f32_e64 v80, v108, v108
	v_mul_f32_e64 v81, v109, v109
	v_mul_f32_e64 v46, v46, v100
	v_mul_f32_e64 v47, v47, v100
	v_cndmask_b32_e64 v39, -v67, v39, vcc
	v_cmp_eq_u32_e32 vcc, 0, v85
	v_fma_f32 v68, v80, s80, v76
	v_fma_f32 v69, v81, s80, v76
	v_and_b32_e32 v88, 1, v128
	v_cndmask_b32_e64 v38, -v66, v38, vcc
	v_fma_f32 v66, v80, s76, v72
	v_fma_f32 v67, v81, s76, v72
	v_fma_f32 v68, v80, v68, s82
	v_fma_f32 v69, v81, v69, s82
	v_fma_f32 v66, v80, v66, s86
	v_fma_f32 v67, v81, v67, s86
	v_fma_f32 v68, v80, v68, s84
	v_fma_f32 v69, v81, v69, s84
	v_mul_f32_e64 v66, v80, v66
	v_mul_f32_e64 v67, v81, v67
	v_mul_f32_e64 v46, v46, v82
	v_mul_f32_e64 v47, v47, v83
	v_lshlrev_b32_e32 v82, 30, v127
	v_lshlrev_b32_e32 v83, 30, v123
	v_and_b32_e32 v89, 1, v124
	v_fma_f32 v66, v108, v66, v108
	v_fma_f32 v67, v109, v67, v109
	v_fma_f32 v68, v80, v68, 1.0
	v_fma_f32 v69, v81, v69, 1.0
	v_cmp_eq_u32_e64 s[8:9], 0, v88
	v_lshlrev_b32_e32 v86, 30, v128
	v_lshlrev_b32_e32 v87, 30, v124
	v_and_b32_e32 v70, 0x80000000, v82
	v_and_b32_e32 v71, 0x80000000, v83
	v_cndmask_b32_e64 v67, v69, v67, s[8:9]
	v_cmp_eq_u32_e64 s[8:9], 0, v89
	v_xor_b32_e32 v39, v70, v39
	v_xor_b32_e32 v38, v71, v38
	v_cndmask_b32_e64 v66, v68, v66, s[8:9]
	v_and_b32_e32 v68, 0x80000000, v86
	v_and_b32_e32 v69, 0x80000000, v87
	v_xor_b32_e32 v70, v126, v125
	v_xor_b32_e32 v71, v121, v120
	v_xor_b32_e32 v68, v70, v68
	v_xor_b32_e32 v69, v71, v69
	v_mul_f32_e64 v40, v40, v100
	v_mul_f32_e64 v41, v41, v100
	v_cmp_class_f32_e64 vcc, v125, s29
	v_cmp_class_f32_e64 s[6:7], v120, s29
	v_xor_b32_e32 v67, v68, v67
	v_xor_b32_e32 v66, v69, v66
	v_mul_f32_e64 v36, v36, v100
	v_mul_f32_e64 v37, v37, v100
	v_mul_f32_e64 v40, v92, v40
	v_mul_f32_e64 v41, v93, v41
	v_cndmask_b32_e32 v67, v167, v67, vcc
	v_cndmask_b32_e64 v66, v167, v66, s[6:7]
	v_mul_f32_e64 v36, v96, v36
	v_mul_f32_e64 v37, v97, v37
	v_cndmask_b32_e32 v39, v167, v39, vcc
	v_cndmask_b32_e64 v38, v167, v38, s[6:7]
	v_mul_f32_e64 v68, v40, v66
	v_mul_f32_e64 v69, v41, v67
	v_cvt_pk_bf16_f32 v34, v34, v35
	v_fma_f32 v68, v36, v38, -v68
	v_fma_f32 v69, v37, v39, -v69
	v_mul_f32_e64 v36, v36, v66
	v_mul_f32_e64 v37, v37, v67
	s_nop 0
	v_fma_f32 v36, v40, v38, v36
	v_fma_f32 v37, v41, v39, v37
	v_lshlrev_b32_e32 v38, 1, v142
	v_mov_b32_e32 v39, v137
	v_lshl_add_u64 v[38:39], v[98:99], 0, v[38:39]
	v_cvt_pk_bf16_f32 v35, v36, v37
	global_store_dwordx2 v[38:39], v[34:35], off offset:16
	v_cvt_pk_bf16_f32 v34, v42, v43
	v_cvt_pk_bf16_f32 v35, v44, v45
	global_store_dwordx2 v[38:39], v[34:35], off offset:32
	v_cvt_pk_bf16_f32 v34, v46, v47
	v_cvt_pk_bf16_f32 v35, v48, v49
	global_store_dwordx2 v[38:39], v[34:35], off offset:48
	v_cvt_pk_bf16_f32 v34, v50, v51
	v_cvt_pk_bf16_f32 v35, v52, v53
	global_store_dwordx2 v[38:39], v[34:35], off offset:64
	v_cvt_pk_bf16_f32 v34, v54, v55
	v_cvt_pk_bf16_f32 v35, v56, v57
	global_store_dwordx2 v[38:39], v[34:35], off offset:80
	v_cvt_pk_bf16_f32 v34, v58, v59
	v_cvt_pk_bf16_f32 v35, v60, v61
	v_cvt_pk_bf16_f32 v40, v74, v75
	v_cvt_pk_bf16_f32 v41, v68, v69
	global_store_dwordx2 v[38:39], v[34:35], off offset:96
	v_cvt_pk_bf16_f32 v34, v62, v63
	v_cvt_pk_bf16_f32 v35, v64, v65
	global_store_dwordx2 v[38:39], v[40:41], off
	global_store_dwordx2 v[38:39], v[34:35], off offset:112

.LBB0_1816:
	s_andn2_b64 vcc, exec, s[6:7]
	s_cbranch_vccnz .LBB0_1229
	v_mul_f32_e32 v44, v19, v19
	v_fmac_f32_e32 v44, v18, v18
	v_fmac_f32_e32 v44, v20, v20
	v_fmac_f32_e32 v44, v21, v21
	v_fmac_f32_e32 v44, v22, v22
	v_fmac_f32_e32 v44, v23, v23
	v_fmac_f32_e32 v44, v24, v24
	v_fmac_f32_e32 v44, v25, v25
	v_fmac_f32_e32 v44, v26, v26
	v_fmac_f32_e32 v44, v27, v27
	v_fmac_f32_e32 v44, v28, v28
	v_fmac_f32_e32 v44, v29, v29
	v_fmac_f32_e32 v44, v30, v30
	v_fmac_f32_e32 v44, v31, v31
	v_fmac_f32_e32 v44, v32, v32
	v_fmac_f32_e32 v44, v33, v33
	v_fmac_f32_e32 v44, v2, v2
	v_fmac_f32_e32 v44, v3, v3
	v_fmac_f32_e32 v44, v4, v4
	v_fmac_f32_e32 v44, v5, v5
	v_fmac_f32_e32 v44, v6, v6
	v_fmac_f32_e32 v44, v7, v7
	v_mul_f32_e64 v42, v8, v8
	v_mul_f32_e64 v43, v9, v9
	v_mul_f32_e64 v40, v10, v10
	v_mul_f32_e64 v41, v11, v11
	v_add_f32_e32 v42, v42, v44
	v_add_f32_e32 v42, v43, v42
	v_lshlrev_b32_e32 v34, 12, v68
	v_add_f32_e32 v40, v40, v42
	v_and_b32_e32 v34, 0xffffe000, v34
	v_mul_f32_e64 v38, v12, v12
	v_mul_f32_e64 v39, v13, v13
	v_add_f32_e32 v40, v41, v40
	v_lshl_add_u32 v34, v66, 4, v34
	v_add_f32_e32 v38, v38, v40
	v_ashrrev_i32_e32 v35, 31, v34
	v_mul_f32_e64 v36, v14, v14
	v_mul_f32_e64 v37, v15, v15
	v_add_f32_e32 v38, v39, v38
	v_lshl_add_u64 v[34:35], v[34:35], 2, s[54:55]
	v_add_f32_e32 v36, v36, v38
	global_load_dword v67, v[34:35], off offset:124
	v_mul_f32_e64 v34, v16, v16
	v_mul_f32_e64 v35, v17, v17
	v_add_f32_e32 v36, v37, v36
	v_add_f32_e32 v34, v34, v36
	v_add_f32_e32 v78, v35, v34
	v_and_b32_e32 v35, 64, v163
	v_xor_b32_e32 v34, 32, v163
	v_add_u32_e32 v35, 64, v35
	v_cmp_lt_i32_e32 vcc, v34, v35
	s_waitcnt vmcnt(0)
	v_cvt_f32_i32_e32 v67, v67
	v_cndmask_b32_e32 v34, v163, v34, vcc
	v_lshlrev_b32_e32 v34, 2, v34
	ds_bpermute_b32 v79, v34, v78
	global_load_dwordx4 v[62:65], v[146:147], off
	global_load_dwordx4 v[58:61], v[146:147], off offset:32
	global_load_dwordx4 v[54:57], v[146:147], off offset:64
	global_load_dwordx4 v[50:53], v[146:147], off offset:96
	global_load_dwordx4 v[46:49], v[146:147], off offset:128
	global_load_dwordx4 v[42:45], v[146:147], off offset:160
	global_load_dwordx4 v[38:41], v[146:147], off offset:192
	global_load_dwordx4 v[34:37], v[146:147], off offset:224
	global_load_dword v69, v[144:145], off
	s_waitcnt vmcnt(0)
	v_mul_f32_e32 v80, v69, v67
	v_and_b32_e32 v81, 0x7fffffff, v80
	v_lshrrev_b32_e32 v69, 23, v81
	v_and_b32_e32 v70, 0x7fffff, v81
	v_cmp_nlt_f32_e64 s[74:75], |v80|, s96
	v_add_u32_e32 v71, 0xffffff88, v69
	v_or_b32_e32 v69, 0x800000, v70
	s_and_saveexec_b64 s[6:7], s[74:75]
	s_xor_b64 s[78:79], exec, s[6:7]
	s_cbranch_execz .LBB0_1819
	v_cmp_lt_u32_e32 vcc, 63, v71
	v_mov_b32_e32 v75, v137
	v_mov_b32_e32 v77, v137
	v_cndmask_b32_e32 v70, 0, v164, vcc
	v_add_u32_e32 v70, v70, v71
	v_cmp_lt_u32_e64 s[6:7], 31, v70
	v_mov_b32_e32 v83, v137
	v_mov_b32_e32 v85, v137
	v_cndmask_b32_e64 v72, 0, v165, s[6:7]
	v_add_u32_e32 v70, v72, v70
	v_cmp_lt_u32_e64 s[8:9], 31, v70
	v_mov_b32_e32 v87, v137
	v_mov_b32_e32 v89, v137
	v_cndmask_b32_e64 v72, 0, v165, s[8:9]
	v_add_u32_e32 v70, v72, v70
	v_mad_u64_u32 v[72:73], s[10:11], v69, s97, 0
	v_mov_b32_e32 v74, v73
	v_mad_u64_u32 v[74:75], s[10:11], v69, s3, v[74:75]
	v_mov_b32_e32 v76, v75
	v_mad_u64_u32 v[76:77], s[10:11], v69, s81, v[76:77]
	v_mov_b32_e32 v82, v77
	v_mad_u64_u32 v[82:83], s[10:11], v69, s14, v[82:83]
	v_mov_b32_e32 v84, v83
	v_mad_u64_u32 v[84:85], s[10:11], v69, s15, v[84:85]
	v_mov_b32_e32 v86, v85
	v_mad_u64_u32 v[86:87], s[10:11], v69, s94, v[86:87]
	v_mov_b32_e32 v88, v87
	v_mad_u64_u32 v[88:89], s[10:11], v69, s95, v[88:89]
	v_cndmask_b32_e32 v73, v86, v82, vcc
	v_cndmask_b32_e32 v75, v88, v84, vcc
	v_cndmask_b32_e32 v83, v89, v86, vcc
	v_cndmask_b32_e64 v77, v75, v73, s[6:7]
	v_cndmask_b32_e64 v75, v83, v75, s[6:7]
	v_cndmask_b32_e32 v83, v84, v76, vcc
	v_cndmask_b32_e64 v73, v73, v83, s[6:7]
	v_sub_u32_e32 v84, 32, v70
	v_cmp_eq_u32_e64 s[10:11], 0, v70
	v_cndmask_b32_e32 v70, v82, v74, vcc
	v_cndmask_b32_e64 v75, v75, v77, s[8:9]
	v_cndmask_b32_e64 v77, v77, v73, s[8:9]
	v_cndmask_b32_e64 v74, v83, v70, s[6:7]
	v_alignbit_b32 v85, v75, v77, v84
	v_cndmask_b32_e64 v73, v73, v74, s[8:9]
	v_cndmask_b32_e64 v75, v85, v75, s[10:11]
	v_alignbit_b32 v82, v77, v73, v84
	v_cndmask_b32_e32 v72, v76, v72, vcc
	v_cndmask_b32_e64 v77, v82, v77, s[10:11]
	v_bfe_u32 v85, v75, 29, 1
	v_cndmask_b32_e64 v70, v70, v72, s[6:7]
	v_alignbit_b32 v82, v75, v77, 30
	v_sub_u32_e32 v86, 0, v85
	v_cndmask_b32_e64 v70, v74, v70, s[8:9]
	v_xor_b32_e32 v82, v82, v86
	v_alignbit_b32 v72, v73, v70, v84
	v_cndmask_b32_e64 v72, v72, v73, s[10:11]
	v_ffbh_u32_e32 v74, v82
	v_alignbit_b32 v73, v77, v72, 30
	v_min_u32_e32 v74, 32, v74
	v_alignbit_b32 v70, v72, v70, 30
	v_xor_b32_e32 v73, v73, v86
	v_sub_u32_e32 v76, 31, v74
	v_xor_b32_e32 v70, v70, v86
	v_alignbit_b32 v77, v82, v73, v76
	v_alignbit_b32 v70, v73, v70, v76
	v_alignbit_b32 v72, v77, v70, 9
	v_ffbh_u32_e32 v73, v72
	v_min_u32_e32 v73, 32, v73
	v_lshrrev_b32_e32 v83, 29, v75
	v_not_b32_e32 v76, v73
	v_alignbit_b32 v70, v72, v70, v76
	v_lshlrev_b32_e32 v72, 31, v83
	v_or_b32_e32 v76, 0x33000000, v72
	v_add_lshl_u32 v73, v73, v74, 23
	v_lshrrev_b32_e32 v70, 9, v70
	v_sub_u32_e32 v73, v76, v73
	v_or_b32_e32 v72, 0.5, v72
	v_lshlrev_b32_e32 v74, 23, v74
	v_or_b32_e32 v70, v73, v70
	v_lshrrev_b32_e32 v73, 9, v77
	v_sub_u32_e32 v72, v72, v74
	v_or_b32_e32 v72, v73, v72
	v_mul_f32_e32 v73, 0x3fc90fda, v72
	v_fma_f32 v74, v72, s24, -v73
	v_fmac_f32_e32 v74, 0x33a22168, v72
	v_fmac_f32_e32 v74, 0x3fc90fda, v70
	v_lshrrev_b32_e32 v72, 30, v75
	v_add_f32_e32 v70, v73, v74
	v_add_u32_e32 v82, v85, v72

.LBB0_1938:
	s_mulk_i32 s20, 0x4800
	v_add_u32_e32 v50, s20, v156
	ds_read_b128 v[2:5], v50
	ds_read_b128 v[6:9], v50 offset:32
	s_waitcnt lgkmcnt(1)
	v_mfma_f32_32x32x16_bf16 v[18:33], v[2:5], v[78:81], 0
	s_waitcnt lgkmcnt(0)
	v_mfma_f32_32x32x16_bf16 v[18:33], v[6:9], v[66:69], v[18:33]
	ds_read_b128 v[2:5], v50 offset:64
	ds_read_b128 v[6:9], v50 offset:96
	s_waitcnt lgkmcnt(1)
	v_mfma_f32_32x32x16_bf16 v[18:33], v[2:5], v[70:73], v[18:33]
	ds_read_b128 v[2:5], v50 offset:4608
	ds_read_b128 v[46:49], v50 offset:4640
	s_waitcnt lgkmcnt(2)
	v_mfma_f32_32x32x16_bf16 v[18:33], v[6:9], v[74:77], v[18:33]
	s_waitcnt lgkmcnt(1)
	v_mfma_f32_32x32x16_bf16 v[2:17], v[2:5], v[78:81], 0
	s_waitcnt lgkmcnt(0)
	v_mfma_f32_32x32x16_bf16 v[2:17], v[46:49], v[66:69], v[2:17]
	ds_read_b128 v[46:49], v50 offset:4672
	ds_read_b128 v[50:53], v50 offset:4704
	s_waitcnt lgkmcnt(1)
	v_mfma_f32_32x32x16_bf16 v[2:17], v[46:49], v[70:73], v[2:17]
	s_waitcnt lgkmcnt(0)
	v_mfma_f32_32x32x16_bf16 v[2:17], v[50:53], v[74:77], v[2:17]
	v_cmp_lt_i32_e32 vcc, 26, v55
	s_nop 0
	v_fma_f32 v18, v18, s48, v100
	v_fma_f32 v19, v19, s48, v101
	v_fma_f32 v20, v20, s48, v100
	v_fma_f32 v21, v21, s48, v101
	v_fma_f32 v22, v22, s48, v100
	v_fma_f32 v23, v23, s48, v101
	v_fma_f32 v24, v24, s48, v100
	v_fma_f32 v25, v25, s48, v101
	v_fma_f32 v26, v26, s48, v100
	v_fma_f32 v27, v27, s48, v101
	v_fma_f32 v28, v28, s48, v100
	v_fma_f32 v29, v29, s48, v101
	v_fma_f32 v30, v30, s48, v100
	v_fma_f32 v31, v31, s48, v101
	s_cmp_eq_u64 vcc, exec
	v_fma_f32 v32, v32, s48, v100
	v_fma_f32 v33, v33, s48, v101
	s_cbranch_scc1 .LBB0_1940
	v_cmp_lt_i32_e64 s[20:21], -1, v55
	v_cndmask_b32_e32 v33, v213, v33, vcc
	s_nop 0
	v_cndmask_b32_e64 v18, v213, v18, s[20:21]
	v_cmp_lt_i32_e64 s[20:21], 0, v55
	s_nop 1
	v_cndmask_b32_e64 v19, v213, v19, s[20:21]
	v_cmp_lt_i32_e64 s[20:21], 1, v55
	s_nop 1
	v_cndmask_b32_e64 v20, v213, v20, s[20:21]
	v_cmp_lt_i32_e64 s[20:21], 2, v55
	s_nop 1
	v_cndmask_b32_e64 v21, v213, v21, s[20:21]
	v_cmp_lt_i32_e64 s[20:21], 7, v55
	s_nop 1
	v_cndmask_b32_e64 v22, v213, v22, s[20:21]
	v_cmp_lt_i32_e64 s[20:21], 8, v55
	s_nop 1
	v_cndmask_b32_e64 v23, v213, v23, s[20:21]
	v_cmp_lt_i32_e64 s[20:21], 9, v55
	s_nop 1
	v_cndmask_b32_e64 v24, v213, v24, s[20:21]
	v_cmp_lt_i32_e64 s[20:21], 10, v55
	s_nop 1
	v_cndmask_b32_e64 v25, v213, v25, s[20:21]
	v_cmp_lt_i32_e64 s[20:21], 15, v55
	s_nop 1
	v_cndmask_b32_e64 v26, v213, v26, s[20:21]
	v_cmp_lt_i32_e64 s[20:21], 16, v55
	s_nop 1
	v_cndmask_b32_e64 v27, v213, v27, s[20:21]
	v_cmp_lt_i32_e64 s[20:21], 17, v55
	s_nop 1
	v_cndmask_b32_e64 v28, v213, v28, s[20:21]
	v_cmp_lt_i32_e64 s[20:21], 18, v55
	s_nop 1
	v_cndmask_b32_e64 v29, v213, v29, s[20:21]
	v_cmp_lt_i32_e64 s[20:21], 23, v55
	s_nop 1
	v_cndmask_b32_e64 v30, v213, v30, s[20:21]
	v_cmp_lt_i32_e64 s[20:21], 24, v55
	s_nop 1
	v_cndmask_b32_e64 v31, v213, v31, s[20:21]
	v_cmp_lt_i32_e64 s[20:21], 25, v55
	s_nop 1
	v_cndmask_b32_e64 v32, v213, v32, s[20:21]
.LBB0_1940:
	v_subrev_u32_e32 v56, 32, v55
	v_cmp_lt_i32_e32 vcc, 26, v56
	v_fma_f32 v52, v2, s48, v100
	v_fma_f32 v53, v3, s48, v101
	v_fma_f32 v50, v4, s48, v100
	v_fma_f32 v51, v5, s48, v101
	v_fma_f32 v48, v6, s48, v100
	v_fma_f32 v49, v7, s48, v101
	v_fma_f32 v46, v8, s48, v100
	v_fma_f32 v47, v9, s48, v101
	v_fma_f32 v8, v10, s48, v100
	v_fma_f32 v9, v11, s48, v101
	v_fma_f32 v6, v12, s48, v100
	v_fma_f32 v7, v13, s48, v101
	v_fma_f32 v2, v14, s48, v100
	v_fma_f32 v3, v15, s48, v101
	s_cmp_eq_u64 vcc, exec
	v_fma_f32 v4, v16, s48, v100
	v_fma_f32 v5, v17, s48, v101
	s_cbranch_scc1 .LBB0_1933
	v_cmp_lt_i32_e64 s[20:21], -1, v56
	v_cndmask_b32_e32 v5, v213, v5, vcc
	s_nop 0
	v_cndmask_b32_e64 v52, v213, v52, s[20:21]
	v_cmp_lt_i32_e64 s[20:21], 0, v56
	s_nop 1
	v_cndmask_b32_e64 v53, v213, v53, s[20:21]
	v_cmp_lt_i32_e64 s[20:21], 1, v56
	s_nop 1
	v_cndmask_b32_e64 v50, v213, v50, s[20:21]
	v_cmp_lt_i32_e64 s[20:21], 2, v56
	s_nop 1
	v_cndmask_b32_e64 v51, v213, v51, s[20:21]
	v_cmp_lt_i32_e64 s[20:21], 7, v56
	s_nop 1
	v_cndmask_b32_e64 v48, v213, v48, s[20:21]
	v_cmp_lt_i32_e64 s[20:21], 8, v56
	s_nop 1
	v_cndmask_b32_e64 v49, v213, v49, s[20:21]
	v_cmp_lt_i32_e64 s[20:21], 9, v56
	s_nop 1
	v_cndmask_b32_e64 v46, v213, v46, s[20:21]
	v_cmp_lt_i32_e64 s[20:21], 10, v56
	s_nop 1
	v_cndmask_b32_e64 v47, v213, v47, s[20:21]
	v_cmp_lt_i32_e64 s[20:21], 15, v56
	s_nop 1
	v_cndmask_b32_e64 v8, v213, v8, s[20:21]
	v_cmp_lt_i32_e64 s[20:21], 16, v56
	s_nop 1
	v_cndmask_b32_e64 v9, v213, v9, s[20:21]
	v_cmp_lt_i32_e64 s[20:21], 17, v56
	s_nop 1
	v_cndmask_b32_e64 v6, v213, v6, s[20:21]
	v_cmp_lt_i32_e64 s[20:21], 18, v56
	s_nop 1
	v_cndmask_b32_e64 v7, v213, v7, s[20:21]
	v_cmp_lt_i32_e64 s[20:21], 23, v56
	s_nop 1
	v_cndmask_b32_e64 v2, v213, v2, s[20:21]
	v_cmp_lt_i32_e64 s[20:21], 24, v56
	s_nop 1
	v_cndmask_b32_e64 v3, v213, v3, s[20:21]
	v_cmp_lt_i32_e64 s[20:21], 25, v56
	s_nop 1
	v_cndmask_b32_e64 v4, v213, v4, s[20:21]
	s_branch .LBB0_1933

.LBB0_1951:
	s_mulk_i32 s20, 0x4800
	v_add_u32_e32 v148, s20, v156
	ds_read_b128 v[34:37], v148
	ds_read_b128 v[38:41], v148 offset:32
	s_waitcnt lgkmcnt(1)
	v_mfma_f32_32x32x16_bf16 v[50:65], v[34:37], v[78:81], 0
	s_waitcnt lgkmcnt(0)
	v_mfma_f32_32x32x16_bf16 v[50:65], v[38:41], v[66:69], v[50:65]
	ds_read_b128 v[34:37], v148 offset:64
	ds_read_b128 v[38:41], v148 offset:96
	s_waitcnt lgkmcnt(1)
	v_mfma_f32_32x32x16_bf16 v[50:65], v[34:37], v[70:73], v[50:65]
	ds_read_b128 v[34:37], v148 offset:4608
	ds_read_b128 v[138:141], v148 offset:4640
	s_waitcnt lgkmcnt(2)
	v_mfma_f32_32x32x16_bf16 v[50:65], v[38:41], v[74:77], v[50:65]
	s_waitcnt lgkmcnt(1)
	v_mfma_f32_32x32x16_bf16 v[34:49], v[34:37], v[78:81], 0
	s_waitcnt lgkmcnt(0)
	v_mfma_f32_32x32x16_bf16 v[34:49], v[138:141], v[66:69], v[34:49]
	ds_read_b128 v[138:141], v148 offset:4672
	ds_read_b128 v[142:145], v148 offset:4704
	s_waitcnt lgkmcnt(1)
	v_mfma_f32_32x32x16_bf16 v[34:49], v[138:141], v[70:73], v[34:49]
	s_waitcnt lgkmcnt(0)
	v_mfma_f32_32x32x16_bf16 v[34:49], v[142:145], v[74:77], v[34:49]
	v_cmp_lt_i32_e32 vcc, 26, v129
	s_nop 0
	v_fma_f32 v138, v50, s48, v100
	v_fma_f32 v139, v51, s48, v101
	v_fma_f32 v140, v52, s48, v100
	v_fma_f32 v141, v53, s48, v101
	v_fma_f32 v54, v54, s48, v100
	v_fma_f32 v55, v55, s48, v101
	v_fma_f32 v56, v56, s48, v100
	v_fma_f32 v57, v57, s48, v101
	v_fma_f32 v58, v58, s48, v100
	v_fma_f32 v59, v59, s48, v101
	v_fma_f32 v52, v60, s48, v100
	v_fma_f32 v53, v61, s48, v101
	v_fma_f32 v50, v62, s48, v100
	v_fma_f32 v51, v63, s48, v101
	s_cmp_eq_u64 vcc, exec
	v_fma_f32 v60, v64, s48, v100
	v_fma_f32 v61, v65, s48, v101
	s_cbranch_scc1 .LBB0_1953
	v_cmp_lt_i32_e64 s[20:21], -1, v129
	v_cndmask_b32_e32 v61, v213, v61, vcc
	s_nop 0
	v_cndmask_b32_e64 v138, v213, v138, s[20:21]
	v_cmp_lt_i32_e64 s[20:21], 0, v129
	s_nop 1
	v_cndmask_b32_e64 v139, v213, v139, s[20:21]
	v_cmp_lt_i32_e64 s[20:21], 1, v129
	s_nop 1
	v_cndmask_b32_e64 v140, v213, v140, s[20:21]
	v_cmp_lt_i32_e64 s[20:21], 2, v129
	s_nop 1
	v_cndmask_b32_e64 v141, v213, v141, s[20:21]
	v_cmp_lt_i32_e64 s[20:21], 7, v129
	s_nop 1
	v_cndmask_b32_e64 v54, v213, v54, s[20:21]
	v_cmp_lt_i32_e64 s[20:21], 8, v129
	s_nop 1
	v_cndmask_b32_e64 v55, v213, v55, s[20:21]
	v_cmp_lt_i32_e64 s[20:21], 9, v129
	s_nop 1
	v_cndmask_b32_e64 v56, v213, v56, s[20:21]
	v_cmp_lt_i32_e64 s[20:21], 10, v129
	s_nop 1
	v_cndmask_b32_e64 v57, v213, v57, s[20:21]
	v_cmp_lt_i32_e64 s[20:21], 15, v129
	s_nop 1
	v_cndmask_b32_e64 v58, v213, v58, s[20:21]
	v_cmp_lt_i32_e64 s[20:21], 16, v129
	s_nop 1
	v_cndmask_b32_e64 v59, v213, v59, s[20:21]
	v_cmp_lt_i32_e64 s[20:21], 17, v129
	s_nop 1
	v_cndmask_b32_e64 v52, v213, v52, s[20:21]
	v_cmp_lt_i32_e64 s[20:21], 18, v129
	s_nop 1
	v_cndmask_b32_e64 v53, v213, v53, s[20:21]
	v_cmp_lt_i32_e64 s[20:21], 23, v129
	s_nop 1
	v_cndmask_b32_e64 v50, v213, v50, s[20:21]
	v_cmp_lt_i32_e64 s[20:21], 24, v129
	s_nop 1
	v_cndmask_b32_e64 v51, v213, v51, s[20:21]
	v_cmp_lt_i32_e64 s[20:21], 25, v129
	s_nop 1
	v_cndmask_b32_e64 v60, v213, v60, s[20:21]
.LBB0_1953:
	v_subrev_u32_e32 v149, 32, v129
	v_cmp_lt_i32_e32 vcc, 26, v149
	v_fma_f32 v142, v34, s48, v100
	v_fma_f32 v143, v35, s48, v101
	v_fma_f32 v144, v36, s48, v100
	v_fma_f32 v145, v37, s48, v101
	v_fma_f32 v62, v38, s48, v100
	v_fma_f32 v63, v39, s48, v101
	v_fma_f32 v64, v40, s48, v100
	v_fma_f32 v65, v41, s48, v101
	v_fma_f32 v38, v42, s48, v100
	v_fma_f32 v39, v43, s48, v101
	v_fma_f32 v40, v44, s48, v100
	v_fma_f32 v41, v45, s48, v101
	v_fma_f32 v34, v46, s48, v100
	v_fma_f32 v35, v47, s48, v101
	s_cmp_eq_u64 vcc, exec
	v_fma_f32 v36, v48, s48, v100
	v_fma_f32 v37, v49, s48, v101
	s_cbranch_scc1 .LBB0_1955
	v_cmp_lt_i32_e64 s[20:21], -1, v149
	v_cndmask_b32_e32 v37, v213, v37, vcc
	s_nop 0
	v_cndmask_b32_e64 v142, v213, v142, s[20:21]
	v_cmp_lt_i32_e64 s[20:21], 0, v149
	s_nop 1
	v_cndmask_b32_e64 v143, v213, v143, s[20:21]
	v_cmp_lt_i32_e64 s[20:21], 1, v149
	s_nop 1
	v_cndmask_b32_e64 v144, v213, v144, s[20:21]
	v_cmp_lt_i32_e64 s[20:21], 2, v149
	s_nop 1
	v_cndmask_b32_e64 v145, v213, v145, s[20:21]
	v_cmp_lt_i32_e64 s[20:21], 7, v149
	s_nop 1
	v_cndmask_b32_e64 v62, v213, v62, s[20:21]
	v_cmp_lt_i32_e64 s[20:21], 8, v149
	s_nop 1
	v_cndmask_b32_e64 v63, v213, v63, s[20:21]
	v_cmp_lt_i32_e64 s[20:21], 9, v149
	s_nop 1
	v_cndmask_b32_e64 v64, v213, v64, s[20:21]
	v_cmp_lt_i32_e64 s[20:21], 10, v149
	s_nop 1
	v_cndmask_b32_e64 v65, v213, v65, s[20:21]
	v_cmp_lt_i32_e64 s[20:21], 15, v149
	s_nop 1
	v_cndmask_b32_e64 v38, v213, v38, s[20:21]
	v_cmp_lt_i32_e64 s[20:21], 16, v149
	s_nop 1
	v_cndmask_b32_e64 v39, v213, v39, s[20:21]
	v_cmp_lt_i32_e64 s[20:21], 17, v149
	s_nop 1
	v_cndmask_b32_e64 v40, v213, v40, s[20:21]
	v_cmp_lt_i32_e64 s[20:21], 18, v149
	s_nop 1
	v_cndmask_b32_e64 v41, v213, v41, s[20:21]
	v_cmp_lt_i32_e64 s[20:21], 23, v149
	s_nop 1
	v_cndmask_b32_e64 v34, v213, v34, s[20:21]
	v_cmp_lt_i32_e64 s[20:21], 24, v149
	s_nop 1
	v_cndmask_b32_e64 v35, v213, v35, s[20:21]
	v_cmp_lt_i32_e64 s[20:21], 25, v149
	s_nop 1
	v_cndmask_b32_e64 v36, v213, v36, s[20:21]

.LBB0_2164:
	s_or_b64 exec, exec, s[20:21]
	v_add_u32_e32 v38, v34, v35
	v_bcnt_u32_b32 v37, v37, 0
	v_add_u32_e32 v38, v38, v36
	v_add_u32_e32 v150, v38, v37
	v_mul_f32_e32 v38, v133, v146
	v_cmp_eq_u32_e32 vcc, 0, v150
	v_mul_f32_e64 v82, v38, v18
	v_mul_f32_e64 v83, v38, v19
	v_add_u32_e32 v215, 0x9000, v214
	v_mul_f32_e64 v84, v38, v20
	v_mul_f32_e64 v85, v38, v21
	v_add_u32_e32 v216, 0x9008, v214
	v_mul_f32_e64 v86, v38, v22
	v_mul_f32_e64 v87, v38, v23
	v_add_u32_e32 v217, 0x9020, v214
	v_mul_f32_e64 v88, v38, v24
	v_mul_f32_e64 v89, v38, v25
	v_add_u32_e32 v218, 0x9028, v214
	v_mul_f32_e64 v90, v38, v26
	v_mul_f32_e64 v91, v38, v27
	v_add_u32_e32 v219, 0x9040, v214
	v_mul_f32_e64 v92, v38, v28
	v_mul_f32_e64 v93, v38, v29
	v_add_u32_e32 v220, 0x9048, v214
	v_mul_f32_e64 v94, v38, v30
	v_mul_f32_e64 v95, v38, v31
	v_add_u32_e32 v221, 0x9060, v214
	v_mul_f32_e64 v96, v38, v32
	v_mul_f32_e64 v97, v38, v33
	v_add_u32_e32 v222, 0x9068, v214
	v_mul_f32_e64 v134, v38, v2
	v_mul_f32_e64 v135, v38, v3
	v_add_u32_e32 v223, 0x9080, v214
	v_mul_f32_e64 v136, v38, v4
	v_mul_f32_e64 v137, v38, v5
	v_add_u32_e32 v224, 0x9088, v214
	v_mul_f32_e64 v138, v38, v6
	v_mul_f32_e64 v139, v38, v7
	v_add_u32_e32 v225, 0x90a0, v214
	v_mul_f32_e64 v140, v38, v8
	v_mul_f32_e64 v141, v38, v9
	v_add_u32_e32 v226, 0x90a8, v214
	v_mul_f32_e64 v142, v38, v10
	v_mul_f32_e64 v143, v38, v11
	v_add_u32_e32 v227, 0x90c0, v214
	v_mul_f32_e64 v144, v38, v12
	v_mul_f32_e64 v145, v38, v13
	v_add_u32_e32 v228, 0x90c8, v214
	v_mul_f32_e64 v146, v38, v14
	v_mul_f32_e64 v147, v38, v15
	v_add_u32_e32 v229, 0x90e0, v214
	v_mul_f32_e64 v148, v38, v16
	v_mul_f32_e64 v149, v38, v17
	v_add_u32_e32 v230, 0x90e8, v214
	s_and_b64 vcc, exec, vcc
	s_lshl_b32 s24, s71, 19
	s_waitcnt lgkmcnt(0)
	s_barrier
	ds_write2_b32 v215, v82, v83 offset1:1
	ds_write2_b32 v216, v84, v85 offset1:1
	ds_write2_b32 v217, v86, v87 offset1:1
	ds_write2_b32 v218, v88, v89 offset1:1
	ds_write2_b32 v219, v90, v91 offset1:1
	ds_write2_b32 v220, v92, v93 offset1:1
	ds_write2_b32 v221, v94, v95 offset1:1
	ds_write2_b32 v222, v96, v97 offset1:1
	ds_write2_b32 v223, v134, v135 offset1:1
	ds_write2_b32 v224, v136, v137 offset1:1
	ds_write2_b32 v225, v138, v139 offset1:1
	ds_write2_b32 v226, v140, v141 offset1:1
	ds_write2_b32 v227, v142, v143 offset1:1
	ds_write2_b32 v228, v144, v145 offset1:1
	ds_write2_b32 v229, v146, v147 offset1:1
	ds_write2_b32 v230, v148, v149 offset1:1
	s_cbranch_vccnz .LBB0_2181
	ds_read_b32 v2, v211
	s_lshl_b32 s22, s24, 1
	v_readlane_b32 s20, v231, 14
	s_add_u32 s20, s20, s22
	v_readlane_b32 s21, v231, 10
	s_addc_u32 s21, s21, 0
	s_waitcnt lgkmcnt(0)
	v_ashrrev_i32_e32 v3, 31, v2
	s_add_u32 s22, s52, s22
	v_lshlrev_b64 v[2:3], 13, v[2:3]
	s_addc_u32 s23, s53, 0
	v_lshl_add_u64 v[4:5], s[20:21], 0, v[2:3]
	v_mov_b32_e32 v129, v105
	v_lshl_add_u64 v[2:3], s[22:23], 0, v[2:3]
	v_lshl_add_u64 v[4:5], v[4:5], 0, v[128:129]
	v_lshl_add_u64 v[6:7], v[4:5], 0, v[106:107]
	v_lshl_add_u64 v[2:3], v[2:3], 0, v[128:129]
	v_lshl_add_u64 v[4:5], v[4:5], 0, v[108:109]
	v_lshl_add_u64 v[8:9], v[2:3], 0, v[106:107]
	global_load_dwordx4 v[82:85], v[6:7], off
	global_load_dwordx4 v[86:89], v[8:9], off
	v_lshl_add_u64 v[2:3], v[2:3], 0, v[108:109]
	global_load_dwordx4 v[90:93], v[4:5], off
	global_load_dwordx4 v[94:97], v[2:3], off
	v_cmp_eq_u32_e32 vcc, 1, v150
	s_and_b64 vcc, exec, vcc
	s_waitcnt vmcnt(3)
	ds_write_b128 v153, v[82:85]
	s_waitcnt vmcnt(2)
	ds_write_b128 v153, v[86:89] offset:9216
	s_waitcnt vmcnt(1)
	ds_write_b128 v155, v[90:93]
	s_waitcnt vmcnt(0)
	ds_write_b128 v155, v[94:97] offset:9216
	s_cbranch_vccnz .LBB0_2167
	ds_read_b32 v2, v212
	s_waitcnt lgkmcnt(0)
	v_ashrrev_i32_e32 v3, 31, v2
	v_lshlrev_b64 v[2:3], 13, v[2:3]
	v_lshl_add_u64 v[4:5], s[20:21], 0, v[2:3]
	v_lshl_add_u64 v[2:3], s[22:23], 0, v[2:3]
	v_lshl_add_u64 v[4:5], v[4:5], 0, v[128:129]
	v_lshl_add_u64 v[2:3], v[2:3], 0, v[128:129]
	v_lshl_add_u64 v[6:7], v[4:5], 0, v[106:107]
	v_lshl_add_u64 v[4:5], v[4:5], 0, v[108:109]
	v_lshl_add_u64 v[8:9], v[2:3], 0, v[106:107]
	global_load_dwordx4 v[82:85], v[6:7], off
	global_load_dwordx4 v[86:89], v[8:9], off
	v_lshl_add_u64 v[2:3], v[2:3], 0, v[108:109]
	global_load_dwordx4 v[90:93], v[4:5], off
	global_load_dwordx4 v[94:97], v[2:3], off

.LBB0_2172:
	v_mov_b32_e32 v34, s25
	ds_read_b32 v138, v34
	s_waitcnt lgkmcnt(0)
	v_ashrrev_i32_e32 v34, 5, v138
	v_lshlrev_b32_e32 v34, 2, v34
	v_add_u32_e32 v34, 0x11200, v34
	v_add_u32_e32 v35, v34, v168
	ds_read2_b32 v[36:37], v35 offset1:4
	ds_read2_b32 v[38:39], v35 offset0:8 offset1:12
	v_lshlrev_b32_e64 v139, v138, 1
	s_waitcnt lgkmcnt(0)
	v_or3_b32 v35, v37, v36, v38
	v_bitop3_b32 v35, v35, v139, v39 bitop3:0xc8
	v_cmp_ne_u32_e32 vcc, 0, v35
	s_and_saveexec_b64 s[22:23], vcc
	s_cbranch_execz .LBB0_2178
	s_mulk_i32 s21, 0x4800
	v_add_u32_e32 v149, s21, v156
	ds_read_b128 v[36:39], v149
	v_add_u32_e32 v34, v34, v172
	ds_read_b32 v151, v34
	s_waitcnt lgkmcnt(1)
	v_mfma_f32_32x32x16_bf16 v[50:65], v[36:39], v[78:81], 0
	ds_read_b128 v[34:37], v149 offset:32
	ds_read_b128 v[38:41], v149 offset:64
	s_waitcnt lgkmcnt(2)
	v_and_b32_e32 v139, v151, v139
	v_cmp_ne_u32_e32 vcc, 0, v139
	s_waitcnt lgkmcnt(1)
	v_mfma_f32_32x32x16_bf16 v[50:65], v[34:37], v[66:69], v[50:65]
	s_waitcnt lgkmcnt(0)
	v_mfma_f32_32x32x16_bf16 v[50:65], v[38:41], v[70:73], v[50:65]
	ds_read_b128 v[34:37], v149 offset:96
	ds_read_b128 v[38:41], v149 offset:4608
	ds_read_b128 v[140:143], v149 offset:4640
	ds_read_b128 v[144:147], v149 offset:4672
	s_waitcnt lgkmcnt(3)
	v_mfma_f32_32x32x16_bf16 v[50:65], v[34:37], v[74:77], v[50:65]
	s_waitcnt lgkmcnt(2)
	v_mfma_f32_32x32x16_bf16 v[34:49], v[38:41], v[78:81], 0
	s_waitcnt lgkmcnt(1)
	v_mfma_f32_32x32x16_bf16 v[34:49], v[140:143], v[66:69], v[34:49]
	ds_read_b128 v[140:143], v149 offset:4704
	s_waitcnt lgkmcnt(1)
	v_mfma_f32_32x32x16_bf16 v[34:49], v[144:147], v[70:73], v[34:49]
	v_cndmask_b32_e32 v144, v213, v100, vcc
	s_waitcnt lgkmcnt(0)
	v_mfma_f32_32x32x16_bf16 v[34:49], v[140:143], v[74:77], v[34:49]
	v_lshl_or_b32 v138, v138, 6, v157
	v_sub_u32_e32 v139, v132, v138
	v_cmp_lt_i32_e32 vcc, 26, v139
	v_fma_f32 v50, v50, s48, v144
	v_fma_f32 v51, v51, s48, v144
	v_fma_f32 v52, v52, s48, v144
	v_fma_f32 v53, v53, s48, v144
	v_fma_f32 v54, v54, s48, v144
	v_fma_f32 v55, v55, s48, v144
	v_fma_f32 v56, v56, s48, v144
	v_fma_f32 v57, v57, s48, v144
	v_fma_f32 v58, v58, s48, v144
	v_fma_f32 v59, v59, s48, v144
	v_fma_f32 v60, v60, s48, v144
	v_fma_f32 v61, v61, s48, v144
	v_fma_f32 v62, v62, s48, v144
	v_fma_f32 v63, v63, s48, v144
	s_cmp_eq_u64 vcc, exec
	v_fma_f32 v64, v64, s48, v144
	v_fma_f32 v65, v65, s48, v144
	s_cbranch_scc1 .LBB0_2175
	v_cmp_lt_i32_e64 s[20:21], -1, v139
	v_cndmask_b32_e32 v65, v213, v65, vcc
	s_nop 0
	v_cndmask_b32_e64 v50, v213, v50, s[20:21]
	v_cmp_lt_i32_e64 s[20:21], 0, v139
	s_nop 1
	v_cndmask_b32_e64 v51, v213, v51, s[20:21]
	v_cmp_lt_i32_e64 s[20:21], 1, v139
	s_nop 1
	v_cndmask_b32_e64 v52, v213, v52, s[20:21]
	v_cmp_lt_i32_e64 s[20:21], 2, v139
	s_nop 1
	v_cndmask_b32_e64 v53, v213, v53, s[20:21]
	v_cmp_lt_i32_e64 s[20:21], 7, v139
	s_nop 1
	v_cndmask_b32_e64 v54, v213, v54, s[20:21]
	v_cmp_lt_i32_e64 s[20:21], 8, v139
	s_nop 1
	v_cndmask_b32_e64 v55, v213, v55, s[20:21]
	v_cmp_lt_i32_e64 s[20:21], 9, v139
	s_nop 1
	v_cndmask_b32_e64 v56, v213, v56, s[20:21]
	v_cmp_lt_i32_e64 s[20:21], 10, v139
	s_nop 1
	v_cndmask_b32_e64 v57, v213, v57, s[20:21]
	v_cmp_lt_i32_e64 s[20:21], 15, v139
	s_nop 1
	v_cndmask_b32_e64 v58, v213, v58, s[20:21]
	v_cmp_lt_i32_e64 s[20:21], 16, v139
	s_nop 1
	v_cndmask_b32_e64 v59, v213, v59, s[20:21]
	v_cmp_lt_i32_e64 s[20:21], 17, v139
	s_nop 1
	v_cndmask_b32_e64 v60, v213, v60, s[20:21]
	v_cmp_lt_i32_e64 s[20:21], 18, v139
	s_nop 1
	v_cndmask_b32_e64 v61, v213, v61, s[20:21]
	v_cmp_lt_i32_e64 s[20:21], 23, v139
	s_nop 1
	v_cndmask_b32_e64 v62, v213, v62, s[20:21]
	v_cmp_lt_i32_e64 s[20:21], 24, v139
	s_nop 1
	v_cndmask_b32_e64 v63, v213, v63, s[20:21]
	v_cmp_lt_i32_e64 s[20:21], 25, v139
	s_nop 1
	v_cndmask_b32_e64 v64, v213, v64, s[20:21]
.LBB0_2175:
	v_sub_u32_e32 v151, v133, v138
	v_mov_b32_e32 v145, v144
	v_cmp_lt_i32_e32 vcc, 26, v151
	v_fma_f32 v146, v34, s48, v144
	v_fma_f32 v147, v35, s48, v145
	v_fma_f32 v142, v36, s48, v144
	v_fma_f32 v143, v37, s48, v145
	v_fma_f32 v140, v38, s48, v144
	v_fma_f32 v141, v39, s48, v145
	v_fma_f32 v138, v40, s48, v144
	v_fma_f32 v139, v41, s48, v145
	v_fma_f32 v40, v42, s48, v144
	v_fma_f32 v41, v43, s48, v145
	v_fma_f32 v36, v44, s48, v144
	v_fma_f32 v37, v45, s48, v145
	v_fma_f32 v34, v46, s48, v144
	v_fma_f32 v35, v47, s48, v145
	s_cmp_eq_u64 vcc, exec
	v_fma_f32 v38, v48, s48, v144
	v_fma_f32 v39, v49, s48, v145
	s_cbranch_scc1 .LBB0_2177
	v_cmp_lt_i32_e64 s[20:21], -1, v151
	v_cndmask_b32_e32 v39, v213, v39, vcc
	s_nop 0
	v_cndmask_b32_e64 v146, v213, v146, s[20:21]
	v_cmp_lt_i32_e64 s[20:21], 0, v151
	s_nop 1
	v_cndmask_b32_e64 v147, v213, v147, s[20:21]
	v_cmp_lt_i32_e64 s[20:21], 1, v151
	s_nop 1
	v_cndmask_b32_e64 v142, v213, v142, s[20:21]
	v_cmp_lt_i32_e64 s[20:21], 2, v151
	s_nop 1
	v_cndmask_b32_e64 v143, v213, v143, s[20:21]
	v_cmp_lt_i32_e64 s[20:21], 7, v151
	s_nop 1
	v_cndmask_b32_e64 v140, v213, v140, s[20:21]
	v_cmp_lt_i32_e64 s[20:21], 8, v151
	s_nop 1
	v_cndmask_b32_e64 v141, v213, v141, s[20:21]
	v_cmp_lt_i32_e64 s[20:21], 9, v151
	s_nop 1
	v_cndmask_b32_e64 v138, v213, v138, s[20:21]
	v_cmp_lt_i32_e64 s[20:21], 10, v151
	s_nop 1
	v_cndmask_b32_e64 v139, v213, v139, s[20:21]
	v_cmp_lt_i32_e64 s[20:21], 15, v151
	s_nop 1
	v_cndmask_b32_e64 v40, v213, v40, s[20:21]
	v_cmp_lt_i32_e64 s[20:21], 16, v151
	s_nop 1
	v_cndmask_b32_e64 v41, v213, v41, s[20:21]
	v_cmp_lt_i32_e64 s[20:21], 17, v151
	s_nop 1
	v_cndmask_b32_e64 v36, v213, v36, s[20:21]
	v_cmp_lt_i32_e64 s[20:21], 18, v151
	s_nop 1
	v_cndmask_b32_e64 v37, v213, v37, s[20:21]
	v_cmp_lt_i32_e64 s[20:21], 23, v151
	s_nop 1
	v_cndmask_b32_e64 v34, v213, v34, s[20:21]
	v_cmp_lt_i32_e64 s[20:21], 24, v151
	s_nop 1
	v_cndmask_b32_e64 v35, v213, v35, s[20:21]
	v_cmp_lt_i32_e64 s[20:21], 25, v151
	s_nop 1
	v_cndmask_b32_e64 v38, v213, v38, s[20:21]

.LBB0_2182:
	global_load_dword v130, v[130:131], off offset:64
	ds_bpermute_b32 v131, v158, v129
	s_sub_i32 s20, 0x1df1, s70
	s_max_i32 s20, s20, 0
	s_lshr_b32 s38, s20, 6
	v_mov_b32_e32 v65, 0
	s_waitcnt lgkmcnt(0)
	v_add_f32_e32 v129, v129, v131
	s_sub_i32 s25, s72, s38
	v_mov_b32_e32 v64, v65
	v_mov_b32_e32 v63, v65
	v_mov_b32_e32 v62, v65
	v_mov_b32_e32 v61, v65
	v_mov_b32_e32 v60, v65
	v_mov_b32_e32 v59, v65
	v_mov_b32_e32 v58, v65
	v_mov_b32_e32 v57, v65
	v_mov_b32_e32 v56, v65
	v_mov_b32_e32 v55, v65
	v_mov_b32_e32 v54, v65
	v_mov_b32_e32 v53, v65
	v_mov_b32_e32 v52, v65
	v_mov_b32_e32 v51, v65
	v_mov_b32_e32 v50, v65
	v_mov_b32_e32 v49, v65
	v_mov_b32_e32 v48, v65
	v_mov_b32_e32 v47, v65
	v_mov_b32_e32 v46, v65
	v_mov_b32_e32 v45, v65
	v_mov_b32_e32 v44, v65
	v_mov_b32_e32 v43, v65
	v_mov_b32_e32 v42, v65
	v_mov_b32_e32 v41, v65
	v_mov_b32_e32 v40, v65
	v_mov_b32_e32 v39, v65
	v_mov_b32_e32 v38, v65
	v_mov_b32_e32 v37, v65
	v_mov_b32_e32 v36, v65
	v_mov_b32_e32 v35, v65
	v_mov_b32_e32 v34, v65
	s_cmp_lt_i32 s25, 0
	s_waitcnt vmcnt(0)
	v_div_scale_f32 v131, s[20:21], v129, v129, v130
	v_rcp_f32_e32 v132, v131
	v_div_scale_f32 v133, vcc, v130, v129, v130
	v_fma_f32 v150, -v131, v132, 1.0
	v_fmac_f32_e32 v132, v150, v132
	v_mul_f32_e32 v150, v133, v132
	v_fma_f32 v151, -v131, v150, v133
	v_fmac_f32_e32 v150, v151, v132
	v_fma_f32 v131, -v131, v150, v133
	v_div_fmas_f32 v131, v131, v132, v150
	v_div_fixup_f32 v232, v131, v129, v130
	v_fma_f32 v150, v18, v232, v82
	v_fma_f32 v151, v19, v232, v83
	v_fma_f32 v132, v20, v232, v84
	v_fma_f32 v133, v21, v232, v85
	v_fma_f32 v130, v22, v232, v86
	v_fma_f32 v131, v23, v232, v87
	v_fma_f32 v84, v24, v232, v88
	v_fma_f32 v85, v25, v232, v89
	v_fma_f32 v86, v26, v232, v90
	v_fma_f32 v87, v27, v232, v91
	v_fma_f32 v82, v28, v232, v92
	v_fma_f32 v83, v29, v232, v93
	v_fma_f32 v28, v30, v232, v94
	v_fma_f32 v29, v31, v232, v95
	v_fma_f32 v26, v32, v232, v96
	v_fma_f32 v27, v33, v232, v97
	v_fma_f32 v24, v2, v232, v134
	v_fma_f32 v25, v3, v232, v135
	v_fma_f32 v22, v4, v232, v136
	v_fma_f32 v23, v5, v232, v137
	v_fma_f32 v20, v6, v232, v138
	v_fma_f32 v21, v7, v232, v139
	v_fma_f32 v18, v8, v232, v140
	v_fma_f32 v19, v9, v232, v141
	v_fma_f32 v8, v10, v232, v142
	v_fma_f32 v9, v11, v232, v143
	v_fma_f32 v6, v12, v232, v144
	v_fma_f32 v7, v13, v232, v145
	v_fma_f32 v4, v14, v232, v146
	v_fma_f32 v5, v15, v232, v147
	v_fma_f32 v2, v16, v232, v148
	v_fma_f32 v3, v17, v232, v149
	v_mov_b32_e32 v129, v65
	ds_write2_b32 v215, v150, v151 offset1:1
	ds_write2_b32 v216, v132, v133 offset1:1
	ds_write2_b32 v217, v130, v131 offset1:1
	ds_write2_b32 v218, v84, v85 offset1:1
	ds_write2_b32 v219, v86, v87 offset1:1
	ds_write2_b32 v220, v82, v83 offset1:1
	ds_write2_b32 v221, v28, v29 offset1:1
	ds_write2_b32 v222, v26, v27 offset1:1
	ds_write2_b32 v223, v24, v25 offset1:1
	ds_write2_b32 v224, v22, v23 offset1:1
	ds_write2_b32 v225, v20, v21 offset1:1
	ds_write2_b32 v226, v18, v19 offset1:1
	ds_write2_b32 v227, v8, v9 offset1:1
	ds_write2_b32 v228, v6, v7 offset1:1
	ds_write2_b32 v229, v4, v5 offset1:1
	ds_write2_b32 v230, v2, v3 offset1:1
	s_cbranch_scc1 .LBB0_2196
	s_lshl_b32 s22, s24, 1
	v_readlane_b32 s20, v231, 26
	s_add_u32 s20, s20, s22
	v_readlane_b32 s21, v231, 27
	s_addc_u32 s21, s21, 0
	v_readlane_b32 s28, v231, 28
	v_readlane_b32 s29, v231, 29
	s_add_u32 s22, s28, s22
	s_addc_u32 s23, s29, 0
	s_lshl_b64 s[28:29], s[38:39], 13
	s_add_u32 s30, s20, s28
	s_addc_u32 s31, s21, s29
	s_add_u32 s28, s22, s28
	v_mov_b32_e32 v129, v105
	s_addc_u32 s29, s23, s29
	v_lshl_add_u64 v[2:3], s[30:31], 0, v[128:129]
	v_lshl_add_u64 v[4:5], v[2:3], 0, v[106:107]
	v_lshl_add_u64 v[6:7], s[28:29], 0, v[128:129]
	v_lshl_add_u64 v[2:3], v[2:3], 0, v[108:109]
	v_lshl_add_u64 v[8:9], v[6:7], 0, v[106:107]
	global_load_dwordx4 v[82:85], v[4:5], off
	global_load_dwordx4 v[86:89], v[8:9], off
	v_lshl_add_u64 v[4:5], v[6:7], 0, v[108:109]
	global_load_dwordx4 v[90:93], v[2:3], off
	global_load_dwordx4 v[94:97], v[4:5], off
	s_cmp_eq_u32 s72, s38
	s_waitcnt vmcnt(3)
	ds_write_b128 v153, v[82:85]
	s_waitcnt vmcnt(2)
	ds_write_b128 v153, v[86:89] offset:9216
	s_waitcnt vmcnt(1)
	ds_write_b128 v155, v[90:93]
	s_waitcnt vmcnt(0)
	ds_write_b128 v155, v[94:97] offset:9216
	s_cbranch_scc1 .LBB0_2185
	s_add_i32 s38, s38, 1
	s_lshl_b64 s[28:29], s[38:39], 13
	s_add_u32 s30, s20, s28
	s_addc_u32 s31, s21, s29
	s_add_u32 s28, s22, s28
	s_addc_u32 s29, s23, s29
	v_lshl_add_u64 v[2:3], s[30:31], 0, v[128:129]
	v_lshl_add_u64 v[4:5], v[2:3], 0, v[106:107]
	v_lshl_add_u64 v[6:7], s[28:29], 0, v[128:129]
	v_lshl_add_u64 v[2:3], v[2:3], 0, v[108:109]
	v_lshl_add_u64 v[8:9], v[6:7], 0, v[106:107]
	global_load_dwordx4 v[82:85], v[4:5], off
	global_load_dwordx4 v[86:89], v[8:9], off
	v_lshl_add_u64 v[4:5], v[6:7], 0, v[108:109]
	global_load_dwordx4 v[90:93], v[2:3], off
	global_load_dwordx4 v[94:97], v[4:5], off

.LBB0_2190:
	s_mulk_i32 s21, 0x4800
	v_add_u32_e32 v143, s21, v156
	ds_read_b128 v[2:5], v143
	ds_read_b128 v[6:9], v143 offset:32
	s_waitcnt lgkmcnt(1)
	v_mfma_f32_32x32x16_bf16 v[18:33], v[2:5], v[78:81], 0
	s_waitcnt lgkmcnt(0)
	v_mfma_f32_32x32x16_bf16 v[18:33], v[6:9], v[66:69], v[18:33]
	ds_read_b128 v[2:5], v143 offset:64
	ds_read_b128 v[6:9], v143 offset:96
	s_waitcnt lgkmcnt(1)
	v_mfma_f32_32x32x16_bf16 v[18:33], v[2:5], v[70:73], v[18:33]
	ds_read_b128 v[2:5], v143 offset:4608
	ds_read_b128 v[134:137], v143 offset:4640
	s_waitcnt lgkmcnt(2)
	v_mfma_f32_32x32x16_bf16 v[18:33], v[6:9], v[74:77], v[18:33]
	s_waitcnt lgkmcnt(1)
	v_mfma_f32_32x32x16_bf16 v[2:17], v[2:5], v[78:81], 0
	s_waitcnt lgkmcnt(0)
	v_mfma_f32_32x32x16_bf16 v[2:17], v[134:137], v[66:69], v[2:17]
	ds_read_b128 v[134:137], v143 offset:4672
	ds_read_b128 v[138:141], v143 offset:4704
	s_waitcnt lgkmcnt(1)
	v_mfma_f32_32x32x16_bf16 v[2:17], v[134:137], v[70:73], v[2:17]
	s_waitcnt lgkmcnt(0)
	v_mfma_f32_32x32x16_bf16 v[2:17], v[138:141], v[74:77], v[2:17]
	v_add_u32_e32 v134, 0x206, v142
	v_cmp_gt_u32_e32 vcc, s51, v134
	v_fma_f32 v18, v18, s48, v100
	v_fma_f32 v19, v19, s48, v101
	v_fma_f32 v20, v20, s48, v100
	v_fma_f32 v21, v21, s48, v101
	v_fma_f32 v22, v22, s48, v100
	v_fma_f32 v23, v23, s48, v101
	v_fma_f32 v24, v24, s48, v100
	v_fma_f32 v25, v25, s48, v101
	v_fma_f32 v26, v26, s48, v100
	v_fma_f32 v27, v27, s48, v101
	v_fma_f32 v28, v28, s48, v100
	v_fma_f32 v29, v29, s48, v101
	v_fma_f32 v30, v30, s48, v100
	v_fma_f32 v31, v31, s48, v101
	s_cmp_eq_u64 vcc, exec
	v_fma_f32 v32, v32, s48, v100
	v_fma_f32 v33, v33, s48, v101
	s_cbranch_scc1 .LBB0_2192
	v_add_u32_e32 v134, 0x221, v142
	v_add_u32_e32 v135, 32, v142
	v_cmp_gt_u32_e32 vcc, s50, v134
	v_add_u32_e32 v134, 30, v142
	s_nop 0
	v_cndmask_b32_e32 v18, v213, v18, vcc
	v_cmp_lt_u32_e32 vcc, s64, v135
	v_add_u32_e32 v135, 31, v142
	s_nop 0
	v_cndmask_b32_e32 v19, v213, v19, vcc
	v_cmp_lt_u32_e32 vcc, s64, v135
	v_add_u32_e32 v135, 25, v142
	s_nop 0
	v_cndmask_b32_e32 v20, v213, v20, vcc
	v_cmp_lt_u32_e32 vcc, s64, v134
	v_add_u32_e32 v134, 24, v142
	s_nop 0
	v_cndmask_b32_e32 v21, v213, v21, vcc
	v_cmp_lt_u32_e32 vcc, s64, v135
	v_add_u32_e32 v135, 23, v142
	s_nop 0
	v_cndmask_b32_e32 v22, v213, v22, vcc
	v_cmp_lt_u32_e32 vcc, s64, v134
	v_add_u32_e32 v134, 22, v142
	s_nop 0
	v_cndmask_b32_e32 v23, v213, v23, vcc
	v_cmp_lt_u32_e32 vcc, s64, v135
	v_add_u32_e32 v135, 17, v142
	s_nop 0
	v_cndmask_b32_e32 v24, v213, v24, vcc
	v_cmp_lt_u32_e32 vcc, s64, v134
	v_add_u32_e32 v134, 16, v142
	s_nop 0
	v_cndmask_b32_e32 v25, v213, v25, vcc
	v_cmp_lt_u32_e32 vcc, s64, v135
	v_add_u32_e32 v135, 15, v142
	s_nop 0
	v_cndmask_b32_e32 v26, v213, v26, vcc
	v_cmp_lt_u32_e32 vcc, s64, v134
	v_add_u32_e32 v134, 14, v142
	s_nop 0
	v_cndmask_b32_e32 v27, v213, v27, vcc
	v_cmp_lt_u32_e32 vcc, s64, v135
	v_add_u32_e32 v135, 9, v142
	s_nop 0
	v_cndmask_b32_e32 v28, v213, v28, vcc
	v_cmp_lt_u32_e32 vcc, s64, v134
	v_add_u32_e32 v134, 8, v142
	s_nop 0
	v_cndmask_b32_e32 v29, v213, v29, vcc
	v_cmp_lt_u32_e32 vcc, s64, v135
	v_add_u32_e32 v135, 7, v142
	s_nop 0
	v_cndmask_b32_e32 v30, v213, v30, vcc
	v_cmp_lt_u32_e32 vcc, s64, v134
	v_add_u32_e32 v134, 6, v142
	s_nop 0
	v_cndmask_b32_e32 v31, v213, v31, vcc
	v_cmp_lt_u32_e32 vcc, s64, v135
	s_nop 1
	v_cndmask_b32_e32 v32, v213, v32, vcc
	v_cmp_lt_u32_e32 vcc, s64, v134
	s_nop 1
	v_cndmask_b32_e32 v33, v213, v33, vcc
.LBB0_2192:
	v_add_u32_e32 v144, 0x1e6, v142
	v_cmp_gt_u32_e32 vcc, s51, v144
	v_fma_f32 v140, v2, s48, v100
	v_fma_f32 v141, v3, s48, v101
	v_fma_f32 v138, v4, s48, v100
	v_fma_f32 v139, v5, s48, v101
	v_fma_f32 v136, v6, s48, v100
	v_fma_f32 v137, v7, s48, v101
	v_fma_f32 v134, v8, s48, v100
	v_fma_f32 v135, v9, s48, v101
	v_fma_f32 v8, v10, s48, v100
	v_fma_f32 v9, v11, s48, v101
	v_fma_f32 v4, v12, s48, v100
	v_fma_f32 v5, v13, s48, v101
	v_fma_f32 v2, v14, s48, v100
	v_fma_f32 v3, v15, s48, v101
	s_cmp_eq_u64 vcc, exec
	v_fma_f32 v6, v16, s48, v100
	v_fma_f32 v7, v17, s48, v101
	s_cbranch_scc1 .LBB0_2194
	v_add_u32_e32 v10, 0x201, v142
	v_cmp_gt_u32_e32 vcc, s50, v10
	v_add_u32_e32 v11, -1, v142
	v_add_u32_e32 v10, -2, v142
	v_cndmask_b32_e32 v140, v213, v140, vcc
	v_cmp_lt_u32_e32 vcc, s64, v142
	s_nop 1
	v_cndmask_b32_e32 v141, v213, v141, vcc
	v_cmp_lt_u32_e32 vcc, s64, v11
	v_add_u32_e32 v11, -7, v142
	s_nop 0
	v_cndmask_b32_e32 v138, v213, v138, vcc
	v_cmp_lt_u32_e32 vcc, s64, v10
	v_add_u32_e32 v10, -8, v142
	s_nop 0
	v_cndmask_b32_e32 v139, v213, v139, vcc
	v_cmp_lt_u32_e32 vcc, s64, v11
	v_add_u32_e32 v11, -9, v142
	s_nop 0
	v_cndmask_b32_e32 v136, v213, v136, vcc
	v_cmp_lt_u32_e32 vcc, s64, v10
	v_add_u32_e32 v10, -10, v142
	s_nop 0
	v_cndmask_b32_e32 v137, v213, v137, vcc
	v_cmp_lt_u32_e32 vcc, s64, v11
	v_add_u32_e32 v11, -15, v142
	s_nop 0
	v_cndmask_b32_e32 v134, v213, v134, vcc
	v_cmp_lt_u32_e32 vcc, s64, v10
	v_add_u32_e32 v10, -16, v142
	s_nop 0
	v_cndmask_b32_e32 v135, v213, v135, vcc
	v_cmp_lt_u32_e32 vcc, s64, v11
	v_subrev_u32_e32 v11, 17, v142
	s_nop 0
	v_cndmask_b32_e32 v8, v213, v8, vcc
	v_cmp_lt_u32_e32 vcc, s64, v10
	v_subrev_u32_e32 v10, 18, v142
	s_nop 0
	v_cndmask_b32_e32 v9, v213, v9, vcc
	v_cmp_lt_u32_e32 vcc, s64, v11
	v_subrev_u32_e32 v11, 23, v142
	s_nop 0
	v_cndmask_b32_e32 v4, v213, v4, vcc
	v_cmp_lt_u32_e32 vcc, s64, v10
	v_subrev_u32_e32 v10, 24, v142
	s_nop 0
	v_cndmask_b32_e32 v5, v213, v5, vcc
	v_cmp_lt_u32_e32 vcc, s64, v11
	v_subrev_u32_e32 v11, 25, v142
	s_nop 0
	v_cndmask_b32_e32 v2, v213, v2, vcc
	v_cmp_lt_u32_e32 vcc, s64, v10
	v_subrev_u32_e32 v10, 26, v142
	s_nop 0
	v_cndmask_b32_e32 v3, v213, v3, vcc
	v_cmp_lt_u32_e32 vcc, s64, v11
	s_nop 1
	v_cndmask_b32_e32 v6, v213, v6, vcc
	v_cmp_lt_u32_e32 vcc, s64, v10
	s_nop 1
	v_cndmask_b32_e32 v7, v213, v7, vcc

.LBB0_2196:
	ds_bpermute_b32 v10, v158, v129
	v_subrev_u32_e32 v11, s68, v189
	s_waitcnt lgkmcnt(0)
	v_add_f32_e32 v12, v129, v10
	v_div_scale_f32 v13, s[20:21], v12, v12, v104
	v_rcp_f32_e32 v14, v13
	v_lshlrev_b32_e32 v10, 6, v11
	v_div_scale_f32 v11, vcc, v104, v12, v104
	v_fma_f32 v15, -v13, v14, 1.0
	v_fmac_f32_e32 v14, v15, v14
	v_mul_f32_e32 v15, v11, v14
	v_fma_f32 v16, -v13, v15, v11
	v_fmac_f32_e32 v15, v16, v14
	v_fma_f32 v11, -v13, v15, v11
	v_div_fmas_f32 v11, v11, v14, v15
	v_div_fixup_f32 v12, v11, v12, v104
	v_fma_f32 v14, v50, v12, v150
	v_fma_f32 v15, v51, v12, v151
	v_fma_f32 v16, v52, v12, v132
	v_fma_f32 v17, v53, v12, v133
	ds_write2_b32 v215, v14, v15 offset1:1
	ds_write2_b32 v216, v16, v17 offset1:1
	v_fma_f32 v14, v54, v12, v130
	v_fma_f32 v15, v55, v12, v131
	ds_write2_b32 v217, v14, v15 offset1:1
	v_fma_f32 v14, v56, v12, v84
	v_fma_f32 v15, v57, v12, v85
	ds_write2_b32 v218, v14, v15 offset1:1
	v_fma_f32 v14, v58, v12, v86
	v_fma_f32 v15, v59, v12, v87
	ds_write2_b32 v219, v14, v15 offset1:1
	v_fma_f32 v14, v60, v12, v82
	v_fma_f32 v15, v61, v12, v83
	s_add_i32 s20, s54, s67
	ds_write2_b32 v220, v14, v15 offset1:1
	v_fma_f32 v14, v62, v12, v28
	v_fma_f32 v15, v63, v12, v29
	v_fma_f32 v2, v48, v12, v2
	v_fma_f32 v3, v49, v12, v3
	s_ashr_i32 s20, s20, 3
	ds_write2_b32 v221, v14, v15 offset1:1
	v_fma_f32 v14, v64, v12, v26
	v_fma_f32 v15, v65, v12, v27
	ds_write2_b32 v230, v2, v3 offset1:1
	v_and_or_b32 v2, s20, -16, v164
	ds_write2_b32 v222, v14, v15 offset1:1
	v_fma_f32 v14, v34, v12, v24
	v_fma_f32 v15, v35, v12, v25
	v_or_b32_e32 v2, s55, v2
	ds_write2_b32 v223, v14, v15 offset1:1
	v_fma_f32 v14, v36, v12, v22
	v_fma_f32 v15, v37, v12, v23
	v_ashrrev_i32_e32 v3, 31, v2
	v_readlane_b32 s20, v231, 24
	ds_write2_b32 v224, v14, v15 offset1:1
	v_fma_f32 v14, v38, v12, v20
	v_fma_f32 v15, v39, v12, v21
	v_fma_f32 v6, v44, v12, v6
	v_fma_f32 v7, v45, v12, v7
	v_fma_f32 v4, v46, v12, v4
	v_fma_f32 v5, v47, v12, v5
	v_lshlrev_b64 v[2:3], 14, v[2:3]
	v_readlane_b32 s21, v231, 25
	ds_write2_b32 v225, v14, v15 offset1:1
	v_fma_f32 v14, v40, v12, v18
	v_fma_f32 v15, v41, v12, v19
	v_fma_f32 v8, v42, v12, v8
	v_fma_f32 v9, v43, v12, v9
	ds_write2_b32 v228, v6, v7 offset1:1
	ds_write2_b32 v229, v4, v5 offset1:1
	v_lshl_add_u64 v[2:3], s[20:21], 0, v[2:3]
	s_mov_b64 s[20:21], 0
	v_mov_b32_e32 v4, v190
	v_mov_b32_e32 v5, v174
	v_mov_b32_e32 v6, v188
	ds_write2_b32 v226, v14, v15 offset1:1
	ds_write2_b32 v227, v8, v9 offset1:1
	s_waitcnt lgkmcnt(0)
	s_barrier

.LBB0_2396:
	s_waitcnt lgkmcnt(1)
	v_mfma_f32_32x32x16_bf16 v[50:65], v[102:105], v[106:109], v[50:65]
	s_waitcnt vmcnt(4)
	ds_write_b128 v140, v[66:69] offset:36864
	s_waitcnt vmcnt(3)
	ds_write_b128 v140, v[74:77] offset:55296
	v_mfma_f32_32x32x16_bf16 v[34:49], v[94:97], v[106:109], v[34:49]
	ds_write_b128 v142, v[70:73] offset:36864
	s_waitcnt vmcnt(2)
	ds_write_b128 v142, v[82:85] offset:55296
	s_waitcnt lgkmcnt(4)
	v_mfma_f32_32x32x16_bf16 v[18:33], v[102:105], v[98:101], v[18:33]
	ds_write_b128 v144, v[78:81] offset:36864
	s_waitcnt vmcnt(1)
	ds_write_b128 v144, v[86:89] offset:55296
	v_mfma_f32_32x32x16_bf16 v[2:17], v[94:97], v[98:101], v[2:17]
	ds_write_b128 v146, v[90:93] offset:36864
	s_waitcnt vmcnt(0)
	ds_write_b128 v146, v[110:113] offset:55296
	ds_read_b128 v[66:69], v151 offset:23072
	ds_read_b128 v[70:73], v152 offset:4640
	s_waitcnt lgkmcnt(0)
	v_mfma_f32_32x32x16_bf16 v[2:17], v[66:69], v[70:73], v[2:17]
	ds_read_b128 v[74:77], v151 offset:18464
	ds_read_b128 v[78:81], v151 offset:18496
	s_waitcnt lgkmcnt(1)
	v_mfma_f32_32x32x16_bf16 v[18:33], v[74:77], v[70:73], v[18:33]
	ds_read_b128 v[70:73], v152 offset:32
	ds_read_b128 v[82:85], v152 offset:64
	s_waitcnt lgkmcnt(1)
	v_mfma_f32_32x32x16_bf16 v[50:65], v[74:77], v[70:73], v[50:65]
	ds_read_b128 v[74:77], v151 offset:23104
	ds_read_b128 v[86:89], v152 offset:4672
	v_mfma_f32_32x32x16_bf16 v[34:49], v[66:69], v[70:73], v[34:49]
	ds_read_b128 v[66:69], v151 offset:18528
	ds_read_b128 v[70:73], v152 offset:96
	s_waitcnt lgkmcnt(4)
	v_mfma_f32_32x32x16_bf16 v[50:65], v[78:81], v[82:85], v[50:65]
	ds_read_b128 v[90:93], v151 offset:23136
	ds_read_b128 v[94:97], v152 offset:4704
	s_waitcnt lgkmcnt(0)
	s_barrier
	v_mfma_f32_32x32x16_bf16 v[34:49], v[74:77], v[82:85], v[34:49]
	ds_read_b128 v[82:85], v168 offset:55296
	ds_read_b128 v[98:101], v169 offset:36864
	v_mfma_f32_32x32x16_bf16 v[18:33], v[78:81], v[86:89], v[18:33]
	ds_read_b128 v[78:81], v168 offset:59904
	ds_read_b128 v[102:105], v169 offset:41472
	v_mfma_f32_32x32x16_bf16 v[2:17], v[74:77], v[86:89], v[2:17]
	ds_read_b128 v[74:77], v151 offset:59936
	ds_read_b128 v[86:89], v152 offset:41504
	v_mfma_f32_32x32x16_bf16 v[50:65], v[66:69], v[70:73], v[50:65]
	ds_read_b128 v[106:109], v151 offset:55328
	ds_read_b128 v[110:113], v151 offset:55360
	v_mfma_f32_32x32x16_bf16 v[34:49], v[90:93], v[70:73], v[34:49]
	ds_read_b128 v[70:73], v152 offset:36896
	ds_read_b128 v[128:131], v152 offset:36928
	v_mfma_f32_32x32x16_bf16 v[18:33], v[66:69], v[94:97], v[18:33]
	ds_read_b128 v[66:69], v151 offset:59968
	ds_read_b128 v[132:135], v152 offset:41536
	v_mfma_f32_32x32x16_bf16 v[2:17], v[90:93], v[94:97], v[2:17]
	ds_read_b128 v[90:93], v151 offset:55392
	ds_read_b128 v[94:97], v152 offset:36960
	s_waitcnt lgkmcnt(12)
	v_mfma_f32_32x32x16_bf16 v[50:65], v[82:85], v[98:101], v[50:65]
	ds_read_b128 v[172:175], v151 offset:60000
	ds_read_b128 v[176:179], v152 offset:41568
	s_waitcnt lgkmcnt(0)
	s_barrier
	s_barrier
	v_mfma_f32_32x32x16_bf16 v[34:49], v[78:81], v[98:101], v[34:49]
	v_mfma_f32_32x32x16_bf16 v[18:33], v[82:85], v[102:105], v[18:33]
	v_mfma_f32_32x32x16_bf16 v[2:17], v[78:81], v[102:105], v[2:17]
	v_mfma_f32_32x32x16_bf16 v[50:65], v[106:109], v[70:73], v[50:65]
	v_mfma_f32_32x32x16_bf16 v[34:49], v[74:77], v[70:73], v[34:49]
	v_mfma_f32_32x32x16_bf16 v[18:33], v[106:109], v[86:89], v[18:33]
	v_mfma_f32_32x32x16_bf16 v[2:17], v[74:77], v[86:89], v[2:17]
	v_mfma_f32_32x32x16_bf16 v[50:65], v[110:113], v[128:131], v[50:65]
	v_mfma_f32_32x32x16_bf16 v[34:49], v[66:69], v[128:131], v[34:49]
	v_mfma_f32_32x32x16_bf16 v[18:33], v[110:113], v[132:135], v[18:33]
	v_mfma_f32_32x32x16_bf16 v[2:17], v[66:69], v[132:135], v[2:17]
	v_add_u32_e32 v67, s36, v148
	v_cmp_gt_u32_e32 vcc, s26, v67
	v_mov_b32_e32 v66, 0
	v_mov_b32_e32 v68, 0
	v_mfma_f32_32x32x16_bf16 v[50:65], v[90:93], v[94:97], v[50:65]
	v_mfma_f32_32x32x16_bf16 v[34:49], v[172:175], v[94:97], v[34:49]
	v_mfma_f32_32x32x16_bf16 v[18:33], v[90:93], v[176:179], v[18:33]
	v_mfma_f32_32x32x16_bf16 v[2:17], v[172:175], v[176:179], v[2:17]
	s_and_saveexec_b64 s[4:5], vcc
	s_cbranch_execz .LBB0_2398
	v_or_b32_e32 v67, s40, v67
	v_lshlrev_b32_e32 v67, 6, v67
	global_load_dwordx4 v[68:71], v67, s[44:45]
	global_load_dwordx4 v[72:75], v67, s[44:45] offset:16
	global_load_dwordx4 v[76:79], v67, s[44:45] offset:32
	global_load_dwordx4 v[80:83], v67, s[44:45] offset:48
	s_waitcnt vmcnt(3)
	v_mov_b32_e32 v84, v69
	v_mov_b32_e32 v85, v70
	v_mov_b32_e32 v69, v71
	s_waitcnt vmcnt(2)
	v_mov_b32_e32 v70, v73
	v_mov_b32_e32 v71, v74
	v_mov_b32_e32 v73, v75
	v_add_f32_e64 v68, v84, v68
	v_add_f32_e64 v69, v85, v69
	v_add_f32_e64 v70, v70, v72
	v_add_f32_e64 v71, v71, v73
	v_pk_add_f32 v[68:69], v[68:69], v[68:69] op_sel:[0,1] op_sel_hi:[1,0]
	v_pk_add_f32 v[70:71], v[70:71], v[70:71] op_sel:[0,1] op_sel_hi:[1,0]
	s_waitcnt vmcnt(1)
	v_add_f32_e32 v74, v76, v77
	v_add_f32_e32 v76, v78, v79
	s_waitcnt vmcnt(0)
	v_mov_b32_e32 v75, v82
	v_mov_b32_e32 v77, v83
	v_mov_b32_e32 v69, v80
	v_mov_b32_e32 v71, v81
	v_add_f32_e64 v72, v74, v76
	v_add_f32_e64 v73, v75, v77
	v_add_f32_e64 v68, v68, v70
	v_add_f32_e64 v69, v69, v71
	s_nop 0
	v_add_f32_e64 v68, v68, v72
	v_add_f32_e64 v69, v69, v73
	s_nop 0
	v_add_f32_e32 v67, v68, v69
	v_fmamk_f32 v67, v67, 0x3a800000, v170
	v_mul_f32_e32 v68, 0x4b800000, v67
	v_cmp_gt_f32_e32 vcc, s29, v67
	s_nop 1
	v_cndmask_b32_e32 v67, v67, v68, vcc
	v_rsq_f32_e32 v67, v67
	s_nop 0
	v_mul_f32_e32 v68, 0x45800000, v67
	v_cndmask_b32_e32 v68, v67, v68, vcc
.LBB0_2398:
	s_or_b64 exec, exec, s[4:5]
	s_nop 6
	v_mul_f32_e64 v34, v34, v68
	v_mul_f32_e64 v35, v35, v68
	ds_write2_b32 v153, v34, v35 offset0:32 offset1:33
	v_mul_f32_e64 v34, v36, v68
	v_mul_f32_e64 v35, v37, v68
	v_mul_f32_e64 v50, v50, v68
	v_mul_f32_e64 v51, v51, v68
	ds_write2_b32 v153, v34, v35 offset0:34 offset1:35
	v_mul_f32_e64 v34, v38, v68
	v_mul_f32_e64 v35, v39, v68
	ds_write2_b32 v153, v50, v51 offset1:1
	v_mul_f32_e64 v50, v52, v68
	v_mul_f32_e64 v51, v53, v68
	ds_write2_b32 v153, v34, v35 offset0:40 offset1:41
	v_mul_f32_e64 v34, v40, v68
	v_mul_f32_e64 v35, v41, v68
	ds_write2_b32 v153, v50, v51 offset0:2 offset1:3
	v_mul_f32_e64 v50, v54, v68
	v_mul_f32_e64 v51, v55, v68
	ds_write2_b32 v153, v34, v35 offset0:42 offset1:43
	v_mul_f32_e64 v34, v42, v68
	v_mul_f32_e64 v35, v43, v68
	ds_write2_b32 v153, v50, v51 offset0:8 offset1:9
	v_mul_f32_e64 v50, v56, v68
	v_mul_f32_e64 v51, v57, v68
	ds_write2_b32 v153, v34, v35 offset0:48 offset1:49
	v_mul_f32_e64 v34, v44, v68
	v_mul_f32_e64 v35, v45, v68
	ds_write2_b32 v153, v50, v51 offset0:10 offset1:11
	v_mul_f32_e64 v50, v58, v68
	v_mul_f32_e64 v51, v59, v68
	ds_write2_b32 v153, v34, v35 offset0:50 offset1:51
	v_mul_f32_e64 v34, v46, v68
	v_mul_f32_e64 v35, v47, v68
	ds_write2_b32 v153, v50, v51 offset0:16 offset1:17
	v_mul_f32_e64 v50, v60, v68
	v_mul_f32_e64 v51, v61, v68
	ds_write2_b32 v153, v34, v35 offset0:56 offset1:57
	v_mul_f32_e64 v34, v48, v68
	v_mul_f32_e64 v35, v49, v68
	ds_write2_b32 v153, v50, v51 offset0:18 offset1:19
	v_mul_f32_e64 v50, v62, v68
	v_mul_f32_e64 v51, v63, v68
	ds_write2_b32 v153, v34, v35 offset0:58 offset1:59
	v_add_u32_e32 v34, s36, v154
	ds_write2_b32 v153, v50, v51 offset0:24 offset1:25
	v_mul_f32_e64 v50, v64, v68
	v_mul_f32_e64 v51, v65, v68
	v_cmp_gt_u32_e32 vcc, s26, v34
	ds_write2_b32 v153, v50, v51 offset0:26 offset1:27
	s_and_saveexec_b64 s[4:5], vcc
	s_cbranch_execz .LBB0_2400
	v_or_b32_e32 v34, s40, v34
	v_lshlrev_b32_e32 v50, 6, v34
	global_load_dwordx4 v[34:37], v50, s[44:45]
	global_load_dwordx4 v[38:41], v50, s[44:45] offset:16
	global_load_dwordx4 v[42:45], v50, s[44:45] offset:32
	global_load_dwordx4 v[46:49], v50, s[44:45] offset:48
	s_waitcnt vmcnt(3)
	v_mov_b32_e32 v50, v35
	v_mov_b32_e32 v51, v36
	v_mov_b32_e32 v35, v37
	s_waitcnt vmcnt(2)
	v_mov_b32_e32 v36, v39
	v_mov_b32_e32 v37, v40
	v_mov_b32_e32 v39, v41
	v_add_f32_e64 v34, v50, v34
	v_add_f32_e64 v35, v51, v35
	v_add_f32_e64 v36, v36, v38
	v_add_f32_e64 v37, v37, v39
	v_pk_add_f32 v[34:35], v[34:35], v[34:35] op_sel:[0,1] op_sel_hi:[1,0]
	v_pk_add_f32 v[36:37], v[36:37], v[36:37] op_sel:[0,1] op_sel_hi:[1,0]
	s_waitcnt vmcnt(1)
	v_add_f32_e32 v40, v42, v43
	v_add_f32_e32 v42, v44, v45
	s_waitcnt vmcnt(0)
	v_mov_b32_e32 v41, v48
	v_mov_b32_e32 v43, v49
	v_mov_b32_e32 v35, v46
	v_mov_b32_e32 v37, v47
	v_add_f32_e64 v38, v40, v42
	v_add_f32_e64 v39, v41, v43
	v_add_f32_e64 v34, v34, v36
	v_add_f32_e64 v35, v35, v37
	s_nop 0
	v_add_f32_e64 v34, v34, v38
	v_add_f32_e64 v35, v35, v39
	s_nop 0
	v_add_f32_e32 v34, v34, v35
	v_fmamk_f32 v34, v34, 0x3a800000, v170
	v_mul_f32_e32 v35, 0x4b800000, v34
	v_cmp_gt_f32_e32 vcc, s29, v34
	s_nop 1
	v_cndmask_b32_e32 v34, v34, v35, vcc
	v_rsq_f32_e32 v34, v34
	s_nop 0
	v_mul_f32_e32 v35, 0x45800000, v34
	v_cndmask_b32_e32 v66, v34, v35, vcc
.LBB0_2400:
	s_or_b64 exec, exec, s[4:5]
	v_mul_f32_e64 v2, v2, v66
	v_mul_f32_e64 v3, v3, v66
	ds_write2_b32 v155, v2, v3 offset0:32 offset1:33
	v_mul_f32_e64 v2, v4, v66
	v_mul_f32_e64 v3, v5, v66
	ds_write2_b32 v155, v2, v3 offset0:34 offset1:35
	v_mul_f32_e64 v2, v6, v66
	v_mul_f32_e64 v3, v7, v66
	ds_write2_b32 v155, v2, v3 offset0:40 offset1:41
	v_mul_f32_e64 v2, v8, v66
	v_mul_f32_e64 v3, v9, v66
	ds_write2_b32 v155, v2, v3 offset0:42 offset1:43
	v_mul_f32_e64 v2, v10, v66
	v_mul_f32_e64 v3, v11, v66
	ds_write2_b32 v155, v2, v3 offset0:48 offset1:49
	v_mul_f32_e64 v2, v12, v66
	v_mul_f32_e64 v3, v13, v66
	ds_write2_b32 v155, v2, v3 offset0:50 offset1:51
	v_mul_f32_e64 v2, v14, v66
	v_mul_f32_e64 v3, v15, v66
	ds_write2_b32 v155, v2, v3 offset0:56 offset1:57
	v_mul_f32_e64 v2, v16, v66
	v_mul_f32_e64 v3, v17, v66
	v_mul_f32_e64 v18, v18, v66
	v_mul_f32_e64 v19, v19, v66
	ds_write2_b32 v155, v2, v3 offset0:58 offset1:59
	v_lshl_or_b32 v2, s18, 6, v114
	ds_write2_b32 v155, v18, v19 offset1:1
	v_mul_f32_e64 v18, v20, v66
	v_mul_f32_e64 v19, v21, v66
	v_ashrrev_i32_e32 v3, 31, v2
	ds_write2_b32 v155, v18, v19 offset0:2 offset1:3
	v_mul_f32_e64 v18, v22, v66
	v_mul_f32_e64 v19, v23, v66
	v_lshlrev_b64 v[8:9], 2, v[2:3]
	ds_write2_b32 v155, v18, v19 offset0:8 offset1:9
	v_mul_f32_e64 v18, v24, v66
	v_mul_f32_e64 v19, v25, v66
	v_lshl_add_u64 v[10:11], s[14:15], 0, v[8:9]
	ds_write2_b32 v155, v18, v19 offset0:10 offset1:11
	v_mul_f32_e64 v18, v26, v66
	v_mul_f32_e64 v19, v27, v66
	v_add_co_u32_e32 v12, vcc, s28, v10
	ds_write2_b32 v155, v18, v19 offset0:16 offset1:17
	v_mul_f32_e64 v18, v28, v66
	v_mul_f32_e64 v19, v29, v66
	v_addc_co_u32_e32 v13, vcc, 0, v11, vcc
	ds_write2_b32 v155, v18, v19 offset0:18 offset1:19
	v_mul_f32_e64 v18, v30, v66
	v_mul_f32_e64 v19, v31, v66
	v_add_co_u32_e32 v14, vcc, s30, v10
	ds_write2_b32 v155, v18, v19 offset0:24 offset1:25
	v_mul_f32_e64 v18, v32, v66
	v_mul_f32_e64 v19, v33, v66
	v_addc_co_u32_e32 v15, vcc, 0, v11, vcc
	ds_write2_b32 v155, v18, v19 offset0:26 offset1:27
	s_waitcnt lgkmcnt(0)
	s_barrier
	global_load_dword v3, v[10:11], off
	global_load_dword v5, v[12:13], off offset:2048
	global_load_dword v7, v[14:15], off
	v_add_co_u32_e32 v14, vcc, s26, v10
	v_lshl_add_u64 v[12:13], s[16:17], 0, v[8:9]
	s_nop 0
	v_addc_co_u32_e32 v15, vcc, 0, v11, vcc
	v_add_co_u32_e32 v16, vcc, s31, v10
	global_load_dword v9, v[12:13], off
	s_nop 0
	v_addc_co_u32_e32 v17, vcc, 0, v11, vcc
	v_add_co_u32_e32 v10, vcc, s33, v10
	s_mul_i32 s4, s37, 0x7e
	s_nop 0
	v_addc_co_u32_e32 v11, vcc, 0, v11, vcc
	global_load_dword v2, v[14:15], off offset:3072
	global_load_dword v4, v[16:17], off offset:1024
	global_load_dword v6, v[10:11], off offset:3072
	v_add_co_u32_e32 v10, vcc, s26, v12
	s_add_i32 s4, s25, s4
	s_nop 0
	v_addc_co_u32_e32 v11, vcc, 0, v13, vcc
	global_load_dword v8, v[10:11], off offset:3072
	ds_read_b32 v15, v159
	ds_read_b32 v10, v160
	ds_read_b32 v14, v161
	ds_read_b32 v11, v162
	s_mulk_i32 s38, 0x7c
	s_sub_i32 s10, s4, s38
	v_add_lshl_u32 v16, v167, s39, 6
	s_mov_b64 s[4:5], 0
	v_mov_b32_e32 v17, v158
	v_mov_b32_e32 v18, v156
	s_waitcnt vmcnt(0)
	s_add_i32 s63, s10, -2
	s_sub_i32 s64, s26, s36
	v_min_i32_e32 v40, s64, v157
	v_add_u32_e32 v40, s63, v40
	v_lshlrev_b32_e32 v41, 1, v114
	s_mov_b32 s62, 4

.LBB0_2479:
	s_nop 0
	v_or_b32_e32 v9, s27, v6
	v_cndmask_b32_e64 v8, 0, 1, s[10:11]
	v_add_u32_e32 v10, 8, v9
	v_cmp_ne_u32_e32 vcc, 1, v8
	v_lshlrev_b32_e32 v8, 7, v9
	v_add_u32_e32 v11, 16, v9
	v_add_u32_e32 v12, 24, v9
	v_lshrrev_b32_e32 v15, 3, v10
	v_add_u32_e32 v13, 40, v9
	v_add_u32_e32 v14, 48, v9
	v_add_u32_e32 v9, 56, v9
	v_and_b32_e32 v114, 0x2f80, v8
	v_lshlrev_b32_e32 v10, 7, v10
	v_lshrrev_b32_e32 v16, 3, v11
	v_lshlrev_b32_e32 v22, 7, v11
	v_lshrrev_b32_e32 v11, 3, v12
	v_and_b32_e32 v15, 0xffffff0, v15
	v_lshlrev_b32_e32 v23, 7, v12
	v_lshrrev_b32_e32 v12, 3, v13
	v_lshlrev_b32_e32 v24, 7, v13
	v_lshrrev_b32_e32 v13, 3, v14
	v_lshlrev_b32_e32 v25, 7, v14
	v_lshrrev_b32_e32 v14, 3, v9
	v_lshlrev_b32_e32 v26, 7, v9
	v_lshl_add_u64 v[8:9], v[2:3], 0, v[114:115]
	v_and_b32_e32 v114, 0x3f80, v10
	v_and_b32_e32 v16, 0xffffff0, v16
	v_and_b32_e32 v11, 0xffffff0, v11
	v_add_u32_e32 v10, v15, v7
	v_mov_b32_e32 v139, v115
	v_and_b32_e32 v17, 0xffffff0, v12
	v_and_b32_e32 v13, 0xffffff0, v13
	v_and_b32_e32 v19, 0xffffff0, v14
	v_add_u32_e32 v12, v16, v7
	v_add_u32_e32 v14, v11, v7
	v_ashrrev_i32_e32 v11, 31, v10
	v_lshl_add_u64 v[8:9], v[8:9], 0, v[138:139]
	v_add_u32_e32 v18, v13, v7
	v_ashrrev_i32_e32 v13, 31, v12
	v_lshlrev_b64 v[10:11], 14, v[10:11]
	v_add_u32_e32 v16, v17, v7
	global_load_dwordx2 v[40:41], v[8:9], off
	v_ashrrev_i32_e32 v15, 31, v14
	v_add_co_u32_e64 v8, s[2:3], s15, v8
	v_lshlrev_b64 v[12:13], 14, v[12:13]
	v_lshl_add_u64 v[10:11], s[92:93], 0, v[10:11]
	v_addc_co_u32_e64 v9, s[2:3], 0, v9, s[2:3]
	v_ashrrev_i32_e32 v17, 31, v16
	v_lshlrev_b64 v[14:15], 14, v[14:15]
	v_lshl_add_u64 v[12:13], s[92:93], 0, v[12:13]
	v_lshl_add_u64 v[10:11], v[10:11], 0, v[114:115]
	v_and_b32_e32 v114, 0x3f80, v22
	v_add_u32_e32 v20, v19, v7
	v_ashrrev_i32_e32 v19, 31, v18
	global_load_dwordx2 v[42:43], v[8:9], off
	v_lshlrev_b64 v[8:9], 14, v[16:17]
	v_lshl_add_u64 v[14:15], s[92:93], 0, v[14:15]
	v_lshl_add_u64 v[10:11], v[10:11], 0, v[138:139]
	v_lshl_add_u64 v[12:13], v[12:13], 0, v[114:115]
	v_and_b32_e32 v114, 0x3f80, v23
	v_ashrrev_i32_e32 v21, 31, v20
	v_lshlrev_b64 v[16:17], 14, v[18:19]
	v_lshl_add_u64 v[8:9], s[92:93], 0, v[8:9]
	global_load_dwordx2 v[44:45], v[10:11], off
	v_lshl_add_u64 v[10:11], v[12:13], 0, v[138:139]
	v_lshl_add_u64 v[12:13], v[14:15], 0, v[114:115]
	v_and_b32_e32 v114, 0x3f80, v24
	v_lshlrev_b64 v[18:19], 14, v[20:21]
	v_lshl_add_u64 v[16:17], s[92:93], 0, v[16:17]
	global_load_dwordx2 v[46:47], v[10:11], off
	v_lshl_add_u64 v[10:11], v[12:13], 0, v[138:139]
	v_lshl_add_u64 v[8:9], v[8:9], 0, v[114:115]
	v_and_b32_e32 v114, 0x3f80, v25
	v_lshl_add_u64 v[18:19], s[92:93], 0, v[18:19]
	global_load_dwordx2 v[48:49], v[10:11], off
	v_lshl_add_u64 v[8:9], v[8:9], 0, v[138:139]
	v_lshl_add_u64 v[10:11], v[16:17], 0, v[114:115]
	v_and_b32_e32 v114, 0x3f80, v26
	global_load_dwordx2 v[50:51], v[8:9], off
	v_lshl_add_u64 v[8:9], v[10:11], 0, v[138:139]
	v_lshl_add_u64 v[10:11], v[18:19], 0, v[114:115]
	global_load_dwordx2 v[52:53], v[8:9], off
	v_lshl_add_u64 v[8:9], v[10:11], 0, v[138:139]
	global_load_dwordx2 v[54:55], v[8:9], off
	v_or_b32_e32 v70, s27, v1
	v_or_b32_e32 v56, s6, v70
	v_mad_u32_u24 v36, v70, s16, v167
	v_add_lshl_u32 v62, v70, s6, 12
	ds_read_b128 v[8:11], v36
	ds_read_b128 v[12:15], v36 offset:4224
	ds_read_b128 v[16:19], v36 offset:8448
	ds_read_b128 v[20:23], v36 offset:12672
	ds_read_b128 v[24:27], v36 offset:16896
	ds_read_b128 v[28:31], v36 offset:21120
	ds_read_b128 v[32:35], v36 offset:25344
	ds_read_b128 v[36:39], v36 offset:29568
	v_lshlrev_b32_e32 v114, 12, v56
	v_lshl_add_u64 v[56:57], v[4:5], 0, v[114:115]
	v_add_u32_e32 v114, 0x8000, v62
	v_lshl_add_u64 v[58:59], v[4:5], 0, v[114:115]
	v_add_u32_e32 v114, 0x10000, v62
	v_or_b32_e32 v64, s23, v70
	v_lshl_add_u64 v[60:61], v[4:5], 0, v[114:115]
	v_add_u32_e32 v114, 0x18000, v62
	v_lshl_add_u64 v[62:63], v[4:5], 0, v[114:115]
	v_lshlrev_b32_e32 v114, 12, v64
	v_lshl_add_u64 v[64:65], v[4:5], 0, v[114:115]
	v_add_lshl_u32 v114, v70, s24, 12
	v_lshl_add_u64 v[66:67], v[4:5], 0, v[114:115]
	v_add_lshl_u32 v114, v70, s25, 12
	v_lshl_add_u64 v[68:69], v[4:5], 0, v[114:115]
	v_add_lshl_u32 v114, v70, s26, 12
	s_mov_b32 s27, 64
	s_mov_b64 s[10:11], 0
	s_and_b64 vcc, exec, vcc
	v_lshl_add_u64 v[70:71], v[4:5], 0, v[114:115]
	s_waitcnt vmcnt(7)
	v_and_b32_e32 v73, 0xffff0000, v41
	v_lshlrev_b32_e32 v72, 16, v41
	v_and_b32_e32 v41, 0xffff0000, v40
	v_lshlrev_b32_e32 v40, 16, v40
	s_waitcnt lgkmcnt(7)
	v_add_f32_e64 v8, v8, v40
	v_add_f32_e64 v9, v9, v41
	v_add_f32_e64 v10, v10, v72
	v_add_f32_e64 v11, v11, v73
	global_store_dwordx4 v[56:57], v[8:11], off nt
	s_waitcnt vmcnt(7)
	v_and_b32_e32 v41, 0xffff0000, v43
	v_lshlrev_b32_e32 v40, 16, v43
	v_and_b32_e32 v43, 0xffff0000, v42
	v_lshlrev_b32_e32 v42, 16, v42
	s_waitcnt lgkmcnt(3)
	v_add_f32_e64 v8, v24, v42
	v_add_f32_e64 v9, v25, v43
	v_add_f32_e64 v10, v26, v40
	v_add_f32_e64 v11, v27, v41
	s_waitcnt vmcnt(6)
	v_and_b32_e32 v25, 0xffff0000, v45
	v_lshlrev_b32_e32 v24, 16, v45
	v_and_b32_e32 v27, 0xffff0000, v44
	v_lshlrev_b32_e32 v26, 16, v44
	v_add_f32_e64 v12, v12, v26
	v_add_f32_e64 v13, v13, v27
	v_add_f32_e64 v14, v14, v24
	v_add_f32_e64 v15, v15, v25
	s_waitcnt vmcnt(5)
	v_and_b32_e32 v25, 0xffff0000, v47
	v_lshlrev_b32_e32 v24, 16, v47
	v_and_b32_e32 v27, 0xffff0000, v46
	v_lshlrev_b32_e32 v26, 16, v46
	global_store_dwordx4 v[58:59], v[12:15], off nt
	s_nop 1
	v_add_f32_e64 v12, v16, v26
	v_add_f32_e64 v13, v17, v27
	v_add_f32_e64 v14, v18, v24
	v_add_f32_e64 v15, v19, v25
	s_waitcnt vmcnt(5)
	v_and_b32_e32 v17, 0xffff0000, v49
	v_lshlrev_b32_e32 v16, 16, v49
	v_and_b32_e32 v19, 0xffff0000, v48
	v_lshlrev_b32_e32 v18, 16, v48
	global_store_dwordx4 v[60:61], v[12:15], off nt
	s_nop 1
	v_add_f32_e64 v12, v20, v18
	v_add_f32_e64 v13, v21, v19
	v_add_f32_e64 v14, v22, v16
	v_add_f32_e64 v15, v23, v17
	s_waitcnt vmcnt(5)
	v_and_b32_e32 v17, 0xffff0000, v51
	v_lshlrev_b32_e32 v16, 16, v51
	v_and_b32_e32 v19, 0xffff0000, v50
	v_lshlrev_b32_e32 v18, 16, v50
	global_store_dwordx4 v[62:63], v[12:15], off nt
	global_store_dwordx4 v[64:65], v[8:11], off nt
	s_waitcnt vmcnt(6)
	v_and_b32_e32 v13, 0xffff0000, v53
	s_waitcnt lgkmcnt(2)
	v_add_f32_e64 v8, v28, v18
	v_add_f32_e64 v9, v29, v19
	v_add_f32_e64 v10, v30, v16
	v_add_f32_e64 v11, v31, v17
	v_lshlrev_b32_e32 v12, 16, v53
	v_and_b32_e32 v15, 0xffff0000, v52
	v_lshlrev_b32_e32 v14, 16, v52
	global_store_dwordx4 v[66:67], v[8:11], off nt
	s_waitcnt lgkmcnt(1)
	s_nop 0
	v_add_f32_e64 v8, v32, v14
	v_add_f32_e64 v9, v33, v15
	v_add_f32_e64 v10, v34, v12
	v_add_f32_e64 v11, v35, v13
	s_waitcnt vmcnt(6)
	v_and_b32_e32 v13, 0xffff0000, v55
	v_lshlrev_b32_e32 v12, 16, v55
	v_and_b32_e32 v15, 0xffff0000, v54
	v_lshlrev_b32_e32 v14, 16, v54
	global_store_dwordx4 v[68:69], v[8:11], off nt
	s_waitcnt lgkmcnt(0)
	s_nop 0
	v_add_f32_e64 v8, v36, v14
	v_add_f32_e64 v9, v37, v15
	v_add_f32_e64 v10, v38, v12
	v_add_f32_e64 v11, v39, v13
	global_store_dwordx4 v[70:71], v[8:11], off nt
	s_cbranch_vccz .LBB0_2479
	s_add_i32 s22, s22, s14
	s_add_i32 s12, s12, s14
	s_cmpk_lt_u32 s22, 0x100
	s_cbranch_scc1 .LBB0_2476
	s_load_dwordx2 s[26:27], s[0:1], 0xf8
